# GEMM MFMA issue order: four consecutive MFMAs share the same B fragment (A0..A3 x Bj), k0 pass then k1 pass
# speedup vs baseline: 1.0080x; 1.0080x over previous
; #define PG8_STAGE(bufoff, gbase, voff) do { _Pragma("unroll") for (int _i = 0; _i < 2; ++_i) \
;         __builtin_amdgcn_global_load_lds((const unsigned*)((const char*)(gbase) + (voff)[_i]), (PG8_LAS unsigned*)(lds + (bufoff) + ldsw + _i * 8192), 16, 0, 0); } while (0)
; #define PG8_LDA(dst, b, h) do { _Pragma("unroll") for (int m = 0; m < 4; ++m) _Pragma("unroll") for (int k = 0; k < 2; ++k) dst[m][k] = *(const PG8_LAS bf16x8*)(lds + PG8_SA(b, h) + aoff + m * 2048 + k * 1024); } while (0)
; #define PG8_LDB(dst, b, h) do { _Pragma("unroll") for (int n = 0; n < 2; ++n) _Pragma("unroll") for (int k = 0; k < 2; ++k) dst[n][k] = *(const PG8_LAS bf16x8*)(lds + PG8_SB(b, h) + boff + n * 2048 + k * 1024); } while (0)
; #define PG8_MMA(ai, bj, At, Bt) do { __builtin_amdgcn_s_setprio(1); _Pragma("unroll") for (int m = 0; m < 4; ++m) _Pragma("unroll") for (int n = 0; n < 2; ++n) _Pragma("unroll") for (int k = 0; k < 2; ++k) \
;         acc[ai][bj][m][n] = __builtin_amdgcn_mfma_f32_16x16x32_bf16(Bt[n][k], At[m][k], acc[ai][bj][m][n], 0, 0, 0); __builtin_amdgcn_s_setprio(0); } while (0)
; #define PG8_BAR __builtin_amdgcn_s_barrier()
; template <class Epi, class Sched, bool ALIGN_EPI = false, bool SP2 = false>
; __device__ __forceinline__ void gemm_phase(PG8_LAS unsigned char* lds, const Gemm g, const Sched& S, const Epi& E) {
;     ...
;         const bool has_next = S.next(ui + 1, nxt);
;         const char* nA = has_next ? (const char*)g.A + (size_t)nxt.pm * tstep : cA; const char* nB = has_next ? (const char*)g.Bt + (size_t)nxt.pn * tstep : cB;
;         for (int t = 0; t < nt; t += 2) {
;             const bool last = (t == nt - 2);
;             const char* a1 = cA + (size_t)(t + 1) * kstep;
;             const char* a2 = last ? nA : cA + (size_t)(t + 2) * kstep; const char* b2 = last ? nB : cB + (size_t)(t + 2) * kstep;
;             const char* a3 = a2 + kstep; const char* b3 = b2 + kstep;
;             if (last && has_next) S.a_ready(nxt);
;             if constexpr (SP2) {
;             PG8_LDB(B0, 0, 0); PG8_LDB(B1, 0, 1); PG8_SCHED; PG8_LDA(At, 0, 0); PG8_STAGE(PG8_SA(1, 1), a1 + hstep, voffA);
;             PG8_WAIT_V(8); PG8_WAIT_L(0); PG8_BAR; PG8_MMA(0, 0, At, B0); PG8_MMA(0, 1, At, B1); PG8_BAR; PG8_SCHED;
;             PG8_LDA(At, 0, 1); PG8_STAGE(PG8_SB(0, 0), b2, voffB); PG8_STAGE(PG8_SB(0, 1), b2 + hstep, voffB); PG8_STAGE(PG8_SA(0, 0), a2, voffA);
.LBB0_190:
	s_ashr_i32 s27, s26, 31
	s_lshl_b64 s[14:15], s[26:27], 19
	s_add_u32 s28, s22, s14
	s_addc_u32 s29, s23, s15
	s_and_b64 s[14:15], s[0:1], exec
	s_cselect_b32 s27, s29, s49
	s_cselect_b32 s67, s28, s48
	s_ashr_i32 s25, s24, 31
	s_lshl_b64 s[14:15], s[24:25], 19
	s_add_u32 s40, s94, s14
	s_addc_u32 s41, s96, s15
	s_and_b64 s[14:15], s[0:1], exec
	s_cselect_b32 s25, s41, s51
	s_cselect_b32 s86, s40, s50
	s_add_u32 s48, s48, 0x40080
	s_addc_u32 s49, s49, 0
	s_add_u32 s87, s50, 0x100
	s_addc_u32 s88, s51, 0
	s_mov_b32 s89, -2
	ds_read_b128 v[144:147], v155
	ds_read_b128 v[148:151], v155 offset:1024
	ds_read_b128 v[160:163], v155 offset:2048
	ds_read_b128 v[168:171], v155 offset:3072
	ds_read_b128 v[172:175], v156
	ds_read_b128 v[176:179], v156 offset:1024
	ds_read_b128 v[182:185], v156 offset:2048
	ds_read_b128 v[186:189], v156 offset:3072
	s_add_u32 s3, s48, 0xfffc0080
	s_addc_u32 s14, s49, -1
	s_cmp_eq_u32 s89, 12
	s_cselect_b32 s55, s27, s14
	s_cselect_b32 s54, s67, s3
	s_cselect_b32 s51, s25, s88
	s_cselect_b32 s50, s86, s87
	v_lshl_add_u64 v[164:165], s[48:49], 0, v[136:137]
	s_add_i32 m0, s45, 0xc000
	ds_read_b128 v[190:193], v157
	ds_read_b128 v[194:197], v157 offset:1024
	ds_read_b128 v[198:201], v157 offset:2048
	ds_read_b128 v[208:211], v157 offset:3072
	ds_read_b128 v[212:215], v157 offset:4096
	ds_read_b128 v[216:219], v157 offset:5120
	ds_read_b128 v[220:223], v157 offset:6144
	ds_read_b128 v[224:227], v157 offset:7168
	global_load_lds_dwordx4 v[164:165], off
	v_lshl_add_u64 v[164:165], s[48:49], 0, v[138:139]
	s_add_i32 m0, s45, 0xe000
	s_nop 0
	global_load_lds_dwordx4 v[164:165], off
	s_waitcnt vmcnt(8)
	s_waitcnt lgkmcnt(0)
	s_barrier
	s_setprio 1
	s_waitcnt lgkmcnt(0)
	v_mfma_f32_16x16x32_bf16 v[124:127], v[144:147], v[190:193], 0
	v_mfma_f32_16x16x32_bf16 v[120:123], v[160:163], v[190:193], 0
	v_mfma_f32_16x16x32_bf16 v[116:119], v[172:175], v[190:193], 0
	v_mfma_f32_16x16x32_bf16 v[112:115], v[182:185], v[190:193], 0
	v_mfma_f32_16x16x32_bf16 v[108:111], v[144:147], v[198:201], 0
	v_mfma_f32_16x16x32_bf16 v[104:107], v[160:163], v[198:201], 0
	v_mfma_f32_16x16x32_bf16 v[100:103], v[172:175], v[198:201], 0
	v_mfma_f32_16x16x32_bf16 v[96:99], v[182:185], v[198:201], 0
	v_mfma_f32_16x16x32_bf16 v[92:95], v[144:147], v[212:215], 0
	v_mfma_f32_16x16x32_bf16 v[88:91], v[160:163], v[212:215], 0
	v_mfma_f32_16x16x32_bf16 v[84:87], v[172:175], v[212:215], 0
	v_mfma_f32_16x16x32_bf16 v[80:83], v[182:185], v[212:215], 0
	v_mfma_f32_16x16x32_bf16 v[76:79], v[144:147], v[220:223], 0
	v_mfma_f32_16x16x32_bf16 v[72:75], v[160:163], v[220:223], 0
	v_mfma_f32_16x16x32_bf16 v[68:71], v[172:175], v[220:223], 0
	v_mfma_f32_16x16x32_bf16 v[64:67], v[182:185], v[220:223], 0
	s_setprio 0
	s_setprio 1
	v_mfma_f32_16x16x32_bf16 v[124:127], v[148:151], v[194:197], v[124:127]
	v_mfma_f32_16x16x32_bf16 v[120:123], v[168:171], v[194:197], v[120:123]
	v_mfma_f32_16x16x32_bf16 v[116:119], v[176:179], v[194:197], v[116:119]
	v_mfma_f32_16x16x32_bf16 v[112:115], v[186:189], v[194:197], v[112:115]
	v_mfma_f32_16x16x32_bf16 v[108:111], v[148:151], v[208:211], v[108:111]
	v_mfma_f32_16x16x32_bf16 v[104:107], v[168:171], v[208:211], v[104:107]
	v_mfma_f32_16x16x32_bf16 v[100:103], v[176:179], v[208:211], v[100:103]
	v_mfma_f32_16x16x32_bf16 v[96:99], v[186:189], v[208:211], v[96:99]
	v_mfma_f32_16x16x32_bf16 v[92:95], v[148:151], v[216:219], v[92:95]
	v_mfma_f32_16x16x32_bf16 v[88:91], v[168:171], v[216:219], v[88:91]
	v_mfma_f32_16x16x32_bf16 v[84:87], v[176:179], v[216:219], v[84:87]
	v_mfma_f32_16x16x32_bf16 v[80:83], v[186:189], v[216:219], v[80:83]
	v_mfma_f32_16x16x32_bf16 v[76:79], v[148:151], v[224:227], v[76:79]
	v_mfma_f32_16x16x32_bf16 v[72:75], v[168:171], v[224:227], v[72:75]
	v_mfma_f32_16x16x32_bf16 v[68:71], v[176:179], v[224:227], v[68:71]
	v_mfma_f32_16x16x32_bf16 v[64:67], v[186:189], v[224:227], v[64:67]
	s_setprio 0
	s_barrier
	s_add_i32 s3, s63, s43
	v_lshl_add_u64 v[164:165], s[50:51], 0, v[132:133]
	s_mov_b32 m0, s3
	ds_read_b128 v[190:193], v157 offset:16384
	ds_read_b128 v[194:197], v157 offset:17408
	ds_read_b128 v[198:201], v157 offset:18432
	ds_read_b128 v[208:211], v157 offset:19456
	ds_read_b128 v[212:215], v157 offset:20480
	ds_read_b128 v[216:219], v157 offset:21504
	ds_read_b128 v[220:223], v157 offset:22528
	ds_read_b128 v[224:227], v157 offset:23552
	global_load_lds_dwordx4 v[164:165], off
	s_add_i32 m0, s3, 0x2000
	s_add_u32 s14, s50, 0x40000
	v_lshl_add_u64 v[202:203], s[50:51], 0, v[128:129]
	s_addc_u32 s15, s51, 0
	s_add_i32 s3, s64, s43
	global_load_lds_dwordx4 v[202:203], off
	v_lshl_add_u64 v[228:229], s[14:15], 0, v[132:133]
	s_mov_b32 m0, s3
	global_load_lds_dwordx4 v[228:229], off
	v_lshl_add_u64 v[228:229], s[14:15], 0, v[128:129]
	s_add_i32 m0, s3, 0x2000
	s_nop 0
	global_load_lds_dwordx4 v[228:229], off
	s_waitcnt vmcnt(6)
	s_waitcnt lgkmcnt(0)
	s_barrier
; #define PG8_STAGE(bufoff, gbase, voff) do { _Pragma("unroll") for (int _i = 0; _i < 2; ++_i) \
;         __builtin_amdgcn_global_load_lds((const unsigned*)((const char*)(gbase) + (voff)[_i]), (PG8_LAS unsigned*)(lds + (bufoff) + ldsw + _i * 8192), 16, 0, 0); } while (0)
; #define PG8_LDA(dst, b, h) do { _Pragma("unroll") for (int m = 0; m < 4; ++m) _Pragma("unroll") for (int k = 0; k < 2; ++k) dst[m][k] = *(const PG8_LAS bf16x8*)(lds + PG8_SA(b, h) + aoff + m * 2048 + k * 1024); } while (0)
; #define PG8_LDB(dst, b, h) do { _Pragma("unroll") for (int n = 0; n < 2; ++n) _Pragma("unroll") for (int k = 0; k < 2; ++k) dst[n][k] = *(const PG8_LAS bf16x8*)(lds + PG8_SB(b, h) + boff + n * 2048 + k * 1024); } while (0)
; #define PG8_MMA(ai, bj, At, Bt) do { __builtin_amdgcn_s_setprio(1); _Pragma("unroll") for (int m = 0; m < 4; ++m) _Pragma("unroll") for (int n = 0; n < 2; ++n) _Pragma("unroll") for (int k = 0; k < 2; ++k) \
;         acc[ai][bj][m][n] = __builtin_amdgcn_mfma_f32_16x16x32_bf16(Bt[n][k], At[m][k], acc[ai][bj][m][n], 0, 0, 0); __builtin_amdgcn_s_setprio(0); } while (0)
; #define PG8_WAIT_V(n) asm volatile("s_waitcnt vmcnt(" #n ")" ::: "memory")
; #define PG8_WAIT_L(n) asm volatile("s_waitcnt lgkmcnt(" #n ")" ::: "memory")
; #define PG8_BAR __builtin_amdgcn_s_barrier()
; #define PG8_SCHED __builtin_amdgcn_sched_barrier(0)
; template <class Epi, class Sched, bool ALIGN_EPI = false, bool SP2 = false>
; __device__ __forceinline__ void gemm_phase(PG8_LAS unsigned char* lds, const Gemm g, const Sched& S, const Epi& E) {
;     ...
;             PG8_WAIT_V(8); PG8_WAIT_L(0); PG8_BAR; PG8_MMA(1, 0, At, B0); PG8_MMA(1, 1, At, B1); PG8_BAR; PG8_SCHED;
;             PG8_LDB(B0, 1, 0); PG8_LDB(B1, 1, 1); PG8_SCHED; PG8_LDA(At, 1, 0); PG8_STAGE(PG8_SA(0, 1), a2 + hstep, voffA);
;             PG8_WAIT_V(8); PG8_WAIT_L(0); PG8_BAR; PG8_MMA(0, 0, At, B0); PG8_MMA(0, 1, At, B1); PG8_BAR; PG8_SCHED;
	s_setprio 1
	s_waitcnt lgkmcnt(0)
	v_mfma_f32_16x16x32_bf16 v[60:63], v[144:147], v[190:193], 0
	v_mfma_f32_16x16x32_bf16 v[56:59], v[160:163], v[190:193], 0
	v_mfma_f32_16x16x32_bf16 v[52:55], v[172:175], v[190:193], 0
	v_mfma_f32_16x16x32_bf16 v[48:51], v[182:185], v[190:193], 0
	v_mfma_f32_16x16x32_bf16 v[44:47], v[144:147], v[198:201], 0
	v_mfma_f32_16x16x32_bf16 v[40:43], v[160:163], v[198:201], 0
	v_mfma_f32_16x16x32_bf16 v[36:39], v[172:175], v[198:201], 0
	v_mfma_f32_16x16x32_bf16 v[32:35], v[182:185], v[198:201], 0
	v_mfma_f32_16x16x32_bf16 v[28:31], v[144:147], v[212:215], 0
	v_mfma_f32_16x16x32_bf16 v[24:27], v[160:163], v[212:215], 0
	v_mfma_f32_16x16x32_bf16 v[20:23], v[172:175], v[212:215], 0
	v_mfma_f32_16x16x32_bf16 v[16:19], v[182:185], v[212:215], 0
	v_mfma_f32_16x16x32_bf16 v[12:15], v[144:147], v[220:223], 0
	v_mfma_f32_16x16x32_bf16 v[8:11], v[160:163], v[220:223], 0
	v_lshl_add_u64 v[228:229], s[54:55], 0, v[134:135]
	s_mov_b32 m0, s45
	s_nop 0
	global_load_lds_dwordx4 v[228:229], off
	v_mfma_f32_16x16x32_bf16 v[4:7], v[172:175], v[220:223], 0
	v_mfma_f32_16x16x32_bf16 v[0:3], v[182:185], v[220:223], 0
	s_setprio 0
	s_setprio 1
	v_mfma_f32_16x16x32_bf16 v[60:63], v[148:151], v[194:197], v[60:63]
	v_mfma_f32_16x16x32_bf16 v[56:59], v[168:171], v[194:197], v[56:59]
	v_mfma_f32_16x16x32_bf16 v[52:55], v[176:179], v[194:197], v[52:55]
	v_mfma_f32_16x16x32_bf16 v[48:51], v[186:189], v[194:197], v[48:51]
	v_mfma_f32_16x16x32_bf16 v[44:47], v[148:151], v[208:211], v[44:47]
	v_mfma_f32_16x16x32_bf16 v[40:43], v[168:171], v[208:211], v[40:43]
	v_mfma_f32_16x16x32_bf16 v[36:39], v[176:179], v[208:211], v[36:39]
	v_mfma_f32_16x16x32_bf16 v[32:35], v[186:189], v[208:211], v[32:35]
	v_mfma_f32_16x16x32_bf16 v[28:31], v[148:151], v[216:219], v[28:31]
	v_mfma_f32_16x16x32_bf16 v[24:27], v[168:171], v[216:219], v[24:27]
	v_mfma_f32_16x16x32_bf16 v[20:23], v[176:179], v[216:219], v[20:23]
	v_mfma_f32_16x16x32_bf16 v[16:19], v[186:189], v[216:219], v[16:19]
	v_mfma_f32_16x16x32_bf16 v[12:15], v[148:151], v[224:227], v[12:15]
	v_mfma_f32_16x16x32_bf16 v[8:11], v[168:171], v[224:227], v[8:11]
	v_lshl_add_u64 v[230:231], s[54:55], 0, v[130:131]
	s_mov_b32 m0, s57
	s_nop 0
	global_load_lds_dwordx4 v[230:231], off
	v_mfma_f32_16x16x32_bf16 v[4:7], v[176:179], v[224:227], v[4:7]
	v_mfma_f32_16x16x32_bf16 v[0:3], v[186:189], v[224:227], v[0:3]
	s_setprio 0
	s_barrier
	s_add_i32 s3, 0, 0x18000
	v_add_u32_e32 v159, s3, v153
	s_add_i32 s33, 0, 0x1c000
	ds_read_b128 v[144:147], v159
	ds_read_b128 v[148:151], v159 offset:1024
	ds_read_b128 v[160:163], v159 offset:2048
	ds_read_b128 v[168:171], v159 offset:3072
	v_add_u32_e32 v159, s33, v153
	ds_read_b128 v[172:175], v159
	ds_read_b128 v[176:179], v159 offset:1024
	ds_read_b128 v[182:185], v159 offset:2048
	ds_read_b128 v[186:189], v159 offset:3072
	s_add_u32 s14, s54, 0x40000
	s_addc_u32 s15, s55, 0
	s_mov_b32 m0, s58
	v_lshl_add_u64 v[232:233], s[14:15], 0, v[134:135]
	ds_read_b128 v[190:193], v157 offset:32768
	ds_read_b128 v[194:197], v157 offset:33792
	ds_read_b128 v[198:201], v157 offset:34816
	ds_read_b128 v[208:211], v157 offset:35840
	ds_read_b128 v[212:215], v157 offset:36864
	ds_read_b128 v[216:219], v157 offset:37888
	ds_read_b128 v[220:223], v157 offset:38912
	ds_read_b128 v[224:227], v157 offset:39936
	global_load_lds_dwordx4 v[232:233], off
	v_lshl_add_u64 v[232:233], s[14:15], 0, v[130:131]
	s_mov_b32 m0, s59
	s_nop 0
	global_load_lds_dwordx4 v[232:233], off
	s_waitcnt vmcnt(8)
	s_waitcnt lgkmcnt(0)
	s_barrier
	s_setprio 1
	s_waitcnt lgkmcnt(0)
	v_mfma_f32_16x16x32_bf16 v[124:127], v[144:147], v[190:193], v[124:127]
	v_mfma_f32_16x16x32_bf16 v[120:123], v[160:163], v[190:193], v[120:123]
	v_mfma_f32_16x16x32_bf16 v[116:119], v[172:175], v[190:193], v[116:119]
	v_mfma_f32_16x16x32_bf16 v[112:115], v[182:185], v[190:193], v[112:115]
	v_mfma_f32_16x16x32_bf16 v[108:111], v[144:147], v[198:201], v[108:111]
	v_mfma_f32_16x16x32_bf16 v[104:107], v[160:163], v[198:201], v[104:107]
	v_mfma_f32_16x16x32_bf16 v[100:103], v[172:175], v[198:201], v[100:103]
	v_mfma_f32_16x16x32_bf16 v[96:99], v[182:185], v[198:201], v[96:99]
	v_mfma_f32_16x16x32_bf16 v[92:95], v[144:147], v[212:215], v[92:95]
	v_mfma_f32_16x16x32_bf16 v[88:91], v[160:163], v[212:215], v[88:91]
	v_mfma_f32_16x16x32_bf16 v[84:87], v[172:175], v[212:215], v[84:87]
	v_mfma_f32_16x16x32_bf16 v[80:83], v[182:185], v[212:215], v[80:83]
	v_mfma_f32_16x16x32_bf16 v[76:79], v[144:147], v[220:223], v[76:79]
	v_mfma_f32_16x16x32_bf16 v[72:75], v[160:163], v[220:223], v[72:75]
	v_mfma_f32_16x16x32_bf16 v[68:71], v[172:175], v[220:223], v[68:71]
	v_mfma_f32_16x16x32_bf16 v[64:67], v[182:185], v[220:223], v[64:67]
	s_setprio 0
	s_setprio 1
	v_mfma_f32_16x16x32_bf16 v[124:127], v[148:151], v[194:197], v[124:127]
	v_mfma_f32_16x16x32_bf16 v[120:123], v[168:171], v[194:197], v[120:123]
	v_mfma_f32_16x16x32_bf16 v[116:119], v[176:179], v[194:197], v[116:119]
	v_mfma_f32_16x16x32_bf16 v[112:115], v[186:189], v[194:197], v[112:115]
	v_mfma_f32_16x16x32_bf16 v[108:111], v[148:151], v[208:211], v[108:111]
	v_mfma_f32_16x16x32_bf16 v[104:107], v[168:171], v[208:211], v[104:107]
	v_mfma_f32_16x16x32_bf16 v[100:103], v[176:179], v[208:211], v[100:103]
	v_mfma_f32_16x16x32_bf16 v[96:99], v[186:189], v[208:211], v[96:99]
	v_mfma_f32_16x16x32_bf16 v[92:95], v[148:151], v[216:219], v[92:95]
	v_mfma_f32_16x16x32_bf16 v[88:91], v[168:171], v[216:219], v[88:91]
	v_mfma_f32_16x16x32_bf16 v[84:87], v[176:179], v[216:219], v[84:87]
	v_mfma_f32_16x16x32_bf16 v[80:83], v[186:189], v[216:219], v[80:83]
	v_mfma_f32_16x16x32_bf16 v[76:79], v[148:151], v[224:227], v[76:79]
	v_mfma_f32_16x16x32_bf16 v[72:75], v[168:171], v[224:227], v[72:75]
	v_mfma_f32_16x16x32_bf16 v[68:71], v[176:179], v[224:227], v[68:71]
	v_mfma_f32_16x16x32_bf16 v[64:67], v[186:189], v[224:227], v[64:67]
	s_setprio 0
	s_barrier
; #define PG8_STAGE(bufoff, gbase, voff) do { _Pragma("unroll") for (int _i = 0; _i < 2; ++_i) \
;         __builtin_amdgcn_global_load_lds((const unsigned*)((const char*)(gbase) + (voff)[_i]), (PG8_LAS unsigned*)(lds + (bufoff) + ldsw + _i * 8192), 16, 0, 0); } while (0)
; #define PG8_LDA(dst, b, h) do { _Pragma("unroll") for (int m = 0; m < 4; ++m) _Pragma("unroll") for (int k = 0; k < 2; ++k) dst[m][k] = *(const PG8_LAS bf16x8*)(lds + PG8_SA(b, h) + aoff + m * 2048 + k * 1024); } while (0)
; #define PG8_LDB(dst, b, h) do { _Pragma("unroll") for (int n = 0; n < 2; ++n) _Pragma("unroll") for (int k = 0; k < 2; ++k) dst[n][k] = *(const PG8_LAS bf16x8*)(lds + PG8_SB(b, h) + boff + n * 2048 + k * 1024); } while (0)
; #define PG8_MMA(ai, bj, At, Bt) do { __builtin_amdgcn_s_setprio(1); _Pragma("unroll") for (int m = 0; m < 4; ++m) _Pragma("unroll") for (int n = 0; n < 2; ++n) _Pragma("unroll") for (int k = 0; k < 2; ++k) \
;         acc[ai][bj][m][n] = __builtin_amdgcn_mfma_f32_16x16x32_bf16(Bt[n][k], At[m][k], acc[ai][bj][m][n], 0, 0, 0); __builtin_amdgcn_s_setprio(0); } while (0)
; #define PG8_WAIT_V(n) asm volatile("s_waitcnt vmcnt(" #n ")" ::: "memory")
; #define PG8_WAIT_L(n) asm volatile("s_waitcnt lgkmcnt(" #n ")" ::: "memory")
; #define PG8_BAR __builtin_amdgcn_s_barrier()
; #define PG8_SCHED __builtin_amdgcn_sched_barrier(0)
; template <class Epi, class Sched, bool ALIGN_EPI = false, bool SP2 = false>
; __device__ __forceinline__ void gemm_phase(PG8_LAS unsigned char* lds, const Gemm g, const Sched& S, const Epi& E) {
;     ...
;             PG8_LDB(B0, 0, 0); PG8_LDB(B1, 0, 1); PG8_SCHED; PG8_LDA(At, 0, 0); PG8_STAGE(PG8_SA(1, 1), a1 + hstep, voffA);
;             PG8_WAIT_V(8); PG8_WAIT_L(0); PG8_BAR; PG8_MMA(0, 0, At, B0); PG8_MMA(0, 1, At, B1); PG8_BAR; PG8_SCHED;
;     ...
;             PG8_LDA(At, 1, 1); PG8_STAGE(PG8_SB(1, 0), b3, voffB); PG8_STAGE(PG8_SB(1, 1), b3 + hstep, voffB); PG8_STAGE(PG8_SA(1, 0), a3, voffA);
;             PG8_WAIT_V(8); PG8_WAIT_L(0); PG8_BAR; PG8_MMA(1, 0, At, B0); PG8_MMA(1, 1, At, B1); PG8_BAR; PG8_SCHED;
	s_add_i32 s3, s3, s43
	v_lshl_add_u64 v[164:165], v[164:165], 0, s[10:11]
	s_mov_b32 m0, s3
	ds_read_b128 v[190:193], v157 offset:49152
	ds_read_b128 v[194:197], v157 offset:50176
	ds_read_b128 v[198:201], v157 offset:51200
	ds_read_b128 v[208:211], v157 offset:52224
	ds_read_b128 v[212:215], v157 offset:53248
	ds_read_b128 v[216:219], v157 offset:54272
	ds_read_b128 v[220:223], v157 offset:55296
	ds_read_b128 v[224:227], v157 offset:56320
	global_load_lds_dwordx4 v[164:165], off
	s_add_i32 m0, s3, 0x2000
	s_add_u32 s14, s50, 0x40080
	v_lshl_add_u64 v[164:165], v[202:203], 0, s[10:11]
	s_addc_u32 s15, s51, 0
	s_add_i32 s3, s33, s43
	global_load_lds_dwordx4 v[164:165], off
	v_lshl_add_u64 v[164:165], s[14:15], 0, v[132:133]
	s_mov_b32 m0, s3
	s_nop 0
	global_load_lds_dwordx4 v[164:165], off
	v_lshl_add_u64 v[164:165], s[14:15], 0, v[128:129]
	s_add_i32 m0, s3, 0x2000
	s_nop 0
	global_load_lds_dwordx4 v[164:165], off
	s_waitcnt vmcnt(6)
	s_waitcnt lgkmcnt(0)
	s_barrier
	s_setprio 1
	s_waitcnt lgkmcnt(0)
	v_mfma_f32_16x16x32_bf16 v[60:63], v[144:147], v[190:193], v[60:63]
	v_mfma_f32_16x16x32_bf16 v[56:59], v[160:163], v[190:193], v[56:59]
	v_mfma_f32_16x16x32_bf16 v[52:55], v[172:175], v[190:193], v[52:55]
	v_mfma_f32_16x16x32_bf16 v[48:51], v[182:185], v[190:193], v[48:51]
	v_mfma_f32_16x16x32_bf16 v[44:47], v[144:147], v[198:201], v[44:47]
	v_mfma_f32_16x16x32_bf16 v[40:43], v[160:163], v[198:201], v[40:43]
	v_mfma_f32_16x16x32_bf16 v[36:39], v[172:175], v[198:201], v[36:39]
	v_mfma_f32_16x16x32_bf16 v[32:35], v[182:185], v[198:201], v[32:35]
	v_mfma_f32_16x16x32_bf16 v[28:31], v[144:147], v[212:215], v[28:31]
	v_mfma_f32_16x16x32_bf16 v[24:27], v[160:163], v[212:215], v[24:27]
	v_mfma_f32_16x16x32_bf16 v[20:23], v[172:175], v[212:215], v[20:23]
	v_mfma_f32_16x16x32_bf16 v[16:19], v[182:185], v[212:215], v[16:19]
	v_mfma_f32_16x16x32_bf16 v[12:15], v[144:147], v[220:223], v[12:15]
	v_mfma_f32_16x16x32_bf16 v[8:11], v[160:163], v[220:223], v[8:11]
	v_lshl_add_u64 v[164:165], v[228:229], 0, s[10:11]
	s_mov_b32 m0, s61
	s_nop 0
	global_load_lds_dwordx4 v[164:165], off
	v_mfma_f32_16x16x32_bf16 v[4:7], v[172:175], v[220:223], v[4:7]
	v_mfma_f32_16x16x32_bf16 v[0:3], v[182:185], v[220:223], v[0:3]
	s_setprio 0
	s_setprio 1
	v_mfma_f32_16x16x32_bf16 v[60:63], v[148:151], v[194:197], v[60:63]
	v_mfma_f32_16x16x32_bf16 v[56:59], v[168:171], v[194:197], v[56:59]
	v_mfma_f32_16x16x32_bf16 v[52:55], v[176:179], v[194:197], v[52:55]
	v_mfma_f32_16x16x32_bf16 v[48:51], v[186:189], v[194:197], v[48:51]
	v_mfma_f32_16x16x32_bf16 v[44:47], v[148:151], v[208:211], v[44:47]
	v_mfma_f32_16x16x32_bf16 v[40:43], v[168:171], v[208:211], v[40:43]
	v_mfma_f32_16x16x32_bf16 v[36:39], v[176:179], v[208:211], v[36:39]
	v_mfma_f32_16x16x32_bf16 v[32:35], v[186:189], v[208:211], v[32:35]
	v_mfma_f32_16x16x32_bf16 v[28:31], v[148:151], v[216:219], v[28:31]
	v_mfma_f32_16x16x32_bf16 v[24:27], v[168:171], v[216:219], v[24:27]
	v_mfma_f32_16x16x32_bf16 v[20:23], v[176:179], v[216:219], v[20:23]
	v_mfma_f32_16x16x32_bf16 v[16:19], v[186:189], v[216:219], v[16:19]
	v_mfma_f32_16x16x32_bf16 v[12:15], v[148:151], v[224:227], v[12:15]
	v_mfma_f32_16x16x32_bf16 v[8:11], v[168:171], v[224:227], v[8:11]
	v_lshl_add_u64 v[164:165], v[230:231], 0, s[10:11]
	s_mov_b32 m0, s62
	s_nop 0
	global_load_lds_dwordx4 v[164:165], off
	v_mfma_f32_16x16x32_bf16 v[4:7], v[176:179], v[224:227], v[4:7]
	v_mfma_f32_16x16x32_bf16 v[0:3], v[186:189], v[224:227], v[0:3]
	s_setprio 0
	s_barrier
	s_add_i32 s89, s89, 2
	s_add_u32 s48, s48, 0x100
	s_addc_u32 s49, s49, 0
	s_add_u32 s87, s87, 0x100
	s_addc_u32 s88, s88, 0
.LBB0_191:
	ds_read_b128 v[144:147], v155
	ds_read_b128 v[148:151], v155 offset:1024
	ds_read_b128 v[160:163], v155 offset:2048
	ds_read_b128 v[168:171], v155 offset:3072
	ds_read_b128 v[172:175], v156
	ds_read_b128 v[176:179], v156 offset:1024
	ds_read_b128 v[182:185], v156 offset:2048
	ds_read_b128 v[186:189], v156 offset:3072
	s_add_u32 s3, s48, 0xfffc0080
	s_addc_u32 s14, s49, -1
	s_cmp_eq_u32 s89, 12
	s_cselect_b32 s55, s27, s14
	s_cselect_b32 s54, s67, s3
	s_cselect_b32 s51, s25, s88
	s_cselect_b32 s50, s86, s87
	v_lshl_add_u64 v[164:165], s[48:49], 0, v[136:137]
	s_add_i32 m0, s45, 0xc000
	ds_read_b128 v[190:193], v157
	ds_read_b128 v[194:197], v157 offset:1024
	ds_read_b128 v[198:201], v157 offset:2048
	ds_read_b128 v[208:211], v157 offset:3072
	ds_read_b128 v[212:215], v157 offset:4096
	ds_read_b128 v[216:219], v157 offset:5120
	ds_read_b128 v[220:223], v157 offset:6144
	ds_read_b128 v[224:227], v157 offset:7168
	global_load_lds_dwordx4 v[164:165], off
	v_lshl_add_u64 v[164:165], s[48:49], 0, v[138:139]
	s_add_i32 m0, s45, 0xe000
	s_nop 0
	global_load_lds_dwordx4 v[164:165], off
	s_waitcnt vmcnt(8)
	s_waitcnt lgkmcnt(0)
	s_barrier
; #define PG8_STAGE(bufoff, gbase, voff) do { _Pragma("unroll") for (int _i = 0; _i < 2; ++_i) \
;         __builtin_amdgcn_global_load_lds((const unsigned*)((const char*)(gbase) + (voff)[_i]), (PG8_LAS unsigned*)(lds + (bufoff) + ldsw + _i * 8192), 16, 0, 0); } while (0)
; #define PG8_LDA(dst, b, h) do { _Pragma("unroll") for (int m = 0; m < 4; ++m) _Pragma("unroll") for (int k = 0; k < 2; ++k) dst[m][k] = *(const PG8_LAS bf16x8*)(lds + PG8_SA(b, h) + aoff + m * 2048 + k * 1024); } while (0)
; #define PG8_MMA(ai, bj, At, Bt) do { __builtin_amdgcn_s_setprio(1); _Pragma("unroll") for (int m = 0; m < 4; ++m) _Pragma("unroll") for (int n = 0; n < 2; ++n) _Pragma("unroll") for (int k = 0; k < 2; ++k) \
;         acc[ai][bj][m][n] = __builtin_amdgcn_mfma_f32_16x16x32_bf16(Bt[n][k], At[m][k], acc[ai][bj][m][n], 0, 0, 0); __builtin_amdgcn_s_setprio(0); } while (0)
; #define PG8_WAIT_V(n) asm volatile("s_waitcnt vmcnt(" #n ")" ::: "memory")
; #define PG8_WAIT_L(n) asm volatile("s_waitcnt lgkmcnt(" #n ")" ::: "memory")
; #define PG8_BAR __builtin_amdgcn_s_barrier()
; #define PG8_SCHED __builtin_amdgcn_sched_barrier(0)
; template <class Epi, class Sched, bool ALIGN_EPI = false, bool SP2 = false>
; __device__ __forceinline__ void gemm_phase(PG8_LAS unsigned char* lds, const Gemm g, const Sched& S, const Epi& E) {
;     ...
;             PG8_WAIT_V(8); PG8_WAIT_L(0); PG8_BAR; PG8_MMA(0, 0, At, B0); PG8_MMA(0, 1, At, B1); PG8_BAR; PG8_SCHED;
;             PG8_LDA(At, 0, 1); PG8_STAGE(PG8_SB(0, 0), b2, voffB); PG8_STAGE(PG8_SB(0, 1), b2 + hstep, voffB); PG8_STAGE(PG8_SA(0, 0), a2, voffA);
;             PG8_WAIT_V(8); PG8_WAIT_L(0); PG8_BAR; PG8_MMA(1, 0, At, B0); PG8_MMA(1, 1, At, B1); PG8_BAR; PG8_SCHED;
	s_setprio 1
	s_waitcnt lgkmcnt(0)
	v_mfma_f32_16x16x32_bf16 v[124:127], v[144:147], v[190:193], v[124:127]
	v_mfma_f32_16x16x32_bf16 v[120:123], v[160:163], v[190:193], v[120:123]
	v_mfma_f32_16x16x32_bf16 v[116:119], v[172:175], v[190:193], v[116:119]
	v_mfma_f32_16x16x32_bf16 v[112:115], v[182:185], v[190:193], v[112:115]
	v_mfma_f32_16x16x32_bf16 v[108:111], v[144:147], v[198:201], v[108:111]
	v_mfma_f32_16x16x32_bf16 v[104:107], v[160:163], v[198:201], v[104:107]
	v_mfma_f32_16x16x32_bf16 v[100:103], v[172:175], v[198:201], v[100:103]
	v_mfma_f32_16x16x32_bf16 v[96:99], v[182:185], v[198:201], v[96:99]
	v_mfma_f32_16x16x32_bf16 v[92:95], v[144:147], v[212:215], v[92:95]
	v_mfma_f32_16x16x32_bf16 v[88:91], v[160:163], v[212:215], v[88:91]
	v_mfma_f32_16x16x32_bf16 v[84:87], v[172:175], v[212:215], v[84:87]
	v_mfma_f32_16x16x32_bf16 v[80:83], v[182:185], v[212:215], v[80:83]
	v_mfma_f32_16x16x32_bf16 v[76:79], v[144:147], v[220:223], v[76:79]
	v_mfma_f32_16x16x32_bf16 v[72:75], v[160:163], v[220:223], v[72:75]
	v_mfma_f32_16x16x32_bf16 v[68:71], v[172:175], v[220:223], v[68:71]
	v_mfma_f32_16x16x32_bf16 v[64:67], v[182:185], v[220:223], v[64:67]
	s_setprio 0
	s_setprio 1
	v_mfma_f32_16x16x32_bf16 v[124:127], v[148:151], v[194:197], v[124:127]
	v_mfma_f32_16x16x32_bf16 v[120:123], v[168:171], v[194:197], v[120:123]
	v_mfma_f32_16x16x32_bf16 v[116:119], v[176:179], v[194:197], v[116:119]
	v_mfma_f32_16x16x32_bf16 v[112:115], v[186:189], v[194:197], v[112:115]
	v_mfma_f32_16x16x32_bf16 v[108:111], v[148:151], v[208:211], v[108:111]
	v_mfma_f32_16x16x32_bf16 v[104:107], v[168:171], v[208:211], v[104:107]
	v_mfma_f32_16x16x32_bf16 v[100:103], v[176:179], v[208:211], v[100:103]
	v_mfma_f32_16x16x32_bf16 v[96:99], v[186:189], v[208:211], v[96:99]
	v_mfma_f32_16x16x32_bf16 v[92:95], v[148:151], v[216:219], v[92:95]
	v_mfma_f32_16x16x32_bf16 v[88:91], v[168:171], v[216:219], v[88:91]
	v_mfma_f32_16x16x32_bf16 v[84:87], v[176:179], v[216:219], v[84:87]
	v_mfma_f32_16x16x32_bf16 v[80:83], v[186:189], v[216:219], v[80:83]
	v_mfma_f32_16x16x32_bf16 v[76:79], v[148:151], v[224:227], v[76:79]
	v_mfma_f32_16x16x32_bf16 v[72:75], v[168:171], v[224:227], v[72:75]
	v_mfma_f32_16x16x32_bf16 v[68:71], v[176:179], v[224:227], v[68:71]
	v_mfma_f32_16x16x32_bf16 v[64:67], v[186:189], v[224:227], v[64:67]
	s_setprio 0
	s_barrier
	s_add_i32 s3, s63, s43
	v_lshl_add_u64 v[164:165], s[50:51], 0, v[132:133]
	s_mov_b32 m0, s3
	ds_read_b128 v[190:193], v157 offset:16384
	ds_read_b128 v[194:197], v157 offset:17408
	ds_read_b128 v[198:201], v157 offset:18432
	ds_read_b128 v[208:211], v157 offset:19456
	ds_read_b128 v[212:215], v157 offset:20480
	ds_read_b128 v[216:219], v157 offset:21504
	ds_read_b128 v[220:223], v157 offset:22528
	ds_read_b128 v[224:227], v157 offset:23552
	global_load_lds_dwordx4 v[164:165], off
	s_add_i32 m0, s3, 0x2000
	s_add_u32 s14, s50, 0x40000
	v_lshl_add_u64 v[202:203], s[50:51], 0, v[128:129]
	s_addc_u32 s15, s51, 0
	s_add_i32 s3, s64, s43
	global_load_lds_dwordx4 v[202:203], off
	v_lshl_add_u64 v[228:229], s[14:15], 0, v[132:133]
	s_mov_b32 m0, s3
	global_load_lds_dwordx4 v[228:229], off
	v_lshl_add_u64 v[228:229], s[14:15], 0, v[128:129]
	s_add_i32 m0, s3, 0x2000
	s_nop 0
	global_load_lds_dwordx4 v[228:229], off
	s_waitcnt vmcnt(6)
	s_waitcnt lgkmcnt(0)
	s_barrier
	s_setprio 1
	s_waitcnt lgkmcnt(0)
	v_mfma_f32_16x16x32_bf16 v[60:63], v[144:147], v[190:193], v[60:63]
	v_mfma_f32_16x16x32_bf16 v[56:59], v[160:163], v[190:193], v[56:59]
	v_mfma_f32_16x16x32_bf16 v[52:55], v[172:175], v[190:193], v[52:55]
	v_mfma_f32_16x16x32_bf16 v[48:51], v[182:185], v[190:193], v[48:51]
	v_mfma_f32_16x16x32_bf16 v[44:47], v[144:147], v[198:201], v[44:47]
	v_mfma_f32_16x16x32_bf16 v[40:43], v[160:163], v[198:201], v[40:43]
	v_mfma_f32_16x16x32_bf16 v[36:39], v[172:175], v[198:201], v[36:39]
	v_mfma_f32_16x16x32_bf16 v[32:35], v[182:185], v[198:201], v[32:35]
	v_mfma_f32_16x16x32_bf16 v[28:31], v[144:147], v[212:215], v[28:31]
	v_mfma_f32_16x16x32_bf16 v[24:27], v[160:163], v[212:215], v[24:27]
	v_mfma_f32_16x16x32_bf16 v[20:23], v[172:175], v[212:215], v[20:23]
	v_mfma_f32_16x16x32_bf16 v[16:19], v[182:185], v[212:215], v[16:19]
	v_mfma_f32_16x16x32_bf16 v[12:15], v[144:147], v[220:223], v[12:15]
	v_mfma_f32_16x16x32_bf16 v[8:11], v[160:163], v[220:223], v[8:11]
	v_lshl_add_u64 v[228:229], s[54:55], 0, v[134:135]
	s_mov_b32 m0, s45
	s_nop 0
	global_load_lds_dwordx4 v[228:229], off
	v_mfma_f32_16x16x32_bf16 v[4:7], v[172:175], v[220:223], v[4:7]
	v_mfma_f32_16x16x32_bf16 v[0:3], v[182:185], v[220:223], v[0:3]
	s_setprio 0
	s_setprio 1
	v_mfma_f32_16x16x32_bf16 v[60:63], v[148:151], v[194:197], v[60:63]
	v_mfma_f32_16x16x32_bf16 v[56:59], v[168:171], v[194:197], v[56:59]
	v_mfma_f32_16x16x32_bf16 v[52:55], v[176:179], v[194:197], v[52:55]
	v_mfma_f32_16x16x32_bf16 v[48:51], v[186:189], v[194:197], v[48:51]
	v_mfma_f32_16x16x32_bf16 v[44:47], v[148:151], v[208:211], v[44:47]
	v_mfma_f32_16x16x32_bf16 v[40:43], v[168:171], v[208:211], v[40:43]
	v_mfma_f32_16x16x32_bf16 v[36:39], v[176:179], v[208:211], v[36:39]
	v_mfma_f32_16x16x32_bf16 v[32:35], v[186:189], v[208:211], v[32:35]
	v_mfma_f32_16x16x32_bf16 v[28:31], v[148:151], v[216:219], v[28:31]
	v_mfma_f32_16x16x32_bf16 v[24:27], v[168:171], v[216:219], v[24:27]
	v_mfma_f32_16x16x32_bf16 v[20:23], v[176:179], v[216:219], v[20:23]
	v_mfma_f32_16x16x32_bf16 v[16:19], v[186:189], v[216:219], v[16:19]
	v_mfma_f32_16x16x32_bf16 v[12:15], v[148:151], v[224:227], v[12:15]
	v_mfma_f32_16x16x32_bf16 v[8:11], v[168:171], v[224:227], v[8:11]
	v_lshl_add_u64 v[230:231], s[54:55], 0, v[130:131]
	s_mov_b32 m0, s57
	s_nop 0
	global_load_lds_dwordx4 v[230:231], off
	v_mfma_f32_16x16x32_bf16 v[4:7], v[176:179], v[224:227], v[4:7]
	v_mfma_f32_16x16x32_bf16 v[0:3], v[186:189], v[224:227], v[0:3]
	s_setprio 0
	s_barrier
; #define PG8_STAGE(bufoff, gbase, voff) do { _Pragma("unroll") for (int _i = 0; _i < 2; ++_i) \
;         __builtin_amdgcn_global_load_lds((const unsigned*)((const char*)(gbase) + (voff)[_i]), (PG8_LAS unsigned*)(lds + (bufoff) + ldsw + _i * 8192), 16, 0, 0); } while (0)
; #define PG8_LDA(dst, b, h) do { _Pragma("unroll") for (int m = 0; m < 4; ++m) _Pragma("unroll") for (int k = 0; k < 2; ++k) dst[m][k] = *(const PG8_LAS bf16x8*)(lds + PG8_SA(b, h) + aoff + m * 2048 + k * 1024); } while (0)
; #define PG8_LDB(dst, b, h) do { _Pragma("unroll") for (int n = 0; n < 2; ++n) _Pragma("unroll") for (int k = 0; k < 2; ++k) dst[n][k] = *(const PG8_LAS bf16x8*)(lds + PG8_SB(b, h) + boff + n * 2048 + k * 1024); } while (0)
; #define PG8_MMA(ai, bj, At, Bt) do { __builtin_amdgcn_s_setprio(1); _Pragma("unroll") for (int m = 0; m < 4; ++m) _Pragma("unroll") for (int n = 0; n < 2; ++n) _Pragma("unroll") for (int k = 0; k < 2; ++k) \
;         acc[ai][bj][m][n] = __builtin_amdgcn_mfma_f32_16x16x32_bf16(Bt[n][k], At[m][k], acc[ai][bj][m][n], 0, 0, 0); __builtin_amdgcn_s_setprio(0); } while (0)
; #define PG8_WAIT_V(n) asm volatile("s_waitcnt vmcnt(" #n ")" ::: "memory")
; #define PG8_WAIT_L(n) asm volatile("s_waitcnt lgkmcnt(" #n ")" ::: "memory")
; #define PG8_BAR __builtin_amdgcn_s_barrier()
; #define PG8_SCHED __builtin_amdgcn_sched_barrier(0)
; template <class Epi, class Sched, bool ALIGN_EPI = false, bool SP2 = false>
; __device__ __forceinline__ void gemm_phase(PG8_LAS unsigned char* lds, const Gemm g, const Sched& S, const Epi& E) {
;     ...
;             PG8_LDB(B0, 1, 0); PG8_LDB(B1, 1, 1); PG8_SCHED; PG8_LDA(At, 1, 0); PG8_STAGE(PG8_SA(0, 1), a2 + hstep, voffA);
;             PG8_WAIT_V(8); PG8_WAIT_L(0); PG8_BAR; PG8_MMA(0, 0, At, B0); PG8_MMA(0, 1, At, B1); PG8_BAR; PG8_SCHED;
	s_add_i32 s3, 0, 0x18000
	v_add_u32_e32 v159, s3, v153
	s_add_i32 s33, 0, 0x1c000
	ds_read_b128 v[144:147], v159
	ds_read_b128 v[148:151], v159 offset:1024
	ds_read_b128 v[160:163], v159 offset:2048
	ds_read_b128 v[168:171], v159 offset:3072
	v_add_u32_e32 v159, s33, v153
	ds_read_b128 v[172:175], v159
	ds_read_b128 v[176:179], v159 offset:1024
	ds_read_b128 v[182:185], v159 offset:2048
	ds_read_b128 v[186:189], v159 offset:3072
	s_add_u32 s14, s54, 0x40000
	s_addc_u32 s15, s55, 0
	s_mov_b32 m0, s58
	v_lshl_add_u64 v[232:233], s[14:15], 0, v[134:135]
	ds_read_b128 v[190:193], v157 offset:32768
	ds_read_b128 v[194:197], v157 offset:33792
	ds_read_b128 v[198:201], v157 offset:34816
	ds_read_b128 v[208:211], v157 offset:35840
	ds_read_b128 v[212:215], v157 offset:36864
	ds_read_b128 v[216:219], v157 offset:37888
	ds_read_b128 v[220:223], v157 offset:38912
	ds_read_b128 v[224:227], v157 offset:39936
	global_load_lds_dwordx4 v[232:233], off
	v_lshl_add_u64 v[232:233], s[14:15], 0, v[130:131]
	s_mov_b32 m0, s59
	s_nop 0
	global_load_lds_dwordx4 v[232:233], off
	s_waitcnt vmcnt(8)
	s_waitcnt lgkmcnt(0)
	s_barrier
	s_setprio 1
	s_waitcnt lgkmcnt(0)
	v_mfma_f32_16x16x32_bf16 v[124:127], v[144:147], v[190:193], v[124:127]
	v_mfma_f32_16x16x32_bf16 v[120:123], v[160:163], v[190:193], v[120:123]
	v_mfma_f32_16x16x32_bf16 v[116:119], v[172:175], v[190:193], v[116:119]
	v_mfma_f32_16x16x32_bf16 v[112:115], v[182:185], v[190:193], v[112:115]
	v_mfma_f32_16x16x32_bf16 v[108:111], v[144:147], v[198:201], v[108:111]
	v_mfma_f32_16x16x32_bf16 v[104:107], v[160:163], v[198:201], v[104:107]
	v_mfma_f32_16x16x32_bf16 v[100:103], v[172:175], v[198:201], v[100:103]
	v_mfma_f32_16x16x32_bf16 v[96:99], v[182:185], v[198:201], v[96:99]
	v_mfma_f32_16x16x32_bf16 v[92:95], v[144:147], v[212:215], v[92:95]
	v_mfma_f32_16x16x32_bf16 v[88:91], v[160:163], v[212:215], v[88:91]
	v_mfma_f32_16x16x32_bf16 v[84:87], v[172:175], v[212:215], v[84:87]
	v_mfma_f32_16x16x32_bf16 v[80:83], v[182:185], v[212:215], v[80:83]
	v_mfma_f32_16x16x32_bf16 v[76:79], v[144:147], v[220:223], v[76:79]
	v_mfma_f32_16x16x32_bf16 v[72:75], v[160:163], v[220:223], v[72:75]
	v_mfma_f32_16x16x32_bf16 v[68:71], v[172:175], v[220:223], v[68:71]
	v_mfma_f32_16x16x32_bf16 v[64:67], v[182:185], v[220:223], v[64:67]
	s_setprio 0
	s_setprio 1
	v_mfma_f32_16x16x32_bf16 v[124:127], v[148:151], v[194:197], v[124:127]
	v_mfma_f32_16x16x32_bf16 v[120:123], v[168:171], v[194:197], v[120:123]
	v_mfma_f32_16x16x32_bf16 v[116:119], v[176:179], v[194:197], v[116:119]
	v_mfma_f32_16x16x32_bf16 v[112:115], v[186:189], v[194:197], v[112:115]
	v_mfma_f32_16x16x32_bf16 v[108:111], v[148:151], v[208:211], v[108:111]
	v_mfma_f32_16x16x32_bf16 v[104:107], v[168:171], v[208:211], v[104:107]
	v_mfma_f32_16x16x32_bf16 v[100:103], v[176:179], v[208:211], v[100:103]
	v_mfma_f32_16x16x32_bf16 v[96:99], v[186:189], v[208:211], v[96:99]
	v_mfma_f32_16x16x32_bf16 v[92:95], v[148:151], v[216:219], v[92:95]
	v_mfma_f32_16x16x32_bf16 v[88:91], v[168:171], v[216:219], v[88:91]
	v_mfma_f32_16x16x32_bf16 v[84:87], v[176:179], v[216:219], v[84:87]
	v_mfma_f32_16x16x32_bf16 v[80:83], v[186:189], v[216:219], v[80:83]
	v_mfma_f32_16x16x32_bf16 v[76:79], v[148:151], v[224:227], v[76:79]
	v_mfma_f32_16x16x32_bf16 v[72:75], v[168:171], v[224:227], v[72:75]
	v_mfma_f32_16x16x32_bf16 v[68:71], v[176:179], v[224:227], v[68:71]
	v_mfma_f32_16x16x32_bf16 v[64:67], v[186:189], v[224:227], v[64:67]
	s_setprio 0
	s_barrier
; #define PG8_STAGE(bufoff, gbase, voff) do { _Pragma("unroll") for (int _i = 0; _i < 2; ++_i) \
;         __builtin_amdgcn_global_load_lds((const unsigned*)((const char*)(gbase) + (voff)[_i]), (PG8_LAS unsigned*)(lds + (bufoff) + ldsw + _i * 8192), 16, 0, 0); } while (0)
; #define PG8_LDA(dst, b, h) do { _Pragma("unroll") for (int m = 0; m < 4; ++m) _Pragma("unroll") for (int k = 0; k < 2; ++k) dst[m][k] = *(const PG8_LAS bf16x8*)(lds + PG8_SA(b, h) + aoff + m * 2048 + k * 1024); } while (0)
; #define PG8_MMA(ai, bj, At, Bt) do { __builtin_amdgcn_s_setprio(1); _Pragma("unroll") for (int m = 0; m < 4; ++m) _Pragma("unroll") for (int n = 0; n < 2; ++n) _Pragma("unroll") for (int k = 0; k < 2; ++k) \
;         acc[ai][bj][m][n] = __builtin_amdgcn_mfma_f32_16x16x32_bf16(Bt[n][k], At[m][k], acc[ai][bj][m][n], 0, 0, 0); __builtin_amdgcn_s_setprio(0); } while (0)
; #define PG8_WAIT_V(n) asm volatile("s_waitcnt vmcnt(" #n ")" ::: "memory")
; #define PG8_WAIT_L(n) asm volatile("s_waitcnt lgkmcnt(" #n ")" ::: "memory")
; #define PG8_BAR __builtin_amdgcn_s_barrier()
; #define PG8_SCHED __builtin_amdgcn_sched_barrier(0)
; __device__ __forceinline__ float row_rs(const float* ssp, int row) { const unsigned long long v = ((const unsigned long long*)ssp)[row];
;     return __builtin_amdgcn_rsqf((float)v * (1.0f / 4294967296.0f) * (1.0f / 1024.0f) + RMS_EPS); }
; template <class Epi, class Sched, bool ALIGN_EPI = false, bool SP2 = false>
; __device__ __forceinline__ void gemm_phase(PG8_LAS unsigned char* lds, const Gemm g, const Sched& S, const Epi& E) {
;     ...
;             PG8_LDA(At, 1, 1); PG8_STAGE(PG8_SB(1, 0), b3, voffB); PG8_STAGE(PG8_SB(1, 1), b3 + hstep, voffB); PG8_STAGE(PG8_SA(1, 0), a3, voffA);
;             PG8_WAIT_V(8); PG8_WAIT_L(0); PG8_BAR; PG8_MMA(1, 0, At, B0); PG8_MMA(1, 1, At, B1); PG8_BAR; PG8_SCHED;
	s_add_i32 s3, s3, s43
	v_lshl_add_u64 v[164:165], v[164:165], 0, s[10:11]
	s_mov_b32 m0, s3
	ds_read_b128 v[190:193], v157 offset:49152
	ds_read_b128 v[194:197], v157 offset:50176
	ds_read_b128 v[198:201], v157 offset:51200
	ds_read_b128 v[208:211], v157 offset:52224
	ds_read_b128 v[212:215], v157 offset:53248
	ds_read_b128 v[216:219], v157 offset:54272
	ds_read_b128 v[220:223], v157 offset:55296
	ds_read_b128 v[224:227], v157 offset:56320
	global_load_lds_dwordx4 v[164:165], off
	s_add_i32 m0, s3, 0x2000
	s_add_u32 s14, s50, 0x40080
	v_lshl_add_u64 v[164:165], v[202:203], 0, s[10:11]
	s_addc_u32 s15, s51, 0
	s_add_i32 s3, s33, s43
	global_load_lds_dwordx4 v[164:165], off
	v_lshl_add_u64 v[164:165], s[14:15], 0, v[132:133]
	s_mov_b32 m0, s3
	s_nop 0
	global_load_lds_dwordx4 v[164:165], off
	v_lshl_add_u64 v[164:165], s[14:15], 0, v[128:129]
	s_add_i32 m0, s3, 0x2000
	s_nop 0
	global_load_lds_dwordx4 v[164:165], off
	s_waitcnt vmcnt(6)
	s_waitcnt lgkmcnt(0)
	s_barrier
	s_setprio 1
	s_waitcnt lgkmcnt(0)
	v_mfma_f32_16x16x32_bf16 v[60:63], v[144:147], v[190:193], v[60:63]
	v_mfma_f32_16x16x32_bf16 v[56:59], v[160:163], v[190:193], v[56:59]
	v_mfma_f32_16x16x32_bf16 v[52:55], v[172:175], v[190:193], v[52:55]
	v_mfma_f32_16x16x32_bf16 v[48:51], v[182:185], v[190:193], v[48:51]
	v_mfma_f32_16x16x32_bf16 v[44:47], v[144:147], v[198:201], v[44:47]
	v_mfma_f32_16x16x32_bf16 v[40:43], v[160:163], v[198:201], v[40:43]
	v_mfma_f32_16x16x32_bf16 v[36:39], v[172:175], v[198:201], v[36:39]
	v_mfma_f32_16x16x32_bf16 v[32:35], v[182:185], v[198:201], v[32:35]
	v_mfma_f32_16x16x32_bf16 v[28:31], v[144:147], v[212:215], v[28:31]
	v_mfma_f32_16x16x32_bf16 v[24:27], v[160:163], v[212:215], v[24:27]
	v_mfma_f32_16x16x32_bf16 v[20:23], v[172:175], v[212:215], v[20:23]
	v_mfma_f32_16x16x32_bf16 v[16:19], v[182:185], v[212:215], v[16:19]
	v_mfma_f32_16x16x32_bf16 v[12:15], v[144:147], v[220:223], v[12:15]
	v_mfma_f32_16x16x32_bf16 v[8:11], v[160:163], v[220:223], v[8:11]
	v_lshl_add_u64 v[164:165], v[228:229], 0, s[10:11]
	s_mov_b32 m0, s61
	s_nop 0
	global_load_lds_dwordx4 v[164:165], off
	v_mfma_f32_16x16x32_bf16 v[4:7], v[172:175], v[220:223], v[4:7]
	v_mfma_f32_16x16x32_bf16 v[0:3], v[182:185], v[220:223], v[0:3]
	s_setprio 0
	s_setprio 1
	v_mfma_f32_16x16x32_bf16 v[60:63], v[148:151], v[194:197], v[60:63]
	v_mfma_f32_16x16x32_bf16 v[56:59], v[168:171], v[194:197], v[56:59]
	v_mfma_f32_16x16x32_bf16 v[52:55], v[176:179], v[194:197], v[52:55]
	v_mfma_f32_16x16x32_bf16 v[48:51], v[186:189], v[194:197], v[48:51]
	v_mfma_f32_16x16x32_bf16 v[44:47], v[148:151], v[208:211], v[44:47]
	v_mfma_f32_16x16x32_bf16 v[40:43], v[168:171], v[208:211], v[40:43]
	v_mfma_f32_16x16x32_bf16 v[36:39], v[176:179], v[208:211], v[36:39]
	v_mfma_f32_16x16x32_bf16 v[32:35], v[186:189], v[208:211], v[32:35]
	v_mfma_f32_16x16x32_bf16 v[28:31], v[148:151], v[216:219], v[28:31]
	v_mfma_f32_16x16x32_bf16 v[24:27], v[168:171], v[216:219], v[24:27]
	v_mfma_f32_16x16x32_bf16 v[20:23], v[176:179], v[216:219], v[20:23]
	v_mfma_f32_16x16x32_bf16 v[16:19], v[186:189], v[216:219], v[16:19]
	v_mfma_f32_16x16x32_bf16 v[12:15], v[148:151], v[224:227], v[12:15]
	v_mfma_f32_16x16x32_bf16 v[8:11], v[168:171], v[224:227], v[8:11]
	v_lshl_add_u64 v[164:165], v[230:231], 0, s[10:11]
	s_mov_b32 m0, s62
	s_nop 0
	global_load_lds_dwordx4 v[164:165], off
	v_mfma_f32_16x16x32_bf16 v[4:7], v[176:179], v[224:227], v[4:7]
	v_mfma_f32_16x16x32_bf16 v[0:3], v[186:189], v[224:227], v[0:3]
	s_setprio 0
	s_barrier
	s_add_i32 s89, s89, 2
	s_add_u32 s48, s48, 0x100
	s_addc_u32 s49, s49, 0
	s_add_u32 s87, s87, 0x100
	s_addc_u32 s88, s88, 0
	s_cmp_gt_u32 s89, 13
	s_cbranch_scc0 .LBB0_191
	v_lshl_add_u32 v144, s44, 8, v152
	v_ashrrev_i32_e32 v145, 31, v144
	v_lshl_add_u64 v[150:151], v[144:145], 3, s[6:7]
	global_load_dwordx2 v[182:183], v[150:151], off
	global_load_dwordx2 v[184:185], v[150:151], off offset:128
	global_load_dwordx2 v[186:187], v[150:151], off offset:256
	global_load_dwordx2 v[188:189], v[150:151], off offset:384
	global_load_dwordx2 v[190:191], v[150:151], off offset:1024
	global_load_dwordx2 v[192:193], v[150:151], off offset:1152
	global_load_dwordx2 v[194:195], v[150:151], off offset:1280
	global_load_dwordx2 v[196:197], v[150:151], off offset:1408
	s_and_b64 vcc, exec, s[16:17]
	s_cbranch_vccz .LBB0_194
	s_barrier

; #define PG8_STAGE(bufoff, gbase, voff) do { _Pragma("unroll") for (int _i = 0; _i < 2; ++_i) \
;         __builtin_amdgcn_global_load_lds((const unsigned*)((const char*)(gbase) + (voff)[_i]), (PG8_LAS unsigned*)(lds + (bufoff) + ldsw + _i * 8192), 16, 0, 0); } while (0)
; #define PG8_LDA(dst, b, h) do { _Pragma("unroll") for (int m = 0; m < 4; ++m) _Pragma("unroll") for (int k = 0; k < 2; ++k) dst[m][k] = *(const PG8_LAS bf16x8*)(lds + PG8_SA(b, h) + aoff + m * 2048 + k * 1024); } while (0)
; #define PG8_LDB(dst, b, h) do { _Pragma("unroll") for (int n = 0; n < 2; ++n) _Pragma("unroll") for (int k = 0; k < 2; ++k) dst[n][k] = *(const PG8_LAS bf16x8*)(lds + PG8_SB(b, h) + boff + n * 2048 + k * 1024); } while (0)
; #define PG8_MMA(ai, bj, At, Bt) do { __builtin_amdgcn_s_setprio(1); _Pragma("unroll") for (int m = 0; m < 4; ++m) _Pragma("unroll") for (int n = 0; n < 2; ++n) _Pragma("unroll") for (int k = 0; k < 2; ++k) \
;         acc[ai][bj][m][n] = __builtin_amdgcn_mfma_f32_16x16x32_bf16(Bt[n][k], At[m][k], acc[ai][bj][m][n], 0, 0, 0); __builtin_amdgcn_s_setprio(0); } while (0)
; #define PG8_WAIT_V(n) asm volatile("s_waitcnt vmcnt(" #n ")" ::: "memory")
; #define PG8_WAIT_L(n) asm volatile("s_waitcnt lgkmcnt(" #n ")" ::: "memory")
; #define PG8_BAR __builtin_amdgcn_s_barrier()
; #define PG8_SCHED __builtin_amdgcn_sched_barrier(0)
; template <class Epi, class Sched, bool ALIGN_EPI = false, bool SP2 = false>
; __device__ __forceinline__ void gemm_phase(PG8_LAS unsigned char* lds, const Gemm g, const Sched& S, const Epi& E) {
;     ...
;         for (int t = 0; t < nt; t += 2) {
;             const bool last = (t == nt - 2);
;             const char* a1 = cA + (size_t)(t + 1) * kstep;
;             const char* a2 = last ? nA : cA + (size_t)(t + 2) * kstep; const char* b2 = last ? nB : cB + (size_t)(t + 2) * kstep;
;             const char* a3 = a2 + kstep; const char* b3 = b2 + kstep;
;             if (last && has_next) S.a_ready(nxt);
;             if constexpr (SP2) {
;             PG8_LDB(B0, 0, 0); PG8_LDB(B1, 0, 1); PG8_SCHED; PG8_LDA(At, 0, 0); PG8_STAGE(PG8_SA(1, 1), a1 + hstep, voffA);
;             PG8_WAIT_V(8); PG8_WAIT_L(0); PG8_BAR; PG8_MMA(0, 0, At, B0); PG8_MMA(0, 1, At, B1); PG8_BAR; PG8_SCHED;
;             PG8_LDA(At, 0, 1); PG8_STAGE(PG8_SB(0, 0), b2, voffB); PG8_STAGE(PG8_SB(0, 1), b2 + hstep, voffB); PG8_STAGE(PG8_SA(0, 0), a2, voffA);
.LBB0_268:
	s_add_u32 s91, s50, 0x100
	s_addc_u32 s92, s51, 0
	s_mov_b32 s93, -2
	s_waitcnt lgkmcnt(0)
	ds_read_b128 v[128:131], v165
	ds_read_b128 v[132:135], v165 offset:1024
	ds_read_b128 v[152:155], v165 offset:2048
	ds_read_b128 v[156:159], v165 offset:3072
	ds_read_b128 v[172:175], v168
	ds_read_b128 v[176:179], v168 offset:1024
	ds_read_b128 v[182:185], v168 offset:2048
	ds_read_b128 v[186:189], v168 offset:3072
	s_add_u32 s50, s10, 0x100
	s_addc_u32 s51, s11, 0
	s_cmp_eq_u32 s93, 40
	s_cselect_b32 s57, s1, s51
	s_cselect_b32 s56, s0, s50
	s_cselect_b32 s55, s49, s92
	s_cselect_b32 s54, s48, s91
	v_lshl_add_u64 v[160:161], s[10:11], 0, v[144:145]
	s_add_i32 m0, s58, 0xc000
	ds_read_b128 v[190:193], v169
	ds_read_b128 v[194:197], v169 offset:1024
	ds_read_b128 v[198:201], v169 offset:2048
	ds_read_b128 v[208:211], v169 offset:3072
	ds_read_b128 v[212:215], v169 offset:4096
	ds_read_b128 v[216:219], v169 offset:5120
	ds_read_b128 v[220:223], v169 offset:6144
	ds_read_b128 v[224:227], v169 offset:7168
	global_load_lds_dwordx4 v[160:161], off
	v_lshl_add_u64 v[160:161], s[10:11], 0, v[146:147]
	s_add_i32 m0, s58, 0xe000
	s_nop 0
	global_load_lds_dwordx4 v[160:161], off
	s_waitcnt vmcnt(8)
	s_waitcnt lgkmcnt(0)
	s_barrier
	s_setprio 1
	s_waitcnt lgkmcnt(0)
	v_mfma_f32_16x16x32_bf16 v[124:127], v[128:131], v[190:193], 0
	v_mfma_f32_16x16x32_bf16 v[120:123], v[152:155], v[190:193], 0
	v_mfma_f32_16x16x32_bf16 v[116:119], v[172:175], v[190:193], 0
	v_mfma_f32_16x16x32_bf16 v[112:115], v[182:185], v[190:193], 0
	v_mfma_f32_16x16x32_bf16 v[108:111], v[128:131], v[198:201], 0
	v_mfma_f32_16x16x32_bf16 v[104:107], v[152:155], v[198:201], 0
	v_mfma_f32_16x16x32_bf16 v[100:103], v[172:175], v[198:201], 0
	v_mfma_f32_16x16x32_bf16 v[96:99], v[182:185], v[198:201], 0
	v_mfma_f32_16x16x32_bf16 v[92:95], v[128:131], v[212:215], 0
	v_mfma_f32_16x16x32_bf16 v[88:91], v[152:155], v[212:215], 0
	v_mfma_f32_16x16x32_bf16 v[84:87], v[172:175], v[212:215], 0
	v_mfma_f32_16x16x32_bf16 v[80:83], v[182:185], v[212:215], 0
	v_mfma_f32_16x16x32_bf16 v[76:79], v[128:131], v[220:223], 0
	v_mfma_f32_16x16x32_bf16 v[72:75], v[152:155], v[220:223], 0
	v_mfma_f32_16x16x32_bf16 v[68:71], v[172:175], v[220:223], 0
	v_mfma_f32_16x16x32_bf16 v[64:67], v[182:185], v[220:223], 0
	s_setprio 0
	s_setprio 1
	v_mfma_f32_16x16x32_bf16 v[124:127], v[132:135], v[194:197], v[124:127]
	v_mfma_f32_16x16x32_bf16 v[120:123], v[156:159], v[194:197], v[120:123]
	v_mfma_f32_16x16x32_bf16 v[116:119], v[176:179], v[194:197], v[116:119]
	v_mfma_f32_16x16x32_bf16 v[112:115], v[186:189], v[194:197], v[112:115]
	v_mfma_f32_16x16x32_bf16 v[108:111], v[132:135], v[208:211], v[108:111]
	v_mfma_f32_16x16x32_bf16 v[104:107], v[156:159], v[208:211], v[104:107]
	v_mfma_f32_16x16x32_bf16 v[100:103], v[176:179], v[208:211], v[100:103]
	v_mfma_f32_16x16x32_bf16 v[96:99], v[186:189], v[208:211], v[96:99]
	v_mfma_f32_16x16x32_bf16 v[92:95], v[132:135], v[216:219], v[92:95]
	v_mfma_f32_16x16x32_bf16 v[88:91], v[156:159], v[216:219], v[88:91]
	v_mfma_f32_16x16x32_bf16 v[84:87], v[176:179], v[216:219], v[84:87]
	v_mfma_f32_16x16x32_bf16 v[80:83], v[186:189], v[216:219], v[80:83]
	v_mfma_f32_16x16x32_bf16 v[76:79], v[132:135], v[224:227], v[76:79]
	v_mfma_f32_16x16x32_bf16 v[72:75], v[156:159], v[224:227], v[72:75]
	v_mfma_f32_16x16x32_bf16 v[68:71], v[176:179], v[224:227], v[68:71]
	v_mfma_f32_16x16x32_bf16 v[64:67], v[186:189], v[224:227], v[64:67]
	s_setprio 0
	s_barrier
	s_add_i32 s3, s65, s43
	v_lshl_add_u64 v[160:161], s[54:55], 0, v[138:139]
	s_mov_b32 m0, s3
	ds_read_b128 v[190:193], v169 offset:16384
	ds_read_b128 v[194:197], v169 offset:17408
	ds_read_b128 v[198:201], v169 offset:18432
	ds_read_b128 v[208:211], v169 offset:19456
	ds_read_b128 v[212:215], v169 offset:20480
	ds_read_b128 v[216:219], v169 offset:21504
	ds_read_b128 v[220:223], v169 offset:22528
	ds_read_b128 v[224:227], v169 offset:23552
	global_load_lds_dwordx4 v[160:161], off
	s_add_i32 m0, s3, 0x2000
	s_add_u32 s10, s54, 0xb0000
	v_lshl_add_u64 v[202:203], s[54:55], 0, v[142:143]
	s_addc_u32 s11, s55, 0
	s_add_i32 s3, s66, s43
	global_load_lds_dwordx4 v[202:203], off
	v_lshl_add_u64 v[228:229], s[10:11], 0, v[138:139]
	s_mov_b32 m0, s3
	global_load_lds_dwordx4 v[228:229], off
	v_lshl_add_u64 v[228:229], s[10:11], 0, v[142:143]
	s_add_i32 m0, s3, 0x2000
	s_nop 0
	global_load_lds_dwordx4 v[228:229], off
	s_waitcnt vmcnt(6)
	s_waitcnt lgkmcnt(0)
	s_barrier
; #define PG8_STAGE(bufoff, gbase, voff) do { _Pragma("unroll") for (int _i = 0; _i < 2; ++_i) \
;         __builtin_amdgcn_global_load_lds((const unsigned*)((const char*)(gbase) + (voff)[_i]), (PG8_LAS unsigned*)(lds + (bufoff) + ldsw + _i * 8192), 16, 0, 0); } while (0)
; #define PG8_LDA(dst, b, h) do { _Pragma("unroll") for (int m = 0; m < 4; ++m) _Pragma("unroll") for (int k = 0; k < 2; ++k) dst[m][k] = *(const PG8_LAS bf16x8*)(lds + PG8_SA(b, h) + aoff + m * 2048 + k * 1024); } while (0)
; #define PG8_LDB(dst, b, h) do { _Pragma("unroll") for (int n = 0; n < 2; ++n) _Pragma("unroll") for (int k = 0; k < 2; ++k) dst[n][k] = *(const PG8_LAS bf16x8*)(lds + PG8_SB(b, h) + boff + n * 2048 + k * 1024); } while (0)
; #define PG8_MMA(ai, bj, At, Bt) do { __builtin_amdgcn_s_setprio(1); _Pragma("unroll") for (int m = 0; m < 4; ++m) _Pragma("unroll") for (int n = 0; n < 2; ++n) _Pragma("unroll") for (int k = 0; k < 2; ++k) \
;         acc[ai][bj][m][n] = __builtin_amdgcn_mfma_f32_16x16x32_bf16(Bt[n][k], At[m][k], acc[ai][bj][m][n], 0, 0, 0); __builtin_amdgcn_s_setprio(0); } while (0)
; #define PG8_WAIT_V(n) asm volatile("s_waitcnt vmcnt(" #n ")" ::: "memory")
; #define PG8_WAIT_L(n) asm volatile("s_waitcnt lgkmcnt(" #n ")" ::: "memory")
; #define PG8_BAR __builtin_amdgcn_s_barrier()
; #define PG8_SCHED __builtin_amdgcn_sched_barrier(0)
; template <class Epi, class Sched, bool ALIGN_EPI = false, bool SP2 = false>
; __device__ __forceinline__ void gemm_phase(PG8_LAS unsigned char* lds, const Gemm g, const Sched& S, const Epi& E) {
;     ...
;             PG8_WAIT_V(8); PG8_WAIT_L(0); PG8_BAR; PG8_MMA(1, 0, At, B0); PG8_MMA(1, 1, At, B1); PG8_BAR; PG8_SCHED;
;             PG8_LDB(B0, 1, 0); PG8_LDB(B1, 1, 1); PG8_SCHED; PG8_LDA(At, 1, 0); PG8_STAGE(PG8_SA(0, 1), a2 + hstep, voffA);
;             PG8_WAIT_V(8); PG8_WAIT_L(0); PG8_BAR; PG8_MMA(0, 0, At, B0); PG8_MMA(0, 1, At, B1); PG8_BAR; PG8_SCHED;
	s_setprio 1
	s_waitcnt lgkmcnt(0)
	v_mfma_f32_16x16x32_bf16 v[60:63], v[128:131], v[190:193], 0
	v_mfma_f32_16x16x32_bf16 v[56:59], v[152:155], v[190:193], 0
	v_mfma_f32_16x16x32_bf16 v[52:55], v[172:175], v[190:193], 0
	v_mfma_f32_16x16x32_bf16 v[48:51], v[182:185], v[190:193], 0
	v_mfma_f32_16x16x32_bf16 v[44:47], v[128:131], v[198:201], 0
	v_mfma_f32_16x16x32_bf16 v[40:43], v[152:155], v[198:201], 0
	v_mfma_f32_16x16x32_bf16 v[36:39], v[172:175], v[198:201], 0
	v_mfma_f32_16x16x32_bf16 v[32:35], v[182:185], v[198:201], 0
	v_mfma_f32_16x16x32_bf16 v[28:31], v[128:131], v[212:215], 0
	v_mfma_f32_16x16x32_bf16 v[24:27], v[152:155], v[212:215], 0
	v_mfma_f32_16x16x32_bf16 v[20:23], v[172:175], v[212:215], 0
	v_mfma_f32_16x16x32_bf16 v[16:19], v[182:185], v[212:215], 0
	v_mfma_f32_16x16x32_bf16 v[12:15], v[128:131], v[220:223], 0
	v_mfma_f32_16x16x32_bf16 v[8:11], v[152:155], v[220:223], 0
	v_lshl_add_u64 v[228:229], s[56:57], 0, v[136:137]
	s_mov_b32 m0, s58
	s_nop 0
	global_load_lds_dwordx4 v[228:229], off
	v_mfma_f32_16x16x32_bf16 v[4:7], v[172:175], v[220:223], 0
	v_mfma_f32_16x16x32_bf16 v[0:3], v[182:185], v[220:223], 0
	s_setprio 0
	s_setprio 1
	v_mfma_f32_16x16x32_bf16 v[60:63], v[132:135], v[194:197], v[60:63]
	v_mfma_f32_16x16x32_bf16 v[56:59], v[156:159], v[194:197], v[56:59]
	v_mfma_f32_16x16x32_bf16 v[52:55], v[176:179], v[194:197], v[52:55]
	v_mfma_f32_16x16x32_bf16 v[48:51], v[186:189], v[194:197], v[48:51]
	v_mfma_f32_16x16x32_bf16 v[44:47], v[132:135], v[208:211], v[44:47]
	v_mfma_f32_16x16x32_bf16 v[40:43], v[156:159], v[208:211], v[40:43]
	v_mfma_f32_16x16x32_bf16 v[36:39], v[176:179], v[208:211], v[36:39]
	v_mfma_f32_16x16x32_bf16 v[32:35], v[186:189], v[208:211], v[32:35]
	v_mfma_f32_16x16x32_bf16 v[28:31], v[132:135], v[216:219], v[28:31]
	v_mfma_f32_16x16x32_bf16 v[24:27], v[156:159], v[216:219], v[24:27]
	v_mfma_f32_16x16x32_bf16 v[20:23], v[176:179], v[216:219], v[20:23]
	v_mfma_f32_16x16x32_bf16 v[16:19], v[186:189], v[216:219], v[16:19]
	v_mfma_f32_16x16x32_bf16 v[12:15], v[132:135], v[224:227], v[12:15]
	v_mfma_f32_16x16x32_bf16 v[8:11], v[156:159], v[224:227], v[8:11]
	v_lshl_add_u64 v[230:231], s[56:57], 0, v[140:141]
	s_mov_b32 m0, s59
	s_nop 0
	global_load_lds_dwordx4 v[230:231], off
	v_mfma_f32_16x16x32_bf16 v[4:7], v[176:179], v[224:227], v[4:7]
	v_mfma_f32_16x16x32_bf16 v[0:3], v[186:189], v[224:227], v[0:3]
	s_setprio 0
	s_barrier
	s_add_i32 s3, 0, 0x18000
	s_add_i32 s14, 0, 0x1c000
	v_add_u32_e32 v156, s3, v163
	v_add_u32_e32 v171, s14, v163
	ds_read_b128 v[128:131], v156
	ds_read_b128 v[132:135], v156 offset:1024
	ds_read_b128 v[152:155], v156 offset:2048
	ds_read_b128 v[156:159], v156 offset:3072
	ds_read_b128 v[172:175], v171
	ds_read_b128 v[176:179], v171 offset:1024
	ds_read_b128 v[182:185], v171 offset:2048
	ds_read_b128 v[186:189], v171 offset:3072
	s_add_u32 s10, s56, 0xb0000
	s_addc_u32 s11, s57, 0
	s_mov_b32 m0, s60
	v_lshl_add_u64 v[232:233], s[10:11], 0, v[136:137]
	ds_read_b128 v[190:193], v169 offset:32768
	ds_read_b128 v[194:197], v169 offset:33792
	ds_read_b128 v[198:201], v169 offset:34816
	ds_read_b128 v[208:211], v169 offset:35840
	ds_read_b128 v[212:215], v169 offset:36864
	ds_read_b128 v[216:219], v169 offset:37888
	ds_read_b128 v[220:223], v169 offset:38912
	ds_read_b128 v[224:227], v169 offset:39936
	global_load_lds_dwordx4 v[232:233], off
	v_lshl_add_u64 v[232:233], s[10:11], 0, v[140:141]
	s_mov_b32 m0, s61
	s_nop 0
	global_load_lds_dwordx4 v[232:233], off
	s_waitcnt vmcnt(8)
	s_waitcnt lgkmcnt(0)
	s_barrier
	s_setprio 1
	s_waitcnt lgkmcnt(0)
	v_mfma_f32_16x16x32_bf16 v[124:127], v[128:131], v[190:193], v[124:127]
	v_mfma_f32_16x16x32_bf16 v[120:123], v[152:155], v[190:193], v[120:123]
	v_mfma_f32_16x16x32_bf16 v[116:119], v[172:175], v[190:193], v[116:119]
	v_mfma_f32_16x16x32_bf16 v[112:115], v[182:185], v[190:193], v[112:115]
	v_mfma_f32_16x16x32_bf16 v[108:111], v[128:131], v[198:201], v[108:111]
	v_mfma_f32_16x16x32_bf16 v[104:107], v[152:155], v[198:201], v[104:107]
	v_mfma_f32_16x16x32_bf16 v[100:103], v[172:175], v[198:201], v[100:103]
	v_mfma_f32_16x16x32_bf16 v[96:99], v[182:185], v[198:201], v[96:99]
	v_mfma_f32_16x16x32_bf16 v[92:95], v[128:131], v[212:215], v[92:95]
	v_mfma_f32_16x16x32_bf16 v[88:91], v[152:155], v[212:215], v[88:91]
	v_mfma_f32_16x16x32_bf16 v[84:87], v[172:175], v[212:215], v[84:87]
	v_mfma_f32_16x16x32_bf16 v[80:83], v[182:185], v[212:215], v[80:83]
	v_mfma_f32_16x16x32_bf16 v[76:79], v[128:131], v[220:223], v[76:79]
	v_mfma_f32_16x16x32_bf16 v[72:75], v[152:155], v[220:223], v[72:75]
	v_mfma_f32_16x16x32_bf16 v[68:71], v[172:175], v[220:223], v[68:71]
	v_mfma_f32_16x16x32_bf16 v[64:67], v[182:185], v[220:223], v[64:67]
	s_setprio 0
	s_setprio 1
	v_mfma_f32_16x16x32_bf16 v[124:127], v[132:135], v[194:197], v[124:127]
	v_mfma_f32_16x16x32_bf16 v[120:123], v[156:159], v[194:197], v[120:123]
	v_mfma_f32_16x16x32_bf16 v[116:119], v[176:179], v[194:197], v[116:119]
	v_mfma_f32_16x16x32_bf16 v[112:115], v[186:189], v[194:197], v[112:115]
	v_mfma_f32_16x16x32_bf16 v[108:111], v[132:135], v[208:211], v[108:111]
	v_mfma_f32_16x16x32_bf16 v[104:107], v[156:159], v[208:211], v[104:107]
	v_mfma_f32_16x16x32_bf16 v[100:103], v[176:179], v[208:211], v[100:103]
	v_mfma_f32_16x16x32_bf16 v[96:99], v[186:189], v[208:211], v[96:99]
	v_mfma_f32_16x16x32_bf16 v[92:95], v[132:135], v[216:219], v[92:95]
	v_mfma_f32_16x16x32_bf16 v[88:91], v[156:159], v[216:219], v[88:91]
	v_mfma_f32_16x16x32_bf16 v[84:87], v[176:179], v[216:219], v[84:87]
	v_mfma_f32_16x16x32_bf16 v[80:83], v[186:189], v[216:219], v[80:83]
	v_mfma_f32_16x16x32_bf16 v[76:79], v[132:135], v[224:227], v[76:79]
	v_mfma_f32_16x16x32_bf16 v[72:75], v[156:159], v[224:227], v[72:75]
	v_mfma_f32_16x16x32_bf16 v[68:71], v[176:179], v[224:227], v[68:71]
	v_mfma_f32_16x16x32_bf16 v[64:67], v[186:189], v[224:227], v[64:67]
	s_setprio 0
	s_barrier
; #define PG8_STAGE(bufoff, gbase, voff) do { _Pragma("unroll") for (int _i = 0; _i < 2; ++_i) \
;         __builtin_amdgcn_global_load_lds((const unsigned*)((const char*)(gbase) + (voff)[_i]), (PG8_LAS unsigned*)(lds + (bufoff) + ldsw + _i * 8192), 16, 0, 0); } while (0)
; #define PG8_LDA(dst, b, h) do { _Pragma("unroll") for (int m = 0; m < 4; ++m) _Pragma("unroll") for (int k = 0; k < 2; ++k) dst[m][k] = *(const PG8_LAS bf16x8*)(lds + PG8_SA(b, h) + aoff + m * 2048 + k * 1024); } while (0)
; #define PG8_LDB(dst, b, h) do { _Pragma("unroll") for (int n = 0; n < 2; ++n) _Pragma("unroll") for (int k = 0; k < 2; ++k) dst[n][k] = *(const PG8_LAS bf16x8*)(lds + PG8_SB(b, h) + boff + n * 2048 + k * 1024); } while (0)
; #define PG8_MMA(ai, bj, At, Bt) do { __builtin_amdgcn_s_setprio(1); _Pragma("unroll") for (int m = 0; m < 4; ++m) _Pragma("unroll") for (int n = 0; n < 2; ++n) _Pragma("unroll") for (int k = 0; k < 2; ++k) \
;         acc[ai][bj][m][n] = __builtin_amdgcn_mfma_f32_16x16x32_bf16(Bt[n][k], At[m][k], acc[ai][bj][m][n], 0, 0, 0); __builtin_amdgcn_s_setprio(0); } while (0)
; #define PG8_WAIT_V(n) asm volatile("s_waitcnt vmcnt(" #n ")" ::: "memory")
; #define PG8_WAIT_L(n) asm volatile("s_waitcnt lgkmcnt(" #n ")" ::: "memory")
; #define PG8_BAR __builtin_amdgcn_s_barrier()
; #define PG8_SCHED __builtin_amdgcn_sched_barrier(0)
; template <class Epi, class Sched, bool ALIGN_EPI = false, bool SP2 = false>
; __device__ __forceinline__ void gemm_phase(PG8_LAS unsigned char* lds, const Gemm g, const Sched& S, const Epi& E) {
;     ...
;             PG8_LDB(B0, 0, 0); PG8_LDB(B1, 0, 1); PG8_SCHED; PG8_LDA(At, 0, 0); PG8_STAGE(PG8_SA(1, 1), a1 + hstep, voffA);
;             PG8_WAIT_V(8); PG8_WAIT_L(0); PG8_BAR; PG8_MMA(0, 0, At, B0); PG8_MMA(0, 1, At, B1); PG8_BAR; PG8_SCHED;
;     ...
;             PG8_LDA(At, 1, 1); PG8_STAGE(PG8_SB(1, 0), b3, voffB); PG8_STAGE(PG8_SB(1, 1), b3 + hstep, voffB); PG8_STAGE(PG8_SA(1, 0), a3, voffA);
;             PG8_WAIT_V(8); PG8_WAIT_L(0); PG8_BAR; PG8_MMA(1, 0, At, B0); PG8_MMA(1, 1, At, B1); PG8_BAR; PG8_SCHED;
	s_add_i32 s3, s3, s43
	v_lshl_add_u64 v[160:161], v[160:161], 0, s[40:41]
	s_mov_b32 m0, s3
	ds_read_b128 v[190:193], v169 offset:49152
	ds_read_b128 v[194:197], v169 offset:50176
	ds_read_b128 v[198:201], v169 offset:51200
	ds_read_b128 v[208:211], v169 offset:52224
	ds_read_b128 v[212:215], v169 offset:53248
	ds_read_b128 v[216:219], v169 offset:54272
	ds_read_b128 v[220:223], v169 offset:55296
	ds_read_b128 v[224:227], v169 offset:56320
	global_load_lds_dwordx4 v[160:161], off
	s_add_i32 m0, s3, 0x2000
	s_add_u32 s10, s54, 0xb0080
	v_lshl_add_u64 v[160:161], v[202:203], 0, s[40:41]
	s_addc_u32 s11, s55, 0
	s_add_i32 s3, s14, s43
	global_load_lds_dwordx4 v[160:161], off
	v_lshl_add_u64 v[160:161], s[10:11], 0, v[138:139]
	s_mov_b32 m0, s3
	s_nop 0
	global_load_lds_dwordx4 v[160:161], off
	v_lshl_add_u64 v[160:161], s[10:11], 0, v[142:143]
	s_add_i32 m0, s3, 0x2000
	s_nop 0
	global_load_lds_dwordx4 v[160:161], off
	s_waitcnt vmcnt(6)
	s_waitcnt lgkmcnt(0)
	s_barrier
	s_setprio 1
	s_waitcnt lgkmcnt(0)
	v_mfma_f32_16x16x32_bf16 v[60:63], v[128:131], v[190:193], v[60:63]
	v_mfma_f32_16x16x32_bf16 v[56:59], v[152:155], v[190:193], v[56:59]
	v_mfma_f32_16x16x32_bf16 v[52:55], v[172:175], v[190:193], v[52:55]
	v_mfma_f32_16x16x32_bf16 v[48:51], v[182:185], v[190:193], v[48:51]
	v_mfma_f32_16x16x32_bf16 v[44:47], v[128:131], v[198:201], v[44:47]
	v_mfma_f32_16x16x32_bf16 v[40:43], v[152:155], v[198:201], v[40:43]
	v_mfma_f32_16x16x32_bf16 v[36:39], v[172:175], v[198:201], v[36:39]
	v_mfma_f32_16x16x32_bf16 v[32:35], v[182:185], v[198:201], v[32:35]
	v_mfma_f32_16x16x32_bf16 v[28:31], v[128:131], v[212:215], v[28:31]
	v_mfma_f32_16x16x32_bf16 v[24:27], v[152:155], v[212:215], v[24:27]
	v_mfma_f32_16x16x32_bf16 v[20:23], v[172:175], v[212:215], v[20:23]
	v_mfma_f32_16x16x32_bf16 v[16:19], v[182:185], v[212:215], v[16:19]
	v_mfma_f32_16x16x32_bf16 v[12:15], v[128:131], v[220:223], v[12:15]
	v_mfma_f32_16x16x32_bf16 v[8:11], v[152:155], v[220:223], v[8:11]
	v_lshl_add_u64 v[160:161], v[228:229], 0, s[40:41]
	s_mov_b32 m0, s63
	s_nop 0
	global_load_lds_dwordx4 v[160:161], off
	v_mfma_f32_16x16x32_bf16 v[4:7], v[172:175], v[220:223], v[4:7]
	v_mfma_f32_16x16x32_bf16 v[0:3], v[182:185], v[220:223], v[0:3]
	s_setprio 0
	s_setprio 1
	v_mfma_f32_16x16x32_bf16 v[60:63], v[132:135], v[194:197], v[60:63]
	v_mfma_f32_16x16x32_bf16 v[56:59], v[156:159], v[194:197], v[56:59]
	v_mfma_f32_16x16x32_bf16 v[52:55], v[176:179], v[194:197], v[52:55]
	v_mfma_f32_16x16x32_bf16 v[48:51], v[186:189], v[194:197], v[48:51]
	v_mfma_f32_16x16x32_bf16 v[44:47], v[132:135], v[208:211], v[44:47]
	v_mfma_f32_16x16x32_bf16 v[40:43], v[156:159], v[208:211], v[40:43]
	v_mfma_f32_16x16x32_bf16 v[36:39], v[176:179], v[208:211], v[36:39]
	v_mfma_f32_16x16x32_bf16 v[32:35], v[186:189], v[208:211], v[32:35]
	v_mfma_f32_16x16x32_bf16 v[28:31], v[132:135], v[216:219], v[28:31]
	v_mfma_f32_16x16x32_bf16 v[24:27], v[156:159], v[216:219], v[24:27]
	v_mfma_f32_16x16x32_bf16 v[20:23], v[176:179], v[216:219], v[20:23]
	v_mfma_f32_16x16x32_bf16 v[16:19], v[186:189], v[216:219], v[16:19]
	v_mfma_f32_16x16x32_bf16 v[12:15], v[132:135], v[224:227], v[12:15]
	v_mfma_f32_16x16x32_bf16 v[8:11], v[156:159], v[224:227], v[8:11]
	v_lshl_add_u64 v[160:161], v[230:231], 0, s[40:41]
	s_mov_b32 m0, s64
	s_nop 0
	global_load_lds_dwordx4 v[160:161], off
	v_mfma_f32_16x16x32_bf16 v[4:7], v[176:179], v[224:227], v[4:7]
	v_mfma_f32_16x16x32_bf16 v[0:3], v[186:189], v[224:227], v[0:3]
	s_setprio 0
	s_barrier
	s_add_i32 s93, s93, 2
	s_add_u32 s91, s91, 0x100
	s_addc_u32 s92, s92, 0
	s_mov_b64 s[10:11], s[50:51]
.LBB0_269:
	ds_read_b128 v[128:131], v165
	ds_read_b128 v[132:135], v165 offset:1024
	ds_read_b128 v[152:155], v165 offset:2048
	ds_read_b128 v[156:159], v165 offset:3072
	ds_read_b128 v[172:175], v168
	ds_read_b128 v[176:179], v168 offset:1024
	ds_read_b128 v[182:185], v168 offset:2048
	ds_read_b128 v[186:189], v168 offset:3072
	s_add_u32 s50, s10, 0x100
	s_addc_u32 s51, s11, 0
	s_cmp_eq_u32 s93, 40
	s_cselect_b32 s57, s1, s51
	s_cselect_b32 s56, s0, s50
	s_cselect_b32 s55, s49, s92
	s_cselect_b32 s54, s48, s91
	v_lshl_add_u64 v[160:161], s[10:11], 0, v[144:145]
	s_add_i32 m0, s58, 0xc000
	ds_read_b128 v[190:193], v169
	ds_read_b128 v[194:197], v169 offset:1024
	ds_read_b128 v[198:201], v169 offset:2048
	ds_read_b128 v[208:211], v169 offset:3072
	ds_read_b128 v[212:215], v169 offset:4096
	ds_read_b128 v[216:219], v169 offset:5120
	ds_read_b128 v[220:223], v169 offset:6144
	ds_read_b128 v[224:227], v169 offset:7168
	global_load_lds_dwordx4 v[160:161], off
	v_lshl_add_u64 v[160:161], s[10:11], 0, v[146:147]
	s_add_i32 m0, s58, 0xe000
	s_nop 0
	global_load_lds_dwordx4 v[160:161], off
	s_waitcnt vmcnt(8)
	s_waitcnt lgkmcnt(0)
	s_barrier
; #define PG8_STAGE(bufoff, gbase, voff) do { _Pragma("unroll") for (int _i = 0; _i < 2; ++_i) \
;         __builtin_amdgcn_global_load_lds((const unsigned*)((const char*)(gbase) + (voff)[_i]), (PG8_LAS unsigned*)(lds + (bufoff) + ldsw + _i * 8192), 16, 0, 0); } while (0)
; #define PG8_LDA(dst, b, h) do { _Pragma("unroll") for (int m = 0; m < 4; ++m) _Pragma("unroll") for (int k = 0; k < 2; ++k) dst[m][k] = *(const PG8_LAS bf16x8*)(lds + PG8_SA(b, h) + aoff + m * 2048 + k * 1024); } while (0)
; #define PG8_MMA(ai, bj, At, Bt) do { __builtin_amdgcn_s_setprio(1); _Pragma("unroll") for (int m = 0; m < 4; ++m) _Pragma("unroll") for (int n = 0; n < 2; ++n) _Pragma("unroll") for (int k = 0; k < 2; ++k) \
;         acc[ai][bj][m][n] = __builtin_amdgcn_mfma_f32_16x16x32_bf16(Bt[n][k], At[m][k], acc[ai][bj][m][n], 0, 0, 0); __builtin_amdgcn_s_setprio(0); } while (0)
; #define PG8_WAIT_V(n) asm volatile("s_waitcnt vmcnt(" #n ")" ::: "memory")
; #define PG8_WAIT_L(n) asm volatile("s_waitcnt lgkmcnt(" #n ")" ::: "memory")
; #define PG8_BAR __builtin_amdgcn_s_barrier()
; #define PG8_SCHED __builtin_amdgcn_sched_barrier(0)
; template <class Epi, class Sched, bool ALIGN_EPI = false, bool SP2 = false>
; __device__ __forceinline__ void gemm_phase(PG8_LAS unsigned char* lds, const Gemm g, const Sched& S, const Epi& E) {
;     ...
;             PG8_WAIT_V(8); PG8_WAIT_L(0); PG8_BAR; PG8_MMA(0, 0, At, B0); PG8_MMA(0, 1, At, B1); PG8_BAR; PG8_SCHED;
;             PG8_LDA(At, 0, 1); PG8_STAGE(PG8_SB(0, 0), b2, voffB); PG8_STAGE(PG8_SB(0, 1), b2 + hstep, voffB); PG8_STAGE(PG8_SA(0, 0), a2, voffA);
;             PG8_WAIT_V(8); PG8_WAIT_L(0); PG8_BAR; PG8_MMA(1, 0, At, B0); PG8_MMA(1, 1, At, B1); PG8_BAR; PG8_SCHED;
	s_setprio 1
	s_waitcnt lgkmcnt(0)
	v_mfma_f32_16x16x32_bf16 v[124:127], v[128:131], v[190:193], v[124:127]
	v_mfma_f32_16x16x32_bf16 v[120:123], v[152:155], v[190:193], v[120:123]
	v_mfma_f32_16x16x32_bf16 v[116:119], v[172:175], v[190:193], v[116:119]
	v_mfma_f32_16x16x32_bf16 v[112:115], v[182:185], v[190:193], v[112:115]
	v_mfma_f32_16x16x32_bf16 v[108:111], v[128:131], v[198:201], v[108:111]
	v_mfma_f32_16x16x32_bf16 v[104:107], v[152:155], v[198:201], v[104:107]
	v_mfma_f32_16x16x32_bf16 v[100:103], v[172:175], v[198:201], v[100:103]
	v_mfma_f32_16x16x32_bf16 v[96:99], v[182:185], v[198:201], v[96:99]
	v_mfma_f32_16x16x32_bf16 v[92:95], v[128:131], v[212:215], v[92:95]
	v_mfma_f32_16x16x32_bf16 v[88:91], v[152:155], v[212:215], v[88:91]
	v_mfma_f32_16x16x32_bf16 v[84:87], v[172:175], v[212:215], v[84:87]
	v_mfma_f32_16x16x32_bf16 v[80:83], v[182:185], v[212:215], v[80:83]
	v_mfma_f32_16x16x32_bf16 v[76:79], v[128:131], v[220:223], v[76:79]
	v_mfma_f32_16x16x32_bf16 v[72:75], v[152:155], v[220:223], v[72:75]
	v_mfma_f32_16x16x32_bf16 v[68:71], v[172:175], v[220:223], v[68:71]
	v_mfma_f32_16x16x32_bf16 v[64:67], v[182:185], v[220:223], v[64:67]
	s_setprio 0
	s_setprio 1
	v_mfma_f32_16x16x32_bf16 v[124:127], v[132:135], v[194:197], v[124:127]
	v_mfma_f32_16x16x32_bf16 v[120:123], v[156:159], v[194:197], v[120:123]
	v_mfma_f32_16x16x32_bf16 v[116:119], v[176:179], v[194:197], v[116:119]
	v_mfma_f32_16x16x32_bf16 v[112:115], v[186:189], v[194:197], v[112:115]
	v_mfma_f32_16x16x32_bf16 v[108:111], v[132:135], v[208:211], v[108:111]
	v_mfma_f32_16x16x32_bf16 v[104:107], v[156:159], v[208:211], v[104:107]
	v_mfma_f32_16x16x32_bf16 v[100:103], v[176:179], v[208:211], v[100:103]
	v_mfma_f32_16x16x32_bf16 v[96:99], v[186:189], v[208:211], v[96:99]
	v_mfma_f32_16x16x32_bf16 v[92:95], v[132:135], v[216:219], v[92:95]
	v_mfma_f32_16x16x32_bf16 v[88:91], v[156:159], v[216:219], v[88:91]
	v_mfma_f32_16x16x32_bf16 v[84:87], v[176:179], v[216:219], v[84:87]
	v_mfma_f32_16x16x32_bf16 v[80:83], v[186:189], v[216:219], v[80:83]
	v_mfma_f32_16x16x32_bf16 v[76:79], v[132:135], v[224:227], v[76:79]
	v_mfma_f32_16x16x32_bf16 v[72:75], v[156:159], v[224:227], v[72:75]
	v_mfma_f32_16x16x32_bf16 v[68:71], v[176:179], v[224:227], v[68:71]
	v_mfma_f32_16x16x32_bf16 v[64:67], v[186:189], v[224:227], v[64:67]
	s_setprio 0
	s_barrier
	s_add_i32 s3, s65, s43
	v_lshl_add_u64 v[160:161], s[54:55], 0, v[138:139]
	s_mov_b32 m0, s3
	ds_read_b128 v[190:193], v169 offset:16384
	ds_read_b128 v[194:197], v169 offset:17408
	ds_read_b128 v[198:201], v169 offset:18432
	ds_read_b128 v[208:211], v169 offset:19456
	ds_read_b128 v[212:215], v169 offset:20480
	ds_read_b128 v[216:219], v169 offset:21504
	ds_read_b128 v[220:223], v169 offset:22528
	ds_read_b128 v[224:227], v169 offset:23552
	global_load_lds_dwordx4 v[160:161], off
	s_add_i32 m0, s3, 0x2000
	s_add_u32 s10, s54, 0xb0000
	v_lshl_add_u64 v[202:203], s[54:55], 0, v[142:143]
	s_addc_u32 s11, s55, 0
	s_add_i32 s3, s66, s43
	global_load_lds_dwordx4 v[202:203], off
	v_lshl_add_u64 v[228:229], s[10:11], 0, v[138:139]
	s_mov_b32 m0, s3
	global_load_lds_dwordx4 v[228:229], off
	v_lshl_add_u64 v[228:229], s[10:11], 0, v[142:143]
	s_add_i32 m0, s3, 0x2000
	s_nop 0
	global_load_lds_dwordx4 v[228:229], off
	s_waitcnt vmcnt(6)
	s_waitcnt lgkmcnt(0)
	s_barrier
	s_setprio 1
	s_waitcnt lgkmcnt(0)
	v_mfma_f32_16x16x32_bf16 v[60:63], v[128:131], v[190:193], v[60:63]
	v_mfma_f32_16x16x32_bf16 v[56:59], v[152:155], v[190:193], v[56:59]
	v_mfma_f32_16x16x32_bf16 v[52:55], v[172:175], v[190:193], v[52:55]
	v_mfma_f32_16x16x32_bf16 v[48:51], v[182:185], v[190:193], v[48:51]
	v_mfma_f32_16x16x32_bf16 v[44:47], v[128:131], v[198:201], v[44:47]
	v_mfma_f32_16x16x32_bf16 v[40:43], v[152:155], v[198:201], v[40:43]
	v_mfma_f32_16x16x32_bf16 v[36:39], v[172:175], v[198:201], v[36:39]
	v_mfma_f32_16x16x32_bf16 v[32:35], v[182:185], v[198:201], v[32:35]
	v_mfma_f32_16x16x32_bf16 v[28:31], v[128:131], v[212:215], v[28:31]
	v_mfma_f32_16x16x32_bf16 v[24:27], v[152:155], v[212:215], v[24:27]
	v_mfma_f32_16x16x32_bf16 v[20:23], v[172:175], v[212:215], v[20:23]
	v_mfma_f32_16x16x32_bf16 v[16:19], v[182:185], v[212:215], v[16:19]
	v_mfma_f32_16x16x32_bf16 v[12:15], v[128:131], v[220:223], v[12:15]
	v_mfma_f32_16x16x32_bf16 v[8:11], v[152:155], v[220:223], v[8:11]
	v_lshl_add_u64 v[228:229], s[56:57], 0, v[136:137]
	s_mov_b32 m0, s58
	s_nop 0
	global_load_lds_dwordx4 v[228:229], off
	v_mfma_f32_16x16x32_bf16 v[4:7], v[172:175], v[220:223], v[4:7]
	v_mfma_f32_16x16x32_bf16 v[0:3], v[182:185], v[220:223], v[0:3]
	s_setprio 0
	s_setprio 1
	v_mfma_f32_16x16x32_bf16 v[60:63], v[132:135], v[194:197], v[60:63]
	v_mfma_f32_16x16x32_bf16 v[56:59], v[156:159], v[194:197], v[56:59]
	v_mfma_f32_16x16x32_bf16 v[52:55], v[176:179], v[194:197], v[52:55]
	v_mfma_f32_16x16x32_bf16 v[48:51], v[186:189], v[194:197], v[48:51]
	v_mfma_f32_16x16x32_bf16 v[44:47], v[132:135], v[208:211], v[44:47]
	v_mfma_f32_16x16x32_bf16 v[40:43], v[156:159], v[208:211], v[40:43]
	v_mfma_f32_16x16x32_bf16 v[36:39], v[176:179], v[208:211], v[36:39]
	v_mfma_f32_16x16x32_bf16 v[32:35], v[186:189], v[208:211], v[32:35]
	v_mfma_f32_16x16x32_bf16 v[28:31], v[132:135], v[216:219], v[28:31]
	v_mfma_f32_16x16x32_bf16 v[24:27], v[156:159], v[216:219], v[24:27]
	v_mfma_f32_16x16x32_bf16 v[20:23], v[176:179], v[216:219], v[20:23]
	v_mfma_f32_16x16x32_bf16 v[16:19], v[186:189], v[216:219], v[16:19]
	v_mfma_f32_16x16x32_bf16 v[12:15], v[132:135], v[224:227], v[12:15]
	v_mfma_f32_16x16x32_bf16 v[8:11], v[156:159], v[224:227], v[8:11]
	v_lshl_add_u64 v[230:231], s[56:57], 0, v[140:141]
	s_mov_b32 m0, s59
	s_nop 0
	global_load_lds_dwordx4 v[230:231], off
	v_mfma_f32_16x16x32_bf16 v[4:7], v[176:179], v[224:227], v[4:7]
	v_mfma_f32_16x16x32_bf16 v[0:3], v[186:189], v[224:227], v[0:3]
	s_setprio 0
	s_barrier
; #define PG8_STAGE(bufoff, gbase, voff) do { _Pragma("unroll") for (int _i = 0; _i < 2; ++_i) \
;         __builtin_amdgcn_global_load_lds((const unsigned*)((const char*)(gbase) + (voff)[_i]), (PG8_LAS unsigned*)(lds + (bufoff) + ldsw + _i * 8192), 16, 0, 0); } while (0)
; #define PG8_LDA(dst, b, h) do { _Pragma("unroll") for (int m = 0; m < 4; ++m) _Pragma("unroll") for (int k = 0; k < 2; ++k) dst[m][k] = *(const PG8_LAS bf16x8*)(lds + PG8_SA(b, h) + aoff + m * 2048 + k * 1024); } while (0)
; #define PG8_LDB(dst, b, h) do { _Pragma("unroll") for (int n = 0; n < 2; ++n) _Pragma("unroll") for (int k = 0; k < 2; ++k) dst[n][k] = *(const PG8_LAS bf16x8*)(lds + PG8_SB(b, h) + boff + n * 2048 + k * 1024); } while (0)
; #define PG8_MMA(ai, bj, At, Bt) do { __builtin_amdgcn_s_setprio(1); _Pragma("unroll") for (int m = 0; m < 4; ++m) _Pragma("unroll") for (int n = 0; n < 2; ++n) _Pragma("unroll") for (int k = 0; k < 2; ++k) \
;         acc[ai][bj][m][n] = __builtin_amdgcn_mfma_f32_16x16x32_bf16(Bt[n][k], At[m][k], acc[ai][bj][m][n], 0, 0, 0); __builtin_amdgcn_s_setprio(0); } while (0)
; #define PG8_WAIT_V(n) asm volatile("s_waitcnt vmcnt(" #n ")" ::: "memory")
; #define PG8_WAIT_L(n) asm volatile("s_waitcnt lgkmcnt(" #n ")" ::: "memory")
; #define PG8_BAR __builtin_amdgcn_s_barrier()
; #define PG8_SCHED __builtin_amdgcn_sched_barrier(0)
; template <class Epi, class Sched, bool ALIGN_EPI = false, bool SP2 = false>
; __device__ __forceinline__ void gemm_phase(PG8_LAS unsigned char* lds, const Gemm g, const Sched& S, const Epi& E) {
;     ...
;             PG8_LDB(B0, 1, 0); PG8_LDB(B1, 1, 1); PG8_SCHED; PG8_LDA(At, 1, 0); PG8_STAGE(PG8_SA(0, 1), a2 + hstep, voffA);
;             PG8_WAIT_V(8); PG8_WAIT_L(0); PG8_BAR; PG8_MMA(0, 0, At, B0); PG8_MMA(0, 1, At, B1); PG8_BAR; PG8_SCHED;
	s_add_i32 s3, 0, 0x18000
	s_add_i32 s14, 0, 0x1c000
	v_add_u32_e32 v156, s3, v163
	v_add_u32_e32 v171, s14, v163
	ds_read_b128 v[128:131], v156
	ds_read_b128 v[132:135], v156 offset:1024
	ds_read_b128 v[152:155], v156 offset:2048
	ds_read_b128 v[156:159], v156 offset:3072
	ds_read_b128 v[172:175], v171
	ds_read_b128 v[176:179], v171 offset:1024
	ds_read_b128 v[182:185], v171 offset:2048
	ds_read_b128 v[186:189], v171 offset:3072
	s_add_u32 s10, s56, 0xb0000
	s_addc_u32 s11, s57, 0
	s_mov_b32 m0, s60
	v_lshl_add_u64 v[232:233], s[10:11], 0, v[136:137]
	ds_read_b128 v[190:193], v169 offset:32768
	ds_read_b128 v[194:197], v169 offset:33792
	ds_read_b128 v[198:201], v169 offset:34816
	ds_read_b128 v[208:211], v169 offset:35840
	ds_read_b128 v[212:215], v169 offset:36864
	ds_read_b128 v[216:219], v169 offset:37888
	ds_read_b128 v[220:223], v169 offset:38912
	ds_read_b128 v[224:227], v169 offset:39936
	global_load_lds_dwordx4 v[232:233], off
	v_lshl_add_u64 v[232:233], s[10:11], 0, v[140:141]
	s_mov_b32 m0, s61
	s_nop 0
	global_load_lds_dwordx4 v[232:233], off
	s_waitcnt vmcnt(8)
	s_waitcnt lgkmcnt(0)
	s_barrier
	s_setprio 1
	s_waitcnt lgkmcnt(0)
	v_mfma_f32_16x16x32_bf16 v[124:127], v[128:131], v[190:193], v[124:127]
	v_mfma_f32_16x16x32_bf16 v[120:123], v[152:155], v[190:193], v[120:123]
	v_mfma_f32_16x16x32_bf16 v[116:119], v[172:175], v[190:193], v[116:119]
	v_mfma_f32_16x16x32_bf16 v[112:115], v[182:185], v[190:193], v[112:115]
	v_mfma_f32_16x16x32_bf16 v[108:111], v[128:131], v[198:201], v[108:111]
	v_mfma_f32_16x16x32_bf16 v[104:107], v[152:155], v[198:201], v[104:107]
	v_mfma_f32_16x16x32_bf16 v[100:103], v[172:175], v[198:201], v[100:103]
	v_mfma_f32_16x16x32_bf16 v[96:99], v[182:185], v[198:201], v[96:99]
	v_mfma_f32_16x16x32_bf16 v[92:95], v[128:131], v[212:215], v[92:95]
	v_mfma_f32_16x16x32_bf16 v[88:91], v[152:155], v[212:215], v[88:91]
	v_mfma_f32_16x16x32_bf16 v[84:87], v[172:175], v[212:215], v[84:87]
	v_mfma_f32_16x16x32_bf16 v[80:83], v[182:185], v[212:215], v[80:83]
	v_mfma_f32_16x16x32_bf16 v[76:79], v[128:131], v[220:223], v[76:79]
	v_mfma_f32_16x16x32_bf16 v[72:75], v[152:155], v[220:223], v[72:75]
	v_mfma_f32_16x16x32_bf16 v[68:71], v[172:175], v[220:223], v[68:71]
	v_mfma_f32_16x16x32_bf16 v[64:67], v[182:185], v[220:223], v[64:67]
	s_setprio 0
	s_setprio 1
	v_mfma_f32_16x16x32_bf16 v[124:127], v[132:135], v[194:197], v[124:127]
	v_mfma_f32_16x16x32_bf16 v[120:123], v[156:159], v[194:197], v[120:123]
	v_mfma_f32_16x16x32_bf16 v[116:119], v[176:179], v[194:197], v[116:119]
	v_mfma_f32_16x16x32_bf16 v[112:115], v[186:189], v[194:197], v[112:115]
	v_mfma_f32_16x16x32_bf16 v[108:111], v[132:135], v[208:211], v[108:111]
	v_mfma_f32_16x16x32_bf16 v[104:107], v[156:159], v[208:211], v[104:107]
	v_mfma_f32_16x16x32_bf16 v[100:103], v[176:179], v[208:211], v[100:103]
	v_mfma_f32_16x16x32_bf16 v[96:99], v[186:189], v[208:211], v[96:99]
	v_mfma_f32_16x16x32_bf16 v[92:95], v[132:135], v[216:219], v[92:95]
	v_mfma_f32_16x16x32_bf16 v[88:91], v[156:159], v[216:219], v[88:91]
	v_mfma_f32_16x16x32_bf16 v[84:87], v[176:179], v[216:219], v[84:87]
	v_mfma_f32_16x16x32_bf16 v[80:83], v[186:189], v[216:219], v[80:83]
	v_mfma_f32_16x16x32_bf16 v[76:79], v[132:135], v[224:227], v[76:79]
	v_mfma_f32_16x16x32_bf16 v[72:75], v[156:159], v[224:227], v[72:75]
	v_mfma_f32_16x16x32_bf16 v[68:71], v[176:179], v[224:227], v[68:71]
	v_mfma_f32_16x16x32_bf16 v[64:67], v[186:189], v[224:227], v[64:67]
	s_setprio 0
	s_barrier
; #define PG8_STAGE(bufoff, gbase, voff) do { _Pragma("unroll") for (int _i = 0; _i < 2; ++_i) \
;         __builtin_amdgcn_global_load_lds((const unsigned*)((const char*)(gbase) + (voff)[_i]), (PG8_LAS unsigned*)(lds + (bufoff) + ldsw + _i * 8192), 16, 0, 0); } while (0)
; #define PG8_LDA(dst, b, h) do { _Pragma("unroll") for (int m = 0; m < 4; ++m) _Pragma("unroll") for (int k = 0; k < 2; ++k) dst[m][k] = *(const PG8_LAS bf16x8*)(lds + PG8_SA(b, h) + aoff + m * 2048 + k * 1024); } while (0)
; #define PG8_MMA(ai, bj, At, Bt) do { __builtin_amdgcn_s_setprio(1); _Pragma("unroll") for (int m = 0; m < 4; ++m) _Pragma("unroll") for (int n = 0; n < 2; ++n) _Pragma("unroll") for (int k = 0; k < 2; ++k) \
;         acc[ai][bj][m][n] = __builtin_amdgcn_mfma_f32_16x16x32_bf16(Bt[n][k], At[m][k], acc[ai][bj][m][n], 0, 0, 0); __builtin_amdgcn_s_setprio(0); } while (0)
; #define PG8_WAIT_V(n) asm volatile("s_waitcnt vmcnt(" #n ")" ::: "memory")
; #define PG8_WAIT_L(n) asm volatile("s_waitcnt lgkmcnt(" #n ")" ::: "memory")
; #define PG8_BAR __builtin_amdgcn_s_barrier()
; #define PG8_SCHED __builtin_amdgcn_sched_barrier(0)
; template <class Epi, class Sched, bool ALIGN_EPI = false, bool SP2 = false>
; __device__ __forceinline__ void gemm_phase(PG8_LAS unsigned char* lds, const Gemm g, const Sched& S, const Epi& E) {
;     ...
;             PG8_LDA(At, 1, 1); PG8_STAGE(PG8_SB(1, 0), b3, voffB); PG8_STAGE(PG8_SB(1, 1), b3 + hstep, voffB); PG8_STAGE(PG8_SA(1, 0), a3, voffA);
;             PG8_WAIT_V(8); PG8_WAIT_L(0); PG8_BAR; PG8_MMA(1, 0, At, B0); PG8_MMA(1, 1, At, B1); PG8_BAR; PG8_SCHED;
;     ...
;         if constexpr (ALIGN_EPI) { if (wr == 0) PG8_BAR; }
	s_add_i32 s3, s3, s43
	v_lshl_add_u64 v[160:161], v[160:161], 0, s[40:41]
	s_mov_b32 m0, s3
	ds_read_b128 v[190:193], v169 offset:49152
	ds_read_b128 v[194:197], v169 offset:50176
	ds_read_b128 v[198:201], v169 offset:51200
	ds_read_b128 v[208:211], v169 offset:52224
	ds_read_b128 v[212:215], v169 offset:53248
	ds_read_b128 v[216:219], v169 offset:54272
	ds_read_b128 v[220:223], v169 offset:55296
	ds_read_b128 v[224:227], v169 offset:56320
	global_load_lds_dwordx4 v[160:161], off
	s_add_i32 m0, s3, 0x2000
	s_add_u32 s10, s54, 0xb0080
	v_lshl_add_u64 v[160:161], v[202:203], 0, s[40:41]
	s_addc_u32 s11, s55, 0
	s_add_i32 s3, s14, s43
	global_load_lds_dwordx4 v[160:161], off
	v_lshl_add_u64 v[160:161], s[10:11], 0, v[138:139]
	s_mov_b32 m0, s3
	s_nop 0
	global_load_lds_dwordx4 v[160:161], off
	v_lshl_add_u64 v[160:161], s[10:11], 0, v[142:143]
	s_add_i32 m0, s3, 0x2000
	s_nop 0
	global_load_lds_dwordx4 v[160:161], off
	s_waitcnt vmcnt(6)
	s_waitcnt lgkmcnt(0)
	s_barrier
	s_setprio 1
	s_waitcnt lgkmcnt(0)
	v_mfma_f32_16x16x32_bf16 v[60:63], v[128:131], v[190:193], v[60:63]
	v_mfma_f32_16x16x32_bf16 v[56:59], v[152:155], v[190:193], v[56:59]
	v_mfma_f32_16x16x32_bf16 v[52:55], v[172:175], v[190:193], v[52:55]
	v_mfma_f32_16x16x32_bf16 v[48:51], v[182:185], v[190:193], v[48:51]
	v_mfma_f32_16x16x32_bf16 v[44:47], v[128:131], v[198:201], v[44:47]
	v_mfma_f32_16x16x32_bf16 v[40:43], v[152:155], v[198:201], v[40:43]
	v_mfma_f32_16x16x32_bf16 v[36:39], v[172:175], v[198:201], v[36:39]
	v_mfma_f32_16x16x32_bf16 v[32:35], v[182:185], v[198:201], v[32:35]
	v_mfma_f32_16x16x32_bf16 v[28:31], v[128:131], v[212:215], v[28:31]
	v_mfma_f32_16x16x32_bf16 v[24:27], v[152:155], v[212:215], v[24:27]
	v_mfma_f32_16x16x32_bf16 v[20:23], v[172:175], v[212:215], v[20:23]
	v_mfma_f32_16x16x32_bf16 v[16:19], v[182:185], v[212:215], v[16:19]
	v_mfma_f32_16x16x32_bf16 v[12:15], v[128:131], v[220:223], v[12:15]
	v_mfma_f32_16x16x32_bf16 v[8:11], v[152:155], v[220:223], v[8:11]
	v_lshl_add_u64 v[160:161], v[228:229], 0, s[40:41]
	s_mov_b32 m0, s63
	s_nop 0
	global_load_lds_dwordx4 v[160:161], off
	v_mfma_f32_16x16x32_bf16 v[4:7], v[172:175], v[220:223], v[4:7]
	v_mfma_f32_16x16x32_bf16 v[0:3], v[182:185], v[220:223], v[0:3]
	s_setprio 0
	s_setprio 1
	v_mfma_f32_16x16x32_bf16 v[60:63], v[132:135], v[194:197], v[60:63]
	v_mfma_f32_16x16x32_bf16 v[56:59], v[156:159], v[194:197], v[56:59]
	v_mfma_f32_16x16x32_bf16 v[52:55], v[176:179], v[194:197], v[52:55]
	v_mfma_f32_16x16x32_bf16 v[48:51], v[186:189], v[194:197], v[48:51]
	v_mfma_f32_16x16x32_bf16 v[44:47], v[132:135], v[208:211], v[44:47]
	v_mfma_f32_16x16x32_bf16 v[40:43], v[156:159], v[208:211], v[40:43]
	v_mfma_f32_16x16x32_bf16 v[36:39], v[176:179], v[208:211], v[36:39]
	v_mfma_f32_16x16x32_bf16 v[32:35], v[186:189], v[208:211], v[32:35]
	v_mfma_f32_16x16x32_bf16 v[28:31], v[132:135], v[216:219], v[28:31]
	v_mfma_f32_16x16x32_bf16 v[24:27], v[156:159], v[216:219], v[24:27]
	v_mfma_f32_16x16x32_bf16 v[20:23], v[176:179], v[216:219], v[20:23]
	v_mfma_f32_16x16x32_bf16 v[16:19], v[186:189], v[216:219], v[16:19]
	v_mfma_f32_16x16x32_bf16 v[12:15], v[132:135], v[224:227], v[12:15]
	v_mfma_f32_16x16x32_bf16 v[8:11], v[156:159], v[224:227], v[8:11]
	v_lshl_add_u64 v[160:161], v[230:231], 0, s[40:41]
	s_mov_b32 m0, s64
	s_nop 0
	global_load_lds_dwordx4 v[160:161], off
	v_mfma_f32_16x16x32_bf16 v[4:7], v[176:179], v[224:227], v[4:7]
	v_mfma_f32_16x16x32_bf16 v[0:3], v[186:189], v[224:227], v[0:3]
	s_setprio 0
	s_barrier
	s_add_i32 s93, s93, 2
	s_add_u32 s91, s91, 0x100
	s_addc_u32 s92, s92, 0
	s_cmp_gt_u32 s93, 41
	s_mov_b64 s[10:11], s[50:51]
	s_cbranch_scc0 .LBB0_269
	s_and_b64 vcc, exec, s[44:45]
	s_cbranch_vccz .LBB0_272
	s_barrier

; #define PG8_STAGE(bufoff, gbase, voff) do { _Pragma("unroll") for (int _i = 0; _i < 2; ++_i) \
;         __builtin_amdgcn_global_load_lds((const unsigned*)((const char*)(gbase) + (voff)[_i]), (PG8_LAS unsigned*)(lds + (bufoff) + ldsw + _i * 8192), 16, 0, 0); } while (0)
; #define PG8_LDA(dst, b, h) do { _Pragma("unroll") for (int m = 0; m < 4; ++m) _Pragma("unroll") for (int k = 0; k < 2; ++k) dst[m][k] = *(const PG8_LAS bf16x8*)(lds + PG8_SA(b, h) + aoff + m * 2048 + k * 1024); } while (0)
; #define PG8_LDB(dst, b, h) do { _Pragma("unroll") for (int n = 0; n < 2; ++n) _Pragma("unroll") for (int k = 0; k < 2; ++k) dst[n][k] = *(const PG8_LAS bf16x8*)(lds + PG8_SB(b, h) + boff + n * 2048 + k * 1024); } while (0)
; #define PG8_MMA(ai, bj, At, Bt) do { __builtin_amdgcn_s_setprio(1); _Pragma("unroll") for (int m = 0; m < 4; ++m) _Pragma("unroll") for (int n = 0; n < 2; ++n) _Pragma("unroll") for (int k = 0; k < 2; ++k) \
;         acc[ai][bj][m][n] = __builtin_amdgcn_mfma_f32_16x16x32_bf16(Bt[n][k], At[m][k], acc[ai][bj][m][n], 0, 0, 0); __builtin_amdgcn_s_setprio(0); } while (0)
; #define PG8_BAR __builtin_amdgcn_s_barrier()
; template <class Epi, class Sched, bool ALIGN_EPI = false, bool SP2 = false>
; __device__ __forceinline__ void gemm_phase(PG8_LAS unsigned char* lds, const Gemm g, const Sched& S, const Epi& E) {
;     ...
;         const bool has_next = S.next(ui + 1, nxt);
;         const char* nA = has_next ? (const char*)g.A + (size_t)nxt.pm * tstep : cA; const char* nB = has_next ? (const char*)g.Bt + (size_t)nxt.pn * tstep : cB;
;         for (int t = 0; t < nt; t += 2) {
;             const bool last = (t == nt - 2);
;             const char* a1 = cA + (size_t)(t + 1) * kstep;
;             const char* a2 = last ? nA : cA + (size_t)(t + 2) * kstep; const char* b2 = last ? nB : cB + (size_t)(t + 2) * kstep;
;             const char* a3 = a2 + kstep; const char* b3 = b2 + kstep;
;             if (last && has_next) S.a_ready(nxt);
;             if constexpr (SP2) {
;             PG8_LDB(B0, 0, 0); PG8_LDB(B1, 0, 1); PG8_SCHED; PG8_LDA(At, 0, 0); PG8_STAGE(PG8_SA(1, 1), a1 + hstep, voffA);
;             PG8_WAIT_V(8); PG8_WAIT_L(0); PG8_BAR; PG8_MMA(0, 0, At, B0); PG8_MMA(0, 1, At, B1); PG8_BAR; PG8_SCHED;
;             PG8_LDA(At, 0, 1); PG8_STAGE(PG8_SB(0, 0), b2, voffB); PG8_STAGE(PG8_SB(0, 1), b2 + hstep, voffB); PG8_STAGE(PG8_SA(0, 0), a2, voffA);
.LBB0_416:
	s_ashr_i32 s45, s44, 31
	s_lshl_b64 s[14:15], s[44:45], 19
	s_add_u32 s48, s22, s14
	s_addc_u32 s49, s23, s15
	s_and_b64 s[14:15], s[6:7], exec
	s_cselect_b32 s45, s49, s55
	s_cselect_b32 s89, s48, s54
	s_ashr_i32 s41, s40, 31
	s_lshl_b64 s[14:15], s[40:41], 19
	s_add_u32 s50, s84, s14
	s_addc_u32 s51, s85, s15
	s_and_b64 s[14:15], s[6:7], exec
	s_cselect_b32 s41, s51, s57
	s_cselect_b32 s90, s50, s56
	s_add_u32 s54, s54, 0x40080
	s_addc_u32 s55, s55, 0
	s_add_u32 s91, s56, 0x100
	s_addc_u32 s92, s57, 0
	s_mov_b32 s93, -2
	ds_read_b128 v[154:157], v169
	ds_read_b128 v[158:161], v169 offset:1024
	ds_read_b128 v[162:165], v169 offset:2048
	ds_read_b128 v[174:177], v169 offset:3072
	ds_read_b128 v[182:185], v170
	ds_read_b128 v[186:189], v170 offset:1024
	ds_read_b128 v[190:193], v170 offset:2048
	ds_read_b128 v[194:197], v170 offset:3072
	s_add_u32 s3, s54, 0xfffc0080
	s_addc_u32 s14, s55, -1
	s_cmp_eq_u32 s93, 12
	s_cselect_b32 s59, s45, s14
	s_cselect_b32 s58, s89, s3
	s_cselect_b32 s57, s41, s92
	s_cselect_b32 s56, s90, s91
	v_lshl_add_u64 v[178:179], s[54:55], 0, v[146:147]
	s_add_i32 m0, s60, 0xc000
	ds_read_b128 v[198:201], v171
	ds_read_b128 v[208:211], v171 offset:1024
	ds_read_b128 v[212:215], v171 offset:2048
	ds_read_b128 v[216:219], v171 offset:3072
	ds_read_b128 v[220:223], v171 offset:4096
	ds_read_b128 v[224:227], v171 offset:5120
	ds_read_b128 v[228:231], v171 offset:6144
	ds_read_b128 v[232:235], v171 offset:7168
	global_load_lds_dwordx4 v[178:179], off
	v_lshl_add_u64 v[178:179], s[54:55], 0, v[148:149]
	s_add_i32 m0, s60, 0xe000
	s_nop 0
	global_load_lds_dwordx4 v[178:179], off
	s_waitcnt vmcnt(8)
	s_waitcnt lgkmcnt(0)
	s_barrier
	s_setprio 1
	s_waitcnt lgkmcnt(0)
	v_mfma_f32_16x16x32_bf16 v[124:127], v[154:157], v[198:201], 0
	v_mfma_f32_16x16x32_bf16 v[120:123], v[162:165], v[198:201], 0
	v_mfma_f32_16x16x32_bf16 v[68:71], v[182:185], v[198:201], 0
	v_mfma_f32_16x16x32_bf16 v[64:67], v[190:193], v[198:201], 0
	v_mfma_f32_16x16x32_bf16 v[116:119], v[154:157], v[212:215], 0
	v_mfma_f32_16x16x32_bf16 v[112:115], v[162:165], v[212:215], 0
	v_mfma_f32_16x16x32_bf16 v[52:55], v[182:185], v[212:215], 0
	v_mfma_f32_16x16x32_bf16 v[48:51], v[190:193], v[212:215], 0
	v_mfma_f32_16x16x32_bf16 v[108:111], v[154:157], v[220:223], 0
	v_mfma_f32_16x16x32_bf16 v[104:107], v[162:165], v[220:223], 0
	v_mfma_f32_16x16x32_bf16 v[44:47], v[182:185], v[220:223], 0
	v_mfma_f32_16x16x32_bf16 v[40:43], v[190:193], v[220:223], 0
	v_mfma_f32_16x16x32_bf16 v[100:103], v[154:157], v[228:231], 0
	v_mfma_f32_16x16x32_bf16 v[96:99], v[162:165], v[228:231], 0
	v_mfma_f32_16x16x32_bf16 v[36:39], v[182:185], v[228:231], 0
	v_mfma_f32_16x16x32_bf16 v[32:35], v[190:193], v[228:231], 0
	s_setprio 0
	s_setprio 1
	v_mfma_f32_16x16x32_bf16 v[124:127], v[158:161], v[208:211], v[124:127]
	v_mfma_f32_16x16x32_bf16 v[120:123], v[174:177], v[208:211], v[120:123]
	v_mfma_f32_16x16x32_bf16 v[68:71], v[186:189], v[208:211], v[68:71]
	v_mfma_f32_16x16x32_bf16 v[64:67], v[194:197], v[208:211], v[64:67]
	v_mfma_f32_16x16x32_bf16 v[116:119], v[158:161], v[216:219], v[116:119]
	v_mfma_f32_16x16x32_bf16 v[112:115], v[174:177], v[216:219], v[112:115]
	v_mfma_f32_16x16x32_bf16 v[52:55], v[186:189], v[216:219], v[52:55]
	v_mfma_f32_16x16x32_bf16 v[48:51], v[194:197], v[216:219], v[48:51]
	v_mfma_f32_16x16x32_bf16 v[108:111], v[158:161], v[224:227], v[108:111]
	v_mfma_f32_16x16x32_bf16 v[104:107], v[174:177], v[224:227], v[104:107]
	v_mfma_f32_16x16x32_bf16 v[44:47], v[186:189], v[224:227], v[44:47]
	v_mfma_f32_16x16x32_bf16 v[40:43], v[194:197], v[224:227], v[40:43]
	v_mfma_f32_16x16x32_bf16 v[100:103], v[158:161], v[232:235], v[100:103]
	v_mfma_f32_16x16x32_bf16 v[96:99], v[174:177], v[232:235], v[96:99]
	v_mfma_f32_16x16x32_bf16 v[36:39], v[186:189], v[232:235], v[36:39]
	v_mfma_f32_16x16x32_bf16 v[32:35], v[194:197], v[232:235], v[32:35]
	s_setprio 0
	s_barrier
	s_add_i32 s3, s86, s34
	v_lshl_add_u64 v[178:179], s[56:57], 0, v[132:133]
	s_mov_b32 m0, s3
	ds_read_b128 v[198:201], v171 offset:16384
	ds_read_b128 v[208:211], v171 offset:17408
	ds_read_b128 v[212:215], v171 offset:18432
	ds_read_b128 v[216:219], v171 offset:19456
	ds_read_b128 v[220:223], v171 offset:20480
	ds_read_b128 v[224:227], v171 offset:21504
	ds_read_b128 v[228:231], v171 offset:22528
	ds_read_b128 v[232:235], v171 offset:23552
	global_load_lds_dwordx4 v[178:179], off
	s_add_i32 m0, s3, 0x2000
	s_add_u32 s14, s56, 0x40000
	v_lshl_add_u64 v[202:203], s[56:57], 0, v[128:129]
	s_addc_u32 s15, s57, 0
	s_add_i32 s3, s87, s34
	global_load_lds_dwordx4 v[202:203], off
	v_lshl_add_u64 v[236:237], s[14:15], 0, v[132:133]
	s_mov_b32 m0, s3
	global_load_lds_dwordx4 v[236:237], off
	v_lshl_add_u64 v[236:237], s[14:15], 0, v[128:129]
	s_add_i32 m0, s3, 0x2000
	s_nop 0
	global_load_lds_dwordx4 v[236:237], off
	s_waitcnt vmcnt(6)
	s_waitcnt lgkmcnt(0)
	s_barrier
; #define PG8_STAGE(bufoff, gbase, voff) do { _Pragma("unroll") for (int _i = 0; _i < 2; ++_i) \
;         __builtin_amdgcn_global_load_lds((const unsigned*)((const char*)(gbase) + (voff)[_i]), (PG8_LAS unsigned*)(lds + (bufoff) + ldsw + _i * 8192), 16, 0, 0); } while (0)
; #define PG8_LDA(dst, b, h) do { _Pragma("unroll") for (int m = 0; m < 4; ++m) _Pragma("unroll") for (int k = 0; k < 2; ++k) dst[m][k] = *(const PG8_LAS bf16x8*)(lds + PG8_SA(b, h) + aoff + m * 2048 + k * 1024); } while (0)
; #define PG8_LDB(dst, b, h) do { _Pragma("unroll") for (int n = 0; n < 2; ++n) _Pragma("unroll") for (int k = 0; k < 2; ++k) dst[n][k] = *(const PG8_LAS bf16x8*)(lds + PG8_SB(b, h) + boff + n * 2048 + k * 1024); } while (0)
; #define PG8_MMA(ai, bj, At, Bt) do { __builtin_amdgcn_s_setprio(1); _Pragma("unroll") for (int m = 0; m < 4; ++m) _Pragma("unroll") for (int n = 0; n < 2; ++n) _Pragma("unroll") for (int k = 0; k < 2; ++k) \
;         acc[ai][bj][m][n] = __builtin_amdgcn_mfma_f32_16x16x32_bf16(Bt[n][k], At[m][k], acc[ai][bj][m][n], 0, 0, 0); __builtin_amdgcn_s_setprio(0); } while (0)
; #define PG8_WAIT_V(n) asm volatile("s_waitcnt vmcnt(" #n ")" ::: "memory")
; #define PG8_WAIT_L(n) asm volatile("s_waitcnt lgkmcnt(" #n ")" ::: "memory")
; #define PG8_BAR __builtin_amdgcn_s_barrier()
; #define PG8_SCHED __builtin_amdgcn_sched_barrier(0)
; template <class Epi, class Sched, bool ALIGN_EPI = false, bool SP2 = false>
; __device__ __forceinline__ void gemm_phase(PG8_LAS unsigned char* lds, const Gemm g, const Sched& S, const Epi& E) {
;     ...
;             PG8_WAIT_V(8); PG8_WAIT_L(0); PG8_BAR; PG8_MMA(1, 0, At, B0); PG8_MMA(1, 1, At, B1); PG8_BAR; PG8_SCHED;
;             PG8_LDB(B0, 1, 0); PG8_LDB(B1, 1, 1); PG8_SCHED; PG8_LDA(At, 1, 0); PG8_STAGE(PG8_SA(0, 1), a2 + hstep, voffA);
;             PG8_WAIT_V(8); PG8_WAIT_L(0); PG8_BAR; PG8_MMA(0, 0, At, B0); PG8_MMA(0, 1, At, B1); PG8_BAR; PG8_SCHED;
	s_setprio 1
	s_waitcnt lgkmcnt(0)
	v_mfma_f32_16x16x32_bf16 v[92:95], v[154:157], v[198:201], 0
	v_mfma_f32_16x16x32_bf16 v[88:91], v[162:165], v[198:201], 0
	v_mfma_f32_16x16x32_bf16 v[28:31], v[182:185], v[198:201], 0
	v_mfma_f32_16x16x32_bf16 v[24:27], v[190:193], v[198:201], 0
	v_mfma_f32_16x16x32_bf16 v[84:87], v[154:157], v[212:215], 0
	v_mfma_f32_16x16x32_bf16 v[80:83], v[162:165], v[212:215], 0
	v_mfma_f32_16x16x32_bf16 v[20:23], v[182:185], v[212:215], 0
	v_mfma_f32_16x16x32_bf16 v[16:19], v[190:193], v[212:215], 0
	v_mfma_f32_16x16x32_bf16 v[76:79], v[154:157], v[220:223], 0
	v_mfma_f32_16x16x32_bf16 v[72:75], v[162:165], v[220:223], 0
	v_mfma_f32_16x16x32_bf16 v[12:15], v[182:185], v[220:223], 0
	v_mfma_f32_16x16x32_bf16 v[8:11], v[190:193], v[220:223], 0
	v_mfma_f32_16x16x32_bf16 v[60:63], v[154:157], v[228:231], 0
	v_mfma_f32_16x16x32_bf16 v[56:59], v[162:165], v[228:231], 0
	v_lshl_add_u64 v[236:237], s[58:59], 0, v[134:135]
	s_mov_b32 m0, s60
	s_nop 0
	global_load_lds_dwordx4 v[236:237], off
	v_mfma_f32_16x16x32_bf16 v[4:7], v[182:185], v[228:231], 0
	v_mfma_f32_16x16x32_bf16 v[0:3], v[190:193], v[228:231], 0
	s_setprio 0
	s_setprio 1
	v_mfma_f32_16x16x32_bf16 v[92:95], v[158:161], v[208:211], v[92:95]
	v_mfma_f32_16x16x32_bf16 v[88:91], v[174:177], v[208:211], v[88:91]
	v_mfma_f32_16x16x32_bf16 v[28:31], v[186:189], v[208:211], v[28:31]
	v_mfma_f32_16x16x32_bf16 v[24:27], v[194:197], v[208:211], v[24:27]
	v_mfma_f32_16x16x32_bf16 v[84:87], v[158:161], v[216:219], v[84:87]
	v_mfma_f32_16x16x32_bf16 v[80:83], v[174:177], v[216:219], v[80:83]
	v_mfma_f32_16x16x32_bf16 v[20:23], v[186:189], v[216:219], v[20:23]
	v_mfma_f32_16x16x32_bf16 v[16:19], v[194:197], v[216:219], v[16:19]
	v_mfma_f32_16x16x32_bf16 v[76:79], v[158:161], v[224:227], v[76:79]
	v_mfma_f32_16x16x32_bf16 v[72:75], v[174:177], v[224:227], v[72:75]
	v_mfma_f32_16x16x32_bf16 v[12:15], v[186:189], v[224:227], v[12:15]
	v_mfma_f32_16x16x32_bf16 v[8:11], v[194:197], v[224:227], v[8:11]
	v_mfma_f32_16x16x32_bf16 v[60:63], v[158:161], v[232:235], v[60:63]
	v_mfma_f32_16x16x32_bf16 v[56:59], v[174:177], v[232:235], v[56:59]
	v_lshl_add_u64 v[238:239], s[58:59], 0, v[130:131]
	s_mov_b32 m0, s61
	s_nop 0
	global_load_lds_dwordx4 v[238:239], off
	v_mfma_f32_16x16x32_bf16 v[4:7], v[186:189], v[232:235], v[4:7]
	v_mfma_f32_16x16x32_bf16 v[0:3], v[194:197], v[232:235], v[0:3]
	s_setprio 0
	s_barrier
	s_add_i32 s3, 0, 0x18000
	v_add_u32_e32 v136, s3, v143
	s_add_i32 s33, 0, 0x1c000
	ds_read_b128 v[154:157], v136
	ds_read_b128 v[158:161], v136 offset:1024
	ds_read_b128 v[162:165], v136 offset:2048
	ds_read_b128 v[174:177], v136 offset:3072
	v_add_u32_e32 v136, s33, v143
	ds_read_b128 v[182:185], v136
	ds_read_b128 v[186:189], v136 offset:1024
	ds_read_b128 v[190:193], v136 offset:2048
	ds_read_b128 v[194:197], v136 offset:3072
	s_add_u32 s14, s58, 0x40000
	s_addc_u32 s15, s59, 0
	s_mov_b32 m0, s62
	v_lshl_add_u64 v[240:241], s[14:15], 0, v[134:135]
	ds_read_b128 v[198:201], v171 offset:32768
	ds_read_b128 v[208:211], v171 offset:33792
	ds_read_b128 v[212:215], v171 offset:34816
	ds_read_b128 v[216:219], v171 offset:35840
	ds_read_b128 v[220:223], v171 offset:36864
	ds_read_b128 v[224:227], v171 offset:37888
	ds_read_b128 v[228:231], v171 offset:38912
	ds_read_b128 v[232:235], v171 offset:39936
	global_load_lds_dwordx4 v[240:241], off
	v_lshl_add_u64 v[240:241], s[14:15], 0, v[130:131]
	s_mov_b32 m0, s63
	s_nop 0
	global_load_lds_dwordx4 v[240:241], off
	s_waitcnt vmcnt(8)
	s_waitcnt lgkmcnt(0)
	s_barrier
	s_setprio 1
	s_waitcnt lgkmcnt(0)
	v_mfma_f32_16x16x32_bf16 v[124:127], v[154:157], v[198:201], v[124:127]
	v_mfma_f32_16x16x32_bf16 v[120:123], v[162:165], v[198:201], v[120:123]
	v_mfma_f32_16x16x32_bf16 v[68:71], v[182:185], v[198:201], v[68:71]
	v_mfma_f32_16x16x32_bf16 v[64:67], v[190:193], v[198:201], v[64:67]
	v_mfma_f32_16x16x32_bf16 v[116:119], v[154:157], v[212:215], v[116:119]
	v_mfma_f32_16x16x32_bf16 v[112:115], v[162:165], v[212:215], v[112:115]
	v_mfma_f32_16x16x32_bf16 v[52:55], v[182:185], v[212:215], v[52:55]
	v_mfma_f32_16x16x32_bf16 v[48:51], v[190:193], v[212:215], v[48:51]
	v_mfma_f32_16x16x32_bf16 v[108:111], v[154:157], v[220:223], v[108:111]
	v_mfma_f32_16x16x32_bf16 v[104:107], v[162:165], v[220:223], v[104:107]
	v_mfma_f32_16x16x32_bf16 v[44:47], v[182:185], v[220:223], v[44:47]
	v_mfma_f32_16x16x32_bf16 v[40:43], v[190:193], v[220:223], v[40:43]
	v_mfma_f32_16x16x32_bf16 v[100:103], v[154:157], v[228:231], v[100:103]
	v_mfma_f32_16x16x32_bf16 v[96:99], v[162:165], v[228:231], v[96:99]
	v_mfma_f32_16x16x32_bf16 v[36:39], v[182:185], v[228:231], v[36:39]
	v_mfma_f32_16x16x32_bf16 v[32:35], v[190:193], v[228:231], v[32:35]
	s_setprio 0
	s_setprio 1
	v_mfma_f32_16x16x32_bf16 v[124:127], v[158:161], v[208:211], v[124:127]
	v_mfma_f32_16x16x32_bf16 v[120:123], v[174:177], v[208:211], v[120:123]
	v_mfma_f32_16x16x32_bf16 v[68:71], v[186:189], v[208:211], v[68:71]
	v_mfma_f32_16x16x32_bf16 v[64:67], v[194:197], v[208:211], v[64:67]
	v_mfma_f32_16x16x32_bf16 v[116:119], v[158:161], v[216:219], v[116:119]
	v_mfma_f32_16x16x32_bf16 v[112:115], v[174:177], v[216:219], v[112:115]
	v_mfma_f32_16x16x32_bf16 v[52:55], v[186:189], v[216:219], v[52:55]
	v_mfma_f32_16x16x32_bf16 v[48:51], v[194:197], v[216:219], v[48:51]
	v_mfma_f32_16x16x32_bf16 v[108:111], v[158:161], v[224:227], v[108:111]
	v_mfma_f32_16x16x32_bf16 v[104:107], v[174:177], v[224:227], v[104:107]
	v_mfma_f32_16x16x32_bf16 v[44:47], v[186:189], v[224:227], v[44:47]
	v_mfma_f32_16x16x32_bf16 v[40:43], v[194:197], v[224:227], v[40:43]
	v_mfma_f32_16x16x32_bf16 v[100:103], v[158:161], v[232:235], v[100:103]
	v_mfma_f32_16x16x32_bf16 v[96:99], v[174:177], v[232:235], v[96:99]
	v_mfma_f32_16x16x32_bf16 v[36:39], v[186:189], v[232:235], v[36:39]
	v_mfma_f32_16x16x32_bf16 v[32:35], v[194:197], v[232:235], v[32:35]
	s_setprio 0
	s_barrier
; #define PG8_STAGE(bufoff, gbase, voff) do { _Pragma("unroll") for (int _i = 0; _i < 2; ++_i) \
;         __builtin_amdgcn_global_load_lds((const unsigned*)((const char*)(gbase) + (voff)[_i]), (PG8_LAS unsigned*)(lds + (bufoff) + ldsw + _i * 8192), 16, 0, 0); } while (0)
; #define PG8_LDA(dst, b, h) do { _Pragma("unroll") for (int m = 0; m < 4; ++m) _Pragma("unroll") for (int k = 0; k < 2; ++k) dst[m][k] = *(const PG8_LAS bf16x8*)(lds + PG8_SA(b, h) + aoff + m * 2048 + k * 1024); } while (0)
; #define PG8_LDB(dst, b, h) do { _Pragma("unroll") for (int n = 0; n < 2; ++n) _Pragma("unroll") for (int k = 0; k < 2; ++k) dst[n][k] = *(const PG8_LAS bf16x8*)(lds + PG8_SB(b, h) + boff + n * 2048 + k * 1024); } while (0)
; #define PG8_MMA(ai, bj, At, Bt) do { __builtin_amdgcn_s_setprio(1); _Pragma("unroll") for (int m = 0; m < 4; ++m) _Pragma("unroll") for (int n = 0; n < 2; ++n) _Pragma("unroll") for (int k = 0; k < 2; ++k) \
;         acc[ai][bj][m][n] = __builtin_amdgcn_mfma_f32_16x16x32_bf16(Bt[n][k], At[m][k], acc[ai][bj][m][n], 0, 0, 0); __builtin_amdgcn_s_setprio(0); } while (0)
; #define PG8_WAIT_V(n) asm volatile("s_waitcnt vmcnt(" #n ")" ::: "memory")
; #define PG8_WAIT_L(n) asm volatile("s_waitcnt lgkmcnt(" #n ")" ::: "memory")
; #define PG8_BAR __builtin_amdgcn_s_barrier()
; #define PG8_SCHED __builtin_amdgcn_sched_barrier(0)
; template <class Epi, class Sched, bool ALIGN_EPI = false, bool SP2 = false>
; __device__ __forceinline__ void gemm_phase(PG8_LAS unsigned char* lds, const Gemm g, const Sched& S, const Epi& E) {
;     ...
;             PG8_LDB(B0, 0, 0); PG8_LDB(B1, 0, 1); PG8_SCHED; PG8_LDA(At, 0, 0); PG8_STAGE(PG8_SA(1, 1), a1 + hstep, voffA);
;             PG8_WAIT_V(8); PG8_WAIT_L(0); PG8_BAR; PG8_MMA(0, 0, At, B0); PG8_MMA(0, 1, At, B1); PG8_BAR; PG8_SCHED;
;     ...
;             PG8_LDA(At, 1, 1); PG8_STAGE(PG8_SB(1, 0), b3, voffB); PG8_STAGE(PG8_SB(1, 1), b3 + hstep, voffB); PG8_STAGE(PG8_SA(1, 0), a3, voffA);
;             PG8_WAIT_V(8); PG8_WAIT_L(0); PG8_BAR; PG8_MMA(1, 0, At, B0); PG8_MMA(1, 1, At, B1); PG8_BAR; PG8_SCHED;
	s_add_i32 s3, s3, s34
	v_lshl_add_u64 v[178:179], v[178:179], 0, s[8:9]
	s_mov_b32 m0, s3
	ds_read_b128 v[198:201], v171 offset:49152
	ds_read_b128 v[208:211], v171 offset:50176
	ds_read_b128 v[212:215], v171 offset:51200
	ds_read_b128 v[216:219], v171 offset:52224
	ds_read_b128 v[220:223], v171 offset:53248
	ds_read_b128 v[224:227], v171 offset:54272
	ds_read_b128 v[228:231], v171 offset:55296
	ds_read_b128 v[232:235], v171 offset:56320
	global_load_lds_dwordx4 v[178:179], off
	s_add_i32 m0, s3, 0x2000
	s_add_u32 s14, s56, 0x40080
	v_lshl_add_u64 v[178:179], v[202:203], 0, s[8:9]
	s_addc_u32 s15, s57, 0
	s_add_i32 s3, s33, s34
	global_load_lds_dwordx4 v[178:179], off
	v_lshl_add_u64 v[178:179], s[14:15], 0, v[132:133]
	s_mov_b32 m0, s3
	s_nop 0
	global_load_lds_dwordx4 v[178:179], off
	v_lshl_add_u64 v[178:179], s[14:15], 0, v[128:129]
	s_add_i32 m0, s3, 0x2000
	s_nop 0
	global_load_lds_dwordx4 v[178:179], off
	s_waitcnt vmcnt(6)
	s_waitcnt lgkmcnt(0)
	s_barrier
	s_setprio 1
	s_waitcnt lgkmcnt(0)
	v_mfma_f32_16x16x32_bf16 v[92:95], v[154:157], v[198:201], v[92:95]
	v_mfma_f32_16x16x32_bf16 v[88:91], v[162:165], v[198:201], v[88:91]
	v_mfma_f32_16x16x32_bf16 v[28:31], v[182:185], v[198:201], v[28:31]
	v_mfma_f32_16x16x32_bf16 v[24:27], v[190:193], v[198:201], v[24:27]
	v_mfma_f32_16x16x32_bf16 v[84:87], v[154:157], v[212:215], v[84:87]
	v_mfma_f32_16x16x32_bf16 v[80:83], v[162:165], v[212:215], v[80:83]
	v_mfma_f32_16x16x32_bf16 v[20:23], v[182:185], v[212:215], v[20:23]
	v_mfma_f32_16x16x32_bf16 v[16:19], v[190:193], v[212:215], v[16:19]
	v_mfma_f32_16x16x32_bf16 v[76:79], v[154:157], v[220:223], v[76:79]
	v_mfma_f32_16x16x32_bf16 v[72:75], v[162:165], v[220:223], v[72:75]
	v_mfma_f32_16x16x32_bf16 v[12:15], v[182:185], v[220:223], v[12:15]
	v_mfma_f32_16x16x32_bf16 v[8:11], v[190:193], v[220:223], v[8:11]
	v_mfma_f32_16x16x32_bf16 v[60:63], v[154:157], v[228:231], v[60:63]
	v_mfma_f32_16x16x32_bf16 v[56:59], v[162:165], v[228:231], v[56:59]
	v_lshl_add_u64 v[178:179], v[236:237], 0, s[8:9]
	s_mov_b32 m0, s66
	s_nop 0
	global_load_lds_dwordx4 v[178:179], off
	v_mfma_f32_16x16x32_bf16 v[4:7], v[182:185], v[228:231], v[4:7]
	v_mfma_f32_16x16x32_bf16 v[0:3], v[190:193], v[228:231], v[0:3]
	s_setprio 0
	s_setprio 1
	v_mfma_f32_16x16x32_bf16 v[92:95], v[158:161], v[208:211], v[92:95]
	v_mfma_f32_16x16x32_bf16 v[88:91], v[174:177], v[208:211], v[88:91]
	v_mfma_f32_16x16x32_bf16 v[28:31], v[186:189], v[208:211], v[28:31]
	v_mfma_f32_16x16x32_bf16 v[24:27], v[194:197], v[208:211], v[24:27]
	v_mfma_f32_16x16x32_bf16 v[84:87], v[158:161], v[216:219], v[84:87]
	v_mfma_f32_16x16x32_bf16 v[80:83], v[174:177], v[216:219], v[80:83]
	v_mfma_f32_16x16x32_bf16 v[20:23], v[186:189], v[216:219], v[20:23]
	v_mfma_f32_16x16x32_bf16 v[16:19], v[194:197], v[216:219], v[16:19]
	v_mfma_f32_16x16x32_bf16 v[76:79], v[158:161], v[224:227], v[76:79]
	v_mfma_f32_16x16x32_bf16 v[72:75], v[174:177], v[224:227], v[72:75]
	v_mfma_f32_16x16x32_bf16 v[12:15], v[186:189], v[224:227], v[12:15]
	v_mfma_f32_16x16x32_bf16 v[8:11], v[194:197], v[224:227], v[8:11]
	v_mfma_f32_16x16x32_bf16 v[60:63], v[158:161], v[232:235], v[60:63]
	v_mfma_f32_16x16x32_bf16 v[56:59], v[174:177], v[232:235], v[56:59]
	v_lshl_add_u64 v[178:179], v[238:239], 0, s[8:9]
	s_mov_b32 m0, s67
	s_nop 0
	global_load_lds_dwordx4 v[178:179], off
	v_mfma_f32_16x16x32_bf16 v[4:7], v[186:189], v[232:235], v[4:7]
	v_mfma_f32_16x16x32_bf16 v[0:3], v[194:197], v[232:235], v[0:3]
	s_setprio 0
	s_barrier
	s_add_i32 s93, s93, 2
	s_add_u32 s54, s54, 0x100
	s_addc_u32 s55, s55, 0
	s_add_u32 s91, s91, 0x100
	s_addc_u32 s92, s92, 0
.LBB0_417:
	ds_read_b128 v[154:157], v169
	ds_read_b128 v[158:161], v169 offset:1024
	ds_read_b128 v[162:165], v169 offset:2048
	ds_read_b128 v[174:177], v169 offset:3072
	ds_read_b128 v[182:185], v170
	ds_read_b128 v[186:189], v170 offset:1024
	ds_read_b128 v[190:193], v170 offset:2048
	ds_read_b128 v[194:197], v170 offset:3072
	s_add_u32 s3, s54, 0xfffc0080
	s_addc_u32 s14, s55, -1
	s_cmp_eq_u32 s93, 12
	s_cselect_b32 s59, s45, s14
	s_cselect_b32 s58, s89, s3
	s_cselect_b32 s57, s41, s92
	s_cselect_b32 s56, s90, s91
	v_lshl_add_u64 v[178:179], s[54:55], 0, v[146:147]
	s_add_i32 m0, s60, 0xc000
	ds_read_b128 v[198:201], v171
	ds_read_b128 v[208:211], v171 offset:1024
	ds_read_b128 v[212:215], v171 offset:2048
	ds_read_b128 v[216:219], v171 offset:3072
	ds_read_b128 v[220:223], v171 offset:4096
	ds_read_b128 v[224:227], v171 offset:5120
	ds_read_b128 v[228:231], v171 offset:6144
	ds_read_b128 v[232:235], v171 offset:7168
	global_load_lds_dwordx4 v[178:179], off
	v_lshl_add_u64 v[178:179], s[54:55], 0, v[148:149]
	s_add_i32 m0, s60, 0xe000
	s_nop 0
	global_load_lds_dwordx4 v[178:179], off
	s_waitcnt vmcnt(8)
	s_waitcnt lgkmcnt(0)
	s_barrier
; #define PG8_STAGE(bufoff, gbase, voff) do { _Pragma("unroll") for (int _i = 0; _i < 2; ++_i) \
;         __builtin_amdgcn_global_load_lds((const unsigned*)((const char*)(gbase) + (voff)[_i]), (PG8_LAS unsigned*)(lds + (bufoff) + ldsw + _i * 8192), 16, 0, 0); } while (0)
; #define PG8_LDA(dst, b, h) do { _Pragma("unroll") for (int m = 0; m < 4; ++m) _Pragma("unroll") for (int k = 0; k < 2; ++k) dst[m][k] = *(const PG8_LAS bf16x8*)(lds + PG8_SA(b, h) + aoff + m * 2048 + k * 1024); } while (0)
; #define PG8_MMA(ai, bj, At, Bt) do { __builtin_amdgcn_s_setprio(1); _Pragma("unroll") for (int m = 0; m < 4; ++m) _Pragma("unroll") for (int n = 0; n < 2; ++n) _Pragma("unroll") for (int k = 0; k < 2; ++k) \
;         acc[ai][bj][m][n] = __builtin_amdgcn_mfma_f32_16x16x32_bf16(Bt[n][k], At[m][k], acc[ai][bj][m][n], 0, 0, 0); __builtin_amdgcn_s_setprio(0); } while (0)
; #define PG8_WAIT_V(n) asm volatile("s_waitcnt vmcnt(" #n ")" ::: "memory")
; #define PG8_WAIT_L(n) asm volatile("s_waitcnt lgkmcnt(" #n ")" ::: "memory")
; #define PG8_BAR __builtin_amdgcn_s_barrier()
; #define PG8_SCHED __builtin_amdgcn_sched_barrier(0)
; template <class Epi, class Sched, bool ALIGN_EPI = false, bool SP2 = false>
; __device__ __forceinline__ void gemm_phase(PG8_LAS unsigned char* lds, const Gemm g, const Sched& S, const Epi& E) {
;     ...
;             PG8_WAIT_V(8); PG8_WAIT_L(0); PG8_BAR; PG8_MMA(0, 0, At, B0); PG8_MMA(0, 1, At, B1); PG8_BAR; PG8_SCHED;
;             PG8_LDA(At, 0, 1); PG8_STAGE(PG8_SB(0, 0), b2, voffB); PG8_STAGE(PG8_SB(0, 1), b2 + hstep, voffB); PG8_STAGE(PG8_SA(0, 0), a2, voffA);
;             PG8_WAIT_V(8); PG8_WAIT_L(0); PG8_BAR; PG8_MMA(1, 0, At, B0); PG8_MMA(1, 1, At, B1); PG8_BAR; PG8_SCHED;
	s_setprio 1
	s_waitcnt lgkmcnt(0)
	v_mfma_f32_16x16x32_bf16 v[124:127], v[154:157], v[198:201], v[124:127]
	v_mfma_f32_16x16x32_bf16 v[120:123], v[162:165], v[198:201], v[120:123]
	v_mfma_f32_16x16x32_bf16 v[68:71], v[182:185], v[198:201], v[68:71]
	v_mfma_f32_16x16x32_bf16 v[64:67], v[190:193], v[198:201], v[64:67]
	v_mfma_f32_16x16x32_bf16 v[116:119], v[154:157], v[212:215], v[116:119]
	v_mfma_f32_16x16x32_bf16 v[112:115], v[162:165], v[212:215], v[112:115]
	v_mfma_f32_16x16x32_bf16 v[52:55], v[182:185], v[212:215], v[52:55]
	v_mfma_f32_16x16x32_bf16 v[48:51], v[190:193], v[212:215], v[48:51]
	v_mfma_f32_16x16x32_bf16 v[108:111], v[154:157], v[220:223], v[108:111]
	v_mfma_f32_16x16x32_bf16 v[104:107], v[162:165], v[220:223], v[104:107]
	v_mfma_f32_16x16x32_bf16 v[44:47], v[182:185], v[220:223], v[44:47]
	v_mfma_f32_16x16x32_bf16 v[40:43], v[190:193], v[220:223], v[40:43]
	v_mfma_f32_16x16x32_bf16 v[100:103], v[154:157], v[228:231], v[100:103]
	v_mfma_f32_16x16x32_bf16 v[96:99], v[162:165], v[228:231], v[96:99]
	v_mfma_f32_16x16x32_bf16 v[36:39], v[182:185], v[228:231], v[36:39]
	v_mfma_f32_16x16x32_bf16 v[32:35], v[190:193], v[228:231], v[32:35]
	s_setprio 0
	s_setprio 1
	v_mfma_f32_16x16x32_bf16 v[124:127], v[158:161], v[208:211], v[124:127]
	v_mfma_f32_16x16x32_bf16 v[120:123], v[174:177], v[208:211], v[120:123]
	v_mfma_f32_16x16x32_bf16 v[68:71], v[186:189], v[208:211], v[68:71]
	v_mfma_f32_16x16x32_bf16 v[64:67], v[194:197], v[208:211], v[64:67]
	v_mfma_f32_16x16x32_bf16 v[116:119], v[158:161], v[216:219], v[116:119]
	v_mfma_f32_16x16x32_bf16 v[112:115], v[174:177], v[216:219], v[112:115]
	v_mfma_f32_16x16x32_bf16 v[52:55], v[186:189], v[216:219], v[52:55]
	v_mfma_f32_16x16x32_bf16 v[48:51], v[194:197], v[216:219], v[48:51]
	v_mfma_f32_16x16x32_bf16 v[108:111], v[158:161], v[224:227], v[108:111]
	v_mfma_f32_16x16x32_bf16 v[104:107], v[174:177], v[224:227], v[104:107]
	v_mfma_f32_16x16x32_bf16 v[44:47], v[186:189], v[224:227], v[44:47]
	v_mfma_f32_16x16x32_bf16 v[40:43], v[194:197], v[224:227], v[40:43]
	v_mfma_f32_16x16x32_bf16 v[100:103], v[158:161], v[232:235], v[100:103]
	v_mfma_f32_16x16x32_bf16 v[96:99], v[174:177], v[232:235], v[96:99]
	v_mfma_f32_16x16x32_bf16 v[36:39], v[186:189], v[232:235], v[36:39]
	v_mfma_f32_16x16x32_bf16 v[32:35], v[194:197], v[232:235], v[32:35]
	s_setprio 0
	s_barrier
	s_add_i32 s3, s86, s34
	v_lshl_add_u64 v[178:179], s[56:57], 0, v[132:133]
	s_mov_b32 m0, s3
	ds_read_b128 v[198:201], v171 offset:16384
	ds_read_b128 v[208:211], v171 offset:17408
	ds_read_b128 v[212:215], v171 offset:18432
	ds_read_b128 v[216:219], v171 offset:19456
	ds_read_b128 v[220:223], v171 offset:20480
	ds_read_b128 v[224:227], v171 offset:21504
	ds_read_b128 v[228:231], v171 offset:22528
	ds_read_b128 v[232:235], v171 offset:23552
	global_load_lds_dwordx4 v[178:179], off
	s_add_i32 m0, s3, 0x2000
	s_add_u32 s14, s56, 0x40000
	v_lshl_add_u64 v[202:203], s[56:57], 0, v[128:129]
	s_addc_u32 s15, s57, 0
	s_add_i32 s3, s87, s34
	global_load_lds_dwordx4 v[202:203], off
	v_lshl_add_u64 v[236:237], s[14:15], 0, v[132:133]
	s_mov_b32 m0, s3
	global_load_lds_dwordx4 v[236:237], off
	v_lshl_add_u64 v[236:237], s[14:15], 0, v[128:129]
	s_add_i32 m0, s3, 0x2000
	s_nop 0
	global_load_lds_dwordx4 v[236:237], off
	s_waitcnt vmcnt(6)
	s_waitcnt lgkmcnt(0)
	s_barrier
	s_setprio 1
	s_waitcnt lgkmcnt(0)
	v_mfma_f32_16x16x32_bf16 v[92:95], v[154:157], v[198:201], v[92:95]
	v_mfma_f32_16x16x32_bf16 v[88:91], v[162:165], v[198:201], v[88:91]
	v_mfma_f32_16x16x32_bf16 v[28:31], v[182:185], v[198:201], v[28:31]
	v_mfma_f32_16x16x32_bf16 v[24:27], v[190:193], v[198:201], v[24:27]
	v_mfma_f32_16x16x32_bf16 v[84:87], v[154:157], v[212:215], v[84:87]
	v_mfma_f32_16x16x32_bf16 v[80:83], v[162:165], v[212:215], v[80:83]
	v_mfma_f32_16x16x32_bf16 v[20:23], v[182:185], v[212:215], v[20:23]
	v_mfma_f32_16x16x32_bf16 v[16:19], v[190:193], v[212:215], v[16:19]
	v_mfma_f32_16x16x32_bf16 v[76:79], v[154:157], v[220:223], v[76:79]
	v_mfma_f32_16x16x32_bf16 v[72:75], v[162:165], v[220:223], v[72:75]
	v_mfma_f32_16x16x32_bf16 v[12:15], v[182:185], v[220:223], v[12:15]
	v_mfma_f32_16x16x32_bf16 v[8:11], v[190:193], v[220:223], v[8:11]
	v_mfma_f32_16x16x32_bf16 v[60:63], v[154:157], v[228:231], v[60:63]
	v_mfma_f32_16x16x32_bf16 v[56:59], v[162:165], v[228:231], v[56:59]
	v_lshl_add_u64 v[236:237], s[58:59], 0, v[134:135]
	s_mov_b32 m0, s60
	s_nop 0
	global_load_lds_dwordx4 v[236:237], off
	v_mfma_f32_16x16x32_bf16 v[4:7], v[182:185], v[228:231], v[4:7]
	v_mfma_f32_16x16x32_bf16 v[0:3], v[190:193], v[228:231], v[0:3]
	s_setprio 0
	s_setprio 1
	v_mfma_f32_16x16x32_bf16 v[92:95], v[158:161], v[208:211], v[92:95]
	v_mfma_f32_16x16x32_bf16 v[88:91], v[174:177], v[208:211], v[88:91]
	v_mfma_f32_16x16x32_bf16 v[28:31], v[186:189], v[208:211], v[28:31]
	v_mfma_f32_16x16x32_bf16 v[24:27], v[194:197], v[208:211], v[24:27]
	v_mfma_f32_16x16x32_bf16 v[84:87], v[158:161], v[216:219], v[84:87]
	v_mfma_f32_16x16x32_bf16 v[80:83], v[174:177], v[216:219], v[80:83]
	v_mfma_f32_16x16x32_bf16 v[20:23], v[186:189], v[216:219], v[20:23]
	v_mfma_f32_16x16x32_bf16 v[16:19], v[194:197], v[216:219], v[16:19]
	v_mfma_f32_16x16x32_bf16 v[76:79], v[158:161], v[224:227], v[76:79]
	v_mfma_f32_16x16x32_bf16 v[72:75], v[174:177], v[224:227], v[72:75]
	v_mfma_f32_16x16x32_bf16 v[12:15], v[186:189], v[224:227], v[12:15]
	v_mfma_f32_16x16x32_bf16 v[8:11], v[194:197], v[224:227], v[8:11]
	v_mfma_f32_16x16x32_bf16 v[60:63], v[158:161], v[232:235], v[60:63]
	v_mfma_f32_16x16x32_bf16 v[56:59], v[174:177], v[232:235], v[56:59]
	v_lshl_add_u64 v[238:239], s[58:59], 0, v[130:131]
	s_mov_b32 m0, s61
	s_nop 0
	global_load_lds_dwordx4 v[238:239], off
	v_mfma_f32_16x16x32_bf16 v[4:7], v[186:189], v[232:235], v[4:7]
	v_mfma_f32_16x16x32_bf16 v[0:3], v[194:197], v[232:235], v[0:3]
	s_setprio 0
	s_barrier
; #define PG8_STAGE(bufoff, gbase, voff) do { _Pragma("unroll") for (int _i = 0; _i < 2; ++_i) \
;         __builtin_amdgcn_global_load_lds((const unsigned*)((const char*)(gbase) + (voff)[_i]), (PG8_LAS unsigned*)(lds + (bufoff) + ldsw + _i * 8192), 16, 0, 0); } while (0)
; #define PG8_LDA(dst, b, h) do { _Pragma("unroll") for (int m = 0; m < 4; ++m) _Pragma("unroll") for (int k = 0; k < 2; ++k) dst[m][k] = *(const PG8_LAS bf16x8*)(lds + PG8_SA(b, h) + aoff + m * 2048 + k * 1024); } while (0)
; #define PG8_LDB(dst, b, h) do { _Pragma("unroll") for (int n = 0; n < 2; ++n) _Pragma("unroll") for (int k = 0; k < 2; ++k) dst[n][k] = *(const PG8_LAS bf16x8*)(lds + PG8_SB(b, h) + boff + n * 2048 + k * 1024); } while (0)
; #define PG8_MMA(ai, bj, At, Bt) do { __builtin_amdgcn_s_setprio(1); _Pragma("unroll") for (int m = 0; m < 4; ++m) _Pragma("unroll") for (int n = 0; n < 2; ++n) _Pragma("unroll") for (int k = 0; k < 2; ++k) \
;         acc[ai][bj][m][n] = __builtin_amdgcn_mfma_f32_16x16x32_bf16(Bt[n][k], At[m][k], acc[ai][bj][m][n], 0, 0, 0); __builtin_amdgcn_s_setprio(0); } while (0)
; #define PG8_WAIT_V(n) asm volatile("s_waitcnt vmcnt(" #n ")" ::: "memory")
; #define PG8_WAIT_L(n) asm volatile("s_waitcnt lgkmcnt(" #n ")" ::: "memory")
; #define PG8_BAR __builtin_amdgcn_s_barrier()
; #define PG8_SCHED __builtin_amdgcn_sched_barrier(0)
; template <class Epi, class Sched, bool ALIGN_EPI = false, bool SP2 = false>
; __device__ __forceinline__ void gemm_phase(PG8_LAS unsigned char* lds, const Gemm g, const Sched& S, const Epi& E) {
;     ...
;             PG8_LDB(B0, 1, 0); PG8_LDB(B1, 1, 1); PG8_SCHED; PG8_LDA(At, 1, 0); PG8_STAGE(PG8_SA(0, 1), a2 + hstep, voffA);
;             PG8_WAIT_V(8); PG8_WAIT_L(0); PG8_BAR; PG8_MMA(0, 0, At, B0); PG8_MMA(0, 1, At, B1); PG8_BAR; PG8_SCHED;
	s_add_i32 s3, 0, 0x18000
	v_add_u32_e32 v136, s3, v143
	s_add_i32 s33, 0, 0x1c000
	ds_read_b128 v[154:157], v136
	ds_read_b128 v[158:161], v136 offset:1024
	ds_read_b128 v[162:165], v136 offset:2048
	ds_read_b128 v[174:177], v136 offset:3072
	v_add_u32_e32 v136, s33, v143
	ds_read_b128 v[182:185], v136
	ds_read_b128 v[186:189], v136 offset:1024
	ds_read_b128 v[190:193], v136 offset:2048
	ds_read_b128 v[194:197], v136 offset:3072
	s_add_u32 s14, s58, 0x40000
	s_addc_u32 s15, s59, 0
	s_mov_b32 m0, s62
	v_lshl_add_u64 v[240:241], s[14:15], 0, v[134:135]
	ds_read_b128 v[198:201], v171 offset:32768
	ds_read_b128 v[208:211], v171 offset:33792
	ds_read_b128 v[212:215], v171 offset:34816
	ds_read_b128 v[216:219], v171 offset:35840
	ds_read_b128 v[220:223], v171 offset:36864
	ds_read_b128 v[224:227], v171 offset:37888
	ds_read_b128 v[228:231], v171 offset:38912
	ds_read_b128 v[232:235], v171 offset:39936
	global_load_lds_dwordx4 v[240:241], off
	v_lshl_add_u64 v[240:241], s[14:15], 0, v[130:131]
	s_mov_b32 m0, s63
	s_nop 0
	global_load_lds_dwordx4 v[240:241], off
	s_waitcnt vmcnt(8)
	s_waitcnt lgkmcnt(0)
	s_barrier
	s_setprio 1
	s_waitcnt lgkmcnt(0)
	v_mfma_f32_16x16x32_bf16 v[124:127], v[154:157], v[198:201], v[124:127]
	v_mfma_f32_16x16x32_bf16 v[120:123], v[162:165], v[198:201], v[120:123]
	v_mfma_f32_16x16x32_bf16 v[68:71], v[182:185], v[198:201], v[68:71]
	v_mfma_f32_16x16x32_bf16 v[64:67], v[190:193], v[198:201], v[64:67]
	v_mfma_f32_16x16x32_bf16 v[116:119], v[154:157], v[212:215], v[116:119]
	v_mfma_f32_16x16x32_bf16 v[112:115], v[162:165], v[212:215], v[112:115]
	v_mfma_f32_16x16x32_bf16 v[52:55], v[182:185], v[212:215], v[52:55]
	v_mfma_f32_16x16x32_bf16 v[48:51], v[190:193], v[212:215], v[48:51]
	v_mfma_f32_16x16x32_bf16 v[108:111], v[154:157], v[220:223], v[108:111]
	v_mfma_f32_16x16x32_bf16 v[104:107], v[162:165], v[220:223], v[104:107]
	v_mfma_f32_16x16x32_bf16 v[44:47], v[182:185], v[220:223], v[44:47]
	v_mfma_f32_16x16x32_bf16 v[40:43], v[190:193], v[220:223], v[40:43]
	v_mfma_f32_16x16x32_bf16 v[100:103], v[154:157], v[228:231], v[100:103]
	v_mfma_f32_16x16x32_bf16 v[96:99], v[162:165], v[228:231], v[96:99]
	v_mfma_f32_16x16x32_bf16 v[36:39], v[182:185], v[228:231], v[36:39]
	v_mfma_f32_16x16x32_bf16 v[32:35], v[190:193], v[228:231], v[32:35]
	s_setprio 0
	s_setprio 1
	v_mfma_f32_16x16x32_bf16 v[124:127], v[158:161], v[208:211], v[124:127]
	v_mfma_f32_16x16x32_bf16 v[120:123], v[174:177], v[208:211], v[120:123]
	v_mfma_f32_16x16x32_bf16 v[68:71], v[186:189], v[208:211], v[68:71]
	v_mfma_f32_16x16x32_bf16 v[64:67], v[194:197], v[208:211], v[64:67]
	v_mfma_f32_16x16x32_bf16 v[116:119], v[158:161], v[216:219], v[116:119]
	v_mfma_f32_16x16x32_bf16 v[112:115], v[174:177], v[216:219], v[112:115]
	v_mfma_f32_16x16x32_bf16 v[52:55], v[186:189], v[216:219], v[52:55]
	v_mfma_f32_16x16x32_bf16 v[48:51], v[194:197], v[216:219], v[48:51]
	v_mfma_f32_16x16x32_bf16 v[108:111], v[158:161], v[224:227], v[108:111]
	v_mfma_f32_16x16x32_bf16 v[104:107], v[174:177], v[224:227], v[104:107]
	v_mfma_f32_16x16x32_bf16 v[44:47], v[186:189], v[224:227], v[44:47]
	v_mfma_f32_16x16x32_bf16 v[40:43], v[194:197], v[224:227], v[40:43]
	v_mfma_f32_16x16x32_bf16 v[100:103], v[158:161], v[232:235], v[100:103]
	v_mfma_f32_16x16x32_bf16 v[96:99], v[174:177], v[232:235], v[96:99]
	v_mfma_f32_16x16x32_bf16 v[36:39], v[186:189], v[232:235], v[36:39]
	v_mfma_f32_16x16x32_bf16 v[32:35], v[194:197], v[232:235], v[32:35]
	s_setprio 0
	s_barrier
; #define PG8_STAGE(bufoff, gbase, voff) do { _Pragma("unroll") for (int _i = 0; _i < 2; ++_i) \
;         __builtin_amdgcn_global_load_lds((const unsigned*)((const char*)(gbase) + (voff)[_i]), (PG8_LAS unsigned*)(lds + (bufoff) + ldsw + _i * 8192), 16, 0, 0); } while (0)
; #define PG8_LDA(dst, b, h) do { _Pragma("unroll") for (int m = 0; m < 4; ++m) _Pragma("unroll") for (int k = 0; k < 2; ++k) dst[m][k] = *(const PG8_LAS bf16x8*)(lds + PG8_SA(b, h) + aoff + m * 2048 + k * 1024); } while (0)
; #define PG8_MMA(ai, bj, At, Bt) do { __builtin_amdgcn_s_setprio(1); _Pragma("unroll") for (int m = 0; m < 4; ++m) _Pragma("unroll") for (int n = 0; n < 2; ++n) _Pragma("unroll") for (int k = 0; k < 2; ++k) \
;         acc[ai][bj][m][n] = __builtin_amdgcn_mfma_f32_16x16x32_bf16(Bt[n][k], At[m][k], acc[ai][bj][m][n], 0, 0, 0); __builtin_amdgcn_s_setprio(0); } while (0)
; #define PG8_WAIT_V(n) asm volatile("s_waitcnt vmcnt(" #n ")" ::: "memory")
; #define PG8_WAIT_L(n) asm volatile("s_waitcnt lgkmcnt(" #n ")" ::: "memory")
; #define PG8_BAR __builtin_amdgcn_s_barrier()
; #define PG8_SCHED __builtin_amdgcn_sched_barrier(0)
; template <class Epi, class Sched, bool ALIGN_EPI = false, bool SP2 = false>
; __device__ __forceinline__ void gemm_phase(PG8_LAS unsigned char* lds, const Gemm g, const Sched& S, const Epi& E) {
;     ...
;             PG8_LDA(At, 1, 1); PG8_STAGE(PG8_SB(1, 0), b3, voffB); PG8_STAGE(PG8_SB(1, 1), b3 + hstep, voffB); PG8_STAGE(PG8_SA(1, 0), a3, voffA);
;             PG8_WAIT_V(8); PG8_WAIT_L(0); PG8_BAR; PG8_MMA(1, 0, At, B0); PG8_MMA(1, 1, At, B1); PG8_BAR; PG8_SCHED;
;     ...
;         if constexpr (ALIGN_EPI) { if (wr == 0) PG8_BAR; }
	s_add_i32 s3, s3, s34
	v_lshl_add_u64 v[178:179], v[178:179], 0, s[8:9]
	s_mov_b32 m0, s3
	ds_read_b128 v[198:201], v171 offset:49152
	ds_read_b128 v[208:211], v171 offset:50176
	ds_read_b128 v[212:215], v171 offset:51200
	ds_read_b128 v[216:219], v171 offset:52224
	ds_read_b128 v[220:223], v171 offset:53248
	ds_read_b128 v[224:227], v171 offset:54272
	ds_read_b128 v[228:231], v171 offset:55296
	ds_read_b128 v[232:235], v171 offset:56320
	global_load_lds_dwordx4 v[178:179], off
	s_add_i32 m0, s3, 0x2000
	s_add_u32 s14, s56, 0x40080
	v_lshl_add_u64 v[178:179], v[202:203], 0, s[8:9]
	s_addc_u32 s15, s57, 0
	s_add_i32 s3, s33, s34
	global_load_lds_dwordx4 v[178:179], off
	v_lshl_add_u64 v[178:179], s[14:15], 0, v[132:133]
	s_mov_b32 m0, s3
	s_nop 0
	global_load_lds_dwordx4 v[178:179], off
	v_lshl_add_u64 v[178:179], s[14:15], 0, v[128:129]
	s_add_i32 m0, s3, 0x2000
	s_nop 0
	global_load_lds_dwordx4 v[178:179], off
	s_waitcnt vmcnt(6)
	s_waitcnt lgkmcnt(0)
	s_barrier
	s_setprio 1
	s_waitcnt lgkmcnt(0)
	v_mfma_f32_16x16x32_bf16 v[92:95], v[154:157], v[198:201], v[92:95]
	v_mfma_f32_16x16x32_bf16 v[88:91], v[162:165], v[198:201], v[88:91]
	v_mfma_f32_16x16x32_bf16 v[28:31], v[182:185], v[198:201], v[28:31]
	v_mfma_f32_16x16x32_bf16 v[24:27], v[190:193], v[198:201], v[24:27]
	v_mfma_f32_16x16x32_bf16 v[84:87], v[154:157], v[212:215], v[84:87]
	v_mfma_f32_16x16x32_bf16 v[80:83], v[162:165], v[212:215], v[80:83]
	v_mfma_f32_16x16x32_bf16 v[20:23], v[182:185], v[212:215], v[20:23]
	v_mfma_f32_16x16x32_bf16 v[16:19], v[190:193], v[212:215], v[16:19]
	v_mfma_f32_16x16x32_bf16 v[76:79], v[154:157], v[220:223], v[76:79]
	v_mfma_f32_16x16x32_bf16 v[72:75], v[162:165], v[220:223], v[72:75]
	v_mfma_f32_16x16x32_bf16 v[12:15], v[182:185], v[220:223], v[12:15]
	v_mfma_f32_16x16x32_bf16 v[8:11], v[190:193], v[220:223], v[8:11]
	v_mfma_f32_16x16x32_bf16 v[60:63], v[154:157], v[228:231], v[60:63]
	v_mfma_f32_16x16x32_bf16 v[56:59], v[162:165], v[228:231], v[56:59]
	v_lshl_add_u64 v[178:179], v[236:237], 0, s[8:9]
	s_mov_b32 m0, s66
	s_nop 0
	global_load_lds_dwordx4 v[178:179], off
	v_mfma_f32_16x16x32_bf16 v[4:7], v[182:185], v[228:231], v[4:7]
	v_mfma_f32_16x16x32_bf16 v[0:3], v[190:193], v[228:231], v[0:3]
	s_setprio 0
	s_setprio 1
	v_mfma_f32_16x16x32_bf16 v[92:95], v[158:161], v[208:211], v[92:95]
	v_mfma_f32_16x16x32_bf16 v[88:91], v[174:177], v[208:211], v[88:91]
	v_mfma_f32_16x16x32_bf16 v[28:31], v[186:189], v[208:211], v[28:31]
	v_mfma_f32_16x16x32_bf16 v[24:27], v[194:197], v[208:211], v[24:27]
	v_mfma_f32_16x16x32_bf16 v[84:87], v[158:161], v[216:219], v[84:87]
	v_mfma_f32_16x16x32_bf16 v[80:83], v[174:177], v[216:219], v[80:83]
	v_mfma_f32_16x16x32_bf16 v[20:23], v[186:189], v[216:219], v[20:23]
	v_mfma_f32_16x16x32_bf16 v[16:19], v[194:197], v[216:219], v[16:19]
	v_mfma_f32_16x16x32_bf16 v[76:79], v[158:161], v[224:227], v[76:79]
	v_mfma_f32_16x16x32_bf16 v[72:75], v[174:177], v[224:227], v[72:75]
	v_mfma_f32_16x16x32_bf16 v[12:15], v[186:189], v[224:227], v[12:15]
	v_mfma_f32_16x16x32_bf16 v[8:11], v[194:197], v[224:227], v[8:11]
	v_mfma_f32_16x16x32_bf16 v[60:63], v[158:161], v[232:235], v[60:63]
	v_mfma_f32_16x16x32_bf16 v[56:59], v[174:177], v[232:235], v[56:59]
	v_lshl_add_u64 v[178:179], v[238:239], 0, s[8:9]
	s_mov_b32 m0, s67
	s_nop 0
	global_load_lds_dwordx4 v[178:179], off
	v_mfma_f32_16x16x32_bf16 v[4:7], v[186:189], v[232:235], v[4:7]
	v_mfma_f32_16x16x32_bf16 v[0:3], v[194:197], v[232:235], v[0:3]
	s_setprio 0
	s_barrier
	s_add_i32 s93, s93, 2
	s_add_u32 s54, s54, 0x100
	s_addc_u32 s55, s55, 0
	s_add_u32 s91, s91, 0x100
	s_addc_u32 s92, s92, 0
	s_cmp_gt_u32 s93, 13
	s_cbranch_scc0 .LBB0_417
	s_and_b64 vcc, exec, s[10:11]
	s_cbranch_vccz .LBB0_420
	s_barrier

; #define PG8_STAGE(bufoff, gbase, voff) do { _Pragma("unroll") for (int _i = 0; _i < 2; ++_i) \
;         __builtin_amdgcn_global_load_lds((const unsigned*)((const char*)(gbase) + (voff)[_i]), (PG8_LAS unsigned*)(lds + (bufoff) + ldsw + _i * 8192), 16, 0, 0); } while (0)
; #define PG8_LDA(dst, b, h) do { _Pragma("unroll") for (int m = 0; m < 4; ++m) _Pragma("unroll") for (int k = 0; k < 2; ++k) dst[m][k] = *(const PG8_LAS bf16x8*)(lds + PG8_SA(b, h) + aoff + m * 2048 + k * 1024); } while (0)
; #define PG8_LDB(dst, b, h) do { _Pragma("unroll") for (int n = 0; n < 2; ++n) _Pragma("unroll") for (int k = 0; k < 2; ++k) dst[n][k] = *(const PG8_LAS bf16x8*)(lds + PG8_SB(b, h) + boff + n * 2048 + k * 1024); } while (0)
; #define PG8_WAIT_V(n) asm volatile("s_waitcnt vmcnt(" #n ")" ::: "memory")
; #define PG8_WAIT_L(n) asm volatile("s_waitcnt lgkmcnt(" #n ")" ::: "memory")
; #define PG8_BAR __builtin_amdgcn_s_barrier()
; #define PG8_SCHED __builtin_amdgcn_sched_barrier(0)
; template <class Epi, class Sched, bool ALIGN_EPI = false, bool SP2 = false>
; __device__ __forceinline__ void gemm_phase(PG8_LAS unsigned char* lds, const Gemm g, const Sched& S, const Epi& E) {
;     ...
;         const bool has_next = S.next(ui + 1, nxt);
;         const char* nA = has_next ? (const char*)g.A + (size_t)nxt.pm * tstep : cA; const char* nB = has_next ? (const char*)g.Bt + (size_t)nxt.pn * tstep : cB;
;         for (int t = 0; t < nt; t += 2) {
;             const bool last = (t == nt - 2);
;             const char* a1 = cA + (size_t)(t + 1) * kstep;
;             const char* a2 = last ? nA : cA + (size_t)(t + 2) * kstep; const char* b2 = last ? nB : cB + (size_t)(t + 2) * kstep;
;             const char* a3 = a2 + kstep; const char* b3 = b2 + kstep;
;             if (last && has_next) S.a_ready(nxt);
;             if constexpr (SP2) {
;             PG8_LDB(B0, 0, 0); PG8_LDB(B1, 0, 1); PG8_SCHED; PG8_LDA(At, 0, 0); PG8_STAGE(PG8_SA(1, 1), a1 + hstep, voffA);
;             PG8_WAIT_V(8); PG8_WAIT_L(0); PG8_BAR; PG8_MMA(0, 0, At, B0); PG8_MMA(0, 1, At, B1); PG8_BAR; PG8_SCHED;
;             PG8_LDA(At, 0, 1); PG8_STAGE(PG8_SB(0, 0), b2, voffB); PG8_STAGE(PG8_SB(0, 1), b2 + hstep, voffB); PG8_STAGE(PG8_SA(0, 0), a2, voffA);
;             PG8_WAIT_V(8); PG8_WAIT_L(0); PG8_BAR; PG8_MMA(1, 0, At, B0); PG8_MMA(1, 1, At, B1); PG8_BAR; PG8_SCHED;
.LBB0_458:
	s_ashr_i32 s49, s48, 31
	s_lshl_b64 s[14:15], s[48:49], 19
	s_add_u32 s50, s34, s14
	s_addc_u32 s51, s43, s15
	s_and_b64 s[14:15], s[40:41], exec
	s_cselect_b32 s49, s51, s59
	s_cselect_b32 s55, s50, s58
	s_ashr_i32 s45, s44, 31
	s_lshl_b64 s[14:15], s[44:45], 19
	v_readlane_b32 s3, v250, 13
	s_add_u32 s52, s3, s14
	v_readlane_b32 s3, v250, 14
	s_addc_u32 s53, s3, s15
	s_and_b64 s[14:15], s[40:41], exec
	s_cselect_b32 s45, s53, s61
	s_cselect_b32 s57, s52, s60
	s_add_u32 s58, s58, 0x40080
	s_addc_u32 s59, s59, 0
	s_add_u32 s96, s60, 0x100
	s_addc_u32 s97, s61, 0
	s_mov_b32 vcc_lo, -2
	ds_read_b128 v[170:173], v165
	ds_read_b128 v[174:177], v165 offset:1024
	ds_read_b128 v[182:185], v165 offset:2048
	ds_read_b128 v[186:189], v165 offset:3072
	ds_read_b128 v[190:193], v168
	ds_read_b128 v[194:197], v168 offset:1024
	ds_read_b128 v[198:201], v168 offset:2048
	ds_read_b128 v[208:211], v168 offset:3072
	s_add_u32 s3, s58, 0xfffc0080
	s_addc_u32 s14, s59, -1
	s_cmp_eq_u32 vcc_lo, 12
	s_cselect_b32 s63, s49, s14
	s_cselect_b32 s62, s55, s3
	s_cselect_b32 s61, s45, s97
	s_cselect_b32 s60, s57, s96
	v_lshl_add_u64 v[178:179], s[58:59], 0, v[160:161]
	s_add_i32 m0, s85, 0xc000
	ds_read_b128 v[212:215], v164
	ds_read_b128 v[216:219], v164 offset:1024
	ds_read_b128 v[220:223], v164 offset:2048
	ds_read_b128 v[224:227], v164 offset:3072
	ds_read_b128 v[228:231], v164 offset:4096
	ds_read_b128 v[232:235], v164 offset:5120
	ds_read_b128 v[236:239], v164 offset:6144
	ds_read_b128 v[240:243], v164 offset:7168
	global_load_lds_dwordx4 v[178:179], off
	v_lshl_add_u64 v[178:179], s[58:59], 0, v[162:163]
	s_add_i32 m0, s85, 0xe000
	s_nop 0
	global_load_lds_dwordx4 v[178:179], off
	s_waitcnt vmcnt(8)
	s_waitcnt lgkmcnt(0)
	s_barrier
	s_setprio 1
	s_waitcnt lgkmcnt(0)
	v_mfma_f32_16x16x32_bf16 v[124:127], v[170:173], v[212:215], 0
	v_mfma_f32_16x16x32_bf16 v[120:123], v[182:185], v[212:215], 0
	v_mfma_f32_16x16x32_bf16 v[60:63], v[190:193], v[212:215], 0
	v_mfma_f32_16x16x32_bf16 v[56:59], v[198:201], v[212:215], 0
	v_mfma_f32_16x16x32_bf16 v[116:119], v[170:173], v[220:223], 0
	v_mfma_f32_16x16x32_bf16 v[112:115], v[182:185], v[220:223], 0
	v_mfma_f32_16x16x32_bf16 v[52:55], v[190:193], v[220:223], 0
	v_mfma_f32_16x16x32_bf16 v[48:51], v[198:201], v[220:223], 0
	v_mfma_f32_16x16x32_bf16 v[108:111], v[170:173], v[228:231], 0
	v_mfma_f32_16x16x32_bf16 v[104:107], v[182:185], v[228:231], 0
	v_mfma_f32_16x16x32_bf16 v[44:47], v[190:193], v[228:231], 0
	v_mfma_f32_16x16x32_bf16 v[40:43], v[198:201], v[228:231], 0
	v_mfma_f32_16x16x32_bf16 v[100:103], v[170:173], v[236:239], 0
	v_mfma_f32_16x16x32_bf16 v[96:99], v[182:185], v[236:239], 0
	v_mfma_f32_16x16x32_bf16 v[36:39], v[190:193], v[236:239], 0
	v_mfma_f32_16x16x32_bf16 v[32:35], v[198:201], v[236:239], 0
	s_setprio 0
	s_setprio 1
	v_mfma_f32_16x16x32_bf16 v[124:127], v[174:177], v[216:219], v[124:127]
	v_mfma_f32_16x16x32_bf16 v[120:123], v[186:189], v[216:219], v[120:123]
	v_mfma_f32_16x16x32_bf16 v[60:63], v[194:197], v[216:219], v[60:63]
	v_mfma_f32_16x16x32_bf16 v[56:59], v[208:211], v[216:219], v[56:59]
	v_mfma_f32_16x16x32_bf16 v[116:119], v[174:177], v[224:227], v[116:119]
	v_mfma_f32_16x16x32_bf16 v[112:115], v[186:189], v[224:227], v[112:115]
	v_mfma_f32_16x16x32_bf16 v[52:55], v[194:197], v[224:227], v[52:55]
	v_mfma_f32_16x16x32_bf16 v[48:51], v[208:211], v[224:227], v[48:51]
	v_mfma_f32_16x16x32_bf16 v[108:111], v[174:177], v[232:235], v[108:111]
	v_mfma_f32_16x16x32_bf16 v[104:107], v[186:189], v[232:235], v[104:107]
	v_mfma_f32_16x16x32_bf16 v[44:47], v[194:197], v[232:235], v[44:47]
	v_mfma_f32_16x16x32_bf16 v[40:43], v[208:211], v[232:235], v[40:43]
	v_mfma_f32_16x16x32_bf16 v[100:103], v[174:177], v[240:243], v[100:103]
	v_mfma_f32_16x16x32_bf16 v[96:99], v[186:189], v[240:243], v[96:99]
	v_mfma_f32_16x16x32_bf16 v[36:39], v[194:197], v[240:243], v[36:39]
	v_mfma_f32_16x16x32_bf16 v[32:35], v[208:211], v[240:243], v[32:35]
	s_setprio 0
	s_barrier
	s_add_i32 s3, s94, s84
	v_lshl_add_u64 v[178:179], s[60:61], 0, v[130:131]
	s_mov_b32 m0, s3
	ds_read_b128 v[212:215], v164 offset:16384
	ds_read_b128 v[216:219], v164 offset:17408
	ds_read_b128 v[220:223], v164 offset:18432
	ds_read_b128 v[224:227], v164 offset:19456
	ds_read_b128 v[228:231], v164 offset:20480
	ds_read_b128 v[232:235], v164 offset:21504
	ds_read_b128 v[236:239], v164 offset:22528
	ds_read_b128 v[240:243], v164 offset:23552
	global_load_lds_dwordx4 v[178:179], off
	s_add_i32 m0, s3, 0x2000
	s_add_u32 s14, s60, 0x40000
	v_lshl_add_u64 v[202:203], s[60:61], 0, v[134:135]
	s_addc_u32 s15, s61, 0
	s_add_i32 s3, s95, s84
	global_load_lds_dwordx4 v[202:203], off
	v_lshl_add_u64 v[244:245], s[14:15], 0, v[130:131]
	s_mov_b32 m0, s3
	global_load_lds_dwordx4 v[244:245], off
	v_lshl_add_u64 v[244:245], s[14:15], 0, v[134:135]
	s_add_i32 m0, s3, 0x2000
	s_nop 0
	global_load_lds_dwordx4 v[244:245], off
	s_waitcnt vmcnt(6)
	s_waitcnt lgkmcnt(0)
	s_barrier
; #define PG8_STAGE(bufoff, gbase, voff) do { _Pragma("unroll") for (int _i = 0; _i < 2; ++_i) \
;         __builtin_amdgcn_global_load_lds((const unsigned*)((const char*)(gbase) + (voff)[_i]), (PG8_LAS unsigned*)(lds + (bufoff) + ldsw + _i * 8192), 16, 0, 0); } while (0)
; #define PG8_LDA(dst, b, h) do { _Pragma("unroll") for (int m = 0; m < 4; ++m) _Pragma("unroll") for (int k = 0; k < 2; ++k) dst[m][k] = *(const PG8_LAS bf16x8*)(lds + PG8_SA(b, h) + aoff + m * 2048 + k * 1024); } while (0)
; #define PG8_LDB(dst, b, h) do { _Pragma("unroll") for (int n = 0; n < 2; ++n) _Pragma("unroll") for (int k = 0; k < 2; ++k) dst[n][k] = *(const PG8_LAS bf16x8*)(lds + PG8_SB(b, h) + boff + n * 2048 + k * 1024); } while (0)
; #define PG8_MMA(ai, bj, At, Bt) do { __builtin_amdgcn_s_setprio(1); _Pragma("unroll") for (int m = 0; m < 4; ++m) _Pragma("unroll") for (int n = 0; n < 2; ++n) _Pragma("unroll") for (int k = 0; k < 2; ++k) \
;         acc[ai][bj][m][n] = __builtin_amdgcn_mfma_f32_16x16x32_bf16(Bt[n][k], At[m][k], acc[ai][bj][m][n], 0, 0, 0); __builtin_amdgcn_s_setprio(0); } while (0)
; #define PG8_WAIT_V(n) asm volatile("s_waitcnt vmcnt(" #n ")" ::: "memory")
; #define PG8_WAIT_L(n) asm volatile("s_waitcnt lgkmcnt(" #n ")" ::: "memory")
; #define PG8_BAR __builtin_amdgcn_s_barrier()
; #define PG8_SCHED __builtin_amdgcn_sched_barrier(0)
; template <class Epi, class Sched, bool ALIGN_EPI = false, bool SP2 = false>
; __device__ __forceinline__ void gemm_phase(PG8_LAS unsigned char* lds, const Gemm g, const Sched& S, const Epi& E) {
;     ...
;             PG8_WAIT_V(8); PG8_WAIT_L(0); PG8_BAR; PG8_MMA(1, 0, At, B0); PG8_MMA(1, 1, At, B1); PG8_BAR; PG8_SCHED;
;             PG8_LDB(B0, 1, 0); PG8_LDB(B1, 1, 1); PG8_SCHED; PG8_LDA(At, 1, 0); PG8_STAGE(PG8_SA(0, 1), a2 + hstep, voffA);
;             PG8_WAIT_V(8); PG8_WAIT_L(0); PG8_BAR; PG8_MMA(0, 0, At, B0); PG8_MMA(0, 1, At, B1); PG8_BAR; PG8_SCHED;
	s_setprio 1
	s_waitcnt lgkmcnt(0)
	v_mfma_f32_16x16x32_bf16 v[92:95], v[170:173], v[212:215], 0
	v_mfma_f32_16x16x32_bf16 v[88:91], v[182:185], v[212:215], 0
	v_mfma_f32_16x16x32_bf16 v[28:31], v[190:193], v[212:215], 0
	v_mfma_f32_16x16x32_bf16 v[24:27], v[198:201], v[212:215], 0
	v_mfma_f32_16x16x32_bf16 v[84:87], v[170:173], v[220:223], 0
	v_mfma_f32_16x16x32_bf16 v[80:83], v[182:185], v[220:223], 0
	v_mfma_f32_16x16x32_bf16 v[20:23], v[190:193], v[220:223], 0
	v_mfma_f32_16x16x32_bf16 v[16:19], v[198:201], v[220:223], 0
	v_mfma_f32_16x16x32_bf16 v[76:79], v[170:173], v[228:231], 0
	v_mfma_f32_16x16x32_bf16 v[72:75], v[182:185], v[228:231], 0
	v_mfma_f32_16x16x32_bf16 v[12:15], v[190:193], v[228:231], 0
	v_mfma_f32_16x16x32_bf16 v[8:11], v[198:201], v[228:231], 0
	v_mfma_f32_16x16x32_bf16 v[68:71], v[170:173], v[236:239], 0
	v_mfma_f32_16x16x32_bf16 v[64:67], v[182:185], v[236:239], 0
	v_lshl_add_u64 v[244:245], s[62:63], 0, v[128:129]
	s_mov_b32 m0, s85
	s_nop 0
	global_load_lds_dwordx4 v[244:245], off
	v_mfma_f32_16x16x32_bf16 v[4:7], v[190:193], v[236:239], 0
	v_mfma_f32_16x16x32_bf16 v[0:3], v[198:201], v[236:239], 0
	s_setprio 0
	s_setprio 1
	v_mfma_f32_16x16x32_bf16 v[92:95], v[174:177], v[216:219], v[92:95]
	v_mfma_f32_16x16x32_bf16 v[88:91], v[186:189], v[216:219], v[88:91]
	v_mfma_f32_16x16x32_bf16 v[28:31], v[194:197], v[216:219], v[28:31]
	v_mfma_f32_16x16x32_bf16 v[24:27], v[208:211], v[216:219], v[24:27]
	v_mfma_f32_16x16x32_bf16 v[84:87], v[174:177], v[224:227], v[84:87]
	v_mfma_f32_16x16x32_bf16 v[80:83], v[186:189], v[224:227], v[80:83]
	v_mfma_f32_16x16x32_bf16 v[20:23], v[194:197], v[224:227], v[20:23]
	v_mfma_f32_16x16x32_bf16 v[16:19], v[208:211], v[224:227], v[16:19]
	v_mfma_f32_16x16x32_bf16 v[76:79], v[174:177], v[232:235], v[76:79]
	v_mfma_f32_16x16x32_bf16 v[72:75], v[186:189], v[232:235], v[72:75]
	v_mfma_f32_16x16x32_bf16 v[12:15], v[194:197], v[232:235], v[12:15]
	v_mfma_f32_16x16x32_bf16 v[8:11], v[208:211], v[232:235], v[8:11]
	v_mfma_f32_16x16x32_bf16 v[68:71], v[174:177], v[240:243], v[68:71]
	v_mfma_f32_16x16x32_bf16 v[64:67], v[186:189], v[240:243], v[64:67]
	v_lshl_add_u64 v[246:247], s[62:63], 0, v[132:133]
	s_mov_b32 m0, s86
	s_nop 0
	global_load_lds_dwordx4 v[246:247], off
	v_mfma_f32_16x16x32_bf16 v[4:7], v[194:197], v[240:243], v[4:7]
	v_mfma_f32_16x16x32_bf16 v[0:3], v[208:211], v[240:243], v[0:3]
	s_setprio 0
	s_barrier
	s_add_i32 s3, 0, 0x18000
	v_add_u32_e32 v136, s3, v141
	s_add_i32 s33, 0, 0x1c000
	ds_read_b128 v[170:173], v136
	ds_read_b128 v[174:177], v136 offset:1024
	ds_read_b128 v[182:185], v136 offset:2048
	ds_read_b128 v[186:189], v136 offset:3072
	v_add_u32_e32 v136, s33, v141
	ds_read_b128 v[190:193], v136
	ds_read_b128 v[194:197], v136 offset:1024
	ds_read_b128 v[198:201], v136 offset:2048
	ds_read_b128 v[208:211], v136 offset:3072
	s_add_u32 s14, s62, 0x40000
	s_addc_u32 s15, s63, 0
	s_mov_b32 m0, s87
	v_lshl_add_u64 v[248:249], s[14:15], 0, v[128:129]
	ds_read_b128 v[212:215], v164 offset:32768
	ds_read_b128 v[216:219], v164 offset:33792
	ds_read_b128 v[220:223], v164 offset:34816
	ds_read_b128 v[224:227], v164 offset:35840
	ds_read_b128 v[228:231], v164 offset:36864
	ds_read_b128 v[232:235], v164 offset:37888
	ds_read_b128 v[236:239], v164 offset:38912
	ds_read_b128 v[240:243], v164 offset:39936
	global_load_lds_dwordx4 v[248:249], off
	v_lshl_add_u64 v[248:249], s[14:15], 0, v[132:133]
	s_mov_b32 m0, s88
	s_nop 0
	global_load_lds_dwordx4 v[248:249], off
	s_waitcnt vmcnt(8)
	s_waitcnt lgkmcnt(0)
	s_barrier
	s_setprio 1
	s_waitcnt lgkmcnt(0)
	v_mfma_f32_16x16x32_bf16 v[124:127], v[170:173], v[212:215], v[124:127]
	v_mfma_f32_16x16x32_bf16 v[120:123], v[182:185], v[212:215], v[120:123]
	v_mfma_f32_16x16x32_bf16 v[60:63], v[190:193], v[212:215], v[60:63]
	v_mfma_f32_16x16x32_bf16 v[56:59], v[198:201], v[212:215], v[56:59]
	v_mfma_f32_16x16x32_bf16 v[116:119], v[170:173], v[220:223], v[116:119]
	v_mfma_f32_16x16x32_bf16 v[112:115], v[182:185], v[220:223], v[112:115]
	v_mfma_f32_16x16x32_bf16 v[52:55], v[190:193], v[220:223], v[52:55]
	v_mfma_f32_16x16x32_bf16 v[48:51], v[198:201], v[220:223], v[48:51]
	v_mfma_f32_16x16x32_bf16 v[108:111], v[170:173], v[228:231], v[108:111]
	v_mfma_f32_16x16x32_bf16 v[104:107], v[182:185], v[228:231], v[104:107]
	v_mfma_f32_16x16x32_bf16 v[44:47], v[190:193], v[228:231], v[44:47]
	v_mfma_f32_16x16x32_bf16 v[40:43], v[198:201], v[228:231], v[40:43]
	v_mfma_f32_16x16x32_bf16 v[100:103], v[170:173], v[236:239], v[100:103]
	v_mfma_f32_16x16x32_bf16 v[96:99], v[182:185], v[236:239], v[96:99]
	v_mfma_f32_16x16x32_bf16 v[36:39], v[190:193], v[236:239], v[36:39]
	v_mfma_f32_16x16x32_bf16 v[32:35], v[198:201], v[236:239], v[32:35]
	s_setprio 0
	s_setprio 1
	v_mfma_f32_16x16x32_bf16 v[124:127], v[174:177], v[216:219], v[124:127]
	v_mfma_f32_16x16x32_bf16 v[120:123], v[186:189], v[216:219], v[120:123]
	v_mfma_f32_16x16x32_bf16 v[60:63], v[194:197], v[216:219], v[60:63]
	v_mfma_f32_16x16x32_bf16 v[56:59], v[208:211], v[216:219], v[56:59]
	v_mfma_f32_16x16x32_bf16 v[116:119], v[174:177], v[224:227], v[116:119]
	v_mfma_f32_16x16x32_bf16 v[112:115], v[186:189], v[224:227], v[112:115]
	v_mfma_f32_16x16x32_bf16 v[52:55], v[194:197], v[224:227], v[52:55]
	v_mfma_f32_16x16x32_bf16 v[48:51], v[208:211], v[224:227], v[48:51]
	v_mfma_f32_16x16x32_bf16 v[108:111], v[174:177], v[232:235], v[108:111]
	v_mfma_f32_16x16x32_bf16 v[104:107], v[186:189], v[232:235], v[104:107]
	v_mfma_f32_16x16x32_bf16 v[44:47], v[194:197], v[232:235], v[44:47]
	v_mfma_f32_16x16x32_bf16 v[40:43], v[208:211], v[232:235], v[40:43]
	v_mfma_f32_16x16x32_bf16 v[100:103], v[174:177], v[240:243], v[100:103]
	v_mfma_f32_16x16x32_bf16 v[96:99], v[186:189], v[240:243], v[96:99]
	v_mfma_f32_16x16x32_bf16 v[36:39], v[194:197], v[240:243], v[36:39]
	v_mfma_f32_16x16x32_bf16 v[32:35], v[208:211], v[240:243], v[32:35]
	s_setprio 0
	s_barrier
; #define PG8_STAGE(bufoff, gbase, voff) do { _Pragma("unroll") for (int _i = 0; _i < 2; ++_i) \
;         __builtin_amdgcn_global_load_lds((const unsigned*)((const char*)(gbase) + (voff)[_i]), (PG8_LAS unsigned*)(lds + (bufoff) + ldsw + _i * 8192), 16, 0, 0); } while (0)
; #define PG8_LDA(dst, b, h) do { _Pragma("unroll") for (int m = 0; m < 4; ++m) _Pragma("unroll") for (int k = 0; k < 2; ++k) dst[m][k] = *(const PG8_LAS bf16x8*)(lds + PG8_SA(b, h) + aoff + m * 2048 + k * 1024); } while (0)
; #define PG8_LDB(dst, b, h) do { _Pragma("unroll") for (int n = 0; n < 2; ++n) _Pragma("unroll") for (int k = 0; k < 2; ++k) dst[n][k] = *(const PG8_LAS bf16x8*)(lds + PG8_SB(b, h) + boff + n * 2048 + k * 1024); } while (0)
; #define PG8_MMA(ai, bj, At, Bt) do { __builtin_amdgcn_s_setprio(1); _Pragma("unroll") for (int m = 0; m < 4; ++m) _Pragma("unroll") for (int n = 0; n < 2; ++n) _Pragma("unroll") for (int k = 0; k < 2; ++k) \
;         acc[ai][bj][m][n] = __builtin_amdgcn_mfma_f32_16x16x32_bf16(Bt[n][k], At[m][k], acc[ai][bj][m][n], 0, 0, 0); __builtin_amdgcn_s_setprio(0); } while (0)
; #define PG8_WAIT_V(n) asm volatile("s_waitcnt vmcnt(" #n ")" ::: "memory")
; template <class Epi, class Sched, bool ALIGN_EPI = false, bool SP2 = false>
; __device__ __forceinline__ void gemm_phase(PG8_LAS unsigned char* lds, const Gemm g, const Sched& S, const Epi& E) {
;     ...
;             PG8_LDB(B0, 0, 0); PG8_LDB(B1, 0, 1); PG8_SCHED; PG8_LDA(At, 0, 0); PG8_STAGE(PG8_SA(1, 1), a1 + hstep, voffA);
;             PG8_WAIT_V(8); PG8_WAIT_L(0); PG8_BAR; PG8_MMA(0, 0, At, B0); PG8_MMA(0, 1, At, B1); PG8_BAR; PG8_SCHED;
;             PG8_LDA(At, 0, 1); PG8_STAGE(PG8_SB(0, 0), b2, voffB); PG8_STAGE(PG8_SB(0, 1), b2 + hstep, voffB); PG8_STAGE(PG8_SA(0, 0), a2, voffA);
;             PG8_WAIT_V(8); PG8_WAIT_L(0); PG8_BAR; PG8_MMA(1, 0, At, B0); PG8_MMA(1, 1, At, B1); PG8_BAR; PG8_SCHED;
;             PG8_LDB(B0, 1, 0); PG8_LDB(B1, 1, 1); PG8_SCHED; PG8_LDA(At, 1, 0); PG8_STAGE(PG8_SA(0, 1), a2 + hstep, voffA);
;             PG8_WAIT_V(8); PG8_WAIT_L(0); PG8_BAR; PG8_MMA(0, 0, At, B0); PG8_MMA(0, 1, At, B1); PG8_BAR; PG8_SCHED;
;             PG8_LDA(At, 1, 1); PG8_STAGE(PG8_SB(1, 0), b3, voffB); PG8_STAGE(PG8_SB(1, 1), b3 + hstep, voffB); PG8_STAGE(PG8_SA(1, 0), a3, voffA);
;             PG8_WAIT_V(8); PG8_WAIT_L(0); PG8_BAR; PG8_MMA(1, 0, At, B0); PG8_MMA(1, 1, At, B1); PG8_BAR; PG8_SCHED;
	s_add_i32 s3, s3, s84
	v_lshl_add_u64 v[178:179], v[178:179], 0, s[8:9]
	s_mov_b32 m0, s3
	ds_read_b128 v[212:215], v164 offset:49152
	ds_read_b128 v[216:219], v164 offset:50176
	ds_read_b128 v[220:223], v164 offset:51200
	ds_read_b128 v[224:227], v164 offset:52224
	ds_read_b128 v[228:231], v164 offset:53248
	ds_read_b128 v[232:235], v164 offset:54272
	ds_read_b128 v[236:239], v164 offset:55296
	ds_read_b128 v[240:243], v164 offset:56320
	global_load_lds_dwordx4 v[178:179], off
	s_add_i32 m0, s3, 0x2000
	s_add_u32 s14, s60, 0x40080
	v_lshl_add_u64 v[178:179], v[202:203], 0, s[8:9]
	s_addc_u32 s15, s61, 0
	s_add_i32 s3, s33, s84
	global_load_lds_dwordx4 v[178:179], off
	v_lshl_add_u64 v[178:179], s[14:15], 0, v[130:131]
	s_mov_b32 m0, s3
	s_nop 0
	global_load_lds_dwordx4 v[178:179], off
	v_lshl_add_u64 v[178:179], s[14:15], 0, v[134:135]
	s_add_i32 m0, s3, 0x2000
	s_nop 0
	global_load_lds_dwordx4 v[178:179], off
	s_waitcnt vmcnt(6)
	s_waitcnt lgkmcnt(0)
	s_barrier
	s_setprio 1
	s_waitcnt lgkmcnt(0)
	v_mfma_f32_16x16x32_bf16 v[92:95], v[170:173], v[212:215], v[92:95]
	v_mfma_f32_16x16x32_bf16 v[88:91], v[182:185], v[212:215], v[88:91]
	v_mfma_f32_16x16x32_bf16 v[28:31], v[190:193], v[212:215], v[28:31]
	v_mfma_f32_16x16x32_bf16 v[24:27], v[198:201], v[212:215], v[24:27]
	v_mfma_f32_16x16x32_bf16 v[84:87], v[170:173], v[220:223], v[84:87]
	v_mfma_f32_16x16x32_bf16 v[80:83], v[182:185], v[220:223], v[80:83]
	v_mfma_f32_16x16x32_bf16 v[20:23], v[190:193], v[220:223], v[20:23]
	v_mfma_f32_16x16x32_bf16 v[16:19], v[198:201], v[220:223], v[16:19]
	v_mfma_f32_16x16x32_bf16 v[76:79], v[170:173], v[228:231], v[76:79]
	v_mfma_f32_16x16x32_bf16 v[72:75], v[182:185], v[228:231], v[72:75]
	v_mfma_f32_16x16x32_bf16 v[12:15], v[190:193], v[228:231], v[12:15]
	v_mfma_f32_16x16x32_bf16 v[8:11], v[198:201], v[228:231], v[8:11]
	v_mfma_f32_16x16x32_bf16 v[68:71], v[170:173], v[236:239], v[68:71]
	v_mfma_f32_16x16x32_bf16 v[64:67], v[182:185], v[236:239], v[64:67]
	v_lshl_add_u64 v[178:179], v[244:245], 0, s[8:9]
	s_mov_b32 m0, s90
	s_nop 0
	global_load_lds_dwordx4 v[178:179], off
	v_mfma_f32_16x16x32_bf16 v[4:7], v[190:193], v[236:239], v[4:7]
	v_mfma_f32_16x16x32_bf16 v[0:3], v[198:201], v[236:239], v[0:3]
	s_setprio 0
	s_setprio 1
	v_mfma_f32_16x16x32_bf16 v[92:95], v[174:177], v[216:219], v[92:95]
	v_mfma_f32_16x16x32_bf16 v[88:91], v[186:189], v[216:219], v[88:91]
	v_mfma_f32_16x16x32_bf16 v[28:31], v[194:197], v[216:219], v[28:31]
	v_mfma_f32_16x16x32_bf16 v[24:27], v[208:211], v[216:219], v[24:27]
	v_mfma_f32_16x16x32_bf16 v[84:87], v[174:177], v[224:227], v[84:87]
	v_mfma_f32_16x16x32_bf16 v[80:83], v[186:189], v[224:227], v[80:83]
	v_mfma_f32_16x16x32_bf16 v[20:23], v[194:197], v[224:227], v[20:23]
	v_mfma_f32_16x16x32_bf16 v[16:19], v[208:211], v[224:227], v[16:19]
	v_mfma_f32_16x16x32_bf16 v[76:79], v[174:177], v[232:235], v[76:79]
	v_mfma_f32_16x16x32_bf16 v[72:75], v[186:189], v[232:235], v[72:75]
	v_mfma_f32_16x16x32_bf16 v[12:15], v[194:197], v[232:235], v[12:15]
	v_mfma_f32_16x16x32_bf16 v[8:11], v[208:211], v[232:235], v[8:11]
	v_mfma_f32_16x16x32_bf16 v[68:71], v[174:177], v[240:243], v[68:71]
	v_mfma_f32_16x16x32_bf16 v[64:67], v[186:189], v[240:243], v[64:67]
	v_lshl_add_u64 v[178:179], v[246:247], 0, s[8:9]
	s_mov_b32 m0, s91
	s_nop 0
	global_load_lds_dwordx4 v[178:179], off
	v_mfma_f32_16x16x32_bf16 v[4:7], v[194:197], v[240:243], v[4:7]
	v_mfma_f32_16x16x32_bf16 v[0:3], v[208:211], v[240:243], v[0:3]
	s_setprio 0
	s_barrier
	s_add_i32 vcc_lo, vcc_lo, 2
	s_add_u32 s58, s58, 0x100
	s_addc_u32 s59, s59, 0
	s_add_u32 s96, s96, 0x100
	s_addc_u32 s97, s97, 0
.LBB0_459:
	ds_read_b128 v[170:173], v165
	ds_read_b128 v[174:177], v165 offset:1024
	ds_read_b128 v[182:185], v165 offset:2048
	ds_read_b128 v[186:189], v165 offset:3072
	ds_read_b128 v[190:193], v168
	ds_read_b128 v[194:197], v168 offset:1024
	ds_read_b128 v[198:201], v168 offset:2048
	ds_read_b128 v[208:211], v168 offset:3072
	s_add_u32 s3, s58, 0xfffc0080
	s_addc_u32 s14, s59, -1
	s_cmp_eq_u32 vcc_lo, 12
	s_cselect_b32 s63, s49, s14
	s_cselect_b32 s62, s55, s3
	s_cselect_b32 s61, s45, s97
	s_cselect_b32 s60, s57, s96
	v_lshl_add_u64 v[178:179], s[58:59], 0, v[160:161]
	s_add_i32 m0, s85, 0xc000
	ds_read_b128 v[212:215], v164
	ds_read_b128 v[216:219], v164 offset:1024
	ds_read_b128 v[220:223], v164 offset:2048
	ds_read_b128 v[224:227], v164 offset:3072
	ds_read_b128 v[228:231], v164 offset:4096
	ds_read_b128 v[232:235], v164 offset:5120
	ds_read_b128 v[236:239], v164 offset:6144
	ds_read_b128 v[240:243], v164 offset:7168
	global_load_lds_dwordx4 v[178:179], off
	v_lshl_add_u64 v[178:179], s[58:59], 0, v[162:163]
	s_add_i32 m0, s85, 0xe000
	s_nop 0
	global_load_lds_dwordx4 v[178:179], off
	s_waitcnt vmcnt(8)
	s_waitcnt lgkmcnt(0)
	s_barrier
; #define PG8_STAGE(bufoff, gbase, voff) do { _Pragma("unroll") for (int _i = 0; _i < 2; ++_i) \
;         __builtin_amdgcn_global_load_lds((const unsigned*)((const char*)(gbase) + (voff)[_i]), (PG8_LAS unsigned*)(lds + (bufoff) + ldsw + _i * 8192), 16, 0, 0); } while (0)
; #define PG8_LDA(dst, b, h) do { _Pragma("unroll") for (int m = 0; m < 4; ++m) _Pragma("unroll") for (int k = 0; k < 2; ++k) dst[m][k] = *(const PG8_LAS bf16x8*)(lds + PG8_SA(b, h) + aoff + m * 2048 + k * 1024); } while (0)
; #define PG8_LDB(dst, b, h) do { _Pragma("unroll") for (int n = 0; n < 2; ++n) _Pragma("unroll") for (int k = 0; k < 2; ++k) dst[n][k] = *(const PG8_LAS bf16x8*)(lds + PG8_SB(b, h) + boff + n * 2048 + k * 1024); } while (0)
; #define PG8_MMA(ai, bj, At, Bt) do { __builtin_amdgcn_s_setprio(1); _Pragma("unroll") for (int m = 0; m < 4; ++m) _Pragma("unroll") for (int n = 0; n < 2; ++n) _Pragma("unroll") for (int k = 0; k < 2; ++k) \
;         acc[ai][bj][m][n] = __builtin_amdgcn_mfma_f32_16x16x32_bf16(Bt[n][k], At[m][k], acc[ai][bj][m][n], 0, 0, 0); __builtin_amdgcn_s_setprio(0); } while (0)
; #define PG8_WAIT_V(n) asm volatile("s_waitcnt vmcnt(" #n ")" ::: "memory")
; #define PG8_WAIT_L(n) asm volatile("s_waitcnt lgkmcnt(" #n ")" ::: "memory")
; #define PG8_BAR __builtin_amdgcn_s_barrier()
; #define PG8_SCHED __builtin_amdgcn_sched_barrier(0)
; template <class Epi, class Sched, bool ALIGN_EPI = false, bool SP2 = false>
; __device__ __forceinline__ void gemm_phase(PG8_LAS unsigned char* lds, const Gemm g, const Sched& S, const Epi& E) {
;     ...
;             PG8_LDB(B0, 0, 0); PG8_LDB(B1, 0, 1); PG8_SCHED; PG8_LDA(At, 0, 0); PG8_STAGE(PG8_SA(1, 1), a1 + hstep, voffA);
;             PG8_WAIT_V(8); PG8_WAIT_L(0); PG8_BAR; PG8_MMA(0, 0, At, B0); PG8_MMA(0, 1, At, B1); PG8_BAR; PG8_SCHED;
;             PG8_LDA(At, 0, 1); PG8_STAGE(PG8_SB(0, 0), b2, voffB); PG8_STAGE(PG8_SB(0, 1), b2 + hstep, voffB); PG8_STAGE(PG8_SA(0, 0), a2, voffA);
;             PG8_WAIT_V(8); PG8_WAIT_L(0); PG8_BAR; PG8_MMA(1, 0, At, B0); PG8_MMA(1, 1, At, B1); PG8_BAR; PG8_SCHED;
	s_setprio 1
	s_waitcnt lgkmcnt(0)
	v_mfma_f32_16x16x32_bf16 v[124:127], v[170:173], v[212:215], v[124:127]
	v_mfma_f32_16x16x32_bf16 v[120:123], v[182:185], v[212:215], v[120:123]
	v_mfma_f32_16x16x32_bf16 v[60:63], v[190:193], v[212:215], v[60:63]
	v_mfma_f32_16x16x32_bf16 v[56:59], v[198:201], v[212:215], v[56:59]
	v_mfma_f32_16x16x32_bf16 v[116:119], v[170:173], v[220:223], v[116:119]
	v_mfma_f32_16x16x32_bf16 v[112:115], v[182:185], v[220:223], v[112:115]
	v_mfma_f32_16x16x32_bf16 v[52:55], v[190:193], v[220:223], v[52:55]
	v_mfma_f32_16x16x32_bf16 v[48:51], v[198:201], v[220:223], v[48:51]
	v_mfma_f32_16x16x32_bf16 v[108:111], v[170:173], v[228:231], v[108:111]
	v_mfma_f32_16x16x32_bf16 v[104:107], v[182:185], v[228:231], v[104:107]
	v_mfma_f32_16x16x32_bf16 v[44:47], v[190:193], v[228:231], v[44:47]
	v_mfma_f32_16x16x32_bf16 v[40:43], v[198:201], v[228:231], v[40:43]
	v_mfma_f32_16x16x32_bf16 v[100:103], v[170:173], v[236:239], v[100:103]
	v_mfma_f32_16x16x32_bf16 v[96:99], v[182:185], v[236:239], v[96:99]
	v_mfma_f32_16x16x32_bf16 v[36:39], v[190:193], v[236:239], v[36:39]
	v_mfma_f32_16x16x32_bf16 v[32:35], v[198:201], v[236:239], v[32:35]
	s_setprio 0
	s_setprio 1
	v_mfma_f32_16x16x32_bf16 v[124:127], v[174:177], v[216:219], v[124:127]
	v_mfma_f32_16x16x32_bf16 v[120:123], v[186:189], v[216:219], v[120:123]
	v_mfma_f32_16x16x32_bf16 v[60:63], v[194:197], v[216:219], v[60:63]
	v_mfma_f32_16x16x32_bf16 v[56:59], v[208:211], v[216:219], v[56:59]
	v_mfma_f32_16x16x32_bf16 v[116:119], v[174:177], v[224:227], v[116:119]
	v_mfma_f32_16x16x32_bf16 v[112:115], v[186:189], v[224:227], v[112:115]
	v_mfma_f32_16x16x32_bf16 v[52:55], v[194:197], v[224:227], v[52:55]
	v_mfma_f32_16x16x32_bf16 v[48:51], v[208:211], v[224:227], v[48:51]
	v_mfma_f32_16x16x32_bf16 v[108:111], v[174:177], v[232:235], v[108:111]
	v_mfma_f32_16x16x32_bf16 v[104:107], v[186:189], v[232:235], v[104:107]
	v_mfma_f32_16x16x32_bf16 v[44:47], v[194:197], v[232:235], v[44:47]
	v_mfma_f32_16x16x32_bf16 v[40:43], v[208:211], v[232:235], v[40:43]
	v_mfma_f32_16x16x32_bf16 v[100:103], v[174:177], v[240:243], v[100:103]
	v_mfma_f32_16x16x32_bf16 v[96:99], v[186:189], v[240:243], v[96:99]
	v_mfma_f32_16x16x32_bf16 v[36:39], v[194:197], v[240:243], v[36:39]
	v_mfma_f32_16x16x32_bf16 v[32:35], v[208:211], v[240:243], v[32:35]
	s_setprio 0
	s_barrier
	s_add_i32 s3, s94, s84
	v_lshl_add_u64 v[178:179], s[60:61], 0, v[130:131]
	s_mov_b32 m0, s3
	ds_read_b128 v[212:215], v164 offset:16384
	ds_read_b128 v[216:219], v164 offset:17408
	ds_read_b128 v[220:223], v164 offset:18432
	ds_read_b128 v[224:227], v164 offset:19456
	ds_read_b128 v[228:231], v164 offset:20480
	ds_read_b128 v[232:235], v164 offset:21504
	ds_read_b128 v[236:239], v164 offset:22528
	ds_read_b128 v[240:243], v164 offset:23552
	global_load_lds_dwordx4 v[178:179], off
	s_add_i32 m0, s3, 0x2000
	s_add_u32 s14, s60, 0x40000
	v_lshl_add_u64 v[202:203], s[60:61], 0, v[134:135]
	s_addc_u32 s15, s61, 0
	s_add_i32 s3, s95, s84
	global_load_lds_dwordx4 v[202:203], off
	v_lshl_add_u64 v[244:245], s[14:15], 0, v[130:131]
	s_mov_b32 m0, s3
	global_load_lds_dwordx4 v[244:245], off
	v_lshl_add_u64 v[244:245], s[14:15], 0, v[134:135]
	s_add_i32 m0, s3, 0x2000
	s_nop 0
	global_load_lds_dwordx4 v[244:245], off
	s_waitcnt vmcnt(6)
	s_waitcnt lgkmcnt(0)
	s_barrier
	s_setprio 1
	s_waitcnt lgkmcnt(0)
	v_mfma_f32_16x16x32_bf16 v[92:95], v[170:173], v[212:215], v[92:95]
	v_mfma_f32_16x16x32_bf16 v[88:91], v[182:185], v[212:215], v[88:91]
	v_mfma_f32_16x16x32_bf16 v[28:31], v[190:193], v[212:215], v[28:31]
	v_mfma_f32_16x16x32_bf16 v[24:27], v[198:201], v[212:215], v[24:27]
	v_mfma_f32_16x16x32_bf16 v[84:87], v[170:173], v[220:223], v[84:87]
	v_mfma_f32_16x16x32_bf16 v[80:83], v[182:185], v[220:223], v[80:83]
	v_mfma_f32_16x16x32_bf16 v[20:23], v[190:193], v[220:223], v[20:23]
	v_mfma_f32_16x16x32_bf16 v[16:19], v[198:201], v[220:223], v[16:19]
	v_mfma_f32_16x16x32_bf16 v[76:79], v[170:173], v[228:231], v[76:79]
	v_mfma_f32_16x16x32_bf16 v[72:75], v[182:185], v[228:231], v[72:75]
	v_mfma_f32_16x16x32_bf16 v[12:15], v[190:193], v[228:231], v[12:15]
	v_mfma_f32_16x16x32_bf16 v[8:11], v[198:201], v[228:231], v[8:11]
	v_mfma_f32_16x16x32_bf16 v[68:71], v[170:173], v[236:239], v[68:71]
	v_mfma_f32_16x16x32_bf16 v[64:67], v[182:185], v[236:239], v[64:67]
	v_lshl_add_u64 v[244:245], s[62:63], 0, v[128:129]
	s_mov_b32 m0, s85
	s_nop 0
	global_load_lds_dwordx4 v[244:245], off
	v_mfma_f32_16x16x32_bf16 v[4:7], v[190:193], v[236:239], v[4:7]
	v_mfma_f32_16x16x32_bf16 v[0:3], v[198:201], v[236:239], v[0:3]
	s_setprio 0
	s_setprio 1
	v_mfma_f32_16x16x32_bf16 v[92:95], v[174:177], v[216:219], v[92:95]
	v_mfma_f32_16x16x32_bf16 v[88:91], v[186:189], v[216:219], v[88:91]
	v_mfma_f32_16x16x32_bf16 v[28:31], v[194:197], v[216:219], v[28:31]
	v_mfma_f32_16x16x32_bf16 v[24:27], v[208:211], v[216:219], v[24:27]
	v_mfma_f32_16x16x32_bf16 v[84:87], v[174:177], v[224:227], v[84:87]
	v_mfma_f32_16x16x32_bf16 v[80:83], v[186:189], v[224:227], v[80:83]
	v_mfma_f32_16x16x32_bf16 v[20:23], v[194:197], v[224:227], v[20:23]
	v_mfma_f32_16x16x32_bf16 v[16:19], v[208:211], v[224:227], v[16:19]
	v_mfma_f32_16x16x32_bf16 v[76:79], v[174:177], v[232:235], v[76:79]
	v_mfma_f32_16x16x32_bf16 v[72:75], v[186:189], v[232:235], v[72:75]
	v_mfma_f32_16x16x32_bf16 v[12:15], v[194:197], v[232:235], v[12:15]
	v_mfma_f32_16x16x32_bf16 v[8:11], v[208:211], v[232:235], v[8:11]
	v_mfma_f32_16x16x32_bf16 v[68:71], v[174:177], v[240:243], v[68:71]
	v_mfma_f32_16x16x32_bf16 v[64:67], v[186:189], v[240:243], v[64:67]
	v_lshl_add_u64 v[246:247], s[62:63], 0, v[132:133]
	s_mov_b32 m0, s86
	s_nop 0
	global_load_lds_dwordx4 v[246:247], off
	v_mfma_f32_16x16x32_bf16 v[4:7], v[194:197], v[240:243], v[4:7]
	v_mfma_f32_16x16x32_bf16 v[0:3], v[208:211], v[240:243], v[0:3]
	s_setprio 0
	s_barrier
; #define PG8_STAGE(bufoff, gbase, voff) do { _Pragma("unroll") for (int _i = 0; _i < 2; ++_i) \
;         __builtin_amdgcn_global_load_lds((const unsigned*)((const char*)(gbase) + (voff)[_i]), (PG8_LAS unsigned*)(lds + (bufoff) + ldsw + _i * 8192), 16, 0, 0); } while (0)
; #define PG8_LDA(dst, b, h) do { _Pragma("unroll") for (int m = 0; m < 4; ++m) _Pragma("unroll") for (int k = 0; k < 2; ++k) dst[m][k] = *(const PG8_LAS bf16x8*)(lds + PG8_SA(b, h) + aoff + m * 2048 + k * 1024); } while (0)
; #define PG8_LDB(dst, b, h) do { _Pragma("unroll") for (int n = 0; n < 2; ++n) _Pragma("unroll") for (int k = 0; k < 2; ++k) dst[n][k] = *(const PG8_LAS bf16x8*)(lds + PG8_SB(b, h) + boff + n * 2048 + k * 1024); } while (0)
; #define PG8_MMA(ai, bj, At, Bt) do { __builtin_amdgcn_s_setprio(1); _Pragma("unroll") for (int m = 0; m < 4; ++m) _Pragma("unroll") for (int n = 0; n < 2; ++n) _Pragma("unroll") for (int k = 0; k < 2; ++k) \
;         acc[ai][bj][m][n] = __builtin_amdgcn_mfma_f32_16x16x32_bf16(Bt[n][k], At[m][k], acc[ai][bj][m][n], 0, 0, 0); __builtin_amdgcn_s_setprio(0); } while (0)
; #define PG8_WAIT_V(n) asm volatile("s_waitcnt vmcnt(" #n ")" ::: "memory")
; #define PG8_WAIT_L(n) asm volatile("s_waitcnt lgkmcnt(" #n ")" ::: "memory")
; #define PG8_BAR __builtin_amdgcn_s_barrier()
; #define PG8_SCHED __builtin_amdgcn_sched_barrier(0)
; template <class Epi, class Sched, bool ALIGN_EPI = false, bool SP2 = false>
; __device__ __forceinline__ void gemm_phase(PG8_LAS unsigned char* lds, const Gemm g, const Sched& S, const Epi& E) {
;     ...
;             PG8_LDB(B0, 1, 0); PG8_LDB(B1, 1, 1); PG8_SCHED; PG8_LDA(At, 1, 0); PG8_STAGE(PG8_SA(0, 1), a2 + hstep, voffA);
;             PG8_WAIT_V(8); PG8_WAIT_L(0); PG8_BAR; PG8_MMA(0, 0, At, B0); PG8_MMA(0, 1, At, B1); PG8_BAR; PG8_SCHED;
	s_add_i32 s3, 0, 0x18000
	v_add_u32_e32 v136, s3, v141
	s_add_i32 s33, 0, 0x1c000
	ds_read_b128 v[170:173], v136
	ds_read_b128 v[174:177], v136 offset:1024
	ds_read_b128 v[182:185], v136 offset:2048
	ds_read_b128 v[186:189], v136 offset:3072
	v_add_u32_e32 v136, s33, v141
	ds_read_b128 v[190:193], v136
	ds_read_b128 v[194:197], v136 offset:1024
	ds_read_b128 v[198:201], v136 offset:2048
	ds_read_b128 v[208:211], v136 offset:3072
	s_add_u32 s14, s62, 0x40000
	s_addc_u32 s15, s63, 0
	s_mov_b32 m0, s87
	v_lshl_add_u64 v[248:249], s[14:15], 0, v[128:129]
	ds_read_b128 v[212:215], v164 offset:32768
	ds_read_b128 v[216:219], v164 offset:33792
	ds_read_b128 v[220:223], v164 offset:34816
	ds_read_b128 v[224:227], v164 offset:35840
	ds_read_b128 v[228:231], v164 offset:36864
	ds_read_b128 v[232:235], v164 offset:37888
	ds_read_b128 v[236:239], v164 offset:38912
	ds_read_b128 v[240:243], v164 offset:39936
	global_load_lds_dwordx4 v[248:249], off
	v_lshl_add_u64 v[248:249], s[14:15], 0, v[132:133]
	s_mov_b32 m0, s88
	s_nop 0
	global_load_lds_dwordx4 v[248:249], off
	s_waitcnt vmcnt(8)
	s_waitcnt lgkmcnt(0)
	s_barrier
	s_setprio 1
	s_waitcnt lgkmcnt(0)
	v_mfma_f32_16x16x32_bf16 v[124:127], v[170:173], v[212:215], v[124:127]
	v_mfma_f32_16x16x32_bf16 v[120:123], v[182:185], v[212:215], v[120:123]
	v_mfma_f32_16x16x32_bf16 v[60:63], v[190:193], v[212:215], v[60:63]
	v_mfma_f32_16x16x32_bf16 v[56:59], v[198:201], v[212:215], v[56:59]
	v_mfma_f32_16x16x32_bf16 v[116:119], v[170:173], v[220:223], v[116:119]
	v_mfma_f32_16x16x32_bf16 v[112:115], v[182:185], v[220:223], v[112:115]
	v_mfma_f32_16x16x32_bf16 v[52:55], v[190:193], v[220:223], v[52:55]
	v_mfma_f32_16x16x32_bf16 v[48:51], v[198:201], v[220:223], v[48:51]
	v_mfma_f32_16x16x32_bf16 v[108:111], v[170:173], v[228:231], v[108:111]
	v_mfma_f32_16x16x32_bf16 v[104:107], v[182:185], v[228:231], v[104:107]
	v_mfma_f32_16x16x32_bf16 v[44:47], v[190:193], v[228:231], v[44:47]
	v_mfma_f32_16x16x32_bf16 v[40:43], v[198:201], v[228:231], v[40:43]
	v_mfma_f32_16x16x32_bf16 v[100:103], v[170:173], v[236:239], v[100:103]
	v_mfma_f32_16x16x32_bf16 v[96:99], v[182:185], v[236:239], v[96:99]
	v_mfma_f32_16x16x32_bf16 v[36:39], v[190:193], v[236:239], v[36:39]
	v_mfma_f32_16x16x32_bf16 v[32:35], v[198:201], v[236:239], v[32:35]
	s_setprio 0
	s_setprio 1
	v_mfma_f32_16x16x32_bf16 v[124:127], v[174:177], v[216:219], v[124:127]
	v_mfma_f32_16x16x32_bf16 v[120:123], v[186:189], v[216:219], v[120:123]
	v_mfma_f32_16x16x32_bf16 v[60:63], v[194:197], v[216:219], v[60:63]
	v_mfma_f32_16x16x32_bf16 v[56:59], v[208:211], v[216:219], v[56:59]
	v_mfma_f32_16x16x32_bf16 v[116:119], v[174:177], v[224:227], v[116:119]
	v_mfma_f32_16x16x32_bf16 v[112:115], v[186:189], v[224:227], v[112:115]
	v_mfma_f32_16x16x32_bf16 v[52:55], v[194:197], v[224:227], v[52:55]
	v_mfma_f32_16x16x32_bf16 v[48:51], v[208:211], v[224:227], v[48:51]
	v_mfma_f32_16x16x32_bf16 v[108:111], v[174:177], v[232:235], v[108:111]
	v_mfma_f32_16x16x32_bf16 v[104:107], v[186:189], v[232:235], v[104:107]
	v_mfma_f32_16x16x32_bf16 v[44:47], v[194:197], v[232:235], v[44:47]
	v_mfma_f32_16x16x32_bf16 v[40:43], v[208:211], v[232:235], v[40:43]
	v_mfma_f32_16x16x32_bf16 v[100:103], v[174:177], v[240:243], v[100:103]
	v_mfma_f32_16x16x32_bf16 v[96:99], v[186:189], v[240:243], v[96:99]
	v_mfma_f32_16x16x32_bf16 v[36:39], v[194:197], v[240:243], v[36:39]
	v_mfma_f32_16x16x32_bf16 v[32:35], v[208:211], v[240:243], v[32:35]
	s_setprio 0
	s_barrier
; #define PG8_STAGE(bufoff, gbase, voff) do { _Pragma("unroll") for (int _i = 0; _i < 2; ++_i) \
;         __builtin_amdgcn_global_load_lds((const unsigned*)((const char*)(gbase) + (voff)[_i]), (PG8_LAS unsigned*)(lds + (bufoff) + ldsw + _i * 8192), 16, 0, 0); } while (0)
; #define PG8_LDA(dst, b, h) do { _Pragma("unroll") for (int m = 0; m < 4; ++m) _Pragma("unroll") for (int k = 0; k < 2; ++k) dst[m][k] = *(const PG8_LAS bf16x8*)(lds + PG8_SA(b, h) + aoff + m * 2048 + k * 1024); } while (0)
; #define PG8_MMA(ai, bj, At, Bt) do { __builtin_amdgcn_s_setprio(1); _Pragma("unroll") for (int m = 0; m < 4; ++m) _Pragma("unroll") for (int n = 0; n < 2; ++n) _Pragma("unroll") for (int k = 0; k < 2; ++k) \
;         acc[ai][bj][m][n] = __builtin_amdgcn_mfma_f32_16x16x32_bf16(Bt[n][k], At[m][k], acc[ai][bj][m][n], 0, 0, 0); __builtin_amdgcn_s_setprio(0); } while (0)
; #define PG8_WAIT_V(n) asm volatile("s_waitcnt vmcnt(" #n ")" ::: "memory")
; #define PG8_WAIT_L(n) asm volatile("s_waitcnt lgkmcnt(" #n ")" ::: "memory")
; #define PG8_BAR __builtin_amdgcn_s_barrier()
; #define PG8_SCHED __builtin_amdgcn_sched_barrier(0)
; template <class Epi, class Sched, bool ALIGN_EPI = false, bool SP2 = false>
; __device__ __forceinline__ void gemm_phase(PG8_LAS unsigned char* lds, const Gemm g, const Sched& S, const Epi& E) {
;     ...
;             PG8_LDA(At, 1, 1); PG8_STAGE(PG8_SB(1, 0), b3, voffB); PG8_STAGE(PG8_SB(1, 1), b3 + hstep, voffB); PG8_STAGE(PG8_SA(1, 0), a3, voffA);
;             PG8_WAIT_V(8); PG8_WAIT_L(0); PG8_BAR; PG8_MMA(1, 0, At, B0); PG8_MMA(1, 1, At, B1); PG8_BAR; PG8_SCHED;
;     ...
;         if constexpr (ALIGN_EPI) { if (wr == 0) PG8_BAR; }
	s_add_i32 s3, s3, s84
	v_lshl_add_u64 v[178:179], v[178:179], 0, s[8:9]
	s_mov_b32 m0, s3
	ds_read_b128 v[212:215], v164 offset:49152
	ds_read_b128 v[216:219], v164 offset:50176
	ds_read_b128 v[220:223], v164 offset:51200
	ds_read_b128 v[224:227], v164 offset:52224
	ds_read_b128 v[228:231], v164 offset:53248
	ds_read_b128 v[232:235], v164 offset:54272
	ds_read_b128 v[236:239], v164 offset:55296
	ds_read_b128 v[240:243], v164 offset:56320
	global_load_lds_dwordx4 v[178:179], off
	s_add_i32 m0, s3, 0x2000
	s_add_u32 s14, s60, 0x40080
	v_lshl_add_u64 v[178:179], v[202:203], 0, s[8:9]
	s_addc_u32 s15, s61, 0
	s_add_i32 s3, s33, s84
	global_load_lds_dwordx4 v[178:179], off
	v_lshl_add_u64 v[178:179], s[14:15], 0, v[130:131]
	s_mov_b32 m0, s3
	s_nop 0
	global_load_lds_dwordx4 v[178:179], off
	v_lshl_add_u64 v[178:179], s[14:15], 0, v[134:135]
	s_add_i32 m0, s3, 0x2000
	s_nop 0
	global_load_lds_dwordx4 v[178:179], off
	s_waitcnt vmcnt(6)
	s_waitcnt lgkmcnt(0)
	s_barrier
	s_setprio 1
	s_waitcnt lgkmcnt(0)
	v_mfma_f32_16x16x32_bf16 v[92:95], v[170:173], v[212:215], v[92:95]
	v_mfma_f32_16x16x32_bf16 v[88:91], v[182:185], v[212:215], v[88:91]
	v_mfma_f32_16x16x32_bf16 v[28:31], v[190:193], v[212:215], v[28:31]
	v_mfma_f32_16x16x32_bf16 v[24:27], v[198:201], v[212:215], v[24:27]
	v_mfma_f32_16x16x32_bf16 v[84:87], v[170:173], v[220:223], v[84:87]
	v_mfma_f32_16x16x32_bf16 v[80:83], v[182:185], v[220:223], v[80:83]
	v_mfma_f32_16x16x32_bf16 v[20:23], v[190:193], v[220:223], v[20:23]
	v_mfma_f32_16x16x32_bf16 v[16:19], v[198:201], v[220:223], v[16:19]
	v_mfma_f32_16x16x32_bf16 v[76:79], v[170:173], v[228:231], v[76:79]
	v_mfma_f32_16x16x32_bf16 v[72:75], v[182:185], v[228:231], v[72:75]
	v_mfma_f32_16x16x32_bf16 v[12:15], v[190:193], v[228:231], v[12:15]
	v_mfma_f32_16x16x32_bf16 v[8:11], v[198:201], v[228:231], v[8:11]
	v_mfma_f32_16x16x32_bf16 v[68:71], v[170:173], v[236:239], v[68:71]
	v_mfma_f32_16x16x32_bf16 v[64:67], v[182:185], v[236:239], v[64:67]
	v_lshl_add_u64 v[178:179], v[244:245], 0, s[8:9]
	s_mov_b32 m0, s90
	s_nop 0
	global_load_lds_dwordx4 v[178:179], off
	v_mfma_f32_16x16x32_bf16 v[4:7], v[190:193], v[236:239], v[4:7]
	v_mfma_f32_16x16x32_bf16 v[0:3], v[198:201], v[236:239], v[0:3]
	s_setprio 0
	s_setprio 1
	v_mfma_f32_16x16x32_bf16 v[92:95], v[174:177], v[216:219], v[92:95]
	v_mfma_f32_16x16x32_bf16 v[88:91], v[186:189], v[216:219], v[88:91]
	v_mfma_f32_16x16x32_bf16 v[28:31], v[194:197], v[216:219], v[28:31]
	v_mfma_f32_16x16x32_bf16 v[24:27], v[208:211], v[216:219], v[24:27]
	v_mfma_f32_16x16x32_bf16 v[84:87], v[174:177], v[224:227], v[84:87]
	v_mfma_f32_16x16x32_bf16 v[80:83], v[186:189], v[224:227], v[80:83]
	v_mfma_f32_16x16x32_bf16 v[20:23], v[194:197], v[224:227], v[20:23]
	v_mfma_f32_16x16x32_bf16 v[16:19], v[208:211], v[224:227], v[16:19]
	v_mfma_f32_16x16x32_bf16 v[76:79], v[174:177], v[232:235], v[76:79]
	v_mfma_f32_16x16x32_bf16 v[72:75], v[186:189], v[232:235], v[72:75]
	v_mfma_f32_16x16x32_bf16 v[12:15], v[194:197], v[232:235], v[12:15]
	v_mfma_f32_16x16x32_bf16 v[8:11], v[208:211], v[232:235], v[8:11]
	v_mfma_f32_16x16x32_bf16 v[68:71], v[174:177], v[240:243], v[68:71]
	v_mfma_f32_16x16x32_bf16 v[64:67], v[186:189], v[240:243], v[64:67]
	v_lshl_add_u64 v[178:179], v[246:247], 0, s[8:9]
	s_mov_b32 m0, s91
	s_nop 0
	global_load_lds_dwordx4 v[178:179], off
	v_mfma_f32_16x16x32_bf16 v[4:7], v[194:197], v[240:243], v[4:7]
	v_mfma_f32_16x16x32_bf16 v[0:3], v[208:211], v[240:243], v[0:3]
	s_setprio 0
	s_barrier
	s_add_i32 vcc_lo, vcc_lo, 2
	s_add_u32 s58, s58, 0x100
	s_addc_u32 s59, s59, 0
	s_add_u32 s96, s96, 0x100
	s_addc_u32 s97, s97, 0
	s_cmp_gt_u32 vcc_lo, 13
	s_cbranch_scc0 .LBB0_459
	s_and_b64 vcc, exec, s[10:11]
	s_cbranch_vccz .LBB0_462
	s_barrier

; #define PG8_STAGE(bufoff, gbase, voff) do { _Pragma("unroll") for (int _i = 0; _i < 2; ++_i) \
;         __builtin_amdgcn_global_load_lds((const unsigned*)((const char*)(gbase) + (voff)[_i]), (PG8_LAS unsigned*)(lds + (bufoff) + ldsw + _i * 8192), 16, 0, 0); } while (0)
; #define PG8_LDA(dst, b, h) do { _Pragma("unroll") for (int m = 0; m < 4; ++m) _Pragma("unroll") for (int k = 0; k < 2; ++k) dst[m][k] = *(const PG8_LAS bf16x8*)(lds + PG8_SA(b, h) + aoff + m * 2048 + k * 1024); } while (0)
; #define PG8_LDB(dst, b, h) do { _Pragma("unroll") for (int n = 0; n < 2; ++n) _Pragma("unroll") for (int k = 0; k < 2; ++k) dst[n][k] = *(const PG8_LAS bf16x8*)(lds + PG8_SB(b, h) + boff + n * 2048 + k * 1024); } while (0)
; #define PG8_MMA(ai, bj, At, Bt) do { __builtin_amdgcn_s_setprio(1); _Pragma("unroll") for (int m = 0; m < 4; ++m) _Pragma("unroll") for (int n = 0; n < 2; ++n) _Pragma("unroll") for (int k = 0; k < 2; ++k) \
;         acc[ai][bj][m][n] = __builtin_amdgcn_mfma_f32_16x16x32_bf16(Bt[n][k], At[m][k], acc[ai][bj][m][n], 0, 0, 0); __builtin_amdgcn_s_setprio(0); } while (0)
; #define PG8_WAIT_V(n) asm volatile("s_waitcnt vmcnt(" #n ")" ::: "memory")
; #define PG8_WAIT_L(n) asm volatile("s_waitcnt lgkmcnt(" #n ")" ::: "memory")
; #define PG8_BAR __builtin_amdgcn_s_barrier()
; #define PG8_SCHED __builtin_amdgcn_sched_barrier(0)
; template <class Epi, class Sched, bool ALIGN_EPI = false, bool SP2 = false>
; __device__ __forceinline__ void gemm_phase(PG8_LAS unsigned char* lds, const Gemm g, const Sched& S, const Epi& E) {
;     ...
;             PG8_LDB(B0, 0, 0); PG8_LDB(B1, 0, 1); PG8_SCHED; PG8_LDA(At, 0, 0); PG8_STAGE(PG8_SA(1, 1), a1 + hstep, voffA);
;             PG8_WAIT_V(8); PG8_WAIT_L(0); PG8_BAR; PG8_MMA(0, 0, At, B0); PG8_MMA(0, 1, At, B1); PG8_BAR; PG8_SCHED;
;             PG8_LDA(At, 0, 1); PG8_STAGE(PG8_SB(0, 0), b2, voffB); PG8_STAGE(PG8_SB(0, 1), b2 + hstep, voffB); PG8_STAGE(PG8_SA(0, 0), a2, voffA);
;             PG8_WAIT_V(8); PG8_WAIT_L(0); PG8_BAR; PG8_MMA(1, 0, At, B0); PG8_MMA(1, 1, At, B1); PG8_BAR; PG8_SCHED;
.LBB0_495:
	ds_read_b128 v[170:173], v165
	ds_read_b128 v[174:177], v165 offset:1024
	ds_read_b128 v[182:185], v165 offset:2048
	ds_read_b128 v[186:189], v165 offset:3072
	ds_read_b128 v[190:193], v168
	ds_read_b128 v[194:197], v168 offset:1024
	ds_read_b128 v[198:201], v168 offset:2048
	ds_read_b128 v[208:211], v168 offset:3072
	s_add_u32 s3, s60, 0xfffc0080
	s_addc_u32 s14, s61, -1
	s_cmp_eq_u32 s97, 12
	s_cselect_b32 s65, s49, s14
	s_cselect_b32 s64, s57, s3
	s_cselect_b32 s63, s45, s96
	s_cselect_b32 s62, s94, s95
	v_lshl_add_u64 v[178:179], s[60:61], 0, v[160:161]
	s_add_i32 m0, s59, 0xc000
	ds_read_b128 v[212:215], v164
	ds_read_b128 v[216:219], v164 offset:1024
	ds_read_b128 v[220:223], v164 offset:2048
	ds_read_b128 v[224:227], v164 offset:3072
	ds_read_b128 v[228:231], v164 offset:4096
	ds_read_b128 v[232:235], v164 offset:5120
	ds_read_b128 v[236:239], v164 offset:6144
	ds_read_b128 v[240:243], v164 offset:7168
	global_load_lds_dwordx4 v[178:179], off
	v_lshl_add_u64 v[178:179], s[60:61], 0, v[162:163]
	s_add_i32 m0, s59, 0xe000
	s_nop 0
	global_load_lds_dwordx4 v[178:179], off
	s_waitcnt vmcnt(8)
	s_waitcnt lgkmcnt(0)
	s_barrier
	s_setprio 1
	s_waitcnt lgkmcnt(0)
	v_mfma_f32_16x16x32_bf16 v[124:127], v[170:173], v[212:215], v[124:127]
	v_mfma_f32_16x16x32_bf16 v[120:123], v[182:185], v[212:215], v[120:123]
	v_mfma_f32_16x16x32_bf16 v[60:63], v[190:193], v[212:215], v[60:63]
	v_mfma_f32_16x16x32_bf16 v[56:59], v[198:201], v[212:215], v[56:59]
	v_mfma_f32_16x16x32_bf16 v[116:119], v[170:173], v[220:223], v[116:119]
	v_mfma_f32_16x16x32_bf16 v[112:115], v[182:185], v[220:223], v[112:115]
	v_mfma_f32_16x16x32_bf16 v[52:55], v[190:193], v[220:223], v[52:55]
	v_mfma_f32_16x16x32_bf16 v[48:51], v[198:201], v[220:223], v[48:51]
	v_mfma_f32_16x16x32_bf16 v[108:111], v[170:173], v[228:231], v[108:111]
	v_mfma_f32_16x16x32_bf16 v[104:107], v[182:185], v[228:231], v[104:107]
	v_mfma_f32_16x16x32_bf16 v[44:47], v[190:193], v[228:231], v[44:47]
	v_mfma_f32_16x16x32_bf16 v[40:43], v[198:201], v[228:231], v[40:43]
	v_mfma_f32_16x16x32_bf16 v[100:103], v[170:173], v[236:239], v[100:103]
	v_mfma_f32_16x16x32_bf16 v[96:99], v[182:185], v[236:239], v[96:99]
	v_mfma_f32_16x16x32_bf16 v[36:39], v[190:193], v[236:239], v[36:39]
	v_mfma_f32_16x16x32_bf16 v[32:35], v[198:201], v[236:239], v[32:35]
	s_setprio 0
	s_setprio 1
	v_mfma_f32_16x16x32_bf16 v[124:127], v[174:177], v[216:219], v[124:127]
	v_mfma_f32_16x16x32_bf16 v[120:123], v[186:189], v[216:219], v[120:123]
	v_mfma_f32_16x16x32_bf16 v[60:63], v[194:197], v[216:219], v[60:63]
	v_mfma_f32_16x16x32_bf16 v[56:59], v[208:211], v[216:219], v[56:59]
	v_mfma_f32_16x16x32_bf16 v[116:119], v[174:177], v[224:227], v[116:119]
	v_mfma_f32_16x16x32_bf16 v[112:115], v[186:189], v[224:227], v[112:115]
	v_mfma_f32_16x16x32_bf16 v[52:55], v[194:197], v[224:227], v[52:55]
	v_mfma_f32_16x16x32_bf16 v[48:51], v[208:211], v[224:227], v[48:51]
	v_mfma_f32_16x16x32_bf16 v[108:111], v[174:177], v[232:235], v[108:111]
	v_mfma_f32_16x16x32_bf16 v[104:107], v[186:189], v[232:235], v[104:107]
	v_mfma_f32_16x16x32_bf16 v[44:47], v[194:197], v[232:235], v[44:47]
	v_mfma_f32_16x16x32_bf16 v[40:43], v[208:211], v[232:235], v[40:43]
	v_mfma_f32_16x16x32_bf16 v[100:103], v[174:177], v[240:243], v[100:103]
	v_mfma_f32_16x16x32_bf16 v[96:99], v[186:189], v[240:243], v[96:99]
	v_mfma_f32_16x16x32_bf16 v[36:39], v[194:197], v[240:243], v[36:39]
	v_mfma_f32_16x16x32_bf16 v[32:35], v[208:211], v[240:243], v[32:35]
	s_setprio 0
	s_barrier
	s_add_i32 s3, s92, s75
	v_lshl_add_u64 v[178:179], s[62:63], 0, v[130:131]
	s_mov_b32 m0, s3
	ds_read_b128 v[212:215], v164 offset:16384
	ds_read_b128 v[216:219], v164 offset:17408
	ds_read_b128 v[220:223], v164 offset:18432
	ds_read_b128 v[224:227], v164 offset:19456
	ds_read_b128 v[228:231], v164 offset:20480
	ds_read_b128 v[232:235], v164 offset:21504
	ds_read_b128 v[236:239], v164 offset:22528
	ds_read_b128 v[240:243], v164 offset:23552
	global_load_lds_dwordx4 v[178:179], off
	s_add_i32 m0, s3, 0x2000
	s_add_u32 s14, s62, 0x40000
	v_lshl_add_u64 v[202:203], s[62:63], 0, v[134:135]
	s_addc_u32 s15, s63, 0
	s_add_i32 s3, s93, s75
	global_load_lds_dwordx4 v[202:203], off
	v_lshl_add_u64 v[244:245], s[14:15], 0, v[130:131]
	s_mov_b32 m0, s3
	global_load_lds_dwordx4 v[244:245], off
	v_lshl_add_u64 v[244:245], s[14:15], 0, v[134:135]
	s_add_i32 m0, s3, 0x2000
	s_nop 0
	global_load_lds_dwordx4 v[244:245], off
	s_waitcnt vmcnt(6)
	s_waitcnt lgkmcnt(0)
	s_barrier
; #define PG8_STAGE(bufoff, gbase, voff) do { _Pragma("unroll") for (int _i = 0; _i < 2; ++_i) \
;         __builtin_amdgcn_global_load_lds((const unsigned*)((const char*)(gbase) + (voff)[_i]), (PG8_LAS unsigned*)(lds + (bufoff) + ldsw + _i * 8192), 16, 0, 0); } while (0)
; #define PG8_LDA(dst, b, h) do { _Pragma("unroll") for (int m = 0; m < 4; ++m) _Pragma("unroll") for (int k = 0; k < 2; ++k) dst[m][k] = *(const PG8_LAS bf16x8*)(lds + PG8_SA(b, h) + aoff + m * 2048 + k * 1024); } while (0)
; #define PG8_LDB(dst, b, h) do { _Pragma("unroll") for (int n = 0; n < 2; ++n) _Pragma("unroll") for (int k = 0; k < 2; ++k) dst[n][k] = *(const PG8_LAS bf16x8*)(lds + PG8_SB(b, h) + boff + n * 2048 + k * 1024); } while (0)
; #define PG8_MMA(ai, bj, At, Bt) do { __builtin_amdgcn_s_setprio(1); _Pragma("unroll") for (int m = 0; m < 4; ++m) _Pragma("unroll") for (int n = 0; n < 2; ++n) _Pragma("unroll") for (int k = 0; k < 2; ++k) \
;         acc[ai][bj][m][n] = __builtin_amdgcn_mfma_f32_16x16x32_bf16(Bt[n][k], At[m][k], acc[ai][bj][m][n], 0, 0, 0); __builtin_amdgcn_s_setprio(0); } while (0)
; #define PG8_WAIT_V(n) asm volatile("s_waitcnt vmcnt(" #n ")" ::: "memory")
; #define PG8_WAIT_L(n) asm volatile("s_waitcnt lgkmcnt(" #n ")" ::: "memory")
; #define PG8_BAR __builtin_amdgcn_s_barrier()
; #define PG8_SCHED __builtin_amdgcn_sched_barrier(0)
; template <class Epi, class Sched, bool ALIGN_EPI = false, bool SP2 = false>
; __device__ __forceinline__ void gemm_phase(PG8_LAS unsigned char* lds, const Gemm g, const Sched& S, const Epi& E) {
;     ...
;             PG8_WAIT_V(8); PG8_WAIT_L(0); PG8_BAR; PG8_MMA(1, 0, At, B0); PG8_MMA(1, 1, At, B1); PG8_BAR; PG8_SCHED;
;             PG8_LDB(B0, 1, 0); PG8_LDB(B1, 1, 1); PG8_SCHED; PG8_LDA(At, 1, 0); PG8_STAGE(PG8_SA(0, 1), a2 + hstep, voffA);
;             PG8_WAIT_V(8); PG8_WAIT_L(0); PG8_BAR; PG8_MMA(0, 0, At, B0); PG8_MMA(0, 1, At, B1); PG8_BAR; PG8_SCHED;
	s_setprio 1
	s_waitcnt lgkmcnt(0)
	v_mfma_f32_16x16x32_bf16 v[92:95], v[170:173], v[212:215], v[92:95]
	v_mfma_f32_16x16x32_bf16 v[88:91], v[182:185], v[212:215], v[88:91]
	v_mfma_f32_16x16x32_bf16 v[28:31], v[190:193], v[212:215], v[28:31]
	v_mfma_f32_16x16x32_bf16 v[24:27], v[198:201], v[212:215], v[24:27]
	v_mfma_f32_16x16x32_bf16 v[84:87], v[170:173], v[220:223], v[84:87]
	v_mfma_f32_16x16x32_bf16 v[80:83], v[182:185], v[220:223], v[80:83]
	v_mfma_f32_16x16x32_bf16 v[20:23], v[190:193], v[220:223], v[20:23]
	v_mfma_f32_16x16x32_bf16 v[16:19], v[198:201], v[220:223], v[16:19]
	v_mfma_f32_16x16x32_bf16 v[76:79], v[170:173], v[228:231], v[76:79]
	v_mfma_f32_16x16x32_bf16 v[72:75], v[182:185], v[228:231], v[72:75]
	v_mfma_f32_16x16x32_bf16 v[12:15], v[190:193], v[228:231], v[12:15]
	v_mfma_f32_16x16x32_bf16 v[8:11], v[198:201], v[228:231], v[8:11]
	v_mfma_f32_16x16x32_bf16 v[68:71], v[170:173], v[236:239], v[68:71]
	v_mfma_f32_16x16x32_bf16 v[64:67], v[182:185], v[236:239], v[64:67]
	v_lshl_add_u64 v[244:245], s[64:65], 0, v[128:129]
	s_mov_b32 m0, s59
	s_nop 0
	global_load_lds_dwordx4 v[244:245], off
	v_mfma_f32_16x16x32_bf16 v[4:7], v[190:193], v[236:239], v[4:7]
	v_mfma_f32_16x16x32_bf16 v[0:3], v[198:201], v[236:239], v[0:3]
	s_setprio 0
	s_setprio 1
	v_mfma_f32_16x16x32_bf16 v[92:95], v[174:177], v[216:219], v[92:95]
	v_mfma_f32_16x16x32_bf16 v[88:91], v[186:189], v[216:219], v[88:91]
	v_mfma_f32_16x16x32_bf16 v[28:31], v[194:197], v[216:219], v[28:31]
	v_mfma_f32_16x16x32_bf16 v[24:27], v[208:211], v[216:219], v[24:27]
	v_mfma_f32_16x16x32_bf16 v[84:87], v[174:177], v[224:227], v[84:87]
	v_mfma_f32_16x16x32_bf16 v[80:83], v[186:189], v[224:227], v[80:83]
	v_mfma_f32_16x16x32_bf16 v[20:23], v[194:197], v[224:227], v[20:23]
	v_mfma_f32_16x16x32_bf16 v[16:19], v[208:211], v[224:227], v[16:19]
	v_mfma_f32_16x16x32_bf16 v[76:79], v[174:177], v[232:235], v[76:79]
	v_mfma_f32_16x16x32_bf16 v[72:75], v[186:189], v[232:235], v[72:75]
	v_mfma_f32_16x16x32_bf16 v[12:15], v[194:197], v[232:235], v[12:15]
	v_mfma_f32_16x16x32_bf16 v[8:11], v[208:211], v[232:235], v[8:11]
	v_mfma_f32_16x16x32_bf16 v[68:71], v[174:177], v[240:243], v[68:71]
	v_mfma_f32_16x16x32_bf16 v[64:67], v[186:189], v[240:243], v[64:67]
	v_lshl_add_u64 v[246:247], s[64:65], 0, v[132:133]
	s_mov_b32 m0, s84
	s_nop 0
	global_load_lds_dwordx4 v[246:247], off
	v_mfma_f32_16x16x32_bf16 v[4:7], v[194:197], v[240:243], v[4:7]
	v_mfma_f32_16x16x32_bf16 v[0:3], v[208:211], v[240:243], v[0:3]
	s_setprio 0
	s_barrier
	s_add_i32 s3, 0, 0x18000
	v_add_u32_e32 v136, s3, v141
	s_add_i32 s33, 0, 0x1c000
	ds_read_b128 v[170:173], v136
	ds_read_b128 v[174:177], v136 offset:1024
	ds_read_b128 v[182:185], v136 offset:2048
	ds_read_b128 v[186:189], v136 offset:3072
	v_add_u32_e32 v136, s33, v141
	ds_read_b128 v[190:193], v136
	ds_read_b128 v[194:197], v136 offset:1024
	ds_read_b128 v[198:201], v136 offset:2048
	ds_read_b128 v[208:211], v136 offset:3072
	s_add_u32 s14, s64, 0x40000
	s_addc_u32 s15, s65, 0
	s_mov_b32 m0, s85
	v_lshl_add_u64 v[248:249], s[14:15], 0, v[128:129]
	ds_read_b128 v[212:215], v164 offset:32768
	ds_read_b128 v[216:219], v164 offset:33792
	ds_read_b128 v[220:223], v164 offset:34816
	ds_read_b128 v[224:227], v164 offset:35840
	ds_read_b128 v[228:231], v164 offset:36864
	ds_read_b128 v[232:235], v164 offset:37888
	ds_read_b128 v[236:239], v164 offset:38912
	ds_read_b128 v[240:243], v164 offset:39936
	global_load_lds_dwordx4 v[248:249], off
	v_lshl_add_u64 v[248:249], s[14:15], 0, v[132:133]
	s_mov_b32 m0, s86
	s_nop 0
	global_load_lds_dwordx4 v[248:249], off
	s_waitcnt vmcnt(8)
	s_waitcnt lgkmcnt(0)
	s_barrier
	s_setprio 1
	s_waitcnt lgkmcnt(0)
	v_mfma_f32_16x16x32_bf16 v[124:127], v[170:173], v[212:215], v[124:127]
	v_mfma_f32_16x16x32_bf16 v[120:123], v[182:185], v[212:215], v[120:123]
	v_mfma_f32_16x16x32_bf16 v[60:63], v[190:193], v[212:215], v[60:63]
	v_mfma_f32_16x16x32_bf16 v[56:59], v[198:201], v[212:215], v[56:59]
	v_mfma_f32_16x16x32_bf16 v[116:119], v[170:173], v[220:223], v[116:119]
	v_mfma_f32_16x16x32_bf16 v[112:115], v[182:185], v[220:223], v[112:115]
	v_mfma_f32_16x16x32_bf16 v[52:55], v[190:193], v[220:223], v[52:55]
	v_mfma_f32_16x16x32_bf16 v[48:51], v[198:201], v[220:223], v[48:51]
	v_mfma_f32_16x16x32_bf16 v[108:111], v[170:173], v[228:231], v[108:111]
	v_mfma_f32_16x16x32_bf16 v[104:107], v[182:185], v[228:231], v[104:107]
	v_mfma_f32_16x16x32_bf16 v[44:47], v[190:193], v[228:231], v[44:47]
	v_mfma_f32_16x16x32_bf16 v[40:43], v[198:201], v[228:231], v[40:43]
	v_mfma_f32_16x16x32_bf16 v[100:103], v[170:173], v[236:239], v[100:103]
	v_mfma_f32_16x16x32_bf16 v[96:99], v[182:185], v[236:239], v[96:99]
	v_mfma_f32_16x16x32_bf16 v[36:39], v[190:193], v[236:239], v[36:39]
	v_mfma_f32_16x16x32_bf16 v[32:35], v[198:201], v[236:239], v[32:35]
	s_setprio 0
	s_setprio 1
	v_mfma_f32_16x16x32_bf16 v[124:127], v[174:177], v[216:219], v[124:127]
	v_mfma_f32_16x16x32_bf16 v[120:123], v[186:189], v[216:219], v[120:123]
	v_mfma_f32_16x16x32_bf16 v[60:63], v[194:197], v[216:219], v[60:63]
	v_mfma_f32_16x16x32_bf16 v[56:59], v[208:211], v[216:219], v[56:59]
	v_mfma_f32_16x16x32_bf16 v[116:119], v[174:177], v[224:227], v[116:119]
	v_mfma_f32_16x16x32_bf16 v[112:115], v[186:189], v[224:227], v[112:115]
	v_mfma_f32_16x16x32_bf16 v[52:55], v[194:197], v[224:227], v[52:55]
	v_mfma_f32_16x16x32_bf16 v[48:51], v[208:211], v[224:227], v[48:51]
	v_mfma_f32_16x16x32_bf16 v[108:111], v[174:177], v[232:235], v[108:111]
	v_mfma_f32_16x16x32_bf16 v[104:107], v[186:189], v[232:235], v[104:107]
	v_mfma_f32_16x16x32_bf16 v[44:47], v[194:197], v[232:235], v[44:47]
	v_mfma_f32_16x16x32_bf16 v[40:43], v[208:211], v[232:235], v[40:43]
	v_mfma_f32_16x16x32_bf16 v[100:103], v[174:177], v[240:243], v[100:103]
	v_mfma_f32_16x16x32_bf16 v[96:99], v[186:189], v[240:243], v[96:99]
	v_mfma_f32_16x16x32_bf16 v[36:39], v[194:197], v[240:243], v[36:39]
	v_mfma_f32_16x16x32_bf16 v[32:35], v[208:211], v[240:243], v[32:35]
	s_setprio 0
	s_barrier
; #define PG8_STAGE(bufoff, gbase, voff) do { _Pragma("unroll") for (int _i = 0; _i < 2; ++_i) \
;         __builtin_amdgcn_global_load_lds((const unsigned*)((const char*)(gbase) + (voff)[_i]), (PG8_LAS unsigned*)(lds + (bufoff) + ldsw + _i * 8192), 16, 0, 0); } while (0)
; #define PG8_LDA(dst, b, h) do { _Pragma("unroll") for (int m = 0; m < 4; ++m) _Pragma("unroll") for (int k = 0; k < 2; ++k) dst[m][k] = *(const PG8_LAS bf16x8*)(lds + PG8_SA(b, h) + aoff + m * 2048 + k * 1024); } while (0)
; #define PG8_MMA(ai, bj, At, Bt) do { __builtin_amdgcn_s_setprio(1); _Pragma("unroll") for (int m = 0; m < 4; ++m) _Pragma("unroll") for (int n = 0; n < 2; ++n) _Pragma("unroll") for (int k = 0; k < 2; ++k) \
;         acc[ai][bj][m][n] = __builtin_amdgcn_mfma_f32_16x16x32_bf16(Bt[n][k], At[m][k], acc[ai][bj][m][n], 0, 0, 0); __builtin_amdgcn_s_setprio(0); } while (0)
; #define PG8_WAIT_V(n) asm volatile("s_waitcnt vmcnt(" #n ")" ::: "memory")
; #define PG8_WAIT_L(n) asm volatile("s_waitcnt lgkmcnt(" #n ")" ::: "memory")
; #define PG8_BAR __builtin_amdgcn_s_barrier()
; #define PG8_SCHED __builtin_amdgcn_sched_barrier(0)
; template <class Epi, class Sched, bool ALIGN_EPI = false, bool SP2 = false>
; __device__ __forceinline__ void gemm_phase(PG8_LAS unsigned char* lds, const Gemm g, const Sched& S, const Epi& E) {
;     ...
;             PG8_LDA(At, 1, 1); PG8_STAGE(PG8_SB(1, 0), b3, voffB); PG8_STAGE(PG8_SB(1, 1), b3 + hstep, voffB); PG8_STAGE(PG8_SA(1, 0), a3, voffA);
;             PG8_WAIT_V(8); PG8_WAIT_L(0); PG8_BAR; PG8_MMA(1, 0, At, B0); PG8_MMA(1, 1, At, B1); PG8_BAR; PG8_SCHED;
;     ...
;         if constexpr (ALIGN_EPI) { if (wr == 0) PG8_BAR; }
	s_add_i32 s3, s3, s75
	v_lshl_add_u64 v[178:179], v[178:179], 0, s[10:11]
	s_mov_b32 m0, s3
	ds_read_b128 v[212:215], v164 offset:49152
	ds_read_b128 v[216:219], v164 offset:50176
	ds_read_b128 v[220:223], v164 offset:51200
	ds_read_b128 v[224:227], v164 offset:52224
	ds_read_b128 v[228:231], v164 offset:53248
	ds_read_b128 v[232:235], v164 offset:54272
	ds_read_b128 v[236:239], v164 offset:55296
	ds_read_b128 v[240:243], v164 offset:56320
	global_load_lds_dwordx4 v[178:179], off
	s_add_i32 m0, s3, 0x2000
	s_add_u32 s14, s62, 0x40080
	v_lshl_add_u64 v[178:179], v[202:203], 0, s[10:11]
	s_addc_u32 s15, s63, 0
	s_add_i32 s3, s33, s75
	global_load_lds_dwordx4 v[178:179], off
	v_lshl_add_u64 v[178:179], s[14:15], 0, v[130:131]
	s_mov_b32 m0, s3
	s_nop 0
	global_load_lds_dwordx4 v[178:179], off
	v_lshl_add_u64 v[178:179], s[14:15], 0, v[134:135]
	s_add_i32 m0, s3, 0x2000
	s_nop 0
	global_load_lds_dwordx4 v[178:179], off
	s_waitcnt vmcnt(6)
	s_waitcnt lgkmcnt(0)
	s_barrier
	s_setprio 1
	s_waitcnt lgkmcnt(0)
	v_mfma_f32_16x16x32_bf16 v[92:95], v[170:173], v[212:215], v[92:95]
	v_mfma_f32_16x16x32_bf16 v[88:91], v[182:185], v[212:215], v[88:91]
	v_mfma_f32_16x16x32_bf16 v[28:31], v[190:193], v[212:215], v[28:31]
	v_mfma_f32_16x16x32_bf16 v[24:27], v[198:201], v[212:215], v[24:27]
	v_mfma_f32_16x16x32_bf16 v[84:87], v[170:173], v[220:223], v[84:87]
	v_mfma_f32_16x16x32_bf16 v[80:83], v[182:185], v[220:223], v[80:83]
	v_mfma_f32_16x16x32_bf16 v[20:23], v[190:193], v[220:223], v[20:23]
	v_mfma_f32_16x16x32_bf16 v[16:19], v[198:201], v[220:223], v[16:19]
	v_mfma_f32_16x16x32_bf16 v[76:79], v[170:173], v[228:231], v[76:79]
	v_mfma_f32_16x16x32_bf16 v[72:75], v[182:185], v[228:231], v[72:75]
	v_mfma_f32_16x16x32_bf16 v[12:15], v[190:193], v[228:231], v[12:15]
	v_mfma_f32_16x16x32_bf16 v[8:11], v[198:201], v[228:231], v[8:11]
	v_mfma_f32_16x16x32_bf16 v[68:71], v[170:173], v[236:239], v[68:71]
	v_mfma_f32_16x16x32_bf16 v[64:67], v[182:185], v[236:239], v[64:67]
	v_lshl_add_u64 v[178:179], v[244:245], 0, s[10:11]
	s_mov_b32 m0, s88
	s_nop 0
	global_load_lds_dwordx4 v[178:179], off
	v_mfma_f32_16x16x32_bf16 v[4:7], v[190:193], v[236:239], v[4:7]
	v_mfma_f32_16x16x32_bf16 v[0:3], v[198:201], v[236:239], v[0:3]
	s_setprio 0
	s_setprio 1
	v_mfma_f32_16x16x32_bf16 v[92:95], v[174:177], v[216:219], v[92:95]
	v_mfma_f32_16x16x32_bf16 v[88:91], v[186:189], v[216:219], v[88:91]
	v_mfma_f32_16x16x32_bf16 v[28:31], v[194:197], v[216:219], v[28:31]
	v_mfma_f32_16x16x32_bf16 v[24:27], v[208:211], v[216:219], v[24:27]
	v_mfma_f32_16x16x32_bf16 v[84:87], v[174:177], v[224:227], v[84:87]
	v_mfma_f32_16x16x32_bf16 v[80:83], v[186:189], v[224:227], v[80:83]
	v_mfma_f32_16x16x32_bf16 v[20:23], v[194:197], v[224:227], v[20:23]
	v_mfma_f32_16x16x32_bf16 v[16:19], v[208:211], v[224:227], v[16:19]
	v_mfma_f32_16x16x32_bf16 v[76:79], v[174:177], v[232:235], v[76:79]
	v_mfma_f32_16x16x32_bf16 v[72:75], v[186:189], v[232:235], v[72:75]
	v_mfma_f32_16x16x32_bf16 v[12:15], v[194:197], v[232:235], v[12:15]
	v_mfma_f32_16x16x32_bf16 v[8:11], v[208:211], v[232:235], v[8:11]
	v_mfma_f32_16x16x32_bf16 v[68:71], v[174:177], v[240:243], v[68:71]
	v_mfma_f32_16x16x32_bf16 v[64:67], v[186:189], v[240:243], v[64:67]
	v_lshl_add_u64 v[178:179], v[246:247], 0, s[10:11]
	s_mov_b32 m0, s89
	s_nop 0
	global_load_lds_dwordx4 v[178:179], off
	v_mfma_f32_16x16x32_bf16 v[4:7], v[194:197], v[240:243], v[4:7]
	v_mfma_f32_16x16x32_bf16 v[0:3], v[208:211], v[240:243], v[0:3]
	s_setprio 0
	s_barrier
	s_add_i32 s97, s97, 2
	s_add_u32 s60, s60, 0x100
	s_addc_u32 s61, s61, 0
	s_add_u32 s95, s95, 0x100
	s_addc_u32 s96, s96, 0
	s_cmp_lt_u32 s97, 14
	s_cbranch_scc1 .LBB0_495
	s_andn2_b64 vcc, exec, s[40:41]
	s_cbranch_vccnz .LBB0_498
	s_barrier

; #define PG8_STAGE(bufoff, gbase, voff) do { _Pragma("unroll") for (int _i = 0; _i < 2; ++_i) \
;         __builtin_amdgcn_global_load_lds((const unsigned*)((const char*)(gbase) + (voff)[_i]), (PG8_LAS unsigned*)(lds + (bufoff) + ldsw + _i * 8192), 16, 0, 0); } while (0)
; #define PG8_LDA(dst, b, h) do { _Pragma("unroll") for (int m = 0; m < 4; ++m) _Pragma("unroll") for (int k = 0; k < 2; ++k) dst[m][k] = *(const PG8_LAS bf16x8*)(lds + PG8_SA(b, h) + aoff + m * 2048 + k * 1024); } while (0)
; #define PG8_LDB(dst, b, h) do { _Pragma("unroll") for (int n = 0; n < 2; ++n) _Pragma("unroll") for (int k = 0; k < 2; ++k) dst[n][k] = *(const PG8_LAS bf16x8*)(lds + PG8_SB(b, h) + boff + n * 2048 + k * 1024); } while (0)
; #define PG8_MMA(ai, bj, At, Bt) do { __builtin_amdgcn_s_setprio(1); _Pragma("unroll") for (int m = 0; m < 4; ++m) _Pragma("unroll") for (int n = 0; n < 2; ++n) _Pragma("unroll") for (int k = 0; k < 2; ++k) \
;         acc[ai][bj][m][n] = __builtin_amdgcn_mfma_f32_16x16x32_bf16(Bt[n][k], At[m][k], acc[ai][bj][m][n], 0, 0, 0); __builtin_amdgcn_s_setprio(0); } while (0)
; #define PG8_BAR __builtin_amdgcn_s_barrier()
; template <class Epi, class Sched, bool ALIGN_EPI = false, bool SP2 = false>
; __device__ __forceinline__ void gemm_phase(PG8_LAS unsigned char* lds, const Gemm g, const Sched& S, const Epi& E) {
;     ...
;         const bool has_next = S.next(ui + 1, nxt);
;         const char* nA = has_next ? (const char*)g.A + (size_t)nxt.pm * tstep : cA; const char* nB = has_next ? (const char*)g.Bt + (size_t)nxt.pn * tstep : cB;
;         for (int t = 0; t < nt; t += 2) {
;             const bool last = (t == nt - 2);
;             const char* a1 = cA + (size_t)(t + 1) * kstep;
;             const char* a2 = last ? nA : cA + (size_t)(t + 2) * kstep; const char* b2 = last ? nB : cB + (size_t)(t + 2) * kstep;
;             const char* a3 = a2 + kstep; const char* b3 = b2 + kstep;
;             if (last && has_next) S.a_ready(nxt);
;             if constexpr (SP2) {
;             PG8_LDB(B0, 0, 0); PG8_LDB(B1, 0, 1); PG8_SCHED; PG8_LDA(At, 0, 0); PG8_STAGE(PG8_SA(1, 1), a1 + hstep, voffA);
;             PG8_WAIT_V(8); PG8_WAIT_L(0); PG8_BAR; PG8_MMA(0, 0, At, B0); PG8_MMA(0, 1, At, B1); PG8_BAR; PG8_SCHED;
;             PG8_LDA(At, 0, 1); PG8_STAGE(PG8_SB(0, 0), b2, voffB); PG8_STAGE(PG8_SB(0, 1), b2 + hstep, voffB); PG8_STAGE(PG8_SA(0, 0), a2, voffA);
.LBB0_649:
	s_ashr_i32 s51, s50, 31
	s_lshl_b64 s[14:15], s[50:51], 19
	s_add_u32 s52, s40, s14
	s_addc_u32 s53, s41, s15
	s_and_b64 s[14:15], s[8:9], exec
	s_cselect_b32 s51, s53, s61
	s_cselect_b32 s57, s52, s60
	s_ashr_i32 s49, s48, 31
	s_lshl_b64 s[14:15], s[48:49], 19
	s_add_u32 s54, s82, s14
	s_addc_u32 s55, s83, s15
	s_and_b64 s[14:15], s[8:9], exec
	s_cselect_b32 s49, s55, s63
	s_cselect_b32 s89, s54, s62
	s_add_u32 s60, s60, 0x40080
	s_addc_u32 s61, s61, 0
	s_add_u32 s90, s62, 0x100
	s_addc_u32 s91, s63, 0
	s_mov_b32 s92, -2
	s_waitcnt lgkmcnt(0)
	s_waitcnt vmcnt(0)
	ds_read_b128 v[148:151], v155
	ds_read_b128 v[160:163], v155 offset:1024
	ds_read_b128 v[164:167], v155 offset:2048
	ds_read_b128 v[168:171], v155 offset:3072
	ds_read_b128 v[172:175], v156
	ds_read_b128 v[176:179], v156 offset:1024
	ds_read_b128 v[182:185], v156 offset:2048
	ds_read_b128 v[186:189], v156 offset:3072
	s_add_u32 s3, s60, 0xfffc0080
	s_addc_u32 s14, s61, -1
	s_cmp_eq_u32 s92, 12
	s_cselect_b32 s65, s51, s14
	s_cselect_b32 s64, s57, s3
	s_cselect_b32 s63, s49, s91
	s_cselect_b32 s62, s89, s90
	v_lshl_add_u64 v[202:203], s[60:61], 0, v[140:141]
	s_add_i32 m0, s43, 0xc000
	ds_read_b128 v[190:193], v157
	ds_read_b128 v[194:197], v157 offset:1024
	ds_read_b128 v[198:201], v157 offset:2048
	ds_read_b128 v[208:211], v157 offset:3072
	ds_read_b128 v[212:215], v157 offset:4096
	ds_read_b128 v[216:219], v157 offset:5120
	ds_read_b128 v[220:223], v157 offset:6144
	ds_read_b128 v[224:227], v157 offset:7168
	global_load_lds_dwordx4 v[202:203], off
	v_lshl_add_u64 v[202:203], s[60:61], 0, v[142:143]
	s_add_i32 m0, s43, 0xe000
	s_nop 0
	global_load_lds_dwordx4 v[202:203], off
	s_waitcnt vmcnt(8)
	s_waitcnt lgkmcnt(0)
	s_barrier
	s_setprio 1
	s_waitcnt lgkmcnt(0)
	v_mfma_f32_16x16x32_bf16 v[124:127], v[148:151], v[190:193], 0
	v_mfma_f32_16x16x32_bf16 v[120:123], v[164:167], v[190:193], 0
	v_mfma_f32_16x16x32_bf16 v[116:119], v[172:175], v[190:193], 0
	v_mfma_f32_16x16x32_bf16 v[112:115], v[182:185], v[190:193], 0
	v_mfma_f32_16x16x32_bf16 v[108:111], v[148:151], v[198:201], 0
	v_mfma_f32_16x16x32_bf16 v[104:107], v[164:167], v[198:201], 0
	v_mfma_f32_16x16x32_bf16 v[100:103], v[172:175], v[198:201], 0
	v_mfma_f32_16x16x32_bf16 v[96:99], v[182:185], v[198:201], 0
	v_mfma_f32_16x16x32_bf16 v[92:95], v[148:151], v[212:215], 0
	v_mfma_f32_16x16x32_bf16 v[88:91], v[164:167], v[212:215], 0
	v_mfma_f32_16x16x32_bf16 v[84:87], v[172:175], v[212:215], 0
	v_mfma_f32_16x16x32_bf16 v[80:83], v[182:185], v[212:215], 0
	v_mfma_f32_16x16x32_bf16 v[76:79], v[148:151], v[220:223], 0
	v_mfma_f32_16x16x32_bf16 v[72:75], v[164:167], v[220:223], 0
	v_mfma_f32_16x16x32_bf16 v[68:71], v[172:175], v[220:223], 0
	v_mfma_f32_16x16x32_bf16 v[64:67], v[182:185], v[220:223], 0
	s_setprio 0
	s_setprio 1
	v_mfma_f32_16x16x32_bf16 v[124:127], v[160:163], v[194:197], v[124:127]
	v_mfma_f32_16x16x32_bf16 v[120:123], v[168:171], v[194:197], v[120:123]
	v_mfma_f32_16x16x32_bf16 v[116:119], v[176:179], v[194:197], v[116:119]
	v_mfma_f32_16x16x32_bf16 v[112:115], v[186:189], v[194:197], v[112:115]
	v_mfma_f32_16x16x32_bf16 v[108:111], v[160:163], v[208:211], v[108:111]
	v_mfma_f32_16x16x32_bf16 v[104:107], v[168:171], v[208:211], v[104:107]
	v_mfma_f32_16x16x32_bf16 v[100:103], v[176:179], v[208:211], v[100:103]
	v_mfma_f32_16x16x32_bf16 v[96:99], v[186:189], v[208:211], v[96:99]
	v_mfma_f32_16x16x32_bf16 v[92:95], v[160:163], v[216:219], v[92:95]
	v_mfma_f32_16x16x32_bf16 v[88:91], v[168:171], v[216:219], v[88:91]
	v_mfma_f32_16x16x32_bf16 v[84:87], v[176:179], v[216:219], v[84:87]
	v_mfma_f32_16x16x32_bf16 v[80:83], v[186:189], v[216:219], v[80:83]
	v_mfma_f32_16x16x32_bf16 v[76:79], v[160:163], v[224:227], v[76:79]
	v_mfma_f32_16x16x32_bf16 v[72:75], v[168:171], v[224:227], v[72:75]
	v_mfma_f32_16x16x32_bf16 v[68:71], v[176:179], v[224:227], v[68:71]
	v_mfma_f32_16x16x32_bf16 v[64:67], v[186:189], v[224:227], v[64:67]
	s_setprio 0
	s_barrier
	s_add_i32 s3, s85, s34
	v_lshl_add_u64 v[202:203], s[62:63], 0, v[134:135]
	s_mov_b32 m0, s3
	ds_read_b128 v[190:193], v157 offset:16384
	ds_read_b128 v[194:197], v157 offset:17408
	ds_read_b128 v[198:201], v157 offset:18432
	ds_read_b128 v[208:211], v157 offset:19456
	ds_read_b128 v[212:215], v157 offset:20480
	ds_read_b128 v[216:219], v157 offset:21504
	ds_read_b128 v[220:223], v157 offset:22528
	ds_read_b128 v[224:227], v157 offset:23552
	global_load_lds_dwordx4 v[202:203], off
	s_add_i32 m0, s3, 0x2000
	s_add_u32 s14, s62, 0x40000
	v_lshl_add_u64 v[228:229], s[62:63], 0, v[138:139]
	s_addc_u32 s15, s63, 0
	s_add_i32 s3, s86, s34
	global_load_lds_dwordx4 v[228:229], off
	v_lshl_add_u64 v[230:231], s[14:15], 0, v[134:135]
	s_mov_b32 m0, s3
	global_load_lds_dwordx4 v[230:231], off
	v_lshl_add_u64 v[230:231], s[14:15], 0, v[138:139]
	s_add_i32 m0, s3, 0x2000
	s_nop 0
	global_load_lds_dwordx4 v[230:231], off
	s_waitcnt vmcnt(6)
	s_waitcnt lgkmcnt(0)
	s_barrier
; #define PG8_STAGE(bufoff, gbase, voff) do { _Pragma("unroll") for (int _i = 0; _i < 2; ++_i) \
;         __builtin_amdgcn_global_load_lds((const unsigned*)((const char*)(gbase) + (voff)[_i]), (PG8_LAS unsigned*)(lds + (bufoff) + ldsw + _i * 8192), 16, 0, 0); } while (0)
; #define PG8_LDA(dst, b, h) do { _Pragma("unroll") for (int m = 0; m < 4; ++m) _Pragma("unroll") for (int k = 0; k < 2; ++k) dst[m][k] = *(const PG8_LAS bf16x8*)(lds + PG8_SA(b, h) + aoff + m * 2048 + k * 1024); } while (0)
; #define PG8_LDB(dst, b, h) do { _Pragma("unroll") for (int n = 0; n < 2; ++n) _Pragma("unroll") for (int k = 0; k < 2; ++k) dst[n][k] = *(const PG8_LAS bf16x8*)(lds + PG8_SB(b, h) + boff + n * 2048 + k * 1024); } while (0)
; #define PG8_MMA(ai, bj, At, Bt) do { __builtin_amdgcn_s_setprio(1); _Pragma("unroll") for (int m = 0; m < 4; ++m) _Pragma("unroll") for (int n = 0; n < 2; ++n) _Pragma("unroll") for (int k = 0; k < 2; ++k) \
;         acc[ai][bj][m][n] = __builtin_amdgcn_mfma_f32_16x16x32_bf16(Bt[n][k], At[m][k], acc[ai][bj][m][n], 0, 0, 0); __builtin_amdgcn_s_setprio(0); } while (0)
; #define PG8_WAIT_V(n) asm volatile("s_waitcnt vmcnt(" #n ")" ::: "memory")
; #define PG8_WAIT_L(n) asm volatile("s_waitcnt lgkmcnt(" #n ")" ::: "memory")
; #define PG8_BAR __builtin_amdgcn_s_barrier()
; #define PG8_SCHED __builtin_amdgcn_sched_barrier(0)
; template <class Epi, class Sched, bool ALIGN_EPI = false, bool SP2 = false>
; __device__ __forceinline__ void gemm_phase(PG8_LAS unsigned char* lds, const Gemm g, const Sched& S, const Epi& E) {
;     ...
;             PG8_WAIT_V(8); PG8_WAIT_L(0); PG8_BAR; PG8_MMA(1, 0, At, B0); PG8_MMA(1, 1, At, B1); PG8_BAR; PG8_SCHED;
;             PG8_LDB(B0, 1, 0); PG8_LDB(B1, 1, 1); PG8_SCHED; PG8_LDA(At, 1, 0); PG8_STAGE(PG8_SA(0, 1), a2 + hstep, voffA);
;             PG8_WAIT_V(8); PG8_WAIT_L(0); PG8_BAR; PG8_MMA(0, 0, At, B0); PG8_MMA(0, 1, At, B1); PG8_BAR; PG8_SCHED;
	s_setprio 1
	s_waitcnt lgkmcnt(0)
	v_mfma_f32_16x16x32_bf16 v[60:63], v[148:151], v[190:193], 0
	v_mfma_f32_16x16x32_bf16 v[56:59], v[164:167], v[190:193], 0
	v_mfma_f32_16x16x32_bf16 v[52:55], v[172:175], v[190:193], 0
	v_mfma_f32_16x16x32_bf16 v[48:51], v[182:185], v[190:193], 0
	v_mfma_f32_16x16x32_bf16 v[44:47], v[148:151], v[198:201], 0
	v_mfma_f32_16x16x32_bf16 v[40:43], v[164:167], v[198:201], 0
	v_mfma_f32_16x16x32_bf16 v[36:39], v[172:175], v[198:201], 0
	v_mfma_f32_16x16x32_bf16 v[32:35], v[182:185], v[198:201], 0
	v_mfma_f32_16x16x32_bf16 v[28:31], v[148:151], v[212:215], 0
	v_mfma_f32_16x16x32_bf16 v[24:27], v[164:167], v[212:215], 0
	v_mfma_f32_16x16x32_bf16 v[20:23], v[172:175], v[212:215], 0
	v_mfma_f32_16x16x32_bf16 v[16:19], v[182:185], v[212:215], 0
	v_mfma_f32_16x16x32_bf16 v[12:15], v[148:151], v[220:223], 0
	v_mfma_f32_16x16x32_bf16 v[8:11], v[164:167], v[220:223], 0
	v_lshl_add_u64 v[230:231], s[64:65], 0, v[132:133]
	s_mov_b32 m0, s43
	s_nop 0
	global_load_lds_dwordx4 v[230:231], off
	v_mfma_f32_16x16x32_bf16 v[4:7], v[172:175], v[220:223], 0
	v_mfma_f32_16x16x32_bf16 v[0:3], v[182:185], v[220:223], 0
	s_setprio 0
	s_setprio 1
	v_mfma_f32_16x16x32_bf16 v[60:63], v[160:163], v[194:197], v[60:63]
	v_mfma_f32_16x16x32_bf16 v[56:59], v[168:171], v[194:197], v[56:59]
	v_mfma_f32_16x16x32_bf16 v[52:55], v[176:179], v[194:197], v[52:55]
	v_mfma_f32_16x16x32_bf16 v[48:51], v[186:189], v[194:197], v[48:51]
	v_mfma_f32_16x16x32_bf16 v[44:47], v[160:163], v[208:211], v[44:47]
	v_mfma_f32_16x16x32_bf16 v[40:43], v[168:171], v[208:211], v[40:43]
	v_mfma_f32_16x16x32_bf16 v[36:39], v[176:179], v[208:211], v[36:39]
	v_mfma_f32_16x16x32_bf16 v[32:35], v[186:189], v[208:211], v[32:35]
	v_mfma_f32_16x16x32_bf16 v[28:31], v[160:163], v[216:219], v[28:31]
	v_mfma_f32_16x16x32_bf16 v[24:27], v[168:171], v[216:219], v[24:27]
	v_mfma_f32_16x16x32_bf16 v[20:23], v[176:179], v[216:219], v[20:23]
	v_mfma_f32_16x16x32_bf16 v[16:19], v[186:189], v[216:219], v[16:19]
	v_mfma_f32_16x16x32_bf16 v[12:15], v[160:163], v[224:227], v[12:15]
	v_mfma_f32_16x16x32_bf16 v[8:11], v[168:171], v[224:227], v[8:11]
	v_lshl_add_u64 v[232:233], s[64:65], 0, v[136:137]
	s_mov_b32 m0, s59
	s_nop 0
	global_load_lds_dwordx4 v[232:233], off
	v_mfma_f32_16x16x32_bf16 v[4:7], v[176:179], v[224:227], v[4:7]
	v_mfma_f32_16x16x32_bf16 v[0:3], v[186:189], v[224:227], v[0:3]
	s_setprio 0
	s_barrier
	s_add_i32 s3, 0, 0x18000
	v_add_u32_e32 v159, s3, v131
	s_add_i32 s33, 0, 0x1c000
	ds_read_b128 v[148:151], v159
	ds_read_b128 v[160:163], v159 offset:1024
	ds_read_b128 v[164:167], v159 offset:2048
	ds_read_b128 v[168:171], v159 offset:3072
	v_add_u32_e32 v159, s33, v131
	ds_read_b128 v[172:175], v159
	ds_read_b128 v[176:179], v159 offset:1024
	ds_read_b128 v[182:185], v159 offset:2048
	ds_read_b128 v[186:189], v159 offset:3072
	s_add_u32 s14, s64, 0x40000
	s_addc_u32 s15, s65, 0
	s_mov_b32 m0, s66
	v_lshl_add_u64 v[234:235], s[14:15], 0, v[132:133]
	ds_read_b128 v[190:193], v157 offset:32768
	ds_read_b128 v[194:197], v157 offset:33792
	ds_read_b128 v[198:201], v157 offset:34816
	ds_read_b128 v[208:211], v157 offset:35840
	ds_read_b128 v[212:215], v157 offset:36864
	ds_read_b128 v[216:219], v157 offset:37888
	ds_read_b128 v[220:223], v157 offset:38912
	ds_read_b128 v[224:227], v157 offset:39936
	global_load_lds_dwordx4 v[234:235], off
	v_lshl_add_u64 v[234:235], s[14:15], 0, v[136:137]
	s_mov_b32 m0, s67
	s_nop 0
	global_load_lds_dwordx4 v[234:235], off
	s_waitcnt vmcnt(8)
	s_waitcnt lgkmcnt(0)
	s_barrier
	s_setprio 1
	s_waitcnt lgkmcnt(0)
	v_mfma_f32_16x16x32_bf16 v[124:127], v[148:151], v[190:193], v[124:127]
	v_mfma_f32_16x16x32_bf16 v[120:123], v[164:167], v[190:193], v[120:123]
	v_mfma_f32_16x16x32_bf16 v[116:119], v[172:175], v[190:193], v[116:119]
	v_mfma_f32_16x16x32_bf16 v[112:115], v[182:185], v[190:193], v[112:115]
	v_mfma_f32_16x16x32_bf16 v[108:111], v[148:151], v[198:201], v[108:111]
	v_mfma_f32_16x16x32_bf16 v[104:107], v[164:167], v[198:201], v[104:107]
	v_mfma_f32_16x16x32_bf16 v[100:103], v[172:175], v[198:201], v[100:103]
	v_mfma_f32_16x16x32_bf16 v[96:99], v[182:185], v[198:201], v[96:99]
	v_mfma_f32_16x16x32_bf16 v[92:95], v[148:151], v[212:215], v[92:95]
	v_mfma_f32_16x16x32_bf16 v[88:91], v[164:167], v[212:215], v[88:91]
	v_mfma_f32_16x16x32_bf16 v[84:87], v[172:175], v[212:215], v[84:87]
	v_mfma_f32_16x16x32_bf16 v[80:83], v[182:185], v[212:215], v[80:83]
	v_mfma_f32_16x16x32_bf16 v[76:79], v[148:151], v[220:223], v[76:79]
	v_mfma_f32_16x16x32_bf16 v[72:75], v[164:167], v[220:223], v[72:75]
	v_mfma_f32_16x16x32_bf16 v[68:71], v[172:175], v[220:223], v[68:71]
	v_mfma_f32_16x16x32_bf16 v[64:67], v[182:185], v[220:223], v[64:67]
	s_setprio 0
	s_setprio 1
	v_mfma_f32_16x16x32_bf16 v[124:127], v[160:163], v[194:197], v[124:127]
	v_mfma_f32_16x16x32_bf16 v[120:123], v[168:171], v[194:197], v[120:123]
	v_mfma_f32_16x16x32_bf16 v[116:119], v[176:179], v[194:197], v[116:119]
	v_mfma_f32_16x16x32_bf16 v[112:115], v[186:189], v[194:197], v[112:115]
	v_mfma_f32_16x16x32_bf16 v[108:111], v[160:163], v[208:211], v[108:111]
	v_mfma_f32_16x16x32_bf16 v[104:107], v[168:171], v[208:211], v[104:107]
	v_mfma_f32_16x16x32_bf16 v[100:103], v[176:179], v[208:211], v[100:103]
	v_mfma_f32_16x16x32_bf16 v[96:99], v[186:189], v[208:211], v[96:99]
	v_mfma_f32_16x16x32_bf16 v[92:95], v[160:163], v[216:219], v[92:95]
	v_mfma_f32_16x16x32_bf16 v[88:91], v[168:171], v[216:219], v[88:91]
	v_mfma_f32_16x16x32_bf16 v[84:87], v[176:179], v[216:219], v[84:87]
	v_mfma_f32_16x16x32_bf16 v[80:83], v[186:189], v[216:219], v[80:83]
	v_mfma_f32_16x16x32_bf16 v[76:79], v[160:163], v[224:227], v[76:79]
	v_mfma_f32_16x16x32_bf16 v[72:75], v[168:171], v[224:227], v[72:75]
	v_mfma_f32_16x16x32_bf16 v[68:71], v[176:179], v[224:227], v[68:71]
	v_mfma_f32_16x16x32_bf16 v[64:67], v[186:189], v[224:227], v[64:67]
	s_setprio 0
	s_barrier
; #define PG8_STAGE(bufoff, gbase, voff) do { _Pragma("unroll") for (int _i = 0; _i < 2; ++_i) \
;         __builtin_amdgcn_global_load_lds((const unsigned*)((const char*)(gbase) + (voff)[_i]), (PG8_LAS unsigned*)(lds + (bufoff) + ldsw + _i * 8192), 16, 0, 0); } while (0)
; #define PG8_LDA(dst, b, h) do { _Pragma("unroll") for (int m = 0; m < 4; ++m) _Pragma("unroll") for (int k = 0; k < 2; ++k) dst[m][k] = *(const PG8_LAS bf16x8*)(lds + PG8_SA(b, h) + aoff + m * 2048 + k * 1024); } while (0)
; #define PG8_LDB(dst, b, h) do { _Pragma("unroll") for (int n = 0; n < 2; ++n) _Pragma("unroll") for (int k = 0; k < 2; ++k) dst[n][k] = *(const PG8_LAS bf16x8*)(lds + PG8_SB(b, h) + boff + n * 2048 + k * 1024); } while (0)
; #define PG8_MMA(ai, bj, At, Bt) do { __builtin_amdgcn_s_setprio(1); _Pragma("unroll") for (int m = 0; m < 4; ++m) _Pragma("unroll") for (int n = 0; n < 2; ++n) _Pragma("unroll") for (int k = 0; k < 2; ++k) \
;         acc[ai][bj][m][n] = __builtin_amdgcn_mfma_f32_16x16x32_bf16(Bt[n][k], At[m][k], acc[ai][bj][m][n], 0, 0, 0); __builtin_amdgcn_s_setprio(0); } while (0)
; #define PG8_WAIT_V(n) asm volatile("s_waitcnt vmcnt(" #n ")" ::: "memory")
; #define PG8_WAIT_L(n) asm volatile("s_waitcnt lgkmcnt(" #n ")" ::: "memory")
; #define PG8_BAR __builtin_amdgcn_s_barrier()
; #define PG8_SCHED __builtin_amdgcn_sched_barrier(0)
; template <class Epi, class Sched, bool ALIGN_EPI = false, bool SP2 = false>
; __device__ __forceinline__ void gemm_phase(PG8_LAS unsigned char* lds, const Gemm g, const Sched& S, const Epi& E) {
;     ...
;             PG8_LDB(B0, 0, 0); PG8_LDB(B1, 0, 1); PG8_SCHED; PG8_LDA(At, 0, 0); PG8_STAGE(PG8_SA(1, 1), a1 + hstep, voffA);
;     ...
;             PG8_LDA(At, 1, 1); PG8_STAGE(PG8_SB(1, 0), b3, voffB); PG8_STAGE(PG8_SB(1, 1), b3 + hstep, voffB); PG8_STAGE(PG8_SA(1, 0), a3, voffA);
;             PG8_WAIT_V(8); PG8_WAIT_L(0); PG8_BAR; PG8_MMA(1, 0, At, B0); PG8_MMA(1, 1, At, B1); PG8_BAR; PG8_SCHED;
	s_add_i32 s3, s3, s34
	v_lshl_add_u64 v[202:203], v[202:203], 0, s[38:39]
	s_mov_b32 m0, s3
	ds_read_b128 v[190:193], v157 offset:49152
	ds_read_b128 v[194:197], v157 offset:50176
	ds_read_b128 v[198:201], v157 offset:51200
	ds_read_b128 v[208:211], v157 offset:52224
	ds_read_b128 v[212:215], v157 offset:53248
	ds_read_b128 v[216:219], v157 offset:54272
	ds_read_b128 v[220:223], v157 offset:55296
	ds_read_b128 v[224:227], v157 offset:56320
	global_load_lds_dwordx4 v[202:203], off
	s_add_i32 m0, s3, 0x2000
	s_add_u32 s14, s62, 0x40080
	v_lshl_add_u64 v[202:203], v[228:229], 0, s[38:39]
	s_addc_u32 s15, s63, 0
	s_add_i32 s3, s33, s34
	global_load_lds_dwordx4 v[202:203], off
	v_lshl_add_u64 v[202:203], s[14:15], 0, v[134:135]
	s_mov_b32 m0, s3
	s_nop 0
	global_load_lds_dwordx4 v[202:203], off
	v_lshl_add_u64 v[202:203], s[14:15], 0, v[138:139]
	s_add_i32 m0, s3, 0x2000
	s_nop 0
	global_load_lds_dwordx4 v[202:203], off
	s_waitcnt vmcnt(6)
	s_waitcnt lgkmcnt(0)
	s_barrier
	s_setprio 1
	s_waitcnt lgkmcnt(0)
	v_mfma_f32_16x16x32_bf16 v[60:63], v[148:151], v[190:193], v[60:63]
	v_mfma_f32_16x16x32_bf16 v[56:59], v[164:167], v[190:193], v[56:59]
	v_mfma_f32_16x16x32_bf16 v[52:55], v[172:175], v[190:193], v[52:55]
	v_mfma_f32_16x16x32_bf16 v[48:51], v[182:185], v[190:193], v[48:51]
	v_mfma_f32_16x16x32_bf16 v[44:47], v[148:151], v[198:201], v[44:47]
	v_mfma_f32_16x16x32_bf16 v[40:43], v[164:167], v[198:201], v[40:43]
	v_mfma_f32_16x16x32_bf16 v[36:39], v[172:175], v[198:201], v[36:39]
	v_mfma_f32_16x16x32_bf16 v[32:35], v[182:185], v[198:201], v[32:35]
	v_mfma_f32_16x16x32_bf16 v[28:31], v[148:151], v[212:215], v[28:31]
	v_mfma_f32_16x16x32_bf16 v[24:27], v[164:167], v[212:215], v[24:27]
	v_mfma_f32_16x16x32_bf16 v[20:23], v[172:175], v[212:215], v[20:23]
	v_mfma_f32_16x16x32_bf16 v[16:19], v[182:185], v[212:215], v[16:19]
	v_mfma_f32_16x16x32_bf16 v[12:15], v[148:151], v[220:223], v[12:15]
	v_mfma_f32_16x16x32_bf16 v[8:11], v[164:167], v[220:223], v[8:11]
	v_lshl_add_u64 v[202:203], v[230:231], 0, s[38:39]
	s_mov_b32 m0, s75
	s_nop 0
	global_load_lds_dwordx4 v[202:203], off
	v_mfma_f32_16x16x32_bf16 v[4:7], v[172:175], v[220:223], v[4:7]
	v_mfma_f32_16x16x32_bf16 v[0:3], v[182:185], v[220:223], v[0:3]
	s_setprio 0
	s_setprio 1
	v_mfma_f32_16x16x32_bf16 v[60:63], v[160:163], v[194:197], v[60:63]
	v_mfma_f32_16x16x32_bf16 v[56:59], v[168:171], v[194:197], v[56:59]
	v_mfma_f32_16x16x32_bf16 v[52:55], v[176:179], v[194:197], v[52:55]
	v_mfma_f32_16x16x32_bf16 v[48:51], v[186:189], v[194:197], v[48:51]
	v_mfma_f32_16x16x32_bf16 v[44:47], v[160:163], v[208:211], v[44:47]
	v_mfma_f32_16x16x32_bf16 v[40:43], v[168:171], v[208:211], v[40:43]
	v_mfma_f32_16x16x32_bf16 v[36:39], v[176:179], v[208:211], v[36:39]
	v_mfma_f32_16x16x32_bf16 v[32:35], v[186:189], v[208:211], v[32:35]
	v_mfma_f32_16x16x32_bf16 v[28:31], v[160:163], v[216:219], v[28:31]
	v_mfma_f32_16x16x32_bf16 v[24:27], v[168:171], v[216:219], v[24:27]
	v_mfma_f32_16x16x32_bf16 v[20:23], v[176:179], v[216:219], v[20:23]
	v_mfma_f32_16x16x32_bf16 v[16:19], v[186:189], v[216:219], v[16:19]
	v_mfma_f32_16x16x32_bf16 v[12:15], v[160:163], v[224:227], v[12:15]
	v_mfma_f32_16x16x32_bf16 v[8:11], v[168:171], v[224:227], v[8:11]
	v_lshl_add_u64 v[202:203], v[232:233], 0, s[38:39]
	s_mov_b32 m0, s84
	s_nop 0
	global_load_lds_dwordx4 v[202:203], off
	v_mfma_f32_16x16x32_bf16 v[4:7], v[176:179], v[224:227], v[4:7]
	v_mfma_f32_16x16x32_bf16 v[0:3], v[186:189], v[224:227], v[0:3]
	s_setprio 0
	s_barrier
	s_add_i32 s92, s92, 2
	s_add_u32 s60, s60, 0x100
	s_addc_u32 s61, s61, 0
	s_add_u32 s90, s90, 0x100
	s_addc_u32 s91, s91, 0
.LBB0_650:
	ds_read_b128 v[148:151], v155
	ds_read_b128 v[160:163], v155 offset:1024
	ds_read_b128 v[164:167], v155 offset:2048
	ds_read_b128 v[168:171], v155 offset:3072
	ds_read_b128 v[172:175], v156
	ds_read_b128 v[176:179], v156 offset:1024
	ds_read_b128 v[182:185], v156 offset:2048
	ds_read_b128 v[186:189], v156 offset:3072
	s_add_u32 s3, s60, 0xfffc0080
	s_addc_u32 s14, s61, -1
	s_cmp_eq_u32 s92, 12
	s_cselect_b32 s65, s51, s14
	s_cselect_b32 s64, s57, s3
	s_cselect_b32 s63, s49, s91
	s_cselect_b32 s62, s89, s90
	v_lshl_add_u64 v[202:203], s[60:61], 0, v[140:141]
	s_add_i32 m0, s43, 0xc000
	ds_read_b128 v[190:193], v157
	ds_read_b128 v[194:197], v157 offset:1024
	ds_read_b128 v[198:201], v157 offset:2048
	ds_read_b128 v[208:211], v157 offset:3072
	ds_read_b128 v[212:215], v157 offset:4096
	ds_read_b128 v[216:219], v157 offset:5120
	ds_read_b128 v[220:223], v157 offset:6144
	ds_read_b128 v[224:227], v157 offset:7168
	global_load_lds_dwordx4 v[202:203], off
	v_lshl_add_u64 v[202:203], s[60:61], 0, v[142:143]
	s_add_i32 m0, s43, 0xe000
	s_nop 0
	global_load_lds_dwordx4 v[202:203], off
	s_waitcnt vmcnt(8)
	s_waitcnt lgkmcnt(0)
	s_barrier
; #define PG8_STAGE(bufoff, gbase, voff) do { _Pragma("unroll") for (int _i = 0; _i < 2; ++_i) \
;         __builtin_amdgcn_global_load_lds((const unsigned*)((const char*)(gbase) + (voff)[_i]), (PG8_LAS unsigned*)(lds + (bufoff) + ldsw + _i * 8192), 16, 0, 0); } while (0)
; #define PG8_LDA(dst, b, h) do { _Pragma("unroll") for (int m = 0; m < 4; ++m) _Pragma("unroll") for (int k = 0; k < 2; ++k) dst[m][k] = *(const PG8_LAS bf16x8*)(lds + PG8_SA(b, h) + aoff + m * 2048 + k * 1024); } while (0)
; #define PG8_LDB(dst, b, h) do { _Pragma("unroll") for (int n = 0; n < 2; ++n) _Pragma("unroll") for (int k = 0; k < 2; ++k) dst[n][k] = *(const PG8_LAS bf16x8*)(lds + PG8_SB(b, h) + boff + n * 2048 + k * 1024); } while (0)
; #define PG8_MMA(ai, bj, At, Bt) do { __builtin_amdgcn_s_setprio(1); _Pragma("unroll") for (int m = 0; m < 4; ++m) _Pragma("unroll") for (int n = 0; n < 2; ++n) _Pragma("unroll") for (int k = 0; k < 2; ++k) \
;         acc[ai][bj][m][n] = __builtin_amdgcn_mfma_f32_16x16x32_bf16(Bt[n][k], At[m][k], acc[ai][bj][m][n], 0, 0, 0); __builtin_amdgcn_s_setprio(0); } while (0)
; #define PG8_WAIT_V(n) asm volatile("s_waitcnt vmcnt(" #n ")" ::: "memory")
; #define PG8_WAIT_L(n) asm volatile("s_waitcnt lgkmcnt(" #n ")" ::: "memory")
; #define PG8_BAR __builtin_amdgcn_s_barrier()
; #define PG8_SCHED __builtin_amdgcn_sched_barrier(0)
; template <class Epi, class Sched, bool ALIGN_EPI = false, bool SP2 = false>
; __device__ __forceinline__ void gemm_phase(PG8_LAS unsigned char* lds, const Gemm g, const Sched& S, const Epi& E) {
;     ...
;             PG8_LDB(B0, 0, 0); PG8_LDB(B1, 0, 1); PG8_SCHED; PG8_LDA(At, 0, 0); PG8_STAGE(PG8_SA(1, 1), a1 + hstep, voffA);
;             PG8_WAIT_V(8); PG8_WAIT_L(0); PG8_BAR; PG8_MMA(0, 0, At, B0); PG8_MMA(0, 1, At, B1); PG8_BAR; PG8_SCHED;
;             PG8_LDA(At, 0, 1); PG8_STAGE(PG8_SB(0, 0), b2, voffB); PG8_STAGE(PG8_SB(0, 1), b2 + hstep, voffB); PG8_STAGE(PG8_SA(0, 0), a2, voffA);
;             PG8_WAIT_V(8); PG8_WAIT_L(0); PG8_BAR; PG8_MMA(1, 0, At, B0); PG8_MMA(1, 1, At, B1); PG8_BAR; PG8_SCHED;
	s_setprio 1
	s_waitcnt lgkmcnt(0)
	v_mfma_f32_16x16x32_bf16 v[124:127], v[148:151], v[190:193], v[124:127]
	v_mfma_f32_16x16x32_bf16 v[120:123], v[164:167], v[190:193], v[120:123]
	v_mfma_f32_16x16x32_bf16 v[116:119], v[172:175], v[190:193], v[116:119]
	v_mfma_f32_16x16x32_bf16 v[112:115], v[182:185], v[190:193], v[112:115]
	v_mfma_f32_16x16x32_bf16 v[108:111], v[148:151], v[198:201], v[108:111]
	v_mfma_f32_16x16x32_bf16 v[104:107], v[164:167], v[198:201], v[104:107]
	v_mfma_f32_16x16x32_bf16 v[100:103], v[172:175], v[198:201], v[100:103]
	v_mfma_f32_16x16x32_bf16 v[96:99], v[182:185], v[198:201], v[96:99]
	v_mfma_f32_16x16x32_bf16 v[92:95], v[148:151], v[212:215], v[92:95]
	v_mfma_f32_16x16x32_bf16 v[88:91], v[164:167], v[212:215], v[88:91]
	v_mfma_f32_16x16x32_bf16 v[84:87], v[172:175], v[212:215], v[84:87]
	v_mfma_f32_16x16x32_bf16 v[80:83], v[182:185], v[212:215], v[80:83]
	v_mfma_f32_16x16x32_bf16 v[76:79], v[148:151], v[220:223], v[76:79]
	v_mfma_f32_16x16x32_bf16 v[72:75], v[164:167], v[220:223], v[72:75]
	v_mfma_f32_16x16x32_bf16 v[68:71], v[172:175], v[220:223], v[68:71]
	v_mfma_f32_16x16x32_bf16 v[64:67], v[182:185], v[220:223], v[64:67]
	s_setprio 0
	s_setprio 1
	v_mfma_f32_16x16x32_bf16 v[124:127], v[160:163], v[194:197], v[124:127]
	v_mfma_f32_16x16x32_bf16 v[120:123], v[168:171], v[194:197], v[120:123]
	v_mfma_f32_16x16x32_bf16 v[116:119], v[176:179], v[194:197], v[116:119]
	v_mfma_f32_16x16x32_bf16 v[112:115], v[186:189], v[194:197], v[112:115]
	v_mfma_f32_16x16x32_bf16 v[108:111], v[160:163], v[208:211], v[108:111]
	v_mfma_f32_16x16x32_bf16 v[104:107], v[168:171], v[208:211], v[104:107]
	v_mfma_f32_16x16x32_bf16 v[100:103], v[176:179], v[208:211], v[100:103]
	v_mfma_f32_16x16x32_bf16 v[96:99], v[186:189], v[208:211], v[96:99]
	v_mfma_f32_16x16x32_bf16 v[92:95], v[160:163], v[216:219], v[92:95]
	v_mfma_f32_16x16x32_bf16 v[88:91], v[168:171], v[216:219], v[88:91]
	v_mfma_f32_16x16x32_bf16 v[84:87], v[176:179], v[216:219], v[84:87]
	v_mfma_f32_16x16x32_bf16 v[80:83], v[186:189], v[216:219], v[80:83]
	v_mfma_f32_16x16x32_bf16 v[76:79], v[160:163], v[224:227], v[76:79]
	v_mfma_f32_16x16x32_bf16 v[72:75], v[168:171], v[224:227], v[72:75]
	v_mfma_f32_16x16x32_bf16 v[68:71], v[176:179], v[224:227], v[68:71]
	v_mfma_f32_16x16x32_bf16 v[64:67], v[186:189], v[224:227], v[64:67]
	s_setprio 0
	s_barrier
	s_add_i32 s3, s85, s34
	v_lshl_add_u64 v[202:203], s[62:63], 0, v[134:135]
	s_mov_b32 m0, s3
	ds_read_b128 v[190:193], v157 offset:16384
	ds_read_b128 v[194:197], v157 offset:17408
	ds_read_b128 v[198:201], v157 offset:18432
	ds_read_b128 v[208:211], v157 offset:19456
	ds_read_b128 v[212:215], v157 offset:20480
	ds_read_b128 v[216:219], v157 offset:21504
	ds_read_b128 v[220:223], v157 offset:22528
	ds_read_b128 v[224:227], v157 offset:23552
	global_load_lds_dwordx4 v[202:203], off
	s_add_i32 m0, s3, 0x2000
	s_add_u32 s14, s62, 0x40000
	v_lshl_add_u64 v[228:229], s[62:63], 0, v[138:139]
	s_addc_u32 s15, s63, 0
	s_add_i32 s3, s86, s34
	global_load_lds_dwordx4 v[228:229], off
	v_lshl_add_u64 v[230:231], s[14:15], 0, v[134:135]
	s_mov_b32 m0, s3
	global_load_lds_dwordx4 v[230:231], off
	v_lshl_add_u64 v[230:231], s[14:15], 0, v[138:139]
	s_add_i32 m0, s3, 0x2000
	s_nop 0
	global_load_lds_dwordx4 v[230:231], off
	s_waitcnt vmcnt(6)
	s_waitcnt lgkmcnt(0)
	s_barrier
	s_setprio 1
	s_waitcnt lgkmcnt(0)
	v_mfma_f32_16x16x32_bf16 v[60:63], v[148:151], v[190:193], v[60:63]
	v_mfma_f32_16x16x32_bf16 v[56:59], v[164:167], v[190:193], v[56:59]
	v_mfma_f32_16x16x32_bf16 v[52:55], v[172:175], v[190:193], v[52:55]
	v_mfma_f32_16x16x32_bf16 v[48:51], v[182:185], v[190:193], v[48:51]
	v_mfma_f32_16x16x32_bf16 v[44:47], v[148:151], v[198:201], v[44:47]
	v_mfma_f32_16x16x32_bf16 v[40:43], v[164:167], v[198:201], v[40:43]
	v_mfma_f32_16x16x32_bf16 v[36:39], v[172:175], v[198:201], v[36:39]
	v_mfma_f32_16x16x32_bf16 v[32:35], v[182:185], v[198:201], v[32:35]
	v_mfma_f32_16x16x32_bf16 v[28:31], v[148:151], v[212:215], v[28:31]
	v_mfma_f32_16x16x32_bf16 v[24:27], v[164:167], v[212:215], v[24:27]
	v_mfma_f32_16x16x32_bf16 v[20:23], v[172:175], v[212:215], v[20:23]
	v_mfma_f32_16x16x32_bf16 v[16:19], v[182:185], v[212:215], v[16:19]
	v_mfma_f32_16x16x32_bf16 v[12:15], v[148:151], v[220:223], v[12:15]
	v_mfma_f32_16x16x32_bf16 v[8:11], v[164:167], v[220:223], v[8:11]
	v_lshl_add_u64 v[230:231], s[64:65], 0, v[132:133]
	s_mov_b32 m0, s43
	s_nop 0
	global_load_lds_dwordx4 v[230:231], off
	v_mfma_f32_16x16x32_bf16 v[4:7], v[172:175], v[220:223], v[4:7]
	v_mfma_f32_16x16x32_bf16 v[0:3], v[182:185], v[220:223], v[0:3]
	s_setprio 0
	s_setprio 1
	v_mfma_f32_16x16x32_bf16 v[60:63], v[160:163], v[194:197], v[60:63]
	v_mfma_f32_16x16x32_bf16 v[56:59], v[168:171], v[194:197], v[56:59]
	v_mfma_f32_16x16x32_bf16 v[52:55], v[176:179], v[194:197], v[52:55]
	v_mfma_f32_16x16x32_bf16 v[48:51], v[186:189], v[194:197], v[48:51]
	v_mfma_f32_16x16x32_bf16 v[44:47], v[160:163], v[208:211], v[44:47]
	v_mfma_f32_16x16x32_bf16 v[40:43], v[168:171], v[208:211], v[40:43]
	v_mfma_f32_16x16x32_bf16 v[36:39], v[176:179], v[208:211], v[36:39]
	v_mfma_f32_16x16x32_bf16 v[32:35], v[186:189], v[208:211], v[32:35]
	v_mfma_f32_16x16x32_bf16 v[28:31], v[160:163], v[216:219], v[28:31]
	v_mfma_f32_16x16x32_bf16 v[24:27], v[168:171], v[216:219], v[24:27]
	v_mfma_f32_16x16x32_bf16 v[20:23], v[176:179], v[216:219], v[20:23]
	v_mfma_f32_16x16x32_bf16 v[16:19], v[186:189], v[216:219], v[16:19]
	v_mfma_f32_16x16x32_bf16 v[12:15], v[160:163], v[224:227], v[12:15]
	v_mfma_f32_16x16x32_bf16 v[8:11], v[168:171], v[224:227], v[8:11]
	v_lshl_add_u64 v[232:233], s[64:65], 0, v[136:137]
	s_mov_b32 m0, s59
	s_nop 0
	global_load_lds_dwordx4 v[232:233], off
	v_mfma_f32_16x16x32_bf16 v[4:7], v[176:179], v[224:227], v[4:7]
	v_mfma_f32_16x16x32_bf16 v[0:3], v[186:189], v[224:227], v[0:3]
	s_setprio 0
	s_barrier
; #define PG8_STAGE(bufoff, gbase, voff) do { _Pragma("unroll") for (int _i = 0; _i < 2; ++_i) \
;         __builtin_amdgcn_global_load_lds((const unsigned*)((const char*)(gbase) + (voff)[_i]), (PG8_LAS unsigned*)(lds + (bufoff) + ldsw + _i * 8192), 16, 0, 0); } while (0)
; #define PG8_LDA(dst, b, h) do { _Pragma("unroll") for (int m = 0; m < 4; ++m) _Pragma("unroll") for (int k = 0; k < 2; ++k) dst[m][k] = *(const PG8_LAS bf16x8*)(lds + PG8_SA(b, h) + aoff + m * 2048 + k * 1024); } while (0)
; #define PG8_LDB(dst, b, h) do { _Pragma("unroll") for (int n = 0; n < 2; ++n) _Pragma("unroll") for (int k = 0; k < 2; ++k) dst[n][k] = *(const PG8_LAS bf16x8*)(lds + PG8_SB(b, h) + boff + n * 2048 + k * 1024); } while (0)
; #define PG8_MMA(ai, bj, At, Bt) do { __builtin_amdgcn_s_setprio(1); _Pragma("unroll") for (int m = 0; m < 4; ++m) _Pragma("unroll") for (int n = 0; n < 2; ++n) _Pragma("unroll") for (int k = 0; k < 2; ++k) \
;         acc[ai][bj][m][n] = __builtin_amdgcn_mfma_f32_16x16x32_bf16(Bt[n][k], At[m][k], acc[ai][bj][m][n], 0, 0, 0); __builtin_amdgcn_s_setprio(0); } while (0)
; #define PG8_WAIT_V(n) asm volatile("s_waitcnt vmcnt(" #n ")" ::: "memory")
; #define PG8_WAIT_L(n) asm volatile("s_waitcnt lgkmcnt(" #n ")" ::: "memory")
; #define PG8_BAR __builtin_amdgcn_s_barrier()
; #define PG8_SCHED __builtin_amdgcn_sched_barrier(0)
; template <class Epi, class Sched, bool ALIGN_EPI = false, bool SP2 = false>
; __device__ __forceinline__ void gemm_phase(PG8_LAS unsigned char* lds, const Gemm g, const Sched& S, const Epi& E) {
;     ...
;             PG8_LDB(B0, 1, 0); PG8_LDB(B1, 1, 1); PG8_SCHED; PG8_LDA(At, 1, 0); PG8_STAGE(PG8_SA(0, 1), a2 + hstep, voffA);
;             PG8_WAIT_V(8); PG8_WAIT_L(0); PG8_BAR; PG8_MMA(0, 0, At, B0); PG8_MMA(0, 1, At, B1); PG8_BAR; PG8_SCHED;
	s_add_i32 s3, 0, 0x18000
	v_add_u32_e32 v159, s3, v131
	s_add_i32 s33, 0, 0x1c000
	ds_read_b128 v[148:151], v159
	ds_read_b128 v[160:163], v159 offset:1024
	ds_read_b128 v[164:167], v159 offset:2048
	ds_read_b128 v[168:171], v159 offset:3072
	v_add_u32_e32 v159, s33, v131
	ds_read_b128 v[172:175], v159
	ds_read_b128 v[176:179], v159 offset:1024
	ds_read_b128 v[182:185], v159 offset:2048
	ds_read_b128 v[186:189], v159 offset:3072
	s_add_u32 s14, s64, 0x40000
	s_addc_u32 s15, s65, 0
	s_mov_b32 m0, s66
	v_lshl_add_u64 v[234:235], s[14:15], 0, v[132:133]
	ds_read_b128 v[190:193], v157 offset:32768
	ds_read_b128 v[194:197], v157 offset:33792
	ds_read_b128 v[198:201], v157 offset:34816
	ds_read_b128 v[208:211], v157 offset:35840
	ds_read_b128 v[212:215], v157 offset:36864
	ds_read_b128 v[216:219], v157 offset:37888
	ds_read_b128 v[220:223], v157 offset:38912
	ds_read_b128 v[224:227], v157 offset:39936
	global_load_lds_dwordx4 v[234:235], off
	v_lshl_add_u64 v[234:235], s[14:15], 0, v[136:137]
	s_mov_b32 m0, s67
	s_nop 0
	global_load_lds_dwordx4 v[234:235], off
	s_waitcnt vmcnt(8)
	s_waitcnt lgkmcnt(0)
	s_barrier
	s_setprio 1
	s_waitcnt lgkmcnt(0)
	v_mfma_f32_16x16x32_bf16 v[124:127], v[148:151], v[190:193], v[124:127]
	v_mfma_f32_16x16x32_bf16 v[120:123], v[164:167], v[190:193], v[120:123]
	v_mfma_f32_16x16x32_bf16 v[116:119], v[172:175], v[190:193], v[116:119]
	v_mfma_f32_16x16x32_bf16 v[112:115], v[182:185], v[190:193], v[112:115]
	v_mfma_f32_16x16x32_bf16 v[108:111], v[148:151], v[198:201], v[108:111]
	v_mfma_f32_16x16x32_bf16 v[104:107], v[164:167], v[198:201], v[104:107]
	v_mfma_f32_16x16x32_bf16 v[100:103], v[172:175], v[198:201], v[100:103]
	v_mfma_f32_16x16x32_bf16 v[96:99], v[182:185], v[198:201], v[96:99]
	v_mfma_f32_16x16x32_bf16 v[92:95], v[148:151], v[212:215], v[92:95]
	v_mfma_f32_16x16x32_bf16 v[88:91], v[164:167], v[212:215], v[88:91]
	v_mfma_f32_16x16x32_bf16 v[84:87], v[172:175], v[212:215], v[84:87]
	v_mfma_f32_16x16x32_bf16 v[80:83], v[182:185], v[212:215], v[80:83]
	v_mfma_f32_16x16x32_bf16 v[76:79], v[148:151], v[220:223], v[76:79]
	v_mfma_f32_16x16x32_bf16 v[72:75], v[164:167], v[220:223], v[72:75]
	v_mfma_f32_16x16x32_bf16 v[68:71], v[172:175], v[220:223], v[68:71]
	v_mfma_f32_16x16x32_bf16 v[64:67], v[182:185], v[220:223], v[64:67]
	s_setprio 0
	s_setprio 1
	v_mfma_f32_16x16x32_bf16 v[124:127], v[160:163], v[194:197], v[124:127]
	v_mfma_f32_16x16x32_bf16 v[120:123], v[168:171], v[194:197], v[120:123]
	v_mfma_f32_16x16x32_bf16 v[116:119], v[176:179], v[194:197], v[116:119]
	v_mfma_f32_16x16x32_bf16 v[112:115], v[186:189], v[194:197], v[112:115]
	v_mfma_f32_16x16x32_bf16 v[108:111], v[160:163], v[208:211], v[108:111]
	v_mfma_f32_16x16x32_bf16 v[104:107], v[168:171], v[208:211], v[104:107]
	v_mfma_f32_16x16x32_bf16 v[100:103], v[176:179], v[208:211], v[100:103]
	v_mfma_f32_16x16x32_bf16 v[96:99], v[186:189], v[208:211], v[96:99]
	v_mfma_f32_16x16x32_bf16 v[92:95], v[160:163], v[216:219], v[92:95]
	v_mfma_f32_16x16x32_bf16 v[88:91], v[168:171], v[216:219], v[88:91]
	v_mfma_f32_16x16x32_bf16 v[84:87], v[176:179], v[216:219], v[84:87]
	v_mfma_f32_16x16x32_bf16 v[80:83], v[186:189], v[216:219], v[80:83]
	v_mfma_f32_16x16x32_bf16 v[76:79], v[160:163], v[224:227], v[76:79]
	v_mfma_f32_16x16x32_bf16 v[72:75], v[168:171], v[224:227], v[72:75]
	v_mfma_f32_16x16x32_bf16 v[68:71], v[176:179], v[224:227], v[68:71]
	v_mfma_f32_16x16x32_bf16 v[64:67], v[186:189], v[224:227], v[64:67]
	s_setprio 0
	s_barrier
; #define PG8_STAGE(bufoff, gbase, voff) do { _Pragma("unroll") for (int _i = 0; _i < 2; ++_i) \
;         __builtin_amdgcn_global_load_lds((const unsigned*)((const char*)(gbase) + (voff)[_i]), (PG8_LAS unsigned*)(lds + (bufoff) + ldsw + _i * 8192), 16, 0, 0); } while (0)
; #define PG8_LDA(dst, b, h) do { _Pragma("unroll") for (int m = 0; m < 4; ++m) _Pragma("unroll") for (int k = 0; k < 2; ++k) dst[m][k] = *(const PG8_LAS bf16x8*)(lds + PG8_SA(b, h) + aoff + m * 2048 + k * 1024); } while (0)
; #define PG8_MMA(ai, bj, At, Bt) do { __builtin_amdgcn_s_setprio(1); _Pragma("unroll") for (int m = 0; m < 4; ++m) _Pragma("unroll") for (int n = 0; n < 2; ++n) _Pragma("unroll") for (int k = 0; k < 2; ++k) \
;         acc[ai][bj][m][n] = __builtin_amdgcn_mfma_f32_16x16x32_bf16(Bt[n][k], At[m][k], acc[ai][bj][m][n], 0, 0, 0); __builtin_amdgcn_s_setprio(0); } while (0)
; #define PG8_WAIT_V(n) asm volatile("s_waitcnt vmcnt(" #n ")" ::: "memory")
; #define PG8_WAIT_L(n) asm volatile("s_waitcnt lgkmcnt(" #n ")" ::: "memory")
; #define PG8_BAR __builtin_amdgcn_s_barrier()
; #define PG8_SCHED __builtin_amdgcn_sched_barrier(0)
; template <class Epi, class Sched, bool ALIGN_EPI = false, bool SP2 = false>
; __device__ __forceinline__ void gemm_phase(PG8_LAS unsigned char* lds, const Gemm g, const Sched& S, const Epi& E) {
;     ...
;             PG8_LDA(At, 1, 1); PG8_STAGE(PG8_SB(1, 0), b3, voffB); PG8_STAGE(PG8_SB(1, 1), b3 + hstep, voffB); PG8_STAGE(PG8_SA(1, 0), a3, voffA);
;             PG8_WAIT_V(8); PG8_WAIT_L(0); PG8_BAR; PG8_MMA(1, 0, At, B0); PG8_MMA(1, 1, At, B1); PG8_BAR; PG8_SCHED;
;     ...
;         if constexpr (ALIGN_EPI) { if (wr == 0) PG8_BAR; }
	s_add_i32 s3, s3, s34
	v_lshl_add_u64 v[202:203], v[202:203], 0, s[38:39]
	s_mov_b32 m0, s3
	ds_read_b128 v[190:193], v157 offset:49152
	ds_read_b128 v[194:197], v157 offset:50176
	ds_read_b128 v[198:201], v157 offset:51200
	ds_read_b128 v[208:211], v157 offset:52224
	ds_read_b128 v[212:215], v157 offset:53248
	ds_read_b128 v[216:219], v157 offset:54272
	ds_read_b128 v[220:223], v157 offset:55296
	ds_read_b128 v[224:227], v157 offset:56320
	global_load_lds_dwordx4 v[202:203], off
	s_add_i32 m0, s3, 0x2000
	s_add_u32 s14, s62, 0x40080
	v_lshl_add_u64 v[202:203], v[228:229], 0, s[38:39]
	s_addc_u32 s15, s63, 0
	s_add_i32 s3, s33, s34
	global_load_lds_dwordx4 v[202:203], off
	v_lshl_add_u64 v[202:203], s[14:15], 0, v[134:135]
	s_mov_b32 m0, s3
	s_nop 0
	global_load_lds_dwordx4 v[202:203], off
	v_lshl_add_u64 v[202:203], s[14:15], 0, v[138:139]
	s_add_i32 m0, s3, 0x2000
	s_nop 0
	global_load_lds_dwordx4 v[202:203], off
	s_waitcnt vmcnt(6)
	s_waitcnt lgkmcnt(0)
	s_barrier
	s_setprio 1
	s_waitcnt lgkmcnt(0)
	v_mfma_f32_16x16x32_bf16 v[60:63], v[148:151], v[190:193], v[60:63]
	v_mfma_f32_16x16x32_bf16 v[56:59], v[164:167], v[190:193], v[56:59]
	v_mfma_f32_16x16x32_bf16 v[52:55], v[172:175], v[190:193], v[52:55]
	v_mfma_f32_16x16x32_bf16 v[48:51], v[182:185], v[190:193], v[48:51]
	v_mfma_f32_16x16x32_bf16 v[44:47], v[148:151], v[198:201], v[44:47]
	v_mfma_f32_16x16x32_bf16 v[40:43], v[164:167], v[198:201], v[40:43]
	v_mfma_f32_16x16x32_bf16 v[36:39], v[172:175], v[198:201], v[36:39]
	v_mfma_f32_16x16x32_bf16 v[32:35], v[182:185], v[198:201], v[32:35]
	v_mfma_f32_16x16x32_bf16 v[28:31], v[148:151], v[212:215], v[28:31]
	v_mfma_f32_16x16x32_bf16 v[24:27], v[164:167], v[212:215], v[24:27]
	v_mfma_f32_16x16x32_bf16 v[20:23], v[172:175], v[212:215], v[20:23]
	v_mfma_f32_16x16x32_bf16 v[16:19], v[182:185], v[212:215], v[16:19]
	v_mfma_f32_16x16x32_bf16 v[12:15], v[148:151], v[220:223], v[12:15]
	v_mfma_f32_16x16x32_bf16 v[8:11], v[164:167], v[220:223], v[8:11]
	v_lshl_add_u64 v[202:203], v[230:231], 0, s[38:39]
	s_mov_b32 m0, s75
	s_nop 0
	global_load_lds_dwordx4 v[202:203], off
	v_mfma_f32_16x16x32_bf16 v[4:7], v[172:175], v[220:223], v[4:7]
	v_mfma_f32_16x16x32_bf16 v[0:3], v[182:185], v[220:223], v[0:3]
	s_setprio 0
	s_setprio 1
	v_mfma_f32_16x16x32_bf16 v[60:63], v[160:163], v[194:197], v[60:63]
	v_mfma_f32_16x16x32_bf16 v[56:59], v[168:171], v[194:197], v[56:59]
	v_mfma_f32_16x16x32_bf16 v[52:55], v[176:179], v[194:197], v[52:55]
	v_mfma_f32_16x16x32_bf16 v[48:51], v[186:189], v[194:197], v[48:51]
	v_mfma_f32_16x16x32_bf16 v[44:47], v[160:163], v[208:211], v[44:47]
	v_mfma_f32_16x16x32_bf16 v[40:43], v[168:171], v[208:211], v[40:43]
	v_mfma_f32_16x16x32_bf16 v[36:39], v[176:179], v[208:211], v[36:39]
	v_mfma_f32_16x16x32_bf16 v[32:35], v[186:189], v[208:211], v[32:35]
	v_mfma_f32_16x16x32_bf16 v[28:31], v[160:163], v[216:219], v[28:31]
	v_mfma_f32_16x16x32_bf16 v[24:27], v[168:171], v[216:219], v[24:27]
	v_mfma_f32_16x16x32_bf16 v[20:23], v[176:179], v[216:219], v[20:23]
	v_mfma_f32_16x16x32_bf16 v[16:19], v[186:189], v[216:219], v[16:19]
	v_mfma_f32_16x16x32_bf16 v[12:15], v[160:163], v[224:227], v[12:15]
	v_mfma_f32_16x16x32_bf16 v[8:11], v[168:171], v[224:227], v[8:11]
	v_lshl_add_u64 v[202:203], v[232:233], 0, s[38:39]
	s_mov_b32 m0, s84
	s_nop 0
	global_load_lds_dwordx4 v[202:203], off
	v_mfma_f32_16x16x32_bf16 v[4:7], v[176:179], v[224:227], v[4:7]
	v_mfma_f32_16x16x32_bf16 v[0:3], v[186:189], v[224:227], v[0:3]
	s_setprio 0
	s_barrier
	s_add_i32 s92, s92, 2
	s_add_u32 s60, s60, 0x100
	s_addc_u32 s61, s61, 0
	s_add_u32 s90, s90, 0x100
	s_addc_u32 s91, s91, 0
	s_cmp_gt_u32 s92, 13
	s_cbranch_scc0 .LBB0_650
	s_and_b64 vcc, exec, s[44:45]
	s_cbranch_vccz .LBB0_653
	s_barrier

; #define PG8_STAGE(bufoff, gbase, voff) do { _Pragma("unroll") for (int _i = 0; _i < 2; ++_i) \
;         __builtin_amdgcn_global_load_lds((const unsigned*)((const char*)(gbase) + (voff)[_i]), (PG8_LAS unsigned*)(lds + (bufoff) + ldsw + _i * 8192), 16, 0, 0); } while (0)
; #define PG8_LDA(dst, b, h) do { _Pragma("unroll") for (int m = 0; m < 4; ++m) _Pragma("unroll") for (int k = 0; k < 2; ++k) dst[m][k] = *(const PG8_LAS bf16x8*)(lds + PG8_SA(b, h) + aoff + m * 2048 + k * 1024); } while (0)
; #define PG8_LDB(dst, b, h) do { _Pragma("unroll") for (int n = 0; n < 2; ++n) _Pragma("unroll") for (int k = 0; k < 2; ++k) dst[n][k] = *(const PG8_LAS bf16x8*)(lds + PG8_SB(b, h) + boff + n * 2048 + k * 1024); } while (0)
; #define PG8_MMA(ai, bj, At, Bt) do { __builtin_amdgcn_s_setprio(1); _Pragma("unroll") for (int m = 0; m < 4; ++m) _Pragma("unroll") for (int n = 0; n < 2; ++n) _Pragma("unroll") for (int k = 0; k < 2; ++k) \
;         acc[ai][bj][m][n] = __builtin_amdgcn_mfma_f32_16x16x32_bf16(Bt[n][k], At[m][k], acc[ai][bj][m][n], 0, 0, 0); __builtin_amdgcn_s_setprio(0); } while (0)
; #define PG8_BAR __builtin_amdgcn_s_barrier()
; template <class Epi, class Sched, bool ALIGN_EPI = false, bool SP2 = false>
; __device__ __forceinline__ void gemm_phase(PG8_LAS unsigned char* lds, const Gemm g, const Sched& S, const Epi& E) {
;     ...
;         const bool has_next = S.next(ui + 1, nxt);
;         const char* nA = has_next ? (const char*)g.A + (size_t)nxt.pm * tstep : cA; const char* nB = has_next ? (const char*)g.Bt + (size_t)nxt.pn * tstep : cB;
;         for (int t = 0; t < nt; t += 2) {
;             const bool last = (t == nt - 2);
;             const char* a1 = cA + (size_t)(t + 1) * kstep;
;             const char* a2 = last ? nA : cA + (size_t)(t + 2) * kstep; const char* b2 = last ? nB : cB + (size_t)(t + 2) * kstep;
;             const char* a3 = a2 + kstep; const char* b3 = b2 + kstep;
;             if (last && has_next) S.a_ready(nxt);
;             if constexpr (SP2) {
;             PG8_LDB(B0, 0, 0); PG8_LDB(B1, 0, 1); PG8_SCHED; PG8_LDA(At, 0, 0); PG8_STAGE(PG8_SA(1, 1), a1 + hstep, voffA);
;             PG8_WAIT_V(8); PG8_WAIT_L(0); PG8_BAR; PG8_MMA(0, 0, At, B0); PG8_MMA(0, 1, At, B1); PG8_BAR; PG8_SCHED;
;             PG8_LDA(At, 0, 1); PG8_STAGE(PG8_SB(0, 0), b2, voffB); PG8_STAGE(PG8_SB(0, 1), b2 + hstep, voffB); PG8_STAGE(PG8_SA(0, 0), a2, voffA);
.LBB0_737:
	s_ashr_i32 s51, s50, 31
	s_lshl_b64 s[14:15], s[50:51], 19
	s_add_u32 s52, s22, s14
	s_addc_u32 s53, s23, s15
	s_and_b64 s[14:15], s[8:9], exec
	s_cselect_b32 s51, s53, s57
	s_cselect_b32 s82, s52, s56
	s_ashr_i32 s49, s48, 31
	s_lshl_b64 s[14:15], s[48:49], 19
	v_readlane_b32 s3, v250, 15
	s_add_u32 s54, s3, s14
	v_readlane_b32 s3, v250, 16
	s_addc_u32 s55, s3, s15
	s_and_b64 s[14:15], s[8:9], exec
	s_cselect_b32 s49, s55, s59
	s_cselect_b32 s83, s54, s58
	s_add_u32 s56, s56, 0x40080
	s_addc_u32 s57, s57, 0
	s_add_u32 s84, s58, 0x100
	s_addc_u32 s85, s59, 0
	s_mov_b32 s86, -2
	s_waitcnt vmcnt(0)
	ds_read_b128 v[148:151], v155
	ds_read_b128 v[160:163], v155 offset:1024
	ds_read_b128 v[164:167], v155 offset:2048
	ds_read_b128 v[168:171], v155 offset:3072
	ds_read_b128 v[172:175], v156
	ds_read_b128 v[176:179], v156 offset:1024
	ds_read_b128 v[182:185], v156 offset:2048
	ds_read_b128 v[186:189], v156 offset:3072
	s_add_u32 s3, s56, 0xfffc0080
	s_addc_u32 s14, s57, -1
	s_cmp_eq_u32 s86, 12
	s_cselect_b32 s61, s51, s14
	s_cselect_b32 s60, s82, s3
	s_cselect_b32 s59, s49, s85
	s_cselect_b32 s58, s83, s84
	v_lshl_add_u64 v[202:203], s[56:57], 0, v[140:141]
	s_add_i32 m0, s43, 0xc000
	ds_read_b128 v[190:193], v157
	ds_read_b128 v[194:197], v157 offset:1024
	ds_read_b128 v[198:201], v157 offset:2048
	ds_read_b128 v[208:211], v157 offset:3072
	ds_read_b128 v[212:215], v157 offset:4096
	ds_read_b128 v[216:219], v157 offset:5120
	ds_read_b128 v[220:223], v157 offset:6144
	ds_read_b128 v[224:227], v157 offset:7168
	global_load_lds_dwordx4 v[202:203], off
	v_lshl_add_u64 v[202:203], s[56:57], 0, v[142:143]
	s_add_i32 m0, s43, 0xe000
	s_nop 0
	global_load_lds_dwordx4 v[202:203], off
	s_waitcnt vmcnt(8)
	s_waitcnt lgkmcnt(0)
	s_barrier
	s_setprio 1
	s_waitcnt lgkmcnt(0)
	v_mfma_f32_16x16x32_bf16 v[124:127], v[148:151], v[190:193], 0
	v_mfma_f32_16x16x32_bf16 v[120:123], v[164:167], v[190:193], 0
	v_mfma_f32_16x16x32_bf16 v[116:119], v[172:175], v[190:193], 0
	v_mfma_f32_16x16x32_bf16 v[112:115], v[182:185], v[190:193], 0
	v_mfma_f32_16x16x32_bf16 v[108:111], v[148:151], v[198:201], 0
	v_mfma_f32_16x16x32_bf16 v[104:107], v[164:167], v[198:201], 0
	v_mfma_f32_16x16x32_bf16 v[100:103], v[172:175], v[198:201], 0
	v_mfma_f32_16x16x32_bf16 v[96:99], v[182:185], v[198:201], 0
	v_mfma_f32_16x16x32_bf16 v[92:95], v[148:151], v[212:215], 0
	v_mfma_f32_16x16x32_bf16 v[88:91], v[164:167], v[212:215], 0
	v_mfma_f32_16x16x32_bf16 v[84:87], v[172:175], v[212:215], 0
	v_mfma_f32_16x16x32_bf16 v[80:83], v[182:185], v[212:215], 0
	v_mfma_f32_16x16x32_bf16 v[76:79], v[148:151], v[220:223], 0
	v_mfma_f32_16x16x32_bf16 v[72:75], v[164:167], v[220:223], 0
	v_mfma_f32_16x16x32_bf16 v[68:71], v[172:175], v[220:223], 0
	v_mfma_f32_16x16x32_bf16 v[64:67], v[182:185], v[220:223], 0
	s_setprio 0
	s_setprio 1
	v_mfma_f32_16x16x32_bf16 v[124:127], v[160:163], v[194:197], v[124:127]
	v_mfma_f32_16x16x32_bf16 v[120:123], v[168:171], v[194:197], v[120:123]
	v_mfma_f32_16x16x32_bf16 v[116:119], v[176:179], v[194:197], v[116:119]
	v_mfma_f32_16x16x32_bf16 v[112:115], v[186:189], v[194:197], v[112:115]
	v_mfma_f32_16x16x32_bf16 v[108:111], v[160:163], v[208:211], v[108:111]
	v_mfma_f32_16x16x32_bf16 v[104:107], v[168:171], v[208:211], v[104:107]
	v_mfma_f32_16x16x32_bf16 v[100:103], v[176:179], v[208:211], v[100:103]
	v_mfma_f32_16x16x32_bf16 v[96:99], v[186:189], v[208:211], v[96:99]
	v_mfma_f32_16x16x32_bf16 v[92:95], v[160:163], v[216:219], v[92:95]
	v_mfma_f32_16x16x32_bf16 v[88:91], v[168:171], v[216:219], v[88:91]
	v_mfma_f32_16x16x32_bf16 v[84:87], v[176:179], v[216:219], v[84:87]
	v_mfma_f32_16x16x32_bf16 v[80:83], v[186:189], v[216:219], v[80:83]
	v_mfma_f32_16x16x32_bf16 v[76:79], v[160:163], v[224:227], v[76:79]
	v_mfma_f32_16x16x32_bf16 v[72:75], v[168:171], v[224:227], v[72:75]
	v_mfma_f32_16x16x32_bf16 v[68:71], v[176:179], v[224:227], v[68:71]
	v_mfma_f32_16x16x32_bf16 v[64:67], v[186:189], v[224:227], v[64:67]
	s_setprio 0
	s_barrier
	s_add_i32 s3, s74, s34
	v_lshl_add_u64 v[202:203], s[58:59], 0, v[136:137]
	s_mov_b32 m0, s3
	ds_read_b128 v[190:193], v157 offset:16384
	ds_read_b128 v[194:197], v157 offset:17408
	ds_read_b128 v[198:201], v157 offset:18432
	ds_read_b128 v[208:211], v157 offset:19456
	ds_read_b128 v[212:215], v157 offset:20480
	ds_read_b128 v[216:219], v157 offset:21504
	ds_read_b128 v[220:223], v157 offset:22528
	ds_read_b128 v[224:227], v157 offset:23552
	global_load_lds_dwordx4 v[202:203], off
	s_add_i32 m0, s3, 0x2000
	s_add_u32 s14, s58, 0x40000
	v_lshl_add_u64 v[228:229], s[58:59], 0, v[132:133]
	s_addc_u32 s15, s59, 0
	s_add_i32 s3, s75, s34
	global_load_lds_dwordx4 v[228:229], off
	v_lshl_add_u64 v[230:231], s[14:15], 0, v[136:137]
	s_mov_b32 m0, s3
	global_load_lds_dwordx4 v[230:231], off
	v_lshl_add_u64 v[230:231], s[14:15], 0, v[132:133]
	s_add_i32 m0, s3, 0x2000
	s_nop 0
	global_load_lds_dwordx4 v[230:231], off
	s_waitcnt vmcnt(6)
	s_waitcnt lgkmcnt(0)
	s_barrier
; #define PG8_STAGE(bufoff, gbase, voff) do { _Pragma("unroll") for (int _i = 0; _i < 2; ++_i) \
;         __builtin_amdgcn_global_load_lds((const unsigned*)((const char*)(gbase) + (voff)[_i]), (PG8_LAS unsigned*)(lds + (bufoff) + ldsw + _i * 8192), 16, 0, 0); } while (0)
; #define PG8_LDA(dst, b, h) do { _Pragma("unroll") for (int m = 0; m < 4; ++m) _Pragma("unroll") for (int k = 0; k < 2; ++k) dst[m][k] = *(const PG8_LAS bf16x8*)(lds + PG8_SA(b, h) + aoff + m * 2048 + k * 1024); } while (0)
; #define PG8_LDB(dst, b, h) do { _Pragma("unroll") for (int n = 0; n < 2; ++n) _Pragma("unroll") for (int k = 0; k < 2; ++k) dst[n][k] = *(const PG8_LAS bf16x8*)(lds + PG8_SB(b, h) + boff + n * 2048 + k * 1024); } while (0)
; #define PG8_MMA(ai, bj, At, Bt) do { __builtin_amdgcn_s_setprio(1); _Pragma("unroll") for (int m = 0; m < 4; ++m) _Pragma("unroll") for (int n = 0; n < 2; ++n) _Pragma("unroll") for (int k = 0; k < 2; ++k) \
;         acc[ai][bj][m][n] = __builtin_amdgcn_mfma_f32_16x16x32_bf16(Bt[n][k], At[m][k], acc[ai][bj][m][n], 0, 0, 0); __builtin_amdgcn_s_setprio(0); } while (0)
; #define PG8_WAIT_V(n) asm volatile("s_waitcnt vmcnt(" #n ")" ::: "memory")
; #define PG8_WAIT_L(n) asm volatile("s_waitcnt lgkmcnt(" #n ")" ::: "memory")
; #define PG8_BAR __builtin_amdgcn_s_barrier()
; #define PG8_SCHED __builtin_amdgcn_sched_barrier(0)
; template <class Epi, class Sched, bool ALIGN_EPI = false, bool SP2 = false>
; __device__ __forceinline__ void gemm_phase(PG8_LAS unsigned char* lds, const Gemm g, const Sched& S, const Epi& E) {
;     ...
;             PG8_WAIT_V(8); PG8_WAIT_L(0); PG8_BAR; PG8_MMA(1, 0, At, B0); PG8_MMA(1, 1, At, B1); PG8_BAR; PG8_SCHED;
;             PG8_LDB(B0, 1, 0); PG8_LDB(B1, 1, 1); PG8_SCHED; PG8_LDA(At, 1, 0); PG8_STAGE(PG8_SA(0, 1), a2 + hstep, voffA);
;             PG8_WAIT_V(8); PG8_WAIT_L(0); PG8_BAR; PG8_MMA(0, 0, At, B0); PG8_MMA(0, 1, At, B1); PG8_BAR; PG8_SCHED;
	s_setprio 1
	s_waitcnt lgkmcnt(0)
	v_mfma_f32_16x16x32_bf16 v[60:63], v[148:151], v[190:193], 0
	v_mfma_f32_16x16x32_bf16 v[56:59], v[164:167], v[190:193], 0
	v_mfma_f32_16x16x32_bf16 v[52:55], v[172:175], v[190:193], 0
	v_mfma_f32_16x16x32_bf16 v[48:51], v[182:185], v[190:193], 0
	v_mfma_f32_16x16x32_bf16 v[44:47], v[148:151], v[198:201], 0
	v_mfma_f32_16x16x32_bf16 v[40:43], v[164:167], v[198:201], 0
	v_mfma_f32_16x16x32_bf16 v[36:39], v[172:175], v[198:201], 0
	v_mfma_f32_16x16x32_bf16 v[32:35], v[182:185], v[198:201], 0
	v_mfma_f32_16x16x32_bf16 v[28:31], v[148:151], v[212:215], 0
	v_mfma_f32_16x16x32_bf16 v[24:27], v[164:167], v[212:215], 0
	v_mfma_f32_16x16x32_bf16 v[20:23], v[172:175], v[212:215], 0
	v_mfma_f32_16x16x32_bf16 v[16:19], v[182:185], v[212:215], 0
	v_mfma_f32_16x16x32_bf16 v[12:15], v[148:151], v[220:223], 0
	v_mfma_f32_16x16x32_bf16 v[8:11], v[164:167], v[220:223], 0
	v_lshl_add_u64 v[230:231], s[60:61], 0, v[138:139]
	s_mov_b32 m0, s43
	s_nop 0
	global_load_lds_dwordx4 v[230:231], off
	v_mfma_f32_16x16x32_bf16 v[4:7], v[172:175], v[220:223], 0
	v_mfma_f32_16x16x32_bf16 v[0:3], v[182:185], v[220:223], 0
	s_setprio 0
	s_setprio 1
	v_mfma_f32_16x16x32_bf16 v[60:63], v[160:163], v[194:197], v[60:63]
	v_mfma_f32_16x16x32_bf16 v[56:59], v[168:171], v[194:197], v[56:59]
	v_mfma_f32_16x16x32_bf16 v[52:55], v[176:179], v[194:197], v[52:55]
	v_mfma_f32_16x16x32_bf16 v[48:51], v[186:189], v[194:197], v[48:51]
	v_mfma_f32_16x16x32_bf16 v[44:47], v[160:163], v[208:211], v[44:47]
	v_mfma_f32_16x16x32_bf16 v[40:43], v[168:171], v[208:211], v[40:43]
	v_mfma_f32_16x16x32_bf16 v[36:39], v[176:179], v[208:211], v[36:39]
	v_mfma_f32_16x16x32_bf16 v[32:35], v[186:189], v[208:211], v[32:35]
	v_mfma_f32_16x16x32_bf16 v[28:31], v[160:163], v[216:219], v[28:31]
	v_mfma_f32_16x16x32_bf16 v[24:27], v[168:171], v[216:219], v[24:27]
	v_mfma_f32_16x16x32_bf16 v[20:23], v[176:179], v[216:219], v[20:23]
	v_mfma_f32_16x16x32_bf16 v[16:19], v[186:189], v[216:219], v[16:19]
	v_mfma_f32_16x16x32_bf16 v[12:15], v[160:163], v[224:227], v[12:15]
	v_mfma_f32_16x16x32_bf16 v[8:11], v[168:171], v[224:227], v[8:11]
	v_lshl_add_u64 v[232:233], s[60:61], 0, v[134:135]
	s_mov_b32 m0, s62
	s_nop 0
	global_load_lds_dwordx4 v[232:233], off
	v_mfma_f32_16x16x32_bf16 v[4:7], v[176:179], v[224:227], v[4:7]
	v_mfma_f32_16x16x32_bf16 v[0:3], v[186:189], v[224:227], v[0:3]
	s_setprio 0
	s_barrier
	s_add_i32 s3, 0, 0x18000
	v_add_u32_e32 v159, s3, v131
	s_add_i32 s33, 0, 0x1c000
	ds_read_b128 v[148:151], v159
	ds_read_b128 v[160:163], v159 offset:1024
	ds_read_b128 v[164:167], v159 offset:2048
	ds_read_b128 v[168:171], v159 offset:3072
	v_add_u32_e32 v159, s33, v131
	ds_read_b128 v[172:175], v159
	ds_read_b128 v[176:179], v159 offset:1024
	ds_read_b128 v[182:185], v159 offset:2048
	ds_read_b128 v[186:189], v159 offset:3072
	s_add_u32 s14, s60, 0x40000
	s_addc_u32 s15, s61, 0
	s_mov_b32 m0, s63
	v_lshl_add_u64 v[234:235], s[14:15], 0, v[138:139]
	ds_read_b128 v[190:193], v157 offset:32768
	ds_read_b128 v[194:197], v157 offset:33792
	ds_read_b128 v[198:201], v157 offset:34816
	ds_read_b128 v[208:211], v157 offset:35840
	ds_read_b128 v[212:215], v157 offset:36864
	ds_read_b128 v[216:219], v157 offset:37888
	ds_read_b128 v[220:223], v157 offset:38912
	ds_read_b128 v[224:227], v157 offset:39936
	global_load_lds_dwordx4 v[234:235], off
	v_lshl_add_u64 v[234:235], s[14:15], 0, v[134:135]
	s_mov_b32 m0, s64
	s_nop 0
	global_load_lds_dwordx4 v[234:235], off
	s_waitcnt vmcnt(8)
	s_waitcnt lgkmcnt(0)
	s_barrier
	s_setprio 1
	s_waitcnt lgkmcnt(0)
	v_mfma_f32_16x16x32_bf16 v[124:127], v[148:151], v[190:193], v[124:127]
	v_mfma_f32_16x16x32_bf16 v[120:123], v[164:167], v[190:193], v[120:123]
	v_mfma_f32_16x16x32_bf16 v[116:119], v[172:175], v[190:193], v[116:119]
	v_mfma_f32_16x16x32_bf16 v[112:115], v[182:185], v[190:193], v[112:115]
	v_mfma_f32_16x16x32_bf16 v[108:111], v[148:151], v[198:201], v[108:111]
	v_mfma_f32_16x16x32_bf16 v[104:107], v[164:167], v[198:201], v[104:107]
	v_mfma_f32_16x16x32_bf16 v[100:103], v[172:175], v[198:201], v[100:103]
	v_mfma_f32_16x16x32_bf16 v[96:99], v[182:185], v[198:201], v[96:99]
	v_mfma_f32_16x16x32_bf16 v[92:95], v[148:151], v[212:215], v[92:95]
	v_mfma_f32_16x16x32_bf16 v[88:91], v[164:167], v[212:215], v[88:91]
	v_mfma_f32_16x16x32_bf16 v[84:87], v[172:175], v[212:215], v[84:87]
	v_mfma_f32_16x16x32_bf16 v[80:83], v[182:185], v[212:215], v[80:83]
	v_mfma_f32_16x16x32_bf16 v[76:79], v[148:151], v[220:223], v[76:79]
	v_mfma_f32_16x16x32_bf16 v[72:75], v[164:167], v[220:223], v[72:75]
	v_mfma_f32_16x16x32_bf16 v[68:71], v[172:175], v[220:223], v[68:71]
	v_mfma_f32_16x16x32_bf16 v[64:67], v[182:185], v[220:223], v[64:67]
	s_setprio 0
	s_setprio 1
	v_mfma_f32_16x16x32_bf16 v[124:127], v[160:163], v[194:197], v[124:127]
	v_mfma_f32_16x16x32_bf16 v[120:123], v[168:171], v[194:197], v[120:123]
	v_mfma_f32_16x16x32_bf16 v[116:119], v[176:179], v[194:197], v[116:119]
	v_mfma_f32_16x16x32_bf16 v[112:115], v[186:189], v[194:197], v[112:115]
	v_mfma_f32_16x16x32_bf16 v[108:111], v[160:163], v[208:211], v[108:111]
	v_mfma_f32_16x16x32_bf16 v[104:107], v[168:171], v[208:211], v[104:107]
	v_mfma_f32_16x16x32_bf16 v[100:103], v[176:179], v[208:211], v[100:103]
	v_mfma_f32_16x16x32_bf16 v[96:99], v[186:189], v[208:211], v[96:99]
	v_mfma_f32_16x16x32_bf16 v[92:95], v[160:163], v[216:219], v[92:95]
	v_mfma_f32_16x16x32_bf16 v[88:91], v[168:171], v[216:219], v[88:91]
	v_mfma_f32_16x16x32_bf16 v[84:87], v[176:179], v[216:219], v[84:87]
	v_mfma_f32_16x16x32_bf16 v[80:83], v[186:189], v[216:219], v[80:83]
	v_mfma_f32_16x16x32_bf16 v[76:79], v[160:163], v[224:227], v[76:79]
	v_mfma_f32_16x16x32_bf16 v[72:75], v[168:171], v[224:227], v[72:75]
	v_mfma_f32_16x16x32_bf16 v[68:71], v[176:179], v[224:227], v[68:71]
	v_mfma_f32_16x16x32_bf16 v[64:67], v[186:189], v[224:227], v[64:67]
	s_setprio 0
	s_barrier
; #define PG8_STAGE(bufoff, gbase, voff) do { _Pragma("unroll") for (int _i = 0; _i < 2; ++_i) \
;         __builtin_amdgcn_global_load_lds((const unsigned*)((const char*)(gbase) + (voff)[_i]), (PG8_LAS unsigned*)(lds + (bufoff) + ldsw + _i * 8192), 16, 0, 0); } while (0)
; #define PG8_LDA(dst, b, h) do { _Pragma("unroll") for (int m = 0; m < 4; ++m) _Pragma("unroll") for (int k = 0; k < 2; ++k) dst[m][k] = *(const PG8_LAS bf16x8*)(lds + PG8_SA(b, h) + aoff + m * 2048 + k * 1024); } while (0)
; #define PG8_LDB(dst, b, h) do { _Pragma("unroll") for (int n = 0; n < 2; ++n) _Pragma("unroll") for (int k = 0; k < 2; ++k) dst[n][k] = *(const PG8_LAS bf16x8*)(lds + PG8_SB(b, h) + boff + n * 2048 + k * 1024); } while (0)
; #define PG8_MMA(ai, bj, At, Bt) do { __builtin_amdgcn_s_setprio(1); _Pragma("unroll") for (int m = 0; m < 4; ++m) _Pragma("unroll") for (int n = 0; n < 2; ++n) _Pragma("unroll") for (int k = 0; k < 2; ++k) \
;         acc[ai][bj][m][n] = __builtin_amdgcn_mfma_f32_16x16x32_bf16(Bt[n][k], At[m][k], acc[ai][bj][m][n], 0, 0, 0); __builtin_amdgcn_s_setprio(0); } while (0)
; #define PG8_WAIT_V(n) asm volatile("s_waitcnt vmcnt(" #n ")" ::: "memory")
; template <class Epi, class Sched, bool ALIGN_EPI = false, bool SP2 = false>
; __device__ __forceinline__ void gemm_phase(PG8_LAS unsigned char* lds, const Gemm g, const Sched& S, const Epi& E) {
;     ...
;             PG8_LDB(B0, 0, 0); PG8_LDB(B1, 0, 1); PG8_SCHED; PG8_LDA(At, 0, 0); PG8_STAGE(PG8_SA(1, 1), a1 + hstep, voffA);
;             PG8_WAIT_V(8); PG8_WAIT_L(0); PG8_BAR; PG8_MMA(0, 0, At, B0); PG8_MMA(0, 1, At, B1); PG8_BAR; PG8_SCHED;
;             PG8_LDA(At, 0, 1); PG8_STAGE(PG8_SB(0, 0), b2, voffB); PG8_STAGE(PG8_SB(0, 1), b2 + hstep, voffB); PG8_STAGE(PG8_SA(0, 0), a2, voffA);
;             PG8_WAIT_V(8); PG8_WAIT_L(0); PG8_BAR; PG8_MMA(1, 0, At, B0); PG8_MMA(1, 1, At, B1); PG8_BAR; PG8_SCHED;
;             PG8_LDB(B0, 1, 0); PG8_LDB(B1, 1, 1); PG8_SCHED; PG8_LDA(At, 1, 0); PG8_STAGE(PG8_SA(0, 1), a2 + hstep, voffA);
;             PG8_WAIT_V(8); PG8_WAIT_L(0); PG8_BAR; PG8_MMA(0, 0, At, B0); PG8_MMA(0, 1, At, B1); PG8_BAR; PG8_SCHED;
;             PG8_LDA(At, 1, 1); PG8_STAGE(PG8_SB(1, 0), b3, voffB); PG8_STAGE(PG8_SB(1, 1), b3 + hstep, voffB); PG8_STAGE(PG8_SA(1, 0), a3, voffA);
;             PG8_WAIT_V(8); PG8_WAIT_L(0); PG8_BAR; PG8_MMA(1, 0, At, B0); PG8_MMA(1, 1, At, B1); PG8_BAR; PG8_SCHED;
	s_add_i32 s3, s3, s34
	v_lshl_add_u64 v[202:203], v[202:203], 0, s[38:39]
	s_mov_b32 m0, s3
	ds_read_b128 v[190:193], v157 offset:49152
	ds_read_b128 v[194:197], v157 offset:50176
	ds_read_b128 v[198:201], v157 offset:51200
	ds_read_b128 v[208:211], v157 offset:52224
	ds_read_b128 v[212:215], v157 offset:53248
	ds_read_b128 v[216:219], v157 offset:54272
	ds_read_b128 v[220:223], v157 offset:55296
	ds_read_b128 v[224:227], v157 offset:56320
	global_load_lds_dwordx4 v[202:203], off
	s_add_i32 m0, s3, 0x2000
	s_add_u32 s14, s58, 0x40080
	v_lshl_add_u64 v[202:203], v[228:229], 0, s[38:39]
	s_addc_u32 s15, s59, 0
	s_add_i32 s3, s33, s34
	global_load_lds_dwordx4 v[202:203], off
	v_lshl_add_u64 v[202:203], s[14:15], 0, v[136:137]
	s_mov_b32 m0, s3
	s_nop 0
	global_load_lds_dwordx4 v[202:203], off
	v_lshl_add_u64 v[202:203], s[14:15], 0, v[132:133]
	s_add_i32 m0, s3, 0x2000
	s_nop 0
	global_load_lds_dwordx4 v[202:203], off
	s_waitcnt vmcnt(6)
	s_waitcnt lgkmcnt(0)
	s_barrier
	s_setprio 1
	s_waitcnt lgkmcnt(0)
	v_mfma_f32_16x16x32_bf16 v[60:63], v[148:151], v[190:193], v[60:63]
	v_mfma_f32_16x16x32_bf16 v[56:59], v[164:167], v[190:193], v[56:59]
	v_mfma_f32_16x16x32_bf16 v[52:55], v[172:175], v[190:193], v[52:55]
	v_mfma_f32_16x16x32_bf16 v[48:51], v[182:185], v[190:193], v[48:51]
	v_mfma_f32_16x16x32_bf16 v[44:47], v[148:151], v[198:201], v[44:47]
	v_mfma_f32_16x16x32_bf16 v[40:43], v[164:167], v[198:201], v[40:43]
	v_mfma_f32_16x16x32_bf16 v[36:39], v[172:175], v[198:201], v[36:39]
	v_mfma_f32_16x16x32_bf16 v[32:35], v[182:185], v[198:201], v[32:35]
	v_mfma_f32_16x16x32_bf16 v[28:31], v[148:151], v[212:215], v[28:31]
	v_mfma_f32_16x16x32_bf16 v[24:27], v[164:167], v[212:215], v[24:27]
	v_mfma_f32_16x16x32_bf16 v[20:23], v[172:175], v[212:215], v[20:23]
	v_mfma_f32_16x16x32_bf16 v[16:19], v[182:185], v[212:215], v[16:19]
	v_mfma_f32_16x16x32_bf16 v[12:15], v[148:151], v[220:223], v[12:15]
	v_mfma_f32_16x16x32_bf16 v[8:11], v[164:167], v[220:223], v[8:11]
	v_lshl_add_u64 v[202:203], v[230:231], 0, s[38:39]
	s_mov_b32 m0, s66
	s_nop 0
	global_load_lds_dwordx4 v[202:203], off
	v_mfma_f32_16x16x32_bf16 v[4:7], v[172:175], v[220:223], v[4:7]
	v_mfma_f32_16x16x32_bf16 v[0:3], v[182:185], v[220:223], v[0:3]
	s_setprio 0
	s_setprio 1
	v_mfma_f32_16x16x32_bf16 v[60:63], v[160:163], v[194:197], v[60:63]
	v_mfma_f32_16x16x32_bf16 v[56:59], v[168:171], v[194:197], v[56:59]
	v_mfma_f32_16x16x32_bf16 v[52:55], v[176:179], v[194:197], v[52:55]
	v_mfma_f32_16x16x32_bf16 v[48:51], v[186:189], v[194:197], v[48:51]
	v_mfma_f32_16x16x32_bf16 v[44:47], v[160:163], v[208:211], v[44:47]
	v_mfma_f32_16x16x32_bf16 v[40:43], v[168:171], v[208:211], v[40:43]
	v_mfma_f32_16x16x32_bf16 v[36:39], v[176:179], v[208:211], v[36:39]
	v_mfma_f32_16x16x32_bf16 v[32:35], v[186:189], v[208:211], v[32:35]
	v_mfma_f32_16x16x32_bf16 v[28:31], v[160:163], v[216:219], v[28:31]
	v_mfma_f32_16x16x32_bf16 v[24:27], v[168:171], v[216:219], v[24:27]
	v_mfma_f32_16x16x32_bf16 v[20:23], v[176:179], v[216:219], v[20:23]
	v_mfma_f32_16x16x32_bf16 v[16:19], v[186:189], v[216:219], v[16:19]
	v_mfma_f32_16x16x32_bf16 v[12:15], v[160:163], v[224:227], v[12:15]
	v_mfma_f32_16x16x32_bf16 v[8:11], v[168:171], v[224:227], v[8:11]
	v_lshl_add_u64 v[202:203], v[232:233], 0, s[38:39]
	s_mov_b32 m0, s67
	s_nop 0
	global_load_lds_dwordx4 v[202:203], off
	v_mfma_f32_16x16x32_bf16 v[4:7], v[176:179], v[224:227], v[4:7]
	v_mfma_f32_16x16x32_bf16 v[0:3], v[186:189], v[224:227], v[0:3]
	s_setprio 0
	s_barrier
	s_add_i32 s86, s86, 2
	s_add_u32 s56, s56, 0x100
	s_addc_u32 s57, s57, 0
	s_add_u32 s84, s84, 0x100
	s_addc_u32 s85, s85, 0
.LBB0_738:
	ds_read_b128 v[148:151], v155
	ds_read_b128 v[160:163], v155 offset:1024
	ds_read_b128 v[164:167], v155 offset:2048
	ds_read_b128 v[168:171], v155 offset:3072
	ds_read_b128 v[172:175], v156
	ds_read_b128 v[176:179], v156 offset:1024
	ds_read_b128 v[182:185], v156 offset:2048
	ds_read_b128 v[186:189], v156 offset:3072
	s_add_u32 s3, s56, 0xfffc0080
	s_addc_u32 s14, s57, -1
	s_cmp_eq_u32 s86, 12
	s_cselect_b32 s61, s51, s14
	s_cselect_b32 s60, s82, s3
	s_cselect_b32 s59, s49, s85
	s_cselect_b32 s58, s83, s84
	v_lshl_add_u64 v[202:203], s[56:57], 0, v[140:141]
	s_add_i32 m0, s43, 0xc000
	ds_read_b128 v[190:193], v157
	ds_read_b128 v[194:197], v157 offset:1024
	ds_read_b128 v[198:201], v157 offset:2048
	ds_read_b128 v[208:211], v157 offset:3072
	ds_read_b128 v[212:215], v157 offset:4096
	ds_read_b128 v[216:219], v157 offset:5120
	ds_read_b128 v[220:223], v157 offset:6144
	ds_read_b128 v[224:227], v157 offset:7168
	global_load_lds_dwordx4 v[202:203], off
	v_lshl_add_u64 v[202:203], s[56:57], 0, v[142:143]
	s_add_i32 m0, s43, 0xe000
	s_nop 0
	global_load_lds_dwordx4 v[202:203], off
	s_waitcnt vmcnt(8)
	s_waitcnt lgkmcnt(0)
	s_barrier
; #define PG8_STAGE(bufoff, gbase, voff) do { _Pragma("unroll") for (int _i = 0; _i < 2; ++_i) \
;         __builtin_amdgcn_global_load_lds((const unsigned*)((const char*)(gbase) + (voff)[_i]), (PG8_LAS unsigned*)(lds + (bufoff) + ldsw + _i * 8192), 16, 0, 0); } while (0)
; #define PG8_LDA(dst, b, h) do { _Pragma("unroll") for (int m = 0; m < 4; ++m) _Pragma("unroll") for (int k = 0; k < 2; ++k) dst[m][k] = *(const PG8_LAS bf16x8*)(lds + PG8_SA(b, h) + aoff + m * 2048 + k * 1024); } while (0)
; #define PG8_LDB(dst, b, h) do { _Pragma("unroll") for (int n = 0; n < 2; ++n) _Pragma("unroll") for (int k = 0; k < 2; ++k) dst[n][k] = *(const PG8_LAS bf16x8*)(lds + PG8_SB(b, h) + boff + n * 2048 + k * 1024); } while (0)
; #define PG8_MMA(ai, bj, At, Bt) do { __builtin_amdgcn_s_setprio(1); _Pragma("unroll") for (int m = 0; m < 4; ++m) _Pragma("unroll") for (int n = 0; n < 2; ++n) _Pragma("unroll") for (int k = 0; k < 2; ++k) \
;         acc[ai][bj][m][n] = __builtin_amdgcn_mfma_f32_16x16x32_bf16(Bt[n][k], At[m][k], acc[ai][bj][m][n], 0, 0, 0); __builtin_amdgcn_s_setprio(0); } while (0)
; #define PG8_WAIT_V(n) asm volatile("s_waitcnt vmcnt(" #n ")" ::: "memory")
; #define PG8_WAIT_L(n) asm volatile("s_waitcnt lgkmcnt(" #n ")" ::: "memory")
; #define PG8_BAR __builtin_amdgcn_s_barrier()
; #define PG8_SCHED __builtin_amdgcn_sched_barrier(0)
; template <class Epi, class Sched, bool ALIGN_EPI = false, bool SP2 = false>
; __device__ __forceinline__ void gemm_phase(PG8_LAS unsigned char* lds, const Gemm g, const Sched& S, const Epi& E) {
;     ...
;             PG8_LDB(B0, 0, 0); PG8_LDB(B1, 0, 1); PG8_SCHED; PG8_LDA(At, 0, 0); PG8_STAGE(PG8_SA(1, 1), a1 + hstep, voffA);
;             PG8_WAIT_V(8); PG8_WAIT_L(0); PG8_BAR; PG8_MMA(0, 0, At, B0); PG8_MMA(0, 1, At, B1); PG8_BAR; PG8_SCHED;
;             PG8_LDA(At, 0, 1); PG8_STAGE(PG8_SB(0, 0), b2, voffB); PG8_STAGE(PG8_SB(0, 1), b2 + hstep, voffB); PG8_STAGE(PG8_SA(0, 0), a2, voffA);
;             PG8_WAIT_V(8); PG8_WAIT_L(0); PG8_BAR; PG8_MMA(1, 0, At, B0); PG8_MMA(1, 1, At, B1); PG8_BAR; PG8_SCHED;
	s_setprio 1
	s_waitcnt lgkmcnt(0)
	v_mfma_f32_16x16x32_bf16 v[124:127], v[148:151], v[190:193], v[124:127]
	v_mfma_f32_16x16x32_bf16 v[120:123], v[164:167], v[190:193], v[120:123]
	v_mfma_f32_16x16x32_bf16 v[116:119], v[172:175], v[190:193], v[116:119]
	v_mfma_f32_16x16x32_bf16 v[112:115], v[182:185], v[190:193], v[112:115]
	v_mfma_f32_16x16x32_bf16 v[108:111], v[148:151], v[198:201], v[108:111]
	v_mfma_f32_16x16x32_bf16 v[104:107], v[164:167], v[198:201], v[104:107]
	v_mfma_f32_16x16x32_bf16 v[100:103], v[172:175], v[198:201], v[100:103]
	v_mfma_f32_16x16x32_bf16 v[96:99], v[182:185], v[198:201], v[96:99]
	v_mfma_f32_16x16x32_bf16 v[92:95], v[148:151], v[212:215], v[92:95]
	v_mfma_f32_16x16x32_bf16 v[88:91], v[164:167], v[212:215], v[88:91]
	v_mfma_f32_16x16x32_bf16 v[84:87], v[172:175], v[212:215], v[84:87]
	v_mfma_f32_16x16x32_bf16 v[80:83], v[182:185], v[212:215], v[80:83]
	v_mfma_f32_16x16x32_bf16 v[76:79], v[148:151], v[220:223], v[76:79]
	v_mfma_f32_16x16x32_bf16 v[72:75], v[164:167], v[220:223], v[72:75]
	v_mfma_f32_16x16x32_bf16 v[68:71], v[172:175], v[220:223], v[68:71]
	v_mfma_f32_16x16x32_bf16 v[64:67], v[182:185], v[220:223], v[64:67]
	s_setprio 0
	s_setprio 1
	v_mfma_f32_16x16x32_bf16 v[124:127], v[160:163], v[194:197], v[124:127]
	v_mfma_f32_16x16x32_bf16 v[120:123], v[168:171], v[194:197], v[120:123]
	v_mfma_f32_16x16x32_bf16 v[116:119], v[176:179], v[194:197], v[116:119]
	v_mfma_f32_16x16x32_bf16 v[112:115], v[186:189], v[194:197], v[112:115]
	v_mfma_f32_16x16x32_bf16 v[108:111], v[160:163], v[208:211], v[108:111]
	v_mfma_f32_16x16x32_bf16 v[104:107], v[168:171], v[208:211], v[104:107]
	v_mfma_f32_16x16x32_bf16 v[100:103], v[176:179], v[208:211], v[100:103]
	v_mfma_f32_16x16x32_bf16 v[96:99], v[186:189], v[208:211], v[96:99]
	v_mfma_f32_16x16x32_bf16 v[92:95], v[160:163], v[216:219], v[92:95]
	v_mfma_f32_16x16x32_bf16 v[88:91], v[168:171], v[216:219], v[88:91]
	v_mfma_f32_16x16x32_bf16 v[84:87], v[176:179], v[216:219], v[84:87]
	v_mfma_f32_16x16x32_bf16 v[80:83], v[186:189], v[216:219], v[80:83]
	v_mfma_f32_16x16x32_bf16 v[76:79], v[160:163], v[224:227], v[76:79]
	v_mfma_f32_16x16x32_bf16 v[72:75], v[168:171], v[224:227], v[72:75]
	v_mfma_f32_16x16x32_bf16 v[68:71], v[176:179], v[224:227], v[68:71]
	v_mfma_f32_16x16x32_bf16 v[64:67], v[186:189], v[224:227], v[64:67]
	s_setprio 0
	s_barrier
	s_add_i32 s3, s74, s34
	v_lshl_add_u64 v[202:203], s[58:59], 0, v[136:137]
	s_mov_b32 m0, s3
	ds_read_b128 v[190:193], v157 offset:16384
	ds_read_b128 v[194:197], v157 offset:17408
	ds_read_b128 v[198:201], v157 offset:18432
	ds_read_b128 v[208:211], v157 offset:19456
	ds_read_b128 v[212:215], v157 offset:20480
	ds_read_b128 v[216:219], v157 offset:21504
	ds_read_b128 v[220:223], v157 offset:22528
	ds_read_b128 v[224:227], v157 offset:23552
	global_load_lds_dwordx4 v[202:203], off
	s_add_i32 m0, s3, 0x2000
	s_add_u32 s14, s58, 0x40000
	v_lshl_add_u64 v[228:229], s[58:59], 0, v[132:133]
	s_addc_u32 s15, s59, 0
	s_add_i32 s3, s75, s34
	global_load_lds_dwordx4 v[228:229], off
	v_lshl_add_u64 v[230:231], s[14:15], 0, v[136:137]
	s_mov_b32 m0, s3
	global_load_lds_dwordx4 v[230:231], off
	v_lshl_add_u64 v[230:231], s[14:15], 0, v[132:133]
	s_add_i32 m0, s3, 0x2000
	s_nop 0
	global_load_lds_dwordx4 v[230:231], off
	s_waitcnt vmcnt(6)
	s_waitcnt lgkmcnt(0)
	s_barrier
	s_setprio 1
	s_waitcnt lgkmcnt(0)
	v_mfma_f32_16x16x32_bf16 v[60:63], v[148:151], v[190:193], v[60:63]
	v_mfma_f32_16x16x32_bf16 v[56:59], v[164:167], v[190:193], v[56:59]
	v_mfma_f32_16x16x32_bf16 v[52:55], v[172:175], v[190:193], v[52:55]
	v_mfma_f32_16x16x32_bf16 v[48:51], v[182:185], v[190:193], v[48:51]
	v_mfma_f32_16x16x32_bf16 v[44:47], v[148:151], v[198:201], v[44:47]
	v_mfma_f32_16x16x32_bf16 v[40:43], v[164:167], v[198:201], v[40:43]
	v_mfma_f32_16x16x32_bf16 v[36:39], v[172:175], v[198:201], v[36:39]
	v_mfma_f32_16x16x32_bf16 v[32:35], v[182:185], v[198:201], v[32:35]
	v_mfma_f32_16x16x32_bf16 v[28:31], v[148:151], v[212:215], v[28:31]
	v_mfma_f32_16x16x32_bf16 v[24:27], v[164:167], v[212:215], v[24:27]
	v_mfma_f32_16x16x32_bf16 v[20:23], v[172:175], v[212:215], v[20:23]
	v_mfma_f32_16x16x32_bf16 v[16:19], v[182:185], v[212:215], v[16:19]
	v_mfma_f32_16x16x32_bf16 v[12:15], v[148:151], v[220:223], v[12:15]
	v_mfma_f32_16x16x32_bf16 v[8:11], v[164:167], v[220:223], v[8:11]
	v_lshl_add_u64 v[230:231], s[60:61], 0, v[138:139]
	s_mov_b32 m0, s43
	s_nop 0
	global_load_lds_dwordx4 v[230:231], off
	v_mfma_f32_16x16x32_bf16 v[4:7], v[172:175], v[220:223], v[4:7]
	v_mfma_f32_16x16x32_bf16 v[0:3], v[182:185], v[220:223], v[0:3]
	s_setprio 0
	s_setprio 1
	v_mfma_f32_16x16x32_bf16 v[60:63], v[160:163], v[194:197], v[60:63]
	v_mfma_f32_16x16x32_bf16 v[56:59], v[168:171], v[194:197], v[56:59]
	v_mfma_f32_16x16x32_bf16 v[52:55], v[176:179], v[194:197], v[52:55]
	v_mfma_f32_16x16x32_bf16 v[48:51], v[186:189], v[194:197], v[48:51]
	v_mfma_f32_16x16x32_bf16 v[44:47], v[160:163], v[208:211], v[44:47]
	v_mfma_f32_16x16x32_bf16 v[40:43], v[168:171], v[208:211], v[40:43]
	v_mfma_f32_16x16x32_bf16 v[36:39], v[176:179], v[208:211], v[36:39]
	v_mfma_f32_16x16x32_bf16 v[32:35], v[186:189], v[208:211], v[32:35]
	v_mfma_f32_16x16x32_bf16 v[28:31], v[160:163], v[216:219], v[28:31]
	v_mfma_f32_16x16x32_bf16 v[24:27], v[168:171], v[216:219], v[24:27]
	v_mfma_f32_16x16x32_bf16 v[20:23], v[176:179], v[216:219], v[20:23]
	v_mfma_f32_16x16x32_bf16 v[16:19], v[186:189], v[216:219], v[16:19]
	v_mfma_f32_16x16x32_bf16 v[12:15], v[160:163], v[224:227], v[12:15]
	v_mfma_f32_16x16x32_bf16 v[8:11], v[168:171], v[224:227], v[8:11]
	v_lshl_add_u64 v[232:233], s[60:61], 0, v[134:135]
	s_mov_b32 m0, s62
	s_nop 0
	global_load_lds_dwordx4 v[232:233], off
	v_mfma_f32_16x16x32_bf16 v[4:7], v[176:179], v[224:227], v[4:7]
	v_mfma_f32_16x16x32_bf16 v[0:3], v[186:189], v[224:227], v[0:3]
	s_setprio 0
	s_barrier
; #define PG8_STAGE(bufoff, gbase, voff) do { _Pragma("unroll") for (int _i = 0; _i < 2; ++_i) \
;         __builtin_amdgcn_global_load_lds((const unsigned*)((const char*)(gbase) + (voff)[_i]), (PG8_LAS unsigned*)(lds + (bufoff) + ldsw + _i * 8192), 16, 0, 0); } while (0)
; #define PG8_LDA(dst, b, h) do { _Pragma("unroll") for (int m = 0; m < 4; ++m) _Pragma("unroll") for (int k = 0; k < 2; ++k) dst[m][k] = *(const PG8_LAS bf16x8*)(lds + PG8_SA(b, h) + aoff + m * 2048 + k * 1024); } while (0)
; #define PG8_LDB(dst, b, h) do { _Pragma("unroll") for (int n = 0; n < 2; ++n) _Pragma("unroll") for (int k = 0; k < 2; ++k) dst[n][k] = *(const PG8_LAS bf16x8*)(lds + PG8_SB(b, h) + boff + n * 2048 + k * 1024); } while (0)
; #define PG8_MMA(ai, bj, At, Bt) do { __builtin_amdgcn_s_setprio(1); _Pragma("unroll") for (int m = 0; m < 4; ++m) _Pragma("unroll") for (int n = 0; n < 2; ++n) _Pragma("unroll") for (int k = 0; k < 2; ++k) \
;         acc[ai][bj][m][n] = __builtin_amdgcn_mfma_f32_16x16x32_bf16(Bt[n][k], At[m][k], acc[ai][bj][m][n], 0, 0, 0); __builtin_amdgcn_s_setprio(0); } while (0)
; #define PG8_WAIT_V(n) asm volatile("s_waitcnt vmcnt(" #n ")" ::: "memory")
; #define PG8_WAIT_L(n) asm volatile("s_waitcnt lgkmcnt(" #n ")" ::: "memory")
; #define PG8_BAR __builtin_amdgcn_s_barrier()
; #define PG8_SCHED __builtin_amdgcn_sched_barrier(0)
; template <class Epi, class Sched, bool ALIGN_EPI = false, bool SP2 = false>
; __device__ __forceinline__ void gemm_phase(PG8_LAS unsigned char* lds, const Gemm g, const Sched& S, const Epi& E) {
;     ...
;             PG8_LDB(B0, 1, 0); PG8_LDB(B1, 1, 1); PG8_SCHED; PG8_LDA(At, 1, 0); PG8_STAGE(PG8_SA(0, 1), a2 + hstep, voffA);
;             PG8_WAIT_V(8); PG8_WAIT_L(0); PG8_BAR; PG8_MMA(0, 0, At, B0); PG8_MMA(0, 1, At, B1); PG8_BAR; PG8_SCHED;
	s_add_i32 s3, 0, 0x18000
	v_add_u32_e32 v159, s3, v131
	s_add_i32 s33, 0, 0x1c000
	ds_read_b128 v[148:151], v159
	ds_read_b128 v[160:163], v159 offset:1024
	ds_read_b128 v[164:167], v159 offset:2048
	ds_read_b128 v[168:171], v159 offset:3072
	v_add_u32_e32 v159, s33, v131
	ds_read_b128 v[172:175], v159
	ds_read_b128 v[176:179], v159 offset:1024
	ds_read_b128 v[182:185], v159 offset:2048
	ds_read_b128 v[186:189], v159 offset:3072
	s_add_u32 s14, s60, 0x40000
	s_addc_u32 s15, s61, 0
	s_mov_b32 m0, s63
	v_lshl_add_u64 v[234:235], s[14:15], 0, v[138:139]
	ds_read_b128 v[190:193], v157 offset:32768
	ds_read_b128 v[194:197], v157 offset:33792
	ds_read_b128 v[198:201], v157 offset:34816
	ds_read_b128 v[208:211], v157 offset:35840
	ds_read_b128 v[212:215], v157 offset:36864
	ds_read_b128 v[216:219], v157 offset:37888
	ds_read_b128 v[220:223], v157 offset:38912
	ds_read_b128 v[224:227], v157 offset:39936
	global_load_lds_dwordx4 v[234:235], off
	v_lshl_add_u64 v[234:235], s[14:15], 0, v[134:135]
	s_mov_b32 m0, s64
	s_nop 0
	global_load_lds_dwordx4 v[234:235], off
	s_waitcnt vmcnt(8)
	s_waitcnt lgkmcnt(0)
	s_barrier
	s_setprio 1
	s_waitcnt lgkmcnt(0)
	v_mfma_f32_16x16x32_bf16 v[124:127], v[148:151], v[190:193], v[124:127]
	v_mfma_f32_16x16x32_bf16 v[120:123], v[164:167], v[190:193], v[120:123]
	v_mfma_f32_16x16x32_bf16 v[116:119], v[172:175], v[190:193], v[116:119]
	v_mfma_f32_16x16x32_bf16 v[112:115], v[182:185], v[190:193], v[112:115]
	v_mfma_f32_16x16x32_bf16 v[108:111], v[148:151], v[198:201], v[108:111]
	v_mfma_f32_16x16x32_bf16 v[104:107], v[164:167], v[198:201], v[104:107]
	v_mfma_f32_16x16x32_bf16 v[100:103], v[172:175], v[198:201], v[100:103]
	v_mfma_f32_16x16x32_bf16 v[96:99], v[182:185], v[198:201], v[96:99]
	v_mfma_f32_16x16x32_bf16 v[92:95], v[148:151], v[212:215], v[92:95]
	v_mfma_f32_16x16x32_bf16 v[88:91], v[164:167], v[212:215], v[88:91]
	v_mfma_f32_16x16x32_bf16 v[84:87], v[172:175], v[212:215], v[84:87]
	v_mfma_f32_16x16x32_bf16 v[80:83], v[182:185], v[212:215], v[80:83]
	v_mfma_f32_16x16x32_bf16 v[76:79], v[148:151], v[220:223], v[76:79]
	v_mfma_f32_16x16x32_bf16 v[72:75], v[164:167], v[220:223], v[72:75]
	v_mfma_f32_16x16x32_bf16 v[68:71], v[172:175], v[220:223], v[68:71]
	v_mfma_f32_16x16x32_bf16 v[64:67], v[182:185], v[220:223], v[64:67]
	s_setprio 0
	s_setprio 1
	v_mfma_f32_16x16x32_bf16 v[124:127], v[160:163], v[194:197], v[124:127]
	v_mfma_f32_16x16x32_bf16 v[120:123], v[168:171], v[194:197], v[120:123]
	v_mfma_f32_16x16x32_bf16 v[116:119], v[176:179], v[194:197], v[116:119]
	v_mfma_f32_16x16x32_bf16 v[112:115], v[186:189], v[194:197], v[112:115]
	v_mfma_f32_16x16x32_bf16 v[108:111], v[160:163], v[208:211], v[108:111]
	v_mfma_f32_16x16x32_bf16 v[104:107], v[168:171], v[208:211], v[104:107]
	v_mfma_f32_16x16x32_bf16 v[100:103], v[176:179], v[208:211], v[100:103]
	v_mfma_f32_16x16x32_bf16 v[96:99], v[186:189], v[208:211], v[96:99]
	v_mfma_f32_16x16x32_bf16 v[92:95], v[160:163], v[216:219], v[92:95]
	v_mfma_f32_16x16x32_bf16 v[88:91], v[168:171], v[216:219], v[88:91]
	v_mfma_f32_16x16x32_bf16 v[84:87], v[176:179], v[216:219], v[84:87]
	v_mfma_f32_16x16x32_bf16 v[80:83], v[186:189], v[216:219], v[80:83]
	v_mfma_f32_16x16x32_bf16 v[76:79], v[160:163], v[224:227], v[76:79]
	v_mfma_f32_16x16x32_bf16 v[72:75], v[168:171], v[224:227], v[72:75]
	v_mfma_f32_16x16x32_bf16 v[68:71], v[176:179], v[224:227], v[68:71]
	v_mfma_f32_16x16x32_bf16 v[64:67], v[186:189], v[224:227], v[64:67]
	s_setprio 0
	s_barrier
; #define PG8_STAGE(bufoff, gbase, voff) do { _Pragma("unroll") for (int _i = 0; _i < 2; ++_i) \
;         __builtin_amdgcn_global_load_lds((const unsigned*)((const char*)(gbase) + (voff)[_i]), (PG8_LAS unsigned*)(lds + (bufoff) + ldsw + _i * 8192), 16, 0, 0); } while (0)
; #define PG8_LDA(dst, b, h) do { _Pragma("unroll") for (int m = 0; m < 4; ++m) _Pragma("unroll") for (int k = 0; k < 2; ++k) dst[m][k] = *(const PG8_LAS bf16x8*)(lds + PG8_SA(b, h) + aoff + m * 2048 + k * 1024); } while (0)
; #define PG8_MMA(ai, bj, At, Bt) do { __builtin_amdgcn_s_setprio(1); _Pragma("unroll") for (int m = 0; m < 4; ++m) _Pragma("unroll") for (int n = 0; n < 2; ++n) _Pragma("unroll") for (int k = 0; k < 2; ++k) \
;         acc[ai][bj][m][n] = __builtin_amdgcn_mfma_f32_16x16x32_bf16(Bt[n][k], At[m][k], acc[ai][bj][m][n], 0, 0, 0); __builtin_amdgcn_s_setprio(0); } while (0)
; #define PG8_WAIT_V(n) asm volatile("s_waitcnt vmcnt(" #n ")" ::: "memory")
; #define PG8_WAIT_L(n) asm volatile("s_waitcnt lgkmcnt(" #n ")" ::: "memory")
; #define PG8_BAR __builtin_amdgcn_s_barrier()
; #define PG8_SCHED __builtin_amdgcn_sched_barrier(0)
; template <class Epi, class Sched, bool ALIGN_EPI = false, bool SP2 = false>
; __device__ __forceinline__ void gemm_phase(PG8_LAS unsigned char* lds, const Gemm g, const Sched& S, const Epi& E) {
;     ...
;             PG8_LDA(At, 1, 1); PG8_STAGE(PG8_SB(1, 0), b3, voffB); PG8_STAGE(PG8_SB(1, 1), b3 + hstep, voffB); PG8_STAGE(PG8_SA(1, 0), a3, voffA);
;             PG8_WAIT_V(8); PG8_WAIT_L(0); PG8_BAR; PG8_MMA(1, 0, At, B0); PG8_MMA(1, 1, At, B1); PG8_BAR; PG8_SCHED;
	s_add_i32 s3, s3, s34
	v_lshl_add_u64 v[202:203], v[202:203], 0, s[38:39]
	s_mov_b32 m0, s3
	ds_read_b128 v[190:193], v157 offset:49152
	ds_read_b128 v[194:197], v157 offset:50176
	ds_read_b128 v[198:201], v157 offset:51200
	ds_read_b128 v[208:211], v157 offset:52224
	ds_read_b128 v[212:215], v157 offset:53248
	ds_read_b128 v[216:219], v157 offset:54272
	ds_read_b128 v[220:223], v157 offset:55296
	ds_read_b128 v[224:227], v157 offset:56320
	global_load_lds_dwordx4 v[202:203], off
	s_add_i32 m0, s3, 0x2000
	s_add_u32 s14, s58, 0x40080
	v_lshl_add_u64 v[202:203], v[228:229], 0, s[38:39]
	s_addc_u32 s15, s59, 0
	s_add_i32 s3, s33, s34
	global_load_lds_dwordx4 v[202:203], off
	v_lshl_add_u64 v[202:203], s[14:15], 0, v[136:137]
	s_mov_b32 m0, s3
	s_nop 0
	global_load_lds_dwordx4 v[202:203], off
	v_lshl_add_u64 v[202:203], s[14:15], 0, v[132:133]
	s_add_i32 m0, s3, 0x2000
	s_nop 0
	global_load_lds_dwordx4 v[202:203], off
	s_waitcnt vmcnt(6)
	s_waitcnt lgkmcnt(0)
	s_barrier
	s_setprio 1
	s_waitcnt lgkmcnt(0)
	v_mfma_f32_16x16x32_bf16 v[60:63], v[148:151], v[190:193], v[60:63]
	v_mfma_f32_16x16x32_bf16 v[56:59], v[164:167], v[190:193], v[56:59]
	v_mfma_f32_16x16x32_bf16 v[52:55], v[172:175], v[190:193], v[52:55]
	v_mfma_f32_16x16x32_bf16 v[48:51], v[182:185], v[190:193], v[48:51]
	v_mfma_f32_16x16x32_bf16 v[44:47], v[148:151], v[198:201], v[44:47]
	v_mfma_f32_16x16x32_bf16 v[40:43], v[164:167], v[198:201], v[40:43]
	v_mfma_f32_16x16x32_bf16 v[36:39], v[172:175], v[198:201], v[36:39]
	v_mfma_f32_16x16x32_bf16 v[32:35], v[182:185], v[198:201], v[32:35]
	v_mfma_f32_16x16x32_bf16 v[28:31], v[148:151], v[212:215], v[28:31]
	v_mfma_f32_16x16x32_bf16 v[24:27], v[164:167], v[212:215], v[24:27]
	v_mfma_f32_16x16x32_bf16 v[20:23], v[172:175], v[212:215], v[20:23]
	v_mfma_f32_16x16x32_bf16 v[16:19], v[182:185], v[212:215], v[16:19]
	v_mfma_f32_16x16x32_bf16 v[12:15], v[148:151], v[220:223], v[12:15]
	v_mfma_f32_16x16x32_bf16 v[8:11], v[164:167], v[220:223], v[8:11]
	v_lshl_add_u64 v[202:203], v[230:231], 0, s[38:39]
	s_mov_b32 m0, s66
	s_nop 0
	global_load_lds_dwordx4 v[202:203], off
	v_mfma_f32_16x16x32_bf16 v[4:7], v[172:175], v[220:223], v[4:7]
	v_mfma_f32_16x16x32_bf16 v[0:3], v[182:185], v[220:223], v[0:3]
	s_setprio 0
	s_setprio 1
	v_mfma_f32_16x16x32_bf16 v[60:63], v[160:163], v[194:197], v[60:63]
	v_mfma_f32_16x16x32_bf16 v[56:59], v[168:171], v[194:197], v[56:59]
	v_mfma_f32_16x16x32_bf16 v[52:55], v[176:179], v[194:197], v[52:55]
	v_mfma_f32_16x16x32_bf16 v[48:51], v[186:189], v[194:197], v[48:51]
	v_mfma_f32_16x16x32_bf16 v[44:47], v[160:163], v[208:211], v[44:47]
	v_mfma_f32_16x16x32_bf16 v[40:43], v[168:171], v[208:211], v[40:43]
	v_mfma_f32_16x16x32_bf16 v[36:39], v[176:179], v[208:211], v[36:39]
	v_mfma_f32_16x16x32_bf16 v[32:35], v[186:189], v[208:211], v[32:35]
	v_mfma_f32_16x16x32_bf16 v[28:31], v[160:163], v[216:219], v[28:31]
	v_mfma_f32_16x16x32_bf16 v[24:27], v[168:171], v[216:219], v[24:27]
	v_mfma_f32_16x16x32_bf16 v[20:23], v[176:179], v[216:219], v[20:23]
	v_mfma_f32_16x16x32_bf16 v[16:19], v[186:189], v[216:219], v[16:19]
	v_mfma_f32_16x16x32_bf16 v[12:15], v[160:163], v[224:227], v[12:15]
	v_mfma_f32_16x16x32_bf16 v[8:11], v[168:171], v[224:227], v[8:11]
	v_lshl_add_u64 v[202:203], v[232:233], 0, s[38:39]
	s_mov_b32 m0, s67
	s_nop 0
	global_load_lds_dwordx4 v[202:203], off
	v_mfma_f32_16x16x32_bf16 v[4:7], v[176:179], v[224:227], v[4:7]
	v_mfma_f32_16x16x32_bf16 v[0:3], v[186:189], v[224:227], v[0:3]
	s_setprio 0
	s_barrier
	s_add_i32 s86, s86, 2
	s_add_u32 s56, s56, 0x100
	s_addc_u32 s57, s57, 0
	s_add_u32 s84, s84, 0x100
	s_addc_u32 s85, s85, 0
	s_cmp_gt_u32 s86, 13
	s_cbranch_scc0 .LBB0_738
	s_and_b64 vcc, exec, s[44:45]
	s_cbranch_vccz .LBB0_741
	s_barrier

; #define PG8_STAGE(bufoff, gbase, voff) do { _Pragma("unroll") for (int _i = 0; _i < 2; ++_i) \
;         __builtin_amdgcn_global_load_lds((const unsigned*)((const char*)(gbase) + (voff)[_i]), (PG8_LAS unsigned*)(lds + (bufoff) + ldsw + _i * 8192), 16, 0, 0); } while (0)
; #define PG8_LDA(dst, b, h) do { _Pragma("unroll") for (int m = 0; m < 4; ++m) _Pragma("unroll") for (int k = 0; k < 2; ++k) dst[m][k] = *(const PG8_LAS bf16x8*)(lds + PG8_SA(b, h) + aoff + m * 2048 + k * 1024); } while (0)
; #define PG8_LDB(dst, b, h) do { _Pragma("unroll") for (int n = 0; n < 2; ++n) _Pragma("unroll") for (int k = 0; k < 2; ++k) dst[n][k] = *(const PG8_LAS bf16x8*)(lds + PG8_SB(b, h) + boff + n * 2048 + k * 1024); } while (0)
; #define PG8_WAIT_V(n) asm volatile("s_waitcnt vmcnt(" #n ")" ::: "memory")
; #define PG8_WAIT_L(n) asm volatile("s_waitcnt lgkmcnt(" #n ")" ::: "memory")
; #define PG8_BAR __builtin_amdgcn_s_barrier()
; #define PG8_SCHED __builtin_amdgcn_sched_barrier(0)
; template <class Epi, class Sched, bool ALIGN_EPI = false, bool SP2 = false>
; __device__ __forceinline__ void gemm_phase(PG8_LAS unsigned char* lds, const Gemm g, const Sched& S, const Epi& E) {
;     ...
;         const bool has_next = S.next(ui + 1, nxt);
;         const char* nA = has_next ? (const char*)g.A + (size_t)nxt.pm * tstep : cA; const char* nB = has_next ? (const char*)g.Bt + (size_t)nxt.pn * tstep : cB;
;         for (int t = 0; t < nt; t += 2) {
;             const bool last = (t == nt - 2);
;             const char* a1 = cA + (size_t)(t + 1) * kstep;
;             const char* a2 = last ? nA : cA + (size_t)(t + 2) * kstep; const char* b2 = last ? nB : cB + (size_t)(t + 2) * kstep;
;             const char* a3 = a2 + kstep; const char* b3 = b2 + kstep;
;             if (last && has_next) S.a_ready(nxt);
;             if constexpr (SP2) {
;             PG8_LDB(B0, 0, 0); PG8_LDB(B1, 0, 1); PG8_SCHED; PG8_LDA(At, 0, 0); PG8_STAGE(PG8_SA(1, 1), a1 + hstep, voffA);
;             PG8_WAIT_V(8); PG8_WAIT_L(0); PG8_BAR; PG8_MMA(0, 0, At, B0); PG8_MMA(0, 1, At, B1); PG8_BAR; PG8_SCHED;
;             PG8_LDA(At, 0, 1); PG8_STAGE(PG8_SB(0, 0), b2, voffB); PG8_STAGE(PG8_SB(0, 1), b2 + hstep, voffB); PG8_STAGE(PG8_SA(0, 0), a2, voffA);
;             PG8_WAIT_V(8); PG8_WAIT_L(0); PG8_BAR; PG8_MMA(1, 0, At, B0); PG8_MMA(1, 1, At, B1); PG8_BAR; PG8_SCHED;
.LBB0_872:
	s_ashr_i32 s49, s48, 31
	s_lshl_b64 s[50:51], s[48:49], 18
	s_add_u32 s50, s92, s50
	s_addc_u32 s51, s93, s51
	s_and_b64 s[52:53], s[10:11], exec
	s_cselect_b32 s49, s51, s59
	s_cselect_b32 s55, s50, s58
	s_ashr_i32 s45, s44, 31
	s_lshl_b64 s[52:53], s[44:45], 18
	s_add_u32 s52, s76, s52
	s_addc_u32 s53, s77, s53
	s_and_b64 s[62:63], s[10:11], exec
	s_cselect_b32 s45, s53, s61
	s_cselect_b32 s84, s52, s60
	s_add_u32 s58, s58, 0x20080
	s_addc_u32 s59, s59, 0
	s_add_u32 s85, s60, 0x100
	s_addc_u32 s86, s61, 0
	s_mov_b32 s87, -2
	s_waitcnt lgkmcnt(0)
	ds_read_b128 v[144:147], v151
	ds_read_b128 v[156:159], v151 offset:1024
	ds_read_b128 v[160:163], v151 offset:2048
	ds_read_b128 v[164:167], v151 offset:3072
	ds_read_b128 v[168:171], v152
	ds_read_b128 v[172:175], v152 offset:1024
	ds_read_b128 v[176:179], v152 offset:2048
	ds_read_b128 v[182:185], v152 offset:3072
	s_add_u32 s3, s58, 0xfffe0080
	s_addc_u32 s33, s59, -1
	s_cmp_eq_u32 s87, 4
	s_cselect_b32 s63, s49, s33
	s_cselect_b32 s62, s55, s3
	s_cselect_b32 s61, s45, s86
	s_cselect_b32 s60, s84, s85
	v_lshl_add_u64 v[202:203], s[58:59], 0, v[136:137]
	s_add_i32 m0, s15, 0xc000
	ds_read_b128 v[186:189], v153
	ds_read_b128 v[190:193], v153 offset:1024
	ds_read_b128 v[194:197], v153 offset:2048
	ds_read_b128 v[198:201], v153 offset:3072
	ds_read_b128 v[208:211], v153 offset:4096
	ds_read_b128 v[212:215], v153 offset:5120
	ds_read_b128 v[216:219], v153 offset:6144
	ds_read_b128 v[220:223], v153 offset:7168
	global_load_lds_dwordx4 v[202:203], off
	v_lshl_add_u64 v[202:203], s[58:59], 0, v[138:139]
	s_add_i32 m0, s15, 0xe000
	s_nop 0
	global_load_lds_dwordx4 v[202:203], off
	s_waitcnt vmcnt(8)
	s_waitcnt lgkmcnt(0)
	s_barrier
	s_setprio 1
	s_waitcnt lgkmcnt(0)
	v_mfma_f32_16x16x32_bf16 v[124:127], v[144:147], v[186:189], 0
	v_mfma_f32_16x16x32_bf16 v[120:123], v[160:163], v[186:189], 0
	v_mfma_f32_16x16x32_bf16 v[116:119], v[168:171], v[186:189], 0
	v_mfma_f32_16x16x32_bf16 v[112:115], v[176:179], v[186:189], 0
	v_mfma_f32_16x16x32_bf16 v[108:111], v[144:147], v[194:197], 0
	v_mfma_f32_16x16x32_bf16 v[104:107], v[160:163], v[194:197], 0
	v_mfma_f32_16x16x32_bf16 v[100:103], v[168:171], v[194:197], 0
	v_mfma_f32_16x16x32_bf16 v[96:99], v[176:179], v[194:197], 0
	v_mfma_f32_16x16x32_bf16 v[92:95], v[144:147], v[208:211], 0
	v_mfma_f32_16x16x32_bf16 v[88:91], v[160:163], v[208:211], 0
	v_mfma_f32_16x16x32_bf16 v[84:87], v[168:171], v[208:211], 0
	v_mfma_f32_16x16x32_bf16 v[80:83], v[176:179], v[208:211], 0
	v_mfma_f32_16x16x32_bf16 v[76:79], v[144:147], v[216:219], 0
	v_mfma_f32_16x16x32_bf16 v[72:75], v[160:163], v[216:219], 0
	v_mfma_f32_16x16x32_bf16 v[68:71], v[168:171], v[216:219], 0
	v_mfma_f32_16x16x32_bf16 v[64:67], v[176:179], v[216:219], 0
	s_setprio 0
	s_setprio 1
	v_mfma_f32_16x16x32_bf16 v[124:127], v[156:159], v[190:193], v[124:127]
	v_mfma_f32_16x16x32_bf16 v[120:123], v[164:167], v[190:193], v[120:123]
	v_mfma_f32_16x16x32_bf16 v[116:119], v[172:175], v[190:193], v[116:119]
	v_mfma_f32_16x16x32_bf16 v[112:115], v[182:185], v[190:193], v[112:115]
	v_mfma_f32_16x16x32_bf16 v[108:111], v[156:159], v[198:201], v[108:111]
	v_mfma_f32_16x16x32_bf16 v[104:107], v[164:167], v[198:201], v[104:107]
	v_mfma_f32_16x16x32_bf16 v[100:103], v[172:175], v[198:201], v[100:103]
	v_mfma_f32_16x16x32_bf16 v[96:99], v[182:185], v[198:201], v[96:99]
	v_mfma_f32_16x16x32_bf16 v[92:95], v[156:159], v[212:215], v[92:95]
	v_mfma_f32_16x16x32_bf16 v[88:91], v[164:167], v[212:215], v[88:91]
	v_mfma_f32_16x16x32_bf16 v[84:87], v[172:175], v[212:215], v[84:87]
	v_mfma_f32_16x16x32_bf16 v[80:83], v[182:185], v[212:215], v[80:83]
	v_mfma_f32_16x16x32_bf16 v[76:79], v[156:159], v[220:223], v[76:79]
	v_mfma_f32_16x16x32_bf16 v[72:75], v[164:167], v[220:223], v[72:75]
	v_mfma_f32_16x16x32_bf16 v[68:71], v[172:175], v[220:223], v[68:71]
	v_mfma_f32_16x16x32_bf16 v[64:67], v[182:185], v[220:223], v[64:67]
	s_setprio 0
	s_barrier
	s_add_i32 s3, s74, s14
	v_lshl_add_u64 v[202:203], s[60:61], 0, v[130:131]
	s_mov_b32 m0, s3
	ds_read_b128 v[186:189], v153 offset:16384
	ds_read_b128 v[190:193], v153 offset:17408
	ds_read_b128 v[194:197], v153 offset:18432
	ds_read_b128 v[198:201], v153 offset:19456
	ds_read_b128 v[208:211], v153 offset:20480
	ds_read_b128 v[212:215], v153 offset:21504
	ds_read_b128 v[216:219], v153 offset:22528
	ds_read_b128 v[220:223], v153 offset:23552
	global_load_lds_dwordx4 v[202:203], off
	s_add_i32 m0, s3, 0x2000
	s_add_u32 s78, s60, 0x20000
	v_lshl_add_u64 v[224:225], s[60:61], 0, v[134:135]
	s_addc_u32 s79, s61, 0
	s_add_i32 s3, s75, s14
	global_load_lds_dwordx4 v[224:225], off
	v_lshl_add_u64 v[226:227], s[78:79], 0, v[130:131]
	s_mov_b32 m0, s3
	global_load_lds_dwordx4 v[226:227], off
	v_lshl_add_u64 v[226:227], s[78:79], 0, v[134:135]
	s_add_i32 m0, s3, 0x2000
	s_nop 0
	global_load_lds_dwordx4 v[226:227], off
	s_waitcnt vmcnt(6)
	s_waitcnt lgkmcnt(0)
	s_barrier
; #define PG8_STAGE(bufoff, gbase, voff) do { _Pragma("unroll") for (int _i = 0; _i < 2; ++_i) \
;         __builtin_amdgcn_global_load_lds((const unsigned*)((const char*)(gbase) + (voff)[_i]), (PG8_LAS unsigned*)(lds + (bufoff) + ldsw + _i * 8192), 16, 0, 0); } while (0)
; #define PG8_LDA(dst, b, h) do { _Pragma("unroll") for (int m = 0; m < 4; ++m) _Pragma("unroll") for (int k = 0; k < 2; ++k) dst[m][k] = *(const PG8_LAS bf16x8*)(lds + PG8_SA(b, h) + aoff + m * 2048 + k * 1024); } while (0)
; #define PG8_LDB(dst, b, h) do { _Pragma("unroll") for (int n = 0; n < 2; ++n) _Pragma("unroll") for (int k = 0; k < 2; ++k) dst[n][k] = *(const PG8_LAS bf16x8*)(lds + PG8_SB(b, h) + boff + n * 2048 + k * 1024); } while (0)
; #define PG8_MMA(ai, bj, At, Bt) do { __builtin_amdgcn_s_setprio(1); _Pragma("unroll") for (int m = 0; m < 4; ++m) _Pragma("unroll") for (int n = 0; n < 2; ++n) _Pragma("unroll") for (int k = 0; k < 2; ++k) \
;         acc[ai][bj][m][n] = __builtin_amdgcn_mfma_f32_16x16x32_bf16(Bt[n][k], At[m][k], acc[ai][bj][m][n], 0, 0, 0); __builtin_amdgcn_s_setprio(0); } while (0)
; #define PG8_WAIT_V(n) asm volatile("s_waitcnt vmcnt(" #n ")" ::: "memory")
; #define PG8_WAIT_L(n) asm volatile("s_waitcnt lgkmcnt(" #n ")" ::: "memory")
; #define PG8_BAR __builtin_amdgcn_s_barrier()
; #define PG8_SCHED __builtin_amdgcn_sched_barrier(0)
; template <class Epi, class Sched, bool ALIGN_EPI = false, bool SP2 = false>
; __device__ __forceinline__ void gemm_phase(PG8_LAS unsigned char* lds, const Gemm g, const Sched& S, const Epi& E) {
;     ...
;             PG8_WAIT_V(8); PG8_WAIT_L(0); PG8_BAR; PG8_MMA(0, 0, At, B0); PG8_MMA(0, 1, At, B1); PG8_BAR; PG8_SCHED;
;             PG8_LDA(At, 0, 1); PG8_STAGE(PG8_SB(0, 0), b2, voffB); PG8_STAGE(PG8_SB(0, 1), b2 + hstep, voffB); PG8_STAGE(PG8_SA(0, 0), a2, voffA);
;             PG8_WAIT_V(8); PG8_WAIT_L(0); PG8_BAR; PG8_MMA(1, 0, At, B0); PG8_MMA(1, 1, At, B1); PG8_BAR; PG8_SCHED;
;             PG8_LDB(B0, 1, 0); PG8_LDB(B1, 1, 1); PG8_SCHED; PG8_LDA(At, 1, 0); PG8_STAGE(PG8_SA(0, 1), a2 + hstep, voffA);
;             PG8_WAIT_V(8); PG8_WAIT_L(0); PG8_BAR; PG8_MMA(0, 0, At, B0); PG8_MMA(0, 1, At, B1); PG8_BAR; PG8_SCHED;
	s_setprio 1
	s_waitcnt lgkmcnt(0)
	v_mfma_f32_16x16x32_bf16 v[60:63], v[144:147], v[186:189], 0
	v_mfma_f32_16x16x32_bf16 v[56:59], v[160:163], v[186:189], 0
	v_mfma_f32_16x16x32_bf16 v[52:55], v[168:171], v[186:189], 0
	v_mfma_f32_16x16x32_bf16 v[48:51], v[176:179], v[186:189], 0
	v_mfma_f32_16x16x32_bf16 v[44:47], v[144:147], v[194:197], 0
	v_mfma_f32_16x16x32_bf16 v[40:43], v[160:163], v[194:197], 0
	v_mfma_f32_16x16x32_bf16 v[36:39], v[168:171], v[194:197], 0
	v_mfma_f32_16x16x32_bf16 v[32:35], v[176:179], v[194:197], 0
	v_mfma_f32_16x16x32_bf16 v[28:31], v[144:147], v[208:211], 0
	v_mfma_f32_16x16x32_bf16 v[24:27], v[160:163], v[208:211], 0
	v_mfma_f32_16x16x32_bf16 v[20:23], v[168:171], v[208:211], 0
	v_mfma_f32_16x16x32_bf16 v[16:19], v[176:179], v[208:211], 0
	v_mfma_f32_16x16x32_bf16 v[12:15], v[144:147], v[216:219], 0
	v_mfma_f32_16x16x32_bf16 v[8:11], v[160:163], v[216:219], 0
	v_lshl_add_u64 v[226:227], s[62:63], 0, v[128:129]
	s_mov_b32 m0, s15
	s_nop 0
	global_load_lds_dwordx4 v[226:227], off
	v_mfma_f32_16x16x32_bf16 v[4:7], v[168:171], v[216:219], 0
	v_mfma_f32_16x16x32_bf16 v[0:3], v[176:179], v[216:219], 0
	s_setprio 0
	s_setprio 1
	v_mfma_f32_16x16x32_bf16 v[60:63], v[156:159], v[190:193], v[60:63]
	v_mfma_f32_16x16x32_bf16 v[56:59], v[164:167], v[190:193], v[56:59]
	v_mfma_f32_16x16x32_bf16 v[52:55], v[172:175], v[190:193], v[52:55]
	v_mfma_f32_16x16x32_bf16 v[48:51], v[182:185], v[190:193], v[48:51]
	v_mfma_f32_16x16x32_bf16 v[44:47], v[156:159], v[198:201], v[44:47]
	v_mfma_f32_16x16x32_bf16 v[40:43], v[164:167], v[198:201], v[40:43]
	v_mfma_f32_16x16x32_bf16 v[36:39], v[172:175], v[198:201], v[36:39]
	v_mfma_f32_16x16x32_bf16 v[32:35], v[182:185], v[198:201], v[32:35]
	v_mfma_f32_16x16x32_bf16 v[28:31], v[156:159], v[212:215], v[28:31]
	v_mfma_f32_16x16x32_bf16 v[24:27], v[164:167], v[212:215], v[24:27]
	v_mfma_f32_16x16x32_bf16 v[20:23], v[172:175], v[212:215], v[20:23]
	v_mfma_f32_16x16x32_bf16 v[16:19], v[182:185], v[212:215], v[16:19]
	v_mfma_f32_16x16x32_bf16 v[12:15], v[156:159], v[220:223], v[12:15]
	v_mfma_f32_16x16x32_bf16 v[8:11], v[164:167], v[220:223], v[8:11]
	v_lshl_add_u64 v[228:229], s[62:63], 0, v[132:133]
	s_mov_b32 m0, s34
	s_nop 0
	global_load_lds_dwordx4 v[228:229], off
	v_mfma_f32_16x16x32_bf16 v[4:7], v[172:175], v[220:223], v[4:7]
	v_mfma_f32_16x16x32_bf16 v[0:3], v[182:185], v[220:223], v[0:3]
	s_setprio 0
	s_barrier
	s_add_i32 s3, 0, 0x18000
	v_add_u32_e32 v155, s3, v149
	s_add_i32 s33, 0, 0x1c000
	ds_read_b128 v[144:147], v155
	ds_read_b128 v[156:159], v155 offset:1024
	ds_read_b128 v[160:163], v155 offset:2048
	ds_read_b128 v[164:167], v155 offset:3072
	v_add_u32_e32 v155, s33, v149
	ds_read_b128 v[168:171], v155
	ds_read_b128 v[172:175], v155 offset:1024
	ds_read_b128 v[176:179], v155 offset:2048
	ds_read_b128 v[182:185], v155 offset:3072
	s_add_u32 s62, s62, 0x20000
	s_addc_u32 s63, s63, 0
	s_mov_b32 m0, s57
	v_lshl_add_u64 v[230:231], s[62:63], 0, v[128:129]
	ds_read_b128 v[186:189], v153 offset:32768
	ds_read_b128 v[190:193], v153 offset:33792
	ds_read_b128 v[194:197], v153 offset:34816
	ds_read_b128 v[198:201], v153 offset:35840
	ds_read_b128 v[208:211], v153 offset:36864
	ds_read_b128 v[212:215], v153 offset:37888
	ds_read_b128 v[216:219], v153 offset:38912
	ds_read_b128 v[220:223], v153 offset:39936
	global_load_lds_dwordx4 v[230:231], off
	v_lshl_add_u64 v[230:231], s[62:63], 0, v[132:133]
	s_mov_b32 m0, s64
	s_nop 0
	global_load_lds_dwordx4 v[230:231], off
	s_waitcnt vmcnt(8)
	s_waitcnt lgkmcnt(0)
	s_barrier
	s_setprio 1
	s_waitcnt lgkmcnt(0)
	v_mfma_f32_16x16x32_bf16 v[124:127], v[144:147], v[186:189], v[124:127]
	v_mfma_f32_16x16x32_bf16 v[120:123], v[160:163], v[186:189], v[120:123]
	v_mfma_f32_16x16x32_bf16 v[116:119], v[168:171], v[186:189], v[116:119]
	v_mfma_f32_16x16x32_bf16 v[112:115], v[176:179], v[186:189], v[112:115]
	v_mfma_f32_16x16x32_bf16 v[108:111], v[144:147], v[194:197], v[108:111]
	v_mfma_f32_16x16x32_bf16 v[104:107], v[160:163], v[194:197], v[104:107]
	v_mfma_f32_16x16x32_bf16 v[100:103], v[168:171], v[194:197], v[100:103]
	v_mfma_f32_16x16x32_bf16 v[96:99], v[176:179], v[194:197], v[96:99]
	v_mfma_f32_16x16x32_bf16 v[92:95], v[144:147], v[208:211], v[92:95]
	v_mfma_f32_16x16x32_bf16 v[88:91], v[160:163], v[208:211], v[88:91]
	v_mfma_f32_16x16x32_bf16 v[84:87], v[168:171], v[208:211], v[84:87]
	v_mfma_f32_16x16x32_bf16 v[80:83], v[176:179], v[208:211], v[80:83]
	v_mfma_f32_16x16x32_bf16 v[76:79], v[144:147], v[216:219], v[76:79]
	v_mfma_f32_16x16x32_bf16 v[72:75], v[160:163], v[216:219], v[72:75]
	v_mfma_f32_16x16x32_bf16 v[68:71], v[168:171], v[216:219], v[68:71]
	v_mfma_f32_16x16x32_bf16 v[64:67], v[176:179], v[216:219], v[64:67]
	s_setprio 0
	s_setprio 1
	v_mfma_f32_16x16x32_bf16 v[124:127], v[156:159], v[190:193], v[124:127]
	v_mfma_f32_16x16x32_bf16 v[120:123], v[164:167], v[190:193], v[120:123]
	v_mfma_f32_16x16x32_bf16 v[116:119], v[172:175], v[190:193], v[116:119]
	v_mfma_f32_16x16x32_bf16 v[112:115], v[182:185], v[190:193], v[112:115]
	v_mfma_f32_16x16x32_bf16 v[108:111], v[156:159], v[198:201], v[108:111]
	v_mfma_f32_16x16x32_bf16 v[104:107], v[164:167], v[198:201], v[104:107]
	v_mfma_f32_16x16x32_bf16 v[100:103], v[172:175], v[198:201], v[100:103]
	v_mfma_f32_16x16x32_bf16 v[96:99], v[182:185], v[198:201], v[96:99]
	v_mfma_f32_16x16x32_bf16 v[92:95], v[156:159], v[212:215], v[92:95]
	v_mfma_f32_16x16x32_bf16 v[88:91], v[164:167], v[212:215], v[88:91]
	v_mfma_f32_16x16x32_bf16 v[84:87], v[172:175], v[212:215], v[84:87]
	v_mfma_f32_16x16x32_bf16 v[80:83], v[182:185], v[212:215], v[80:83]
	v_mfma_f32_16x16x32_bf16 v[76:79], v[156:159], v[220:223], v[76:79]
	v_mfma_f32_16x16x32_bf16 v[72:75], v[164:167], v[220:223], v[72:75]
	v_mfma_f32_16x16x32_bf16 v[68:71], v[172:175], v[220:223], v[68:71]
	v_mfma_f32_16x16x32_bf16 v[64:67], v[182:185], v[220:223], v[64:67]
	s_setprio 0
	s_barrier
; #define PG8_STAGE(bufoff, gbase, voff) do { _Pragma("unroll") for (int _i = 0; _i < 2; ++_i) \
;         __builtin_amdgcn_global_load_lds((const unsigned*)((const char*)(gbase) + (voff)[_i]), (PG8_LAS unsigned*)(lds + (bufoff) + ldsw + _i * 8192), 16, 0, 0); } while (0)
; #define PG8_LDA(dst, b, h) do { _Pragma("unroll") for (int m = 0; m < 4; ++m) _Pragma("unroll") for (int k = 0; k < 2; ++k) dst[m][k] = *(const PG8_LAS bf16x8*)(lds + PG8_SA(b, h) + aoff + m * 2048 + k * 1024); } while (0)
; #define PG8_LDB(dst, b, h) do { _Pragma("unroll") for (int n = 0; n < 2; ++n) _Pragma("unroll") for (int k = 0; k < 2; ++k) dst[n][k] = *(const PG8_LAS bf16x8*)(lds + PG8_SB(b, h) + boff + n * 2048 + k * 1024); } while (0)
; #define PG8_MMA(ai, bj, At, Bt) do { __builtin_amdgcn_s_setprio(1); _Pragma("unroll") for (int m = 0; m < 4; ++m) _Pragma("unroll") for (int n = 0; n < 2; ++n) _Pragma("unroll") for (int k = 0; k < 2; ++k) \
;         acc[ai][bj][m][n] = __builtin_amdgcn_mfma_f32_16x16x32_bf16(Bt[n][k], At[m][k], acc[ai][bj][m][n], 0, 0, 0); __builtin_amdgcn_s_setprio(0); } while (0)
; #define PG8_WAIT_V(n) asm volatile("s_waitcnt vmcnt(" #n ")" ::: "memory")
; template <class Epi, class Sched, bool ALIGN_EPI = false, bool SP2 = false>
; __device__ __forceinline__ void gemm_phase(PG8_LAS unsigned char* lds, const Gemm g, const Sched& S, const Epi& E) {
;     ...
;             PG8_LDB(B0, 0, 0); PG8_LDB(B1, 0, 1); PG8_SCHED; PG8_LDA(At, 0, 0); PG8_STAGE(PG8_SA(1, 1), a1 + hstep, voffA);
;             PG8_WAIT_V(8); PG8_WAIT_L(0); PG8_BAR; PG8_MMA(0, 0, At, B0); PG8_MMA(0, 1, At, B1); PG8_BAR; PG8_SCHED;
;             PG8_LDA(At, 0, 1); PG8_STAGE(PG8_SB(0, 0), b2, voffB); PG8_STAGE(PG8_SB(0, 1), b2 + hstep, voffB); PG8_STAGE(PG8_SA(0, 0), a2, voffA);
;             PG8_WAIT_V(8); PG8_WAIT_L(0); PG8_BAR; PG8_MMA(1, 0, At, B0); PG8_MMA(1, 1, At, B1); PG8_BAR; PG8_SCHED;
;             PG8_LDB(B0, 1, 0); PG8_LDB(B1, 1, 1); PG8_SCHED; PG8_LDA(At, 1, 0); PG8_STAGE(PG8_SA(0, 1), a2 + hstep, voffA);
;             PG8_WAIT_V(8); PG8_WAIT_L(0); PG8_BAR; PG8_MMA(0, 0, At, B0); PG8_MMA(0, 1, At, B1); PG8_BAR; PG8_SCHED;
;             PG8_LDA(At, 1, 1); PG8_STAGE(PG8_SB(1, 0), b3, voffB); PG8_STAGE(PG8_SB(1, 1), b3 + hstep, voffB); PG8_STAGE(PG8_SA(1, 0), a3, voffA);
;             PG8_WAIT_V(8); PG8_WAIT_L(0); PG8_BAR; PG8_MMA(1, 0, At, B0); PG8_MMA(1, 1, At, B1); PG8_BAR; PG8_SCHED;
	s_add_i32 s3, s3, s14
	v_lshl_add_u64 v[202:203], v[202:203], 0, s[38:39]
	s_mov_b32 m0, s3
	ds_read_b128 v[186:189], v153 offset:49152
	ds_read_b128 v[190:193], v153 offset:50176
	ds_read_b128 v[194:197], v153 offset:51200
	ds_read_b128 v[198:201], v153 offset:52224
	ds_read_b128 v[208:211], v153 offset:53248
	ds_read_b128 v[212:215], v153 offset:54272
	ds_read_b128 v[216:219], v153 offset:55296
	ds_read_b128 v[220:223], v153 offset:56320
	global_load_lds_dwordx4 v[202:203], off
	s_add_i32 m0, s3, 0x2000
	s_add_u32 s60, s60, 0x20080
	v_lshl_add_u64 v[202:203], v[224:225], 0, s[38:39]
	s_addc_u32 s61, s61, 0
	s_add_i32 s3, s33, s14
	global_load_lds_dwordx4 v[202:203], off
	v_lshl_add_u64 v[202:203], s[60:61], 0, v[130:131]
	s_mov_b32 m0, s3
	s_nop 0
	global_load_lds_dwordx4 v[202:203], off
	v_lshl_add_u64 v[202:203], s[60:61], 0, v[134:135]
	s_add_i32 m0, s3, 0x2000
	s_nop 0
	global_load_lds_dwordx4 v[202:203], off
	s_waitcnt vmcnt(6)
	s_waitcnt lgkmcnt(0)
	s_barrier
	s_setprio 1
	s_waitcnt lgkmcnt(0)
	v_mfma_f32_16x16x32_bf16 v[60:63], v[144:147], v[186:189], v[60:63]
	v_mfma_f32_16x16x32_bf16 v[56:59], v[160:163], v[186:189], v[56:59]
	v_mfma_f32_16x16x32_bf16 v[52:55], v[168:171], v[186:189], v[52:55]
	v_mfma_f32_16x16x32_bf16 v[48:51], v[176:179], v[186:189], v[48:51]
	v_mfma_f32_16x16x32_bf16 v[44:47], v[144:147], v[194:197], v[44:47]
	v_mfma_f32_16x16x32_bf16 v[40:43], v[160:163], v[194:197], v[40:43]
	v_mfma_f32_16x16x32_bf16 v[36:39], v[168:171], v[194:197], v[36:39]
	v_mfma_f32_16x16x32_bf16 v[32:35], v[176:179], v[194:197], v[32:35]
	v_mfma_f32_16x16x32_bf16 v[28:31], v[144:147], v[208:211], v[28:31]
	v_mfma_f32_16x16x32_bf16 v[24:27], v[160:163], v[208:211], v[24:27]
	v_mfma_f32_16x16x32_bf16 v[20:23], v[168:171], v[208:211], v[20:23]
	v_mfma_f32_16x16x32_bf16 v[16:19], v[176:179], v[208:211], v[16:19]
	v_mfma_f32_16x16x32_bf16 v[12:15], v[144:147], v[216:219], v[12:15]
	v_mfma_f32_16x16x32_bf16 v[8:11], v[160:163], v[216:219], v[8:11]
	v_lshl_add_u64 v[202:203], v[226:227], 0, s[38:39]
	s_mov_b32 m0, s66
	s_nop 0
	global_load_lds_dwordx4 v[202:203], off
	v_mfma_f32_16x16x32_bf16 v[4:7], v[168:171], v[216:219], v[4:7]
	v_mfma_f32_16x16x32_bf16 v[0:3], v[176:179], v[216:219], v[0:3]
	s_setprio 0
	s_setprio 1
	v_mfma_f32_16x16x32_bf16 v[60:63], v[156:159], v[190:193], v[60:63]
	v_mfma_f32_16x16x32_bf16 v[56:59], v[164:167], v[190:193], v[56:59]
	v_mfma_f32_16x16x32_bf16 v[52:55], v[172:175], v[190:193], v[52:55]
	v_mfma_f32_16x16x32_bf16 v[48:51], v[182:185], v[190:193], v[48:51]
	v_mfma_f32_16x16x32_bf16 v[44:47], v[156:159], v[198:201], v[44:47]
	v_mfma_f32_16x16x32_bf16 v[40:43], v[164:167], v[198:201], v[40:43]
	v_mfma_f32_16x16x32_bf16 v[36:39], v[172:175], v[198:201], v[36:39]
	v_mfma_f32_16x16x32_bf16 v[32:35], v[182:185], v[198:201], v[32:35]
	v_mfma_f32_16x16x32_bf16 v[28:31], v[156:159], v[212:215], v[28:31]
	v_mfma_f32_16x16x32_bf16 v[24:27], v[164:167], v[212:215], v[24:27]
	v_mfma_f32_16x16x32_bf16 v[20:23], v[172:175], v[212:215], v[20:23]
	v_mfma_f32_16x16x32_bf16 v[16:19], v[182:185], v[212:215], v[16:19]
	v_mfma_f32_16x16x32_bf16 v[12:15], v[156:159], v[220:223], v[12:15]
	v_mfma_f32_16x16x32_bf16 v[8:11], v[164:167], v[220:223], v[8:11]
	v_lshl_add_u64 v[202:203], v[228:229], 0, s[38:39]
	s_mov_b32 m0, s67
	s_nop 0
	global_load_lds_dwordx4 v[202:203], off
	v_mfma_f32_16x16x32_bf16 v[4:7], v[172:175], v[220:223], v[4:7]
	v_mfma_f32_16x16x32_bf16 v[0:3], v[182:185], v[220:223], v[0:3]
	s_setprio 0
	s_barrier
	s_add_i32 s87, s87, 2
	s_add_u32 s58, s58, 0x100
	s_addc_u32 s59, s59, 0
	s_add_u32 s85, s85, 0x100
	s_addc_u32 s86, s86, 0
.LBB0_873:
	ds_read_b128 v[144:147], v151
	ds_read_b128 v[156:159], v151 offset:1024
	ds_read_b128 v[160:163], v151 offset:2048
	ds_read_b128 v[164:167], v151 offset:3072
	ds_read_b128 v[168:171], v152
	ds_read_b128 v[172:175], v152 offset:1024
	ds_read_b128 v[176:179], v152 offset:2048
	ds_read_b128 v[182:185], v152 offset:3072
	s_add_u32 s3, s58, 0xfffe0080
	s_addc_u32 s33, s59, -1
	s_cmp_eq_u32 s87, 4
	s_cselect_b32 s63, s49, s33
	s_cselect_b32 s62, s55, s3
	s_cselect_b32 s61, s45, s86
	s_cselect_b32 s60, s84, s85
	v_lshl_add_u64 v[202:203], s[58:59], 0, v[136:137]
	s_add_i32 m0, s15, 0xc000
	ds_read_b128 v[186:189], v153
	ds_read_b128 v[190:193], v153 offset:1024
	ds_read_b128 v[194:197], v153 offset:2048
	ds_read_b128 v[198:201], v153 offset:3072
	ds_read_b128 v[208:211], v153 offset:4096
	ds_read_b128 v[212:215], v153 offset:5120
	ds_read_b128 v[216:219], v153 offset:6144
	ds_read_b128 v[220:223], v153 offset:7168
	global_load_lds_dwordx4 v[202:203], off
	v_lshl_add_u64 v[202:203], s[58:59], 0, v[138:139]
	s_add_i32 m0, s15, 0xe000
	s_nop 0
	global_load_lds_dwordx4 v[202:203], off
	s_waitcnt vmcnt(8)
	s_waitcnt lgkmcnt(0)
	s_barrier
; #define PG8_STAGE(bufoff, gbase, voff) do { _Pragma("unroll") for (int _i = 0; _i < 2; ++_i) \
;         __builtin_amdgcn_global_load_lds((const unsigned*)((const char*)(gbase) + (voff)[_i]), (PG8_LAS unsigned*)(lds + (bufoff) + ldsw + _i * 8192), 16, 0, 0); } while (0)
; #define PG8_LDA(dst, b, h) do { _Pragma("unroll") for (int m = 0; m < 4; ++m) _Pragma("unroll") for (int k = 0; k < 2; ++k) dst[m][k] = *(const PG8_LAS bf16x8*)(lds + PG8_SA(b, h) + aoff + m * 2048 + k * 1024); } while (0)
; #define PG8_LDB(dst, b, h) do { _Pragma("unroll") for (int n = 0; n < 2; ++n) _Pragma("unroll") for (int k = 0; k < 2; ++k) dst[n][k] = *(const PG8_LAS bf16x8*)(lds + PG8_SB(b, h) + boff + n * 2048 + k * 1024); } while (0)
; #define PG8_MMA(ai, bj, At, Bt) do { __builtin_amdgcn_s_setprio(1); _Pragma("unroll") for (int m = 0; m < 4; ++m) _Pragma("unroll") for (int n = 0; n < 2; ++n) _Pragma("unroll") for (int k = 0; k < 2; ++k) \
;         acc[ai][bj][m][n] = __builtin_amdgcn_mfma_f32_16x16x32_bf16(Bt[n][k], At[m][k], acc[ai][bj][m][n], 0, 0, 0); __builtin_amdgcn_s_setprio(0); } while (0)
; #define PG8_WAIT_V(n) asm volatile("s_waitcnt vmcnt(" #n ")" ::: "memory")
; #define PG8_WAIT_L(n) asm volatile("s_waitcnt lgkmcnt(" #n ")" ::: "memory")
; #define PG8_BAR __builtin_amdgcn_s_barrier()
; #define PG8_SCHED __builtin_amdgcn_sched_barrier(0)
; template <class Epi, class Sched, bool ALIGN_EPI = false, bool SP2 = false>
; __device__ __forceinline__ void gemm_phase(PG8_LAS unsigned char* lds, const Gemm g, const Sched& S, const Epi& E) {
;     ...
;             PG8_LDB(B0, 0, 0); PG8_LDB(B1, 0, 1); PG8_SCHED; PG8_LDA(At, 0, 0); PG8_STAGE(PG8_SA(1, 1), a1 + hstep, voffA);
;             PG8_WAIT_V(8); PG8_WAIT_L(0); PG8_BAR; PG8_MMA(0, 0, At, B0); PG8_MMA(0, 1, At, B1); PG8_BAR; PG8_SCHED;
;             PG8_LDA(At, 0, 1); PG8_STAGE(PG8_SB(0, 0), b2, voffB); PG8_STAGE(PG8_SB(0, 1), b2 + hstep, voffB); PG8_STAGE(PG8_SA(0, 0), a2, voffA);
;             PG8_WAIT_V(8); PG8_WAIT_L(0); PG8_BAR; PG8_MMA(1, 0, At, B0); PG8_MMA(1, 1, At, B1); PG8_BAR; PG8_SCHED;
	s_setprio 1
	s_waitcnt lgkmcnt(0)
	v_mfma_f32_16x16x32_bf16 v[124:127], v[144:147], v[186:189], v[124:127]
	v_mfma_f32_16x16x32_bf16 v[120:123], v[160:163], v[186:189], v[120:123]
	v_mfma_f32_16x16x32_bf16 v[116:119], v[168:171], v[186:189], v[116:119]
	v_mfma_f32_16x16x32_bf16 v[112:115], v[176:179], v[186:189], v[112:115]
	v_mfma_f32_16x16x32_bf16 v[108:111], v[144:147], v[194:197], v[108:111]
	v_mfma_f32_16x16x32_bf16 v[104:107], v[160:163], v[194:197], v[104:107]
	v_mfma_f32_16x16x32_bf16 v[100:103], v[168:171], v[194:197], v[100:103]
	v_mfma_f32_16x16x32_bf16 v[96:99], v[176:179], v[194:197], v[96:99]
	v_mfma_f32_16x16x32_bf16 v[92:95], v[144:147], v[208:211], v[92:95]
	v_mfma_f32_16x16x32_bf16 v[88:91], v[160:163], v[208:211], v[88:91]
	v_mfma_f32_16x16x32_bf16 v[84:87], v[168:171], v[208:211], v[84:87]
	v_mfma_f32_16x16x32_bf16 v[80:83], v[176:179], v[208:211], v[80:83]
	v_mfma_f32_16x16x32_bf16 v[76:79], v[144:147], v[216:219], v[76:79]
	v_mfma_f32_16x16x32_bf16 v[72:75], v[160:163], v[216:219], v[72:75]
	v_mfma_f32_16x16x32_bf16 v[68:71], v[168:171], v[216:219], v[68:71]
	v_mfma_f32_16x16x32_bf16 v[64:67], v[176:179], v[216:219], v[64:67]
	s_setprio 0
	s_setprio 1
	v_mfma_f32_16x16x32_bf16 v[124:127], v[156:159], v[190:193], v[124:127]
	v_mfma_f32_16x16x32_bf16 v[120:123], v[164:167], v[190:193], v[120:123]
	v_mfma_f32_16x16x32_bf16 v[116:119], v[172:175], v[190:193], v[116:119]
	v_mfma_f32_16x16x32_bf16 v[112:115], v[182:185], v[190:193], v[112:115]
	v_mfma_f32_16x16x32_bf16 v[108:111], v[156:159], v[198:201], v[108:111]
	v_mfma_f32_16x16x32_bf16 v[104:107], v[164:167], v[198:201], v[104:107]
	v_mfma_f32_16x16x32_bf16 v[100:103], v[172:175], v[198:201], v[100:103]
	v_mfma_f32_16x16x32_bf16 v[96:99], v[182:185], v[198:201], v[96:99]
	v_mfma_f32_16x16x32_bf16 v[92:95], v[156:159], v[212:215], v[92:95]
	v_mfma_f32_16x16x32_bf16 v[88:91], v[164:167], v[212:215], v[88:91]
	v_mfma_f32_16x16x32_bf16 v[84:87], v[172:175], v[212:215], v[84:87]
	v_mfma_f32_16x16x32_bf16 v[80:83], v[182:185], v[212:215], v[80:83]
	v_mfma_f32_16x16x32_bf16 v[76:79], v[156:159], v[220:223], v[76:79]
	v_mfma_f32_16x16x32_bf16 v[72:75], v[164:167], v[220:223], v[72:75]
	v_mfma_f32_16x16x32_bf16 v[68:71], v[172:175], v[220:223], v[68:71]
	v_mfma_f32_16x16x32_bf16 v[64:67], v[182:185], v[220:223], v[64:67]
	s_setprio 0
	s_barrier
	s_add_i32 s3, s74, s14
	v_lshl_add_u64 v[202:203], s[60:61], 0, v[130:131]
	s_mov_b32 m0, s3
	ds_read_b128 v[186:189], v153 offset:16384
	ds_read_b128 v[190:193], v153 offset:17408
	ds_read_b128 v[194:197], v153 offset:18432
	ds_read_b128 v[198:201], v153 offset:19456
	ds_read_b128 v[208:211], v153 offset:20480
	ds_read_b128 v[212:215], v153 offset:21504
	ds_read_b128 v[216:219], v153 offset:22528
	ds_read_b128 v[220:223], v153 offset:23552
	global_load_lds_dwordx4 v[202:203], off
	s_add_i32 m0, s3, 0x2000
	s_add_u32 s78, s60, 0x20000
	v_lshl_add_u64 v[224:225], s[60:61], 0, v[134:135]
	s_addc_u32 s79, s61, 0
	s_add_i32 s3, s75, s14
	global_load_lds_dwordx4 v[224:225], off
	v_lshl_add_u64 v[226:227], s[78:79], 0, v[130:131]
	s_mov_b32 m0, s3
	global_load_lds_dwordx4 v[226:227], off
	v_lshl_add_u64 v[226:227], s[78:79], 0, v[134:135]
	s_add_i32 m0, s3, 0x2000
	s_nop 0
	global_load_lds_dwordx4 v[226:227], off
	s_waitcnt vmcnt(6)
	s_waitcnt lgkmcnt(0)
	s_barrier
	s_setprio 1
	s_waitcnt lgkmcnt(0)
	v_mfma_f32_16x16x32_bf16 v[60:63], v[144:147], v[186:189], v[60:63]
	v_mfma_f32_16x16x32_bf16 v[56:59], v[160:163], v[186:189], v[56:59]
	v_mfma_f32_16x16x32_bf16 v[52:55], v[168:171], v[186:189], v[52:55]
	v_mfma_f32_16x16x32_bf16 v[48:51], v[176:179], v[186:189], v[48:51]
	v_mfma_f32_16x16x32_bf16 v[44:47], v[144:147], v[194:197], v[44:47]
	v_mfma_f32_16x16x32_bf16 v[40:43], v[160:163], v[194:197], v[40:43]
	v_mfma_f32_16x16x32_bf16 v[36:39], v[168:171], v[194:197], v[36:39]
	v_mfma_f32_16x16x32_bf16 v[32:35], v[176:179], v[194:197], v[32:35]
	v_mfma_f32_16x16x32_bf16 v[28:31], v[144:147], v[208:211], v[28:31]
	v_mfma_f32_16x16x32_bf16 v[24:27], v[160:163], v[208:211], v[24:27]
	v_mfma_f32_16x16x32_bf16 v[20:23], v[168:171], v[208:211], v[20:23]
	v_mfma_f32_16x16x32_bf16 v[16:19], v[176:179], v[208:211], v[16:19]
	v_mfma_f32_16x16x32_bf16 v[12:15], v[144:147], v[216:219], v[12:15]
	v_mfma_f32_16x16x32_bf16 v[8:11], v[160:163], v[216:219], v[8:11]
	v_lshl_add_u64 v[226:227], s[62:63], 0, v[128:129]
	s_mov_b32 m0, s15
	s_nop 0
	global_load_lds_dwordx4 v[226:227], off
	v_mfma_f32_16x16x32_bf16 v[4:7], v[168:171], v[216:219], v[4:7]
	v_mfma_f32_16x16x32_bf16 v[0:3], v[176:179], v[216:219], v[0:3]
	s_setprio 0
	s_setprio 1
	v_mfma_f32_16x16x32_bf16 v[60:63], v[156:159], v[190:193], v[60:63]
	v_mfma_f32_16x16x32_bf16 v[56:59], v[164:167], v[190:193], v[56:59]
	v_mfma_f32_16x16x32_bf16 v[52:55], v[172:175], v[190:193], v[52:55]
	v_mfma_f32_16x16x32_bf16 v[48:51], v[182:185], v[190:193], v[48:51]
	v_mfma_f32_16x16x32_bf16 v[44:47], v[156:159], v[198:201], v[44:47]
	v_mfma_f32_16x16x32_bf16 v[40:43], v[164:167], v[198:201], v[40:43]
	v_mfma_f32_16x16x32_bf16 v[36:39], v[172:175], v[198:201], v[36:39]
	v_mfma_f32_16x16x32_bf16 v[32:35], v[182:185], v[198:201], v[32:35]
	v_mfma_f32_16x16x32_bf16 v[28:31], v[156:159], v[212:215], v[28:31]
	v_mfma_f32_16x16x32_bf16 v[24:27], v[164:167], v[212:215], v[24:27]
	v_mfma_f32_16x16x32_bf16 v[20:23], v[172:175], v[212:215], v[20:23]
	v_mfma_f32_16x16x32_bf16 v[16:19], v[182:185], v[212:215], v[16:19]
	v_mfma_f32_16x16x32_bf16 v[12:15], v[156:159], v[220:223], v[12:15]
	v_mfma_f32_16x16x32_bf16 v[8:11], v[164:167], v[220:223], v[8:11]
	v_lshl_add_u64 v[228:229], s[62:63], 0, v[132:133]
	s_mov_b32 m0, s34
	s_nop 0
	global_load_lds_dwordx4 v[228:229], off
	v_mfma_f32_16x16x32_bf16 v[4:7], v[172:175], v[220:223], v[4:7]
	v_mfma_f32_16x16x32_bf16 v[0:3], v[182:185], v[220:223], v[0:3]
	s_setprio 0
	s_barrier
; #define PG8_STAGE(bufoff, gbase, voff) do { _Pragma("unroll") for (int _i = 0; _i < 2; ++_i) \
;         __builtin_amdgcn_global_load_lds((const unsigned*)((const char*)(gbase) + (voff)[_i]), (PG8_LAS unsigned*)(lds + (bufoff) + ldsw + _i * 8192), 16, 0, 0); } while (0)
; #define PG8_LDA(dst, b, h) do { _Pragma("unroll") for (int m = 0; m < 4; ++m) _Pragma("unroll") for (int k = 0; k < 2; ++k) dst[m][k] = *(const PG8_LAS bf16x8*)(lds + PG8_SA(b, h) + aoff + m * 2048 + k * 1024); } while (0)
; #define PG8_LDB(dst, b, h) do { _Pragma("unroll") for (int n = 0; n < 2; ++n) _Pragma("unroll") for (int k = 0; k < 2; ++k) dst[n][k] = *(const PG8_LAS bf16x8*)(lds + PG8_SB(b, h) + boff + n * 2048 + k * 1024); } while (0)
; #define PG8_MMA(ai, bj, At, Bt) do { __builtin_amdgcn_s_setprio(1); _Pragma("unroll") for (int m = 0; m < 4; ++m) _Pragma("unroll") for (int n = 0; n < 2; ++n) _Pragma("unroll") for (int k = 0; k < 2; ++k) \
;         acc[ai][bj][m][n] = __builtin_amdgcn_mfma_f32_16x16x32_bf16(Bt[n][k], At[m][k], acc[ai][bj][m][n], 0, 0, 0); __builtin_amdgcn_s_setprio(0); } while (0)
; #define PG8_WAIT_V(n) asm volatile("s_waitcnt vmcnt(" #n ")" ::: "memory")
; #define PG8_WAIT_L(n) asm volatile("s_waitcnt lgkmcnt(" #n ")" ::: "memory")
; #define PG8_BAR __builtin_amdgcn_s_barrier()
; #define PG8_SCHED __builtin_amdgcn_sched_barrier(0)
; template <class Epi, class Sched, bool ALIGN_EPI = false, bool SP2 = false>
; __device__ __forceinline__ void gemm_phase(PG8_LAS unsigned char* lds, const Gemm g, const Sched& S, const Epi& E) {
;     ...
;             PG8_LDB(B0, 1, 0); PG8_LDB(B1, 1, 1); PG8_SCHED; PG8_LDA(At, 1, 0); PG8_STAGE(PG8_SA(0, 1), a2 + hstep, voffA);
;             PG8_WAIT_V(8); PG8_WAIT_L(0); PG8_BAR; PG8_MMA(0, 0, At, B0); PG8_MMA(0, 1, At, B1); PG8_BAR; PG8_SCHED;
	s_add_i32 s3, 0, 0x18000
	v_add_u32_e32 v155, s3, v149
	s_add_i32 s33, 0, 0x1c000
	ds_read_b128 v[144:147], v155
	ds_read_b128 v[156:159], v155 offset:1024
	ds_read_b128 v[160:163], v155 offset:2048
	ds_read_b128 v[164:167], v155 offset:3072
	v_add_u32_e32 v155, s33, v149
	ds_read_b128 v[168:171], v155
	ds_read_b128 v[172:175], v155 offset:1024
	ds_read_b128 v[176:179], v155 offset:2048
	ds_read_b128 v[182:185], v155 offset:3072
	s_add_u32 s62, s62, 0x20000
	s_addc_u32 s63, s63, 0
	s_mov_b32 m0, s57
	v_lshl_add_u64 v[230:231], s[62:63], 0, v[128:129]
	ds_read_b128 v[186:189], v153 offset:32768
	ds_read_b128 v[190:193], v153 offset:33792
	ds_read_b128 v[194:197], v153 offset:34816
	ds_read_b128 v[198:201], v153 offset:35840
	ds_read_b128 v[208:211], v153 offset:36864
	ds_read_b128 v[212:215], v153 offset:37888
	ds_read_b128 v[216:219], v153 offset:38912
	ds_read_b128 v[220:223], v153 offset:39936
	global_load_lds_dwordx4 v[230:231], off
	v_lshl_add_u64 v[230:231], s[62:63], 0, v[132:133]
	s_mov_b32 m0, s64
	s_nop 0
	global_load_lds_dwordx4 v[230:231], off
	s_waitcnt vmcnt(8)
	s_waitcnt lgkmcnt(0)
	s_barrier
	s_setprio 1
	s_waitcnt lgkmcnt(0)
	v_mfma_f32_16x16x32_bf16 v[124:127], v[144:147], v[186:189], v[124:127]
	v_mfma_f32_16x16x32_bf16 v[120:123], v[160:163], v[186:189], v[120:123]
	v_mfma_f32_16x16x32_bf16 v[116:119], v[168:171], v[186:189], v[116:119]
	v_mfma_f32_16x16x32_bf16 v[112:115], v[176:179], v[186:189], v[112:115]
	v_mfma_f32_16x16x32_bf16 v[108:111], v[144:147], v[194:197], v[108:111]
	v_mfma_f32_16x16x32_bf16 v[104:107], v[160:163], v[194:197], v[104:107]
	v_mfma_f32_16x16x32_bf16 v[100:103], v[168:171], v[194:197], v[100:103]
	v_mfma_f32_16x16x32_bf16 v[96:99], v[176:179], v[194:197], v[96:99]
	v_mfma_f32_16x16x32_bf16 v[92:95], v[144:147], v[208:211], v[92:95]
	v_mfma_f32_16x16x32_bf16 v[88:91], v[160:163], v[208:211], v[88:91]
	v_mfma_f32_16x16x32_bf16 v[84:87], v[168:171], v[208:211], v[84:87]
	v_mfma_f32_16x16x32_bf16 v[80:83], v[176:179], v[208:211], v[80:83]
	v_mfma_f32_16x16x32_bf16 v[76:79], v[144:147], v[216:219], v[76:79]
	v_mfma_f32_16x16x32_bf16 v[72:75], v[160:163], v[216:219], v[72:75]
	v_mfma_f32_16x16x32_bf16 v[68:71], v[168:171], v[216:219], v[68:71]
	v_mfma_f32_16x16x32_bf16 v[64:67], v[176:179], v[216:219], v[64:67]
	s_setprio 0
	s_setprio 1
	v_mfma_f32_16x16x32_bf16 v[124:127], v[156:159], v[190:193], v[124:127]
	v_mfma_f32_16x16x32_bf16 v[120:123], v[164:167], v[190:193], v[120:123]
	v_mfma_f32_16x16x32_bf16 v[116:119], v[172:175], v[190:193], v[116:119]
	v_mfma_f32_16x16x32_bf16 v[112:115], v[182:185], v[190:193], v[112:115]
	v_mfma_f32_16x16x32_bf16 v[108:111], v[156:159], v[198:201], v[108:111]
	v_mfma_f32_16x16x32_bf16 v[104:107], v[164:167], v[198:201], v[104:107]
	v_mfma_f32_16x16x32_bf16 v[100:103], v[172:175], v[198:201], v[100:103]
	v_mfma_f32_16x16x32_bf16 v[96:99], v[182:185], v[198:201], v[96:99]
	v_mfma_f32_16x16x32_bf16 v[92:95], v[156:159], v[212:215], v[92:95]
	v_mfma_f32_16x16x32_bf16 v[88:91], v[164:167], v[212:215], v[88:91]
	v_mfma_f32_16x16x32_bf16 v[84:87], v[172:175], v[212:215], v[84:87]
	v_mfma_f32_16x16x32_bf16 v[80:83], v[182:185], v[212:215], v[80:83]
	v_mfma_f32_16x16x32_bf16 v[76:79], v[156:159], v[220:223], v[76:79]
	v_mfma_f32_16x16x32_bf16 v[72:75], v[164:167], v[220:223], v[72:75]
	v_mfma_f32_16x16x32_bf16 v[68:71], v[172:175], v[220:223], v[68:71]
	v_mfma_f32_16x16x32_bf16 v[64:67], v[182:185], v[220:223], v[64:67]
	s_setprio 0
	s_barrier
; #define PG8_STAGE(bufoff, gbase, voff) do { _Pragma("unroll") for (int _i = 0; _i < 2; ++_i) \
;         __builtin_amdgcn_global_load_lds((const unsigned*)((const char*)(gbase) + (voff)[_i]), (PG8_LAS unsigned*)(lds + (bufoff) + ldsw + _i * 8192), 16, 0, 0); } while (0)
; #define PG8_LDA(dst, b, h) do { _Pragma("unroll") for (int m = 0; m < 4; ++m) _Pragma("unroll") for (int k = 0; k < 2; ++k) dst[m][k] = *(const PG8_LAS bf16x8*)(lds + PG8_SA(b, h) + aoff + m * 2048 + k * 1024); } while (0)
; #define PG8_MMA(ai, bj, At, Bt) do { __builtin_amdgcn_s_setprio(1); _Pragma("unroll") for (int m = 0; m < 4; ++m) _Pragma("unroll") for (int n = 0; n < 2; ++n) _Pragma("unroll") for (int k = 0; k < 2; ++k) \
;         acc[ai][bj][m][n] = __builtin_amdgcn_mfma_f32_16x16x32_bf16(Bt[n][k], At[m][k], acc[ai][bj][m][n], 0, 0, 0); __builtin_amdgcn_s_setprio(0); } while (0)
; #define PG8_WAIT_V(n) asm volatile("s_waitcnt vmcnt(" #n ")" ::: "memory")
; #define PG8_WAIT_L(n) asm volatile("s_waitcnt lgkmcnt(" #n ")" ::: "memory")
; #define PG8_BAR __builtin_amdgcn_s_barrier()
; #define PG8_SCHED __builtin_amdgcn_sched_barrier(0)
; template <class Epi, class Sched, bool ALIGN_EPI = false, bool SP2 = false>
; __device__ __forceinline__ void gemm_phase(PG8_LAS unsigned char* lds, const Gemm g, const Sched& S, const Epi& E) {
;     ...
;             PG8_LDA(At, 1, 1); PG8_STAGE(PG8_SB(1, 0), b3, voffB); PG8_STAGE(PG8_SB(1, 1), b3 + hstep, voffB); PG8_STAGE(PG8_SA(1, 0), a3, voffA);
;             PG8_WAIT_V(8); PG8_WAIT_L(0); PG8_BAR; PG8_MMA(1, 0, At, B0); PG8_MMA(1, 1, At, B1); PG8_BAR; PG8_SCHED;
	s_add_i32 s3, s3, s14
	v_lshl_add_u64 v[202:203], v[202:203], 0, s[38:39]
	s_mov_b32 m0, s3
	ds_read_b128 v[186:189], v153 offset:49152
	ds_read_b128 v[190:193], v153 offset:50176
	ds_read_b128 v[194:197], v153 offset:51200
	ds_read_b128 v[198:201], v153 offset:52224
	ds_read_b128 v[208:211], v153 offset:53248
	ds_read_b128 v[212:215], v153 offset:54272
	ds_read_b128 v[216:219], v153 offset:55296
	ds_read_b128 v[220:223], v153 offset:56320
	global_load_lds_dwordx4 v[202:203], off
	s_add_i32 m0, s3, 0x2000
	s_add_u32 s60, s60, 0x20080
	v_lshl_add_u64 v[202:203], v[224:225], 0, s[38:39]
	s_addc_u32 s61, s61, 0
	s_add_i32 s3, s33, s14
	global_load_lds_dwordx4 v[202:203], off
	v_lshl_add_u64 v[202:203], s[60:61], 0, v[130:131]
	s_mov_b32 m0, s3
	s_nop 0
	global_load_lds_dwordx4 v[202:203], off
	v_lshl_add_u64 v[202:203], s[60:61], 0, v[134:135]
	s_add_i32 m0, s3, 0x2000
	s_nop 0
	global_load_lds_dwordx4 v[202:203], off
	s_waitcnt vmcnt(6)
	s_waitcnt lgkmcnt(0)
	s_barrier
	s_setprio 1
	s_waitcnt lgkmcnt(0)
	v_mfma_f32_16x16x32_bf16 v[60:63], v[144:147], v[186:189], v[60:63]
	v_mfma_f32_16x16x32_bf16 v[56:59], v[160:163], v[186:189], v[56:59]
	v_mfma_f32_16x16x32_bf16 v[52:55], v[168:171], v[186:189], v[52:55]
	v_mfma_f32_16x16x32_bf16 v[48:51], v[176:179], v[186:189], v[48:51]
	v_mfma_f32_16x16x32_bf16 v[44:47], v[144:147], v[194:197], v[44:47]
	v_mfma_f32_16x16x32_bf16 v[40:43], v[160:163], v[194:197], v[40:43]
	v_mfma_f32_16x16x32_bf16 v[36:39], v[168:171], v[194:197], v[36:39]
	v_mfma_f32_16x16x32_bf16 v[32:35], v[176:179], v[194:197], v[32:35]
	v_mfma_f32_16x16x32_bf16 v[28:31], v[144:147], v[208:211], v[28:31]
	v_mfma_f32_16x16x32_bf16 v[24:27], v[160:163], v[208:211], v[24:27]
	v_mfma_f32_16x16x32_bf16 v[20:23], v[168:171], v[208:211], v[20:23]
	v_mfma_f32_16x16x32_bf16 v[16:19], v[176:179], v[208:211], v[16:19]
	v_mfma_f32_16x16x32_bf16 v[12:15], v[144:147], v[216:219], v[12:15]
	v_mfma_f32_16x16x32_bf16 v[8:11], v[160:163], v[216:219], v[8:11]
	v_lshl_add_u64 v[202:203], v[226:227], 0, s[38:39]
	s_mov_b32 m0, s66
	s_nop 0
	global_load_lds_dwordx4 v[202:203], off
	v_mfma_f32_16x16x32_bf16 v[4:7], v[168:171], v[216:219], v[4:7]
	v_mfma_f32_16x16x32_bf16 v[0:3], v[176:179], v[216:219], v[0:3]
	s_setprio 0
	s_setprio 1
	v_mfma_f32_16x16x32_bf16 v[60:63], v[156:159], v[190:193], v[60:63]
	v_mfma_f32_16x16x32_bf16 v[56:59], v[164:167], v[190:193], v[56:59]
	v_mfma_f32_16x16x32_bf16 v[52:55], v[172:175], v[190:193], v[52:55]
	v_mfma_f32_16x16x32_bf16 v[48:51], v[182:185], v[190:193], v[48:51]
	v_mfma_f32_16x16x32_bf16 v[44:47], v[156:159], v[198:201], v[44:47]
	v_mfma_f32_16x16x32_bf16 v[40:43], v[164:167], v[198:201], v[40:43]
	v_mfma_f32_16x16x32_bf16 v[36:39], v[172:175], v[198:201], v[36:39]
	v_mfma_f32_16x16x32_bf16 v[32:35], v[182:185], v[198:201], v[32:35]
	v_mfma_f32_16x16x32_bf16 v[28:31], v[156:159], v[212:215], v[28:31]
	v_mfma_f32_16x16x32_bf16 v[24:27], v[164:167], v[212:215], v[24:27]
	v_mfma_f32_16x16x32_bf16 v[20:23], v[172:175], v[212:215], v[20:23]
	v_mfma_f32_16x16x32_bf16 v[16:19], v[182:185], v[212:215], v[16:19]
	v_mfma_f32_16x16x32_bf16 v[12:15], v[156:159], v[220:223], v[12:15]
	v_mfma_f32_16x16x32_bf16 v[8:11], v[164:167], v[220:223], v[8:11]
	v_lshl_add_u64 v[202:203], v[228:229], 0, s[38:39]
	s_mov_b32 m0, s67
	s_nop 0
	global_load_lds_dwordx4 v[202:203], off
	v_mfma_f32_16x16x32_bf16 v[4:7], v[172:175], v[220:223], v[4:7]
	v_mfma_f32_16x16x32_bf16 v[0:3], v[182:185], v[220:223], v[0:3]
	s_setprio 0
	s_barrier
	s_add_i32 s87, s87, 2
	s_add_u32 s58, s58, 0x100
	s_addc_u32 s59, s59, 0
	s_add_u32 s85, s85, 0x100
	s_addc_u32 s86, s86, 0
	s_cmp_gt_u32 s87, 5
	s_cbranch_scc0 .LBB0_873
	s_and_b64 vcc, exec, s[42:43]
	s_cbranch_vccz .LBB0_876
	s_barrier

; #define PG8_STAGE(bufoff, gbase, voff) do { _Pragma("unroll") for (int _i = 0; _i < 2; ++_i) \
;         __builtin_amdgcn_global_load_lds((const unsigned*)((const char*)(gbase) + (voff)[_i]), (PG8_LAS unsigned*)(lds + (bufoff) + ldsw + _i * 8192), 16, 0, 0); } while (0)
; #define PG8_LDA(dst, b, h) do { _Pragma("unroll") for (int m = 0; m < 4; ++m) _Pragma("unroll") for (int k = 0; k < 2; ++k) dst[m][k] = *(const PG8_LAS bf16x8*)(lds + PG8_SA(b, h) + aoff + m * 2048 + k * 1024); } while (0)
; #define PG8_LDB(dst, b, h) do { _Pragma("unroll") for (int n = 0; n < 2; ++n) _Pragma("unroll") for (int k = 0; k < 2; ++k) dst[n][k] = *(const PG8_LAS bf16x8*)(lds + PG8_SB(b, h) + boff + n * 2048 + k * 1024); } while (0)
; #define PG8_WAIT_V(n) asm volatile("s_waitcnt vmcnt(" #n ")" ::: "memory")
; #define PG8_WAIT_L(n) asm volatile("s_waitcnt lgkmcnt(" #n ")" ::: "memory")
; #define PG8_BAR __builtin_amdgcn_s_barrier()
; #define PG8_SCHED __builtin_amdgcn_sched_barrier(0)
; template <class Epi, class Sched, bool ALIGN_EPI = false, bool SP2 = false>
; __device__ __forceinline__ void gemm_phase(PG8_LAS unsigned char* lds, const Gemm g, const Sched& S, const Epi& E) {
;     ...
;         const bool has_next = S.next(ui + 1, nxt);
;         const char* nA = has_next ? (const char*)g.A + (size_t)nxt.pm * tstep : cA; const char* nB = has_next ? (const char*)g.Bt + (size_t)nxt.pn * tstep : cB;
;         for (int t = 0; t < nt; t += 2) {
;             const bool last = (t == nt - 2);
;             const char* a1 = cA + (size_t)(t + 1) * kstep;
;             const char* a2 = last ? nA : cA + (size_t)(t + 2) * kstep; const char* b2 = last ? nB : cB + (size_t)(t + 2) * kstep;
;             const char* a3 = a2 + kstep; const char* b3 = b2 + kstep;
;             if (last && has_next) S.a_ready(nxt);
;             if constexpr (SP2) {
;             PG8_LDB(B0, 0, 0); PG8_LDB(B1, 0, 1); PG8_SCHED; PG8_LDA(At, 0, 0); PG8_STAGE(PG8_SA(1, 1), a1 + hstep, voffA);
;             PG8_WAIT_V(8); PG8_WAIT_L(0); PG8_BAR; PG8_MMA(0, 0, At, B0); PG8_MMA(0, 1, At, B1); PG8_BAR; PG8_SCHED;
;             PG8_LDA(At, 0, 1); PG8_STAGE(PG8_SB(0, 0), b2, voffB); PG8_STAGE(PG8_SB(0, 1), b2 + hstep, voffB); PG8_STAGE(PG8_SA(0, 0), a2, voffA);
;             PG8_WAIT_V(8); PG8_WAIT_L(0); PG8_BAR; PG8_MMA(1, 0, At, B0); PG8_MMA(1, 1, At, B1); PG8_BAR; PG8_SCHED;
.LBB0_956:
	s_ashr_i32 s45, s44, 31
	s_lshl_b64 s[48:49], s[44:45], 19
	s_add_u32 s48, s22, s48
	s_addc_u32 s49, s23, s49
	s_and_b64 s[50:51], s[10:11], exec
	s_cselect_b32 s45, s49, s55
	s_cselect_b32 s75, s48, s54
	s_ashr_i32 s43, s42, 31
	s_lshl_b64 s[50:51], s[42:43], 19
	v_readlane_b32 s3, v250, 18
	s_add_u32 s50, s3, s50
	v_readlane_b32 s3, v250, 19
	s_addc_u32 s51, s3, s51
	s_and_b64 s[58:59], s[10:11], exec
	s_cselect_b32 s43, s51, s57
	s_cselect_b32 s76, s50, s56
	s_add_u32 s54, s54, 0x40080
	s_addc_u32 s55, s55, 0
	s_add_u32 s77, s56, 0x100
	s_addc_u32 s82, s57, 0
	s_mov_b32 s83, -2
	ds_read_b128 v[144:147], v155
	ds_read_b128 v[148:151], v155 offset:1024
	ds_read_b128 v[160:163], v155 offset:2048
	ds_read_b128 v[164:167], v155 offset:3072
	ds_read_b128 v[168:171], v156
	ds_read_b128 v[172:175], v156 offset:1024
	ds_read_b128 v[176:179], v156 offset:2048
	ds_read_b128 v[182:185], v156 offset:3072
	s_add_u32 s3, s54, 0xfffc0080
	s_addc_u32 s33, s55, -1
	s_cmp_eq_u32 s83, 12
	s_cselect_b32 s59, s45, s33
	s_cselect_b32 s58, s75, s3
	s_cselect_b32 s57, s43, s82
	s_cselect_b32 s56, s76, s77
	v_lshl_add_u64 v[202:203], s[54:55], 0, v[136:137]
	s_add_i32 m0, s34, 0xc000
	ds_read_b128 v[186:189], v157
	ds_read_b128 v[190:193], v157 offset:1024
	ds_read_b128 v[194:197], v157 offset:2048
	ds_read_b128 v[198:201], v157 offset:3072
	ds_read_b128 v[208:211], v157 offset:4096
	ds_read_b128 v[212:215], v157 offset:5120
	ds_read_b128 v[216:219], v157 offset:6144
	ds_read_b128 v[220:223], v157 offset:7168
	global_load_lds_dwordx4 v[202:203], off
	v_lshl_add_u64 v[202:203], s[54:55], 0, v[138:139]
	s_add_i32 m0, s34, 0xe000
	s_nop 0
	global_load_lds_dwordx4 v[202:203], off
	s_waitcnt vmcnt(8)
	s_waitcnt lgkmcnt(0)
	s_barrier
	s_setprio 1
	s_waitcnt lgkmcnt(0)
	v_mfma_f32_16x16x32_bf16 v[124:127], v[144:147], v[186:189], 0
	v_mfma_f32_16x16x32_bf16 v[120:123], v[160:163], v[186:189], 0
	v_mfma_f32_16x16x32_bf16 v[116:119], v[168:171], v[186:189], 0
	v_mfma_f32_16x16x32_bf16 v[112:115], v[176:179], v[186:189], 0
	v_mfma_f32_16x16x32_bf16 v[108:111], v[144:147], v[194:197], 0
	v_mfma_f32_16x16x32_bf16 v[104:107], v[160:163], v[194:197], 0
	v_mfma_f32_16x16x32_bf16 v[100:103], v[168:171], v[194:197], 0
	v_mfma_f32_16x16x32_bf16 v[96:99], v[176:179], v[194:197], 0
	v_mfma_f32_16x16x32_bf16 v[92:95], v[144:147], v[208:211], 0
	v_mfma_f32_16x16x32_bf16 v[88:91], v[160:163], v[208:211], 0
	v_mfma_f32_16x16x32_bf16 v[84:87], v[168:171], v[208:211], 0
	v_mfma_f32_16x16x32_bf16 v[80:83], v[176:179], v[208:211], 0
	v_mfma_f32_16x16x32_bf16 v[76:79], v[144:147], v[216:219], 0
	v_mfma_f32_16x16x32_bf16 v[72:75], v[160:163], v[216:219], 0
	v_mfma_f32_16x16x32_bf16 v[68:71], v[168:171], v[216:219], 0
	v_mfma_f32_16x16x32_bf16 v[64:67], v[176:179], v[216:219], 0
	s_setprio 0
	s_setprio 1
	v_mfma_f32_16x16x32_bf16 v[124:127], v[148:151], v[190:193], v[124:127]
	v_mfma_f32_16x16x32_bf16 v[120:123], v[164:167], v[190:193], v[120:123]
	v_mfma_f32_16x16x32_bf16 v[116:119], v[172:175], v[190:193], v[116:119]
	v_mfma_f32_16x16x32_bf16 v[112:115], v[182:185], v[190:193], v[112:115]
	v_mfma_f32_16x16x32_bf16 v[108:111], v[148:151], v[198:201], v[108:111]
	v_mfma_f32_16x16x32_bf16 v[104:107], v[164:167], v[198:201], v[104:107]
	v_mfma_f32_16x16x32_bf16 v[100:103], v[172:175], v[198:201], v[100:103]
	v_mfma_f32_16x16x32_bf16 v[96:99], v[182:185], v[198:201], v[96:99]
	v_mfma_f32_16x16x32_bf16 v[92:95], v[148:151], v[212:215], v[92:95]
	v_mfma_f32_16x16x32_bf16 v[88:91], v[164:167], v[212:215], v[88:91]
	v_mfma_f32_16x16x32_bf16 v[84:87], v[172:175], v[212:215], v[84:87]
	v_mfma_f32_16x16x32_bf16 v[80:83], v[182:185], v[212:215], v[80:83]
	v_mfma_f32_16x16x32_bf16 v[76:79], v[148:151], v[220:223], v[76:79]
	v_mfma_f32_16x16x32_bf16 v[72:75], v[164:167], v[220:223], v[72:75]
	v_mfma_f32_16x16x32_bf16 v[68:71], v[172:175], v[220:223], v[68:71]
	v_mfma_f32_16x16x32_bf16 v[64:67], v[182:185], v[220:223], v[64:67]
	s_setprio 0
	s_barrier
	s_add_i32 s3, s65, s14
	v_lshl_add_u64 v[202:203], s[56:57], 0, v[132:133]
	s_mov_b32 m0, s3
	ds_read_b128 v[186:189], v157 offset:16384
	ds_read_b128 v[190:193], v157 offset:17408
	ds_read_b128 v[194:197], v157 offset:18432
	ds_read_b128 v[198:201], v157 offset:19456
	ds_read_b128 v[208:211], v157 offset:20480
	ds_read_b128 v[212:215], v157 offset:21504
	ds_read_b128 v[216:219], v157 offset:22528
	ds_read_b128 v[220:223], v157 offset:23552
	global_load_lds_dwordx4 v[202:203], off
	s_add_i32 m0, s3, 0x2000
	s_add_u32 s78, s56, 0x40000
	v_lshl_add_u64 v[224:225], s[56:57], 0, v[128:129]
	s_addc_u32 s79, s57, 0
	s_add_i32 s3, s66, s14
	global_load_lds_dwordx4 v[224:225], off
	v_lshl_add_u64 v[226:227], s[78:79], 0, v[132:133]
	s_mov_b32 m0, s3
	global_load_lds_dwordx4 v[226:227], off
	v_lshl_add_u64 v[226:227], s[78:79], 0, v[128:129]
	s_add_i32 m0, s3, 0x2000
	s_nop 0
	global_load_lds_dwordx4 v[226:227], off
	s_waitcnt vmcnt(6)
	s_waitcnt lgkmcnt(0)
	s_barrier
; #define PG8_STAGE(bufoff, gbase, voff) do { _Pragma("unroll") for (int _i = 0; _i < 2; ++_i) \
;         __builtin_amdgcn_global_load_lds((const unsigned*)((const char*)(gbase) + (voff)[_i]), (PG8_LAS unsigned*)(lds + (bufoff) + ldsw + _i * 8192), 16, 0, 0); } while (0)
; #define PG8_LDA(dst, b, h) do { _Pragma("unroll") for (int m = 0; m < 4; ++m) _Pragma("unroll") for (int k = 0; k < 2; ++k) dst[m][k] = *(const PG8_LAS bf16x8*)(lds + PG8_SA(b, h) + aoff + m * 2048 + k * 1024); } while (0)
; #define PG8_LDB(dst, b, h) do { _Pragma("unroll") for (int n = 0; n < 2; ++n) _Pragma("unroll") for (int k = 0; k < 2; ++k) dst[n][k] = *(const PG8_LAS bf16x8*)(lds + PG8_SB(b, h) + boff + n * 2048 + k * 1024); } while (0)
; #define PG8_MMA(ai, bj, At, Bt) do { __builtin_amdgcn_s_setprio(1); _Pragma("unroll") for (int m = 0; m < 4; ++m) _Pragma("unroll") for (int n = 0; n < 2; ++n) _Pragma("unroll") for (int k = 0; k < 2; ++k) \
;         acc[ai][bj][m][n] = __builtin_amdgcn_mfma_f32_16x16x32_bf16(Bt[n][k], At[m][k], acc[ai][bj][m][n], 0, 0, 0); __builtin_amdgcn_s_setprio(0); } while (0)
; #define PG8_WAIT_V(n) asm volatile("s_waitcnt vmcnt(" #n ")" ::: "memory")
; #define PG8_WAIT_L(n) asm volatile("s_waitcnt lgkmcnt(" #n ")" ::: "memory")
; #define PG8_BAR __builtin_amdgcn_s_barrier()
; #define PG8_SCHED __builtin_amdgcn_sched_barrier(0)
; template <class Epi, class Sched, bool ALIGN_EPI = false, bool SP2 = false>
; __device__ __forceinline__ void gemm_phase(PG8_LAS unsigned char* lds, const Gemm g, const Sched& S, const Epi& E) {
;     ...
;             PG8_WAIT_V(8); PG8_WAIT_L(0); PG8_BAR; PG8_MMA(0, 0, At, B0); PG8_MMA(0, 1, At, B1); PG8_BAR; PG8_SCHED;
;             PG8_LDA(At, 0, 1); PG8_STAGE(PG8_SB(0, 0), b2, voffB); PG8_STAGE(PG8_SB(0, 1), b2 + hstep, voffB); PG8_STAGE(PG8_SA(0, 0), a2, voffA);
;             PG8_WAIT_V(8); PG8_WAIT_L(0); PG8_BAR; PG8_MMA(1, 0, At, B0); PG8_MMA(1, 1, At, B1); PG8_BAR; PG8_SCHED;
;             PG8_LDB(B0, 1, 0); PG8_LDB(B1, 1, 1); PG8_SCHED; PG8_LDA(At, 1, 0); PG8_STAGE(PG8_SA(0, 1), a2 + hstep, voffA);
;             PG8_WAIT_V(8); PG8_WAIT_L(0); PG8_BAR; PG8_MMA(0, 0, At, B0); PG8_MMA(0, 1, At, B1); PG8_BAR; PG8_SCHED;
	s_setprio 1
	s_waitcnt lgkmcnt(0)
	v_mfma_f32_16x16x32_bf16 v[60:63], v[144:147], v[186:189], 0
	v_mfma_f32_16x16x32_bf16 v[56:59], v[160:163], v[186:189], 0
	v_mfma_f32_16x16x32_bf16 v[52:55], v[168:171], v[186:189], 0
	v_mfma_f32_16x16x32_bf16 v[48:51], v[176:179], v[186:189], 0
	v_mfma_f32_16x16x32_bf16 v[44:47], v[144:147], v[194:197], 0
	v_mfma_f32_16x16x32_bf16 v[40:43], v[160:163], v[194:197], 0
	v_mfma_f32_16x16x32_bf16 v[36:39], v[168:171], v[194:197], 0
	v_mfma_f32_16x16x32_bf16 v[32:35], v[176:179], v[194:197], 0
	v_mfma_f32_16x16x32_bf16 v[28:31], v[144:147], v[208:211], 0
	v_mfma_f32_16x16x32_bf16 v[24:27], v[160:163], v[208:211], 0
	v_mfma_f32_16x16x32_bf16 v[20:23], v[168:171], v[208:211], 0
	v_mfma_f32_16x16x32_bf16 v[16:19], v[176:179], v[208:211], 0
	v_mfma_f32_16x16x32_bf16 v[12:15], v[144:147], v[216:219], 0
	v_mfma_f32_16x16x32_bf16 v[8:11], v[160:163], v[216:219], 0
	v_lshl_add_u64 v[226:227], s[58:59], 0, v[134:135]
	s_mov_b32 m0, s34
	s_nop 0
	global_load_lds_dwordx4 v[226:227], off
	v_mfma_f32_16x16x32_bf16 v[4:7], v[168:171], v[216:219], 0
	v_mfma_f32_16x16x32_bf16 v[0:3], v[176:179], v[216:219], 0
	s_setprio 0
	s_setprio 1
	v_mfma_f32_16x16x32_bf16 v[60:63], v[148:151], v[190:193], v[60:63]
	v_mfma_f32_16x16x32_bf16 v[56:59], v[164:167], v[190:193], v[56:59]
	v_mfma_f32_16x16x32_bf16 v[52:55], v[172:175], v[190:193], v[52:55]
	v_mfma_f32_16x16x32_bf16 v[48:51], v[182:185], v[190:193], v[48:51]
	v_mfma_f32_16x16x32_bf16 v[44:47], v[148:151], v[198:201], v[44:47]
	v_mfma_f32_16x16x32_bf16 v[40:43], v[164:167], v[198:201], v[40:43]
	v_mfma_f32_16x16x32_bf16 v[36:39], v[172:175], v[198:201], v[36:39]
	v_mfma_f32_16x16x32_bf16 v[32:35], v[182:185], v[198:201], v[32:35]
	v_mfma_f32_16x16x32_bf16 v[28:31], v[148:151], v[212:215], v[28:31]
	v_mfma_f32_16x16x32_bf16 v[24:27], v[164:167], v[212:215], v[24:27]
	v_mfma_f32_16x16x32_bf16 v[20:23], v[172:175], v[212:215], v[20:23]
	v_mfma_f32_16x16x32_bf16 v[16:19], v[182:185], v[212:215], v[16:19]
	v_mfma_f32_16x16x32_bf16 v[12:15], v[148:151], v[220:223], v[12:15]
	v_mfma_f32_16x16x32_bf16 v[8:11], v[164:167], v[220:223], v[8:11]
	v_lshl_add_u64 v[228:229], s[58:59], 0, v[130:131]
	s_mov_b32 m0, s53
	s_nop 0
	global_load_lds_dwordx4 v[228:229], off
	v_mfma_f32_16x16x32_bf16 v[4:7], v[172:175], v[220:223], v[4:7]
	v_mfma_f32_16x16x32_bf16 v[0:3], v[182:185], v[220:223], v[0:3]
	s_setprio 0
	s_barrier
	s_add_i32 s3, 0, 0x18000
	v_add_u32_e32 v159, s3, v153
	s_add_i32 s33, 0, 0x1c000
	ds_read_b128 v[144:147], v159
	ds_read_b128 v[148:151], v159 offset:1024
	ds_read_b128 v[160:163], v159 offset:2048
	ds_read_b128 v[164:167], v159 offset:3072
	v_add_u32_e32 v159, s33, v153
	ds_read_b128 v[168:171], v159
	ds_read_b128 v[172:175], v159 offset:1024
	ds_read_b128 v[176:179], v159 offset:2048
	ds_read_b128 v[182:185], v159 offset:3072
	s_add_u32 s58, s58, 0x40000
	s_addc_u32 s59, s59, 0
	s_mov_b32 m0, s60
	v_lshl_add_u64 v[230:231], s[58:59], 0, v[134:135]
	ds_read_b128 v[186:189], v157 offset:32768
	ds_read_b128 v[190:193], v157 offset:33792
	ds_read_b128 v[194:197], v157 offset:34816
	ds_read_b128 v[198:201], v157 offset:35840
	ds_read_b128 v[208:211], v157 offset:36864
	ds_read_b128 v[212:215], v157 offset:37888
	ds_read_b128 v[216:219], v157 offset:38912
	ds_read_b128 v[220:223], v157 offset:39936
	global_load_lds_dwordx4 v[230:231], off
	v_lshl_add_u64 v[230:231], s[58:59], 0, v[130:131]
	s_mov_b32 m0, s61
	s_nop 0
	global_load_lds_dwordx4 v[230:231], off
	s_waitcnt vmcnt(8)
	s_waitcnt lgkmcnt(0)
	s_barrier
	s_setprio 1
	s_waitcnt lgkmcnt(0)
	v_mfma_f32_16x16x32_bf16 v[124:127], v[144:147], v[186:189], v[124:127]
	v_mfma_f32_16x16x32_bf16 v[120:123], v[160:163], v[186:189], v[120:123]
	v_mfma_f32_16x16x32_bf16 v[116:119], v[168:171], v[186:189], v[116:119]
	v_mfma_f32_16x16x32_bf16 v[112:115], v[176:179], v[186:189], v[112:115]
	v_mfma_f32_16x16x32_bf16 v[108:111], v[144:147], v[194:197], v[108:111]
	v_mfma_f32_16x16x32_bf16 v[104:107], v[160:163], v[194:197], v[104:107]
	v_mfma_f32_16x16x32_bf16 v[100:103], v[168:171], v[194:197], v[100:103]
	v_mfma_f32_16x16x32_bf16 v[96:99], v[176:179], v[194:197], v[96:99]
	v_mfma_f32_16x16x32_bf16 v[92:95], v[144:147], v[208:211], v[92:95]
	v_mfma_f32_16x16x32_bf16 v[88:91], v[160:163], v[208:211], v[88:91]
	v_mfma_f32_16x16x32_bf16 v[84:87], v[168:171], v[208:211], v[84:87]
	v_mfma_f32_16x16x32_bf16 v[80:83], v[176:179], v[208:211], v[80:83]
	v_mfma_f32_16x16x32_bf16 v[76:79], v[144:147], v[216:219], v[76:79]
	v_mfma_f32_16x16x32_bf16 v[72:75], v[160:163], v[216:219], v[72:75]
	v_mfma_f32_16x16x32_bf16 v[68:71], v[168:171], v[216:219], v[68:71]
	v_mfma_f32_16x16x32_bf16 v[64:67], v[176:179], v[216:219], v[64:67]
	s_setprio 0
	s_setprio 1
	v_mfma_f32_16x16x32_bf16 v[124:127], v[148:151], v[190:193], v[124:127]
	v_mfma_f32_16x16x32_bf16 v[120:123], v[164:167], v[190:193], v[120:123]
	v_mfma_f32_16x16x32_bf16 v[116:119], v[172:175], v[190:193], v[116:119]
	v_mfma_f32_16x16x32_bf16 v[112:115], v[182:185], v[190:193], v[112:115]
	v_mfma_f32_16x16x32_bf16 v[108:111], v[148:151], v[198:201], v[108:111]
	v_mfma_f32_16x16x32_bf16 v[104:107], v[164:167], v[198:201], v[104:107]
	v_mfma_f32_16x16x32_bf16 v[100:103], v[172:175], v[198:201], v[100:103]
	v_mfma_f32_16x16x32_bf16 v[96:99], v[182:185], v[198:201], v[96:99]
	v_mfma_f32_16x16x32_bf16 v[92:95], v[148:151], v[212:215], v[92:95]
	v_mfma_f32_16x16x32_bf16 v[88:91], v[164:167], v[212:215], v[88:91]
	v_mfma_f32_16x16x32_bf16 v[84:87], v[172:175], v[212:215], v[84:87]
	v_mfma_f32_16x16x32_bf16 v[80:83], v[182:185], v[212:215], v[80:83]
	v_mfma_f32_16x16x32_bf16 v[76:79], v[148:151], v[220:223], v[76:79]
	v_mfma_f32_16x16x32_bf16 v[72:75], v[164:167], v[220:223], v[72:75]
	v_mfma_f32_16x16x32_bf16 v[68:71], v[172:175], v[220:223], v[68:71]
	v_mfma_f32_16x16x32_bf16 v[64:67], v[182:185], v[220:223], v[64:67]
	s_setprio 0
	s_barrier
; #define PG8_STAGE(bufoff, gbase, voff) do { _Pragma("unroll") for (int _i = 0; _i < 2; ++_i) \
;         __builtin_amdgcn_global_load_lds((const unsigned*)((const char*)(gbase) + (voff)[_i]), (PG8_LAS unsigned*)(lds + (bufoff) + ldsw + _i * 8192), 16, 0, 0); } while (0)
; #define PG8_LDA(dst, b, h) do { _Pragma("unroll") for (int m = 0; m < 4; ++m) _Pragma("unroll") for (int k = 0; k < 2; ++k) dst[m][k] = *(const PG8_LAS bf16x8*)(lds + PG8_SA(b, h) + aoff + m * 2048 + k * 1024); } while (0)
; #define PG8_LDB(dst, b, h) do { _Pragma("unroll") for (int n = 0; n < 2; ++n) _Pragma("unroll") for (int k = 0; k < 2; ++k) dst[n][k] = *(const PG8_LAS bf16x8*)(lds + PG8_SB(b, h) + boff + n * 2048 + k * 1024); } while (0)
; #define PG8_MMA(ai, bj, At, Bt) do { __builtin_amdgcn_s_setprio(1); _Pragma("unroll") for (int m = 0; m < 4; ++m) _Pragma("unroll") for (int n = 0; n < 2; ++n) _Pragma("unroll") for (int k = 0; k < 2; ++k) \
;         acc[ai][bj][m][n] = __builtin_amdgcn_mfma_f32_16x16x32_bf16(Bt[n][k], At[m][k], acc[ai][bj][m][n], 0, 0, 0); __builtin_amdgcn_s_setprio(0); } while (0)
; #define PG8_WAIT_V(n) asm volatile("s_waitcnt vmcnt(" #n ")" ::: "memory")
; template <class Epi, class Sched, bool ALIGN_EPI = false, bool SP2 = false>
; __device__ __forceinline__ void gemm_phase(PG8_LAS unsigned char* lds, const Gemm g, const Sched& S, const Epi& E) {
;     ...
;             PG8_LDB(B0, 0, 0); PG8_LDB(B1, 0, 1); PG8_SCHED; PG8_LDA(At, 0, 0); PG8_STAGE(PG8_SA(1, 1), a1 + hstep, voffA);
;             PG8_WAIT_V(8); PG8_WAIT_L(0); PG8_BAR; PG8_MMA(0, 0, At, B0); PG8_MMA(0, 1, At, B1); PG8_BAR; PG8_SCHED;
;             PG8_LDA(At, 0, 1); PG8_STAGE(PG8_SB(0, 0), b2, voffB); PG8_STAGE(PG8_SB(0, 1), b2 + hstep, voffB); PG8_STAGE(PG8_SA(0, 0), a2, voffA);
;             PG8_WAIT_V(8); PG8_WAIT_L(0); PG8_BAR; PG8_MMA(1, 0, At, B0); PG8_MMA(1, 1, At, B1); PG8_BAR; PG8_SCHED;
;             PG8_LDB(B0, 1, 0); PG8_LDB(B1, 1, 1); PG8_SCHED; PG8_LDA(At, 1, 0); PG8_STAGE(PG8_SA(0, 1), a2 + hstep, voffA);
;             PG8_WAIT_V(8); PG8_WAIT_L(0); PG8_BAR; PG8_MMA(0, 0, At, B0); PG8_MMA(0, 1, At, B1); PG8_BAR; PG8_SCHED;
;             PG8_LDA(At, 1, 1); PG8_STAGE(PG8_SB(1, 0), b3, voffB); PG8_STAGE(PG8_SB(1, 1), b3 + hstep, voffB); PG8_STAGE(PG8_SA(1, 0), a3, voffA);
;             PG8_WAIT_V(8); PG8_WAIT_L(0); PG8_BAR; PG8_MMA(1, 0, At, B0); PG8_MMA(1, 1, At, B1); PG8_BAR; PG8_SCHED;
	s_add_i32 s3, s3, s14
	v_lshl_add_u64 v[202:203], v[202:203], 0, s[36:37]
	s_mov_b32 m0, s3
	ds_read_b128 v[186:189], v157 offset:49152
	ds_read_b128 v[190:193], v157 offset:50176
	ds_read_b128 v[194:197], v157 offset:51200
	ds_read_b128 v[198:201], v157 offset:52224
	ds_read_b128 v[208:211], v157 offset:53248
	ds_read_b128 v[212:215], v157 offset:54272
	ds_read_b128 v[216:219], v157 offset:55296
	ds_read_b128 v[220:223], v157 offset:56320
	global_load_lds_dwordx4 v[202:203], off
	s_add_i32 m0, s3, 0x2000
	s_add_u32 s56, s56, 0x40080
	v_lshl_add_u64 v[202:203], v[224:225], 0, s[36:37]
	s_addc_u32 s57, s57, 0
	s_add_i32 s3, s33, s14
	global_load_lds_dwordx4 v[202:203], off
	v_lshl_add_u64 v[202:203], s[56:57], 0, v[132:133]
	s_mov_b32 m0, s3
	s_nop 0
	global_load_lds_dwordx4 v[202:203], off
	v_lshl_add_u64 v[202:203], s[56:57], 0, v[128:129]
	s_add_i32 m0, s3, 0x2000
	s_nop 0
	global_load_lds_dwordx4 v[202:203], off
	s_waitcnt vmcnt(6)
	s_waitcnt lgkmcnt(0)
	s_barrier
	s_setprio 1
	s_waitcnt lgkmcnt(0)
	v_mfma_f32_16x16x32_bf16 v[60:63], v[144:147], v[186:189], v[60:63]
	v_mfma_f32_16x16x32_bf16 v[56:59], v[160:163], v[186:189], v[56:59]
	v_mfma_f32_16x16x32_bf16 v[52:55], v[168:171], v[186:189], v[52:55]
	v_mfma_f32_16x16x32_bf16 v[48:51], v[176:179], v[186:189], v[48:51]
	v_mfma_f32_16x16x32_bf16 v[44:47], v[144:147], v[194:197], v[44:47]
	v_mfma_f32_16x16x32_bf16 v[40:43], v[160:163], v[194:197], v[40:43]
	v_mfma_f32_16x16x32_bf16 v[36:39], v[168:171], v[194:197], v[36:39]
	v_mfma_f32_16x16x32_bf16 v[32:35], v[176:179], v[194:197], v[32:35]
	v_mfma_f32_16x16x32_bf16 v[28:31], v[144:147], v[208:211], v[28:31]
	v_mfma_f32_16x16x32_bf16 v[24:27], v[160:163], v[208:211], v[24:27]
	v_mfma_f32_16x16x32_bf16 v[20:23], v[168:171], v[208:211], v[20:23]
	v_mfma_f32_16x16x32_bf16 v[16:19], v[176:179], v[208:211], v[16:19]
	v_mfma_f32_16x16x32_bf16 v[12:15], v[144:147], v[216:219], v[12:15]
	v_mfma_f32_16x16x32_bf16 v[8:11], v[160:163], v[216:219], v[8:11]
	v_lshl_add_u64 v[202:203], v[226:227], 0, s[36:37]
	s_mov_b32 m0, s63
	s_nop 0
	global_load_lds_dwordx4 v[202:203], off
	v_mfma_f32_16x16x32_bf16 v[4:7], v[168:171], v[216:219], v[4:7]
	v_mfma_f32_16x16x32_bf16 v[0:3], v[176:179], v[216:219], v[0:3]
	s_setprio 0
	s_setprio 1
	v_mfma_f32_16x16x32_bf16 v[60:63], v[148:151], v[190:193], v[60:63]
	v_mfma_f32_16x16x32_bf16 v[56:59], v[164:167], v[190:193], v[56:59]
	v_mfma_f32_16x16x32_bf16 v[52:55], v[172:175], v[190:193], v[52:55]
	v_mfma_f32_16x16x32_bf16 v[48:51], v[182:185], v[190:193], v[48:51]
	v_mfma_f32_16x16x32_bf16 v[44:47], v[148:151], v[198:201], v[44:47]
	v_mfma_f32_16x16x32_bf16 v[40:43], v[164:167], v[198:201], v[40:43]
	v_mfma_f32_16x16x32_bf16 v[36:39], v[172:175], v[198:201], v[36:39]
	v_mfma_f32_16x16x32_bf16 v[32:35], v[182:185], v[198:201], v[32:35]
	v_mfma_f32_16x16x32_bf16 v[28:31], v[148:151], v[212:215], v[28:31]
	v_mfma_f32_16x16x32_bf16 v[24:27], v[164:167], v[212:215], v[24:27]
	v_mfma_f32_16x16x32_bf16 v[20:23], v[172:175], v[212:215], v[20:23]
	v_mfma_f32_16x16x32_bf16 v[16:19], v[182:185], v[212:215], v[16:19]
	v_mfma_f32_16x16x32_bf16 v[12:15], v[148:151], v[220:223], v[12:15]
	v_mfma_f32_16x16x32_bf16 v[8:11], v[164:167], v[220:223], v[8:11]
	v_lshl_add_u64 v[202:203], v[228:229], 0, s[36:37]
	s_mov_b32 m0, s64
	s_nop 0
	global_load_lds_dwordx4 v[202:203], off
	v_mfma_f32_16x16x32_bf16 v[4:7], v[172:175], v[220:223], v[4:7]
	v_mfma_f32_16x16x32_bf16 v[0:3], v[182:185], v[220:223], v[0:3]
	s_setprio 0
	s_barrier
	s_add_i32 s83, s83, 2
	s_add_u32 s54, s54, 0x100
	s_addc_u32 s55, s55, 0
	s_add_u32 s77, s77, 0x100
	s_addc_u32 s82, s82, 0
.LBB0_957:
	ds_read_b128 v[144:147], v155
	ds_read_b128 v[148:151], v155 offset:1024
	ds_read_b128 v[160:163], v155 offset:2048
	ds_read_b128 v[164:167], v155 offset:3072
	ds_read_b128 v[168:171], v156
	ds_read_b128 v[172:175], v156 offset:1024
	ds_read_b128 v[176:179], v156 offset:2048
	ds_read_b128 v[182:185], v156 offset:3072
	s_add_u32 s3, s54, 0xfffc0080
	s_addc_u32 s33, s55, -1
	s_cmp_eq_u32 s83, 12
	s_cselect_b32 s59, s45, s33
	s_cselect_b32 s58, s75, s3
	s_cselect_b32 s57, s43, s82
	s_cselect_b32 s56, s76, s77
	v_lshl_add_u64 v[202:203], s[54:55], 0, v[136:137]
	s_add_i32 m0, s34, 0xc000
	ds_read_b128 v[186:189], v157
	ds_read_b128 v[190:193], v157 offset:1024
	ds_read_b128 v[194:197], v157 offset:2048
	ds_read_b128 v[198:201], v157 offset:3072
	ds_read_b128 v[208:211], v157 offset:4096
	ds_read_b128 v[212:215], v157 offset:5120
	ds_read_b128 v[216:219], v157 offset:6144
	ds_read_b128 v[220:223], v157 offset:7168
	global_load_lds_dwordx4 v[202:203], off
	v_lshl_add_u64 v[202:203], s[54:55], 0, v[138:139]
	s_add_i32 m0, s34, 0xe000
	s_nop 0
	global_load_lds_dwordx4 v[202:203], off
	s_waitcnt vmcnt(8)
	s_waitcnt lgkmcnt(0)
	s_barrier
; #define PG8_STAGE(bufoff, gbase, voff) do { _Pragma("unroll") for (int _i = 0; _i < 2; ++_i) \
;         __builtin_amdgcn_global_load_lds((const unsigned*)((const char*)(gbase) + (voff)[_i]), (PG8_LAS unsigned*)(lds + (bufoff) + ldsw + _i * 8192), 16, 0, 0); } while (0)
; #define PG8_LDA(dst, b, h) do { _Pragma("unroll") for (int m = 0; m < 4; ++m) _Pragma("unroll") for (int k = 0; k < 2; ++k) dst[m][k] = *(const PG8_LAS bf16x8*)(lds + PG8_SA(b, h) + aoff + m * 2048 + k * 1024); } while (0)
; #define PG8_LDB(dst, b, h) do { _Pragma("unroll") for (int n = 0; n < 2; ++n) _Pragma("unroll") for (int k = 0; k < 2; ++k) dst[n][k] = *(const PG8_LAS bf16x8*)(lds + PG8_SB(b, h) + boff + n * 2048 + k * 1024); } while (0)
; #define PG8_MMA(ai, bj, At, Bt) do { __builtin_amdgcn_s_setprio(1); _Pragma("unroll") for (int m = 0; m < 4; ++m) _Pragma("unroll") for (int n = 0; n < 2; ++n) _Pragma("unroll") for (int k = 0; k < 2; ++k) \
;         acc[ai][bj][m][n] = __builtin_amdgcn_mfma_f32_16x16x32_bf16(Bt[n][k], At[m][k], acc[ai][bj][m][n], 0, 0, 0); __builtin_amdgcn_s_setprio(0); } while (0)
; #define PG8_WAIT_V(n) asm volatile("s_waitcnt vmcnt(" #n ")" ::: "memory")
; #define PG8_WAIT_L(n) asm volatile("s_waitcnt lgkmcnt(" #n ")" ::: "memory")
; #define PG8_BAR __builtin_amdgcn_s_barrier()
; #define PG8_SCHED __builtin_amdgcn_sched_barrier(0)
; template <class Epi, class Sched, bool ALIGN_EPI = false, bool SP2 = false>
; __device__ __forceinline__ void gemm_phase(PG8_LAS unsigned char* lds, const Gemm g, const Sched& S, const Epi& E) {
;     ...
;             PG8_LDB(B0, 0, 0); PG8_LDB(B1, 0, 1); PG8_SCHED; PG8_LDA(At, 0, 0); PG8_STAGE(PG8_SA(1, 1), a1 + hstep, voffA);
;             PG8_WAIT_V(8); PG8_WAIT_L(0); PG8_BAR; PG8_MMA(0, 0, At, B0); PG8_MMA(0, 1, At, B1); PG8_BAR; PG8_SCHED;
;             PG8_LDA(At, 0, 1); PG8_STAGE(PG8_SB(0, 0), b2, voffB); PG8_STAGE(PG8_SB(0, 1), b2 + hstep, voffB); PG8_STAGE(PG8_SA(0, 0), a2, voffA);
;             PG8_WAIT_V(8); PG8_WAIT_L(0); PG8_BAR; PG8_MMA(1, 0, At, B0); PG8_MMA(1, 1, At, B1); PG8_BAR; PG8_SCHED;
	s_setprio 1
	s_waitcnt lgkmcnt(0)
	v_mfma_f32_16x16x32_bf16 v[124:127], v[144:147], v[186:189], v[124:127]
	v_mfma_f32_16x16x32_bf16 v[120:123], v[160:163], v[186:189], v[120:123]
	v_mfma_f32_16x16x32_bf16 v[116:119], v[168:171], v[186:189], v[116:119]
	v_mfma_f32_16x16x32_bf16 v[112:115], v[176:179], v[186:189], v[112:115]
	v_mfma_f32_16x16x32_bf16 v[108:111], v[144:147], v[194:197], v[108:111]
	v_mfma_f32_16x16x32_bf16 v[104:107], v[160:163], v[194:197], v[104:107]
	v_mfma_f32_16x16x32_bf16 v[100:103], v[168:171], v[194:197], v[100:103]
	v_mfma_f32_16x16x32_bf16 v[96:99], v[176:179], v[194:197], v[96:99]
	v_mfma_f32_16x16x32_bf16 v[92:95], v[144:147], v[208:211], v[92:95]
	v_mfma_f32_16x16x32_bf16 v[88:91], v[160:163], v[208:211], v[88:91]
	v_mfma_f32_16x16x32_bf16 v[84:87], v[168:171], v[208:211], v[84:87]
	v_mfma_f32_16x16x32_bf16 v[80:83], v[176:179], v[208:211], v[80:83]
	v_mfma_f32_16x16x32_bf16 v[76:79], v[144:147], v[216:219], v[76:79]
	v_mfma_f32_16x16x32_bf16 v[72:75], v[160:163], v[216:219], v[72:75]
	v_mfma_f32_16x16x32_bf16 v[68:71], v[168:171], v[216:219], v[68:71]
	v_mfma_f32_16x16x32_bf16 v[64:67], v[176:179], v[216:219], v[64:67]
	s_setprio 0
	s_setprio 1
	v_mfma_f32_16x16x32_bf16 v[124:127], v[148:151], v[190:193], v[124:127]
	v_mfma_f32_16x16x32_bf16 v[120:123], v[164:167], v[190:193], v[120:123]
	v_mfma_f32_16x16x32_bf16 v[116:119], v[172:175], v[190:193], v[116:119]
	v_mfma_f32_16x16x32_bf16 v[112:115], v[182:185], v[190:193], v[112:115]
	v_mfma_f32_16x16x32_bf16 v[108:111], v[148:151], v[198:201], v[108:111]
	v_mfma_f32_16x16x32_bf16 v[104:107], v[164:167], v[198:201], v[104:107]
	v_mfma_f32_16x16x32_bf16 v[100:103], v[172:175], v[198:201], v[100:103]
	v_mfma_f32_16x16x32_bf16 v[96:99], v[182:185], v[198:201], v[96:99]
	v_mfma_f32_16x16x32_bf16 v[92:95], v[148:151], v[212:215], v[92:95]
	v_mfma_f32_16x16x32_bf16 v[88:91], v[164:167], v[212:215], v[88:91]
	v_mfma_f32_16x16x32_bf16 v[84:87], v[172:175], v[212:215], v[84:87]
	v_mfma_f32_16x16x32_bf16 v[80:83], v[182:185], v[212:215], v[80:83]
	v_mfma_f32_16x16x32_bf16 v[76:79], v[148:151], v[220:223], v[76:79]
	v_mfma_f32_16x16x32_bf16 v[72:75], v[164:167], v[220:223], v[72:75]
	v_mfma_f32_16x16x32_bf16 v[68:71], v[172:175], v[220:223], v[68:71]
	v_mfma_f32_16x16x32_bf16 v[64:67], v[182:185], v[220:223], v[64:67]
	s_setprio 0
	s_barrier
	s_add_i32 s3, s65, s14
	v_lshl_add_u64 v[202:203], s[56:57], 0, v[132:133]
	s_mov_b32 m0, s3
	ds_read_b128 v[186:189], v157 offset:16384
	ds_read_b128 v[190:193], v157 offset:17408
	ds_read_b128 v[194:197], v157 offset:18432
	ds_read_b128 v[198:201], v157 offset:19456
	ds_read_b128 v[208:211], v157 offset:20480
	ds_read_b128 v[212:215], v157 offset:21504
	ds_read_b128 v[216:219], v157 offset:22528
	ds_read_b128 v[220:223], v157 offset:23552
	global_load_lds_dwordx4 v[202:203], off
	s_add_i32 m0, s3, 0x2000
	s_add_u32 s78, s56, 0x40000
	v_lshl_add_u64 v[224:225], s[56:57], 0, v[128:129]
	s_addc_u32 s79, s57, 0
	s_add_i32 s3, s66, s14
	global_load_lds_dwordx4 v[224:225], off
	v_lshl_add_u64 v[226:227], s[78:79], 0, v[132:133]
	s_mov_b32 m0, s3
	global_load_lds_dwordx4 v[226:227], off
	v_lshl_add_u64 v[226:227], s[78:79], 0, v[128:129]
	s_add_i32 m0, s3, 0x2000
	s_nop 0
	global_load_lds_dwordx4 v[226:227], off
	s_waitcnt vmcnt(6)
	s_waitcnt lgkmcnt(0)
	s_barrier
	s_setprio 1
	s_waitcnt lgkmcnt(0)
	v_mfma_f32_16x16x32_bf16 v[60:63], v[144:147], v[186:189], v[60:63]
	v_mfma_f32_16x16x32_bf16 v[56:59], v[160:163], v[186:189], v[56:59]
	v_mfma_f32_16x16x32_bf16 v[52:55], v[168:171], v[186:189], v[52:55]
	v_mfma_f32_16x16x32_bf16 v[48:51], v[176:179], v[186:189], v[48:51]
	v_mfma_f32_16x16x32_bf16 v[44:47], v[144:147], v[194:197], v[44:47]
	v_mfma_f32_16x16x32_bf16 v[40:43], v[160:163], v[194:197], v[40:43]
	v_mfma_f32_16x16x32_bf16 v[36:39], v[168:171], v[194:197], v[36:39]
	v_mfma_f32_16x16x32_bf16 v[32:35], v[176:179], v[194:197], v[32:35]
	v_mfma_f32_16x16x32_bf16 v[28:31], v[144:147], v[208:211], v[28:31]
	v_mfma_f32_16x16x32_bf16 v[24:27], v[160:163], v[208:211], v[24:27]
	v_mfma_f32_16x16x32_bf16 v[20:23], v[168:171], v[208:211], v[20:23]
	v_mfma_f32_16x16x32_bf16 v[16:19], v[176:179], v[208:211], v[16:19]
	v_mfma_f32_16x16x32_bf16 v[12:15], v[144:147], v[216:219], v[12:15]
	v_mfma_f32_16x16x32_bf16 v[8:11], v[160:163], v[216:219], v[8:11]
	v_lshl_add_u64 v[226:227], s[58:59], 0, v[134:135]
	s_mov_b32 m0, s34
	s_nop 0
	global_load_lds_dwordx4 v[226:227], off
	v_mfma_f32_16x16x32_bf16 v[4:7], v[168:171], v[216:219], v[4:7]
	v_mfma_f32_16x16x32_bf16 v[0:3], v[176:179], v[216:219], v[0:3]
	s_setprio 0
	s_setprio 1
	v_mfma_f32_16x16x32_bf16 v[60:63], v[148:151], v[190:193], v[60:63]
	v_mfma_f32_16x16x32_bf16 v[56:59], v[164:167], v[190:193], v[56:59]
	v_mfma_f32_16x16x32_bf16 v[52:55], v[172:175], v[190:193], v[52:55]
	v_mfma_f32_16x16x32_bf16 v[48:51], v[182:185], v[190:193], v[48:51]
	v_mfma_f32_16x16x32_bf16 v[44:47], v[148:151], v[198:201], v[44:47]
	v_mfma_f32_16x16x32_bf16 v[40:43], v[164:167], v[198:201], v[40:43]
	v_mfma_f32_16x16x32_bf16 v[36:39], v[172:175], v[198:201], v[36:39]
	v_mfma_f32_16x16x32_bf16 v[32:35], v[182:185], v[198:201], v[32:35]
	v_mfma_f32_16x16x32_bf16 v[28:31], v[148:151], v[212:215], v[28:31]
	v_mfma_f32_16x16x32_bf16 v[24:27], v[164:167], v[212:215], v[24:27]
	v_mfma_f32_16x16x32_bf16 v[20:23], v[172:175], v[212:215], v[20:23]
	v_mfma_f32_16x16x32_bf16 v[16:19], v[182:185], v[212:215], v[16:19]
	v_mfma_f32_16x16x32_bf16 v[12:15], v[148:151], v[220:223], v[12:15]
	v_mfma_f32_16x16x32_bf16 v[8:11], v[164:167], v[220:223], v[8:11]
	v_lshl_add_u64 v[228:229], s[58:59], 0, v[130:131]
	s_mov_b32 m0, s53
	s_nop 0
	global_load_lds_dwordx4 v[228:229], off
	v_mfma_f32_16x16x32_bf16 v[4:7], v[172:175], v[220:223], v[4:7]
	v_mfma_f32_16x16x32_bf16 v[0:3], v[182:185], v[220:223], v[0:3]
	s_setprio 0
	s_barrier
; #define PG8_STAGE(bufoff, gbase, voff) do { _Pragma("unroll") for (int _i = 0; _i < 2; ++_i) \
;         __builtin_amdgcn_global_load_lds((const unsigned*)((const char*)(gbase) + (voff)[_i]), (PG8_LAS unsigned*)(lds + (bufoff) + ldsw + _i * 8192), 16, 0, 0); } while (0)
; #define PG8_LDA(dst, b, h) do { _Pragma("unroll") for (int m = 0; m < 4; ++m) _Pragma("unroll") for (int k = 0; k < 2; ++k) dst[m][k] = *(const PG8_LAS bf16x8*)(lds + PG8_SA(b, h) + aoff + m * 2048 + k * 1024); } while (0)
; #define PG8_LDB(dst, b, h) do { _Pragma("unroll") for (int n = 0; n < 2; ++n) _Pragma("unroll") for (int k = 0; k < 2; ++k) dst[n][k] = *(const PG8_LAS bf16x8*)(lds + PG8_SB(b, h) + boff + n * 2048 + k * 1024); } while (0)
; #define PG8_MMA(ai, bj, At, Bt) do { __builtin_amdgcn_s_setprio(1); _Pragma("unroll") for (int m = 0; m < 4; ++m) _Pragma("unroll") for (int n = 0; n < 2; ++n) _Pragma("unroll") for (int k = 0; k < 2; ++k) \
;         acc[ai][bj][m][n] = __builtin_amdgcn_mfma_f32_16x16x32_bf16(Bt[n][k], At[m][k], acc[ai][bj][m][n], 0, 0, 0); __builtin_amdgcn_s_setprio(0); } while (0)
; #define PG8_WAIT_V(n) asm volatile("s_waitcnt vmcnt(" #n ")" ::: "memory")
; #define PG8_WAIT_L(n) asm volatile("s_waitcnt lgkmcnt(" #n ")" ::: "memory")
; #define PG8_BAR __builtin_amdgcn_s_barrier()
; #define PG8_SCHED __builtin_amdgcn_sched_barrier(0)
; template <class Epi, class Sched, bool ALIGN_EPI = false, bool SP2 = false>
; __device__ __forceinline__ void gemm_phase(PG8_LAS unsigned char* lds, const Gemm g, const Sched& S, const Epi& E) {
;     ...
;             PG8_LDB(B0, 1, 0); PG8_LDB(B1, 1, 1); PG8_SCHED; PG8_LDA(At, 1, 0); PG8_STAGE(PG8_SA(0, 1), a2 + hstep, voffA);
;             PG8_WAIT_V(8); PG8_WAIT_L(0); PG8_BAR; PG8_MMA(0, 0, At, B0); PG8_MMA(0, 1, At, B1); PG8_BAR; PG8_SCHED;
	s_add_i32 s3, 0, 0x18000
	v_add_u32_e32 v159, s3, v153
	s_add_i32 s33, 0, 0x1c000
	ds_read_b128 v[144:147], v159
	ds_read_b128 v[148:151], v159 offset:1024
	ds_read_b128 v[160:163], v159 offset:2048
	ds_read_b128 v[164:167], v159 offset:3072
	v_add_u32_e32 v159, s33, v153
	ds_read_b128 v[168:171], v159
	ds_read_b128 v[172:175], v159 offset:1024
	ds_read_b128 v[176:179], v159 offset:2048
	ds_read_b128 v[182:185], v159 offset:3072
	s_add_u32 s58, s58, 0x40000
	s_addc_u32 s59, s59, 0
	s_mov_b32 m0, s60
	v_lshl_add_u64 v[230:231], s[58:59], 0, v[134:135]
	ds_read_b128 v[186:189], v157 offset:32768
	ds_read_b128 v[190:193], v157 offset:33792
	ds_read_b128 v[194:197], v157 offset:34816
	ds_read_b128 v[198:201], v157 offset:35840
	ds_read_b128 v[208:211], v157 offset:36864
	ds_read_b128 v[212:215], v157 offset:37888
	ds_read_b128 v[216:219], v157 offset:38912
	ds_read_b128 v[220:223], v157 offset:39936
	global_load_lds_dwordx4 v[230:231], off
	v_lshl_add_u64 v[230:231], s[58:59], 0, v[130:131]
	s_mov_b32 m0, s61
	s_nop 0
	global_load_lds_dwordx4 v[230:231], off
	s_waitcnt vmcnt(8)
	s_waitcnt lgkmcnt(0)
	s_barrier
	s_setprio 1
	s_waitcnt lgkmcnt(0)
	v_mfma_f32_16x16x32_bf16 v[124:127], v[144:147], v[186:189], v[124:127]
	v_mfma_f32_16x16x32_bf16 v[120:123], v[160:163], v[186:189], v[120:123]
	v_mfma_f32_16x16x32_bf16 v[116:119], v[168:171], v[186:189], v[116:119]
	v_mfma_f32_16x16x32_bf16 v[112:115], v[176:179], v[186:189], v[112:115]
	v_mfma_f32_16x16x32_bf16 v[108:111], v[144:147], v[194:197], v[108:111]
	v_mfma_f32_16x16x32_bf16 v[104:107], v[160:163], v[194:197], v[104:107]
	v_mfma_f32_16x16x32_bf16 v[100:103], v[168:171], v[194:197], v[100:103]
	v_mfma_f32_16x16x32_bf16 v[96:99], v[176:179], v[194:197], v[96:99]
	v_mfma_f32_16x16x32_bf16 v[92:95], v[144:147], v[208:211], v[92:95]
	v_mfma_f32_16x16x32_bf16 v[88:91], v[160:163], v[208:211], v[88:91]
	v_mfma_f32_16x16x32_bf16 v[84:87], v[168:171], v[208:211], v[84:87]
	v_mfma_f32_16x16x32_bf16 v[80:83], v[176:179], v[208:211], v[80:83]
	v_mfma_f32_16x16x32_bf16 v[76:79], v[144:147], v[216:219], v[76:79]
	v_mfma_f32_16x16x32_bf16 v[72:75], v[160:163], v[216:219], v[72:75]
	v_mfma_f32_16x16x32_bf16 v[68:71], v[168:171], v[216:219], v[68:71]
	v_mfma_f32_16x16x32_bf16 v[64:67], v[176:179], v[216:219], v[64:67]
	s_setprio 0
	s_setprio 1
	v_mfma_f32_16x16x32_bf16 v[124:127], v[148:151], v[190:193], v[124:127]
	v_mfma_f32_16x16x32_bf16 v[120:123], v[164:167], v[190:193], v[120:123]
	v_mfma_f32_16x16x32_bf16 v[116:119], v[172:175], v[190:193], v[116:119]
	v_mfma_f32_16x16x32_bf16 v[112:115], v[182:185], v[190:193], v[112:115]
	v_mfma_f32_16x16x32_bf16 v[108:111], v[148:151], v[198:201], v[108:111]
	v_mfma_f32_16x16x32_bf16 v[104:107], v[164:167], v[198:201], v[104:107]
	v_mfma_f32_16x16x32_bf16 v[100:103], v[172:175], v[198:201], v[100:103]
	v_mfma_f32_16x16x32_bf16 v[96:99], v[182:185], v[198:201], v[96:99]
	v_mfma_f32_16x16x32_bf16 v[92:95], v[148:151], v[212:215], v[92:95]
	v_mfma_f32_16x16x32_bf16 v[88:91], v[164:167], v[212:215], v[88:91]
	v_mfma_f32_16x16x32_bf16 v[84:87], v[172:175], v[212:215], v[84:87]
	v_mfma_f32_16x16x32_bf16 v[80:83], v[182:185], v[212:215], v[80:83]
	v_mfma_f32_16x16x32_bf16 v[76:79], v[148:151], v[220:223], v[76:79]
	v_mfma_f32_16x16x32_bf16 v[72:75], v[164:167], v[220:223], v[72:75]
	v_mfma_f32_16x16x32_bf16 v[68:71], v[172:175], v[220:223], v[68:71]
	v_mfma_f32_16x16x32_bf16 v[64:67], v[182:185], v[220:223], v[64:67]
	s_setprio 0
	s_barrier
; #define PG8_STAGE(bufoff, gbase, voff) do { _Pragma("unroll") for (int _i = 0; _i < 2; ++_i) \
;         __builtin_amdgcn_global_load_lds((const unsigned*)((const char*)(gbase) + (voff)[_i]), (PG8_LAS unsigned*)(lds + (bufoff) + ldsw + _i * 8192), 16, 0, 0); } while (0)
; #define PG8_LDA(dst, b, h) do { _Pragma("unroll") for (int m = 0; m < 4; ++m) _Pragma("unroll") for (int k = 0; k < 2; ++k) dst[m][k] = *(const PG8_LAS bf16x8*)(lds + PG8_SA(b, h) + aoff + m * 2048 + k * 1024); } while (0)
; #define PG8_MMA(ai, bj, At, Bt) do { __builtin_amdgcn_s_setprio(1); _Pragma("unroll") for (int m = 0; m < 4; ++m) _Pragma("unroll") for (int n = 0; n < 2; ++n) _Pragma("unroll") for (int k = 0; k < 2; ++k) \
;         acc[ai][bj][m][n] = __builtin_amdgcn_mfma_f32_16x16x32_bf16(Bt[n][k], At[m][k], acc[ai][bj][m][n], 0, 0, 0); __builtin_amdgcn_s_setprio(0); } while (0)
; #define PG8_WAIT_V(n) asm volatile("s_waitcnt vmcnt(" #n ")" ::: "memory")
; #define PG8_WAIT_L(n) asm volatile("s_waitcnt lgkmcnt(" #n ")" ::: "memory")
; #define PG8_BAR __builtin_amdgcn_s_barrier()
; #define PG8_SCHED __builtin_amdgcn_sched_barrier(0)
; __device__ __forceinline__ float row_rs(const float* ssp, int row) { const unsigned long long v = ((const unsigned long long*)ssp)[row];
;     return __builtin_amdgcn_rsqf((float)v * (1.0f / 4294967296.0f) * (1.0f / 1024.0f) + RMS_EPS); }
; template <class Epi, class Sched, bool ALIGN_EPI = false, bool SP2 = false>
; __device__ __forceinline__ void gemm_phase(PG8_LAS unsigned char* lds, const Gemm g, const Sched& S, const Epi& E) {
;     ...
;             PG8_LDA(At, 1, 1); PG8_STAGE(PG8_SB(1, 0), b3, voffB); PG8_STAGE(PG8_SB(1, 1), b3 + hstep, voffB); PG8_STAGE(PG8_SA(1, 0), a3, voffA);
;             PG8_WAIT_V(8); PG8_WAIT_L(0); PG8_BAR; PG8_MMA(1, 0, At, B0); PG8_MMA(1, 1, At, B1); PG8_BAR; PG8_SCHED;
	s_add_i32 s3, s3, s14
	v_lshl_add_u64 v[202:203], v[202:203], 0, s[36:37]
	s_mov_b32 m0, s3
	ds_read_b128 v[186:189], v157 offset:49152
	ds_read_b128 v[190:193], v157 offset:50176
	ds_read_b128 v[194:197], v157 offset:51200
	ds_read_b128 v[198:201], v157 offset:52224
	ds_read_b128 v[208:211], v157 offset:53248
	ds_read_b128 v[212:215], v157 offset:54272
	ds_read_b128 v[216:219], v157 offset:55296
	ds_read_b128 v[220:223], v157 offset:56320
	global_load_lds_dwordx4 v[202:203], off
	s_add_i32 m0, s3, 0x2000
	s_add_u32 s56, s56, 0x40080
	v_lshl_add_u64 v[202:203], v[224:225], 0, s[36:37]
	s_addc_u32 s57, s57, 0
	s_add_i32 s3, s33, s14
	global_load_lds_dwordx4 v[202:203], off
	v_lshl_add_u64 v[202:203], s[56:57], 0, v[132:133]
	s_mov_b32 m0, s3
	s_nop 0
	global_load_lds_dwordx4 v[202:203], off
	v_lshl_add_u64 v[202:203], s[56:57], 0, v[128:129]
	s_add_i32 m0, s3, 0x2000
	s_nop 0
	global_load_lds_dwordx4 v[202:203], off
	s_waitcnt vmcnt(6)
	s_waitcnt lgkmcnt(0)
	s_barrier
	s_setprio 1
	s_waitcnt lgkmcnt(0)
	v_mfma_f32_16x16x32_bf16 v[60:63], v[144:147], v[186:189], v[60:63]
	v_mfma_f32_16x16x32_bf16 v[56:59], v[160:163], v[186:189], v[56:59]
	v_mfma_f32_16x16x32_bf16 v[52:55], v[168:171], v[186:189], v[52:55]
	v_mfma_f32_16x16x32_bf16 v[48:51], v[176:179], v[186:189], v[48:51]
	v_mfma_f32_16x16x32_bf16 v[44:47], v[144:147], v[194:197], v[44:47]
	v_mfma_f32_16x16x32_bf16 v[40:43], v[160:163], v[194:197], v[40:43]
	v_mfma_f32_16x16x32_bf16 v[36:39], v[168:171], v[194:197], v[36:39]
	v_mfma_f32_16x16x32_bf16 v[32:35], v[176:179], v[194:197], v[32:35]
	v_mfma_f32_16x16x32_bf16 v[28:31], v[144:147], v[208:211], v[28:31]
	v_mfma_f32_16x16x32_bf16 v[24:27], v[160:163], v[208:211], v[24:27]
	v_mfma_f32_16x16x32_bf16 v[20:23], v[168:171], v[208:211], v[20:23]
	v_mfma_f32_16x16x32_bf16 v[16:19], v[176:179], v[208:211], v[16:19]
	v_mfma_f32_16x16x32_bf16 v[12:15], v[144:147], v[216:219], v[12:15]
	v_mfma_f32_16x16x32_bf16 v[8:11], v[160:163], v[216:219], v[8:11]
	v_lshl_add_u64 v[202:203], v[226:227], 0, s[36:37]
	s_mov_b32 m0, s63
	s_nop 0
	global_load_lds_dwordx4 v[202:203], off
	v_mfma_f32_16x16x32_bf16 v[4:7], v[168:171], v[216:219], v[4:7]
	v_mfma_f32_16x16x32_bf16 v[0:3], v[176:179], v[216:219], v[0:3]
	s_setprio 0
	s_setprio 1
	v_mfma_f32_16x16x32_bf16 v[60:63], v[148:151], v[190:193], v[60:63]
	v_mfma_f32_16x16x32_bf16 v[56:59], v[164:167], v[190:193], v[56:59]
	v_mfma_f32_16x16x32_bf16 v[52:55], v[172:175], v[190:193], v[52:55]
	v_mfma_f32_16x16x32_bf16 v[48:51], v[182:185], v[190:193], v[48:51]
	v_mfma_f32_16x16x32_bf16 v[44:47], v[148:151], v[198:201], v[44:47]
	v_mfma_f32_16x16x32_bf16 v[40:43], v[164:167], v[198:201], v[40:43]
	v_mfma_f32_16x16x32_bf16 v[36:39], v[172:175], v[198:201], v[36:39]
	v_mfma_f32_16x16x32_bf16 v[32:35], v[182:185], v[198:201], v[32:35]
	v_mfma_f32_16x16x32_bf16 v[28:31], v[148:151], v[212:215], v[28:31]
	v_mfma_f32_16x16x32_bf16 v[24:27], v[164:167], v[212:215], v[24:27]
	v_mfma_f32_16x16x32_bf16 v[20:23], v[172:175], v[212:215], v[20:23]
	v_mfma_f32_16x16x32_bf16 v[16:19], v[182:185], v[212:215], v[16:19]
	v_mfma_f32_16x16x32_bf16 v[12:15], v[148:151], v[220:223], v[12:15]
	v_mfma_f32_16x16x32_bf16 v[8:11], v[164:167], v[220:223], v[8:11]
	v_lshl_add_u64 v[202:203], v[228:229], 0, s[36:37]
	s_mov_b32 m0, s64
	s_nop 0
	global_load_lds_dwordx4 v[202:203], off
	v_mfma_f32_16x16x32_bf16 v[4:7], v[172:175], v[220:223], v[4:7]
	v_mfma_f32_16x16x32_bf16 v[0:3], v[182:185], v[220:223], v[0:3]
	s_setprio 0
	s_barrier
	s_add_i32 s83, s83, 2
	s_add_u32 s54, s54, 0x100
	s_addc_u32 s55, s55, 0
	s_add_u32 s77, s77, 0x100
	s_addc_u32 s82, s82, 0
	s_cmp_gt_u32 s83, 13
	s_cbranch_scc0 .LBB0_957
	v_lshl_add_u32 v144, s52, 8, v152
	v_ashrrev_i32_e32 v145, 31, v144
	v_lshl_add_u64 v[150:151], v[144:145], 3, s[0:1]
	global_load_dwordx2 v[182:183], v[150:151], off
	global_load_dwordx2 v[184:185], v[150:151], off offset:128
	global_load_dwordx2 v[186:187], v[150:151], off offset:256
	global_load_dwordx2 v[188:189], v[150:151], off offset:384
	global_load_dwordx2 v[190:191], v[150:151], off offset:1024
	global_load_dwordx2 v[192:193], v[150:151], off offset:1152
	global_load_dwordx2 v[194:195], v[150:151], off offset:1280
	global_load_dwordx2 v[196:197], v[150:151], off offset:1408
	s_and_b64 vcc, exec, s[38:39]
	s_cbranch_vccz .LBB0_960
	s_barrier

; #define PG8_STAGE(bufoff, gbase, voff) do { _Pragma("unroll") for (int _i = 0; _i < 2; ++_i) \
;         __builtin_amdgcn_global_load_lds((const unsigned*)((const char*)(gbase) + (voff)[_i]), (PG8_LAS unsigned*)(lds + (bufoff) + ldsw + _i * 8192), 16, 0, 0); } while (0)
; #define PG8_LDA(dst, b, h) do { _Pragma("unroll") for (int m = 0; m < 4; ++m) _Pragma("unroll") for (int k = 0; k < 2; ++k) dst[m][k] = *(const PG8_LAS bf16x8*)(lds + PG8_SA(b, h) + aoff + m * 2048 + k * 1024); } while (0)
; #define PG8_LDB(dst, b, h) do { _Pragma("unroll") for (int n = 0; n < 2; ++n) _Pragma("unroll") for (int k = 0; k < 2; ++k) dst[n][k] = *(const PG8_LAS bf16x8*)(lds + PG8_SB(b, h) + boff + n * 2048 + k * 1024); } while (0)
; #define PG8_WAIT_V(n) asm volatile("s_waitcnt vmcnt(" #n ")" ::: "memory")
; #define PG8_WAIT_L(n) asm volatile("s_waitcnt lgkmcnt(" #n ")" ::: "memory")
; #define PG8_BAR __builtin_amdgcn_s_barrier()
; #define PG8_SCHED __builtin_amdgcn_sched_barrier(0)
; template <class Epi, class Sched, bool ALIGN_EPI = false, bool SP2 = false>
; __device__ __forceinline__ void gemm_phase(PG8_LAS unsigned char* lds, const Gemm g, const Sched& S, const Epi& E) {
;     ...
;         const bool has_next = S.next(ui + 1, nxt);
;         const char* nA = has_next ? (const char*)g.A + (size_t)nxt.pm * tstep : cA; const char* nB = has_next ? (const char*)g.Bt + (size_t)nxt.pn * tstep : cB;
;         for (int t = 0; t < nt; t += 2) {
;             const bool last = (t == nt - 2);
;             const char* a1 = cA + (size_t)(t + 1) * kstep;
;             const char* a2 = last ? nA : cA + (size_t)(t + 2) * kstep; const char* b2 = last ? nB : cB + (size_t)(t + 2) * kstep;
;             const char* a3 = a2 + kstep; const char* b3 = b2 + kstep;
;             if (last && has_next) S.a_ready(nxt);
;             if constexpr (SP2) {
;             PG8_LDB(B0, 0, 0); PG8_LDB(B1, 0, 1); PG8_SCHED; PG8_LDA(At, 0, 0); PG8_STAGE(PG8_SA(1, 1), a1 + hstep, voffA);
;             PG8_WAIT_V(8); PG8_WAIT_L(0); PG8_BAR; PG8_MMA(0, 0, At, B0); PG8_MMA(0, 1, At, B1); PG8_BAR; PG8_SCHED;
;             PG8_LDA(At, 0, 1); PG8_STAGE(PG8_SB(0, 0), b2, voffB); PG8_STAGE(PG8_SB(0, 1), b2 + hstep, voffB); PG8_STAGE(PG8_SA(0, 0), a2, voffA);
;             PG8_WAIT_V(8); PG8_WAIT_L(0); PG8_BAR; PG8_MMA(1, 0, At, B0); PG8_MMA(1, 1, At, B1); PG8_BAR; PG8_SCHED;
.LBB0_1034:
	s_add_u32 s75, s52, 0x100
	s_addc_u32 s76, s53, 0
	s_mov_b32 s77, -2
	s_waitcnt lgkmcnt(0)
	ds_read_b128 v[144:147], v151
	ds_read_b128 v[156:159], v151 offset:1024
	ds_read_b128 v[160:163], v151 offset:2048
	ds_read_b128 v[164:167], v151 offset:3072
	ds_read_b128 v[168:171], v152
	ds_read_b128 v[172:175], v152 offset:1024
	ds_read_b128 v[176:179], v152 offset:2048
	ds_read_b128 v[182:185], v152 offset:3072
	s_add_u32 s52, s50, 0x100
	s_addc_u32 s53, s51, 0
	s_cmp_eq_u32 s77, 40
	s_cselect_b32 s57, s1, s53
	s_cselect_b32 s56, s0, s52
	s_cselect_b32 s55, s49, s76
	s_cselect_b32 s54, s48, s75
	v_lshl_add_u64 v[202:203], s[50:51], 0, v[136:137]
	s_add_i32 m0, s14, 0xc000
	ds_read_b128 v[186:189], v153
	ds_read_b128 v[190:193], v153 offset:1024
	ds_read_b128 v[194:197], v153 offset:2048
	ds_read_b128 v[198:201], v153 offset:3072
	ds_read_b128 v[208:211], v153 offset:4096
	ds_read_b128 v[212:215], v153 offset:5120
	ds_read_b128 v[216:219], v153 offset:6144
	ds_read_b128 v[220:223], v153 offset:7168
	global_load_lds_dwordx4 v[202:203], off
	v_lshl_add_u64 v[202:203], s[50:51], 0, v[138:139]
	s_add_i32 m0, s14, 0xe000
	s_nop 0
	global_load_lds_dwordx4 v[202:203], off
	s_waitcnt vmcnt(8)
	s_waitcnt lgkmcnt(0)
	s_barrier
	s_setprio 1
	s_waitcnt lgkmcnt(0)
	v_mfma_f32_16x16x32_bf16 v[124:127], v[144:147], v[186:189], 0
	v_mfma_f32_16x16x32_bf16 v[120:123], v[160:163], v[186:189], 0
	v_mfma_f32_16x16x32_bf16 v[116:119], v[168:171], v[186:189], 0
	v_mfma_f32_16x16x32_bf16 v[112:115], v[176:179], v[186:189], 0
	v_mfma_f32_16x16x32_bf16 v[108:111], v[144:147], v[194:197], 0
	v_mfma_f32_16x16x32_bf16 v[104:107], v[160:163], v[194:197], 0
	v_mfma_f32_16x16x32_bf16 v[100:103], v[168:171], v[194:197], 0
	v_mfma_f32_16x16x32_bf16 v[96:99], v[176:179], v[194:197], 0
	v_mfma_f32_16x16x32_bf16 v[92:95], v[144:147], v[208:211], 0
	v_mfma_f32_16x16x32_bf16 v[88:91], v[160:163], v[208:211], 0
	v_mfma_f32_16x16x32_bf16 v[84:87], v[168:171], v[208:211], 0
	v_mfma_f32_16x16x32_bf16 v[80:83], v[176:179], v[208:211], 0
	v_mfma_f32_16x16x32_bf16 v[76:79], v[144:147], v[216:219], 0
	v_mfma_f32_16x16x32_bf16 v[72:75], v[160:163], v[216:219], 0
	v_mfma_f32_16x16x32_bf16 v[68:71], v[168:171], v[216:219], 0
	v_mfma_f32_16x16x32_bf16 v[64:67], v[176:179], v[216:219], 0
	s_setprio 0
	s_setprio 1
	v_mfma_f32_16x16x32_bf16 v[124:127], v[156:159], v[190:193], v[124:127]
	v_mfma_f32_16x16x32_bf16 v[120:123], v[164:167], v[190:193], v[120:123]
	v_mfma_f32_16x16x32_bf16 v[116:119], v[172:175], v[190:193], v[116:119]
	v_mfma_f32_16x16x32_bf16 v[112:115], v[182:185], v[190:193], v[112:115]
	v_mfma_f32_16x16x32_bf16 v[108:111], v[156:159], v[198:201], v[108:111]
	v_mfma_f32_16x16x32_bf16 v[104:107], v[164:167], v[198:201], v[104:107]
	v_mfma_f32_16x16x32_bf16 v[100:103], v[172:175], v[198:201], v[100:103]
	v_mfma_f32_16x16x32_bf16 v[96:99], v[182:185], v[198:201], v[96:99]
	v_mfma_f32_16x16x32_bf16 v[92:95], v[156:159], v[212:215], v[92:95]
	v_mfma_f32_16x16x32_bf16 v[88:91], v[164:167], v[212:215], v[88:91]
	v_mfma_f32_16x16x32_bf16 v[84:87], v[172:175], v[212:215], v[84:87]
	v_mfma_f32_16x16x32_bf16 v[80:83], v[182:185], v[212:215], v[80:83]
	v_mfma_f32_16x16x32_bf16 v[76:79], v[156:159], v[220:223], v[76:79]
	v_mfma_f32_16x16x32_bf16 v[72:75], v[164:167], v[220:223], v[72:75]
	v_mfma_f32_16x16x32_bf16 v[68:71], v[172:175], v[220:223], v[68:71]
	v_mfma_f32_16x16x32_bf16 v[64:67], v[182:185], v[220:223], v[64:67]
	s_setprio 0
	s_barrier
	s_add_i32 s50, s61, s3
	v_lshl_add_u64 v[202:203], s[54:55], 0, v[130:131]
	s_mov_b32 m0, s50
	ds_read_b128 v[186:189], v153 offset:16384
	ds_read_b128 v[190:193], v153 offset:17408
	ds_read_b128 v[194:197], v153 offset:18432
	ds_read_b128 v[198:201], v153 offset:19456
	ds_read_b128 v[208:211], v153 offset:20480
	ds_read_b128 v[212:215], v153 offset:21504
	ds_read_b128 v[216:219], v153 offset:22528
	ds_read_b128 v[220:223], v153 offset:23552
	global_load_lds_dwordx4 v[202:203], off
	s_add_i32 m0, s50, 0x2000
	s_add_u32 s50, s54, 0xb0000
	v_lshl_add_u64 v[224:225], s[54:55], 0, v[134:135]
	s_addc_u32 s51, s55, 0
	s_add_i32 s78, s62, s3
	global_load_lds_dwordx4 v[224:225], off
	v_lshl_add_u64 v[226:227], s[50:51], 0, v[130:131]
	s_mov_b32 m0, s78
	global_load_lds_dwordx4 v[226:227], off
	v_lshl_add_u64 v[226:227], s[50:51], 0, v[134:135]
	s_add_i32 m0, s78, 0x2000
	s_nop 0
	global_load_lds_dwordx4 v[226:227], off
	s_waitcnt vmcnt(6)
	s_waitcnt lgkmcnt(0)
	s_barrier
; #define PG8_STAGE(bufoff, gbase, voff) do { _Pragma("unroll") for (int _i = 0; _i < 2; ++_i) \
;         __builtin_amdgcn_global_load_lds((const unsigned*)((const char*)(gbase) + (voff)[_i]), (PG8_LAS unsigned*)(lds + (bufoff) + ldsw + _i * 8192), 16, 0, 0); } while (0)
; #define PG8_LDA(dst, b, h) do { _Pragma("unroll") for (int m = 0; m < 4; ++m) _Pragma("unroll") for (int k = 0; k < 2; ++k) dst[m][k] = *(const PG8_LAS bf16x8*)(lds + PG8_SA(b, h) + aoff + m * 2048 + k * 1024); } while (0)
; #define PG8_LDB(dst, b, h) do { _Pragma("unroll") for (int n = 0; n < 2; ++n) _Pragma("unroll") for (int k = 0; k < 2; ++k) dst[n][k] = *(const PG8_LAS bf16x8*)(lds + PG8_SB(b, h) + boff + n * 2048 + k * 1024); } while (0)
; #define PG8_MMA(ai, bj, At, Bt) do { __builtin_amdgcn_s_setprio(1); _Pragma("unroll") for (int m = 0; m < 4; ++m) _Pragma("unroll") for (int n = 0; n < 2; ++n) _Pragma("unroll") for (int k = 0; k < 2; ++k) \
;         acc[ai][bj][m][n] = __builtin_amdgcn_mfma_f32_16x16x32_bf16(Bt[n][k], At[m][k], acc[ai][bj][m][n], 0, 0, 0); __builtin_amdgcn_s_setprio(0); } while (0)
; #define PG8_WAIT_V(n) asm volatile("s_waitcnt vmcnt(" #n ")" ::: "memory")
; #define PG8_WAIT_L(n) asm volatile("s_waitcnt lgkmcnt(" #n ")" ::: "memory")
; #define PG8_BAR __builtin_amdgcn_s_barrier()
; #define PG8_SCHED __builtin_amdgcn_sched_barrier(0)
; template <class Epi, class Sched, bool ALIGN_EPI = false, bool SP2 = false>
; __device__ __forceinline__ void gemm_phase(PG8_LAS unsigned char* lds, const Gemm g, const Sched& S, const Epi& E) {
;     ...
;             PG8_WAIT_V(8); PG8_WAIT_L(0); PG8_BAR; PG8_MMA(1, 0, At, B0); PG8_MMA(1, 1, At, B1); PG8_BAR; PG8_SCHED;
;             PG8_LDB(B0, 1, 0); PG8_LDB(B1, 1, 1); PG8_SCHED; PG8_LDA(At, 1, 0); PG8_STAGE(PG8_SA(0, 1), a2 + hstep, voffA);
;             PG8_WAIT_V(8); PG8_WAIT_L(0); PG8_BAR; PG8_MMA(0, 0, At, B0); PG8_MMA(0, 1, At, B1); PG8_BAR; PG8_SCHED;
	s_setprio 1
	s_waitcnt lgkmcnt(0)
	v_mfma_f32_16x16x32_bf16 v[60:63], v[144:147], v[186:189], 0
	v_mfma_f32_16x16x32_bf16 v[56:59], v[160:163], v[186:189], 0
	v_mfma_f32_16x16x32_bf16 v[52:55], v[168:171], v[186:189], 0
	v_mfma_f32_16x16x32_bf16 v[48:51], v[176:179], v[186:189], 0
	v_mfma_f32_16x16x32_bf16 v[44:47], v[144:147], v[194:197], 0
	v_mfma_f32_16x16x32_bf16 v[40:43], v[160:163], v[194:197], 0
	v_mfma_f32_16x16x32_bf16 v[36:39], v[168:171], v[194:197], 0
	v_mfma_f32_16x16x32_bf16 v[32:35], v[176:179], v[194:197], 0
	v_mfma_f32_16x16x32_bf16 v[28:31], v[144:147], v[208:211], 0
	v_mfma_f32_16x16x32_bf16 v[24:27], v[160:163], v[208:211], 0
	v_mfma_f32_16x16x32_bf16 v[20:23], v[168:171], v[208:211], 0
	v_mfma_f32_16x16x32_bf16 v[16:19], v[176:179], v[208:211], 0
	v_mfma_f32_16x16x32_bf16 v[12:15], v[144:147], v[216:219], 0
	v_mfma_f32_16x16x32_bf16 v[8:11], v[160:163], v[216:219], 0
	v_lshl_add_u64 v[226:227], s[56:57], 0, v[128:129]
	s_mov_b32 m0, s14
	s_nop 0
	global_load_lds_dwordx4 v[226:227], off
	v_mfma_f32_16x16x32_bf16 v[4:7], v[168:171], v[216:219], 0
	v_mfma_f32_16x16x32_bf16 v[0:3], v[176:179], v[216:219], 0
	s_setprio 0
	s_setprio 1
	v_mfma_f32_16x16x32_bf16 v[60:63], v[156:159], v[190:193], v[60:63]
	v_mfma_f32_16x16x32_bf16 v[56:59], v[164:167], v[190:193], v[56:59]
	v_mfma_f32_16x16x32_bf16 v[52:55], v[172:175], v[190:193], v[52:55]
	v_mfma_f32_16x16x32_bf16 v[48:51], v[182:185], v[190:193], v[48:51]
	v_mfma_f32_16x16x32_bf16 v[44:47], v[156:159], v[198:201], v[44:47]
	v_mfma_f32_16x16x32_bf16 v[40:43], v[164:167], v[198:201], v[40:43]
	v_mfma_f32_16x16x32_bf16 v[36:39], v[172:175], v[198:201], v[36:39]
	v_mfma_f32_16x16x32_bf16 v[32:35], v[182:185], v[198:201], v[32:35]
	v_mfma_f32_16x16x32_bf16 v[28:31], v[156:159], v[212:215], v[28:31]
	v_mfma_f32_16x16x32_bf16 v[24:27], v[164:167], v[212:215], v[24:27]
	v_mfma_f32_16x16x32_bf16 v[20:23], v[172:175], v[212:215], v[20:23]
	v_mfma_f32_16x16x32_bf16 v[16:19], v[182:185], v[212:215], v[16:19]
	v_mfma_f32_16x16x32_bf16 v[12:15], v[156:159], v[220:223], v[12:15]
	v_mfma_f32_16x16x32_bf16 v[8:11], v[164:167], v[220:223], v[8:11]
	v_lshl_add_u64 v[228:229], s[56:57], 0, v[132:133]
	s_mov_b32 m0, s15
	s_nop 0
	global_load_lds_dwordx4 v[228:229], off
	v_mfma_f32_16x16x32_bf16 v[4:7], v[172:175], v[220:223], v[4:7]
	v_mfma_f32_16x16x32_bf16 v[0:3], v[182:185], v[220:223], v[0:3]
	s_setprio 0
	s_barrier
	s_add_i32 s78, 0, 0x18000
	v_add_u32_e32 v155, s78, v149
	s_add_i32 s79, 0, 0x1c000
	ds_read_b128 v[144:147], v155
	ds_read_b128 v[156:159], v155 offset:1024
	ds_read_b128 v[160:163], v155 offset:2048
	ds_read_b128 v[164:167], v155 offset:3072
	v_add_u32_e32 v155, s79, v149
	ds_read_b128 v[168:171], v155
	ds_read_b128 v[172:175], v155 offset:1024
	ds_read_b128 v[176:179], v155 offset:2048
	ds_read_b128 v[182:185], v155 offset:3072
	s_add_u32 s50, s56, 0xb0000
	s_addc_u32 s51, s57, 0
	s_mov_b32 m0, s33
	v_lshl_add_u64 v[230:231], s[50:51], 0, v[128:129]
	ds_read_b128 v[186:189], v153 offset:32768
	ds_read_b128 v[190:193], v153 offset:33792
	ds_read_b128 v[194:197], v153 offset:34816
	ds_read_b128 v[198:201], v153 offset:35840
	ds_read_b128 v[208:211], v153 offset:36864
	ds_read_b128 v[212:215], v153 offset:37888
	ds_read_b128 v[216:219], v153 offset:38912
	ds_read_b128 v[220:223], v153 offset:39936
	global_load_lds_dwordx4 v[230:231], off
	v_lshl_add_u64 v[230:231], s[50:51], 0, v[132:133]
	s_mov_b32 m0, s34
	s_nop 0
	global_load_lds_dwordx4 v[230:231], off
	s_waitcnt vmcnt(8)
	s_waitcnt lgkmcnt(0)
	s_barrier
	s_setprio 1
	s_waitcnt lgkmcnt(0)
	v_mfma_f32_16x16x32_bf16 v[124:127], v[144:147], v[186:189], v[124:127]
	v_mfma_f32_16x16x32_bf16 v[120:123], v[160:163], v[186:189], v[120:123]
	v_mfma_f32_16x16x32_bf16 v[116:119], v[168:171], v[186:189], v[116:119]
	v_mfma_f32_16x16x32_bf16 v[112:115], v[176:179], v[186:189], v[112:115]
	v_mfma_f32_16x16x32_bf16 v[108:111], v[144:147], v[194:197], v[108:111]
	v_mfma_f32_16x16x32_bf16 v[104:107], v[160:163], v[194:197], v[104:107]
	v_mfma_f32_16x16x32_bf16 v[100:103], v[168:171], v[194:197], v[100:103]
	v_mfma_f32_16x16x32_bf16 v[96:99], v[176:179], v[194:197], v[96:99]
	v_mfma_f32_16x16x32_bf16 v[92:95], v[144:147], v[208:211], v[92:95]
	v_mfma_f32_16x16x32_bf16 v[88:91], v[160:163], v[208:211], v[88:91]
	v_mfma_f32_16x16x32_bf16 v[84:87], v[168:171], v[208:211], v[84:87]
	v_mfma_f32_16x16x32_bf16 v[80:83], v[176:179], v[208:211], v[80:83]
	v_mfma_f32_16x16x32_bf16 v[76:79], v[144:147], v[216:219], v[76:79]
	v_mfma_f32_16x16x32_bf16 v[72:75], v[160:163], v[216:219], v[72:75]
	v_mfma_f32_16x16x32_bf16 v[68:71], v[168:171], v[216:219], v[68:71]
	v_mfma_f32_16x16x32_bf16 v[64:67], v[176:179], v[216:219], v[64:67]
	s_setprio 0
	s_setprio 1
	v_mfma_f32_16x16x32_bf16 v[124:127], v[156:159], v[190:193], v[124:127]
	v_mfma_f32_16x16x32_bf16 v[120:123], v[164:167], v[190:193], v[120:123]
	v_mfma_f32_16x16x32_bf16 v[116:119], v[172:175], v[190:193], v[116:119]
	v_mfma_f32_16x16x32_bf16 v[112:115], v[182:185], v[190:193], v[112:115]
	v_mfma_f32_16x16x32_bf16 v[108:111], v[156:159], v[198:201], v[108:111]
	v_mfma_f32_16x16x32_bf16 v[104:107], v[164:167], v[198:201], v[104:107]
	v_mfma_f32_16x16x32_bf16 v[100:103], v[172:175], v[198:201], v[100:103]
	v_mfma_f32_16x16x32_bf16 v[96:99], v[182:185], v[198:201], v[96:99]
	v_mfma_f32_16x16x32_bf16 v[92:95], v[156:159], v[212:215], v[92:95]
	v_mfma_f32_16x16x32_bf16 v[88:91], v[164:167], v[212:215], v[88:91]
	v_mfma_f32_16x16x32_bf16 v[84:87], v[172:175], v[212:215], v[84:87]
	v_mfma_f32_16x16x32_bf16 v[80:83], v[182:185], v[212:215], v[80:83]
	v_mfma_f32_16x16x32_bf16 v[76:79], v[156:159], v[220:223], v[76:79]
	v_mfma_f32_16x16x32_bf16 v[72:75], v[164:167], v[220:223], v[72:75]
	v_mfma_f32_16x16x32_bf16 v[68:71], v[172:175], v[220:223], v[68:71]
	v_mfma_f32_16x16x32_bf16 v[64:67], v[182:185], v[220:223], v[64:67]
	s_setprio 0
	s_barrier
; #define PG8_STAGE(bufoff, gbase, voff) do { _Pragma("unroll") for (int _i = 0; _i < 2; ++_i) \
;         __builtin_amdgcn_global_load_lds((const unsigned*)((const char*)(gbase) + (voff)[_i]), (PG8_LAS unsigned*)(lds + (bufoff) + ldsw + _i * 8192), 16, 0, 0); } while (0)
; #define PG8_LDA(dst, b, h) do { _Pragma("unroll") for (int m = 0; m < 4; ++m) _Pragma("unroll") for (int k = 0; k < 2; ++k) dst[m][k] = *(const PG8_LAS bf16x8*)(lds + PG8_SA(b, h) + aoff + m * 2048 + k * 1024); } while (0)
; #define PG8_LDB(dst, b, h) do { _Pragma("unroll") for (int n = 0; n < 2; ++n) _Pragma("unroll") for (int k = 0; k < 2; ++k) dst[n][k] = *(const PG8_LAS bf16x8*)(lds + PG8_SB(b, h) + boff + n * 2048 + k * 1024); } while (0)
; #define PG8_BAR __builtin_amdgcn_s_barrier()
; template <class Epi, class Sched, bool ALIGN_EPI = false, bool SP2 = false>
; __device__ __forceinline__ void gemm_phase(PG8_LAS unsigned char* lds, const Gemm g, const Sched& S, const Epi& E) {
;     ...
;             const bool last = (t == nt - 2);
;             const char* a1 = cA + (size_t)(t + 1) * kstep;
;             const char* a2 = last ? nA : cA + (size_t)(t + 2) * kstep; const char* b2 = last ? nB : cB + (size_t)(t + 2) * kstep;
;             const char* a3 = a2 + kstep; const char* b3 = b2 + kstep;
;             if (last && has_next) S.a_ready(nxt);
;             if constexpr (SP2) {
;             PG8_LDB(B0, 0, 0); PG8_LDB(B1, 0, 1); PG8_SCHED; PG8_LDA(At, 0, 0); PG8_STAGE(PG8_SA(1, 1), a1 + hstep, voffA);
;             PG8_WAIT_V(8); PG8_WAIT_L(0); PG8_BAR; PG8_MMA(0, 0, At, B0); PG8_MMA(0, 1, At, B1); PG8_BAR; PG8_SCHED;
;             PG8_LDA(At, 0, 1); PG8_STAGE(PG8_SB(0, 0), b2, voffB); PG8_STAGE(PG8_SB(0, 1), b2 + hstep, voffB); PG8_STAGE(PG8_SA(0, 0), a2, voffA);
;             PG8_WAIT_V(8); PG8_WAIT_L(0); PG8_BAR; PG8_MMA(1, 0, At, B0); PG8_MMA(1, 1, At, B1); PG8_BAR; PG8_SCHED;
;             PG8_LDB(B0, 1, 0); PG8_LDB(B1, 1, 1); PG8_SCHED; PG8_LDA(At, 1, 0); PG8_STAGE(PG8_SA(0, 1), a2 + hstep, voffA);
;             PG8_WAIT_V(8); PG8_WAIT_L(0); PG8_BAR; PG8_MMA(0, 0, At, B0); PG8_MMA(0, 1, At, B1); PG8_BAR; PG8_SCHED;
;             PG8_LDA(At, 1, 1); PG8_STAGE(PG8_SB(1, 0), b3, voffB); PG8_STAGE(PG8_SB(1, 1), b3 + hstep, voffB); PG8_STAGE(PG8_SA(1, 0), a3, voffA);
;             PG8_WAIT_V(8); PG8_WAIT_L(0); PG8_BAR; PG8_MMA(1, 0, At, B0); PG8_MMA(1, 1, At, B1); PG8_BAR; PG8_SCHED;
	s_add_i32 s50, s78, s3
	v_lshl_add_u64 v[202:203], v[202:203], 0, s[42:43]
	s_mov_b32 m0, s50
	ds_read_b128 v[186:189], v153 offset:49152
	ds_read_b128 v[190:193], v153 offset:50176
	ds_read_b128 v[194:197], v153 offset:51200
	ds_read_b128 v[198:201], v153 offset:52224
	ds_read_b128 v[208:211], v153 offset:53248
	ds_read_b128 v[212:215], v153 offset:54272
	ds_read_b128 v[216:219], v153 offset:55296
	ds_read_b128 v[220:223], v153 offset:56320
	global_load_lds_dwordx4 v[202:203], off
	s_add_i32 m0, s50, 0x2000
	s_add_u32 s50, s54, 0xb0080
	v_lshl_add_u64 v[202:203], v[224:225], 0, s[42:43]
	s_addc_u32 s51, s55, 0
	s_add_i32 s54, s79, s3
	global_load_lds_dwordx4 v[202:203], off
	v_lshl_add_u64 v[202:203], s[50:51], 0, v[130:131]
	s_mov_b32 m0, s54
	s_nop 0
	global_load_lds_dwordx4 v[202:203], off
	v_lshl_add_u64 v[202:203], s[50:51], 0, v[134:135]
	s_add_i32 m0, s54, 0x2000
	s_nop 0
	global_load_lds_dwordx4 v[202:203], off
	s_waitcnt vmcnt(6)
	s_waitcnt lgkmcnt(0)
	s_barrier
	s_setprio 1
	s_waitcnt lgkmcnt(0)
	v_mfma_f32_16x16x32_bf16 v[60:63], v[144:147], v[186:189], v[60:63]
	v_mfma_f32_16x16x32_bf16 v[56:59], v[160:163], v[186:189], v[56:59]
	v_mfma_f32_16x16x32_bf16 v[52:55], v[168:171], v[186:189], v[52:55]
	v_mfma_f32_16x16x32_bf16 v[48:51], v[176:179], v[186:189], v[48:51]
	v_mfma_f32_16x16x32_bf16 v[44:47], v[144:147], v[194:197], v[44:47]
	v_mfma_f32_16x16x32_bf16 v[40:43], v[160:163], v[194:197], v[40:43]
	v_mfma_f32_16x16x32_bf16 v[36:39], v[168:171], v[194:197], v[36:39]
	v_mfma_f32_16x16x32_bf16 v[32:35], v[176:179], v[194:197], v[32:35]
	v_mfma_f32_16x16x32_bf16 v[28:31], v[144:147], v[208:211], v[28:31]
	v_mfma_f32_16x16x32_bf16 v[24:27], v[160:163], v[208:211], v[24:27]
	v_mfma_f32_16x16x32_bf16 v[20:23], v[168:171], v[208:211], v[20:23]
	v_mfma_f32_16x16x32_bf16 v[16:19], v[176:179], v[208:211], v[16:19]
	v_mfma_f32_16x16x32_bf16 v[12:15], v[144:147], v[216:219], v[12:15]
	v_mfma_f32_16x16x32_bf16 v[8:11], v[160:163], v[216:219], v[8:11]
	v_lshl_add_u64 v[202:203], v[226:227], 0, s[42:43]
	s_mov_b32 m0, s59
	s_nop 0
	global_load_lds_dwordx4 v[202:203], off
	v_mfma_f32_16x16x32_bf16 v[4:7], v[168:171], v[216:219], v[4:7]
	v_mfma_f32_16x16x32_bf16 v[0:3], v[176:179], v[216:219], v[0:3]
	s_setprio 0
	s_setprio 1
	v_mfma_f32_16x16x32_bf16 v[60:63], v[156:159], v[190:193], v[60:63]
	v_mfma_f32_16x16x32_bf16 v[56:59], v[164:167], v[190:193], v[56:59]
	v_mfma_f32_16x16x32_bf16 v[52:55], v[172:175], v[190:193], v[52:55]
	v_mfma_f32_16x16x32_bf16 v[48:51], v[182:185], v[190:193], v[48:51]
	v_mfma_f32_16x16x32_bf16 v[44:47], v[156:159], v[198:201], v[44:47]
	v_mfma_f32_16x16x32_bf16 v[40:43], v[164:167], v[198:201], v[40:43]
	v_mfma_f32_16x16x32_bf16 v[36:39], v[172:175], v[198:201], v[36:39]
	v_mfma_f32_16x16x32_bf16 v[32:35], v[182:185], v[198:201], v[32:35]
	v_mfma_f32_16x16x32_bf16 v[28:31], v[156:159], v[212:215], v[28:31]
	v_mfma_f32_16x16x32_bf16 v[24:27], v[164:167], v[212:215], v[24:27]
	v_mfma_f32_16x16x32_bf16 v[20:23], v[172:175], v[212:215], v[20:23]
	v_mfma_f32_16x16x32_bf16 v[16:19], v[182:185], v[212:215], v[16:19]
	v_mfma_f32_16x16x32_bf16 v[12:15], v[156:159], v[220:223], v[12:15]
	v_mfma_f32_16x16x32_bf16 v[8:11], v[164:167], v[220:223], v[8:11]
	v_lshl_add_u64 v[202:203], v[228:229], 0, s[42:43]
	s_mov_b32 m0, s60
	s_nop 0
	global_load_lds_dwordx4 v[202:203], off
	v_mfma_f32_16x16x32_bf16 v[4:7], v[172:175], v[220:223], v[4:7]
	v_mfma_f32_16x16x32_bf16 v[0:3], v[182:185], v[220:223], v[0:3]
	s_setprio 0
	s_barrier
	s_add_i32 s77, s77, 2
	s_add_u32 s75, s75, 0x100
	s_addc_u32 s76, s76, 0
	s_mov_b64 s[50:51], s[52:53]
.LBB0_1035:
	ds_read_b128 v[144:147], v151
	ds_read_b128 v[156:159], v151 offset:1024
	ds_read_b128 v[160:163], v151 offset:2048
	ds_read_b128 v[164:167], v151 offset:3072
	ds_read_b128 v[168:171], v152
	ds_read_b128 v[172:175], v152 offset:1024
	ds_read_b128 v[176:179], v152 offset:2048
	ds_read_b128 v[182:185], v152 offset:3072
	s_add_u32 s52, s50, 0x100
	s_addc_u32 s53, s51, 0
	s_cmp_eq_u32 s77, 40
	s_cselect_b32 s57, s1, s53
	s_cselect_b32 s56, s0, s52
	s_cselect_b32 s55, s49, s76
	s_cselect_b32 s54, s48, s75
	v_lshl_add_u64 v[202:203], s[50:51], 0, v[136:137]
	s_add_i32 m0, s14, 0xc000
	ds_read_b128 v[186:189], v153
	ds_read_b128 v[190:193], v153 offset:1024
	ds_read_b128 v[194:197], v153 offset:2048
	ds_read_b128 v[198:201], v153 offset:3072
	ds_read_b128 v[208:211], v153 offset:4096
	ds_read_b128 v[212:215], v153 offset:5120
	ds_read_b128 v[216:219], v153 offset:6144
	ds_read_b128 v[220:223], v153 offset:7168
	global_load_lds_dwordx4 v[202:203], off
	v_lshl_add_u64 v[202:203], s[50:51], 0, v[138:139]
	s_add_i32 m0, s14, 0xe000
	s_nop 0
	global_load_lds_dwordx4 v[202:203], off
	s_waitcnt vmcnt(8)
	s_waitcnt lgkmcnt(0)
	s_barrier
; #define PG8_STAGE(bufoff, gbase, voff) do { _Pragma("unroll") for (int _i = 0; _i < 2; ++_i) \
;         __builtin_amdgcn_global_load_lds((const unsigned*)((const char*)(gbase) + (voff)[_i]), (PG8_LAS unsigned*)(lds + (bufoff) + ldsw + _i * 8192), 16, 0, 0); } while (0)
; #define PG8_LDA(dst, b, h) do { _Pragma("unroll") for (int m = 0; m < 4; ++m) _Pragma("unroll") for (int k = 0; k < 2; ++k) dst[m][k] = *(const PG8_LAS bf16x8*)(lds + PG8_SA(b, h) + aoff + m * 2048 + k * 1024); } while (0)
; #define PG8_MMA(ai, bj, At, Bt) do { __builtin_amdgcn_s_setprio(1); _Pragma("unroll") for (int m = 0; m < 4; ++m) _Pragma("unroll") for (int n = 0; n < 2; ++n) _Pragma("unroll") for (int k = 0; k < 2; ++k) \
;         acc[ai][bj][m][n] = __builtin_amdgcn_mfma_f32_16x16x32_bf16(Bt[n][k], At[m][k], acc[ai][bj][m][n], 0, 0, 0); __builtin_amdgcn_s_setprio(0); } while (0)
; #define PG8_WAIT_V(n) asm volatile("s_waitcnt vmcnt(" #n ")" ::: "memory")
; #define PG8_WAIT_L(n) asm volatile("s_waitcnt lgkmcnt(" #n ")" ::: "memory")
; #define PG8_BAR __builtin_amdgcn_s_barrier()
; #define PG8_SCHED __builtin_amdgcn_sched_barrier(0)
; template <class Epi, class Sched, bool ALIGN_EPI = false, bool SP2 = false>
; __device__ __forceinline__ void gemm_phase(PG8_LAS unsigned char* lds, const Gemm g, const Sched& S, const Epi& E) {
;     ...
;             PG8_WAIT_V(8); PG8_WAIT_L(0); PG8_BAR; PG8_MMA(0, 0, At, B0); PG8_MMA(0, 1, At, B1); PG8_BAR; PG8_SCHED;
;             PG8_LDA(At, 0, 1); PG8_STAGE(PG8_SB(0, 0), b2, voffB); PG8_STAGE(PG8_SB(0, 1), b2 + hstep, voffB); PG8_STAGE(PG8_SA(0, 0), a2, voffA);
;             PG8_WAIT_V(8); PG8_WAIT_L(0); PG8_BAR; PG8_MMA(1, 0, At, B0); PG8_MMA(1, 1, At, B1); PG8_BAR; PG8_SCHED;
	s_setprio 1
	s_waitcnt lgkmcnt(0)
	v_mfma_f32_16x16x32_bf16 v[124:127], v[144:147], v[186:189], v[124:127]
	v_mfma_f32_16x16x32_bf16 v[120:123], v[160:163], v[186:189], v[120:123]
	v_mfma_f32_16x16x32_bf16 v[116:119], v[168:171], v[186:189], v[116:119]
	v_mfma_f32_16x16x32_bf16 v[112:115], v[176:179], v[186:189], v[112:115]
	v_mfma_f32_16x16x32_bf16 v[108:111], v[144:147], v[194:197], v[108:111]
	v_mfma_f32_16x16x32_bf16 v[104:107], v[160:163], v[194:197], v[104:107]
	v_mfma_f32_16x16x32_bf16 v[100:103], v[168:171], v[194:197], v[100:103]
	v_mfma_f32_16x16x32_bf16 v[96:99], v[176:179], v[194:197], v[96:99]
	v_mfma_f32_16x16x32_bf16 v[92:95], v[144:147], v[208:211], v[92:95]
	v_mfma_f32_16x16x32_bf16 v[88:91], v[160:163], v[208:211], v[88:91]
	v_mfma_f32_16x16x32_bf16 v[84:87], v[168:171], v[208:211], v[84:87]
	v_mfma_f32_16x16x32_bf16 v[80:83], v[176:179], v[208:211], v[80:83]
	v_mfma_f32_16x16x32_bf16 v[76:79], v[144:147], v[216:219], v[76:79]
	v_mfma_f32_16x16x32_bf16 v[72:75], v[160:163], v[216:219], v[72:75]
	v_mfma_f32_16x16x32_bf16 v[68:71], v[168:171], v[216:219], v[68:71]
	v_mfma_f32_16x16x32_bf16 v[64:67], v[176:179], v[216:219], v[64:67]
	s_setprio 0
	s_setprio 1
	v_mfma_f32_16x16x32_bf16 v[124:127], v[156:159], v[190:193], v[124:127]
	v_mfma_f32_16x16x32_bf16 v[120:123], v[164:167], v[190:193], v[120:123]
	v_mfma_f32_16x16x32_bf16 v[116:119], v[172:175], v[190:193], v[116:119]
	v_mfma_f32_16x16x32_bf16 v[112:115], v[182:185], v[190:193], v[112:115]
	v_mfma_f32_16x16x32_bf16 v[108:111], v[156:159], v[198:201], v[108:111]
	v_mfma_f32_16x16x32_bf16 v[104:107], v[164:167], v[198:201], v[104:107]
	v_mfma_f32_16x16x32_bf16 v[100:103], v[172:175], v[198:201], v[100:103]
	v_mfma_f32_16x16x32_bf16 v[96:99], v[182:185], v[198:201], v[96:99]
	v_mfma_f32_16x16x32_bf16 v[92:95], v[156:159], v[212:215], v[92:95]
	v_mfma_f32_16x16x32_bf16 v[88:91], v[164:167], v[212:215], v[88:91]
	v_mfma_f32_16x16x32_bf16 v[84:87], v[172:175], v[212:215], v[84:87]
	v_mfma_f32_16x16x32_bf16 v[80:83], v[182:185], v[212:215], v[80:83]
	v_mfma_f32_16x16x32_bf16 v[76:79], v[156:159], v[220:223], v[76:79]
	v_mfma_f32_16x16x32_bf16 v[72:75], v[164:167], v[220:223], v[72:75]
	v_mfma_f32_16x16x32_bf16 v[68:71], v[172:175], v[220:223], v[68:71]
	v_mfma_f32_16x16x32_bf16 v[64:67], v[182:185], v[220:223], v[64:67]
	s_setprio 0
	s_barrier
	s_add_i32 s50, s61, s3
	v_lshl_add_u64 v[202:203], s[54:55], 0, v[130:131]
	s_mov_b32 m0, s50
	ds_read_b128 v[186:189], v153 offset:16384
	ds_read_b128 v[190:193], v153 offset:17408
	ds_read_b128 v[194:197], v153 offset:18432
	ds_read_b128 v[198:201], v153 offset:19456
	ds_read_b128 v[208:211], v153 offset:20480
	ds_read_b128 v[212:215], v153 offset:21504
	ds_read_b128 v[216:219], v153 offset:22528
	ds_read_b128 v[220:223], v153 offset:23552
	global_load_lds_dwordx4 v[202:203], off
	s_add_i32 m0, s50, 0x2000
	s_add_u32 s50, s54, 0xb0000
	v_lshl_add_u64 v[224:225], s[54:55], 0, v[134:135]
	s_addc_u32 s51, s55, 0
	s_add_i32 s78, s62, s3
	global_load_lds_dwordx4 v[224:225], off
	v_lshl_add_u64 v[226:227], s[50:51], 0, v[130:131]
	s_mov_b32 m0, s78
	global_load_lds_dwordx4 v[226:227], off
	v_lshl_add_u64 v[226:227], s[50:51], 0, v[134:135]
	s_add_i32 m0, s78, 0x2000
	s_nop 0
	global_load_lds_dwordx4 v[226:227], off
	s_waitcnt vmcnt(6)
	s_waitcnt lgkmcnt(0)
	s_barrier
	s_setprio 1
	s_waitcnt lgkmcnt(0)
	v_mfma_f32_16x16x32_bf16 v[60:63], v[144:147], v[186:189], v[60:63]
	v_mfma_f32_16x16x32_bf16 v[56:59], v[160:163], v[186:189], v[56:59]
	v_mfma_f32_16x16x32_bf16 v[52:55], v[168:171], v[186:189], v[52:55]
	v_mfma_f32_16x16x32_bf16 v[48:51], v[176:179], v[186:189], v[48:51]
	v_mfma_f32_16x16x32_bf16 v[44:47], v[144:147], v[194:197], v[44:47]
	v_mfma_f32_16x16x32_bf16 v[40:43], v[160:163], v[194:197], v[40:43]
	v_mfma_f32_16x16x32_bf16 v[36:39], v[168:171], v[194:197], v[36:39]
	v_mfma_f32_16x16x32_bf16 v[32:35], v[176:179], v[194:197], v[32:35]
	v_mfma_f32_16x16x32_bf16 v[28:31], v[144:147], v[208:211], v[28:31]
	v_mfma_f32_16x16x32_bf16 v[24:27], v[160:163], v[208:211], v[24:27]
	v_mfma_f32_16x16x32_bf16 v[20:23], v[168:171], v[208:211], v[20:23]
	v_mfma_f32_16x16x32_bf16 v[16:19], v[176:179], v[208:211], v[16:19]
	v_mfma_f32_16x16x32_bf16 v[12:15], v[144:147], v[216:219], v[12:15]
	v_mfma_f32_16x16x32_bf16 v[8:11], v[160:163], v[216:219], v[8:11]
	v_lshl_add_u64 v[226:227], s[56:57], 0, v[128:129]
	s_mov_b32 m0, s14
	s_nop 0
	global_load_lds_dwordx4 v[226:227], off
	v_mfma_f32_16x16x32_bf16 v[4:7], v[168:171], v[216:219], v[4:7]
	v_mfma_f32_16x16x32_bf16 v[0:3], v[176:179], v[216:219], v[0:3]
	s_setprio 0
	s_setprio 1
	v_mfma_f32_16x16x32_bf16 v[60:63], v[156:159], v[190:193], v[60:63]
	v_mfma_f32_16x16x32_bf16 v[56:59], v[164:167], v[190:193], v[56:59]
	v_mfma_f32_16x16x32_bf16 v[52:55], v[172:175], v[190:193], v[52:55]
	v_mfma_f32_16x16x32_bf16 v[48:51], v[182:185], v[190:193], v[48:51]
	v_mfma_f32_16x16x32_bf16 v[44:47], v[156:159], v[198:201], v[44:47]
	v_mfma_f32_16x16x32_bf16 v[40:43], v[164:167], v[198:201], v[40:43]
	v_mfma_f32_16x16x32_bf16 v[36:39], v[172:175], v[198:201], v[36:39]
	v_mfma_f32_16x16x32_bf16 v[32:35], v[182:185], v[198:201], v[32:35]
	v_mfma_f32_16x16x32_bf16 v[28:31], v[156:159], v[212:215], v[28:31]
	v_mfma_f32_16x16x32_bf16 v[24:27], v[164:167], v[212:215], v[24:27]
	v_mfma_f32_16x16x32_bf16 v[20:23], v[172:175], v[212:215], v[20:23]
	v_mfma_f32_16x16x32_bf16 v[16:19], v[182:185], v[212:215], v[16:19]
	v_mfma_f32_16x16x32_bf16 v[12:15], v[156:159], v[220:223], v[12:15]
	v_mfma_f32_16x16x32_bf16 v[8:11], v[164:167], v[220:223], v[8:11]
	v_lshl_add_u64 v[228:229], s[56:57], 0, v[132:133]
	s_mov_b32 m0, s15
	s_nop 0
	global_load_lds_dwordx4 v[228:229], off
	v_mfma_f32_16x16x32_bf16 v[4:7], v[172:175], v[220:223], v[4:7]
	v_mfma_f32_16x16x32_bf16 v[0:3], v[182:185], v[220:223], v[0:3]
	s_setprio 0
	s_barrier
; #define PG8_STAGE(bufoff, gbase, voff) do { _Pragma("unroll") for (int _i = 0; _i < 2; ++_i) \
;         __builtin_amdgcn_global_load_lds((const unsigned*)((const char*)(gbase) + (voff)[_i]), (PG8_LAS unsigned*)(lds + (bufoff) + ldsw + _i * 8192), 16, 0, 0); } while (0)
; #define PG8_LDA(dst, b, h) do { _Pragma("unroll") for (int m = 0; m < 4; ++m) _Pragma("unroll") for (int k = 0; k < 2; ++k) dst[m][k] = *(const PG8_LAS bf16x8*)(lds + PG8_SA(b, h) + aoff + m * 2048 + k * 1024); } while (0)
; #define PG8_LDB(dst, b, h) do { _Pragma("unroll") for (int n = 0; n < 2; ++n) _Pragma("unroll") for (int k = 0; k < 2; ++k) dst[n][k] = *(const PG8_LAS bf16x8*)(lds + PG8_SB(b, h) + boff + n * 2048 + k * 1024); } while (0)
; #define PG8_MMA(ai, bj, At, Bt) do { __builtin_amdgcn_s_setprio(1); _Pragma("unroll") for (int m = 0; m < 4; ++m) _Pragma("unroll") for (int n = 0; n < 2; ++n) _Pragma("unroll") for (int k = 0; k < 2; ++k) \
;         acc[ai][bj][m][n] = __builtin_amdgcn_mfma_f32_16x16x32_bf16(Bt[n][k], At[m][k], acc[ai][bj][m][n], 0, 0, 0); __builtin_amdgcn_s_setprio(0); } while (0)
; #define PG8_WAIT_V(n) asm volatile("s_waitcnt vmcnt(" #n ")" ::: "memory")
; #define PG8_WAIT_L(n) asm volatile("s_waitcnt lgkmcnt(" #n ")" ::: "memory")
; #define PG8_BAR __builtin_amdgcn_s_barrier()
; #define PG8_SCHED __builtin_amdgcn_sched_barrier(0)
; template <class Epi, class Sched, bool ALIGN_EPI = false, bool SP2 = false>
; __device__ __forceinline__ void gemm_phase(PG8_LAS unsigned char* lds, const Gemm g, const Sched& S, const Epi& E) {
;     ...
;             PG8_LDB(B0, 1, 0); PG8_LDB(B1, 1, 1); PG8_SCHED; PG8_LDA(At, 1, 0); PG8_STAGE(PG8_SA(0, 1), a2 + hstep, voffA);
;             PG8_WAIT_V(8); PG8_WAIT_L(0); PG8_BAR; PG8_MMA(0, 0, At, B0); PG8_MMA(0, 1, At, B1); PG8_BAR; PG8_SCHED;
	s_add_i32 s78, 0, 0x18000
	v_add_u32_e32 v155, s78, v149
	s_add_i32 s79, 0, 0x1c000
	ds_read_b128 v[144:147], v155
	ds_read_b128 v[156:159], v155 offset:1024
	ds_read_b128 v[160:163], v155 offset:2048
	ds_read_b128 v[164:167], v155 offset:3072
	v_add_u32_e32 v155, s79, v149
	ds_read_b128 v[168:171], v155
	ds_read_b128 v[172:175], v155 offset:1024
	ds_read_b128 v[176:179], v155 offset:2048
	ds_read_b128 v[182:185], v155 offset:3072
	s_add_u32 s50, s56, 0xb0000
	s_addc_u32 s51, s57, 0
	s_mov_b32 m0, s33
	v_lshl_add_u64 v[230:231], s[50:51], 0, v[128:129]
	ds_read_b128 v[186:189], v153 offset:32768
	ds_read_b128 v[190:193], v153 offset:33792
	ds_read_b128 v[194:197], v153 offset:34816
	ds_read_b128 v[198:201], v153 offset:35840
	ds_read_b128 v[208:211], v153 offset:36864
	ds_read_b128 v[212:215], v153 offset:37888
	ds_read_b128 v[216:219], v153 offset:38912
	ds_read_b128 v[220:223], v153 offset:39936
	global_load_lds_dwordx4 v[230:231], off
	v_lshl_add_u64 v[230:231], s[50:51], 0, v[132:133]
	s_mov_b32 m0, s34
	s_nop 0
	global_load_lds_dwordx4 v[230:231], off
	s_waitcnt vmcnt(8)
	s_waitcnt lgkmcnt(0)
	s_barrier
	s_setprio 1
	s_waitcnt lgkmcnt(0)
	v_mfma_f32_16x16x32_bf16 v[124:127], v[144:147], v[186:189], v[124:127]
	v_mfma_f32_16x16x32_bf16 v[120:123], v[160:163], v[186:189], v[120:123]
	v_mfma_f32_16x16x32_bf16 v[116:119], v[168:171], v[186:189], v[116:119]
	v_mfma_f32_16x16x32_bf16 v[112:115], v[176:179], v[186:189], v[112:115]
	v_mfma_f32_16x16x32_bf16 v[108:111], v[144:147], v[194:197], v[108:111]
	v_mfma_f32_16x16x32_bf16 v[104:107], v[160:163], v[194:197], v[104:107]
	v_mfma_f32_16x16x32_bf16 v[100:103], v[168:171], v[194:197], v[100:103]
	v_mfma_f32_16x16x32_bf16 v[96:99], v[176:179], v[194:197], v[96:99]
	v_mfma_f32_16x16x32_bf16 v[92:95], v[144:147], v[208:211], v[92:95]
	v_mfma_f32_16x16x32_bf16 v[88:91], v[160:163], v[208:211], v[88:91]
	v_mfma_f32_16x16x32_bf16 v[84:87], v[168:171], v[208:211], v[84:87]
	v_mfma_f32_16x16x32_bf16 v[80:83], v[176:179], v[208:211], v[80:83]
	v_mfma_f32_16x16x32_bf16 v[76:79], v[144:147], v[216:219], v[76:79]
	v_mfma_f32_16x16x32_bf16 v[72:75], v[160:163], v[216:219], v[72:75]
	v_mfma_f32_16x16x32_bf16 v[68:71], v[168:171], v[216:219], v[68:71]
	v_mfma_f32_16x16x32_bf16 v[64:67], v[176:179], v[216:219], v[64:67]
	s_setprio 0
	s_setprio 1
	v_mfma_f32_16x16x32_bf16 v[124:127], v[156:159], v[190:193], v[124:127]
	v_mfma_f32_16x16x32_bf16 v[120:123], v[164:167], v[190:193], v[120:123]
	v_mfma_f32_16x16x32_bf16 v[116:119], v[172:175], v[190:193], v[116:119]
	v_mfma_f32_16x16x32_bf16 v[112:115], v[182:185], v[190:193], v[112:115]
	v_mfma_f32_16x16x32_bf16 v[108:111], v[156:159], v[198:201], v[108:111]
	v_mfma_f32_16x16x32_bf16 v[104:107], v[164:167], v[198:201], v[104:107]
	v_mfma_f32_16x16x32_bf16 v[100:103], v[172:175], v[198:201], v[100:103]
	v_mfma_f32_16x16x32_bf16 v[96:99], v[182:185], v[198:201], v[96:99]
	v_mfma_f32_16x16x32_bf16 v[92:95], v[156:159], v[212:215], v[92:95]
	v_mfma_f32_16x16x32_bf16 v[88:91], v[164:167], v[212:215], v[88:91]
	v_mfma_f32_16x16x32_bf16 v[84:87], v[172:175], v[212:215], v[84:87]
	v_mfma_f32_16x16x32_bf16 v[80:83], v[182:185], v[212:215], v[80:83]
	v_mfma_f32_16x16x32_bf16 v[76:79], v[156:159], v[220:223], v[76:79]
	v_mfma_f32_16x16x32_bf16 v[72:75], v[164:167], v[220:223], v[72:75]
	v_mfma_f32_16x16x32_bf16 v[68:71], v[172:175], v[220:223], v[68:71]
	v_mfma_f32_16x16x32_bf16 v[64:67], v[182:185], v[220:223], v[64:67]
	s_setprio 0
	s_barrier
; #define PG8_STAGE(bufoff, gbase, voff) do { _Pragma("unroll") for (int _i = 0; _i < 2; ++_i) \
;         __builtin_amdgcn_global_load_lds((const unsigned*)((const char*)(gbase) + (voff)[_i]), (PG8_LAS unsigned*)(lds + (bufoff) + ldsw + _i * 8192), 16, 0, 0); } while (0)
; #define PG8_LDA(dst, b, h) do { _Pragma("unroll") for (int m = 0; m < 4; ++m) _Pragma("unroll") for (int k = 0; k < 2; ++k) dst[m][k] = *(const PG8_LAS bf16x8*)(lds + PG8_SA(b, h) + aoff + m * 2048 + k * 1024); } while (0)
; #define PG8_MMA(ai, bj, At, Bt) do { __builtin_amdgcn_s_setprio(1); _Pragma("unroll") for (int m = 0; m < 4; ++m) _Pragma("unroll") for (int n = 0; n < 2; ++n) _Pragma("unroll") for (int k = 0; k < 2; ++k) \
;         acc[ai][bj][m][n] = __builtin_amdgcn_mfma_f32_16x16x32_bf16(Bt[n][k], At[m][k], acc[ai][bj][m][n], 0, 0, 0); __builtin_amdgcn_s_setprio(0); } while (0)
; #define PG8_WAIT_V(n) asm volatile("s_waitcnt vmcnt(" #n ")" ::: "memory")
; #define PG8_WAIT_L(n) asm volatile("s_waitcnt lgkmcnt(" #n ")" ::: "memory")
; #define PG8_BAR __builtin_amdgcn_s_barrier()
; #define PG8_SCHED __builtin_amdgcn_sched_barrier(0)
; template <class Epi, class Sched, bool ALIGN_EPI = false, bool SP2 = false>
; __device__ __forceinline__ void gemm_phase(PG8_LAS unsigned char* lds, const Gemm g, const Sched& S, const Epi& E) {
;     ...
;             PG8_LDA(At, 1, 1); PG8_STAGE(PG8_SB(1, 0), b3, voffB); PG8_STAGE(PG8_SB(1, 1), b3 + hstep, voffB); PG8_STAGE(PG8_SA(1, 0), a3, voffA);
;             PG8_WAIT_V(8); PG8_WAIT_L(0); PG8_BAR; PG8_MMA(1, 0, At, B0); PG8_MMA(1, 1, At, B1); PG8_BAR; PG8_SCHED;
;     ...
;         if constexpr (ALIGN_EPI) { if (wr == 0) PG8_BAR; }
	s_add_i32 s50, s78, s3
	v_lshl_add_u64 v[202:203], v[202:203], 0, s[42:43]
	s_mov_b32 m0, s50
	ds_read_b128 v[186:189], v153 offset:49152
	ds_read_b128 v[190:193], v153 offset:50176
	ds_read_b128 v[194:197], v153 offset:51200
	ds_read_b128 v[198:201], v153 offset:52224
	ds_read_b128 v[208:211], v153 offset:53248
	ds_read_b128 v[212:215], v153 offset:54272
	ds_read_b128 v[216:219], v153 offset:55296
	ds_read_b128 v[220:223], v153 offset:56320
	global_load_lds_dwordx4 v[202:203], off
	s_add_i32 m0, s50, 0x2000
	s_add_u32 s50, s54, 0xb0080
	v_lshl_add_u64 v[202:203], v[224:225], 0, s[42:43]
	s_addc_u32 s51, s55, 0
	s_add_i32 s54, s79, s3
	global_load_lds_dwordx4 v[202:203], off
	v_lshl_add_u64 v[202:203], s[50:51], 0, v[130:131]
	s_mov_b32 m0, s54
	s_nop 0
	global_load_lds_dwordx4 v[202:203], off
	v_lshl_add_u64 v[202:203], s[50:51], 0, v[134:135]
	s_add_i32 m0, s54, 0x2000
	s_nop 0
	global_load_lds_dwordx4 v[202:203], off
	s_waitcnt vmcnt(6)
	s_waitcnt lgkmcnt(0)
	s_barrier
	s_setprio 1
	s_waitcnt lgkmcnt(0)
	v_mfma_f32_16x16x32_bf16 v[60:63], v[144:147], v[186:189], v[60:63]
	v_mfma_f32_16x16x32_bf16 v[56:59], v[160:163], v[186:189], v[56:59]
	v_mfma_f32_16x16x32_bf16 v[52:55], v[168:171], v[186:189], v[52:55]
	v_mfma_f32_16x16x32_bf16 v[48:51], v[176:179], v[186:189], v[48:51]
	v_mfma_f32_16x16x32_bf16 v[44:47], v[144:147], v[194:197], v[44:47]
	v_mfma_f32_16x16x32_bf16 v[40:43], v[160:163], v[194:197], v[40:43]
	v_mfma_f32_16x16x32_bf16 v[36:39], v[168:171], v[194:197], v[36:39]
	v_mfma_f32_16x16x32_bf16 v[32:35], v[176:179], v[194:197], v[32:35]
	v_mfma_f32_16x16x32_bf16 v[28:31], v[144:147], v[208:211], v[28:31]
	v_mfma_f32_16x16x32_bf16 v[24:27], v[160:163], v[208:211], v[24:27]
	v_mfma_f32_16x16x32_bf16 v[20:23], v[168:171], v[208:211], v[20:23]
	v_mfma_f32_16x16x32_bf16 v[16:19], v[176:179], v[208:211], v[16:19]
	v_mfma_f32_16x16x32_bf16 v[12:15], v[144:147], v[216:219], v[12:15]
	v_mfma_f32_16x16x32_bf16 v[8:11], v[160:163], v[216:219], v[8:11]
	v_lshl_add_u64 v[202:203], v[226:227], 0, s[42:43]
	s_mov_b32 m0, s59
	s_nop 0
	global_load_lds_dwordx4 v[202:203], off
	v_mfma_f32_16x16x32_bf16 v[4:7], v[168:171], v[216:219], v[4:7]
	v_mfma_f32_16x16x32_bf16 v[0:3], v[176:179], v[216:219], v[0:3]
	s_setprio 0
	s_setprio 1
	v_mfma_f32_16x16x32_bf16 v[60:63], v[156:159], v[190:193], v[60:63]
	v_mfma_f32_16x16x32_bf16 v[56:59], v[164:167], v[190:193], v[56:59]
	v_mfma_f32_16x16x32_bf16 v[52:55], v[172:175], v[190:193], v[52:55]
	v_mfma_f32_16x16x32_bf16 v[48:51], v[182:185], v[190:193], v[48:51]
	v_mfma_f32_16x16x32_bf16 v[44:47], v[156:159], v[198:201], v[44:47]
	v_mfma_f32_16x16x32_bf16 v[40:43], v[164:167], v[198:201], v[40:43]
	v_mfma_f32_16x16x32_bf16 v[36:39], v[172:175], v[198:201], v[36:39]
	v_mfma_f32_16x16x32_bf16 v[32:35], v[182:185], v[198:201], v[32:35]
	v_mfma_f32_16x16x32_bf16 v[28:31], v[156:159], v[212:215], v[28:31]
	v_mfma_f32_16x16x32_bf16 v[24:27], v[164:167], v[212:215], v[24:27]
	v_mfma_f32_16x16x32_bf16 v[20:23], v[172:175], v[212:215], v[20:23]
	v_mfma_f32_16x16x32_bf16 v[16:19], v[182:185], v[212:215], v[16:19]
	v_mfma_f32_16x16x32_bf16 v[12:15], v[156:159], v[220:223], v[12:15]
	v_mfma_f32_16x16x32_bf16 v[8:11], v[164:167], v[220:223], v[8:11]
	v_lshl_add_u64 v[202:203], v[228:229], 0, s[42:43]
	s_mov_b32 m0, s60
	s_nop 0
	global_load_lds_dwordx4 v[202:203], off
	v_mfma_f32_16x16x32_bf16 v[4:7], v[172:175], v[220:223], v[4:7]
	v_mfma_f32_16x16x32_bf16 v[0:3], v[182:185], v[220:223], v[0:3]
	s_setprio 0
	s_barrier
	s_add_i32 s77, s77, 2
	s_add_u32 s75, s75, 0x100
	s_addc_u32 s76, s76, 0
	s_cmp_gt_u32 s77, 41
	s_mov_b64 s[50:51], s[52:53]
	s_cbranch_scc0 .LBB0_1035
	s_and_b64 vcc, exec, s[44:45]
	s_cbranch_vccz .LBB0_1038
	s_barrier

; #define PG8_STAGE(bufoff, gbase, voff) do { _Pragma("unroll") for (int _i = 0; _i < 2; ++_i) \
;         __builtin_amdgcn_global_load_lds((const unsigned*)((const char*)(gbase) + (voff)[_i]), (PG8_LAS unsigned*)(lds + (bufoff) + ldsw + _i * 8192), 16, 0, 0); } while (0)
; #define PG8_LDA(dst, b, h) do { _Pragma("unroll") for (int m = 0; m < 4; ++m) _Pragma("unroll") for (int k = 0; k < 2; ++k) dst[m][k] = *(const PG8_LAS bf16x8*)(lds + PG8_SA(b, h) + aoff + m * 2048 + k * 1024); } while (0)
; #define PG8_LDB(dst, b, h) do { _Pragma("unroll") for (int n = 0; n < 2; ++n) _Pragma("unroll") for (int k = 0; k < 2; ++k) dst[n][k] = *(const PG8_LAS bf16x8*)(lds + PG8_SB(b, h) + boff + n * 2048 + k * 1024); } while (0)
; #define PG8_MMA(ai, bj, At, Bt) do { __builtin_amdgcn_s_setprio(1); _Pragma("unroll") for (int m = 0; m < 4; ++m) _Pragma("unroll") for (int n = 0; n < 2; ++n) _Pragma("unroll") for (int k = 0; k < 2; ++k) \
;         acc[ai][bj][m][n] = __builtin_amdgcn_mfma_f32_16x16x32_bf16(Bt[n][k], At[m][k], acc[ai][bj][m][n], 0, 0, 0); __builtin_amdgcn_s_setprio(0); } while (0)
; #define PG8_BAR __builtin_amdgcn_s_barrier()
; template <class Epi, class Sched, bool ALIGN_EPI = false, bool SP2 = false>
; __device__ __forceinline__ void gemm_phase(PG8_LAS unsigned char* lds, const Gemm g, const Sched& S, const Epi& E) {
;     ...
;         const bool has_next = S.next(ui + 1, nxt);
;         const char* nA = has_next ? (const char*)g.A + (size_t)nxt.pm * tstep : cA; const char* nB = has_next ? (const char*)g.Bt + (size_t)nxt.pn * tstep : cB;
;         for (int t = 0; t < nt; t += 2) {
;             const bool last = (t == nt - 2);
;             const char* a1 = cA + (size_t)(t + 1) * kstep;
;             const char* a2 = last ? nA : cA + (size_t)(t + 2) * kstep; const char* b2 = last ? nB : cB + (size_t)(t + 2) * kstep;
;             const char* a3 = a2 + kstep; const char* b3 = b2 + kstep;
;             if (last && has_next) S.a_ready(nxt);
;             if constexpr (SP2) {
;             PG8_LDB(B0, 0, 0); PG8_LDB(B1, 0, 1); PG8_SCHED; PG8_LDA(At, 0, 0); PG8_STAGE(PG8_SA(1, 1), a1 + hstep, voffA);
;             PG8_WAIT_V(8); PG8_WAIT_L(0); PG8_BAR; PG8_MMA(0, 0, At, B0); PG8_MMA(0, 1, At, B1); PG8_BAR; PG8_SCHED;
;             PG8_LDA(At, 0, 1); PG8_STAGE(PG8_SB(0, 0), b2, voffB); PG8_STAGE(PG8_SB(0, 1), b2 + hstep, voffB); PG8_STAGE(PG8_SA(0, 0), a2, voffA);
.LBB0_1118:
	s_ashr_i32 s45, s44, 31
	s_lshl_b64 s[48:49], s[44:45], 19
	s_add_u32 s48, s22, s48
	s_addc_u32 s49, s23, s49
	s_and_b64 s[50:51], s[10:11], exec
	s_cselect_b32 s45, s49, s55
	s_cselect_b32 s76, s48, s54
	s_ashr_i32 s43, s42, 31
	s_lshl_b64 s[50:51], s[42:43], 19
	s_add_u32 s50, s14, s50
	s_addc_u32 s51, s15, s51
	s_and_b64 s[58:59], s[10:11], exec
	s_cselect_b32 s43, s51, s57
	s_cselect_b32 s77, s50, s56
	s_add_u32 s54, s54, 0x40080
	s_addc_u32 s55, s55, 0
	s_add_u32 s82, s56, 0x100
	s_addc_u32 s83, s57, 0
	s_mov_b32 s84, -2
	ds_read_b128 v[144:147], v155
	ds_read_b128 v[148:151], v155 offset:1024
	ds_read_b128 v[160:163], v155 offset:2048
	ds_read_b128 v[164:167], v155 offset:3072
	ds_read_b128 v[168:171], v156
	ds_read_b128 v[172:175], v156 offset:1024
	ds_read_b128 v[176:179], v156 offset:2048
	ds_read_b128 v[182:185], v156 offset:3072
	s_add_u32 s56, s54, 0xfffc0080
	s_addc_u32 s57, s55, -1
	s_cmp_eq_u32 s84, 12
	s_cselect_b32 s59, s45, s57
	s_cselect_b32 s58, s76, s56
	s_cselect_b32 s57, s43, s83
	s_cselect_b32 s56, s77, s82
	v_lshl_add_u64 v[224:225], s[54:55], 0, v[136:137]
	s_add_i32 m0, s53, 0xc000
	ds_read_b128 v[186:189], v157
	ds_read_b128 v[190:193], v157 offset:1024
	ds_read_b128 v[194:197], v157 offset:2048
	ds_read_b128 v[198:201], v157 offset:3072
	ds_read_b128 v[208:211], v157 offset:4096
	ds_read_b128 v[212:215], v157 offset:5120
	ds_read_b128 v[216:219], v157 offset:6144
	ds_read_b128 v[220:223], v157 offset:7168
	global_load_lds_dwordx4 v[224:225], off
	v_lshl_add_u64 v[224:225], s[54:55], 0, v[138:139]
	s_add_i32 m0, s53, 0xe000
	s_nop 0
	global_load_lds_dwordx4 v[224:225], off
	s_waitcnt vmcnt(8)
	s_waitcnt lgkmcnt(0)
	s_barrier
	s_setprio 1
	s_waitcnt lgkmcnt(0)
	v_mfma_f32_16x16x32_bf16 v[124:127], v[144:147], v[186:189], 0
	v_mfma_f32_16x16x32_bf16 v[120:123], v[160:163], v[186:189], 0
	v_mfma_f32_16x16x32_bf16 v[116:119], v[168:171], v[186:189], 0
	v_mfma_f32_16x16x32_bf16 v[112:115], v[176:179], v[186:189], 0
	v_mfma_f32_16x16x32_bf16 v[108:111], v[144:147], v[194:197], 0
	v_mfma_f32_16x16x32_bf16 v[104:107], v[160:163], v[194:197], 0
	v_mfma_f32_16x16x32_bf16 v[100:103], v[168:171], v[194:197], 0
	v_mfma_f32_16x16x32_bf16 v[96:99], v[176:179], v[194:197], 0
	v_mfma_f32_16x16x32_bf16 v[92:95], v[144:147], v[208:211], 0
	v_mfma_f32_16x16x32_bf16 v[88:91], v[160:163], v[208:211], 0
	v_mfma_f32_16x16x32_bf16 v[84:87], v[168:171], v[208:211], 0
	v_mfma_f32_16x16x32_bf16 v[80:83], v[176:179], v[208:211], 0
	v_mfma_f32_16x16x32_bf16 v[76:79], v[144:147], v[216:219], 0
	v_mfma_f32_16x16x32_bf16 v[72:75], v[160:163], v[216:219], 0
	v_mfma_f32_16x16x32_bf16 v[68:71], v[168:171], v[216:219], 0
	v_mfma_f32_16x16x32_bf16 v[64:67], v[176:179], v[216:219], 0
	s_setprio 0
	s_setprio 1
	v_mfma_f32_16x16x32_bf16 v[124:127], v[148:151], v[190:193], v[124:127]
	v_mfma_f32_16x16x32_bf16 v[120:123], v[164:167], v[190:193], v[120:123]
	v_mfma_f32_16x16x32_bf16 v[116:119], v[172:175], v[190:193], v[116:119]
	v_mfma_f32_16x16x32_bf16 v[112:115], v[182:185], v[190:193], v[112:115]
	v_mfma_f32_16x16x32_bf16 v[108:111], v[148:151], v[198:201], v[108:111]
	v_mfma_f32_16x16x32_bf16 v[104:107], v[164:167], v[198:201], v[104:107]
	v_mfma_f32_16x16x32_bf16 v[100:103], v[172:175], v[198:201], v[100:103]
	v_mfma_f32_16x16x32_bf16 v[96:99], v[182:185], v[198:201], v[96:99]
	v_mfma_f32_16x16x32_bf16 v[92:95], v[148:151], v[212:215], v[92:95]
	v_mfma_f32_16x16x32_bf16 v[88:91], v[164:167], v[212:215], v[88:91]
	v_mfma_f32_16x16x32_bf16 v[84:87], v[172:175], v[212:215], v[84:87]
	v_mfma_f32_16x16x32_bf16 v[80:83], v[182:185], v[212:215], v[80:83]
	v_mfma_f32_16x16x32_bf16 v[76:79], v[148:151], v[220:223], v[76:79]
	v_mfma_f32_16x16x32_bf16 v[72:75], v[164:167], v[220:223], v[72:75]
	v_mfma_f32_16x16x32_bf16 v[68:71], v[172:175], v[220:223], v[68:71]
	v_mfma_f32_16x16x32_bf16 v[64:67], v[182:185], v[220:223], v[64:67]
	s_setprio 0
	s_barrier
	s_add_i32 s78, s66, s33
	v_lshl_add_u64 v[224:225], s[56:57], 0, v[132:133]
	s_mov_b32 m0, s78
	ds_read_b128 v[186:189], v157 offset:16384
	ds_read_b128 v[190:193], v157 offset:17408
	ds_read_b128 v[194:197], v157 offset:18432
	ds_read_b128 v[198:201], v157 offset:19456
	ds_read_b128 v[208:211], v157 offset:20480
	ds_read_b128 v[212:215], v157 offset:21504
	ds_read_b128 v[216:219], v157 offset:22528
	ds_read_b128 v[220:223], v157 offset:23552
	global_load_lds_dwordx4 v[224:225], off
	s_add_i32 m0, s78, 0x2000
	s_add_u32 s78, s56, 0x40000
	v_lshl_add_u64 v[226:227], s[56:57], 0, v[128:129]
	s_addc_u32 s79, s57, 0
	s_add_i32 s85, s67, s33
	global_load_lds_dwordx4 v[226:227], off
	v_lshl_add_u64 v[228:229], s[78:79], 0, v[132:133]
	s_mov_b32 m0, s85
	global_load_lds_dwordx4 v[228:229], off
	v_lshl_add_u64 v[228:229], s[78:79], 0, v[128:129]
	s_add_i32 m0, s85, 0x2000
	s_nop 0
	global_load_lds_dwordx4 v[228:229], off
	s_waitcnt vmcnt(6)
	s_waitcnt lgkmcnt(0)
	s_barrier
; #define PG8_STAGE(bufoff, gbase, voff) do { _Pragma("unroll") for (int _i = 0; _i < 2; ++_i) \
;         __builtin_amdgcn_global_load_lds((const unsigned*)((const char*)(gbase) + (voff)[_i]), (PG8_LAS unsigned*)(lds + (bufoff) + ldsw + _i * 8192), 16, 0, 0); } while (0)
; #define PG8_LDA(dst, b, h) do { _Pragma("unroll") for (int m = 0; m < 4; ++m) _Pragma("unroll") for (int k = 0; k < 2; ++k) dst[m][k] = *(const PG8_LAS bf16x8*)(lds + PG8_SA(b, h) + aoff + m * 2048 + k * 1024); } while (0)
; #define PG8_LDB(dst, b, h) do { _Pragma("unroll") for (int n = 0; n < 2; ++n) _Pragma("unroll") for (int k = 0; k < 2; ++k) dst[n][k] = *(const PG8_LAS bf16x8*)(lds + PG8_SB(b, h) + boff + n * 2048 + k * 1024); } while (0)
; #define PG8_MMA(ai, bj, At, Bt) do { __builtin_amdgcn_s_setprio(1); _Pragma("unroll") for (int m = 0; m < 4; ++m) _Pragma("unroll") for (int n = 0; n < 2; ++n) _Pragma("unroll") for (int k = 0; k < 2; ++k) \
;         acc[ai][bj][m][n] = __builtin_amdgcn_mfma_f32_16x16x32_bf16(Bt[n][k], At[m][k], acc[ai][bj][m][n], 0, 0, 0); __builtin_amdgcn_s_setprio(0); } while (0)
; #define PG8_WAIT_V(n) asm volatile("s_waitcnt vmcnt(" #n ")" ::: "memory")
; #define PG8_WAIT_L(n) asm volatile("s_waitcnt lgkmcnt(" #n ")" ::: "memory")
; #define PG8_BAR __builtin_amdgcn_s_barrier()
; #define PG8_SCHED __builtin_amdgcn_sched_barrier(0)
; template <class Epi, class Sched, bool ALIGN_EPI = false, bool SP2 = false>
; __device__ __forceinline__ void gemm_phase(PG8_LAS unsigned char* lds, const Gemm g, const Sched& S, const Epi& E) {
;     ...
;             PG8_WAIT_V(8); PG8_WAIT_L(0); PG8_BAR; PG8_MMA(1, 0, At, B0); PG8_MMA(1, 1, At, B1); PG8_BAR; PG8_SCHED;
;             PG8_LDB(B0, 1, 0); PG8_LDB(B1, 1, 1); PG8_SCHED; PG8_LDA(At, 1, 0); PG8_STAGE(PG8_SA(0, 1), a2 + hstep, voffA);
;             PG8_WAIT_V(8); PG8_WAIT_L(0); PG8_BAR; PG8_MMA(0, 0, At, B0); PG8_MMA(0, 1, At, B1); PG8_BAR; PG8_SCHED;
	s_setprio 1
	s_waitcnt lgkmcnt(0)
	v_mfma_f32_16x16x32_bf16 v[60:63], v[144:147], v[186:189], 0
	v_mfma_f32_16x16x32_bf16 v[56:59], v[160:163], v[186:189], 0
	v_mfma_f32_16x16x32_bf16 v[52:55], v[168:171], v[186:189], 0
	v_mfma_f32_16x16x32_bf16 v[48:51], v[176:179], v[186:189], 0
	v_mfma_f32_16x16x32_bf16 v[44:47], v[144:147], v[194:197], 0
	v_mfma_f32_16x16x32_bf16 v[40:43], v[160:163], v[194:197], 0
	v_mfma_f32_16x16x32_bf16 v[36:39], v[168:171], v[194:197], 0
	v_mfma_f32_16x16x32_bf16 v[32:35], v[176:179], v[194:197], 0
	v_mfma_f32_16x16x32_bf16 v[28:31], v[144:147], v[208:211], 0
	v_mfma_f32_16x16x32_bf16 v[24:27], v[160:163], v[208:211], 0
	v_mfma_f32_16x16x32_bf16 v[20:23], v[168:171], v[208:211], 0
	v_mfma_f32_16x16x32_bf16 v[16:19], v[176:179], v[208:211], 0
	v_mfma_f32_16x16x32_bf16 v[12:15], v[144:147], v[216:219], 0
	v_mfma_f32_16x16x32_bf16 v[8:11], v[160:163], v[216:219], 0
	v_lshl_add_u64 v[228:229], s[58:59], 0, v[134:135]
	s_mov_b32 m0, s53
	s_nop 0
	global_load_lds_dwordx4 v[228:229], off
	v_mfma_f32_16x16x32_bf16 v[4:7], v[168:171], v[216:219], 0
	v_mfma_f32_16x16x32_bf16 v[0:3], v[176:179], v[216:219], 0
	s_setprio 0
	s_setprio 1
	v_mfma_f32_16x16x32_bf16 v[60:63], v[148:151], v[190:193], v[60:63]
	v_mfma_f32_16x16x32_bf16 v[56:59], v[164:167], v[190:193], v[56:59]
	v_mfma_f32_16x16x32_bf16 v[52:55], v[172:175], v[190:193], v[52:55]
	v_mfma_f32_16x16x32_bf16 v[48:51], v[182:185], v[190:193], v[48:51]
	v_mfma_f32_16x16x32_bf16 v[44:47], v[148:151], v[198:201], v[44:47]
	v_mfma_f32_16x16x32_bf16 v[40:43], v[164:167], v[198:201], v[40:43]
	v_mfma_f32_16x16x32_bf16 v[36:39], v[172:175], v[198:201], v[36:39]
	v_mfma_f32_16x16x32_bf16 v[32:35], v[182:185], v[198:201], v[32:35]
	v_mfma_f32_16x16x32_bf16 v[28:31], v[148:151], v[212:215], v[28:31]
	v_mfma_f32_16x16x32_bf16 v[24:27], v[164:167], v[212:215], v[24:27]
	v_mfma_f32_16x16x32_bf16 v[20:23], v[172:175], v[212:215], v[20:23]
	v_mfma_f32_16x16x32_bf16 v[16:19], v[182:185], v[212:215], v[16:19]
	v_mfma_f32_16x16x32_bf16 v[12:15], v[148:151], v[220:223], v[12:15]
	v_mfma_f32_16x16x32_bf16 v[8:11], v[164:167], v[220:223], v[8:11]
	v_lshl_add_u64 v[230:231], s[58:59], 0, v[130:131]
	s_mov_b32 m0, s60
	s_nop 0
	global_load_lds_dwordx4 v[230:231], off
	v_mfma_f32_16x16x32_bf16 v[4:7], v[172:175], v[220:223], v[4:7]
	v_mfma_f32_16x16x32_bf16 v[0:3], v[182:185], v[220:223], v[0:3]
	s_setprio 0
	s_barrier
	s_add_i32 s78, 0, 0x18000
	v_add_u32_e32 v159, s78, v153
	s_add_i32 s79, 0, 0x1c000
	ds_read_b128 v[144:147], v159
	ds_read_b128 v[148:151], v159 offset:1024
	ds_read_b128 v[160:163], v159 offset:2048
	ds_read_b128 v[164:167], v159 offset:3072
	v_add_u32_e32 v159, s79, v153
	ds_read_b128 v[168:171], v159
	ds_read_b128 v[172:175], v159 offset:1024
	ds_read_b128 v[176:179], v159 offset:2048
	ds_read_b128 v[182:185], v159 offset:3072
	s_add_u32 s58, s58, 0x40000
	s_addc_u32 s59, s59, 0
	s_mov_b32 m0, s61
	v_lshl_add_u64 v[232:233], s[58:59], 0, v[134:135]
	ds_read_b128 v[186:189], v157 offset:32768
	ds_read_b128 v[190:193], v157 offset:33792
	ds_read_b128 v[194:197], v157 offset:34816
	ds_read_b128 v[198:201], v157 offset:35840
	ds_read_b128 v[208:211], v157 offset:36864
	ds_read_b128 v[212:215], v157 offset:37888
	ds_read_b128 v[216:219], v157 offset:38912
	ds_read_b128 v[220:223], v157 offset:39936
	global_load_lds_dwordx4 v[232:233], off
	v_lshl_add_u64 v[232:233], s[58:59], 0, v[130:131]
	s_mov_b32 m0, s62
	s_nop 0
	global_load_lds_dwordx4 v[232:233], off
	s_waitcnt vmcnt(8)
	s_waitcnt lgkmcnt(0)
	s_barrier
	s_setprio 1
	s_waitcnt lgkmcnt(0)
	v_mfma_f32_16x16x32_bf16 v[124:127], v[144:147], v[186:189], v[124:127]
	v_mfma_f32_16x16x32_bf16 v[120:123], v[160:163], v[186:189], v[120:123]
	v_mfma_f32_16x16x32_bf16 v[116:119], v[168:171], v[186:189], v[116:119]
	v_mfma_f32_16x16x32_bf16 v[112:115], v[176:179], v[186:189], v[112:115]
	v_mfma_f32_16x16x32_bf16 v[108:111], v[144:147], v[194:197], v[108:111]
	v_mfma_f32_16x16x32_bf16 v[104:107], v[160:163], v[194:197], v[104:107]
	v_mfma_f32_16x16x32_bf16 v[100:103], v[168:171], v[194:197], v[100:103]
	v_mfma_f32_16x16x32_bf16 v[96:99], v[176:179], v[194:197], v[96:99]
	v_mfma_f32_16x16x32_bf16 v[92:95], v[144:147], v[208:211], v[92:95]
	v_mfma_f32_16x16x32_bf16 v[88:91], v[160:163], v[208:211], v[88:91]
	v_mfma_f32_16x16x32_bf16 v[84:87], v[168:171], v[208:211], v[84:87]
	v_mfma_f32_16x16x32_bf16 v[80:83], v[176:179], v[208:211], v[80:83]
	v_mfma_f32_16x16x32_bf16 v[76:79], v[144:147], v[216:219], v[76:79]
	v_mfma_f32_16x16x32_bf16 v[72:75], v[160:163], v[216:219], v[72:75]
	v_mfma_f32_16x16x32_bf16 v[68:71], v[168:171], v[216:219], v[68:71]
	v_mfma_f32_16x16x32_bf16 v[64:67], v[176:179], v[216:219], v[64:67]
	s_setprio 0
	s_setprio 1
	v_mfma_f32_16x16x32_bf16 v[124:127], v[148:151], v[190:193], v[124:127]
	v_mfma_f32_16x16x32_bf16 v[120:123], v[164:167], v[190:193], v[120:123]
	v_mfma_f32_16x16x32_bf16 v[116:119], v[172:175], v[190:193], v[116:119]
	v_mfma_f32_16x16x32_bf16 v[112:115], v[182:185], v[190:193], v[112:115]
	v_mfma_f32_16x16x32_bf16 v[108:111], v[148:151], v[198:201], v[108:111]
	v_mfma_f32_16x16x32_bf16 v[104:107], v[164:167], v[198:201], v[104:107]
	v_mfma_f32_16x16x32_bf16 v[100:103], v[172:175], v[198:201], v[100:103]
	v_mfma_f32_16x16x32_bf16 v[96:99], v[182:185], v[198:201], v[96:99]
	v_mfma_f32_16x16x32_bf16 v[92:95], v[148:151], v[212:215], v[92:95]
	v_mfma_f32_16x16x32_bf16 v[88:91], v[164:167], v[212:215], v[88:91]
	v_mfma_f32_16x16x32_bf16 v[84:87], v[172:175], v[212:215], v[84:87]
	v_mfma_f32_16x16x32_bf16 v[80:83], v[182:185], v[212:215], v[80:83]
	v_mfma_f32_16x16x32_bf16 v[76:79], v[148:151], v[220:223], v[76:79]
	v_mfma_f32_16x16x32_bf16 v[72:75], v[164:167], v[220:223], v[72:75]
	v_mfma_f32_16x16x32_bf16 v[68:71], v[172:175], v[220:223], v[68:71]
	v_mfma_f32_16x16x32_bf16 v[64:67], v[182:185], v[220:223], v[64:67]
	s_setprio 0
	s_barrier
; #define PG8_STAGE(bufoff, gbase, voff) do { _Pragma("unroll") for (int _i = 0; _i < 2; ++_i) \
;         __builtin_amdgcn_global_load_lds((const unsigned*)((const char*)(gbase) + (voff)[_i]), (PG8_LAS unsigned*)(lds + (bufoff) + ldsw + _i * 8192), 16, 0, 0); } while (0)
; #define PG8_LDA(dst, b, h) do { _Pragma("unroll") for (int m = 0; m < 4; ++m) _Pragma("unroll") for (int k = 0; k < 2; ++k) dst[m][k] = *(const PG8_LAS bf16x8*)(lds + PG8_SA(b, h) + aoff + m * 2048 + k * 1024); } while (0)
; #define PG8_LDB(dst, b, h) do { _Pragma("unroll") for (int n = 0; n < 2; ++n) _Pragma("unroll") for (int k = 0; k < 2; ++k) dst[n][k] = *(const PG8_LAS bf16x8*)(lds + PG8_SB(b, h) + boff + n * 2048 + k * 1024); } while (0)
; #define PG8_BAR __builtin_amdgcn_s_barrier()
; template <class Epi, class Sched, bool ALIGN_EPI = false, bool SP2 = false>
; __device__ __forceinline__ void gemm_phase(PG8_LAS unsigned char* lds, const Gemm g, const Sched& S, const Epi& E) {
;     ...
;             const bool last = (t == nt - 2);
;             const char* a1 = cA + (size_t)(t + 1) * kstep;
;             const char* a2 = last ? nA : cA + (size_t)(t + 2) * kstep; const char* b2 = last ? nB : cB + (size_t)(t + 2) * kstep;
;             const char* a3 = a2 + kstep; const char* b3 = b2 + kstep;
;             if (last && has_next) S.a_ready(nxt);
;             if constexpr (SP2) {
;             PG8_LDB(B0, 0, 0); PG8_LDB(B1, 0, 1); PG8_SCHED; PG8_LDA(At, 0, 0); PG8_STAGE(PG8_SA(1, 1), a1 + hstep, voffA);
;             PG8_WAIT_V(8); PG8_WAIT_L(0); PG8_BAR; PG8_MMA(0, 0, At, B0); PG8_MMA(0, 1, At, B1); PG8_BAR; PG8_SCHED;
;             PG8_LDA(At, 0, 1); PG8_STAGE(PG8_SB(0, 0), b2, voffB); PG8_STAGE(PG8_SB(0, 1), b2 + hstep, voffB); PG8_STAGE(PG8_SA(0, 0), a2, voffA);
;             PG8_WAIT_V(8); PG8_WAIT_L(0); PG8_BAR; PG8_MMA(1, 0, At, B0); PG8_MMA(1, 1, At, B1); PG8_BAR; PG8_SCHED;
;             PG8_LDB(B0, 1, 0); PG8_LDB(B1, 1, 1); PG8_SCHED; PG8_LDA(At, 1, 0); PG8_STAGE(PG8_SA(0, 1), a2 + hstep, voffA);
;             PG8_WAIT_V(8); PG8_WAIT_L(0); PG8_BAR; PG8_MMA(0, 0, At, B0); PG8_MMA(0, 1, At, B1); PG8_BAR; PG8_SCHED;
;             PG8_LDA(At, 1, 1); PG8_STAGE(PG8_SB(1, 0), b3, voffB); PG8_STAGE(PG8_SB(1, 1), b3 + hstep, voffB); PG8_STAGE(PG8_SA(1, 0), a3, voffA);
;             PG8_WAIT_V(8); PG8_WAIT_L(0); PG8_BAR; PG8_MMA(1, 0, At, B0); PG8_MMA(1, 1, At, B1); PG8_BAR; PG8_SCHED;
	s_add_i32 s58, s78, s33
	v_lshl_add_u64 v[224:225], v[224:225], 0, s[12:13]
	s_mov_b32 m0, s58
	ds_read_b128 v[186:189], v157 offset:49152
	ds_read_b128 v[190:193], v157 offset:50176
	ds_read_b128 v[194:197], v157 offset:51200
	ds_read_b128 v[198:201], v157 offset:52224
	ds_read_b128 v[208:211], v157 offset:53248
	ds_read_b128 v[212:215], v157 offset:54272
	ds_read_b128 v[216:219], v157 offset:55296
	ds_read_b128 v[220:223], v157 offset:56320
	global_load_lds_dwordx4 v[224:225], off
	s_add_i32 m0, s58, 0x2000
	s_add_u32 s56, s56, 0x40080
	v_lshl_add_u64 v[224:225], v[226:227], 0, s[12:13]
	s_addc_u32 s57, s57, 0
	s_add_i32 s58, s79, s33
	global_load_lds_dwordx4 v[224:225], off
	v_lshl_add_u64 v[224:225], s[56:57], 0, v[132:133]
	s_mov_b32 m0, s58
	s_nop 0
	global_load_lds_dwordx4 v[224:225], off
	v_lshl_add_u64 v[224:225], s[56:57], 0, v[128:129]
	s_add_i32 m0, s58, 0x2000
	s_nop 0
	global_load_lds_dwordx4 v[224:225], off
	s_waitcnt vmcnt(6)
	s_waitcnt lgkmcnt(0)
	s_barrier
	s_setprio 1
	s_waitcnt lgkmcnt(0)
	v_mfma_f32_16x16x32_bf16 v[60:63], v[144:147], v[186:189], v[60:63]
	v_mfma_f32_16x16x32_bf16 v[56:59], v[160:163], v[186:189], v[56:59]
	v_mfma_f32_16x16x32_bf16 v[52:55], v[168:171], v[186:189], v[52:55]
	v_mfma_f32_16x16x32_bf16 v[48:51], v[176:179], v[186:189], v[48:51]
	v_mfma_f32_16x16x32_bf16 v[44:47], v[144:147], v[194:197], v[44:47]
	v_mfma_f32_16x16x32_bf16 v[40:43], v[160:163], v[194:197], v[40:43]
	v_mfma_f32_16x16x32_bf16 v[36:39], v[168:171], v[194:197], v[36:39]
	v_mfma_f32_16x16x32_bf16 v[32:35], v[176:179], v[194:197], v[32:35]
	v_mfma_f32_16x16x32_bf16 v[28:31], v[144:147], v[208:211], v[28:31]
	v_mfma_f32_16x16x32_bf16 v[24:27], v[160:163], v[208:211], v[24:27]
	v_mfma_f32_16x16x32_bf16 v[20:23], v[168:171], v[208:211], v[20:23]
	v_mfma_f32_16x16x32_bf16 v[16:19], v[176:179], v[208:211], v[16:19]
	v_mfma_f32_16x16x32_bf16 v[12:15], v[144:147], v[216:219], v[12:15]
	v_mfma_f32_16x16x32_bf16 v[8:11], v[160:163], v[216:219], v[8:11]
	v_lshl_add_u64 v[224:225], v[228:229], 0, s[12:13]
	s_mov_b32 m0, s64
	s_nop 0
	global_load_lds_dwordx4 v[224:225], off
	v_mfma_f32_16x16x32_bf16 v[4:7], v[168:171], v[216:219], v[4:7]
	v_mfma_f32_16x16x32_bf16 v[0:3], v[176:179], v[216:219], v[0:3]
	s_setprio 0
	s_setprio 1
	v_mfma_f32_16x16x32_bf16 v[60:63], v[148:151], v[190:193], v[60:63]
	v_mfma_f32_16x16x32_bf16 v[56:59], v[164:167], v[190:193], v[56:59]
	v_mfma_f32_16x16x32_bf16 v[52:55], v[172:175], v[190:193], v[52:55]
	v_mfma_f32_16x16x32_bf16 v[48:51], v[182:185], v[190:193], v[48:51]
	v_mfma_f32_16x16x32_bf16 v[44:47], v[148:151], v[198:201], v[44:47]
	v_mfma_f32_16x16x32_bf16 v[40:43], v[164:167], v[198:201], v[40:43]
	v_mfma_f32_16x16x32_bf16 v[36:39], v[172:175], v[198:201], v[36:39]
	v_mfma_f32_16x16x32_bf16 v[32:35], v[182:185], v[198:201], v[32:35]
	v_mfma_f32_16x16x32_bf16 v[28:31], v[148:151], v[212:215], v[28:31]
	v_mfma_f32_16x16x32_bf16 v[24:27], v[164:167], v[212:215], v[24:27]
	v_mfma_f32_16x16x32_bf16 v[20:23], v[172:175], v[212:215], v[20:23]
	v_mfma_f32_16x16x32_bf16 v[16:19], v[182:185], v[212:215], v[16:19]
	v_mfma_f32_16x16x32_bf16 v[12:15], v[148:151], v[220:223], v[12:15]
	v_mfma_f32_16x16x32_bf16 v[8:11], v[164:167], v[220:223], v[8:11]
	v_lshl_add_u64 v[224:225], v[230:231], 0, s[12:13]
	s_mov_b32 m0, s65
	s_nop 0
	global_load_lds_dwordx4 v[224:225], off
	v_mfma_f32_16x16x32_bf16 v[4:7], v[172:175], v[220:223], v[4:7]
	v_mfma_f32_16x16x32_bf16 v[0:3], v[182:185], v[220:223], v[0:3]
	s_setprio 0
	s_barrier
	s_add_i32 s84, s84, 2
	s_add_u32 s54, s54, 0x100
	s_addc_u32 s55, s55, 0
	s_add_u32 s82, s82, 0x100
	s_addc_u32 s83, s83, 0
.LBB0_1119:
	ds_read_b128 v[144:147], v155
	ds_read_b128 v[148:151], v155 offset:1024
	ds_read_b128 v[160:163], v155 offset:2048
	ds_read_b128 v[164:167], v155 offset:3072
	ds_read_b128 v[168:171], v156
	ds_read_b128 v[172:175], v156 offset:1024
	ds_read_b128 v[176:179], v156 offset:2048
	ds_read_b128 v[182:185], v156 offset:3072
	s_add_u32 s56, s54, 0xfffc0080
	s_addc_u32 s57, s55, -1
	s_cmp_eq_u32 s84, 12
	s_cselect_b32 s59, s45, s57
	s_cselect_b32 s58, s76, s56
	s_cselect_b32 s57, s43, s83
	s_cselect_b32 s56, s77, s82
	v_lshl_add_u64 v[224:225], s[54:55], 0, v[136:137]
	s_add_i32 m0, s53, 0xc000
	ds_read_b128 v[186:189], v157
	ds_read_b128 v[190:193], v157 offset:1024
	ds_read_b128 v[194:197], v157 offset:2048
	ds_read_b128 v[198:201], v157 offset:3072
	ds_read_b128 v[208:211], v157 offset:4096
	ds_read_b128 v[212:215], v157 offset:5120
	ds_read_b128 v[216:219], v157 offset:6144
	ds_read_b128 v[220:223], v157 offset:7168
	global_load_lds_dwordx4 v[224:225], off
	v_lshl_add_u64 v[224:225], s[54:55], 0, v[138:139]
	s_add_i32 m0, s53, 0xe000
	s_nop 0
	global_load_lds_dwordx4 v[224:225], off
	s_waitcnt vmcnt(8)
	s_waitcnt lgkmcnt(0)
	s_barrier
; #define PG8_STAGE(bufoff, gbase, voff) do { _Pragma("unroll") for (int _i = 0; _i < 2; ++_i) \
;         __builtin_amdgcn_global_load_lds((const unsigned*)((const char*)(gbase) + (voff)[_i]), (PG8_LAS unsigned*)(lds + (bufoff) + ldsw + _i * 8192), 16, 0, 0); } while (0)
; #define PG8_LDA(dst, b, h) do { _Pragma("unroll") for (int m = 0; m < 4; ++m) _Pragma("unroll") for (int k = 0; k < 2; ++k) dst[m][k] = *(const PG8_LAS bf16x8*)(lds + PG8_SA(b, h) + aoff + m * 2048 + k * 1024); } while (0)
; #define PG8_MMA(ai, bj, At, Bt) do { __builtin_amdgcn_s_setprio(1); _Pragma("unroll") for (int m = 0; m < 4; ++m) _Pragma("unroll") for (int n = 0; n < 2; ++n) _Pragma("unroll") for (int k = 0; k < 2; ++k) \
;         acc[ai][bj][m][n] = __builtin_amdgcn_mfma_f32_16x16x32_bf16(Bt[n][k], At[m][k], acc[ai][bj][m][n], 0, 0, 0); __builtin_amdgcn_s_setprio(0); } while (0)
; #define PG8_WAIT_V(n) asm volatile("s_waitcnt vmcnt(" #n ")" ::: "memory")
; #define PG8_WAIT_L(n) asm volatile("s_waitcnt lgkmcnt(" #n ")" ::: "memory")
; #define PG8_BAR __builtin_amdgcn_s_barrier()
; #define PG8_SCHED __builtin_amdgcn_sched_barrier(0)
; template <class Epi, class Sched, bool ALIGN_EPI = false, bool SP2 = false>
; __device__ __forceinline__ void gemm_phase(PG8_LAS unsigned char* lds, const Gemm g, const Sched& S, const Epi& E) {
;     ...
;             PG8_WAIT_V(8); PG8_WAIT_L(0); PG8_BAR; PG8_MMA(0, 0, At, B0); PG8_MMA(0, 1, At, B1); PG8_BAR; PG8_SCHED;
;             PG8_LDA(At, 0, 1); PG8_STAGE(PG8_SB(0, 0), b2, voffB); PG8_STAGE(PG8_SB(0, 1), b2 + hstep, voffB); PG8_STAGE(PG8_SA(0, 0), a2, voffA);
;             PG8_WAIT_V(8); PG8_WAIT_L(0); PG8_BAR; PG8_MMA(1, 0, At, B0); PG8_MMA(1, 1, At, B1); PG8_BAR; PG8_SCHED;
	s_setprio 1
	s_waitcnt lgkmcnt(0)
	v_mfma_f32_16x16x32_bf16 v[124:127], v[144:147], v[186:189], v[124:127]
	v_mfma_f32_16x16x32_bf16 v[120:123], v[160:163], v[186:189], v[120:123]
	v_mfma_f32_16x16x32_bf16 v[116:119], v[168:171], v[186:189], v[116:119]
	v_mfma_f32_16x16x32_bf16 v[112:115], v[176:179], v[186:189], v[112:115]
	v_mfma_f32_16x16x32_bf16 v[108:111], v[144:147], v[194:197], v[108:111]
	v_mfma_f32_16x16x32_bf16 v[104:107], v[160:163], v[194:197], v[104:107]
	v_mfma_f32_16x16x32_bf16 v[100:103], v[168:171], v[194:197], v[100:103]
	v_mfma_f32_16x16x32_bf16 v[96:99], v[176:179], v[194:197], v[96:99]
	v_mfma_f32_16x16x32_bf16 v[92:95], v[144:147], v[208:211], v[92:95]
	v_mfma_f32_16x16x32_bf16 v[88:91], v[160:163], v[208:211], v[88:91]
	v_mfma_f32_16x16x32_bf16 v[84:87], v[168:171], v[208:211], v[84:87]
	v_mfma_f32_16x16x32_bf16 v[80:83], v[176:179], v[208:211], v[80:83]
	v_mfma_f32_16x16x32_bf16 v[76:79], v[144:147], v[216:219], v[76:79]
	v_mfma_f32_16x16x32_bf16 v[72:75], v[160:163], v[216:219], v[72:75]
	v_mfma_f32_16x16x32_bf16 v[68:71], v[168:171], v[216:219], v[68:71]
	v_mfma_f32_16x16x32_bf16 v[64:67], v[176:179], v[216:219], v[64:67]
	s_setprio 0
	s_setprio 1
	v_mfma_f32_16x16x32_bf16 v[124:127], v[148:151], v[190:193], v[124:127]
	v_mfma_f32_16x16x32_bf16 v[120:123], v[164:167], v[190:193], v[120:123]
	v_mfma_f32_16x16x32_bf16 v[116:119], v[172:175], v[190:193], v[116:119]
	v_mfma_f32_16x16x32_bf16 v[112:115], v[182:185], v[190:193], v[112:115]
	v_mfma_f32_16x16x32_bf16 v[108:111], v[148:151], v[198:201], v[108:111]
	v_mfma_f32_16x16x32_bf16 v[104:107], v[164:167], v[198:201], v[104:107]
	v_mfma_f32_16x16x32_bf16 v[100:103], v[172:175], v[198:201], v[100:103]
	v_mfma_f32_16x16x32_bf16 v[96:99], v[182:185], v[198:201], v[96:99]
	v_mfma_f32_16x16x32_bf16 v[92:95], v[148:151], v[212:215], v[92:95]
	v_mfma_f32_16x16x32_bf16 v[88:91], v[164:167], v[212:215], v[88:91]
	v_mfma_f32_16x16x32_bf16 v[84:87], v[172:175], v[212:215], v[84:87]
	v_mfma_f32_16x16x32_bf16 v[80:83], v[182:185], v[212:215], v[80:83]
	v_mfma_f32_16x16x32_bf16 v[76:79], v[148:151], v[220:223], v[76:79]
	v_mfma_f32_16x16x32_bf16 v[72:75], v[164:167], v[220:223], v[72:75]
	v_mfma_f32_16x16x32_bf16 v[68:71], v[172:175], v[220:223], v[68:71]
	v_mfma_f32_16x16x32_bf16 v[64:67], v[182:185], v[220:223], v[64:67]
	s_setprio 0
	s_barrier
	s_add_i32 s78, s66, s33
	v_lshl_add_u64 v[224:225], s[56:57], 0, v[132:133]
	s_mov_b32 m0, s78
	ds_read_b128 v[186:189], v157 offset:16384
	ds_read_b128 v[190:193], v157 offset:17408
	ds_read_b128 v[194:197], v157 offset:18432
	ds_read_b128 v[198:201], v157 offset:19456
	ds_read_b128 v[208:211], v157 offset:20480
	ds_read_b128 v[212:215], v157 offset:21504
	ds_read_b128 v[216:219], v157 offset:22528
	ds_read_b128 v[220:223], v157 offset:23552
	global_load_lds_dwordx4 v[224:225], off
	s_add_i32 m0, s78, 0x2000
	s_add_u32 s78, s56, 0x40000
	v_lshl_add_u64 v[226:227], s[56:57], 0, v[128:129]
	s_addc_u32 s79, s57, 0
	s_add_i32 s85, s67, s33
	global_load_lds_dwordx4 v[226:227], off
	v_lshl_add_u64 v[228:229], s[78:79], 0, v[132:133]
	s_mov_b32 m0, s85
	global_load_lds_dwordx4 v[228:229], off
	v_lshl_add_u64 v[228:229], s[78:79], 0, v[128:129]
	s_add_i32 m0, s85, 0x2000
	s_nop 0
	global_load_lds_dwordx4 v[228:229], off
	s_waitcnt vmcnt(6)
	s_waitcnt lgkmcnt(0)
	s_barrier
	s_setprio 1
	s_waitcnt lgkmcnt(0)
	v_mfma_f32_16x16x32_bf16 v[60:63], v[144:147], v[186:189], v[60:63]
	v_mfma_f32_16x16x32_bf16 v[56:59], v[160:163], v[186:189], v[56:59]
	v_mfma_f32_16x16x32_bf16 v[52:55], v[168:171], v[186:189], v[52:55]
	v_mfma_f32_16x16x32_bf16 v[48:51], v[176:179], v[186:189], v[48:51]
	v_mfma_f32_16x16x32_bf16 v[44:47], v[144:147], v[194:197], v[44:47]
	v_mfma_f32_16x16x32_bf16 v[40:43], v[160:163], v[194:197], v[40:43]
	v_mfma_f32_16x16x32_bf16 v[36:39], v[168:171], v[194:197], v[36:39]
	v_mfma_f32_16x16x32_bf16 v[32:35], v[176:179], v[194:197], v[32:35]
	v_mfma_f32_16x16x32_bf16 v[28:31], v[144:147], v[208:211], v[28:31]
	v_mfma_f32_16x16x32_bf16 v[24:27], v[160:163], v[208:211], v[24:27]
	v_mfma_f32_16x16x32_bf16 v[20:23], v[168:171], v[208:211], v[20:23]
	v_mfma_f32_16x16x32_bf16 v[16:19], v[176:179], v[208:211], v[16:19]
	v_mfma_f32_16x16x32_bf16 v[12:15], v[144:147], v[216:219], v[12:15]
	v_mfma_f32_16x16x32_bf16 v[8:11], v[160:163], v[216:219], v[8:11]
	v_lshl_add_u64 v[228:229], s[58:59], 0, v[134:135]
	s_mov_b32 m0, s53
	s_nop 0
	global_load_lds_dwordx4 v[228:229], off
	v_mfma_f32_16x16x32_bf16 v[4:7], v[168:171], v[216:219], v[4:7]
	v_mfma_f32_16x16x32_bf16 v[0:3], v[176:179], v[216:219], v[0:3]
	s_setprio 0
	s_setprio 1
	v_mfma_f32_16x16x32_bf16 v[60:63], v[148:151], v[190:193], v[60:63]
	v_mfma_f32_16x16x32_bf16 v[56:59], v[164:167], v[190:193], v[56:59]
	v_mfma_f32_16x16x32_bf16 v[52:55], v[172:175], v[190:193], v[52:55]
	v_mfma_f32_16x16x32_bf16 v[48:51], v[182:185], v[190:193], v[48:51]
	v_mfma_f32_16x16x32_bf16 v[44:47], v[148:151], v[198:201], v[44:47]
	v_mfma_f32_16x16x32_bf16 v[40:43], v[164:167], v[198:201], v[40:43]
	v_mfma_f32_16x16x32_bf16 v[36:39], v[172:175], v[198:201], v[36:39]
	v_mfma_f32_16x16x32_bf16 v[32:35], v[182:185], v[198:201], v[32:35]
	v_mfma_f32_16x16x32_bf16 v[28:31], v[148:151], v[212:215], v[28:31]
	v_mfma_f32_16x16x32_bf16 v[24:27], v[164:167], v[212:215], v[24:27]
	v_mfma_f32_16x16x32_bf16 v[20:23], v[172:175], v[212:215], v[20:23]
	v_mfma_f32_16x16x32_bf16 v[16:19], v[182:185], v[212:215], v[16:19]
	v_mfma_f32_16x16x32_bf16 v[12:15], v[148:151], v[220:223], v[12:15]
	v_mfma_f32_16x16x32_bf16 v[8:11], v[164:167], v[220:223], v[8:11]
	v_lshl_add_u64 v[230:231], s[58:59], 0, v[130:131]
	s_mov_b32 m0, s60
	s_nop 0
	global_load_lds_dwordx4 v[230:231], off
	v_mfma_f32_16x16x32_bf16 v[4:7], v[172:175], v[220:223], v[4:7]
	v_mfma_f32_16x16x32_bf16 v[0:3], v[182:185], v[220:223], v[0:3]
	s_setprio 0
	s_barrier
; #define PG8_STAGE(bufoff, gbase, voff) do { _Pragma("unroll") for (int _i = 0; _i < 2; ++_i) \
;         __builtin_amdgcn_global_load_lds((const unsigned*)((const char*)(gbase) + (voff)[_i]), (PG8_LAS unsigned*)(lds + (bufoff) + ldsw + _i * 8192), 16, 0, 0); } while (0)
; #define PG8_LDA(dst, b, h) do { _Pragma("unroll") for (int m = 0; m < 4; ++m) _Pragma("unroll") for (int k = 0; k < 2; ++k) dst[m][k] = *(const PG8_LAS bf16x8*)(lds + PG8_SA(b, h) + aoff + m * 2048 + k * 1024); } while (0)
; #define PG8_LDB(dst, b, h) do { _Pragma("unroll") for (int n = 0; n < 2; ++n) _Pragma("unroll") for (int k = 0; k < 2; ++k) dst[n][k] = *(const PG8_LAS bf16x8*)(lds + PG8_SB(b, h) + boff + n * 2048 + k * 1024); } while (0)
; #define PG8_MMA(ai, bj, At, Bt) do { __builtin_amdgcn_s_setprio(1); _Pragma("unroll") for (int m = 0; m < 4; ++m) _Pragma("unroll") for (int n = 0; n < 2; ++n) _Pragma("unroll") for (int k = 0; k < 2; ++k) \
;         acc[ai][bj][m][n] = __builtin_amdgcn_mfma_f32_16x16x32_bf16(Bt[n][k], At[m][k], acc[ai][bj][m][n], 0, 0, 0); __builtin_amdgcn_s_setprio(0); } while (0)
; #define PG8_WAIT_V(n) asm volatile("s_waitcnt vmcnt(" #n ")" ::: "memory")
; #define PG8_WAIT_L(n) asm volatile("s_waitcnt lgkmcnt(" #n ")" ::: "memory")
; #define PG8_BAR __builtin_amdgcn_s_barrier()
; #define PG8_SCHED __builtin_amdgcn_sched_barrier(0)
; template <class Epi, class Sched, bool ALIGN_EPI = false, bool SP2 = false>
; __device__ __forceinline__ void gemm_phase(PG8_LAS unsigned char* lds, const Gemm g, const Sched& S, const Epi& E) {
;     ...
;             PG8_LDB(B0, 1, 0); PG8_LDB(B1, 1, 1); PG8_SCHED; PG8_LDA(At, 1, 0); PG8_STAGE(PG8_SA(0, 1), a2 + hstep, voffA);
;             PG8_WAIT_V(8); PG8_WAIT_L(0); PG8_BAR; PG8_MMA(0, 0, At, B0); PG8_MMA(0, 1, At, B1); PG8_BAR; PG8_SCHED;
	s_add_i32 s78, 0, 0x18000
	v_add_u32_e32 v159, s78, v153
	s_add_i32 s79, 0, 0x1c000
	ds_read_b128 v[144:147], v159
	ds_read_b128 v[148:151], v159 offset:1024
	ds_read_b128 v[160:163], v159 offset:2048
	ds_read_b128 v[164:167], v159 offset:3072
	v_add_u32_e32 v159, s79, v153
	ds_read_b128 v[168:171], v159
	ds_read_b128 v[172:175], v159 offset:1024
	ds_read_b128 v[176:179], v159 offset:2048
	ds_read_b128 v[182:185], v159 offset:3072
	s_add_u32 s58, s58, 0x40000
	s_addc_u32 s59, s59, 0
	s_mov_b32 m0, s61
	v_lshl_add_u64 v[232:233], s[58:59], 0, v[134:135]
	ds_read_b128 v[186:189], v157 offset:32768
	ds_read_b128 v[190:193], v157 offset:33792
	ds_read_b128 v[194:197], v157 offset:34816
	ds_read_b128 v[198:201], v157 offset:35840
	ds_read_b128 v[208:211], v157 offset:36864
	ds_read_b128 v[212:215], v157 offset:37888
	ds_read_b128 v[216:219], v157 offset:38912
	ds_read_b128 v[220:223], v157 offset:39936
	global_load_lds_dwordx4 v[232:233], off
	v_lshl_add_u64 v[232:233], s[58:59], 0, v[130:131]
	s_mov_b32 m0, s62
	s_nop 0
	global_load_lds_dwordx4 v[232:233], off
	s_waitcnt vmcnt(8)
	s_waitcnt lgkmcnt(0)
	s_barrier
	s_setprio 1
	s_waitcnt lgkmcnt(0)
	v_mfma_f32_16x16x32_bf16 v[124:127], v[144:147], v[186:189], v[124:127]
	v_mfma_f32_16x16x32_bf16 v[120:123], v[160:163], v[186:189], v[120:123]
	v_mfma_f32_16x16x32_bf16 v[116:119], v[168:171], v[186:189], v[116:119]
	v_mfma_f32_16x16x32_bf16 v[112:115], v[176:179], v[186:189], v[112:115]
	v_mfma_f32_16x16x32_bf16 v[108:111], v[144:147], v[194:197], v[108:111]
	v_mfma_f32_16x16x32_bf16 v[104:107], v[160:163], v[194:197], v[104:107]
	v_mfma_f32_16x16x32_bf16 v[100:103], v[168:171], v[194:197], v[100:103]
	v_mfma_f32_16x16x32_bf16 v[96:99], v[176:179], v[194:197], v[96:99]
	v_mfma_f32_16x16x32_bf16 v[92:95], v[144:147], v[208:211], v[92:95]
	v_mfma_f32_16x16x32_bf16 v[88:91], v[160:163], v[208:211], v[88:91]
	v_mfma_f32_16x16x32_bf16 v[84:87], v[168:171], v[208:211], v[84:87]
	v_mfma_f32_16x16x32_bf16 v[80:83], v[176:179], v[208:211], v[80:83]
	v_mfma_f32_16x16x32_bf16 v[76:79], v[144:147], v[216:219], v[76:79]
	v_mfma_f32_16x16x32_bf16 v[72:75], v[160:163], v[216:219], v[72:75]
	v_mfma_f32_16x16x32_bf16 v[68:71], v[168:171], v[216:219], v[68:71]
	v_mfma_f32_16x16x32_bf16 v[64:67], v[176:179], v[216:219], v[64:67]
	s_setprio 0
	s_setprio 1
	v_mfma_f32_16x16x32_bf16 v[124:127], v[148:151], v[190:193], v[124:127]
	v_mfma_f32_16x16x32_bf16 v[120:123], v[164:167], v[190:193], v[120:123]
	v_mfma_f32_16x16x32_bf16 v[116:119], v[172:175], v[190:193], v[116:119]
	v_mfma_f32_16x16x32_bf16 v[112:115], v[182:185], v[190:193], v[112:115]
	v_mfma_f32_16x16x32_bf16 v[108:111], v[148:151], v[198:201], v[108:111]
	v_mfma_f32_16x16x32_bf16 v[104:107], v[164:167], v[198:201], v[104:107]
	v_mfma_f32_16x16x32_bf16 v[100:103], v[172:175], v[198:201], v[100:103]
	v_mfma_f32_16x16x32_bf16 v[96:99], v[182:185], v[198:201], v[96:99]
	v_mfma_f32_16x16x32_bf16 v[92:95], v[148:151], v[212:215], v[92:95]
	v_mfma_f32_16x16x32_bf16 v[88:91], v[164:167], v[212:215], v[88:91]
	v_mfma_f32_16x16x32_bf16 v[84:87], v[172:175], v[212:215], v[84:87]
	v_mfma_f32_16x16x32_bf16 v[80:83], v[182:185], v[212:215], v[80:83]
	v_mfma_f32_16x16x32_bf16 v[76:79], v[148:151], v[220:223], v[76:79]
	v_mfma_f32_16x16x32_bf16 v[72:75], v[164:167], v[220:223], v[72:75]
	v_mfma_f32_16x16x32_bf16 v[68:71], v[172:175], v[220:223], v[68:71]
	v_mfma_f32_16x16x32_bf16 v[64:67], v[182:185], v[220:223], v[64:67]
	s_setprio 0
	s_barrier
; #define PG8_STAGE(bufoff, gbase, voff) do { _Pragma("unroll") for (int _i = 0; _i < 2; ++_i) \
;         __builtin_amdgcn_global_load_lds((const unsigned*)((const char*)(gbase) + (voff)[_i]), (PG8_LAS unsigned*)(lds + (bufoff) + ldsw + _i * 8192), 16, 0, 0); } while (0)
; #define PG8_LDA(dst, b, h) do { _Pragma("unroll") for (int m = 0; m < 4; ++m) _Pragma("unroll") for (int k = 0; k < 2; ++k) dst[m][k] = *(const PG8_LAS bf16x8*)(lds + PG8_SA(b, h) + aoff + m * 2048 + k * 1024); } while (0)
; #define PG8_MMA(ai, bj, At, Bt) do { __builtin_amdgcn_s_setprio(1); _Pragma("unroll") for (int m = 0; m < 4; ++m) _Pragma("unroll") for (int n = 0; n < 2; ++n) _Pragma("unroll") for (int k = 0; k < 2; ++k) \
;         acc[ai][bj][m][n] = __builtin_amdgcn_mfma_f32_16x16x32_bf16(Bt[n][k], At[m][k], acc[ai][bj][m][n], 0, 0, 0); __builtin_amdgcn_s_setprio(0); } while (0)
; #define PG8_WAIT_V(n) asm volatile("s_waitcnt vmcnt(" #n ")" ::: "memory")
; #define PG8_WAIT_L(n) asm volatile("s_waitcnt lgkmcnt(" #n ")" ::: "memory")
; #define PG8_BAR __builtin_amdgcn_s_barrier()
; #define PG8_SCHED __builtin_amdgcn_sched_barrier(0)
; __device__ __forceinline__ float row_rs(const float* ssp, int row) { const unsigned long long v = ((const unsigned long long*)ssp)[row];
;     return __builtin_amdgcn_rsqf((float)v * (1.0f / 4294967296.0f) * (1.0f / 1024.0f) + RMS_EPS); }
; template <class Epi, class Sched, bool ALIGN_EPI = false, bool SP2 = false>
; __device__ __forceinline__ void gemm_phase(PG8_LAS unsigned char* lds, const Gemm g, const Sched& S, const Epi& E) {
;     ...
;             PG8_LDA(At, 1, 1); PG8_STAGE(PG8_SB(1, 0), b3, voffB); PG8_STAGE(PG8_SB(1, 1), b3 + hstep, voffB); PG8_STAGE(PG8_SA(1, 0), a3, voffA);
;             PG8_WAIT_V(8); PG8_WAIT_L(0); PG8_BAR; PG8_MMA(1, 0, At, B0); PG8_MMA(1, 1, At, B1); PG8_BAR; PG8_SCHED;
	s_add_i32 s58, s78, s33
	v_lshl_add_u64 v[224:225], v[224:225], 0, s[12:13]
	s_mov_b32 m0, s58
	ds_read_b128 v[186:189], v157 offset:49152
	ds_read_b128 v[190:193], v157 offset:50176
	ds_read_b128 v[194:197], v157 offset:51200
	ds_read_b128 v[198:201], v157 offset:52224
	ds_read_b128 v[208:211], v157 offset:53248
	ds_read_b128 v[212:215], v157 offset:54272
	ds_read_b128 v[216:219], v157 offset:55296
	ds_read_b128 v[220:223], v157 offset:56320
	global_load_lds_dwordx4 v[224:225], off
	s_add_i32 m0, s58, 0x2000
	s_add_u32 s56, s56, 0x40080
	v_lshl_add_u64 v[224:225], v[226:227], 0, s[12:13]
	s_addc_u32 s57, s57, 0
	s_add_i32 s58, s79, s33
	global_load_lds_dwordx4 v[224:225], off
	v_lshl_add_u64 v[224:225], s[56:57], 0, v[132:133]
	s_mov_b32 m0, s58
	s_nop 0
	global_load_lds_dwordx4 v[224:225], off
	v_lshl_add_u64 v[224:225], s[56:57], 0, v[128:129]
	s_add_i32 m0, s58, 0x2000
	s_nop 0
	global_load_lds_dwordx4 v[224:225], off
	s_waitcnt vmcnt(6)
	s_waitcnt lgkmcnt(0)
	s_barrier
	s_setprio 1
	s_waitcnt lgkmcnt(0)
	v_mfma_f32_16x16x32_bf16 v[60:63], v[144:147], v[186:189], v[60:63]
	v_mfma_f32_16x16x32_bf16 v[56:59], v[160:163], v[186:189], v[56:59]
	v_mfma_f32_16x16x32_bf16 v[52:55], v[168:171], v[186:189], v[52:55]
	v_mfma_f32_16x16x32_bf16 v[48:51], v[176:179], v[186:189], v[48:51]
	v_mfma_f32_16x16x32_bf16 v[44:47], v[144:147], v[194:197], v[44:47]
	v_mfma_f32_16x16x32_bf16 v[40:43], v[160:163], v[194:197], v[40:43]
	v_mfma_f32_16x16x32_bf16 v[36:39], v[168:171], v[194:197], v[36:39]
	v_mfma_f32_16x16x32_bf16 v[32:35], v[176:179], v[194:197], v[32:35]
	v_mfma_f32_16x16x32_bf16 v[28:31], v[144:147], v[208:211], v[28:31]
	v_mfma_f32_16x16x32_bf16 v[24:27], v[160:163], v[208:211], v[24:27]
	v_mfma_f32_16x16x32_bf16 v[20:23], v[168:171], v[208:211], v[20:23]
	v_mfma_f32_16x16x32_bf16 v[16:19], v[176:179], v[208:211], v[16:19]
	v_mfma_f32_16x16x32_bf16 v[12:15], v[144:147], v[216:219], v[12:15]
	v_mfma_f32_16x16x32_bf16 v[8:11], v[160:163], v[216:219], v[8:11]
	v_lshl_add_u64 v[224:225], v[228:229], 0, s[12:13]
	s_mov_b32 m0, s64
	s_nop 0
	global_load_lds_dwordx4 v[224:225], off
	v_mfma_f32_16x16x32_bf16 v[4:7], v[168:171], v[216:219], v[4:7]
	v_mfma_f32_16x16x32_bf16 v[0:3], v[176:179], v[216:219], v[0:3]
	s_setprio 0
	s_setprio 1
	v_mfma_f32_16x16x32_bf16 v[60:63], v[148:151], v[190:193], v[60:63]
	v_mfma_f32_16x16x32_bf16 v[56:59], v[164:167], v[190:193], v[56:59]
	v_mfma_f32_16x16x32_bf16 v[52:55], v[172:175], v[190:193], v[52:55]
	v_mfma_f32_16x16x32_bf16 v[48:51], v[182:185], v[190:193], v[48:51]
	v_mfma_f32_16x16x32_bf16 v[44:47], v[148:151], v[198:201], v[44:47]
	v_mfma_f32_16x16x32_bf16 v[40:43], v[164:167], v[198:201], v[40:43]
	v_mfma_f32_16x16x32_bf16 v[36:39], v[172:175], v[198:201], v[36:39]
	v_mfma_f32_16x16x32_bf16 v[32:35], v[182:185], v[198:201], v[32:35]
	v_mfma_f32_16x16x32_bf16 v[28:31], v[148:151], v[212:215], v[28:31]
	v_mfma_f32_16x16x32_bf16 v[24:27], v[164:167], v[212:215], v[24:27]
	v_mfma_f32_16x16x32_bf16 v[20:23], v[172:175], v[212:215], v[20:23]
	v_mfma_f32_16x16x32_bf16 v[16:19], v[182:185], v[212:215], v[16:19]
	v_mfma_f32_16x16x32_bf16 v[12:15], v[148:151], v[220:223], v[12:15]
	v_mfma_f32_16x16x32_bf16 v[8:11], v[164:167], v[220:223], v[8:11]
	v_lshl_add_u64 v[224:225], v[230:231], 0, s[12:13]
	s_mov_b32 m0, s65
	s_nop 0
	global_load_lds_dwordx4 v[224:225], off
	v_mfma_f32_16x16x32_bf16 v[4:7], v[172:175], v[220:223], v[4:7]
	v_mfma_f32_16x16x32_bf16 v[0:3], v[182:185], v[220:223], v[0:3]
	s_setprio 0
	s_barrier
	s_add_i32 s84, s84, 2
	s_add_u32 s54, s54, 0x100
	s_addc_u32 s55, s55, 0
	s_add_u32 s82, s82, 0x100
	s_addc_u32 s83, s83, 0
	s_cmp_gt_u32 s84, 13
	s_cbranch_scc0 .LBB0_1119
	v_lshl_add_u32 v144, s52, 8, v152
	v_ashrrev_i32_e32 v145, 31, v144
	v_lshl_add_u64 v[150:151], v[144:145], 3, s[36:37]
	global_load_dwordx2 v[182:183], v[150:151], off
	global_load_dwordx2 v[184:185], v[150:151], off offset:128
	global_load_dwordx2 v[186:187], v[150:151], off offset:256
	global_load_dwordx2 v[188:189], v[150:151], off offset:384
	global_load_dwordx2 v[190:191], v[150:151], off offset:1024
	global_load_dwordx2 v[192:193], v[150:151], off offset:1152
	global_load_dwordx2 v[194:195], v[150:151], off offset:1280
	global_load_dwordx2 v[196:197], v[150:151], off offset:1408
	s_and_b64 vcc, exec, s[38:39]
	s_cbranch_vccz .LBB0_1122
	s_barrier

; #define PG8_STAGE(bufoff, gbase, voff) do { _Pragma("unroll") for (int _i = 0; _i < 2; ++_i) \
;         __builtin_amdgcn_global_load_lds((const unsigned*)((const char*)(gbase) + (voff)[_i]), (PG8_LAS unsigned*)(lds + (bufoff) + ldsw + _i * 8192), 16, 0, 0); } while (0)
; #define PG8_LDA(dst, b, h) do { _Pragma("unroll") for (int m = 0; m < 4; ++m) _Pragma("unroll") for (int k = 0; k < 2; ++k) dst[m][k] = *(const PG8_LAS bf16x8*)(lds + PG8_SA(b, h) + aoff + m * 2048 + k * 1024); } while (0)
; #define PG8_LDB(dst, b, h) do { _Pragma("unroll") for (int n = 0; n < 2; ++n) _Pragma("unroll") for (int k = 0; k < 2; ++k) dst[n][k] = *(const PG8_LAS bf16x8*)(lds + PG8_SB(b, h) + boff + n * 2048 + k * 1024); } while (0)
; #define PG8_MMA(ai, bj, At, Bt) do { __builtin_amdgcn_s_setprio(1); _Pragma("unroll") for (int m = 0; m < 4; ++m) _Pragma("unroll") for (int n = 0; n < 2; ++n) _Pragma("unroll") for (int k = 0; k < 2; ++k) \
;         acc[ai][bj][m][n] = __builtin_amdgcn_mfma_f32_16x16x32_bf16(Bt[n][k], At[m][k], acc[ai][bj][m][n], 0, 0, 0); __builtin_amdgcn_s_setprio(0); } while (0)
; #define PG8_WAIT_V(n) asm volatile("s_waitcnt vmcnt(" #n ")" ::: "memory")
; #define PG8_WAIT_L(n) asm volatile("s_waitcnt lgkmcnt(" #n ")" ::: "memory")
; #define PG8_BAR __builtin_amdgcn_s_barrier()
; #define PG8_SCHED __builtin_amdgcn_sched_barrier(0)
; template <class Epi, class Sched, bool ALIGN_EPI = false, bool SP2 = false>
; __device__ __forceinline__ void gemm_phase(PG8_LAS unsigned char* lds, const Gemm g, const Sched& S, const Epi& E) {
;     ...
;             const bool last = (t == nt - 2);
;             const char* a1 = cA + (size_t)(t + 1) * kstep;
;             const char* a2 = last ? nA : cA + (size_t)(t + 2) * kstep; const char* b2 = last ? nB : cB + (size_t)(t + 2) * kstep;
;             const char* a3 = a2 + kstep; const char* b3 = b2 + kstep;
;             if (last && has_next) S.a_ready(nxt);
;             if constexpr (SP2) {
;             PG8_LDB(B0, 0, 0); PG8_LDB(B1, 0, 1); PG8_SCHED; PG8_LDA(At, 0, 0); PG8_STAGE(PG8_SA(1, 1), a1 + hstep, voffA);
;             PG8_WAIT_V(8); PG8_WAIT_L(0); PG8_BAR; PG8_MMA(0, 0, At, B0); PG8_MMA(0, 1, At, B1); PG8_BAR; PG8_SCHED;
;             PG8_LDA(At, 0, 1); PG8_STAGE(PG8_SB(0, 0), b2, voffB); PG8_STAGE(PG8_SB(0, 1), b2 + hstep, voffB); PG8_STAGE(PG8_SA(0, 0), a2, voffA);
.LBB0_1196:
	s_add_u32 s82, s52, 0x100
	s_addc_u32 s83, s53, 0
	s_mov_b32 s84, -2
	s_waitcnt lgkmcnt(0)
	ds_read_b128 v[144:147], v151
	ds_read_b128 v[156:159], v151 offset:1024
	ds_read_b128 v[160:163], v151 offset:2048
	ds_read_b128 v[164:167], v151 offset:3072
	ds_read_b128 v[168:171], v152
	ds_read_b128 v[172:175], v152 offset:1024
	ds_read_b128 v[176:179], v152 offset:2048
	ds_read_b128 v[182:185], v152 offset:3072
	s_add_u32 s52, s50, 0x100
	s_addc_u32 s53, s51, 0
	s_cmp_eq_u32 s84, 40
	s_cselect_b32 s57, s1, s53
	s_cselect_b32 s56, s0, s52
	s_cselect_b32 s55, s49, s83
	s_cselect_b32 s54, s48, s82
	v_lshl_add_u64 v[224:225], s[50:51], 0, v[136:137]
	s_add_i32 m0, s34, 0xc000
	ds_read_b128 v[186:189], v153
	ds_read_b128 v[190:193], v153 offset:1024
	ds_read_b128 v[194:197], v153 offset:2048
	ds_read_b128 v[198:201], v153 offset:3072
	ds_read_b128 v[208:211], v153 offset:4096
	ds_read_b128 v[212:215], v153 offset:5120
	ds_read_b128 v[216:219], v153 offset:6144
	ds_read_b128 v[220:223], v153 offset:7168
	global_load_lds_dwordx4 v[224:225], off
	v_lshl_add_u64 v[224:225], s[50:51], 0, v[138:139]
	s_add_i32 m0, s34, 0xe000
	s_nop 0
	global_load_lds_dwordx4 v[224:225], off
	s_waitcnt vmcnt(8)
	s_waitcnt lgkmcnt(0)
	s_barrier
	s_setprio 1
	s_waitcnt lgkmcnt(0)
	v_mfma_f32_16x16x32_bf16 v[124:127], v[144:147], v[186:189], 0
	v_mfma_f32_16x16x32_bf16 v[120:123], v[160:163], v[186:189], 0
	v_mfma_f32_16x16x32_bf16 v[116:119], v[168:171], v[186:189], 0
	v_mfma_f32_16x16x32_bf16 v[112:115], v[176:179], v[186:189], 0
	v_mfma_f32_16x16x32_bf16 v[108:111], v[144:147], v[194:197], 0
	v_mfma_f32_16x16x32_bf16 v[104:107], v[160:163], v[194:197], 0
	v_mfma_f32_16x16x32_bf16 v[100:103], v[168:171], v[194:197], 0
	v_mfma_f32_16x16x32_bf16 v[96:99], v[176:179], v[194:197], 0
	v_mfma_f32_16x16x32_bf16 v[92:95], v[144:147], v[208:211], 0
	v_mfma_f32_16x16x32_bf16 v[88:91], v[160:163], v[208:211], 0
	v_mfma_f32_16x16x32_bf16 v[84:87], v[168:171], v[208:211], 0
	v_mfma_f32_16x16x32_bf16 v[80:83], v[176:179], v[208:211], 0
	v_mfma_f32_16x16x32_bf16 v[76:79], v[144:147], v[216:219], 0
	v_mfma_f32_16x16x32_bf16 v[72:75], v[160:163], v[216:219], 0
	v_mfma_f32_16x16x32_bf16 v[68:71], v[168:171], v[216:219], 0
	v_mfma_f32_16x16x32_bf16 v[64:67], v[176:179], v[216:219], 0
	s_setprio 0
	s_setprio 1
	v_mfma_f32_16x16x32_bf16 v[124:127], v[156:159], v[190:193], v[124:127]
	v_mfma_f32_16x16x32_bf16 v[120:123], v[164:167], v[190:193], v[120:123]
	v_mfma_f32_16x16x32_bf16 v[116:119], v[172:175], v[190:193], v[116:119]
	v_mfma_f32_16x16x32_bf16 v[112:115], v[182:185], v[190:193], v[112:115]
	v_mfma_f32_16x16x32_bf16 v[108:111], v[156:159], v[198:201], v[108:111]
	v_mfma_f32_16x16x32_bf16 v[104:107], v[164:167], v[198:201], v[104:107]
	v_mfma_f32_16x16x32_bf16 v[100:103], v[172:175], v[198:201], v[100:103]
	v_mfma_f32_16x16x32_bf16 v[96:99], v[182:185], v[198:201], v[96:99]
	v_mfma_f32_16x16x32_bf16 v[92:95], v[156:159], v[212:215], v[92:95]
	v_mfma_f32_16x16x32_bf16 v[88:91], v[164:167], v[212:215], v[88:91]
	v_mfma_f32_16x16x32_bf16 v[84:87], v[172:175], v[212:215], v[84:87]
	v_mfma_f32_16x16x32_bf16 v[80:83], v[182:185], v[212:215], v[80:83]
	v_mfma_f32_16x16x32_bf16 v[76:79], v[156:159], v[220:223], v[76:79]
	v_mfma_f32_16x16x32_bf16 v[72:75], v[164:167], v[220:223], v[72:75]
	v_mfma_f32_16x16x32_bf16 v[68:71], v[172:175], v[220:223], v[68:71]
	v_mfma_f32_16x16x32_bf16 v[64:67], v[182:185], v[220:223], v[64:67]
	s_setprio 0
	s_barrier
	s_add_i32 s50, s64, s33
	v_lshl_add_u64 v[224:225], s[54:55], 0, v[130:131]
	s_mov_b32 m0, s50
	ds_read_b128 v[186:189], v153 offset:16384
	ds_read_b128 v[190:193], v153 offset:17408
	ds_read_b128 v[194:197], v153 offset:18432
	ds_read_b128 v[198:201], v153 offset:19456
	ds_read_b128 v[208:211], v153 offset:20480
	ds_read_b128 v[212:215], v153 offset:21504
	ds_read_b128 v[216:219], v153 offset:22528
	ds_read_b128 v[220:223], v153 offset:23552
	global_load_lds_dwordx4 v[224:225], off
	s_add_i32 m0, s50, 0x2000
	s_add_u32 s50, s54, 0xb0000
	v_lshl_add_u64 v[226:227], s[54:55], 0, v[134:135]
	s_addc_u32 s51, s55, 0
	s_add_i32 s78, s65, s33
	global_load_lds_dwordx4 v[226:227], off
	v_lshl_add_u64 v[228:229], s[50:51], 0, v[130:131]
	s_mov_b32 m0, s78
	global_load_lds_dwordx4 v[228:229], off
	v_lshl_add_u64 v[228:229], s[50:51], 0, v[134:135]
	s_add_i32 m0, s78, 0x2000
	s_nop 0
	global_load_lds_dwordx4 v[228:229], off
	s_waitcnt vmcnt(6)
	s_waitcnt lgkmcnt(0)
	s_barrier
; #define PG8_STAGE(bufoff, gbase, voff) do { _Pragma("unroll") for (int _i = 0; _i < 2; ++_i) \
;         __builtin_amdgcn_global_load_lds((const unsigned*)((const char*)(gbase) + (voff)[_i]), (PG8_LAS unsigned*)(lds + (bufoff) + ldsw + _i * 8192), 16, 0, 0); } while (0)
; #define PG8_LDA(dst, b, h) do { _Pragma("unroll") for (int m = 0; m < 4; ++m) _Pragma("unroll") for (int k = 0; k < 2; ++k) dst[m][k] = *(const PG8_LAS bf16x8*)(lds + PG8_SA(b, h) + aoff + m * 2048 + k * 1024); } while (0)
; #define PG8_LDB(dst, b, h) do { _Pragma("unroll") for (int n = 0; n < 2; ++n) _Pragma("unroll") for (int k = 0; k < 2; ++k) dst[n][k] = *(const PG8_LAS bf16x8*)(lds + PG8_SB(b, h) + boff + n * 2048 + k * 1024); } while (0)
; #define PG8_MMA(ai, bj, At, Bt) do { __builtin_amdgcn_s_setprio(1); _Pragma("unroll") for (int m = 0; m < 4; ++m) _Pragma("unroll") for (int n = 0; n < 2; ++n) _Pragma("unroll") for (int k = 0; k < 2; ++k) \
;         acc[ai][bj][m][n] = __builtin_amdgcn_mfma_f32_16x16x32_bf16(Bt[n][k], At[m][k], acc[ai][bj][m][n], 0, 0, 0); __builtin_amdgcn_s_setprio(0); } while (0)
; #define PG8_WAIT_V(n) asm volatile("s_waitcnt vmcnt(" #n ")" ::: "memory")
; #define PG8_WAIT_L(n) asm volatile("s_waitcnt lgkmcnt(" #n ")" ::: "memory")
; #define PG8_BAR __builtin_amdgcn_s_barrier()
; #define PG8_SCHED __builtin_amdgcn_sched_barrier(0)
; template <class Epi, class Sched, bool ALIGN_EPI = false, bool SP2 = false>
; __device__ __forceinline__ void gemm_phase(PG8_LAS unsigned char* lds, const Gemm g, const Sched& S, const Epi& E) {
;     ...
;             PG8_WAIT_V(8); PG8_WAIT_L(0); PG8_BAR; PG8_MMA(1, 0, At, B0); PG8_MMA(1, 1, At, B1); PG8_BAR; PG8_SCHED;
;             PG8_LDB(B0, 1, 0); PG8_LDB(B1, 1, 1); PG8_SCHED; PG8_LDA(At, 1, 0); PG8_STAGE(PG8_SA(0, 1), a2 + hstep, voffA);
;             PG8_WAIT_V(8); PG8_WAIT_L(0); PG8_BAR; PG8_MMA(0, 0, At, B0); PG8_MMA(0, 1, At, B1); PG8_BAR; PG8_SCHED;
	s_setprio 1
	s_waitcnt lgkmcnt(0)
	v_mfma_f32_16x16x32_bf16 v[60:63], v[144:147], v[186:189], 0
	v_mfma_f32_16x16x32_bf16 v[56:59], v[160:163], v[186:189], 0
	v_mfma_f32_16x16x32_bf16 v[52:55], v[168:171], v[186:189], 0
	v_mfma_f32_16x16x32_bf16 v[48:51], v[176:179], v[186:189], 0
	v_mfma_f32_16x16x32_bf16 v[44:47], v[144:147], v[194:197], 0
	v_mfma_f32_16x16x32_bf16 v[40:43], v[160:163], v[194:197], 0
	v_mfma_f32_16x16x32_bf16 v[36:39], v[168:171], v[194:197], 0
	v_mfma_f32_16x16x32_bf16 v[32:35], v[176:179], v[194:197], 0
	v_mfma_f32_16x16x32_bf16 v[28:31], v[144:147], v[208:211], 0
	v_mfma_f32_16x16x32_bf16 v[24:27], v[160:163], v[208:211], 0
	v_mfma_f32_16x16x32_bf16 v[20:23], v[168:171], v[208:211], 0
	v_mfma_f32_16x16x32_bf16 v[16:19], v[176:179], v[208:211], 0
	v_mfma_f32_16x16x32_bf16 v[12:15], v[144:147], v[216:219], 0
	v_mfma_f32_16x16x32_bf16 v[8:11], v[160:163], v[216:219], 0
	v_lshl_add_u64 v[228:229], s[56:57], 0, v[128:129]
	s_mov_b32 m0, s34
	s_nop 0
	global_load_lds_dwordx4 v[228:229], off
	v_mfma_f32_16x16x32_bf16 v[4:7], v[168:171], v[216:219], 0
	v_mfma_f32_16x16x32_bf16 v[0:3], v[176:179], v[216:219], 0
	s_setprio 0
	s_setprio 1
	v_mfma_f32_16x16x32_bf16 v[60:63], v[156:159], v[190:193], v[60:63]
	v_mfma_f32_16x16x32_bf16 v[56:59], v[164:167], v[190:193], v[56:59]
	v_mfma_f32_16x16x32_bf16 v[52:55], v[172:175], v[190:193], v[52:55]
	v_mfma_f32_16x16x32_bf16 v[48:51], v[182:185], v[190:193], v[48:51]
	v_mfma_f32_16x16x32_bf16 v[44:47], v[156:159], v[198:201], v[44:47]
	v_mfma_f32_16x16x32_bf16 v[40:43], v[164:167], v[198:201], v[40:43]
	v_mfma_f32_16x16x32_bf16 v[36:39], v[172:175], v[198:201], v[36:39]
	v_mfma_f32_16x16x32_bf16 v[32:35], v[182:185], v[198:201], v[32:35]
	v_mfma_f32_16x16x32_bf16 v[28:31], v[156:159], v[212:215], v[28:31]
	v_mfma_f32_16x16x32_bf16 v[24:27], v[164:167], v[212:215], v[24:27]
	v_mfma_f32_16x16x32_bf16 v[20:23], v[172:175], v[212:215], v[20:23]
	v_mfma_f32_16x16x32_bf16 v[16:19], v[182:185], v[212:215], v[16:19]
	v_mfma_f32_16x16x32_bf16 v[12:15], v[156:159], v[220:223], v[12:15]
	v_mfma_f32_16x16x32_bf16 v[8:11], v[164:167], v[220:223], v[8:11]
	v_lshl_add_u64 v[230:231], s[56:57], 0, v[132:133]
	s_mov_b32 m0, s58
	s_nop 0
	global_load_lds_dwordx4 v[230:231], off
	v_mfma_f32_16x16x32_bf16 v[4:7], v[172:175], v[220:223], v[4:7]
	v_mfma_f32_16x16x32_bf16 v[0:3], v[182:185], v[220:223], v[0:3]
	s_setprio 0
	s_barrier
	s_add_i32 s78, 0, 0x18000
	v_add_u32_e32 v155, s78, v149
	s_add_i32 s79, 0, 0x1c000
	ds_read_b128 v[144:147], v155
	ds_read_b128 v[156:159], v155 offset:1024
	ds_read_b128 v[160:163], v155 offset:2048
	ds_read_b128 v[164:167], v155 offset:3072
	v_add_u32_e32 v155, s79, v149
	ds_read_b128 v[168:171], v155
	ds_read_b128 v[172:175], v155 offset:1024
	ds_read_b128 v[176:179], v155 offset:2048
	ds_read_b128 v[182:185], v155 offset:3072
	s_add_u32 s50, s56, 0xb0000
	s_addc_u32 s51, s57, 0
	s_mov_b32 m0, s59
	v_lshl_add_u64 v[232:233], s[50:51], 0, v[128:129]
	ds_read_b128 v[186:189], v153 offset:32768
	ds_read_b128 v[190:193], v153 offset:33792
	ds_read_b128 v[194:197], v153 offset:34816
	ds_read_b128 v[198:201], v153 offset:35840
	ds_read_b128 v[208:211], v153 offset:36864
	ds_read_b128 v[212:215], v153 offset:37888
	ds_read_b128 v[216:219], v153 offset:38912
	ds_read_b128 v[220:223], v153 offset:39936
	global_load_lds_dwordx4 v[232:233], off
	v_lshl_add_u64 v[232:233], s[50:51], 0, v[132:133]
	s_mov_b32 m0, s60
	s_nop 0
	global_load_lds_dwordx4 v[232:233], off
	s_waitcnt vmcnt(8)
	s_waitcnt lgkmcnt(0)
	s_barrier
	s_setprio 1
	s_waitcnt lgkmcnt(0)
	v_mfma_f32_16x16x32_bf16 v[124:127], v[144:147], v[186:189], v[124:127]
	v_mfma_f32_16x16x32_bf16 v[120:123], v[160:163], v[186:189], v[120:123]
	v_mfma_f32_16x16x32_bf16 v[116:119], v[168:171], v[186:189], v[116:119]
	v_mfma_f32_16x16x32_bf16 v[112:115], v[176:179], v[186:189], v[112:115]
	v_mfma_f32_16x16x32_bf16 v[108:111], v[144:147], v[194:197], v[108:111]
	v_mfma_f32_16x16x32_bf16 v[104:107], v[160:163], v[194:197], v[104:107]
	v_mfma_f32_16x16x32_bf16 v[100:103], v[168:171], v[194:197], v[100:103]
	v_mfma_f32_16x16x32_bf16 v[96:99], v[176:179], v[194:197], v[96:99]
	v_mfma_f32_16x16x32_bf16 v[92:95], v[144:147], v[208:211], v[92:95]
	v_mfma_f32_16x16x32_bf16 v[88:91], v[160:163], v[208:211], v[88:91]
	v_mfma_f32_16x16x32_bf16 v[84:87], v[168:171], v[208:211], v[84:87]
	v_mfma_f32_16x16x32_bf16 v[80:83], v[176:179], v[208:211], v[80:83]
	v_mfma_f32_16x16x32_bf16 v[76:79], v[144:147], v[216:219], v[76:79]
	v_mfma_f32_16x16x32_bf16 v[72:75], v[160:163], v[216:219], v[72:75]
	v_mfma_f32_16x16x32_bf16 v[68:71], v[168:171], v[216:219], v[68:71]
	v_mfma_f32_16x16x32_bf16 v[64:67], v[176:179], v[216:219], v[64:67]
	s_setprio 0
	s_setprio 1
	v_mfma_f32_16x16x32_bf16 v[124:127], v[156:159], v[190:193], v[124:127]
	v_mfma_f32_16x16x32_bf16 v[120:123], v[164:167], v[190:193], v[120:123]
	v_mfma_f32_16x16x32_bf16 v[116:119], v[172:175], v[190:193], v[116:119]
	v_mfma_f32_16x16x32_bf16 v[112:115], v[182:185], v[190:193], v[112:115]
	v_mfma_f32_16x16x32_bf16 v[108:111], v[156:159], v[198:201], v[108:111]
	v_mfma_f32_16x16x32_bf16 v[104:107], v[164:167], v[198:201], v[104:107]
	v_mfma_f32_16x16x32_bf16 v[100:103], v[172:175], v[198:201], v[100:103]
	v_mfma_f32_16x16x32_bf16 v[96:99], v[182:185], v[198:201], v[96:99]
	v_mfma_f32_16x16x32_bf16 v[92:95], v[156:159], v[212:215], v[92:95]
	v_mfma_f32_16x16x32_bf16 v[88:91], v[164:167], v[212:215], v[88:91]
	v_mfma_f32_16x16x32_bf16 v[84:87], v[172:175], v[212:215], v[84:87]
	v_mfma_f32_16x16x32_bf16 v[80:83], v[182:185], v[212:215], v[80:83]
	v_mfma_f32_16x16x32_bf16 v[76:79], v[156:159], v[220:223], v[76:79]
	v_mfma_f32_16x16x32_bf16 v[72:75], v[164:167], v[220:223], v[72:75]
	v_mfma_f32_16x16x32_bf16 v[68:71], v[172:175], v[220:223], v[68:71]
	v_mfma_f32_16x16x32_bf16 v[64:67], v[182:185], v[220:223], v[64:67]
	s_setprio 0
	s_barrier
; #define PG8_STAGE(bufoff, gbase, voff) do { _Pragma("unroll") for (int _i = 0; _i < 2; ++_i) \
;         __builtin_amdgcn_global_load_lds((const unsigned*)((const char*)(gbase) + (voff)[_i]), (PG8_LAS unsigned*)(lds + (bufoff) + ldsw + _i * 8192), 16, 0, 0); } while (0)
; #define PG8_LDA(dst, b, h) do { _Pragma("unroll") for (int m = 0; m < 4; ++m) _Pragma("unroll") for (int k = 0; k < 2; ++k) dst[m][k] = *(const PG8_LAS bf16x8*)(lds + PG8_SA(b, h) + aoff + m * 2048 + k * 1024); } while (0)
; #define PG8_LDB(dst, b, h) do { _Pragma("unroll") for (int n = 0; n < 2; ++n) _Pragma("unroll") for (int k = 0; k < 2; ++k) dst[n][k] = *(const PG8_LAS bf16x8*)(lds + PG8_SB(b, h) + boff + n * 2048 + k * 1024); } while (0)
; #define PG8_BAR __builtin_amdgcn_s_barrier()
; template <class Epi, class Sched, bool ALIGN_EPI = false, bool SP2 = false>
; __device__ __forceinline__ void gemm_phase(PG8_LAS unsigned char* lds, const Gemm g, const Sched& S, const Epi& E) {
;     ...
;             const bool last = (t == nt - 2);
;             const char* a1 = cA + (size_t)(t + 1) * kstep;
;             const char* a2 = last ? nA : cA + (size_t)(t + 2) * kstep; const char* b2 = last ? nB : cB + (size_t)(t + 2) * kstep;
;             const char* a3 = a2 + kstep; const char* b3 = b2 + kstep;
;             if (last && has_next) S.a_ready(nxt);
;             if constexpr (SP2) {
;             PG8_LDB(B0, 0, 0); PG8_LDB(B1, 0, 1); PG8_SCHED; PG8_LDA(At, 0, 0); PG8_STAGE(PG8_SA(1, 1), a1 + hstep, voffA);
;             PG8_WAIT_V(8); PG8_WAIT_L(0); PG8_BAR; PG8_MMA(0, 0, At, B0); PG8_MMA(0, 1, At, B1); PG8_BAR; PG8_SCHED;
;             PG8_LDA(At, 0, 1); PG8_STAGE(PG8_SB(0, 0), b2, voffB); PG8_STAGE(PG8_SB(0, 1), b2 + hstep, voffB); PG8_STAGE(PG8_SA(0, 0), a2, voffA);
;             PG8_WAIT_V(8); PG8_WAIT_L(0); PG8_BAR; PG8_MMA(1, 0, At, B0); PG8_MMA(1, 1, At, B1); PG8_BAR; PG8_SCHED;
;             PG8_LDB(B0, 1, 0); PG8_LDB(B1, 1, 1); PG8_SCHED; PG8_LDA(At, 1, 0); PG8_STAGE(PG8_SA(0, 1), a2 + hstep, voffA);
;             PG8_WAIT_V(8); PG8_WAIT_L(0); PG8_BAR; PG8_MMA(0, 0, At, B0); PG8_MMA(0, 1, At, B1); PG8_BAR; PG8_SCHED;
;             PG8_LDA(At, 1, 1); PG8_STAGE(PG8_SB(1, 0), b3, voffB); PG8_STAGE(PG8_SB(1, 1), b3 + hstep, voffB); PG8_STAGE(PG8_SA(1, 0), a3, voffA);
;             PG8_WAIT_V(8); PG8_WAIT_L(0); PG8_BAR; PG8_MMA(1, 0, At, B0); PG8_MMA(1, 1, At, B1); PG8_BAR; PG8_SCHED;
	s_add_i32 s50, s78, s33
	v_lshl_add_u64 v[224:225], v[224:225], 0, s[42:43]
	s_mov_b32 m0, s50
	ds_read_b128 v[186:189], v153 offset:49152
	ds_read_b128 v[190:193], v153 offset:50176
	ds_read_b128 v[194:197], v153 offset:51200
	ds_read_b128 v[198:201], v153 offset:52224
	ds_read_b128 v[208:211], v153 offset:53248
	ds_read_b128 v[212:215], v153 offset:54272
	ds_read_b128 v[216:219], v153 offset:55296
	ds_read_b128 v[220:223], v153 offset:56320
	global_load_lds_dwordx4 v[224:225], off
	s_add_i32 m0, s50, 0x2000
	s_add_u32 s50, s54, 0xb0080
	v_lshl_add_u64 v[224:225], v[226:227], 0, s[42:43]
	s_addc_u32 s51, s55, 0
	s_add_i32 s54, s79, s33
	global_load_lds_dwordx4 v[224:225], off
	v_lshl_add_u64 v[224:225], s[50:51], 0, v[130:131]
	s_mov_b32 m0, s54
	s_nop 0
	global_load_lds_dwordx4 v[224:225], off
	v_lshl_add_u64 v[224:225], s[50:51], 0, v[134:135]
	s_add_i32 m0, s54, 0x2000
	s_nop 0
	global_load_lds_dwordx4 v[224:225], off
	s_waitcnt vmcnt(6)
	s_waitcnt lgkmcnt(0)
	s_barrier
	s_setprio 1
	s_waitcnt lgkmcnt(0)
	v_mfma_f32_16x16x32_bf16 v[60:63], v[144:147], v[186:189], v[60:63]
	v_mfma_f32_16x16x32_bf16 v[56:59], v[160:163], v[186:189], v[56:59]
	v_mfma_f32_16x16x32_bf16 v[52:55], v[168:171], v[186:189], v[52:55]
	v_mfma_f32_16x16x32_bf16 v[48:51], v[176:179], v[186:189], v[48:51]
	v_mfma_f32_16x16x32_bf16 v[44:47], v[144:147], v[194:197], v[44:47]
	v_mfma_f32_16x16x32_bf16 v[40:43], v[160:163], v[194:197], v[40:43]
	v_mfma_f32_16x16x32_bf16 v[36:39], v[168:171], v[194:197], v[36:39]
	v_mfma_f32_16x16x32_bf16 v[32:35], v[176:179], v[194:197], v[32:35]
	v_mfma_f32_16x16x32_bf16 v[28:31], v[144:147], v[208:211], v[28:31]
	v_mfma_f32_16x16x32_bf16 v[24:27], v[160:163], v[208:211], v[24:27]
	v_mfma_f32_16x16x32_bf16 v[20:23], v[168:171], v[208:211], v[20:23]
	v_mfma_f32_16x16x32_bf16 v[16:19], v[176:179], v[208:211], v[16:19]
	v_mfma_f32_16x16x32_bf16 v[12:15], v[144:147], v[216:219], v[12:15]
	v_mfma_f32_16x16x32_bf16 v[8:11], v[160:163], v[216:219], v[8:11]
	v_lshl_add_u64 v[224:225], v[228:229], 0, s[42:43]
	s_mov_b32 m0, s62
	s_nop 0
	global_load_lds_dwordx4 v[224:225], off
	v_mfma_f32_16x16x32_bf16 v[4:7], v[168:171], v[216:219], v[4:7]
	v_mfma_f32_16x16x32_bf16 v[0:3], v[176:179], v[216:219], v[0:3]
	s_setprio 0
	s_setprio 1
	v_mfma_f32_16x16x32_bf16 v[60:63], v[156:159], v[190:193], v[60:63]
	v_mfma_f32_16x16x32_bf16 v[56:59], v[164:167], v[190:193], v[56:59]
	v_mfma_f32_16x16x32_bf16 v[52:55], v[172:175], v[190:193], v[52:55]
	v_mfma_f32_16x16x32_bf16 v[48:51], v[182:185], v[190:193], v[48:51]
	v_mfma_f32_16x16x32_bf16 v[44:47], v[156:159], v[198:201], v[44:47]
	v_mfma_f32_16x16x32_bf16 v[40:43], v[164:167], v[198:201], v[40:43]
	v_mfma_f32_16x16x32_bf16 v[36:39], v[172:175], v[198:201], v[36:39]
	v_mfma_f32_16x16x32_bf16 v[32:35], v[182:185], v[198:201], v[32:35]
	v_mfma_f32_16x16x32_bf16 v[28:31], v[156:159], v[212:215], v[28:31]
	v_mfma_f32_16x16x32_bf16 v[24:27], v[164:167], v[212:215], v[24:27]
	v_mfma_f32_16x16x32_bf16 v[20:23], v[172:175], v[212:215], v[20:23]
	v_mfma_f32_16x16x32_bf16 v[16:19], v[182:185], v[212:215], v[16:19]
	v_mfma_f32_16x16x32_bf16 v[12:15], v[156:159], v[220:223], v[12:15]
	v_mfma_f32_16x16x32_bf16 v[8:11], v[164:167], v[220:223], v[8:11]
	v_lshl_add_u64 v[224:225], v[230:231], 0, s[42:43]
	s_mov_b32 m0, s63
	s_nop 0
	global_load_lds_dwordx4 v[224:225], off
	v_mfma_f32_16x16x32_bf16 v[4:7], v[172:175], v[220:223], v[4:7]
	v_mfma_f32_16x16x32_bf16 v[0:3], v[182:185], v[220:223], v[0:3]
	s_setprio 0
	s_barrier
	s_add_i32 s84, s84, 2
	s_add_u32 s82, s82, 0x100
	s_addc_u32 s83, s83, 0
	s_mov_b64 s[50:51], s[52:53]
.LBB0_1197:
	ds_read_b128 v[144:147], v151
	ds_read_b128 v[156:159], v151 offset:1024
	ds_read_b128 v[160:163], v151 offset:2048
	ds_read_b128 v[164:167], v151 offset:3072
	ds_read_b128 v[168:171], v152
	ds_read_b128 v[172:175], v152 offset:1024
	ds_read_b128 v[176:179], v152 offset:2048
	ds_read_b128 v[182:185], v152 offset:3072
	s_add_u32 s52, s50, 0x100
	s_addc_u32 s53, s51, 0
	s_cmp_eq_u32 s84, 40
	s_cselect_b32 s57, s1, s53
	s_cselect_b32 s56, s0, s52
	s_cselect_b32 s55, s49, s83
	s_cselect_b32 s54, s48, s82
	v_lshl_add_u64 v[224:225], s[50:51], 0, v[136:137]
	s_add_i32 m0, s34, 0xc000
	ds_read_b128 v[186:189], v153
	ds_read_b128 v[190:193], v153 offset:1024
	ds_read_b128 v[194:197], v153 offset:2048
	ds_read_b128 v[198:201], v153 offset:3072
	ds_read_b128 v[208:211], v153 offset:4096
	ds_read_b128 v[212:215], v153 offset:5120
	ds_read_b128 v[216:219], v153 offset:6144
	ds_read_b128 v[220:223], v153 offset:7168
	global_load_lds_dwordx4 v[224:225], off
	v_lshl_add_u64 v[224:225], s[50:51], 0, v[138:139]
	s_add_i32 m0, s34, 0xe000
	s_nop 0
	global_load_lds_dwordx4 v[224:225], off
	s_waitcnt vmcnt(8)
	s_waitcnt lgkmcnt(0)
	s_barrier
; #define PG8_STAGE(bufoff, gbase, voff) do { _Pragma("unroll") for (int _i = 0; _i < 2; ++_i) \
;         __builtin_amdgcn_global_load_lds((const unsigned*)((const char*)(gbase) + (voff)[_i]), (PG8_LAS unsigned*)(lds + (bufoff) + ldsw + _i * 8192), 16, 0, 0); } while (0)
; #define PG8_LDA(dst, b, h) do { _Pragma("unroll") for (int m = 0; m < 4; ++m) _Pragma("unroll") for (int k = 0; k < 2; ++k) dst[m][k] = *(const PG8_LAS bf16x8*)(lds + PG8_SA(b, h) + aoff + m * 2048 + k * 1024); } while (0)
; #define PG8_MMA(ai, bj, At, Bt) do { __builtin_amdgcn_s_setprio(1); _Pragma("unroll") for (int m = 0; m < 4; ++m) _Pragma("unroll") for (int n = 0; n < 2; ++n) _Pragma("unroll") for (int k = 0; k < 2; ++k) \
;         acc[ai][bj][m][n] = __builtin_amdgcn_mfma_f32_16x16x32_bf16(Bt[n][k], At[m][k], acc[ai][bj][m][n], 0, 0, 0); __builtin_amdgcn_s_setprio(0); } while (0)
; #define PG8_WAIT_V(n) asm volatile("s_waitcnt vmcnt(" #n ")" ::: "memory")
; #define PG8_WAIT_L(n) asm volatile("s_waitcnt lgkmcnt(" #n ")" ::: "memory")
; #define PG8_BAR __builtin_amdgcn_s_barrier()
; #define PG8_SCHED __builtin_amdgcn_sched_barrier(0)
; template <class Epi, class Sched, bool ALIGN_EPI = false, bool SP2 = false>
; __device__ __forceinline__ void gemm_phase(PG8_LAS unsigned char* lds, const Gemm g, const Sched& S, const Epi& E) {
;     ...
;             PG8_WAIT_V(8); PG8_WAIT_L(0); PG8_BAR; PG8_MMA(0, 0, At, B0); PG8_MMA(0, 1, At, B1); PG8_BAR; PG8_SCHED;
;             PG8_LDA(At, 0, 1); PG8_STAGE(PG8_SB(0, 0), b2, voffB); PG8_STAGE(PG8_SB(0, 1), b2 + hstep, voffB); PG8_STAGE(PG8_SA(0, 0), a2, voffA);
;             PG8_WAIT_V(8); PG8_WAIT_L(0); PG8_BAR; PG8_MMA(1, 0, At, B0); PG8_MMA(1, 1, At, B1); PG8_BAR; PG8_SCHED;
	s_setprio 1
	s_waitcnt lgkmcnt(0)
	v_mfma_f32_16x16x32_bf16 v[124:127], v[144:147], v[186:189], v[124:127]
	v_mfma_f32_16x16x32_bf16 v[120:123], v[160:163], v[186:189], v[120:123]
	v_mfma_f32_16x16x32_bf16 v[116:119], v[168:171], v[186:189], v[116:119]
	v_mfma_f32_16x16x32_bf16 v[112:115], v[176:179], v[186:189], v[112:115]
	v_mfma_f32_16x16x32_bf16 v[108:111], v[144:147], v[194:197], v[108:111]
	v_mfma_f32_16x16x32_bf16 v[104:107], v[160:163], v[194:197], v[104:107]
	v_mfma_f32_16x16x32_bf16 v[100:103], v[168:171], v[194:197], v[100:103]
	v_mfma_f32_16x16x32_bf16 v[96:99], v[176:179], v[194:197], v[96:99]
	v_mfma_f32_16x16x32_bf16 v[92:95], v[144:147], v[208:211], v[92:95]
	v_mfma_f32_16x16x32_bf16 v[88:91], v[160:163], v[208:211], v[88:91]
	v_mfma_f32_16x16x32_bf16 v[84:87], v[168:171], v[208:211], v[84:87]
	v_mfma_f32_16x16x32_bf16 v[80:83], v[176:179], v[208:211], v[80:83]
	v_mfma_f32_16x16x32_bf16 v[76:79], v[144:147], v[216:219], v[76:79]
	v_mfma_f32_16x16x32_bf16 v[72:75], v[160:163], v[216:219], v[72:75]
	v_mfma_f32_16x16x32_bf16 v[68:71], v[168:171], v[216:219], v[68:71]
	v_mfma_f32_16x16x32_bf16 v[64:67], v[176:179], v[216:219], v[64:67]
	s_setprio 0
	s_setprio 1
	v_mfma_f32_16x16x32_bf16 v[124:127], v[156:159], v[190:193], v[124:127]
	v_mfma_f32_16x16x32_bf16 v[120:123], v[164:167], v[190:193], v[120:123]
	v_mfma_f32_16x16x32_bf16 v[116:119], v[172:175], v[190:193], v[116:119]
	v_mfma_f32_16x16x32_bf16 v[112:115], v[182:185], v[190:193], v[112:115]
	v_mfma_f32_16x16x32_bf16 v[108:111], v[156:159], v[198:201], v[108:111]
	v_mfma_f32_16x16x32_bf16 v[104:107], v[164:167], v[198:201], v[104:107]
	v_mfma_f32_16x16x32_bf16 v[100:103], v[172:175], v[198:201], v[100:103]
	v_mfma_f32_16x16x32_bf16 v[96:99], v[182:185], v[198:201], v[96:99]
	v_mfma_f32_16x16x32_bf16 v[92:95], v[156:159], v[212:215], v[92:95]
	v_mfma_f32_16x16x32_bf16 v[88:91], v[164:167], v[212:215], v[88:91]
	v_mfma_f32_16x16x32_bf16 v[84:87], v[172:175], v[212:215], v[84:87]
	v_mfma_f32_16x16x32_bf16 v[80:83], v[182:185], v[212:215], v[80:83]
	v_mfma_f32_16x16x32_bf16 v[76:79], v[156:159], v[220:223], v[76:79]
	v_mfma_f32_16x16x32_bf16 v[72:75], v[164:167], v[220:223], v[72:75]
	v_mfma_f32_16x16x32_bf16 v[68:71], v[172:175], v[220:223], v[68:71]
	v_mfma_f32_16x16x32_bf16 v[64:67], v[182:185], v[220:223], v[64:67]
	s_setprio 0
	s_barrier
	s_add_i32 s50, s64, s33
	v_lshl_add_u64 v[224:225], s[54:55], 0, v[130:131]
	s_mov_b32 m0, s50
	ds_read_b128 v[186:189], v153 offset:16384
	ds_read_b128 v[190:193], v153 offset:17408
	ds_read_b128 v[194:197], v153 offset:18432
	ds_read_b128 v[198:201], v153 offset:19456
	ds_read_b128 v[208:211], v153 offset:20480
	ds_read_b128 v[212:215], v153 offset:21504
	ds_read_b128 v[216:219], v153 offset:22528
	ds_read_b128 v[220:223], v153 offset:23552
	global_load_lds_dwordx4 v[224:225], off
	s_add_i32 m0, s50, 0x2000
	s_add_u32 s50, s54, 0xb0000
	v_lshl_add_u64 v[226:227], s[54:55], 0, v[134:135]
	s_addc_u32 s51, s55, 0
	s_add_i32 s78, s65, s33
	global_load_lds_dwordx4 v[226:227], off
	v_lshl_add_u64 v[228:229], s[50:51], 0, v[130:131]
	s_mov_b32 m0, s78
	global_load_lds_dwordx4 v[228:229], off
	v_lshl_add_u64 v[228:229], s[50:51], 0, v[134:135]
	s_add_i32 m0, s78, 0x2000
	s_nop 0
	global_load_lds_dwordx4 v[228:229], off
	s_waitcnt vmcnt(6)
	s_waitcnt lgkmcnt(0)
	s_barrier
	s_setprio 1
	s_waitcnt lgkmcnt(0)
	v_mfma_f32_16x16x32_bf16 v[60:63], v[144:147], v[186:189], v[60:63]
	v_mfma_f32_16x16x32_bf16 v[56:59], v[160:163], v[186:189], v[56:59]
	v_mfma_f32_16x16x32_bf16 v[52:55], v[168:171], v[186:189], v[52:55]
	v_mfma_f32_16x16x32_bf16 v[48:51], v[176:179], v[186:189], v[48:51]
	v_mfma_f32_16x16x32_bf16 v[44:47], v[144:147], v[194:197], v[44:47]
	v_mfma_f32_16x16x32_bf16 v[40:43], v[160:163], v[194:197], v[40:43]
	v_mfma_f32_16x16x32_bf16 v[36:39], v[168:171], v[194:197], v[36:39]
	v_mfma_f32_16x16x32_bf16 v[32:35], v[176:179], v[194:197], v[32:35]
	v_mfma_f32_16x16x32_bf16 v[28:31], v[144:147], v[208:211], v[28:31]
	v_mfma_f32_16x16x32_bf16 v[24:27], v[160:163], v[208:211], v[24:27]
	v_mfma_f32_16x16x32_bf16 v[20:23], v[168:171], v[208:211], v[20:23]
	v_mfma_f32_16x16x32_bf16 v[16:19], v[176:179], v[208:211], v[16:19]
	v_mfma_f32_16x16x32_bf16 v[12:15], v[144:147], v[216:219], v[12:15]
	v_mfma_f32_16x16x32_bf16 v[8:11], v[160:163], v[216:219], v[8:11]
	v_lshl_add_u64 v[228:229], s[56:57], 0, v[128:129]
	s_mov_b32 m0, s34
	s_nop 0
	global_load_lds_dwordx4 v[228:229], off
	v_mfma_f32_16x16x32_bf16 v[4:7], v[168:171], v[216:219], v[4:7]
	v_mfma_f32_16x16x32_bf16 v[0:3], v[176:179], v[216:219], v[0:3]
	s_setprio 0
	s_setprio 1
	v_mfma_f32_16x16x32_bf16 v[60:63], v[156:159], v[190:193], v[60:63]
	v_mfma_f32_16x16x32_bf16 v[56:59], v[164:167], v[190:193], v[56:59]
	v_mfma_f32_16x16x32_bf16 v[52:55], v[172:175], v[190:193], v[52:55]
	v_mfma_f32_16x16x32_bf16 v[48:51], v[182:185], v[190:193], v[48:51]
	v_mfma_f32_16x16x32_bf16 v[44:47], v[156:159], v[198:201], v[44:47]
	v_mfma_f32_16x16x32_bf16 v[40:43], v[164:167], v[198:201], v[40:43]
	v_mfma_f32_16x16x32_bf16 v[36:39], v[172:175], v[198:201], v[36:39]
	v_mfma_f32_16x16x32_bf16 v[32:35], v[182:185], v[198:201], v[32:35]
	v_mfma_f32_16x16x32_bf16 v[28:31], v[156:159], v[212:215], v[28:31]
	v_mfma_f32_16x16x32_bf16 v[24:27], v[164:167], v[212:215], v[24:27]
	v_mfma_f32_16x16x32_bf16 v[20:23], v[172:175], v[212:215], v[20:23]
	v_mfma_f32_16x16x32_bf16 v[16:19], v[182:185], v[212:215], v[16:19]
	v_mfma_f32_16x16x32_bf16 v[12:15], v[156:159], v[220:223], v[12:15]
	v_mfma_f32_16x16x32_bf16 v[8:11], v[164:167], v[220:223], v[8:11]
	v_lshl_add_u64 v[230:231], s[56:57], 0, v[132:133]
	s_mov_b32 m0, s58
	s_nop 0
	global_load_lds_dwordx4 v[230:231], off
	v_mfma_f32_16x16x32_bf16 v[4:7], v[172:175], v[220:223], v[4:7]
	v_mfma_f32_16x16x32_bf16 v[0:3], v[182:185], v[220:223], v[0:3]
	s_setprio 0
	s_barrier
; #define PG8_STAGE(bufoff, gbase, voff) do { _Pragma("unroll") for (int _i = 0; _i < 2; ++_i) \
;         __builtin_amdgcn_global_load_lds((const unsigned*)((const char*)(gbase) + (voff)[_i]), (PG8_LAS unsigned*)(lds + (bufoff) + ldsw + _i * 8192), 16, 0, 0); } while (0)
; #define PG8_LDA(dst, b, h) do { _Pragma("unroll") for (int m = 0; m < 4; ++m) _Pragma("unroll") for (int k = 0; k < 2; ++k) dst[m][k] = *(const PG8_LAS bf16x8*)(lds + PG8_SA(b, h) + aoff + m * 2048 + k * 1024); } while (0)
; #define PG8_LDB(dst, b, h) do { _Pragma("unroll") for (int n = 0; n < 2; ++n) _Pragma("unroll") for (int k = 0; k < 2; ++k) dst[n][k] = *(const PG8_LAS bf16x8*)(lds + PG8_SB(b, h) + boff + n * 2048 + k * 1024); } while (0)
; #define PG8_MMA(ai, bj, At, Bt) do { __builtin_amdgcn_s_setprio(1); _Pragma("unroll") for (int m = 0; m < 4; ++m) _Pragma("unroll") for (int n = 0; n < 2; ++n) _Pragma("unroll") for (int k = 0; k < 2; ++k) \
;         acc[ai][bj][m][n] = __builtin_amdgcn_mfma_f32_16x16x32_bf16(Bt[n][k], At[m][k], acc[ai][bj][m][n], 0, 0, 0); __builtin_amdgcn_s_setprio(0); } while (0)
; #define PG8_WAIT_V(n) asm volatile("s_waitcnt vmcnt(" #n ")" ::: "memory")
; #define PG8_WAIT_L(n) asm volatile("s_waitcnt lgkmcnt(" #n ")" ::: "memory")
; #define PG8_BAR __builtin_amdgcn_s_barrier()
; #define PG8_SCHED __builtin_amdgcn_sched_barrier(0)
; template <class Epi, class Sched, bool ALIGN_EPI = false, bool SP2 = false>
; __device__ __forceinline__ void gemm_phase(PG8_LAS unsigned char* lds, const Gemm g, const Sched& S, const Epi& E) {
;     ...
;             PG8_LDB(B0, 1, 0); PG8_LDB(B1, 1, 1); PG8_SCHED; PG8_LDA(At, 1, 0); PG8_STAGE(PG8_SA(0, 1), a2 + hstep, voffA);
;             PG8_WAIT_V(8); PG8_WAIT_L(0); PG8_BAR; PG8_MMA(0, 0, At, B0); PG8_MMA(0, 1, At, B1); PG8_BAR; PG8_SCHED;
	s_add_i32 s78, 0, 0x18000
	v_add_u32_e32 v155, s78, v149
	s_add_i32 s79, 0, 0x1c000
	ds_read_b128 v[144:147], v155
	ds_read_b128 v[156:159], v155 offset:1024
	ds_read_b128 v[160:163], v155 offset:2048
	ds_read_b128 v[164:167], v155 offset:3072
	v_add_u32_e32 v155, s79, v149
	ds_read_b128 v[168:171], v155
	ds_read_b128 v[172:175], v155 offset:1024
	ds_read_b128 v[176:179], v155 offset:2048
	ds_read_b128 v[182:185], v155 offset:3072
	s_add_u32 s50, s56, 0xb0000
	s_addc_u32 s51, s57, 0
	s_mov_b32 m0, s59
	v_lshl_add_u64 v[232:233], s[50:51], 0, v[128:129]
	ds_read_b128 v[186:189], v153 offset:32768
	ds_read_b128 v[190:193], v153 offset:33792
	ds_read_b128 v[194:197], v153 offset:34816
	ds_read_b128 v[198:201], v153 offset:35840
	ds_read_b128 v[208:211], v153 offset:36864
	ds_read_b128 v[212:215], v153 offset:37888
	ds_read_b128 v[216:219], v153 offset:38912
	ds_read_b128 v[220:223], v153 offset:39936
	global_load_lds_dwordx4 v[232:233], off
	v_lshl_add_u64 v[232:233], s[50:51], 0, v[132:133]
	s_mov_b32 m0, s60
	s_nop 0
	global_load_lds_dwordx4 v[232:233], off
	s_waitcnt vmcnt(8)
	s_waitcnt lgkmcnt(0)
	s_barrier
	s_setprio 1
	s_waitcnt lgkmcnt(0)
	v_mfma_f32_16x16x32_bf16 v[124:127], v[144:147], v[186:189], v[124:127]
	v_mfma_f32_16x16x32_bf16 v[120:123], v[160:163], v[186:189], v[120:123]
	v_mfma_f32_16x16x32_bf16 v[116:119], v[168:171], v[186:189], v[116:119]
	v_mfma_f32_16x16x32_bf16 v[112:115], v[176:179], v[186:189], v[112:115]
	v_mfma_f32_16x16x32_bf16 v[108:111], v[144:147], v[194:197], v[108:111]
	v_mfma_f32_16x16x32_bf16 v[104:107], v[160:163], v[194:197], v[104:107]
	v_mfma_f32_16x16x32_bf16 v[100:103], v[168:171], v[194:197], v[100:103]
	v_mfma_f32_16x16x32_bf16 v[96:99], v[176:179], v[194:197], v[96:99]
	v_mfma_f32_16x16x32_bf16 v[92:95], v[144:147], v[208:211], v[92:95]
	v_mfma_f32_16x16x32_bf16 v[88:91], v[160:163], v[208:211], v[88:91]
	v_mfma_f32_16x16x32_bf16 v[84:87], v[168:171], v[208:211], v[84:87]
	v_mfma_f32_16x16x32_bf16 v[80:83], v[176:179], v[208:211], v[80:83]
	v_mfma_f32_16x16x32_bf16 v[76:79], v[144:147], v[216:219], v[76:79]
	v_mfma_f32_16x16x32_bf16 v[72:75], v[160:163], v[216:219], v[72:75]
	v_mfma_f32_16x16x32_bf16 v[68:71], v[168:171], v[216:219], v[68:71]
	v_mfma_f32_16x16x32_bf16 v[64:67], v[176:179], v[216:219], v[64:67]
	s_setprio 0
	s_setprio 1
	v_mfma_f32_16x16x32_bf16 v[124:127], v[156:159], v[190:193], v[124:127]
	v_mfma_f32_16x16x32_bf16 v[120:123], v[164:167], v[190:193], v[120:123]
	v_mfma_f32_16x16x32_bf16 v[116:119], v[172:175], v[190:193], v[116:119]
	v_mfma_f32_16x16x32_bf16 v[112:115], v[182:185], v[190:193], v[112:115]
	v_mfma_f32_16x16x32_bf16 v[108:111], v[156:159], v[198:201], v[108:111]
	v_mfma_f32_16x16x32_bf16 v[104:107], v[164:167], v[198:201], v[104:107]
	v_mfma_f32_16x16x32_bf16 v[100:103], v[172:175], v[198:201], v[100:103]
	v_mfma_f32_16x16x32_bf16 v[96:99], v[182:185], v[198:201], v[96:99]
	v_mfma_f32_16x16x32_bf16 v[92:95], v[156:159], v[212:215], v[92:95]
	v_mfma_f32_16x16x32_bf16 v[88:91], v[164:167], v[212:215], v[88:91]
	v_mfma_f32_16x16x32_bf16 v[84:87], v[172:175], v[212:215], v[84:87]
	v_mfma_f32_16x16x32_bf16 v[80:83], v[182:185], v[212:215], v[80:83]
	v_mfma_f32_16x16x32_bf16 v[76:79], v[156:159], v[220:223], v[76:79]
	v_mfma_f32_16x16x32_bf16 v[72:75], v[164:167], v[220:223], v[72:75]
	v_mfma_f32_16x16x32_bf16 v[68:71], v[172:175], v[220:223], v[68:71]
	v_mfma_f32_16x16x32_bf16 v[64:67], v[182:185], v[220:223], v[64:67]
	s_setprio 0
	s_barrier
; #define PG8_STAGE(bufoff, gbase, voff) do { _Pragma("unroll") for (int _i = 0; _i < 2; ++_i) \
;         __builtin_amdgcn_global_load_lds((const unsigned*)((const char*)(gbase) + (voff)[_i]), (PG8_LAS unsigned*)(lds + (bufoff) + ldsw + _i * 8192), 16, 0, 0); } while (0)
; #define PG8_LDA(dst, b, h) do { _Pragma("unroll") for (int m = 0; m < 4; ++m) _Pragma("unroll") for (int k = 0; k < 2; ++k) dst[m][k] = *(const PG8_LAS bf16x8*)(lds + PG8_SA(b, h) + aoff + m * 2048 + k * 1024); } while (0)
; #define PG8_MMA(ai, bj, At, Bt) do { __builtin_amdgcn_s_setprio(1); _Pragma("unroll") for (int m = 0; m < 4; ++m) _Pragma("unroll") for (int n = 0; n < 2; ++n) _Pragma("unroll") for (int k = 0; k < 2; ++k) \
;         acc[ai][bj][m][n] = __builtin_amdgcn_mfma_f32_16x16x32_bf16(Bt[n][k], At[m][k], acc[ai][bj][m][n], 0, 0, 0); __builtin_amdgcn_s_setprio(0); } while (0)
; #define PG8_WAIT_V(n) asm volatile("s_waitcnt vmcnt(" #n ")" ::: "memory")
; #define PG8_WAIT_L(n) asm volatile("s_waitcnt lgkmcnt(" #n ")" ::: "memory")
; #define PG8_BAR __builtin_amdgcn_s_barrier()
; #define PG8_SCHED __builtin_amdgcn_sched_barrier(0)
; template <class Epi, class Sched, bool ALIGN_EPI = false, bool SP2 = false>
; __device__ __forceinline__ void gemm_phase(PG8_LAS unsigned char* lds, const Gemm g, const Sched& S, const Epi& E) {
;     ...
;             PG8_LDA(At, 1, 1); PG8_STAGE(PG8_SB(1, 0), b3, voffB); PG8_STAGE(PG8_SB(1, 1), b3 + hstep, voffB); PG8_STAGE(PG8_SA(1, 0), a3, voffA);
;             PG8_WAIT_V(8); PG8_WAIT_L(0); PG8_BAR; PG8_MMA(1, 0, At, B0); PG8_MMA(1, 1, At, B1); PG8_BAR; PG8_SCHED;
;     ...
;         if constexpr (ALIGN_EPI) { if (wr == 0) PG8_BAR; }
	s_add_i32 s50, s78, s33
	v_lshl_add_u64 v[224:225], v[224:225], 0, s[42:43]
	s_mov_b32 m0, s50
	ds_read_b128 v[186:189], v153 offset:49152
	ds_read_b128 v[190:193], v153 offset:50176
	ds_read_b128 v[194:197], v153 offset:51200
	ds_read_b128 v[198:201], v153 offset:52224
	ds_read_b128 v[208:211], v153 offset:53248
	ds_read_b128 v[212:215], v153 offset:54272
	ds_read_b128 v[216:219], v153 offset:55296
	ds_read_b128 v[220:223], v153 offset:56320
	global_load_lds_dwordx4 v[224:225], off
	s_add_i32 m0, s50, 0x2000
	s_add_u32 s50, s54, 0xb0080
	v_lshl_add_u64 v[224:225], v[226:227], 0, s[42:43]
	s_addc_u32 s51, s55, 0
	s_add_i32 s54, s79, s33
	global_load_lds_dwordx4 v[224:225], off
	v_lshl_add_u64 v[224:225], s[50:51], 0, v[130:131]
	s_mov_b32 m0, s54
	s_nop 0
	global_load_lds_dwordx4 v[224:225], off
	v_lshl_add_u64 v[224:225], s[50:51], 0, v[134:135]
	s_add_i32 m0, s54, 0x2000
	s_nop 0
	global_load_lds_dwordx4 v[224:225], off
	s_waitcnt vmcnt(6)
	s_waitcnt lgkmcnt(0)
	s_barrier
	s_setprio 1
	s_waitcnt lgkmcnt(0)
	v_mfma_f32_16x16x32_bf16 v[60:63], v[144:147], v[186:189], v[60:63]
	v_mfma_f32_16x16x32_bf16 v[56:59], v[160:163], v[186:189], v[56:59]
	v_mfma_f32_16x16x32_bf16 v[52:55], v[168:171], v[186:189], v[52:55]
	v_mfma_f32_16x16x32_bf16 v[48:51], v[176:179], v[186:189], v[48:51]
	v_mfma_f32_16x16x32_bf16 v[44:47], v[144:147], v[194:197], v[44:47]
	v_mfma_f32_16x16x32_bf16 v[40:43], v[160:163], v[194:197], v[40:43]
	v_mfma_f32_16x16x32_bf16 v[36:39], v[168:171], v[194:197], v[36:39]
	v_mfma_f32_16x16x32_bf16 v[32:35], v[176:179], v[194:197], v[32:35]
	v_mfma_f32_16x16x32_bf16 v[28:31], v[144:147], v[208:211], v[28:31]
	v_mfma_f32_16x16x32_bf16 v[24:27], v[160:163], v[208:211], v[24:27]
	v_mfma_f32_16x16x32_bf16 v[20:23], v[168:171], v[208:211], v[20:23]
	v_mfma_f32_16x16x32_bf16 v[16:19], v[176:179], v[208:211], v[16:19]
	v_mfma_f32_16x16x32_bf16 v[12:15], v[144:147], v[216:219], v[12:15]
	v_mfma_f32_16x16x32_bf16 v[8:11], v[160:163], v[216:219], v[8:11]
	v_lshl_add_u64 v[224:225], v[228:229], 0, s[42:43]
	s_mov_b32 m0, s62
	s_nop 0
	global_load_lds_dwordx4 v[224:225], off
	v_mfma_f32_16x16x32_bf16 v[4:7], v[168:171], v[216:219], v[4:7]
	v_mfma_f32_16x16x32_bf16 v[0:3], v[176:179], v[216:219], v[0:3]
	s_setprio 0
	s_setprio 1
	v_mfma_f32_16x16x32_bf16 v[60:63], v[156:159], v[190:193], v[60:63]
	v_mfma_f32_16x16x32_bf16 v[56:59], v[164:167], v[190:193], v[56:59]
	v_mfma_f32_16x16x32_bf16 v[52:55], v[172:175], v[190:193], v[52:55]
	v_mfma_f32_16x16x32_bf16 v[48:51], v[182:185], v[190:193], v[48:51]
	v_mfma_f32_16x16x32_bf16 v[44:47], v[156:159], v[198:201], v[44:47]
	v_mfma_f32_16x16x32_bf16 v[40:43], v[164:167], v[198:201], v[40:43]
	v_mfma_f32_16x16x32_bf16 v[36:39], v[172:175], v[198:201], v[36:39]
	v_mfma_f32_16x16x32_bf16 v[32:35], v[182:185], v[198:201], v[32:35]
	v_mfma_f32_16x16x32_bf16 v[28:31], v[156:159], v[212:215], v[28:31]
	v_mfma_f32_16x16x32_bf16 v[24:27], v[164:167], v[212:215], v[24:27]
	v_mfma_f32_16x16x32_bf16 v[20:23], v[172:175], v[212:215], v[20:23]
	v_mfma_f32_16x16x32_bf16 v[16:19], v[182:185], v[212:215], v[16:19]
	v_mfma_f32_16x16x32_bf16 v[12:15], v[156:159], v[220:223], v[12:15]
	v_mfma_f32_16x16x32_bf16 v[8:11], v[164:167], v[220:223], v[8:11]
	v_lshl_add_u64 v[224:225], v[230:231], 0, s[42:43]
	s_mov_b32 m0, s63
	s_nop 0
	global_load_lds_dwordx4 v[224:225], off
	v_mfma_f32_16x16x32_bf16 v[4:7], v[172:175], v[220:223], v[4:7]
	v_mfma_f32_16x16x32_bf16 v[0:3], v[182:185], v[220:223], v[0:3]
	s_setprio 0
	s_barrier
	s_add_i32 s84, s84, 2
	s_add_u32 s82, s82, 0x100
	s_addc_u32 s83, s83, 0
	s_cmp_gt_u32 s84, 41
	s_mov_b64 s[50:51], s[52:53]
	s_cbranch_scc0 .LBB0_1197
	s_and_b64 vcc, exec, s[44:45]
	s_cbranch_vccz .LBB0_1200
	s_barrier

; #define PG8_STAGE(bufoff, gbase, voff) do { _Pragma("unroll") for (int _i = 0; _i < 2; ++_i) \
;         __builtin_amdgcn_global_load_lds((const unsigned*)((const char*)(gbase) + (voff)[_i]), (PG8_LAS unsigned*)(lds + (bufoff) + ldsw + _i * 8192), 16, 0, 0); } while (0)
; #define PG8_LDA(dst, b, h) do { _Pragma("unroll") for (int m = 0; m < 4; ++m) _Pragma("unroll") for (int k = 0; k < 2; ++k) dst[m][k] = *(const PG8_LAS bf16x8*)(lds + PG8_SA(b, h) + aoff + m * 2048 + k * 1024); } while (0)
; #define PG8_LDB(dst, b, h) do { _Pragma("unroll") for (int n = 0; n < 2; ++n) _Pragma("unroll") for (int k = 0; k < 2; ++k) dst[n][k] = *(const PG8_LAS bf16x8*)(lds + PG8_SB(b, h) + boff + n * 2048 + k * 1024); } while (0)
; #define PG8_WAIT_V(n) asm volatile("s_waitcnt vmcnt(" #n ")" ::: "memory")
; #define PG8_WAIT_L(n) asm volatile("s_waitcnt lgkmcnt(" #n ")" ::: "memory")
; #define PG8_BAR __builtin_amdgcn_s_barrier()
; #define PG8_SCHED __builtin_amdgcn_sched_barrier(0)
; template <class Epi, class Sched, bool ALIGN_EPI = false, bool SP2 = false>
; __device__ __forceinline__ void gemm_phase(PG8_LAS unsigned char* lds, const Gemm g, const Sched& S, const Epi& E) {
;     ...
;         const bool has_next = S.next(ui + 1, nxt);
;         const char* nA = has_next ? (const char*)g.A + (size_t)nxt.pm * tstep : cA; const char* nB = has_next ? (const char*)g.Bt + (size_t)nxt.pn * tstep : cB;
;         for (int t = 0; t < nt; t += 2) {
;             const bool last = (t == nt - 2);
;             const char* a1 = cA + (size_t)(t + 1) * kstep;
;             const char* a2 = last ? nA : cA + (size_t)(t + 2) * kstep; const char* b2 = last ? nB : cB + (size_t)(t + 2) * kstep;
;             const char* a3 = a2 + kstep; const char* b3 = b2 + kstep;
;             if (last && has_next) S.a_ready(nxt);
;             if constexpr (SP2) {
;             PG8_LDB(B0, 0, 0); PG8_LDB(B1, 0, 1); PG8_SCHED; PG8_LDA(At, 0, 0); PG8_STAGE(PG8_SA(1, 1), a1 + hstep, voffA);
;             PG8_WAIT_V(8); PG8_WAIT_L(0); PG8_BAR; PG8_MMA(0, 0, At, B0); PG8_MMA(0, 1, At, B1); PG8_BAR; PG8_SCHED;
;             PG8_LDA(At, 0, 1); PG8_STAGE(PG8_SB(0, 0), b2, voffB); PG8_STAGE(PG8_SB(0, 1), b2 + hstep, voffB); PG8_STAGE(PG8_SA(0, 0), a2, voffA);
;             PG8_WAIT_V(8); PG8_WAIT_L(0); PG8_BAR; PG8_MMA(1, 0, At, B0); PG8_MMA(1, 1, At, B1); PG8_BAR; PG8_SCHED;
.LBB0_1286:
	s_ashr_i32 s51, s50, 31
	s_lshl_b64 s[52:53], s[50:51], 19
	s_add_u32 s52, s22, s52
	s_addc_u32 s53, s23, s53
	s_and_b64 s[54:55], s[12:13], exec
	s_cselect_b32 s51, s53, s59
	s_cselect_b32 s61, s52, s58
	s_ashr_i32 s49, s48, 31
	s_lshl_b64 s[54:55], s[48:49], 19
	v_readlane_b32 s64, v250, 9
	v_readlane_b32 s65, v250, 10
	s_add_u32 s54, s64, s54
	s_addc_u32 s55, s65, s55
	s_and_b64 s[64:65], s[12:13], exec
	s_cselect_b32 s49, s55, s63
	s_cselect_b32 s87, s54, s62
	s_add_u32 s58, s58, 0x40080
	s_addc_u32 s59, s59, 0
	s_add_u32 s88, s62, 0x100
	s_addc_u32 s89, s63, 0
	s_mov_b32 s90, -2
	s_waitcnt lgkmcnt(0)
	ds_read_b128 v[128:131], v181
	ds_read_b128 v[160:163], v181 offset:1024
	ds_read_b128 v[164:167], v181 offset:2048
	ds_read_b128 v[168:171], v181 offset:3072
	ds_read_b128 v[172:175], v203
	ds_read_b128 v[176:179], v203 offset:1024
	ds_read_b128 v[182:185], v203 offset:2048
	ds_read_b128 v[186:189], v203 offset:3072
	s_add_u32 s62, s58, 0xfffc0080
	s_addc_u32 s63, s59, -1
	s_cmp_eq_u32 s90, 12
	s_cselect_b32 s65, s51, s63
	s_cselect_b32 s64, s61, s62
	s_cselect_b32 s63, s49, s89
	s_cselect_b32 s62, s87, s88
	v_lshl_add_u64 v[232:233], s[58:59], 0, v[152:153]
	s_add_i32 m0, s15, 0xc000
	ds_read_b128 v[190:193], v208
	ds_read_b128 v[194:197], v208 offset:1024
	ds_read_b128 v[198:201], v208 offset:2048
	ds_read_b128 v[212:215], v208 offset:3072
	ds_read_b128 v[216:219], v208 offset:4096
	ds_read_b128 v[220:223], v208 offset:5120
	ds_read_b128 v[224:227], v208 offset:6144
	ds_read_b128 v[228:231], v208 offset:7168
	global_load_lds_dwordx4 v[232:233], off
	v_lshl_add_u64 v[232:233], s[58:59], 0, v[154:155]
	s_add_i32 m0, s15, 0xe000
	s_nop 0
	global_load_lds_dwordx4 v[232:233], off
	s_waitcnt vmcnt(8)
	s_waitcnt lgkmcnt(0)
	s_barrier
	s_setprio 1
	s_waitcnt lgkmcnt(0)
	v_mfma_f32_16x16x32_bf16 v[124:127], v[128:131], v[190:193], 0
	v_mfma_f32_16x16x32_bf16 v[120:123], v[164:167], v[190:193], 0
	v_mfma_f32_16x16x32_bf16 v[60:63], v[172:175], v[190:193], 0
	v_mfma_f32_16x16x32_bf16 v[56:59], v[182:185], v[190:193], 0
	v_mfma_f32_16x16x32_bf16 v[116:119], v[128:131], v[198:201], 0
	v_mfma_f32_16x16x32_bf16 v[112:115], v[164:167], v[198:201], 0
	v_mfma_f32_16x16x32_bf16 v[52:55], v[172:175], v[198:201], 0
	v_mfma_f32_16x16x32_bf16 v[48:51], v[182:185], v[198:201], 0
	v_mfma_f32_16x16x32_bf16 v[108:111], v[128:131], v[216:219], 0
	v_mfma_f32_16x16x32_bf16 v[104:107], v[164:167], v[216:219], 0
	v_mfma_f32_16x16x32_bf16 v[44:47], v[172:175], v[216:219], 0
	v_mfma_f32_16x16x32_bf16 v[40:43], v[182:185], v[216:219], 0
	v_mfma_f32_16x16x32_bf16 v[100:103], v[128:131], v[224:227], 0
	v_mfma_f32_16x16x32_bf16 v[96:99], v[164:167], v[224:227], 0
	v_mfma_f32_16x16x32_bf16 v[36:39], v[172:175], v[224:227], 0
	v_mfma_f32_16x16x32_bf16 v[32:35], v[182:185], v[224:227], 0
	s_setprio 0
	s_setprio 1
	v_mfma_f32_16x16x32_bf16 v[124:127], v[160:163], v[194:197], v[124:127]
	v_mfma_f32_16x16x32_bf16 v[120:123], v[168:171], v[194:197], v[120:123]
	v_mfma_f32_16x16x32_bf16 v[60:63], v[176:179], v[194:197], v[60:63]
	v_mfma_f32_16x16x32_bf16 v[56:59], v[186:189], v[194:197], v[56:59]
	v_mfma_f32_16x16x32_bf16 v[116:119], v[160:163], v[212:215], v[116:119]
	v_mfma_f32_16x16x32_bf16 v[112:115], v[168:171], v[212:215], v[112:115]
	v_mfma_f32_16x16x32_bf16 v[52:55], v[176:179], v[212:215], v[52:55]
	v_mfma_f32_16x16x32_bf16 v[48:51], v[186:189], v[212:215], v[48:51]
	v_mfma_f32_16x16x32_bf16 v[108:111], v[160:163], v[220:223], v[108:111]
	v_mfma_f32_16x16x32_bf16 v[104:107], v[168:171], v[220:223], v[104:107]
	v_mfma_f32_16x16x32_bf16 v[44:47], v[176:179], v[220:223], v[44:47]
	v_mfma_f32_16x16x32_bf16 v[40:43], v[186:189], v[220:223], v[40:43]
	v_mfma_f32_16x16x32_bf16 v[100:103], v[160:163], v[228:231], v[100:103]
	v_mfma_f32_16x16x32_bf16 v[96:99], v[168:171], v[228:231], v[96:99]
	v_mfma_f32_16x16x32_bf16 v[36:39], v[176:179], v[228:231], v[36:39]
	v_mfma_f32_16x16x32_bf16 v[32:35], v[186:189], v[228:231], v[32:35]
	s_setprio 0
	s_barrier
	s_add_i32 s78, s75, s14
	v_lshl_add_u64 v[232:233], s[62:63], 0, v[134:135]
	s_mov_b32 m0, s78
	ds_read_b128 v[190:193], v208 offset:16384
	ds_read_b128 v[194:197], v208 offset:17408
	ds_read_b128 v[198:201], v208 offset:18432
	ds_read_b128 v[212:215], v208 offset:19456
	ds_read_b128 v[216:219], v208 offset:20480
	ds_read_b128 v[220:223], v208 offset:21504
	ds_read_b128 v[224:227], v208 offset:22528
	ds_read_b128 v[228:231], v208 offset:23552
	global_load_lds_dwordx4 v[232:233], off
	s_add_i32 m0, s78, 0x2000
	s_add_u32 s78, s62, 0x40000
	v_lshl_add_u64 v[234:235], s[62:63], 0, v[138:139]
	s_addc_u32 s79, s63, 0
	s_add_i32 s91, s76, s14
	global_load_lds_dwordx4 v[234:235], off
	v_lshl_add_u64 v[236:237], s[78:79], 0, v[134:135]
	s_mov_b32 m0, s91
	global_load_lds_dwordx4 v[236:237], off
	v_lshl_add_u64 v[236:237], s[78:79], 0, v[138:139]
	s_add_i32 m0, s91, 0x2000
	s_nop 0
	global_load_lds_dwordx4 v[236:237], off
	s_waitcnt vmcnt(6)
	s_waitcnt lgkmcnt(0)
	s_barrier
; #define PG8_STAGE(bufoff, gbase, voff) do { _Pragma("unroll") for (int _i = 0; _i < 2; ++_i) \
;         __builtin_amdgcn_global_load_lds((const unsigned*)((const char*)(gbase) + (voff)[_i]), (PG8_LAS unsigned*)(lds + (bufoff) + ldsw + _i * 8192), 16, 0, 0); } while (0)
; #define PG8_LDA(dst, b, h) do { _Pragma("unroll") for (int m = 0; m < 4; ++m) _Pragma("unroll") for (int k = 0; k < 2; ++k) dst[m][k] = *(const PG8_LAS bf16x8*)(lds + PG8_SA(b, h) + aoff + m * 2048 + k * 1024); } while (0)
; #define PG8_LDB(dst, b, h) do { _Pragma("unroll") for (int n = 0; n < 2; ++n) _Pragma("unroll") for (int k = 0; k < 2; ++k) dst[n][k] = *(const PG8_LAS bf16x8*)(lds + PG8_SB(b, h) + boff + n * 2048 + k * 1024); } while (0)
; #define PG8_MMA(ai, bj, At, Bt) do { __builtin_amdgcn_s_setprio(1); _Pragma("unroll") for (int m = 0; m < 4; ++m) _Pragma("unroll") for (int n = 0; n < 2; ++n) _Pragma("unroll") for (int k = 0; k < 2; ++k) \
;         acc[ai][bj][m][n] = __builtin_amdgcn_mfma_f32_16x16x32_bf16(Bt[n][k], At[m][k], acc[ai][bj][m][n], 0, 0, 0); __builtin_amdgcn_s_setprio(0); } while (0)
; #define PG8_WAIT_V(n) asm volatile("s_waitcnt vmcnt(" #n ")" ::: "memory")
; #define PG8_WAIT_L(n) asm volatile("s_waitcnt lgkmcnt(" #n ")" ::: "memory")
; #define PG8_BAR __builtin_amdgcn_s_barrier()
; #define PG8_SCHED __builtin_amdgcn_sched_barrier(0)
; template <class Epi, class Sched, bool ALIGN_EPI = false, bool SP2 = false>
; __device__ __forceinline__ void gemm_phase(PG8_LAS unsigned char* lds, const Gemm g, const Sched& S, const Epi& E) {
;     ...
;             PG8_WAIT_V(8); PG8_WAIT_L(0); PG8_BAR; PG8_MMA(1, 0, At, B0); PG8_MMA(1, 1, At, B1); PG8_BAR; PG8_SCHED;
;             PG8_LDB(B0, 1, 0); PG8_LDB(B1, 1, 1); PG8_SCHED; PG8_LDA(At, 1, 0); PG8_STAGE(PG8_SA(0, 1), a2 + hstep, voffA);
;             PG8_WAIT_V(8); PG8_WAIT_L(0); PG8_BAR; PG8_MMA(0, 0, At, B0); PG8_MMA(0, 1, At, B1); PG8_BAR; PG8_SCHED;
	s_setprio 1
	s_waitcnt lgkmcnt(0)
	v_mfma_f32_16x16x32_bf16 v[92:95], v[128:131], v[190:193], 0
	v_mfma_f32_16x16x32_bf16 v[88:91], v[164:167], v[190:193], 0
	v_mfma_f32_16x16x32_bf16 v[28:31], v[172:175], v[190:193], 0
	v_mfma_f32_16x16x32_bf16 v[24:27], v[182:185], v[190:193], 0
	v_mfma_f32_16x16x32_bf16 v[84:87], v[128:131], v[198:201], 0
	v_mfma_f32_16x16x32_bf16 v[80:83], v[164:167], v[198:201], 0
	v_mfma_f32_16x16x32_bf16 v[20:23], v[172:175], v[198:201], 0
	v_mfma_f32_16x16x32_bf16 v[16:19], v[182:185], v[198:201], 0
	v_mfma_f32_16x16x32_bf16 v[76:79], v[128:131], v[216:219], 0
	v_mfma_f32_16x16x32_bf16 v[72:75], v[164:167], v[216:219], 0
	v_mfma_f32_16x16x32_bf16 v[12:15], v[172:175], v[216:219], 0
	v_mfma_f32_16x16x32_bf16 v[8:11], v[182:185], v[216:219], 0
	v_mfma_f32_16x16x32_bf16 v[68:71], v[128:131], v[224:227], 0
	v_mfma_f32_16x16x32_bf16 v[64:67], v[164:167], v[224:227], 0
	v_lshl_add_u64 v[236:237], s[64:65], 0, v[132:133]
	s_mov_b32 m0, s15
	s_nop 0
	global_load_lds_dwordx4 v[236:237], off
	v_mfma_f32_16x16x32_bf16 v[4:7], v[172:175], v[224:227], 0
	v_mfma_f32_16x16x32_bf16 v[0:3], v[182:185], v[224:227], 0
	s_setprio 0
	s_setprio 1
	v_mfma_f32_16x16x32_bf16 v[92:95], v[160:163], v[194:197], v[92:95]
	v_mfma_f32_16x16x32_bf16 v[88:91], v[168:171], v[194:197], v[88:91]
	v_mfma_f32_16x16x32_bf16 v[28:31], v[176:179], v[194:197], v[28:31]
	v_mfma_f32_16x16x32_bf16 v[24:27], v[186:189], v[194:197], v[24:27]
	v_mfma_f32_16x16x32_bf16 v[84:87], v[160:163], v[212:215], v[84:87]
	v_mfma_f32_16x16x32_bf16 v[80:83], v[168:171], v[212:215], v[80:83]
	v_mfma_f32_16x16x32_bf16 v[20:23], v[176:179], v[212:215], v[20:23]
	v_mfma_f32_16x16x32_bf16 v[16:19], v[186:189], v[212:215], v[16:19]
	v_mfma_f32_16x16x32_bf16 v[76:79], v[160:163], v[220:223], v[76:79]
	v_mfma_f32_16x16x32_bf16 v[72:75], v[168:171], v[220:223], v[72:75]
	v_mfma_f32_16x16x32_bf16 v[12:15], v[176:179], v[220:223], v[12:15]
	v_mfma_f32_16x16x32_bf16 v[8:11], v[186:189], v[220:223], v[8:11]
	v_mfma_f32_16x16x32_bf16 v[68:71], v[160:163], v[228:231], v[68:71]
	v_mfma_f32_16x16x32_bf16 v[64:67], v[168:171], v[228:231], v[64:67]
	v_lshl_add_u64 v[238:239], s[64:65], 0, v[136:137]
	s_mov_b32 m0, s33
	s_nop 0
	global_load_lds_dwordx4 v[238:239], off
	v_mfma_f32_16x16x32_bf16 v[4:7], v[176:179], v[228:231], v[4:7]
	v_mfma_f32_16x16x32_bf16 v[0:3], v[186:189], v[228:231], v[0:3]
	s_setprio 0
	s_barrier
	s_add_i32 s78, 0, 0x18000
	v_add_u32_e32 v140, s78, v147
	s_add_i32 s79, 0, 0x1c000
	ds_read_b128 v[128:131], v140
	ds_read_b128 v[160:163], v140 offset:1024
	ds_read_b128 v[164:167], v140 offset:2048
	ds_read_b128 v[168:171], v140 offset:3072
	v_add_u32_e32 v140, s79, v147
	ds_read_b128 v[172:175], v140
	ds_read_b128 v[176:179], v140 offset:1024
	ds_read_b128 v[182:185], v140 offset:2048
	ds_read_b128 v[186:189], v140 offset:3072
	s_add_u32 s64, s64, 0x40000
	s_addc_u32 s65, s65, 0
	s_mov_b32 m0, s34
	v_lshl_add_u64 v[240:241], s[64:65], 0, v[132:133]
	ds_read_b128 v[190:193], v208 offset:32768
	ds_read_b128 v[194:197], v208 offset:33792
	ds_read_b128 v[198:201], v208 offset:34816
	ds_read_b128 v[212:215], v208 offset:35840
	ds_read_b128 v[216:219], v208 offset:36864
	ds_read_b128 v[220:223], v208 offset:37888
	ds_read_b128 v[224:227], v208 offset:38912
	ds_read_b128 v[228:231], v208 offset:39936
	global_load_lds_dwordx4 v[240:241], off
	v_lshl_add_u64 v[240:241], s[64:65], 0, v[136:137]
	s_mov_b32 m0, s57
	s_nop 0
	global_load_lds_dwordx4 v[240:241], off
	s_waitcnt vmcnt(8)
	s_waitcnt lgkmcnt(0)
	s_barrier
	s_setprio 1
	s_waitcnt lgkmcnt(0)
	v_mfma_f32_16x16x32_bf16 v[124:127], v[128:131], v[190:193], v[124:127]
	v_mfma_f32_16x16x32_bf16 v[120:123], v[164:167], v[190:193], v[120:123]
	v_mfma_f32_16x16x32_bf16 v[60:63], v[172:175], v[190:193], v[60:63]
	v_mfma_f32_16x16x32_bf16 v[56:59], v[182:185], v[190:193], v[56:59]
	v_mfma_f32_16x16x32_bf16 v[116:119], v[128:131], v[198:201], v[116:119]
	v_mfma_f32_16x16x32_bf16 v[112:115], v[164:167], v[198:201], v[112:115]
	v_mfma_f32_16x16x32_bf16 v[52:55], v[172:175], v[198:201], v[52:55]
	v_mfma_f32_16x16x32_bf16 v[48:51], v[182:185], v[198:201], v[48:51]
	v_mfma_f32_16x16x32_bf16 v[108:111], v[128:131], v[216:219], v[108:111]
	v_mfma_f32_16x16x32_bf16 v[104:107], v[164:167], v[216:219], v[104:107]
	v_mfma_f32_16x16x32_bf16 v[44:47], v[172:175], v[216:219], v[44:47]
	v_mfma_f32_16x16x32_bf16 v[40:43], v[182:185], v[216:219], v[40:43]
	v_mfma_f32_16x16x32_bf16 v[100:103], v[128:131], v[224:227], v[100:103]
	v_mfma_f32_16x16x32_bf16 v[96:99], v[164:167], v[224:227], v[96:99]
	v_mfma_f32_16x16x32_bf16 v[36:39], v[172:175], v[224:227], v[36:39]
	v_mfma_f32_16x16x32_bf16 v[32:35], v[182:185], v[224:227], v[32:35]
	s_setprio 0
	s_setprio 1
	v_mfma_f32_16x16x32_bf16 v[124:127], v[160:163], v[194:197], v[124:127]
	v_mfma_f32_16x16x32_bf16 v[120:123], v[168:171], v[194:197], v[120:123]
	v_mfma_f32_16x16x32_bf16 v[60:63], v[176:179], v[194:197], v[60:63]
	v_mfma_f32_16x16x32_bf16 v[56:59], v[186:189], v[194:197], v[56:59]
	v_mfma_f32_16x16x32_bf16 v[116:119], v[160:163], v[212:215], v[116:119]
	v_mfma_f32_16x16x32_bf16 v[112:115], v[168:171], v[212:215], v[112:115]
	v_mfma_f32_16x16x32_bf16 v[52:55], v[176:179], v[212:215], v[52:55]
	v_mfma_f32_16x16x32_bf16 v[48:51], v[186:189], v[212:215], v[48:51]
	v_mfma_f32_16x16x32_bf16 v[108:111], v[160:163], v[220:223], v[108:111]
	v_mfma_f32_16x16x32_bf16 v[104:107], v[168:171], v[220:223], v[104:107]
	v_mfma_f32_16x16x32_bf16 v[44:47], v[176:179], v[220:223], v[44:47]
	v_mfma_f32_16x16x32_bf16 v[40:43], v[186:189], v[220:223], v[40:43]
	v_mfma_f32_16x16x32_bf16 v[100:103], v[160:163], v[228:231], v[100:103]
	v_mfma_f32_16x16x32_bf16 v[96:99], v[168:171], v[228:231], v[96:99]
	v_mfma_f32_16x16x32_bf16 v[36:39], v[176:179], v[228:231], v[36:39]
	v_mfma_f32_16x16x32_bf16 v[32:35], v[186:189], v[228:231], v[32:35]
	s_setprio 0
	s_barrier
; #define PG8_STAGE(bufoff, gbase, voff) do { _Pragma("unroll") for (int _i = 0; _i < 2; ++_i) \
;         __builtin_amdgcn_global_load_lds((const unsigned*)((const char*)(gbase) + (voff)[_i]), (PG8_LAS unsigned*)(lds + (bufoff) + ldsw + _i * 8192), 16, 0, 0); } while (0)
; #define PG8_LDA(dst, b, h) do { _Pragma("unroll") for (int m = 0; m < 4; ++m) _Pragma("unroll") for (int k = 0; k < 2; ++k) dst[m][k] = *(const PG8_LAS bf16x8*)(lds + PG8_SA(b, h) + aoff + m * 2048 + k * 1024); } while (0)
; #define PG8_LDB(dst, b, h) do { _Pragma("unroll") for (int n = 0; n < 2; ++n) _Pragma("unroll") for (int k = 0; k < 2; ++k) dst[n][k] = *(const PG8_LAS bf16x8*)(lds + PG8_SB(b, h) + boff + n * 2048 + k * 1024); } while (0)
; #define PG8_MMA(ai, bj, At, Bt) do { __builtin_amdgcn_s_setprio(1); _Pragma("unroll") for (int m = 0; m < 4; ++m) _Pragma("unroll") for (int n = 0; n < 2; ++n) _Pragma("unroll") for (int k = 0; k < 2; ++k) \
;         acc[ai][bj][m][n] = __builtin_amdgcn_mfma_f32_16x16x32_bf16(Bt[n][k], At[m][k], acc[ai][bj][m][n], 0, 0, 0); __builtin_amdgcn_s_setprio(0); } while (0)
; #define PG8_WAIT_V(n) asm volatile("s_waitcnt vmcnt(" #n ")" ::: "memory")
; #define PG8_BAR __builtin_amdgcn_s_barrier()
; template <class Epi, class Sched, bool ALIGN_EPI = false, bool SP2 = false>
; __device__ __forceinline__ void gemm_phase(PG8_LAS unsigned char* lds, const Gemm g, const Sched& S, const Epi& E) {
;     ...
;         for (int t = 0; t < nt; t += 2) {
;             const bool last = (t == nt - 2);
;             const char* a1 = cA + (size_t)(t + 1) * kstep;
;             const char* a2 = last ? nA : cA + (size_t)(t + 2) * kstep; const char* b2 = last ? nB : cB + (size_t)(t + 2) * kstep;
;             const char* a3 = a2 + kstep; const char* b3 = b2 + kstep;
;             if (last && has_next) S.a_ready(nxt);
;             if constexpr (SP2) {
;             PG8_LDB(B0, 0, 0); PG8_LDB(B1, 0, 1); PG8_SCHED; PG8_LDA(At, 0, 0); PG8_STAGE(PG8_SA(1, 1), a1 + hstep, voffA);
;             PG8_WAIT_V(8); PG8_WAIT_L(0); PG8_BAR; PG8_MMA(0, 0, At, B0); PG8_MMA(0, 1, At, B1); PG8_BAR; PG8_SCHED;
;     ...
;             PG8_LDA(At, 1, 1); PG8_STAGE(PG8_SB(1, 0), b3, voffB); PG8_STAGE(PG8_SB(1, 1), b3 + hstep, voffB); PG8_STAGE(PG8_SA(1, 0), a3, voffA);
;             PG8_WAIT_V(8); PG8_WAIT_L(0); PG8_BAR; PG8_MMA(1, 0, At, B0); PG8_MMA(1, 1, At, B1); PG8_BAR; PG8_SCHED;
	s_add_i32 s64, s78, s14
	v_lshl_add_u64 v[232:233], v[232:233], 0, s[42:43]
	s_mov_b32 m0, s64
	ds_read_b128 v[190:193], v208 offset:49152
	ds_read_b128 v[194:197], v208 offset:50176
	ds_read_b128 v[198:201], v208 offset:51200
	ds_read_b128 v[212:215], v208 offset:52224
	ds_read_b128 v[216:219], v208 offset:53248
	ds_read_b128 v[220:223], v208 offset:54272
	ds_read_b128 v[224:227], v208 offset:55296
	ds_read_b128 v[228:231], v208 offset:56320
	global_load_lds_dwordx4 v[232:233], off
	s_add_i32 m0, s64, 0x2000
	s_add_u32 s62, s62, 0x40080
	v_lshl_add_u64 v[232:233], v[234:235], 0, s[42:43]
	s_addc_u32 s63, s63, 0
	s_add_i32 s64, s79, s14
	global_load_lds_dwordx4 v[232:233], off
	v_lshl_add_u64 v[232:233], s[62:63], 0, v[134:135]
	s_mov_b32 m0, s64
	s_nop 0
	global_load_lds_dwordx4 v[232:233], off
	v_lshl_add_u64 v[232:233], s[62:63], 0, v[138:139]
	s_add_i32 m0, s64, 0x2000
	s_nop 0
	global_load_lds_dwordx4 v[232:233], off
	s_waitcnt vmcnt(6)
	s_waitcnt lgkmcnt(0)
	s_barrier
	s_setprio 1
	s_waitcnt lgkmcnt(0)
	v_mfma_f32_16x16x32_bf16 v[92:95], v[128:131], v[190:193], v[92:95]
	v_mfma_f32_16x16x32_bf16 v[88:91], v[164:167], v[190:193], v[88:91]
	v_mfma_f32_16x16x32_bf16 v[28:31], v[172:175], v[190:193], v[28:31]
	v_mfma_f32_16x16x32_bf16 v[24:27], v[182:185], v[190:193], v[24:27]
	v_mfma_f32_16x16x32_bf16 v[84:87], v[128:131], v[198:201], v[84:87]
	v_mfma_f32_16x16x32_bf16 v[80:83], v[164:167], v[198:201], v[80:83]
	v_mfma_f32_16x16x32_bf16 v[20:23], v[172:175], v[198:201], v[20:23]
	v_mfma_f32_16x16x32_bf16 v[16:19], v[182:185], v[198:201], v[16:19]
	v_mfma_f32_16x16x32_bf16 v[76:79], v[128:131], v[216:219], v[76:79]
	v_mfma_f32_16x16x32_bf16 v[72:75], v[164:167], v[216:219], v[72:75]
	v_mfma_f32_16x16x32_bf16 v[12:15], v[172:175], v[216:219], v[12:15]
	v_mfma_f32_16x16x32_bf16 v[8:11], v[182:185], v[216:219], v[8:11]
	v_mfma_f32_16x16x32_bf16 v[68:71], v[128:131], v[224:227], v[68:71]
	v_mfma_f32_16x16x32_bf16 v[64:67], v[164:167], v[224:227], v[64:67]
	v_lshl_add_u64 v[232:233], v[236:237], 0, s[42:43]
	s_mov_b32 m0, s67
	s_nop 0
	global_load_lds_dwordx4 v[232:233], off
	v_mfma_f32_16x16x32_bf16 v[4:7], v[172:175], v[224:227], v[4:7]
	v_mfma_f32_16x16x32_bf16 v[0:3], v[182:185], v[224:227], v[0:3]
	s_setprio 0
	s_setprio 1
	v_mfma_f32_16x16x32_bf16 v[92:95], v[160:163], v[194:197], v[92:95]
	v_mfma_f32_16x16x32_bf16 v[88:91], v[168:171], v[194:197], v[88:91]
	v_mfma_f32_16x16x32_bf16 v[28:31], v[176:179], v[194:197], v[28:31]
	v_mfma_f32_16x16x32_bf16 v[24:27], v[186:189], v[194:197], v[24:27]
	v_mfma_f32_16x16x32_bf16 v[84:87], v[160:163], v[212:215], v[84:87]
	v_mfma_f32_16x16x32_bf16 v[80:83], v[168:171], v[212:215], v[80:83]
	v_mfma_f32_16x16x32_bf16 v[20:23], v[176:179], v[212:215], v[20:23]
	v_mfma_f32_16x16x32_bf16 v[16:19], v[186:189], v[212:215], v[16:19]
	v_mfma_f32_16x16x32_bf16 v[76:79], v[160:163], v[220:223], v[76:79]
	v_mfma_f32_16x16x32_bf16 v[72:75], v[168:171], v[220:223], v[72:75]
	v_mfma_f32_16x16x32_bf16 v[12:15], v[176:179], v[220:223], v[12:15]
	v_mfma_f32_16x16x32_bf16 v[8:11], v[186:189], v[220:223], v[8:11]
	v_mfma_f32_16x16x32_bf16 v[68:71], v[160:163], v[228:231], v[68:71]
	v_mfma_f32_16x16x32_bf16 v[64:67], v[168:171], v[228:231], v[64:67]
	v_lshl_add_u64 v[232:233], v[238:239], 0, s[42:43]
	s_mov_b32 m0, s74
	s_nop 0
	global_load_lds_dwordx4 v[232:233], off
	v_mfma_f32_16x16x32_bf16 v[4:7], v[176:179], v[228:231], v[4:7]
	v_mfma_f32_16x16x32_bf16 v[0:3], v[186:189], v[228:231], v[0:3]
	s_setprio 0
	s_barrier
	s_add_i32 s90, s90, 2
	s_add_u32 s58, s58, 0x100
	s_addc_u32 s59, s59, 0
	s_add_u32 s88, s88, 0x100
	s_addc_u32 s89, s89, 0
.LBB0_1287:
	ds_read_b128 v[128:131], v181
	ds_read_b128 v[160:163], v181 offset:1024
	ds_read_b128 v[164:167], v181 offset:2048
	ds_read_b128 v[168:171], v181 offset:3072
	ds_read_b128 v[172:175], v203
	ds_read_b128 v[176:179], v203 offset:1024
	ds_read_b128 v[182:185], v203 offset:2048
	ds_read_b128 v[186:189], v203 offset:3072
	s_add_u32 s62, s58, 0xfffc0080
	s_addc_u32 s63, s59, -1
	s_cmp_eq_u32 s90, 12
	s_cselect_b32 s65, s51, s63
	s_cselect_b32 s64, s61, s62
	s_cselect_b32 s63, s49, s89
	s_cselect_b32 s62, s87, s88
	v_lshl_add_u64 v[232:233], s[58:59], 0, v[152:153]
	s_add_i32 m0, s15, 0xc000
	ds_read_b128 v[190:193], v208
	ds_read_b128 v[194:197], v208 offset:1024
	ds_read_b128 v[198:201], v208 offset:2048
	ds_read_b128 v[212:215], v208 offset:3072
	ds_read_b128 v[216:219], v208 offset:4096
	ds_read_b128 v[220:223], v208 offset:5120
	ds_read_b128 v[224:227], v208 offset:6144
	ds_read_b128 v[228:231], v208 offset:7168
	global_load_lds_dwordx4 v[232:233], off
	v_lshl_add_u64 v[232:233], s[58:59], 0, v[154:155]
	s_add_i32 m0, s15, 0xe000
	s_nop 0
	global_load_lds_dwordx4 v[232:233], off
	s_waitcnt vmcnt(8)
	s_waitcnt lgkmcnt(0)
	s_barrier
; #define PG8_STAGE(bufoff, gbase, voff) do { _Pragma("unroll") for (int _i = 0; _i < 2; ++_i) \
;         __builtin_amdgcn_global_load_lds((const unsigned*)((const char*)(gbase) + (voff)[_i]), (PG8_LAS unsigned*)(lds + (bufoff) + ldsw + _i * 8192), 16, 0, 0); } while (0)
; #define PG8_LDA(dst, b, h) do { _Pragma("unroll") for (int m = 0; m < 4; ++m) _Pragma("unroll") for (int k = 0; k < 2; ++k) dst[m][k] = *(const PG8_LAS bf16x8*)(lds + PG8_SA(b, h) + aoff + m * 2048 + k * 1024); } while (0)
; #define PG8_MMA(ai, bj, At, Bt) do { __builtin_amdgcn_s_setprio(1); _Pragma("unroll") for (int m = 0; m < 4; ++m) _Pragma("unroll") for (int n = 0; n < 2; ++n) _Pragma("unroll") for (int k = 0; k < 2; ++k) \
;         acc[ai][bj][m][n] = __builtin_amdgcn_mfma_f32_16x16x32_bf16(Bt[n][k], At[m][k], acc[ai][bj][m][n], 0, 0, 0); __builtin_amdgcn_s_setprio(0); } while (0)
; #define PG8_WAIT_V(n) asm volatile("s_waitcnt vmcnt(" #n ")" ::: "memory")
; #define PG8_WAIT_L(n) asm volatile("s_waitcnt lgkmcnt(" #n ")" ::: "memory")
; #define PG8_BAR __builtin_amdgcn_s_barrier()
; #define PG8_SCHED __builtin_amdgcn_sched_barrier(0)
; template <class Epi, class Sched, bool ALIGN_EPI = false, bool SP2 = false>
; __device__ __forceinline__ void gemm_phase(PG8_LAS unsigned char* lds, const Gemm g, const Sched& S, const Epi& E) {
;     ...
;             PG8_WAIT_V(8); PG8_WAIT_L(0); PG8_BAR; PG8_MMA(0, 0, At, B0); PG8_MMA(0, 1, At, B1); PG8_BAR; PG8_SCHED;
;             PG8_LDA(At, 0, 1); PG8_STAGE(PG8_SB(0, 0), b2, voffB); PG8_STAGE(PG8_SB(0, 1), b2 + hstep, voffB); PG8_STAGE(PG8_SA(0, 0), a2, voffA);
;             PG8_WAIT_V(8); PG8_WAIT_L(0); PG8_BAR; PG8_MMA(1, 0, At, B0); PG8_MMA(1, 1, At, B1); PG8_BAR; PG8_SCHED;
	s_setprio 1
	s_waitcnt lgkmcnt(0)
	v_mfma_f32_16x16x32_bf16 v[124:127], v[128:131], v[190:193], v[124:127]
	v_mfma_f32_16x16x32_bf16 v[120:123], v[164:167], v[190:193], v[120:123]
	v_mfma_f32_16x16x32_bf16 v[60:63], v[172:175], v[190:193], v[60:63]
	v_mfma_f32_16x16x32_bf16 v[56:59], v[182:185], v[190:193], v[56:59]
	v_mfma_f32_16x16x32_bf16 v[116:119], v[128:131], v[198:201], v[116:119]
	v_mfma_f32_16x16x32_bf16 v[112:115], v[164:167], v[198:201], v[112:115]
	v_mfma_f32_16x16x32_bf16 v[52:55], v[172:175], v[198:201], v[52:55]
	v_mfma_f32_16x16x32_bf16 v[48:51], v[182:185], v[198:201], v[48:51]
	v_mfma_f32_16x16x32_bf16 v[108:111], v[128:131], v[216:219], v[108:111]
	v_mfma_f32_16x16x32_bf16 v[104:107], v[164:167], v[216:219], v[104:107]
	v_mfma_f32_16x16x32_bf16 v[44:47], v[172:175], v[216:219], v[44:47]
	v_mfma_f32_16x16x32_bf16 v[40:43], v[182:185], v[216:219], v[40:43]
	v_mfma_f32_16x16x32_bf16 v[100:103], v[128:131], v[224:227], v[100:103]
	v_mfma_f32_16x16x32_bf16 v[96:99], v[164:167], v[224:227], v[96:99]
	v_mfma_f32_16x16x32_bf16 v[36:39], v[172:175], v[224:227], v[36:39]
	v_mfma_f32_16x16x32_bf16 v[32:35], v[182:185], v[224:227], v[32:35]
	s_setprio 0
	s_setprio 1
	v_mfma_f32_16x16x32_bf16 v[124:127], v[160:163], v[194:197], v[124:127]
	v_mfma_f32_16x16x32_bf16 v[120:123], v[168:171], v[194:197], v[120:123]
	v_mfma_f32_16x16x32_bf16 v[60:63], v[176:179], v[194:197], v[60:63]
	v_mfma_f32_16x16x32_bf16 v[56:59], v[186:189], v[194:197], v[56:59]
	v_mfma_f32_16x16x32_bf16 v[116:119], v[160:163], v[212:215], v[116:119]
	v_mfma_f32_16x16x32_bf16 v[112:115], v[168:171], v[212:215], v[112:115]
	v_mfma_f32_16x16x32_bf16 v[52:55], v[176:179], v[212:215], v[52:55]
	v_mfma_f32_16x16x32_bf16 v[48:51], v[186:189], v[212:215], v[48:51]
	v_mfma_f32_16x16x32_bf16 v[108:111], v[160:163], v[220:223], v[108:111]
	v_mfma_f32_16x16x32_bf16 v[104:107], v[168:171], v[220:223], v[104:107]
	v_mfma_f32_16x16x32_bf16 v[44:47], v[176:179], v[220:223], v[44:47]
	v_mfma_f32_16x16x32_bf16 v[40:43], v[186:189], v[220:223], v[40:43]
	v_mfma_f32_16x16x32_bf16 v[100:103], v[160:163], v[228:231], v[100:103]
	v_mfma_f32_16x16x32_bf16 v[96:99], v[168:171], v[228:231], v[96:99]
	v_mfma_f32_16x16x32_bf16 v[36:39], v[176:179], v[228:231], v[36:39]
	v_mfma_f32_16x16x32_bf16 v[32:35], v[186:189], v[228:231], v[32:35]
	s_setprio 0
	s_barrier
	s_add_i32 s78, s75, s14
	v_lshl_add_u64 v[232:233], s[62:63], 0, v[134:135]
	s_mov_b32 m0, s78
	ds_read_b128 v[190:193], v208 offset:16384
	ds_read_b128 v[194:197], v208 offset:17408
	ds_read_b128 v[198:201], v208 offset:18432
	ds_read_b128 v[212:215], v208 offset:19456
	ds_read_b128 v[216:219], v208 offset:20480
	ds_read_b128 v[220:223], v208 offset:21504
	ds_read_b128 v[224:227], v208 offset:22528
	ds_read_b128 v[228:231], v208 offset:23552
	global_load_lds_dwordx4 v[232:233], off
	s_add_i32 m0, s78, 0x2000
	s_add_u32 s78, s62, 0x40000
	v_lshl_add_u64 v[234:235], s[62:63], 0, v[138:139]
	s_addc_u32 s79, s63, 0
	s_add_i32 s91, s76, s14
	global_load_lds_dwordx4 v[234:235], off
	v_lshl_add_u64 v[236:237], s[78:79], 0, v[134:135]
	s_mov_b32 m0, s91
	global_load_lds_dwordx4 v[236:237], off
	v_lshl_add_u64 v[236:237], s[78:79], 0, v[138:139]
	s_add_i32 m0, s91, 0x2000
	s_nop 0
	global_load_lds_dwordx4 v[236:237], off
	s_waitcnt vmcnt(6)
	s_waitcnt lgkmcnt(0)
	s_barrier
	s_setprio 1
	s_waitcnt lgkmcnt(0)
	v_mfma_f32_16x16x32_bf16 v[92:95], v[128:131], v[190:193], v[92:95]
	v_mfma_f32_16x16x32_bf16 v[88:91], v[164:167], v[190:193], v[88:91]
	v_mfma_f32_16x16x32_bf16 v[28:31], v[172:175], v[190:193], v[28:31]
	v_mfma_f32_16x16x32_bf16 v[24:27], v[182:185], v[190:193], v[24:27]
	v_mfma_f32_16x16x32_bf16 v[84:87], v[128:131], v[198:201], v[84:87]
	v_mfma_f32_16x16x32_bf16 v[80:83], v[164:167], v[198:201], v[80:83]
	v_mfma_f32_16x16x32_bf16 v[20:23], v[172:175], v[198:201], v[20:23]
	v_mfma_f32_16x16x32_bf16 v[16:19], v[182:185], v[198:201], v[16:19]
	v_mfma_f32_16x16x32_bf16 v[76:79], v[128:131], v[216:219], v[76:79]
	v_mfma_f32_16x16x32_bf16 v[72:75], v[164:167], v[216:219], v[72:75]
	v_mfma_f32_16x16x32_bf16 v[12:15], v[172:175], v[216:219], v[12:15]
	v_mfma_f32_16x16x32_bf16 v[8:11], v[182:185], v[216:219], v[8:11]
	v_mfma_f32_16x16x32_bf16 v[68:71], v[128:131], v[224:227], v[68:71]
	v_mfma_f32_16x16x32_bf16 v[64:67], v[164:167], v[224:227], v[64:67]
	v_lshl_add_u64 v[236:237], s[64:65], 0, v[132:133]
	s_mov_b32 m0, s15
	s_nop 0
	global_load_lds_dwordx4 v[236:237], off
	v_mfma_f32_16x16x32_bf16 v[4:7], v[172:175], v[224:227], v[4:7]
	v_mfma_f32_16x16x32_bf16 v[0:3], v[182:185], v[224:227], v[0:3]
	s_setprio 0
	s_setprio 1
	v_mfma_f32_16x16x32_bf16 v[92:95], v[160:163], v[194:197], v[92:95]
	v_mfma_f32_16x16x32_bf16 v[88:91], v[168:171], v[194:197], v[88:91]
	v_mfma_f32_16x16x32_bf16 v[28:31], v[176:179], v[194:197], v[28:31]
	v_mfma_f32_16x16x32_bf16 v[24:27], v[186:189], v[194:197], v[24:27]
	v_mfma_f32_16x16x32_bf16 v[84:87], v[160:163], v[212:215], v[84:87]
	v_mfma_f32_16x16x32_bf16 v[80:83], v[168:171], v[212:215], v[80:83]
	v_mfma_f32_16x16x32_bf16 v[20:23], v[176:179], v[212:215], v[20:23]
	v_mfma_f32_16x16x32_bf16 v[16:19], v[186:189], v[212:215], v[16:19]
	v_mfma_f32_16x16x32_bf16 v[76:79], v[160:163], v[220:223], v[76:79]
	v_mfma_f32_16x16x32_bf16 v[72:75], v[168:171], v[220:223], v[72:75]
	v_mfma_f32_16x16x32_bf16 v[12:15], v[176:179], v[220:223], v[12:15]
	v_mfma_f32_16x16x32_bf16 v[8:11], v[186:189], v[220:223], v[8:11]
	v_mfma_f32_16x16x32_bf16 v[68:71], v[160:163], v[228:231], v[68:71]
	v_mfma_f32_16x16x32_bf16 v[64:67], v[168:171], v[228:231], v[64:67]
	v_lshl_add_u64 v[238:239], s[64:65], 0, v[136:137]
	s_mov_b32 m0, s33
	s_nop 0
	global_load_lds_dwordx4 v[238:239], off
	v_mfma_f32_16x16x32_bf16 v[4:7], v[176:179], v[228:231], v[4:7]
	v_mfma_f32_16x16x32_bf16 v[0:3], v[186:189], v[228:231], v[0:3]
	s_setprio 0
	s_barrier
; #define PG8_STAGE(bufoff, gbase, voff) do { _Pragma("unroll") for (int _i = 0; _i < 2; ++_i) \
;         __builtin_amdgcn_global_load_lds((const unsigned*)((const char*)(gbase) + (voff)[_i]), (PG8_LAS unsigned*)(lds + (bufoff) + ldsw + _i * 8192), 16, 0, 0); } while (0)
; #define PG8_LDA(dst, b, h) do { _Pragma("unroll") for (int m = 0; m < 4; ++m) _Pragma("unroll") for (int k = 0; k < 2; ++k) dst[m][k] = *(const PG8_LAS bf16x8*)(lds + PG8_SA(b, h) + aoff + m * 2048 + k * 1024); } while (0)
; #define PG8_LDB(dst, b, h) do { _Pragma("unroll") for (int n = 0; n < 2; ++n) _Pragma("unroll") for (int k = 0; k < 2; ++k) dst[n][k] = *(const PG8_LAS bf16x8*)(lds + PG8_SB(b, h) + boff + n * 2048 + k * 1024); } while (0)
; #define PG8_MMA(ai, bj, At, Bt) do { __builtin_amdgcn_s_setprio(1); _Pragma("unroll") for (int m = 0; m < 4; ++m) _Pragma("unroll") for (int n = 0; n < 2; ++n) _Pragma("unroll") for (int k = 0; k < 2; ++k) \
;         acc[ai][bj][m][n] = __builtin_amdgcn_mfma_f32_16x16x32_bf16(Bt[n][k], At[m][k], acc[ai][bj][m][n], 0, 0, 0); __builtin_amdgcn_s_setprio(0); } while (0)
; #define PG8_WAIT_V(n) asm volatile("s_waitcnt vmcnt(" #n ")" ::: "memory")
; #define PG8_WAIT_L(n) asm volatile("s_waitcnt lgkmcnt(" #n ")" ::: "memory")
; #define PG8_BAR __builtin_amdgcn_s_barrier()
; #define PG8_SCHED __builtin_amdgcn_sched_barrier(0)
; template <class Epi, class Sched, bool ALIGN_EPI = false, bool SP2 = false>
; __device__ __forceinline__ void gemm_phase(PG8_LAS unsigned char* lds, const Gemm g, const Sched& S, const Epi& E) {
;     ...
;             PG8_LDB(B0, 1, 0); PG8_LDB(B1, 1, 1); PG8_SCHED; PG8_LDA(At, 1, 0); PG8_STAGE(PG8_SA(0, 1), a2 + hstep, voffA);
;             PG8_WAIT_V(8); PG8_WAIT_L(0); PG8_BAR; PG8_MMA(0, 0, At, B0); PG8_MMA(0, 1, At, B1); PG8_BAR; PG8_SCHED;
	s_add_i32 s78, 0, 0x18000
	v_add_u32_e32 v140, s78, v147
	s_add_i32 s79, 0, 0x1c000
	ds_read_b128 v[128:131], v140
	ds_read_b128 v[160:163], v140 offset:1024
	ds_read_b128 v[164:167], v140 offset:2048
	ds_read_b128 v[168:171], v140 offset:3072
	v_add_u32_e32 v140, s79, v147
	ds_read_b128 v[172:175], v140
	ds_read_b128 v[176:179], v140 offset:1024
	ds_read_b128 v[182:185], v140 offset:2048
	ds_read_b128 v[186:189], v140 offset:3072
	s_add_u32 s64, s64, 0x40000
	s_addc_u32 s65, s65, 0
	s_mov_b32 m0, s34
	v_lshl_add_u64 v[240:241], s[64:65], 0, v[132:133]
	ds_read_b128 v[190:193], v208 offset:32768
	ds_read_b128 v[194:197], v208 offset:33792
	ds_read_b128 v[198:201], v208 offset:34816
	ds_read_b128 v[212:215], v208 offset:35840
	ds_read_b128 v[216:219], v208 offset:36864
	ds_read_b128 v[220:223], v208 offset:37888
	ds_read_b128 v[224:227], v208 offset:38912
	ds_read_b128 v[228:231], v208 offset:39936
	global_load_lds_dwordx4 v[240:241], off
	v_lshl_add_u64 v[240:241], s[64:65], 0, v[136:137]
	s_mov_b32 m0, s57
	s_nop 0
	global_load_lds_dwordx4 v[240:241], off
	s_waitcnt vmcnt(8)
	s_waitcnt lgkmcnt(0)
	s_barrier
	s_setprio 1
	s_waitcnt lgkmcnt(0)
	v_mfma_f32_16x16x32_bf16 v[124:127], v[128:131], v[190:193], v[124:127]
	v_mfma_f32_16x16x32_bf16 v[120:123], v[164:167], v[190:193], v[120:123]
	v_mfma_f32_16x16x32_bf16 v[60:63], v[172:175], v[190:193], v[60:63]
	v_mfma_f32_16x16x32_bf16 v[56:59], v[182:185], v[190:193], v[56:59]
	v_mfma_f32_16x16x32_bf16 v[116:119], v[128:131], v[198:201], v[116:119]
	v_mfma_f32_16x16x32_bf16 v[112:115], v[164:167], v[198:201], v[112:115]
	v_mfma_f32_16x16x32_bf16 v[52:55], v[172:175], v[198:201], v[52:55]
	v_mfma_f32_16x16x32_bf16 v[48:51], v[182:185], v[198:201], v[48:51]
	v_mfma_f32_16x16x32_bf16 v[108:111], v[128:131], v[216:219], v[108:111]
	v_mfma_f32_16x16x32_bf16 v[104:107], v[164:167], v[216:219], v[104:107]
	v_mfma_f32_16x16x32_bf16 v[44:47], v[172:175], v[216:219], v[44:47]
	v_mfma_f32_16x16x32_bf16 v[40:43], v[182:185], v[216:219], v[40:43]
	v_mfma_f32_16x16x32_bf16 v[100:103], v[128:131], v[224:227], v[100:103]
	v_mfma_f32_16x16x32_bf16 v[96:99], v[164:167], v[224:227], v[96:99]
	v_mfma_f32_16x16x32_bf16 v[36:39], v[172:175], v[224:227], v[36:39]
	v_mfma_f32_16x16x32_bf16 v[32:35], v[182:185], v[224:227], v[32:35]
	s_setprio 0
	s_setprio 1
	v_mfma_f32_16x16x32_bf16 v[124:127], v[160:163], v[194:197], v[124:127]
	v_mfma_f32_16x16x32_bf16 v[120:123], v[168:171], v[194:197], v[120:123]
	v_mfma_f32_16x16x32_bf16 v[60:63], v[176:179], v[194:197], v[60:63]
	v_mfma_f32_16x16x32_bf16 v[56:59], v[186:189], v[194:197], v[56:59]
	v_mfma_f32_16x16x32_bf16 v[116:119], v[160:163], v[212:215], v[116:119]
	v_mfma_f32_16x16x32_bf16 v[112:115], v[168:171], v[212:215], v[112:115]
	v_mfma_f32_16x16x32_bf16 v[52:55], v[176:179], v[212:215], v[52:55]
	v_mfma_f32_16x16x32_bf16 v[48:51], v[186:189], v[212:215], v[48:51]
	v_mfma_f32_16x16x32_bf16 v[108:111], v[160:163], v[220:223], v[108:111]
	v_mfma_f32_16x16x32_bf16 v[104:107], v[168:171], v[220:223], v[104:107]
	v_mfma_f32_16x16x32_bf16 v[44:47], v[176:179], v[220:223], v[44:47]
	v_mfma_f32_16x16x32_bf16 v[40:43], v[186:189], v[220:223], v[40:43]
	v_mfma_f32_16x16x32_bf16 v[100:103], v[160:163], v[228:231], v[100:103]
	v_mfma_f32_16x16x32_bf16 v[96:99], v[168:171], v[228:231], v[96:99]
	v_mfma_f32_16x16x32_bf16 v[36:39], v[176:179], v[228:231], v[36:39]
	v_mfma_f32_16x16x32_bf16 v[32:35], v[186:189], v[228:231], v[32:35]
	s_setprio 0
	s_barrier
; #define PG8_STAGE(bufoff, gbase, voff) do { _Pragma("unroll") for (int _i = 0; _i < 2; ++_i) \
;         __builtin_amdgcn_global_load_lds((const unsigned*)((const char*)(gbase) + (voff)[_i]), (PG8_LAS unsigned*)(lds + (bufoff) + ldsw + _i * 8192), 16, 0, 0); } while (0)
; #define PG8_LDA(dst, b, h) do { _Pragma("unroll") for (int m = 0; m < 4; ++m) _Pragma("unroll") for (int k = 0; k < 2; ++k) dst[m][k] = *(const PG8_LAS bf16x8*)(lds + PG8_SA(b, h) + aoff + m * 2048 + k * 1024); } while (0)
; #define PG8_MMA(ai, bj, At, Bt) do { __builtin_amdgcn_s_setprio(1); _Pragma("unroll") for (int m = 0; m < 4; ++m) _Pragma("unroll") for (int n = 0; n < 2; ++n) _Pragma("unroll") for (int k = 0; k < 2; ++k) \
;         acc[ai][bj][m][n] = __builtin_amdgcn_mfma_f32_16x16x32_bf16(Bt[n][k], At[m][k], acc[ai][bj][m][n], 0, 0, 0); __builtin_amdgcn_s_setprio(0); } while (0)
; #define PG8_WAIT_V(n) asm volatile("s_waitcnt vmcnt(" #n ")" ::: "memory")
; #define PG8_WAIT_L(n) asm volatile("s_waitcnt lgkmcnt(" #n ")" ::: "memory")
; #define PG8_BAR __builtin_amdgcn_s_barrier()
; #define PG8_SCHED __builtin_amdgcn_sched_barrier(0)
; template <class Epi, class Sched, bool ALIGN_EPI = false, bool SP2 = false>
; __device__ __forceinline__ void gemm_phase(PG8_LAS unsigned char* lds, const Gemm g, const Sched& S, const Epi& E) {
;     ...
;             PG8_LDA(At, 1, 1); PG8_STAGE(PG8_SB(1, 0), b3, voffB); PG8_STAGE(PG8_SB(1, 1), b3 + hstep, voffB); PG8_STAGE(PG8_SA(1, 0), a3, voffA);
;             PG8_WAIT_V(8); PG8_WAIT_L(0); PG8_BAR; PG8_MMA(1, 0, At, B0); PG8_MMA(1, 1, At, B1); PG8_BAR; PG8_SCHED;
;     ...
;         }
;         if constexpr (ALIGN_EPI) { if (wr == 0) PG8_BAR; }
	s_add_i32 s64, s78, s14
	v_lshl_add_u64 v[232:233], v[232:233], 0, s[42:43]
	s_mov_b32 m0, s64
	ds_read_b128 v[190:193], v208 offset:49152
	ds_read_b128 v[194:197], v208 offset:50176
	ds_read_b128 v[198:201], v208 offset:51200
	ds_read_b128 v[212:215], v208 offset:52224
	ds_read_b128 v[216:219], v208 offset:53248
	ds_read_b128 v[220:223], v208 offset:54272
	ds_read_b128 v[224:227], v208 offset:55296
	ds_read_b128 v[228:231], v208 offset:56320
	global_load_lds_dwordx4 v[232:233], off
	s_add_i32 m0, s64, 0x2000
	s_add_u32 s62, s62, 0x40080
	v_lshl_add_u64 v[232:233], v[234:235], 0, s[42:43]
	s_addc_u32 s63, s63, 0
	s_add_i32 s64, s79, s14
	global_load_lds_dwordx4 v[232:233], off
	v_lshl_add_u64 v[232:233], s[62:63], 0, v[134:135]
	s_mov_b32 m0, s64
	s_nop 0
	global_load_lds_dwordx4 v[232:233], off
	v_lshl_add_u64 v[232:233], s[62:63], 0, v[138:139]
	s_add_i32 m0, s64, 0x2000
	s_nop 0
	global_load_lds_dwordx4 v[232:233], off
	s_waitcnt vmcnt(6)
	s_waitcnt lgkmcnt(0)
	s_barrier
	s_setprio 1
	s_waitcnt lgkmcnt(0)
	v_mfma_f32_16x16x32_bf16 v[92:95], v[128:131], v[190:193], v[92:95]
	v_mfma_f32_16x16x32_bf16 v[88:91], v[164:167], v[190:193], v[88:91]
	v_mfma_f32_16x16x32_bf16 v[28:31], v[172:175], v[190:193], v[28:31]
	v_mfma_f32_16x16x32_bf16 v[24:27], v[182:185], v[190:193], v[24:27]
	v_mfma_f32_16x16x32_bf16 v[84:87], v[128:131], v[198:201], v[84:87]
	v_mfma_f32_16x16x32_bf16 v[80:83], v[164:167], v[198:201], v[80:83]
	v_mfma_f32_16x16x32_bf16 v[20:23], v[172:175], v[198:201], v[20:23]
	v_mfma_f32_16x16x32_bf16 v[16:19], v[182:185], v[198:201], v[16:19]
	v_mfma_f32_16x16x32_bf16 v[76:79], v[128:131], v[216:219], v[76:79]
	v_mfma_f32_16x16x32_bf16 v[72:75], v[164:167], v[216:219], v[72:75]
	v_mfma_f32_16x16x32_bf16 v[12:15], v[172:175], v[216:219], v[12:15]
	v_mfma_f32_16x16x32_bf16 v[8:11], v[182:185], v[216:219], v[8:11]
	v_mfma_f32_16x16x32_bf16 v[68:71], v[128:131], v[224:227], v[68:71]
	v_mfma_f32_16x16x32_bf16 v[64:67], v[164:167], v[224:227], v[64:67]
	v_lshl_add_u64 v[232:233], v[236:237], 0, s[42:43]
	s_mov_b32 m0, s67
	s_nop 0
	global_load_lds_dwordx4 v[232:233], off
	v_mfma_f32_16x16x32_bf16 v[4:7], v[172:175], v[224:227], v[4:7]
	v_mfma_f32_16x16x32_bf16 v[0:3], v[182:185], v[224:227], v[0:3]
	s_setprio 0
	s_setprio 1
	v_mfma_f32_16x16x32_bf16 v[92:95], v[160:163], v[194:197], v[92:95]
	v_mfma_f32_16x16x32_bf16 v[88:91], v[168:171], v[194:197], v[88:91]
	v_mfma_f32_16x16x32_bf16 v[28:31], v[176:179], v[194:197], v[28:31]
	v_mfma_f32_16x16x32_bf16 v[24:27], v[186:189], v[194:197], v[24:27]
	v_mfma_f32_16x16x32_bf16 v[84:87], v[160:163], v[212:215], v[84:87]
	v_mfma_f32_16x16x32_bf16 v[80:83], v[168:171], v[212:215], v[80:83]
	v_mfma_f32_16x16x32_bf16 v[20:23], v[176:179], v[212:215], v[20:23]
	v_mfma_f32_16x16x32_bf16 v[16:19], v[186:189], v[212:215], v[16:19]
	v_mfma_f32_16x16x32_bf16 v[76:79], v[160:163], v[220:223], v[76:79]
	v_mfma_f32_16x16x32_bf16 v[72:75], v[168:171], v[220:223], v[72:75]
	v_mfma_f32_16x16x32_bf16 v[12:15], v[176:179], v[220:223], v[12:15]
	v_mfma_f32_16x16x32_bf16 v[8:11], v[186:189], v[220:223], v[8:11]
	v_mfma_f32_16x16x32_bf16 v[68:71], v[160:163], v[228:231], v[68:71]
	v_mfma_f32_16x16x32_bf16 v[64:67], v[168:171], v[228:231], v[64:67]
	v_lshl_add_u64 v[232:233], v[238:239], 0, s[42:43]
	s_mov_b32 m0, s74
	s_nop 0
	global_load_lds_dwordx4 v[232:233], off
	v_mfma_f32_16x16x32_bf16 v[4:7], v[176:179], v[228:231], v[4:7]
	v_mfma_f32_16x16x32_bf16 v[0:3], v[186:189], v[228:231], v[0:3]
	s_setprio 0
	s_barrier
	s_add_i32 s90, s90, 2
	s_add_u32 s58, s58, 0x100
	s_addc_u32 s59, s59, 0
	s_add_u32 s88, s88, 0x100
	s_addc_u32 s89, s89, 0
	s_cmp_gt_u32 s90, 13
	s_cbranch_scc0 .LBB0_1287
	s_and_b64 vcc, exec, s[44:45]
	s_cbranch_vccz .LBB0_1290
	s_barrier

; #define PG8_STAGE(bufoff, gbase, voff) do { _Pragma("unroll") for (int _i = 0; _i < 2; ++_i) \
;         __builtin_amdgcn_global_load_lds((const unsigned*)((const char*)(gbase) + (voff)[_i]), (PG8_LAS unsigned*)(lds + (bufoff) + ldsw + _i * 8192), 16, 0, 0); } while (0)
; #define PG8_LDA(dst, b, h) do { _Pragma("unroll") for (int m = 0; m < 4; ++m) _Pragma("unroll") for (int k = 0; k < 2; ++k) dst[m][k] = *(const PG8_LAS bf16x8*)(lds + PG8_SA(b, h) + aoff + m * 2048 + k * 1024); } while (0)
; #define PG8_LDB(dst, b, h) do { _Pragma("unroll") for (int n = 0; n < 2; ++n) _Pragma("unroll") for (int k = 0; k < 2; ++k) dst[n][k] = *(const PG8_LAS bf16x8*)(lds + PG8_SB(b, h) + boff + n * 2048 + k * 1024); } while (0)
; #define PG8_WAIT_V(n) asm volatile("s_waitcnt vmcnt(" #n ")" ::: "memory")
; #define PG8_WAIT_L(n) asm volatile("s_waitcnt lgkmcnt(" #n ")" ::: "memory")
; #define PG8_BAR __builtin_amdgcn_s_barrier()
; #define PG8_SCHED __builtin_amdgcn_sched_barrier(0)
; template <class Epi, class Sched, bool ALIGN_EPI = false, bool SP2 = false>
; __device__ __forceinline__ void gemm_phase(PG8_LAS unsigned char* lds, const Gemm g, const Sched& S, const Epi& E) {
;     ...
;         const bool has_next = S.next(ui + 1, nxt);
;         const char* nA = has_next ? (const char*)g.A + (size_t)nxt.pm * tstep : cA; const char* nB = has_next ? (const char*)g.Bt + (size_t)nxt.pn * tstep : cB;
;         for (int t = 0; t < nt; t += 2) {
;             const bool last = (t == nt - 2);
;             const char* a1 = cA + (size_t)(t + 1) * kstep;
;             const char* a2 = last ? nA : cA + (size_t)(t + 2) * kstep; const char* b2 = last ? nB : cB + (size_t)(t + 2) * kstep;
;             const char* a3 = a2 + kstep; const char* b3 = b2 + kstep;
;             if (last && has_next) S.a_ready(nxt);
;             if constexpr (SP2) {
;             PG8_LDB(B0, 0, 0); PG8_LDB(B1, 0, 1); PG8_SCHED; PG8_LDA(At, 0, 0); PG8_STAGE(PG8_SA(1, 1), a1 + hstep, voffA);
;             PG8_WAIT_V(8); PG8_WAIT_L(0); PG8_BAR; PG8_MMA(0, 0, At, B0); PG8_MMA(0, 1, At, B1); PG8_BAR; PG8_SCHED;
;             PG8_LDA(At, 0, 1); PG8_STAGE(PG8_SB(0, 0), b2, voffB); PG8_STAGE(PG8_SB(0, 1), b2 + hstep, voffB); PG8_STAGE(PG8_SA(0, 0), a2, voffA);
;             PG8_WAIT_V(8); PG8_WAIT_L(0); PG8_BAR; PG8_MMA(1, 0, At, B0); PG8_MMA(1, 1, At, B1); PG8_BAR; PG8_SCHED;
.LBB0_1592:
	s_ashr_i32 s39, s38, 31
	s_lshl_b64 s[42:43], s[38:39], 19
	s_add_u32 s42, s40, s42
	s_addc_u32 s43, s41, s43
	s_and_b64 s[44:45], s[10:11], exec
	s_cselect_b32 s39, s43, s51
	s_cselect_b32 s47, s42, s50
	s_ashr_i32 s37, s36, 31
	s_lshl_b64 s[44:45], s[36:37], 19
	v_readlane_b32 s54, v250, 11
	v_readlane_b32 s55, v250, 12
	s_add_u32 s44, s54, s44
	s_addc_u32 s45, s55, s45
	s_and_b64 s[54:55], s[10:11], exec
	s_cselect_b32 s37, s45, s53
	s_cselect_b32 s64, s44, s52
	s_add_u32 s50, s50, 0x40080
	s_addc_u32 s51, s51, 0
	s_add_u32 s65, s52, 0x100
	s_addc_u32 s66, s53, 0
	s_mov_b32 s67, -2
	s_waitcnt lgkmcnt(0)
	ds_read_b128 v[146:149], v152
	ds_read_b128 v[156:159], v152 offset:1024
	ds_read_b128 v[160:163], v152 offset:2048
	ds_read_b128 v[164:167], v152 offset:3072
	ds_read_b128 v[168:171], v153
	ds_read_b128 v[172:175], v153 offset:1024
	ds_read_b128 v[180:183], v153 offset:2048
	ds_read_b128 v[184:187], v153 offset:3072
	s_add_u32 s52, s50, 0xfffc0080
	s_addc_u32 s53, s51, -1
	s_cmp_eq_u32 s67, 12
	s_cselect_b32 s55, s39, s53
	s_cselect_b32 s54, s47, s52
	s_cselect_b32 s53, s37, s66
	s_cselect_b32 s52, s64, s65
	v_lshl_add_u64 v[200:201], s[50:51], 0, v[136:137]
	s_add_i32 m0, s33, 0xc000
	ds_read_b128 v[188:191], v154
	ds_read_b128 v[192:195], v154 offset:1024
	ds_read_b128 v[196:199], v154 offset:2048
	ds_read_b128 v[206:209], v154 offset:3072
	ds_read_b128 v[210:213], v154 offset:4096
	ds_read_b128 v[214:217], v154 offset:5120
	ds_read_b128 v[218:221], v154 offset:6144
	ds_read_b128 v[222:225], v154 offset:7168
	global_load_lds_dwordx4 v[200:201], off
	v_lshl_add_u64 v[200:201], s[50:51], 0, v[138:139]
	s_add_i32 m0, s33, 0xe000
	s_nop 0
	global_load_lds_dwordx4 v[200:201], off
	s_waitcnt vmcnt(8)
	s_waitcnt lgkmcnt(0)
	s_barrier
	s_setprio 1
	s_waitcnt lgkmcnt(0)
	v_mfma_f32_16x16x32_bf16 v[124:127], v[146:149], v[188:191], 0
	v_mfma_f32_16x16x32_bf16 v[120:123], v[160:163], v[188:191], 0
	v_mfma_f32_16x16x32_bf16 v[116:119], v[168:171], v[188:191], 0
	v_mfma_f32_16x16x32_bf16 v[112:115], v[180:183], v[188:191], 0
	v_mfma_f32_16x16x32_bf16 v[108:111], v[146:149], v[196:199], 0
	v_mfma_f32_16x16x32_bf16 v[104:107], v[160:163], v[196:199], 0
	v_mfma_f32_16x16x32_bf16 v[100:103], v[168:171], v[196:199], 0
	v_mfma_f32_16x16x32_bf16 v[96:99], v[180:183], v[196:199], 0
	v_mfma_f32_16x16x32_bf16 v[92:95], v[146:149], v[210:213], 0
	v_mfma_f32_16x16x32_bf16 v[88:91], v[160:163], v[210:213], 0
	v_mfma_f32_16x16x32_bf16 v[84:87], v[168:171], v[210:213], 0
	v_mfma_f32_16x16x32_bf16 v[80:83], v[180:183], v[210:213], 0
	v_mfma_f32_16x16x32_bf16 v[76:79], v[146:149], v[218:221], 0
	v_mfma_f32_16x16x32_bf16 v[72:75], v[160:163], v[218:221], 0
	v_mfma_f32_16x16x32_bf16 v[68:71], v[168:171], v[218:221], 0
	v_mfma_f32_16x16x32_bf16 v[64:67], v[180:183], v[218:221], 0
	s_setprio 0
	s_setprio 1
	v_mfma_f32_16x16x32_bf16 v[124:127], v[156:159], v[192:195], v[124:127]
	v_mfma_f32_16x16x32_bf16 v[120:123], v[164:167], v[192:195], v[120:123]
	v_mfma_f32_16x16x32_bf16 v[116:119], v[172:175], v[192:195], v[116:119]
	v_mfma_f32_16x16x32_bf16 v[112:115], v[184:187], v[192:195], v[112:115]
	v_mfma_f32_16x16x32_bf16 v[108:111], v[156:159], v[206:209], v[108:111]
	v_mfma_f32_16x16x32_bf16 v[104:107], v[164:167], v[206:209], v[104:107]
	v_mfma_f32_16x16x32_bf16 v[100:103], v[172:175], v[206:209], v[100:103]
	v_mfma_f32_16x16x32_bf16 v[96:99], v[184:187], v[206:209], v[96:99]
	v_mfma_f32_16x16x32_bf16 v[92:95], v[156:159], v[214:217], v[92:95]
	v_mfma_f32_16x16x32_bf16 v[88:91], v[164:167], v[214:217], v[88:91]
	v_mfma_f32_16x16x32_bf16 v[84:87], v[172:175], v[214:217], v[84:87]
	v_mfma_f32_16x16x32_bf16 v[80:83], v[184:187], v[214:217], v[80:83]
	v_mfma_f32_16x16x32_bf16 v[76:79], v[156:159], v[222:225], v[76:79]
	v_mfma_f32_16x16x32_bf16 v[72:75], v[164:167], v[222:225], v[72:75]
	v_mfma_f32_16x16x32_bf16 v[68:71], v[172:175], v[222:225], v[68:71]
	v_mfma_f32_16x16x32_bf16 v[64:67], v[184:187], v[222:225], v[64:67]
	s_setprio 0
	s_barrier
	s_add_i32 s74, s60, s15
	v_lshl_add_u64 v[200:201], s[52:53], 0, v[130:131]
	s_mov_b32 m0, s74
	ds_read_b128 v[188:191], v154 offset:16384
	ds_read_b128 v[192:195], v154 offset:17408
	ds_read_b128 v[196:199], v154 offset:18432
	ds_read_b128 v[206:209], v154 offset:19456
	ds_read_b128 v[210:213], v154 offset:20480
	ds_read_b128 v[214:217], v154 offset:21504
	ds_read_b128 v[218:221], v154 offset:22528
	ds_read_b128 v[222:225], v154 offset:23552
	global_load_lds_dwordx4 v[200:201], off
	s_add_i32 m0, s74, 0x2000
	s_add_u32 s74, s52, 0x40000
	v_lshl_add_u64 v[226:227], s[52:53], 0, v[134:135]
	s_addc_u32 s75, s53, 0
	s_add_i32 s76, s61, s15
	global_load_lds_dwordx4 v[226:227], off
	v_lshl_add_u64 v[228:229], s[74:75], 0, v[130:131]
	s_mov_b32 m0, s76
	global_load_lds_dwordx4 v[228:229], off
	v_lshl_add_u64 v[228:229], s[74:75], 0, v[134:135]
	s_add_i32 m0, s76, 0x2000
	s_nop 0
	global_load_lds_dwordx4 v[228:229], off
	s_waitcnt vmcnt(6)
	s_waitcnt lgkmcnt(0)
	s_barrier
; #define PG8_STAGE(bufoff, gbase, voff) do { _Pragma("unroll") for (int _i = 0; _i < 2; ++_i) \
;         __builtin_amdgcn_global_load_lds((const unsigned*)((const char*)(gbase) + (voff)[_i]), (PG8_LAS unsigned*)(lds + (bufoff) + ldsw + _i * 8192), 16, 0, 0); } while (0)
; #define PG8_LDA(dst, b, h) do { _Pragma("unroll") for (int m = 0; m < 4; ++m) _Pragma("unroll") for (int k = 0; k < 2; ++k) dst[m][k] = *(const PG8_LAS bf16x8*)(lds + PG8_SA(b, h) + aoff + m * 2048 + k * 1024); } while (0)
; #define PG8_LDB(dst, b, h) do { _Pragma("unroll") for (int n = 0; n < 2; ++n) _Pragma("unroll") for (int k = 0; k < 2; ++k) dst[n][k] = *(const PG8_LAS bf16x8*)(lds + PG8_SB(b, h) + boff + n * 2048 + k * 1024); } while (0)
; #define PG8_MMA(ai, bj, At, Bt) do { __builtin_amdgcn_s_setprio(1); _Pragma("unroll") for (int m = 0; m < 4; ++m) _Pragma("unroll") for (int n = 0; n < 2; ++n) _Pragma("unroll") for (int k = 0; k < 2; ++k) \
;         acc[ai][bj][m][n] = __builtin_amdgcn_mfma_f32_16x16x32_bf16(Bt[n][k], At[m][k], acc[ai][bj][m][n], 0, 0, 0); __builtin_amdgcn_s_setprio(0); } while (0)
; #define PG8_WAIT_V(n) asm volatile("s_waitcnt vmcnt(" #n ")" ::: "memory")
; #define PG8_WAIT_L(n) asm volatile("s_waitcnt lgkmcnt(" #n ")" ::: "memory")
; #define PG8_BAR __builtin_amdgcn_s_barrier()
; #define PG8_SCHED __builtin_amdgcn_sched_barrier(0)
; template <class Epi, class Sched, bool ALIGN_EPI = false, bool SP2 = false>
; __device__ __forceinline__ void gemm_phase(PG8_LAS unsigned char* lds, const Gemm g, const Sched& S, const Epi& E) {
;     ...
;             PG8_WAIT_V(8); PG8_WAIT_L(0); PG8_BAR; PG8_MMA(1, 0, At, B0); PG8_MMA(1, 1, At, B1); PG8_BAR; PG8_SCHED;
;             PG8_LDB(B0, 1, 0); PG8_LDB(B1, 1, 1); PG8_SCHED; PG8_LDA(At, 1, 0); PG8_STAGE(PG8_SA(0, 1), a2 + hstep, voffA);
;             PG8_WAIT_V(8); PG8_WAIT_L(0); PG8_BAR; PG8_MMA(0, 0, At, B0); PG8_MMA(0, 1, At, B1); PG8_BAR; PG8_SCHED;
	s_setprio 1
	s_waitcnt lgkmcnt(0)
	v_mfma_f32_16x16x32_bf16 v[60:63], v[146:149], v[188:191], 0
	v_mfma_f32_16x16x32_bf16 v[56:59], v[160:163], v[188:191], 0
	v_mfma_f32_16x16x32_bf16 v[52:55], v[168:171], v[188:191], 0
	v_mfma_f32_16x16x32_bf16 v[48:51], v[180:183], v[188:191], 0
	v_mfma_f32_16x16x32_bf16 v[44:47], v[146:149], v[196:199], 0
	v_mfma_f32_16x16x32_bf16 v[40:43], v[160:163], v[196:199], 0
	v_mfma_f32_16x16x32_bf16 v[36:39], v[168:171], v[196:199], 0
	v_mfma_f32_16x16x32_bf16 v[32:35], v[180:183], v[196:199], 0
	v_mfma_f32_16x16x32_bf16 v[28:31], v[146:149], v[210:213], 0
	v_mfma_f32_16x16x32_bf16 v[24:27], v[160:163], v[210:213], 0
	v_mfma_f32_16x16x32_bf16 v[20:23], v[168:171], v[210:213], 0
	v_mfma_f32_16x16x32_bf16 v[16:19], v[180:183], v[210:213], 0
	v_mfma_f32_16x16x32_bf16 v[12:15], v[146:149], v[218:221], 0
	v_mfma_f32_16x16x32_bf16 v[8:11], v[160:163], v[218:221], 0
	v_lshl_add_u64 v[228:229], s[54:55], 0, v[128:129]
	s_mov_b32 m0, s33
	s_nop 0
	global_load_lds_dwordx4 v[228:229], off
	v_mfma_f32_16x16x32_bf16 v[4:7], v[168:171], v[218:221], 0
	v_mfma_f32_16x16x32_bf16 v[0:3], v[180:183], v[218:221], 0
	s_setprio 0
	s_setprio 1
	v_mfma_f32_16x16x32_bf16 v[60:63], v[156:159], v[192:195], v[60:63]
	v_mfma_f32_16x16x32_bf16 v[56:59], v[164:167], v[192:195], v[56:59]
	v_mfma_f32_16x16x32_bf16 v[52:55], v[172:175], v[192:195], v[52:55]
	v_mfma_f32_16x16x32_bf16 v[48:51], v[184:187], v[192:195], v[48:51]
	v_mfma_f32_16x16x32_bf16 v[44:47], v[156:159], v[206:209], v[44:47]
	v_mfma_f32_16x16x32_bf16 v[40:43], v[164:167], v[206:209], v[40:43]
	v_mfma_f32_16x16x32_bf16 v[36:39], v[172:175], v[206:209], v[36:39]
	v_mfma_f32_16x16x32_bf16 v[32:35], v[184:187], v[206:209], v[32:35]
	v_mfma_f32_16x16x32_bf16 v[28:31], v[156:159], v[214:217], v[28:31]
	v_mfma_f32_16x16x32_bf16 v[24:27], v[164:167], v[214:217], v[24:27]
	v_mfma_f32_16x16x32_bf16 v[20:23], v[172:175], v[214:217], v[20:23]
	v_mfma_f32_16x16x32_bf16 v[16:19], v[184:187], v[214:217], v[16:19]
	v_mfma_f32_16x16x32_bf16 v[12:15], v[156:159], v[222:225], v[12:15]
	v_mfma_f32_16x16x32_bf16 v[8:11], v[164:167], v[222:225], v[8:11]
	v_lshl_add_u64 v[230:231], s[54:55], 0, v[132:133]
	s_mov_b32 m0, s34
	s_nop 0
	global_load_lds_dwordx4 v[230:231], off
	v_mfma_f32_16x16x32_bf16 v[4:7], v[172:175], v[222:225], v[4:7]
	v_mfma_f32_16x16x32_bf16 v[0:3], v[184:187], v[222:225], v[0:3]
	s_setprio 0
	s_barrier
	s_add_i32 s74, 0, 0x18000
	s_add_i32 s75, 0, 0x1c000
	v_add_u32_e32 v164, s74, v150
	v_add_u32_e32 v179, s75, v150
	ds_read_b128 v[146:149], v164
	ds_read_b128 v[156:159], v164 offset:1024
	ds_read_b128 v[160:163], v164 offset:2048
	ds_read_b128 v[164:167], v164 offset:3072
	ds_read_b128 v[168:171], v179
	ds_read_b128 v[172:175], v179 offset:1024
	ds_read_b128 v[180:183], v179 offset:2048
	ds_read_b128 v[184:187], v179 offset:3072
	s_add_u32 s54, s54, 0x40000
	s_addc_u32 s55, s55, 0
	s_mov_b32 m0, s49
	v_lshl_add_u64 v[232:233], s[54:55], 0, v[128:129]
	ds_read_b128 v[188:191], v154 offset:32768
	ds_read_b128 v[192:195], v154 offset:33792
	ds_read_b128 v[196:199], v154 offset:34816
	ds_read_b128 v[206:209], v154 offset:35840
	ds_read_b128 v[210:213], v154 offset:36864
	ds_read_b128 v[214:217], v154 offset:37888
	ds_read_b128 v[218:221], v154 offset:38912
	ds_read_b128 v[222:225], v154 offset:39936
	global_load_lds_dwordx4 v[232:233], off
	v_lshl_add_u64 v[232:233], s[54:55], 0, v[132:133]
	s_mov_b32 m0, s56
	s_nop 0
	global_load_lds_dwordx4 v[232:233], off
	s_waitcnt vmcnt(8)
	s_waitcnt lgkmcnt(0)
	s_barrier
	s_setprio 1
	s_waitcnt lgkmcnt(0)
	v_mfma_f32_16x16x32_bf16 v[124:127], v[146:149], v[188:191], v[124:127]
	v_mfma_f32_16x16x32_bf16 v[120:123], v[160:163], v[188:191], v[120:123]
	v_mfma_f32_16x16x32_bf16 v[116:119], v[168:171], v[188:191], v[116:119]
	v_mfma_f32_16x16x32_bf16 v[112:115], v[180:183], v[188:191], v[112:115]
	v_mfma_f32_16x16x32_bf16 v[108:111], v[146:149], v[196:199], v[108:111]
	v_mfma_f32_16x16x32_bf16 v[104:107], v[160:163], v[196:199], v[104:107]
	v_mfma_f32_16x16x32_bf16 v[100:103], v[168:171], v[196:199], v[100:103]
	v_mfma_f32_16x16x32_bf16 v[96:99], v[180:183], v[196:199], v[96:99]
	v_mfma_f32_16x16x32_bf16 v[92:95], v[146:149], v[210:213], v[92:95]
	v_mfma_f32_16x16x32_bf16 v[88:91], v[160:163], v[210:213], v[88:91]
	v_mfma_f32_16x16x32_bf16 v[84:87], v[168:171], v[210:213], v[84:87]
	v_mfma_f32_16x16x32_bf16 v[80:83], v[180:183], v[210:213], v[80:83]
	v_mfma_f32_16x16x32_bf16 v[76:79], v[146:149], v[218:221], v[76:79]
	v_mfma_f32_16x16x32_bf16 v[72:75], v[160:163], v[218:221], v[72:75]
	v_mfma_f32_16x16x32_bf16 v[68:71], v[168:171], v[218:221], v[68:71]
	v_mfma_f32_16x16x32_bf16 v[64:67], v[180:183], v[218:221], v[64:67]
	s_setprio 0
	s_setprio 1
	v_mfma_f32_16x16x32_bf16 v[124:127], v[156:159], v[192:195], v[124:127]
	v_mfma_f32_16x16x32_bf16 v[120:123], v[164:167], v[192:195], v[120:123]
	v_mfma_f32_16x16x32_bf16 v[116:119], v[172:175], v[192:195], v[116:119]
	v_mfma_f32_16x16x32_bf16 v[112:115], v[184:187], v[192:195], v[112:115]
	v_mfma_f32_16x16x32_bf16 v[108:111], v[156:159], v[206:209], v[108:111]
	v_mfma_f32_16x16x32_bf16 v[104:107], v[164:167], v[206:209], v[104:107]
	v_mfma_f32_16x16x32_bf16 v[100:103], v[172:175], v[206:209], v[100:103]
	v_mfma_f32_16x16x32_bf16 v[96:99], v[184:187], v[206:209], v[96:99]
	v_mfma_f32_16x16x32_bf16 v[92:95], v[156:159], v[214:217], v[92:95]
	v_mfma_f32_16x16x32_bf16 v[88:91], v[164:167], v[214:217], v[88:91]
	v_mfma_f32_16x16x32_bf16 v[84:87], v[172:175], v[214:217], v[84:87]
	v_mfma_f32_16x16x32_bf16 v[80:83], v[184:187], v[214:217], v[80:83]
	v_mfma_f32_16x16x32_bf16 v[76:79], v[156:159], v[222:225], v[76:79]
	v_mfma_f32_16x16x32_bf16 v[72:75], v[164:167], v[222:225], v[72:75]
	v_mfma_f32_16x16x32_bf16 v[68:71], v[172:175], v[222:225], v[68:71]
	v_mfma_f32_16x16x32_bf16 v[64:67], v[184:187], v[222:225], v[64:67]
	s_setprio 0
	s_barrier
; #define PG8_STAGE(bufoff, gbase, voff) do { _Pragma("unroll") for (int _i = 0; _i < 2; ++_i) \
;         __builtin_amdgcn_global_load_lds((const unsigned*)((const char*)(gbase) + (voff)[_i]), (PG8_LAS unsigned*)(lds + (bufoff) + ldsw + _i * 8192), 16, 0, 0); } while (0)
; #define PG8_LDA(dst, b, h) do { _Pragma("unroll") for (int m = 0; m < 4; ++m) _Pragma("unroll") for (int k = 0; k < 2; ++k) dst[m][k] = *(const PG8_LAS bf16x8*)(lds + PG8_SA(b, h) + aoff + m * 2048 + k * 1024); } while (0)
; #define PG8_LDB(dst, b, h) do { _Pragma("unroll") for (int n = 0; n < 2; ++n) _Pragma("unroll") for (int k = 0; k < 2; ++k) dst[n][k] = *(const PG8_LAS bf16x8*)(lds + PG8_SB(b, h) + boff + n * 2048 + k * 1024); } while (0)
; #define PG8_MMA(ai, bj, At, Bt) do { __builtin_amdgcn_s_setprio(1); _Pragma("unroll") for (int m = 0; m < 4; ++m) _Pragma("unroll") for (int n = 0; n < 2; ++n) _Pragma("unroll") for (int k = 0; k < 2; ++k) \
;         acc[ai][bj][m][n] = __builtin_amdgcn_mfma_f32_16x16x32_bf16(Bt[n][k], At[m][k], acc[ai][bj][m][n], 0, 0, 0); __builtin_amdgcn_s_setprio(0); } while (0)
; #define PG8_WAIT_V(n) asm volatile("s_waitcnt vmcnt(" #n ")" ::: "memory")
; #define PG8_BAR __builtin_amdgcn_s_barrier()
; template <class Epi, class Sched, bool ALIGN_EPI = false, bool SP2 = false>
; __device__ __forceinline__ void gemm_phase(PG8_LAS unsigned char* lds, const Gemm g, const Sched& S, const Epi& E) {
;     ...
;         for (int t = 0; t < nt; t += 2) {
;             const bool last = (t == nt - 2);
;             const char* a1 = cA + (size_t)(t + 1) * kstep;
;             const char* a2 = last ? nA : cA + (size_t)(t + 2) * kstep; const char* b2 = last ? nB : cB + (size_t)(t + 2) * kstep;
;             const char* a3 = a2 + kstep; const char* b3 = b2 + kstep;
;             if (last && has_next) S.a_ready(nxt);
;             if constexpr (SP2) {
;             PG8_LDB(B0, 0, 0); PG8_LDB(B1, 0, 1); PG8_SCHED; PG8_LDA(At, 0, 0); PG8_STAGE(PG8_SA(1, 1), a1 + hstep, voffA);
;             PG8_WAIT_V(8); PG8_WAIT_L(0); PG8_BAR; PG8_MMA(0, 0, At, B0); PG8_MMA(0, 1, At, B1); PG8_BAR; PG8_SCHED;
;     ...
;             PG8_LDA(At, 1, 1); PG8_STAGE(PG8_SB(1, 0), b3, voffB); PG8_STAGE(PG8_SB(1, 1), b3 + hstep, voffB); PG8_STAGE(PG8_SA(1, 0), a3, voffA);
;             PG8_WAIT_V(8); PG8_WAIT_L(0); PG8_BAR; PG8_MMA(1, 0, At, B0); PG8_MMA(1, 1, At, B1); PG8_BAR; PG8_SCHED;
	s_add_i32 s54, s74, s15
	v_lshl_add_u64 v[200:201], v[200:201], 0, s[26:27]
	s_mov_b32 m0, s54
	ds_read_b128 v[188:191], v154 offset:49152
	ds_read_b128 v[192:195], v154 offset:50176
	ds_read_b128 v[196:199], v154 offset:51200
	ds_read_b128 v[206:209], v154 offset:52224
	ds_read_b128 v[210:213], v154 offset:53248
	ds_read_b128 v[214:217], v154 offset:54272
	ds_read_b128 v[218:221], v154 offset:55296
	ds_read_b128 v[222:225], v154 offset:56320
	global_load_lds_dwordx4 v[200:201], off
	s_add_i32 m0, s54, 0x2000
	s_add_u32 s52, s52, 0x40080
	v_lshl_add_u64 v[200:201], v[226:227], 0, s[26:27]
	s_addc_u32 s53, s53, 0
	s_add_i32 s54, s75, s15
	global_load_lds_dwordx4 v[200:201], off
	v_lshl_add_u64 v[200:201], s[52:53], 0, v[130:131]
	s_mov_b32 m0, s54
	s_nop 0
	global_load_lds_dwordx4 v[200:201], off
	v_lshl_add_u64 v[200:201], s[52:53], 0, v[134:135]
	s_add_i32 m0, s54, 0x2000
	s_nop 0
	global_load_lds_dwordx4 v[200:201], off
	s_waitcnt vmcnt(6)
	s_waitcnt lgkmcnt(0)
	s_barrier
	s_setprio 1
	s_waitcnt lgkmcnt(0)
	v_mfma_f32_16x16x32_bf16 v[60:63], v[146:149], v[188:191], v[60:63]
	v_mfma_f32_16x16x32_bf16 v[56:59], v[160:163], v[188:191], v[56:59]
	v_mfma_f32_16x16x32_bf16 v[52:55], v[168:171], v[188:191], v[52:55]
	v_mfma_f32_16x16x32_bf16 v[48:51], v[180:183], v[188:191], v[48:51]
	v_mfma_f32_16x16x32_bf16 v[44:47], v[146:149], v[196:199], v[44:47]
	v_mfma_f32_16x16x32_bf16 v[40:43], v[160:163], v[196:199], v[40:43]
	v_mfma_f32_16x16x32_bf16 v[36:39], v[168:171], v[196:199], v[36:39]
	v_mfma_f32_16x16x32_bf16 v[32:35], v[180:183], v[196:199], v[32:35]
	v_mfma_f32_16x16x32_bf16 v[28:31], v[146:149], v[210:213], v[28:31]
	v_mfma_f32_16x16x32_bf16 v[24:27], v[160:163], v[210:213], v[24:27]
	v_mfma_f32_16x16x32_bf16 v[20:23], v[168:171], v[210:213], v[20:23]
	v_mfma_f32_16x16x32_bf16 v[16:19], v[180:183], v[210:213], v[16:19]
	v_mfma_f32_16x16x32_bf16 v[12:15], v[146:149], v[218:221], v[12:15]
	v_mfma_f32_16x16x32_bf16 v[8:11], v[160:163], v[218:221], v[8:11]
	v_lshl_add_u64 v[200:201], v[228:229], 0, s[26:27]
	s_mov_b32 m0, s58
	s_nop 0
	global_load_lds_dwordx4 v[200:201], off
	v_mfma_f32_16x16x32_bf16 v[4:7], v[168:171], v[218:221], v[4:7]
	v_mfma_f32_16x16x32_bf16 v[0:3], v[180:183], v[218:221], v[0:3]
	s_setprio 0
	s_setprio 1
	v_mfma_f32_16x16x32_bf16 v[60:63], v[156:159], v[192:195], v[60:63]
	v_mfma_f32_16x16x32_bf16 v[56:59], v[164:167], v[192:195], v[56:59]
	v_mfma_f32_16x16x32_bf16 v[52:55], v[172:175], v[192:195], v[52:55]
	v_mfma_f32_16x16x32_bf16 v[48:51], v[184:187], v[192:195], v[48:51]
	v_mfma_f32_16x16x32_bf16 v[44:47], v[156:159], v[206:209], v[44:47]
	v_mfma_f32_16x16x32_bf16 v[40:43], v[164:167], v[206:209], v[40:43]
	v_mfma_f32_16x16x32_bf16 v[36:39], v[172:175], v[206:209], v[36:39]
	v_mfma_f32_16x16x32_bf16 v[32:35], v[184:187], v[206:209], v[32:35]
	v_mfma_f32_16x16x32_bf16 v[28:31], v[156:159], v[214:217], v[28:31]
	v_mfma_f32_16x16x32_bf16 v[24:27], v[164:167], v[214:217], v[24:27]
	v_mfma_f32_16x16x32_bf16 v[20:23], v[172:175], v[214:217], v[20:23]
	v_mfma_f32_16x16x32_bf16 v[16:19], v[184:187], v[214:217], v[16:19]
	v_mfma_f32_16x16x32_bf16 v[12:15], v[156:159], v[222:225], v[12:15]
	v_mfma_f32_16x16x32_bf16 v[8:11], v[164:167], v[222:225], v[8:11]
	v_lshl_add_u64 v[200:201], v[230:231], 0, s[26:27]
	s_mov_b32 m0, s59
	s_nop 0
	global_load_lds_dwordx4 v[200:201], off
	v_mfma_f32_16x16x32_bf16 v[4:7], v[172:175], v[222:225], v[4:7]
	v_mfma_f32_16x16x32_bf16 v[0:3], v[184:187], v[222:225], v[0:3]
	s_setprio 0
	s_barrier
	s_add_i32 s67, s67, 2
	s_add_u32 s50, s50, 0x100
	s_addc_u32 s51, s51, 0
	s_add_u32 s65, s65, 0x100
	s_addc_u32 s66, s66, 0
.LBB0_1593:
	ds_read_b128 v[146:149], v152
	ds_read_b128 v[156:159], v152 offset:1024
	ds_read_b128 v[160:163], v152 offset:2048
	ds_read_b128 v[164:167], v152 offset:3072
	ds_read_b128 v[168:171], v153
	ds_read_b128 v[172:175], v153 offset:1024
	ds_read_b128 v[180:183], v153 offset:2048
	ds_read_b128 v[184:187], v153 offset:3072
	s_add_u32 s52, s50, 0xfffc0080
	s_addc_u32 s53, s51, -1
	s_cmp_eq_u32 s67, 12
	s_cselect_b32 s55, s39, s53
	s_cselect_b32 s54, s47, s52
	s_cselect_b32 s53, s37, s66
	s_cselect_b32 s52, s64, s65
	v_lshl_add_u64 v[200:201], s[50:51], 0, v[136:137]
	s_add_i32 m0, s33, 0xc000
	ds_read_b128 v[188:191], v154
	ds_read_b128 v[192:195], v154 offset:1024
	ds_read_b128 v[196:199], v154 offset:2048
	ds_read_b128 v[206:209], v154 offset:3072
	ds_read_b128 v[210:213], v154 offset:4096
	ds_read_b128 v[214:217], v154 offset:5120
	ds_read_b128 v[218:221], v154 offset:6144
	ds_read_b128 v[222:225], v154 offset:7168
	global_load_lds_dwordx4 v[200:201], off
	v_lshl_add_u64 v[200:201], s[50:51], 0, v[138:139]
	s_add_i32 m0, s33, 0xe000
	s_nop 0
	global_load_lds_dwordx4 v[200:201], off
	s_waitcnt vmcnt(8)
	s_waitcnt lgkmcnt(0)
	s_barrier
; #define PG8_STAGE(bufoff, gbase, voff) do { _Pragma("unroll") for (int _i = 0; _i < 2; ++_i) \
;         __builtin_amdgcn_global_load_lds((const unsigned*)((const char*)(gbase) + (voff)[_i]), (PG8_LAS unsigned*)(lds + (bufoff) + ldsw + _i * 8192), 16, 0, 0); } while (0)
; #define PG8_LDA(dst, b, h) do { _Pragma("unroll") for (int m = 0; m < 4; ++m) _Pragma("unroll") for (int k = 0; k < 2; ++k) dst[m][k] = *(const PG8_LAS bf16x8*)(lds + PG8_SA(b, h) + aoff + m * 2048 + k * 1024); } while (0)
; #define PG8_MMA(ai, bj, At, Bt) do { __builtin_amdgcn_s_setprio(1); _Pragma("unroll") for (int m = 0; m < 4; ++m) _Pragma("unroll") for (int n = 0; n < 2; ++n) _Pragma("unroll") for (int k = 0; k < 2; ++k) \
;         acc[ai][bj][m][n] = __builtin_amdgcn_mfma_f32_16x16x32_bf16(Bt[n][k], At[m][k], acc[ai][bj][m][n], 0, 0, 0); __builtin_amdgcn_s_setprio(0); } while (0)
; #define PG8_WAIT_V(n) asm volatile("s_waitcnt vmcnt(" #n ")" ::: "memory")
; #define PG8_WAIT_L(n) asm volatile("s_waitcnt lgkmcnt(" #n ")" ::: "memory")
; #define PG8_BAR __builtin_amdgcn_s_barrier()
; #define PG8_SCHED __builtin_amdgcn_sched_barrier(0)
; template <class Epi, class Sched, bool ALIGN_EPI = false, bool SP2 = false>
; __device__ __forceinline__ void gemm_phase(PG8_LAS unsigned char* lds, const Gemm g, const Sched& S, const Epi& E) {
;     ...
;             PG8_WAIT_V(8); PG8_WAIT_L(0); PG8_BAR; PG8_MMA(0, 0, At, B0); PG8_MMA(0, 1, At, B1); PG8_BAR; PG8_SCHED;
;             PG8_LDA(At, 0, 1); PG8_STAGE(PG8_SB(0, 0), b2, voffB); PG8_STAGE(PG8_SB(0, 1), b2 + hstep, voffB); PG8_STAGE(PG8_SA(0, 0), a2, voffA);
;             PG8_WAIT_V(8); PG8_WAIT_L(0); PG8_BAR; PG8_MMA(1, 0, At, B0); PG8_MMA(1, 1, At, B1); PG8_BAR; PG8_SCHED;
	s_setprio 1
	s_waitcnt lgkmcnt(0)
	v_mfma_f32_16x16x32_bf16 v[124:127], v[146:149], v[188:191], v[124:127]
	v_mfma_f32_16x16x32_bf16 v[120:123], v[160:163], v[188:191], v[120:123]
	v_mfma_f32_16x16x32_bf16 v[116:119], v[168:171], v[188:191], v[116:119]
	v_mfma_f32_16x16x32_bf16 v[112:115], v[180:183], v[188:191], v[112:115]
	v_mfma_f32_16x16x32_bf16 v[108:111], v[146:149], v[196:199], v[108:111]
	v_mfma_f32_16x16x32_bf16 v[104:107], v[160:163], v[196:199], v[104:107]
	v_mfma_f32_16x16x32_bf16 v[100:103], v[168:171], v[196:199], v[100:103]
	v_mfma_f32_16x16x32_bf16 v[96:99], v[180:183], v[196:199], v[96:99]
	v_mfma_f32_16x16x32_bf16 v[92:95], v[146:149], v[210:213], v[92:95]
	v_mfma_f32_16x16x32_bf16 v[88:91], v[160:163], v[210:213], v[88:91]
	v_mfma_f32_16x16x32_bf16 v[84:87], v[168:171], v[210:213], v[84:87]
	v_mfma_f32_16x16x32_bf16 v[80:83], v[180:183], v[210:213], v[80:83]
	v_mfma_f32_16x16x32_bf16 v[76:79], v[146:149], v[218:221], v[76:79]
	v_mfma_f32_16x16x32_bf16 v[72:75], v[160:163], v[218:221], v[72:75]
	v_mfma_f32_16x16x32_bf16 v[68:71], v[168:171], v[218:221], v[68:71]
	v_mfma_f32_16x16x32_bf16 v[64:67], v[180:183], v[218:221], v[64:67]
	s_setprio 0
	s_setprio 1
	v_mfma_f32_16x16x32_bf16 v[124:127], v[156:159], v[192:195], v[124:127]
	v_mfma_f32_16x16x32_bf16 v[120:123], v[164:167], v[192:195], v[120:123]
	v_mfma_f32_16x16x32_bf16 v[116:119], v[172:175], v[192:195], v[116:119]
	v_mfma_f32_16x16x32_bf16 v[112:115], v[184:187], v[192:195], v[112:115]
	v_mfma_f32_16x16x32_bf16 v[108:111], v[156:159], v[206:209], v[108:111]
	v_mfma_f32_16x16x32_bf16 v[104:107], v[164:167], v[206:209], v[104:107]
	v_mfma_f32_16x16x32_bf16 v[100:103], v[172:175], v[206:209], v[100:103]
	v_mfma_f32_16x16x32_bf16 v[96:99], v[184:187], v[206:209], v[96:99]
	v_mfma_f32_16x16x32_bf16 v[92:95], v[156:159], v[214:217], v[92:95]
	v_mfma_f32_16x16x32_bf16 v[88:91], v[164:167], v[214:217], v[88:91]
	v_mfma_f32_16x16x32_bf16 v[84:87], v[172:175], v[214:217], v[84:87]
	v_mfma_f32_16x16x32_bf16 v[80:83], v[184:187], v[214:217], v[80:83]
	v_mfma_f32_16x16x32_bf16 v[76:79], v[156:159], v[222:225], v[76:79]
	v_mfma_f32_16x16x32_bf16 v[72:75], v[164:167], v[222:225], v[72:75]
	v_mfma_f32_16x16x32_bf16 v[68:71], v[172:175], v[222:225], v[68:71]
	v_mfma_f32_16x16x32_bf16 v[64:67], v[184:187], v[222:225], v[64:67]
	s_setprio 0
	s_barrier
	s_add_i32 s74, s60, s15
	v_lshl_add_u64 v[200:201], s[52:53], 0, v[130:131]
	s_mov_b32 m0, s74
	ds_read_b128 v[188:191], v154 offset:16384
	ds_read_b128 v[192:195], v154 offset:17408
	ds_read_b128 v[196:199], v154 offset:18432
	ds_read_b128 v[206:209], v154 offset:19456
	ds_read_b128 v[210:213], v154 offset:20480
	ds_read_b128 v[214:217], v154 offset:21504
	ds_read_b128 v[218:221], v154 offset:22528
	ds_read_b128 v[222:225], v154 offset:23552
	global_load_lds_dwordx4 v[200:201], off
	s_add_i32 m0, s74, 0x2000
	s_add_u32 s74, s52, 0x40000
	v_lshl_add_u64 v[226:227], s[52:53], 0, v[134:135]
	s_addc_u32 s75, s53, 0
	s_add_i32 s76, s61, s15
	global_load_lds_dwordx4 v[226:227], off
	v_lshl_add_u64 v[228:229], s[74:75], 0, v[130:131]
	s_mov_b32 m0, s76
	global_load_lds_dwordx4 v[228:229], off
	v_lshl_add_u64 v[228:229], s[74:75], 0, v[134:135]
	s_add_i32 m0, s76, 0x2000
	s_nop 0
	global_load_lds_dwordx4 v[228:229], off
	s_waitcnt vmcnt(6)
	s_waitcnt lgkmcnt(0)
	s_barrier
	s_setprio 1
	s_waitcnt lgkmcnt(0)
	v_mfma_f32_16x16x32_bf16 v[60:63], v[146:149], v[188:191], v[60:63]
	v_mfma_f32_16x16x32_bf16 v[56:59], v[160:163], v[188:191], v[56:59]
	v_mfma_f32_16x16x32_bf16 v[52:55], v[168:171], v[188:191], v[52:55]
	v_mfma_f32_16x16x32_bf16 v[48:51], v[180:183], v[188:191], v[48:51]
	v_mfma_f32_16x16x32_bf16 v[44:47], v[146:149], v[196:199], v[44:47]
	v_mfma_f32_16x16x32_bf16 v[40:43], v[160:163], v[196:199], v[40:43]
	v_mfma_f32_16x16x32_bf16 v[36:39], v[168:171], v[196:199], v[36:39]
	v_mfma_f32_16x16x32_bf16 v[32:35], v[180:183], v[196:199], v[32:35]
	v_mfma_f32_16x16x32_bf16 v[28:31], v[146:149], v[210:213], v[28:31]
	v_mfma_f32_16x16x32_bf16 v[24:27], v[160:163], v[210:213], v[24:27]
	v_mfma_f32_16x16x32_bf16 v[20:23], v[168:171], v[210:213], v[20:23]
	v_mfma_f32_16x16x32_bf16 v[16:19], v[180:183], v[210:213], v[16:19]
	v_mfma_f32_16x16x32_bf16 v[12:15], v[146:149], v[218:221], v[12:15]
	v_mfma_f32_16x16x32_bf16 v[8:11], v[160:163], v[218:221], v[8:11]
	v_lshl_add_u64 v[228:229], s[54:55], 0, v[128:129]
	s_mov_b32 m0, s33
	s_nop 0
	global_load_lds_dwordx4 v[228:229], off
	v_mfma_f32_16x16x32_bf16 v[4:7], v[168:171], v[218:221], v[4:7]
	v_mfma_f32_16x16x32_bf16 v[0:3], v[180:183], v[218:221], v[0:3]
	s_setprio 0
	s_setprio 1
	v_mfma_f32_16x16x32_bf16 v[60:63], v[156:159], v[192:195], v[60:63]
	v_mfma_f32_16x16x32_bf16 v[56:59], v[164:167], v[192:195], v[56:59]
	v_mfma_f32_16x16x32_bf16 v[52:55], v[172:175], v[192:195], v[52:55]
	v_mfma_f32_16x16x32_bf16 v[48:51], v[184:187], v[192:195], v[48:51]
	v_mfma_f32_16x16x32_bf16 v[44:47], v[156:159], v[206:209], v[44:47]
	v_mfma_f32_16x16x32_bf16 v[40:43], v[164:167], v[206:209], v[40:43]
	v_mfma_f32_16x16x32_bf16 v[36:39], v[172:175], v[206:209], v[36:39]
	v_mfma_f32_16x16x32_bf16 v[32:35], v[184:187], v[206:209], v[32:35]
	v_mfma_f32_16x16x32_bf16 v[28:31], v[156:159], v[214:217], v[28:31]
	v_mfma_f32_16x16x32_bf16 v[24:27], v[164:167], v[214:217], v[24:27]
	v_mfma_f32_16x16x32_bf16 v[20:23], v[172:175], v[214:217], v[20:23]
	v_mfma_f32_16x16x32_bf16 v[16:19], v[184:187], v[214:217], v[16:19]
	v_mfma_f32_16x16x32_bf16 v[12:15], v[156:159], v[222:225], v[12:15]
	v_mfma_f32_16x16x32_bf16 v[8:11], v[164:167], v[222:225], v[8:11]
	v_lshl_add_u64 v[230:231], s[54:55], 0, v[132:133]
	s_mov_b32 m0, s34
	s_nop 0
	global_load_lds_dwordx4 v[230:231], off
	v_mfma_f32_16x16x32_bf16 v[4:7], v[172:175], v[222:225], v[4:7]
	v_mfma_f32_16x16x32_bf16 v[0:3], v[184:187], v[222:225], v[0:3]
	s_setprio 0
	s_barrier
; #define PG8_STAGE(bufoff, gbase, voff) do { _Pragma("unroll") for (int _i = 0; _i < 2; ++_i) \
;         __builtin_amdgcn_global_load_lds((const unsigned*)((const char*)(gbase) + (voff)[_i]), (PG8_LAS unsigned*)(lds + (bufoff) + ldsw + _i * 8192), 16, 0, 0); } while (0)
; #define PG8_LDA(dst, b, h) do { _Pragma("unroll") for (int m = 0; m < 4; ++m) _Pragma("unroll") for (int k = 0; k < 2; ++k) dst[m][k] = *(const PG8_LAS bf16x8*)(lds + PG8_SA(b, h) + aoff + m * 2048 + k * 1024); } while (0)
; #define PG8_LDB(dst, b, h) do { _Pragma("unroll") for (int n = 0; n < 2; ++n) _Pragma("unroll") for (int k = 0; k < 2; ++k) dst[n][k] = *(const PG8_LAS bf16x8*)(lds + PG8_SB(b, h) + boff + n * 2048 + k * 1024); } while (0)
; #define PG8_MMA(ai, bj, At, Bt) do { __builtin_amdgcn_s_setprio(1); _Pragma("unroll") for (int m = 0; m < 4; ++m) _Pragma("unroll") for (int n = 0; n < 2; ++n) _Pragma("unroll") for (int k = 0; k < 2; ++k) \
;         acc[ai][bj][m][n] = __builtin_amdgcn_mfma_f32_16x16x32_bf16(Bt[n][k], At[m][k], acc[ai][bj][m][n], 0, 0, 0); __builtin_amdgcn_s_setprio(0); } while (0)
; #define PG8_WAIT_V(n) asm volatile("s_waitcnt vmcnt(" #n ")" ::: "memory")
; #define PG8_WAIT_L(n) asm volatile("s_waitcnt lgkmcnt(" #n ")" ::: "memory")
; #define PG8_BAR __builtin_amdgcn_s_barrier()
; #define PG8_SCHED __builtin_amdgcn_sched_barrier(0)
; template <class Epi, class Sched, bool ALIGN_EPI = false, bool SP2 = false>
; __device__ __forceinline__ void gemm_phase(PG8_LAS unsigned char* lds, const Gemm g, const Sched& S, const Epi& E) {
;     ...
;             PG8_LDB(B0, 1, 0); PG8_LDB(B1, 1, 1); PG8_SCHED; PG8_LDA(At, 1, 0); PG8_STAGE(PG8_SA(0, 1), a2 + hstep, voffA);
;             PG8_WAIT_V(8); PG8_WAIT_L(0); PG8_BAR; PG8_MMA(0, 0, At, B0); PG8_MMA(0, 1, At, B1); PG8_BAR; PG8_SCHED;
	s_add_i32 s74, 0, 0x18000
	s_add_i32 s75, 0, 0x1c000
	v_add_u32_e32 v164, s74, v150
	v_add_u32_e32 v179, s75, v150
	ds_read_b128 v[146:149], v164
	ds_read_b128 v[156:159], v164 offset:1024
	ds_read_b128 v[160:163], v164 offset:2048
	ds_read_b128 v[164:167], v164 offset:3072
	ds_read_b128 v[168:171], v179
	ds_read_b128 v[172:175], v179 offset:1024
	ds_read_b128 v[180:183], v179 offset:2048
	ds_read_b128 v[184:187], v179 offset:3072
	s_add_u32 s54, s54, 0x40000
	s_addc_u32 s55, s55, 0
	s_mov_b32 m0, s49
	v_lshl_add_u64 v[232:233], s[54:55], 0, v[128:129]
	ds_read_b128 v[188:191], v154 offset:32768
	ds_read_b128 v[192:195], v154 offset:33792
	ds_read_b128 v[196:199], v154 offset:34816
	ds_read_b128 v[206:209], v154 offset:35840
	ds_read_b128 v[210:213], v154 offset:36864
	ds_read_b128 v[214:217], v154 offset:37888
	ds_read_b128 v[218:221], v154 offset:38912
	ds_read_b128 v[222:225], v154 offset:39936
	global_load_lds_dwordx4 v[232:233], off
	v_lshl_add_u64 v[232:233], s[54:55], 0, v[132:133]
	s_mov_b32 m0, s56
	s_nop 0
	global_load_lds_dwordx4 v[232:233], off
	s_waitcnt vmcnt(8)
	s_waitcnt lgkmcnt(0)
	s_barrier
	s_setprio 1
	s_waitcnt lgkmcnt(0)
	v_mfma_f32_16x16x32_bf16 v[124:127], v[146:149], v[188:191], v[124:127]
	v_mfma_f32_16x16x32_bf16 v[120:123], v[160:163], v[188:191], v[120:123]
	v_mfma_f32_16x16x32_bf16 v[116:119], v[168:171], v[188:191], v[116:119]
	v_mfma_f32_16x16x32_bf16 v[112:115], v[180:183], v[188:191], v[112:115]
	v_mfma_f32_16x16x32_bf16 v[108:111], v[146:149], v[196:199], v[108:111]
	v_mfma_f32_16x16x32_bf16 v[104:107], v[160:163], v[196:199], v[104:107]
	v_mfma_f32_16x16x32_bf16 v[100:103], v[168:171], v[196:199], v[100:103]
	v_mfma_f32_16x16x32_bf16 v[96:99], v[180:183], v[196:199], v[96:99]
	v_mfma_f32_16x16x32_bf16 v[92:95], v[146:149], v[210:213], v[92:95]
	v_mfma_f32_16x16x32_bf16 v[88:91], v[160:163], v[210:213], v[88:91]
	v_mfma_f32_16x16x32_bf16 v[84:87], v[168:171], v[210:213], v[84:87]
	v_mfma_f32_16x16x32_bf16 v[80:83], v[180:183], v[210:213], v[80:83]
	v_mfma_f32_16x16x32_bf16 v[76:79], v[146:149], v[218:221], v[76:79]
	v_mfma_f32_16x16x32_bf16 v[72:75], v[160:163], v[218:221], v[72:75]
	v_mfma_f32_16x16x32_bf16 v[68:71], v[168:171], v[218:221], v[68:71]
	v_mfma_f32_16x16x32_bf16 v[64:67], v[180:183], v[218:221], v[64:67]
	s_setprio 0
	s_setprio 1
	v_mfma_f32_16x16x32_bf16 v[124:127], v[156:159], v[192:195], v[124:127]
	v_mfma_f32_16x16x32_bf16 v[120:123], v[164:167], v[192:195], v[120:123]
	v_mfma_f32_16x16x32_bf16 v[116:119], v[172:175], v[192:195], v[116:119]
	v_mfma_f32_16x16x32_bf16 v[112:115], v[184:187], v[192:195], v[112:115]
	v_mfma_f32_16x16x32_bf16 v[108:111], v[156:159], v[206:209], v[108:111]
	v_mfma_f32_16x16x32_bf16 v[104:107], v[164:167], v[206:209], v[104:107]
	v_mfma_f32_16x16x32_bf16 v[100:103], v[172:175], v[206:209], v[100:103]
	v_mfma_f32_16x16x32_bf16 v[96:99], v[184:187], v[206:209], v[96:99]
	v_mfma_f32_16x16x32_bf16 v[92:95], v[156:159], v[214:217], v[92:95]
	v_mfma_f32_16x16x32_bf16 v[88:91], v[164:167], v[214:217], v[88:91]
	v_mfma_f32_16x16x32_bf16 v[84:87], v[172:175], v[214:217], v[84:87]
	v_mfma_f32_16x16x32_bf16 v[80:83], v[184:187], v[214:217], v[80:83]
	v_mfma_f32_16x16x32_bf16 v[76:79], v[156:159], v[222:225], v[76:79]
	v_mfma_f32_16x16x32_bf16 v[72:75], v[164:167], v[222:225], v[72:75]
	v_mfma_f32_16x16x32_bf16 v[68:71], v[172:175], v[222:225], v[68:71]
	v_mfma_f32_16x16x32_bf16 v[64:67], v[184:187], v[222:225], v[64:67]
	s_setprio 0
	s_barrier
; #define PG8_STAGE(bufoff, gbase, voff) do { _Pragma("unroll") for (int _i = 0; _i < 2; ++_i) \
;         __builtin_amdgcn_global_load_lds((const unsigned*)((const char*)(gbase) + (voff)[_i]), (PG8_LAS unsigned*)(lds + (bufoff) + ldsw + _i * 8192), 16, 0, 0); } while (0)
; #define PG8_LDA(dst, b, h) do { _Pragma("unroll") for (int m = 0; m < 4; ++m) _Pragma("unroll") for (int k = 0; k < 2; ++k) dst[m][k] = *(const PG8_LAS bf16x8*)(lds + PG8_SA(b, h) + aoff + m * 2048 + k * 1024); } while (0)
; #define PG8_MMA(ai, bj, At, Bt) do { __builtin_amdgcn_s_setprio(1); _Pragma("unroll") for (int m = 0; m < 4; ++m) _Pragma("unroll") for (int n = 0; n < 2; ++n) _Pragma("unroll") for (int k = 0; k < 2; ++k) \
;         acc[ai][bj][m][n] = __builtin_amdgcn_mfma_f32_16x16x32_bf16(Bt[n][k], At[m][k], acc[ai][bj][m][n], 0, 0, 0); __builtin_amdgcn_s_setprio(0); } while (0)
; #define PG8_WAIT_V(n) asm volatile("s_waitcnt vmcnt(" #n ")" ::: "memory")
; #define PG8_WAIT_L(n) asm volatile("s_waitcnt lgkmcnt(" #n ")" ::: "memory")
; #define PG8_BAR __builtin_amdgcn_s_barrier()
; #define PG8_SCHED __builtin_amdgcn_sched_barrier(0)
; template <class Epi, class Sched, bool ALIGN_EPI = false, bool SP2 = false>
; __device__ __forceinline__ void gemm_phase(PG8_LAS unsigned char* lds, const Gemm g, const Sched& S, const Epi& E) {
;     ...
;             PG8_LDA(At, 1, 1); PG8_STAGE(PG8_SB(1, 0), b3, voffB); PG8_STAGE(PG8_SB(1, 1), b3 + hstep, voffB); PG8_STAGE(PG8_SA(1, 0), a3, voffA);
;             PG8_WAIT_V(8); PG8_WAIT_L(0); PG8_BAR; PG8_MMA(1, 0, At, B0); PG8_MMA(1, 1, At, B1); PG8_BAR; PG8_SCHED;
;     ...
;         }
;         if constexpr (ALIGN_EPI) { if (wr == 0) PG8_BAR; }
	s_add_i32 s54, s74, s15
	v_lshl_add_u64 v[200:201], v[200:201], 0, s[26:27]
	s_mov_b32 m0, s54
	ds_read_b128 v[188:191], v154 offset:49152
	ds_read_b128 v[192:195], v154 offset:50176
	ds_read_b128 v[196:199], v154 offset:51200
	ds_read_b128 v[206:209], v154 offset:52224
	ds_read_b128 v[210:213], v154 offset:53248
	ds_read_b128 v[214:217], v154 offset:54272
	ds_read_b128 v[218:221], v154 offset:55296
	ds_read_b128 v[222:225], v154 offset:56320
	global_load_lds_dwordx4 v[200:201], off
	s_add_i32 m0, s54, 0x2000
	s_add_u32 s52, s52, 0x40080
	v_lshl_add_u64 v[200:201], v[226:227], 0, s[26:27]
	s_addc_u32 s53, s53, 0
	s_add_i32 s54, s75, s15
	global_load_lds_dwordx4 v[200:201], off
	v_lshl_add_u64 v[200:201], s[52:53], 0, v[130:131]
	s_mov_b32 m0, s54
	s_nop 0
	global_load_lds_dwordx4 v[200:201], off
	v_lshl_add_u64 v[200:201], s[52:53], 0, v[134:135]
	s_add_i32 m0, s54, 0x2000
	s_nop 0
	global_load_lds_dwordx4 v[200:201], off
	s_waitcnt vmcnt(6)
	s_waitcnt lgkmcnt(0)
	s_barrier
	s_setprio 1
	s_waitcnt lgkmcnt(0)
	v_mfma_f32_16x16x32_bf16 v[60:63], v[146:149], v[188:191], v[60:63]
	v_mfma_f32_16x16x32_bf16 v[56:59], v[160:163], v[188:191], v[56:59]
	v_mfma_f32_16x16x32_bf16 v[52:55], v[168:171], v[188:191], v[52:55]
	v_mfma_f32_16x16x32_bf16 v[48:51], v[180:183], v[188:191], v[48:51]
	v_mfma_f32_16x16x32_bf16 v[44:47], v[146:149], v[196:199], v[44:47]
	v_mfma_f32_16x16x32_bf16 v[40:43], v[160:163], v[196:199], v[40:43]
	v_mfma_f32_16x16x32_bf16 v[36:39], v[168:171], v[196:199], v[36:39]
	v_mfma_f32_16x16x32_bf16 v[32:35], v[180:183], v[196:199], v[32:35]
	v_mfma_f32_16x16x32_bf16 v[28:31], v[146:149], v[210:213], v[28:31]
	v_mfma_f32_16x16x32_bf16 v[24:27], v[160:163], v[210:213], v[24:27]
	v_mfma_f32_16x16x32_bf16 v[20:23], v[168:171], v[210:213], v[20:23]
	v_mfma_f32_16x16x32_bf16 v[16:19], v[180:183], v[210:213], v[16:19]
	v_mfma_f32_16x16x32_bf16 v[12:15], v[146:149], v[218:221], v[12:15]
	v_mfma_f32_16x16x32_bf16 v[8:11], v[160:163], v[218:221], v[8:11]
	v_lshl_add_u64 v[200:201], v[228:229], 0, s[26:27]
	s_mov_b32 m0, s58
	s_nop 0
	global_load_lds_dwordx4 v[200:201], off
	v_mfma_f32_16x16x32_bf16 v[4:7], v[168:171], v[218:221], v[4:7]
	v_mfma_f32_16x16x32_bf16 v[0:3], v[180:183], v[218:221], v[0:3]
	s_setprio 0
	s_setprio 1
	v_mfma_f32_16x16x32_bf16 v[60:63], v[156:159], v[192:195], v[60:63]
	v_mfma_f32_16x16x32_bf16 v[56:59], v[164:167], v[192:195], v[56:59]
	v_mfma_f32_16x16x32_bf16 v[52:55], v[172:175], v[192:195], v[52:55]
	v_mfma_f32_16x16x32_bf16 v[48:51], v[184:187], v[192:195], v[48:51]
	v_mfma_f32_16x16x32_bf16 v[44:47], v[156:159], v[206:209], v[44:47]
	v_mfma_f32_16x16x32_bf16 v[40:43], v[164:167], v[206:209], v[40:43]
	v_mfma_f32_16x16x32_bf16 v[36:39], v[172:175], v[206:209], v[36:39]
	v_mfma_f32_16x16x32_bf16 v[32:35], v[184:187], v[206:209], v[32:35]
	v_mfma_f32_16x16x32_bf16 v[28:31], v[156:159], v[214:217], v[28:31]
	v_mfma_f32_16x16x32_bf16 v[24:27], v[164:167], v[214:217], v[24:27]
	v_mfma_f32_16x16x32_bf16 v[20:23], v[172:175], v[214:217], v[20:23]
	v_mfma_f32_16x16x32_bf16 v[16:19], v[184:187], v[214:217], v[16:19]
	v_mfma_f32_16x16x32_bf16 v[12:15], v[156:159], v[222:225], v[12:15]
	v_mfma_f32_16x16x32_bf16 v[8:11], v[164:167], v[222:225], v[8:11]
	v_lshl_add_u64 v[200:201], v[230:231], 0, s[26:27]
	s_mov_b32 m0, s59
	s_nop 0
	global_load_lds_dwordx4 v[200:201], off
	v_mfma_f32_16x16x32_bf16 v[4:7], v[172:175], v[222:225], v[4:7]
	v_mfma_f32_16x16x32_bf16 v[0:3], v[184:187], v[222:225], v[0:3]
	s_setprio 0
	s_barrier
	s_add_i32 s67, s67, 2
	s_add_u32 s50, s50, 0x100
	s_addc_u32 s51, s51, 0
	s_add_u32 s65, s65, 0x100
	s_addc_u32 s66, s66, 0
	s_cmp_gt_u32 s67, 13
	s_cbranch_scc0 .LBB0_1593
	s_and_b64 vcc, exec, s[28:29]
	s_cbranch_vccz .LBB0_1596
	s_barrier

; #define PG8_STAGE(bufoff, gbase, voff) do { _Pragma("unroll") for (int _i = 0; _i < 2; ++_i) \
;         __builtin_amdgcn_global_load_lds((const unsigned*)((const char*)(gbase) + (voff)[_i]), (PG8_LAS unsigned*)(lds + (bufoff) + ldsw + _i * 8192), 16, 0, 0); } while (0)
; #define PG8_LDA(dst, b, h) do { _Pragma("unroll") for (int m = 0; m < 4; ++m) _Pragma("unroll") for (int k = 0; k < 2; ++k) dst[m][k] = *(const PG8_LAS bf16x8*)(lds + PG8_SA(b, h) + aoff + m * 2048 + k * 1024); } while (0)
; #define PG8_LDB(dst, b, h) do { _Pragma("unroll") for (int n = 0; n < 2; ++n) _Pragma("unroll") for (int k = 0; k < 2; ++k) dst[n][k] = *(const PG8_LAS bf16x8*)(lds + PG8_SB(b, h) + boff + n * 2048 + k * 1024); } while (0)
; #define PG8_WAIT_V(n) asm volatile("s_waitcnt vmcnt(" #n ")" ::: "memory")
; #define PG8_WAIT_L(n) asm volatile("s_waitcnt lgkmcnt(" #n ")" ::: "memory")
; #define PG8_BAR __builtin_amdgcn_s_barrier()
; #define PG8_SCHED __builtin_amdgcn_sched_barrier(0)
; template <class Epi, class Sched, bool ALIGN_EPI = false, bool SP2 = false>
; __device__ __forceinline__ void gemm_phase(PG8_LAS unsigned char* lds, const Gemm g, const Sched& S, const Epi& E) {
;     ...
;         const bool has_next = S.next(ui + 1, nxt);
;         const char* nA = has_next ? (const char*)g.A + (size_t)nxt.pm * tstep : cA; const char* nB = has_next ? (const char*)g.Bt + (size_t)nxt.pn * tstep : cB;
;         for (int t = 0; t < nt; t += 2) {
;             const bool last = (t == nt - 2);
;             const char* a1 = cA + (size_t)(t + 1) * kstep;
;             const char* a2 = last ? nA : cA + (size_t)(t + 2) * kstep; const char* b2 = last ? nB : cB + (size_t)(t + 2) * kstep;
;             const char* a3 = a2 + kstep; const char* b3 = b2 + kstep;
;             if (last && has_next) S.a_ready(nxt);
;             if constexpr (SP2) {
;             PG8_LDB(B0, 0, 0); PG8_LDB(B1, 0, 1); PG8_SCHED; PG8_LDA(At, 0, 0); PG8_STAGE(PG8_SA(1, 1), a1 + hstep, voffA);
;             PG8_WAIT_V(8); PG8_WAIT_L(0); PG8_BAR; PG8_MMA(0, 0, At, B0); PG8_MMA(0, 1, At, B1); PG8_BAR; PG8_SCHED;
;             PG8_LDA(At, 0, 1); PG8_STAGE(PG8_SB(0, 0), b2, voffB); PG8_STAGE(PG8_SB(0, 1), b2 + hstep, voffB); PG8_STAGE(PG8_SA(0, 0), a2, voffA);
;             PG8_WAIT_V(8); PG8_WAIT_L(0); PG8_BAR; PG8_MMA(1, 0, At, B0); PG8_MMA(1, 1, At, B1); PG8_BAR; PG8_SCHED;
.LBB0_1680:
	s_ashr_i32 s47, s46, 31
	s_lshl_b64 s[48:49], s[46:47], 19
	s_add_u32 s48, s22, s48
	s_addc_u32 s49, s23, s49
	s_and_b64 s[50:51], s[4:5], exec
	s_cselect_b32 s47, s49, s53
	s_cselect_b32 s77, s48, s52
	s_ashr_i32 s45, s44, 31
	s_lshl_b64 s[50:51], s[44:45], 19
	s_add_u32 s50, s15, s50
	s_addc_u32 s51, s33, s51
	s_and_b64 s[56:57], s[4:5], exec
	s_cselect_b32 s45, s51, s55
	s_cselect_b32 s78, s50, s54
	s_add_u32 s52, s52, 0x40080
	s_addc_u32 s53, s53, 0
	s_add_u32 s79, s54, 0x100
	s_addc_u32 s80, s55, 0
	s_mov_b32 s81, -2
	ds_read_b128 v[146:149], v152
	ds_read_b128 v[156:159], v152 offset:1024
	ds_read_b128 v[160:163], v152 offset:2048
	ds_read_b128 v[164:167], v152 offset:3072
	ds_read_b128 v[168:171], v153
	ds_read_b128 v[172:175], v153 offset:1024
	ds_read_b128 v[180:183], v153 offset:2048
	ds_read_b128 v[184:187], v153 offset:3072
	s_add_u32 s54, s52, 0xfffc0080
	s_addc_u32 s55, s53, -1
	s_cmp_eq_u32 s81, 12
	s_cselect_b32 s57, s47, s55
	s_cselect_b32 s56, s77, s54
	s_cselect_b32 s55, s45, s80
	s_cselect_b32 s54, s78, s79
	v_lshl_add_u64 v[200:201], s[52:53], 0, v[136:137]
	s_add_i32 m0, s58, 0xc000
	ds_read_b128 v[188:191], v154
	ds_read_b128 v[192:195], v154 offset:1024
	ds_read_b128 v[196:199], v154 offset:2048
	ds_read_b128 v[206:209], v154 offset:3072
	ds_read_b128 v[210:213], v154 offset:4096
	ds_read_b128 v[214:217], v154 offset:5120
	ds_read_b128 v[218:221], v154 offset:6144
	ds_read_b128 v[222:225], v154 offset:7168
	global_load_lds_dwordx4 v[200:201], off
	v_lshl_add_u64 v[200:201], s[52:53], 0, v[138:139]
	s_add_i32 m0, s58, 0xe000
	s_nop 0
	global_load_lds_dwordx4 v[200:201], off
	s_waitcnt vmcnt(8)
	s_waitcnt lgkmcnt(0)
	s_barrier
	s_setprio 1
	s_waitcnt lgkmcnt(0)
	v_mfma_f32_16x16x32_bf16 v[124:127], v[146:149], v[188:191], 0
	v_mfma_f32_16x16x32_bf16 v[120:123], v[160:163], v[188:191], 0
	v_mfma_f32_16x16x32_bf16 v[116:119], v[168:171], v[188:191], 0
	v_mfma_f32_16x16x32_bf16 v[112:115], v[180:183], v[188:191], 0
	v_mfma_f32_16x16x32_bf16 v[108:111], v[146:149], v[196:199], 0
	v_mfma_f32_16x16x32_bf16 v[104:107], v[160:163], v[196:199], 0
	v_mfma_f32_16x16x32_bf16 v[100:103], v[168:171], v[196:199], 0
	v_mfma_f32_16x16x32_bf16 v[96:99], v[180:183], v[196:199], 0
	v_mfma_f32_16x16x32_bf16 v[92:95], v[146:149], v[210:213], 0
	v_mfma_f32_16x16x32_bf16 v[88:91], v[160:163], v[210:213], 0
	v_mfma_f32_16x16x32_bf16 v[84:87], v[168:171], v[210:213], 0
	v_mfma_f32_16x16x32_bf16 v[80:83], v[180:183], v[210:213], 0
	v_mfma_f32_16x16x32_bf16 v[76:79], v[146:149], v[218:221], 0
	v_mfma_f32_16x16x32_bf16 v[72:75], v[160:163], v[218:221], 0
	v_mfma_f32_16x16x32_bf16 v[68:71], v[168:171], v[218:221], 0
	v_mfma_f32_16x16x32_bf16 v[64:67], v[180:183], v[218:221], 0
	s_setprio 0
	s_setprio 1
	v_mfma_f32_16x16x32_bf16 v[124:127], v[156:159], v[192:195], v[124:127]
	v_mfma_f32_16x16x32_bf16 v[120:123], v[164:167], v[192:195], v[120:123]
	v_mfma_f32_16x16x32_bf16 v[116:119], v[172:175], v[192:195], v[116:119]
	v_mfma_f32_16x16x32_bf16 v[112:115], v[184:187], v[192:195], v[112:115]
	v_mfma_f32_16x16x32_bf16 v[108:111], v[156:159], v[206:209], v[108:111]
	v_mfma_f32_16x16x32_bf16 v[104:107], v[164:167], v[206:209], v[104:107]
	v_mfma_f32_16x16x32_bf16 v[100:103], v[172:175], v[206:209], v[100:103]
	v_mfma_f32_16x16x32_bf16 v[96:99], v[184:187], v[206:209], v[96:99]
	v_mfma_f32_16x16x32_bf16 v[92:95], v[156:159], v[214:217], v[92:95]
	v_mfma_f32_16x16x32_bf16 v[88:91], v[164:167], v[214:217], v[88:91]
	v_mfma_f32_16x16x32_bf16 v[84:87], v[172:175], v[214:217], v[84:87]
	v_mfma_f32_16x16x32_bf16 v[80:83], v[184:187], v[214:217], v[80:83]
	v_mfma_f32_16x16x32_bf16 v[76:79], v[156:159], v[222:225], v[76:79]
	v_mfma_f32_16x16x32_bf16 v[72:75], v[164:167], v[222:225], v[72:75]
	v_mfma_f32_16x16x32_bf16 v[68:71], v[172:175], v[222:225], v[68:71]
	v_mfma_f32_16x16x32_bf16 v[64:67], v[184:187], v[222:225], v[64:67]
	s_setprio 0
	s_barrier
	s_add_i32 s82, s65, s34
	v_lshl_add_u64 v[200:201], s[54:55], 0, v[132:133]
	s_mov_b32 m0, s82
	ds_read_b128 v[188:191], v154 offset:16384
	ds_read_b128 v[192:195], v154 offset:17408
	ds_read_b128 v[196:199], v154 offset:18432
	ds_read_b128 v[206:209], v154 offset:19456
	ds_read_b128 v[210:213], v154 offset:20480
	ds_read_b128 v[214:217], v154 offset:21504
	ds_read_b128 v[218:221], v154 offset:22528
	ds_read_b128 v[222:225], v154 offset:23552
	global_load_lds_dwordx4 v[200:201], off
	s_add_i32 m0, s82, 0x2000
	s_add_u32 s82, s54, 0x40000
	v_lshl_add_u64 v[226:227], s[54:55], 0, v[128:129]
	s_addc_u32 s83, s55, 0
	s_add_i32 s84, s66, s34
	global_load_lds_dwordx4 v[226:227], off
	v_lshl_add_u64 v[228:229], s[82:83], 0, v[132:133]
	s_mov_b32 m0, s84
	global_load_lds_dwordx4 v[228:229], off
	v_lshl_add_u64 v[228:229], s[82:83], 0, v[128:129]
	s_add_i32 m0, s84, 0x2000
	s_nop 0
	global_load_lds_dwordx4 v[228:229], off
	s_waitcnt vmcnt(6)
	s_waitcnt lgkmcnt(0)
	s_barrier
; #define PG8_STAGE(bufoff, gbase, voff) do { _Pragma("unroll") for (int _i = 0; _i < 2; ++_i) \
;         __builtin_amdgcn_global_load_lds((const unsigned*)((const char*)(gbase) + (voff)[_i]), (PG8_LAS unsigned*)(lds + (bufoff) + ldsw + _i * 8192), 16, 0, 0); } while (0)
; #define PG8_LDA(dst, b, h) do { _Pragma("unroll") for (int m = 0; m < 4; ++m) _Pragma("unroll") for (int k = 0; k < 2; ++k) dst[m][k] = *(const PG8_LAS bf16x8*)(lds + PG8_SA(b, h) + aoff + m * 2048 + k * 1024); } while (0)
; #define PG8_LDB(dst, b, h) do { _Pragma("unroll") for (int n = 0; n < 2; ++n) _Pragma("unroll") for (int k = 0; k < 2; ++k) dst[n][k] = *(const PG8_LAS bf16x8*)(lds + PG8_SB(b, h) + boff + n * 2048 + k * 1024); } while (0)
; #define PG8_MMA(ai, bj, At, Bt) do { __builtin_amdgcn_s_setprio(1); _Pragma("unroll") for (int m = 0; m < 4; ++m) _Pragma("unroll") for (int n = 0; n < 2; ++n) _Pragma("unroll") for (int k = 0; k < 2; ++k) \
;         acc[ai][bj][m][n] = __builtin_amdgcn_mfma_f32_16x16x32_bf16(Bt[n][k], At[m][k], acc[ai][bj][m][n], 0, 0, 0); __builtin_amdgcn_s_setprio(0); } while (0)
; #define PG8_WAIT_V(n) asm volatile("s_waitcnt vmcnt(" #n ")" ::: "memory")
; #define PG8_WAIT_L(n) asm volatile("s_waitcnt lgkmcnt(" #n ")" ::: "memory")
; #define PG8_BAR __builtin_amdgcn_s_barrier()
; #define PG8_SCHED __builtin_amdgcn_sched_barrier(0)
; template <class Epi, class Sched, bool ALIGN_EPI = false, bool SP2 = false>
; __device__ __forceinline__ void gemm_phase(PG8_LAS unsigned char* lds, const Gemm g, const Sched& S, const Epi& E) {
;     ...
;             PG8_WAIT_V(8); PG8_WAIT_L(0); PG8_BAR; PG8_MMA(1, 0, At, B0); PG8_MMA(1, 1, At, B1); PG8_BAR; PG8_SCHED;
;             PG8_LDB(B0, 1, 0); PG8_LDB(B1, 1, 1); PG8_SCHED; PG8_LDA(At, 1, 0); PG8_STAGE(PG8_SA(0, 1), a2 + hstep, voffA);
;             PG8_WAIT_V(8); PG8_WAIT_L(0); PG8_BAR; PG8_MMA(0, 0, At, B0); PG8_MMA(0, 1, At, B1); PG8_BAR; PG8_SCHED;
	s_setprio 1
	s_waitcnt lgkmcnt(0)
	v_mfma_f32_16x16x32_bf16 v[60:63], v[146:149], v[188:191], 0
	v_mfma_f32_16x16x32_bf16 v[56:59], v[160:163], v[188:191], 0
	v_mfma_f32_16x16x32_bf16 v[52:55], v[168:171], v[188:191], 0
	v_mfma_f32_16x16x32_bf16 v[48:51], v[180:183], v[188:191], 0
	v_mfma_f32_16x16x32_bf16 v[44:47], v[146:149], v[196:199], 0
	v_mfma_f32_16x16x32_bf16 v[40:43], v[160:163], v[196:199], 0
	v_mfma_f32_16x16x32_bf16 v[36:39], v[168:171], v[196:199], 0
	v_mfma_f32_16x16x32_bf16 v[32:35], v[180:183], v[196:199], 0
	v_mfma_f32_16x16x32_bf16 v[28:31], v[146:149], v[210:213], 0
	v_mfma_f32_16x16x32_bf16 v[24:27], v[160:163], v[210:213], 0
	v_mfma_f32_16x16x32_bf16 v[20:23], v[168:171], v[210:213], 0
	v_mfma_f32_16x16x32_bf16 v[16:19], v[180:183], v[210:213], 0
	v_mfma_f32_16x16x32_bf16 v[12:15], v[146:149], v[218:221], 0
	v_mfma_f32_16x16x32_bf16 v[8:11], v[160:163], v[218:221], 0
	v_lshl_add_u64 v[228:229], s[56:57], 0, v[134:135]
	s_mov_b32 m0, s58
	s_nop 0
	global_load_lds_dwordx4 v[228:229], off
	v_mfma_f32_16x16x32_bf16 v[4:7], v[168:171], v[218:221], 0
	v_mfma_f32_16x16x32_bf16 v[0:3], v[180:183], v[218:221], 0
	s_setprio 0
	s_setprio 1
	v_mfma_f32_16x16x32_bf16 v[60:63], v[156:159], v[192:195], v[60:63]
	v_mfma_f32_16x16x32_bf16 v[56:59], v[164:167], v[192:195], v[56:59]
	v_mfma_f32_16x16x32_bf16 v[52:55], v[172:175], v[192:195], v[52:55]
	v_mfma_f32_16x16x32_bf16 v[48:51], v[184:187], v[192:195], v[48:51]
	v_mfma_f32_16x16x32_bf16 v[44:47], v[156:159], v[206:209], v[44:47]
	v_mfma_f32_16x16x32_bf16 v[40:43], v[164:167], v[206:209], v[40:43]
	v_mfma_f32_16x16x32_bf16 v[36:39], v[172:175], v[206:209], v[36:39]
	v_mfma_f32_16x16x32_bf16 v[32:35], v[184:187], v[206:209], v[32:35]
	v_mfma_f32_16x16x32_bf16 v[28:31], v[156:159], v[214:217], v[28:31]
	v_mfma_f32_16x16x32_bf16 v[24:27], v[164:167], v[214:217], v[24:27]
	v_mfma_f32_16x16x32_bf16 v[20:23], v[172:175], v[214:217], v[20:23]
	v_mfma_f32_16x16x32_bf16 v[16:19], v[184:187], v[214:217], v[16:19]
	v_mfma_f32_16x16x32_bf16 v[12:15], v[156:159], v[222:225], v[12:15]
	v_mfma_f32_16x16x32_bf16 v[8:11], v[164:167], v[222:225], v[8:11]
	v_lshl_add_u64 v[230:231], s[56:57], 0, v[130:131]
	s_mov_b32 m0, s59
	s_nop 0
	global_load_lds_dwordx4 v[230:231], off
	v_mfma_f32_16x16x32_bf16 v[4:7], v[172:175], v[222:225], v[4:7]
	v_mfma_f32_16x16x32_bf16 v[0:3], v[184:187], v[222:225], v[0:3]
	s_setprio 0
	s_barrier
	s_add_i32 s82, 0, 0x18000
	s_add_i32 s83, 0, 0x1c000
	v_add_u32_e32 v164, s82, v150
	v_add_u32_e32 v179, s83, v150
	ds_read_b128 v[146:149], v164
	ds_read_b128 v[156:159], v164 offset:1024
	ds_read_b128 v[160:163], v164 offset:2048
	ds_read_b128 v[164:167], v164 offset:3072
	ds_read_b128 v[168:171], v179
	ds_read_b128 v[172:175], v179 offset:1024
	ds_read_b128 v[180:183], v179 offset:2048
	ds_read_b128 v[184:187], v179 offset:3072
	s_add_u32 s56, s56, 0x40000
	s_addc_u32 s57, s57, 0
	s_mov_b32 m0, s60
	v_lshl_add_u64 v[232:233], s[56:57], 0, v[134:135]
	ds_read_b128 v[188:191], v154 offset:32768
	ds_read_b128 v[192:195], v154 offset:33792
	ds_read_b128 v[196:199], v154 offset:34816
	ds_read_b128 v[206:209], v154 offset:35840
	ds_read_b128 v[210:213], v154 offset:36864
	ds_read_b128 v[214:217], v154 offset:37888
	ds_read_b128 v[218:221], v154 offset:38912
	ds_read_b128 v[222:225], v154 offset:39936
	global_load_lds_dwordx4 v[232:233], off
	v_lshl_add_u64 v[232:233], s[56:57], 0, v[130:131]
	s_mov_b32 m0, s61
	s_nop 0
	global_load_lds_dwordx4 v[232:233], off
	s_waitcnt vmcnt(8)
	s_waitcnt lgkmcnt(0)
	s_barrier
	s_setprio 1
	s_waitcnt lgkmcnt(0)
	v_mfma_f32_16x16x32_bf16 v[124:127], v[146:149], v[188:191], v[124:127]
	v_mfma_f32_16x16x32_bf16 v[120:123], v[160:163], v[188:191], v[120:123]
	v_mfma_f32_16x16x32_bf16 v[116:119], v[168:171], v[188:191], v[116:119]
	v_mfma_f32_16x16x32_bf16 v[112:115], v[180:183], v[188:191], v[112:115]
	v_mfma_f32_16x16x32_bf16 v[108:111], v[146:149], v[196:199], v[108:111]
	v_mfma_f32_16x16x32_bf16 v[104:107], v[160:163], v[196:199], v[104:107]
	v_mfma_f32_16x16x32_bf16 v[100:103], v[168:171], v[196:199], v[100:103]
	v_mfma_f32_16x16x32_bf16 v[96:99], v[180:183], v[196:199], v[96:99]
	v_mfma_f32_16x16x32_bf16 v[92:95], v[146:149], v[210:213], v[92:95]
	v_mfma_f32_16x16x32_bf16 v[88:91], v[160:163], v[210:213], v[88:91]
	v_mfma_f32_16x16x32_bf16 v[84:87], v[168:171], v[210:213], v[84:87]
	v_mfma_f32_16x16x32_bf16 v[80:83], v[180:183], v[210:213], v[80:83]
	v_mfma_f32_16x16x32_bf16 v[76:79], v[146:149], v[218:221], v[76:79]
	v_mfma_f32_16x16x32_bf16 v[72:75], v[160:163], v[218:221], v[72:75]
	v_mfma_f32_16x16x32_bf16 v[68:71], v[168:171], v[218:221], v[68:71]
	v_mfma_f32_16x16x32_bf16 v[64:67], v[180:183], v[218:221], v[64:67]
	s_setprio 0
	s_setprio 1
	v_mfma_f32_16x16x32_bf16 v[124:127], v[156:159], v[192:195], v[124:127]
	v_mfma_f32_16x16x32_bf16 v[120:123], v[164:167], v[192:195], v[120:123]
	v_mfma_f32_16x16x32_bf16 v[116:119], v[172:175], v[192:195], v[116:119]
	v_mfma_f32_16x16x32_bf16 v[112:115], v[184:187], v[192:195], v[112:115]
	v_mfma_f32_16x16x32_bf16 v[108:111], v[156:159], v[206:209], v[108:111]
	v_mfma_f32_16x16x32_bf16 v[104:107], v[164:167], v[206:209], v[104:107]
	v_mfma_f32_16x16x32_bf16 v[100:103], v[172:175], v[206:209], v[100:103]
	v_mfma_f32_16x16x32_bf16 v[96:99], v[184:187], v[206:209], v[96:99]
	v_mfma_f32_16x16x32_bf16 v[92:95], v[156:159], v[214:217], v[92:95]
	v_mfma_f32_16x16x32_bf16 v[88:91], v[164:167], v[214:217], v[88:91]
	v_mfma_f32_16x16x32_bf16 v[84:87], v[172:175], v[214:217], v[84:87]
	v_mfma_f32_16x16x32_bf16 v[80:83], v[184:187], v[214:217], v[80:83]
	v_mfma_f32_16x16x32_bf16 v[76:79], v[156:159], v[222:225], v[76:79]
	v_mfma_f32_16x16x32_bf16 v[72:75], v[164:167], v[222:225], v[72:75]
	v_mfma_f32_16x16x32_bf16 v[68:71], v[172:175], v[222:225], v[68:71]
	v_mfma_f32_16x16x32_bf16 v[64:67], v[184:187], v[222:225], v[64:67]
	s_setprio 0
	s_barrier
; #define PG8_STAGE(bufoff, gbase, voff) do { _Pragma("unroll") for (int _i = 0; _i < 2; ++_i) \
;         __builtin_amdgcn_global_load_lds((const unsigned*)((const char*)(gbase) + (voff)[_i]), (PG8_LAS unsigned*)(lds + (bufoff) + ldsw + _i * 8192), 16, 0, 0); } while (0)
; #define PG8_LDA(dst, b, h) do { _Pragma("unroll") for (int m = 0; m < 4; ++m) _Pragma("unroll") for (int k = 0; k < 2; ++k) dst[m][k] = *(const PG8_LAS bf16x8*)(lds + PG8_SA(b, h) + aoff + m * 2048 + k * 1024); } while (0)
; #define PG8_LDB(dst, b, h) do { _Pragma("unroll") for (int n = 0; n < 2; ++n) _Pragma("unroll") for (int k = 0; k < 2; ++k) dst[n][k] = *(const PG8_LAS bf16x8*)(lds + PG8_SB(b, h) + boff + n * 2048 + k * 1024); } while (0)
; #define PG8_MMA(ai, bj, At, Bt) do { __builtin_amdgcn_s_setprio(1); _Pragma("unroll") for (int m = 0; m < 4; ++m) _Pragma("unroll") for (int n = 0; n < 2; ++n) _Pragma("unroll") for (int k = 0; k < 2; ++k) \
;         acc[ai][bj][m][n] = __builtin_amdgcn_mfma_f32_16x16x32_bf16(Bt[n][k], At[m][k], acc[ai][bj][m][n], 0, 0, 0); __builtin_amdgcn_s_setprio(0); } while (0)
; #define PG8_WAIT_V(n) asm volatile("s_waitcnt vmcnt(" #n ")" ::: "memory")
; #define PG8_BAR __builtin_amdgcn_s_barrier()
; template <class Epi, class Sched, bool ALIGN_EPI = false, bool SP2 = false>
; __device__ __forceinline__ void gemm_phase(PG8_LAS unsigned char* lds, const Gemm g, const Sched& S, const Epi& E) {
;     ...
;         for (int t = 0; t < nt; t += 2) {
;             const bool last = (t == nt - 2);
;             const char* a1 = cA + (size_t)(t + 1) * kstep;
;             const char* a2 = last ? nA : cA + (size_t)(t + 2) * kstep; const char* b2 = last ? nB : cB + (size_t)(t + 2) * kstep;
;             const char* a3 = a2 + kstep; const char* b3 = b2 + kstep;
;             if (last && has_next) S.a_ready(nxt);
;             if constexpr (SP2) {
;             PG8_LDB(B0, 0, 0); PG8_LDB(B1, 0, 1); PG8_SCHED; PG8_LDA(At, 0, 0); PG8_STAGE(PG8_SA(1, 1), a1 + hstep, voffA);
;             PG8_WAIT_V(8); PG8_WAIT_L(0); PG8_BAR; PG8_MMA(0, 0, At, B0); PG8_MMA(0, 1, At, B1); PG8_BAR; PG8_SCHED;
;     ...
;             PG8_LDA(At, 1, 1); PG8_STAGE(PG8_SB(1, 0), b3, voffB); PG8_STAGE(PG8_SB(1, 1), b3 + hstep, voffB); PG8_STAGE(PG8_SA(1, 0), a3, voffA);
;             PG8_WAIT_V(8); PG8_WAIT_L(0); PG8_BAR; PG8_MMA(1, 0, At, B0); PG8_MMA(1, 1, At, B1); PG8_BAR; PG8_SCHED;
	s_add_i32 s56, s82, s34
	v_lshl_add_u64 v[200:201], v[200:201], 0, s[26:27]
	s_mov_b32 m0, s56
	ds_read_b128 v[188:191], v154 offset:49152
	ds_read_b128 v[192:195], v154 offset:50176
	ds_read_b128 v[196:199], v154 offset:51200
	ds_read_b128 v[206:209], v154 offset:52224
	ds_read_b128 v[210:213], v154 offset:53248
	ds_read_b128 v[214:217], v154 offset:54272
	ds_read_b128 v[218:221], v154 offset:55296
	ds_read_b128 v[222:225], v154 offset:56320
	global_load_lds_dwordx4 v[200:201], off
	s_add_i32 m0, s56, 0x2000
	s_add_u32 s54, s54, 0x40080
	v_lshl_add_u64 v[200:201], v[226:227], 0, s[26:27]
	s_addc_u32 s55, s55, 0
	s_add_i32 s56, s83, s34
	global_load_lds_dwordx4 v[200:201], off
	v_lshl_add_u64 v[200:201], s[54:55], 0, v[132:133]
	s_mov_b32 m0, s56
	s_nop 0
	global_load_lds_dwordx4 v[200:201], off
	v_lshl_add_u64 v[200:201], s[54:55], 0, v[128:129]
	s_add_i32 m0, s56, 0x2000
	s_nop 0
	global_load_lds_dwordx4 v[200:201], off
	s_waitcnt vmcnt(6)
	s_waitcnt lgkmcnt(0)
	s_barrier
	s_setprio 1
	s_waitcnt lgkmcnt(0)
	v_mfma_f32_16x16x32_bf16 v[60:63], v[146:149], v[188:191], v[60:63]
	v_mfma_f32_16x16x32_bf16 v[56:59], v[160:163], v[188:191], v[56:59]
	v_mfma_f32_16x16x32_bf16 v[52:55], v[168:171], v[188:191], v[52:55]
	v_mfma_f32_16x16x32_bf16 v[48:51], v[180:183], v[188:191], v[48:51]
	v_mfma_f32_16x16x32_bf16 v[44:47], v[146:149], v[196:199], v[44:47]
	v_mfma_f32_16x16x32_bf16 v[40:43], v[160:163], v[196:199], v[40:43]
	v_mfma_f32_16x16x32_bf16 v[36:39], v[168:171], v[196:199], v[36:39]
	v_mfma_f32_16x16x32_bf16 v[32:35], v[180:183], v[196:199], v[32:35]
	v_mfma_f32_16x16x32_bf16 v[28:31], v[146:149], v[210:213], v[28:31]
	v_mfma_f32_16x16x32_bf16 v[24:27], v[160:163], v[210:213], v[24:27]
	v_mfma_f32_16x16x32_bf16 v[20:23], v[168:171], v[210:213], v[20:23]
	v_mfma_f32_16x16x32_bf16 v[16:19], v[180:183], v[210:213], v[16:19]
	v_mfma_f32_16x16x32_bf16 v[12:15], v[146:149], v[218:221], v[12:15]
	v_mfma_f32_16x16x32_bf16 v[8:11], v[160:163], v[218:221], v[8:11]
	v_lshl_add_u64 v[200:201], v[228:229], 0, s[26:27]
	s_mov_b32 m0, s63
	s_nop 0
	global_load_lds_dwordx4 v[200:201], off
	v_mfma_f32_16x16x32_bf16 v[4:7], v[168:171], v[218:221], v[4:7]
	v_mfma_f32_16x16x32_bf16 v[0:3], v[180:183], v[218:221], v[0:3]
	s_setprio 0
	s_setprio 1
	v_mfma_f32_16x16x32_bf16 v[60:63], v[156:159], v[192:195], v[60:63]
	v_mfma_f32_16x16x32_bf16 v[56:59], v[164:167], v[192:195], v[56:59]
	v_mfma_f32_16x16x32_bf16 v[52:55], v[172:175], v[192:195], v[52:55]
	v_mfma_f32_16x16x32_bf16 v[48:51], v[184:187], v[192:195], v[48:51]
	v_mfma_f32_16x16x32_bf16 v[44:47], v[156:159], v[206:209], v[44:47]
	v_mfma_f32_16x16x32_bf16 v[40:43], v[164:167], v[206:209], v[40:43]
	v_mfma_f32_16x16x32_bf16 v[36:39], v[172:175], v[206:209], v[36:39]
	v_mfma_f32_16x16x32_bf16 v[32:35], v[184:187], v[206:209], v[32:35]
	v_mfma_f32_16x16x32_bf16 v[28:31], v[156:159], v[214:217], v[28:31]
	v_mfma_f32_16x16x32_bf16 v[24:27], v[164:167], v[214:217], v[24:27]
	v_mfma_f32_16x16x32_bf16 v[20:23], v[172:175], v[214:217], v[20:23]
	v_mfma_f32_16x16x32_bf16 v[16:19], v[184:187], v[214:217], v[16:19]
	v_mfma_f32_16x16x32_bf16 v[12:15], v[156:159], v[222:225], v[12:15]
	v_mfma_f32_16x16x32_bf16 v[8:11], v[164:167], v[222:225], v[8:11]
	v_lshl_add_u64 v[200:201], v[230:231], 0, s[26:27]
	s_mov_b32 m0, s64
	s_nop 0
	global_load_lds_dwordx4 v[200:201], off
	v_mfma_f32_16x16x32_bf16 v[4:7], v[172:175], v[222:225], v[4:7]
	v_mfma_f32_16x16x32_bf16 v[0:3], v[184:187], v[222:225], v[0:3]
	s_setprio 0
	s_barrier
	s_add_i32 s81, s81, 2
	s_add_u32 s52, s52, 0x100
	s_addc_u32 s53, s53, 0
	s_add_u32 s79, s79, 0x100
	s_addc_u32 s80, s80, 0
.LBB0_1681:
	ds_read_b128 v[146:149], v152
	ds_read_b128 v[156:159], v152 offset:1024
	ds_read_b128 v[160:163], v152 offset:2048
	ds_read_b128 v[164:167], v152 offset:3072
	ds_read_b128 v[168:171], v153
	ds_read_b128 v[172:175], v153 offset:1024
	ds_read_b128 v[180:183], v153 offset:2048
	ds_read_b128 v[184:187], v153 offset:3072
	s_add_u32 s54, s52, 0xfffc0080
	s_addc_u32 s55, s53, -1
	s_cmp_eq_u32 s81, 12
	s_cselect_b32 s57, s47, s55
	s_cselect_b32 s56, s77, s54
	s_cselect_b32 s55, s45, s80
	s_cselect_b32 s54, s78, s79
	v_lshl_add_u64 v[200:201], s[52:53], 0, v[136:137]
	s_add_i32 m0, s58, 0xc000
	ds_read_b128 v[188:191], v154
	ds_read_b128 v[192:195], v154 offset:1024
	ds_read_b128 v[196:199], v154 offset:2048
	ds_read_b128 v[206:209], v154 offset:3072
	ds_read_b128 v[210:213], v154 offset:4096
	ds_read_b128 v[214:217], v154 offset:5120
	ds_read_b128 v[218:221], v154 offset:6144
	ds_read_b128 v[222:225], v154 offset:7168
	global_load_lds_dwordx4 v[200:201], off
	v_lshl_add_u64 v[200:201], s[52:53], 0, v[138:139]
	s_add_i32 m0, s58, 0xe000
	s_nop 0
	global_load_lds_dwordx4 v[200:201], off
	s_waitcnt vmcnt(8)
	s_waitcnt lgkmcnt(0)
	s_barrier
; #define PG8_STAGE(bufoff, gbase, voff) do { _Pragma("unroll") for (int _i = 0; _i < 2; ++_i) \
;         __builtin_amdgcn_global_load_lds((const unsigned*)((const char*)(gbase) + (voff)[_i]), (PG8_LAS unsigned*)(lds + (bufoff) + ldsw + _i * 8192), 16, 0, 0); } while (0)
; #define PG8_LDA(dst, b, h) do { _Pragma("unroll") for (int m = 0; m < 4; ++m) _Pragma("unroll") for (int k = 0; k < 2; ++k) dst[m][k] = *(const PG8_LAS bf16x8*)(lds + PG8_SA(b, h) + aoff + m * 2048 + k * 1024); } while (0)
; #define PG8_MMA(ai, bj, At, Bt) do { __builtin_amdgcn_s_setprio(1); _Pragma("unroll") for (int m = 0; m < 4; ++m) _Pragma("unroll") for (int n = 0; n < 2; ++n) _Pragma("unroll") for (int k = 0; k < 2; ++k) \
;         acc[ai][bj][m][n] = __builtin_amdgcn_mfma_f32_16x16x32_bf16(Bt[n][k], At[m][k], acc[ai][bj][m][n], 0, 0, 0); __builtin_amdgcn_s_setprio(0); } while (0)
; #define PG8_WAIT_V(n) asm volatile("s_waitcnt vmcnt(" #n ")" ::: "memory")
; #define PG8_WAIT_L(n) asm volatile("s_waitcnt lgkmcnt(" #n ")" ::: "memory")
; #define PG8_BAR __builtin_amdgcn_s_barrier()
; #define PG8_SCHED __builtin_amdgcn_sched_barrier(0)
; template <class Epi, class Sched, bool ALIGN_EPI = false, bool SP2 = false>
; __device__ __forceinline__ void gemm_phase(PG8_LAS unsigned char* lds, const Gemm g, const Sched& S, const Epi& E) {
;     ...
;             PG8_WAIT_V(8); PG8_WAIT_L(0); PG8_BAR; PG8_MMA(0, 0, At, B0); PG8_MMA(0, 1, At, B1); PG8_BAR; PG8_SCHED;
;             PG8_LDA(At, 0, 1); PG8_STAGE(PG8_SB(0, 0), b2, voffB); PG8_STAGE(PG8_SB(0, 1), b2 + hstep, voffB); PG8_STAGE(PG8_SA(0, 0), a2, voffA);
;             PG8_WAIT_V(8); PG8_WAIT_L(0); PG8_BAR; PG8_MMA(1, 0, At, B0); PG8_MMA(1, 1, At, B1); PG8_BAR; PG8_SCHED;
	s_setprio 1
	s_waitcnt lgkmcnt(0)
	v_mfma_f32_16x16x32_bf16 v[124:127], v[146:149], v[188:191], v[124:127]
	v_mfma_f32_16x16x32_bf16 v[120:123], v[160:163], v[188:191], v[120:123]
	v_mfma_f32_16x16x32_bf16 v[116:119], v[168:171], v[188:191], v[116:119]
	v_mfma_f32_16x16x32_bf16 v[112:115], v[180:183], v[188:191], v[112:115]
	v_mfma_f32_16x16x32_bf16 v[108:111], v[146:149], v[196:199], v[108:111]
	v_mfma_f32_16x16x32_bf16 v[104:107], v[160:163], v[196:199], v[104:107]
	v_mfma_f32_16x16x32_bf16 v[100:103], v[168:171], v[196:199], v[100:103]
	v_mfma_f32_16x16x32_bf16 v[96:99], v[180:183], v[196:199], v[96:99]
	v_mfma_f32_16x16x32_bf16 v[92:95], v[146:149], v[210:213], v[92:95]
	v_mfma_f32_16x16x32_bf16 v[88:91], v[160:163], v[210:213], v[88:91]
	v_mfma_f32_16x16x32_bf16 v[84:87], v[168:171], v[210:213], v[84:87]
	v_mfma_f32_16x16x32_bf16 v[80:83], v[180:183], v[210:213], v[80:83]
	v_mfma_f32_16x16x32_bf16 v[76:79], v[146:149], v[218:221], v[76:79]
	v_mfma_f32_16x16x32_bf16 v[72:75], v[160:163], v[218:221], v[72:75]
	v_mfma_f32_16x16x32_bf16 v[68:71], v[168:171], v[218:221], v[68:71]
	v_mfma_f32_16x16x32_bf16 v[64:67], v[180:183], v[218:221], v[64:67]
	s_setprio 0
	s_setprio 1
	v_mfma_f32_16x16x32_bf16 v[124:127], v[156:159], v[192:195], v[124:127]
	v_mfma_f32_16x16x32_bf16 v[120:123], v[164:167], v[192:195], v[120:123]
	v_mfma_f32_16x16x32_bf16 v[116:119], v[172:175], v[192:195], v[116:119]
	v_mfma_f32_16x16x32_bf16 v[112:115], v[184:187], v[192:195], v[112:115]
	v_mfma_f32_16x16x32_bf16 v[108:111], v[156:159], v[206:209], v[108:111]
	v_mfma_f32_16x16x32_bf16 v[104:107], v[164:167], v[206:209], v[104:107]
	v_mfma_f32_16x16x32_bf16 v[100:103], v[172:175], v[206:209], v[100:103]
	v_mfma_f32_16x16x32_bf16 v[96:99], v[184:187], v[206:209], v[96:99]
	v_mfma_f32_16x16x32_bf16 v[92:95], v[156:159], v[214:217], v[92:95]
	v_mfma_f32_16x16x32_bf16 v[88:91], v[164:167], v[214:217], v[88:91]
	v_mfma_f32_16x16x32_bf16 v[84:87], v[172:175], v[214:217], v[84:87]
	v_mfma_f32_16x16x32_bf16 v[80:83], v[184:187], v[214:217], v[80:83]
	v_mfma_f32_16x16x32_bf16 v[76:79], v[156:159], v[222:225], v[76:79]
	v_mfma_f32_16x16x32_bf16 v[72:75], v[164:167], v[222:225], v[72:75]
	v_mfma_f32_16x16x32_bf16 v[68:71], v[172:175], v[222:225], v[68:71]
	v_mfma_f32_16x16x32_bf16 v[64:67], v[184:187], v[222:225], v[64:67]
	s_setprio 0
	s_barrier
	s_add_i32 s82, s65, s34
	v_lshl_add_u64 v[200:201], s[54:55], 0, v[132:133]
	s_mov_b32 m0, s82
	ds_read_b128 v[188:191], v154 offset:16384
	ds_read_b128 v[192:195], v154 offset:17408
	ds_read_b128 v[196:199], v154 offset:18432
	ds_read_b128 v[206:209], v154 offset:19456
	ds_read_b128 v[210:213], v154 offset:20480
	ds_read_b128 v[214:217], v154 offset:21504
	ds_read_b128 v[218:221], v154 offset:22528
	ds_read_b128 v[222:225], v154 offset:23552
	global_load_lds_dwordx4 v[200:201], off
	s_add_i32 m0, s82, 0x2000
	s_add_u32 s82, s54, 0x40000
	v_lshl_add_u64 v[226:227], s[54:55], 0, v[128:129]
	s_addc_u32 s83, s55, 0
	s_add_i32 s84, s66, s34
	global_load_lds_dwordx4 v[226:227], off
	v_lshl_add_u64 v[228:229], s[82:83], 0, v[132:133]
	s_mov_b32 m0, s84
	global_load_lds_dwordx4 v[228:229], off
	v_lshl_add_u64 v[228:229], s[82:83], 0, v[128:129]
	s_add_i32 m0, s84, 0x2000
	s_nop 0
	global_load_lds_dwordx4 v[228:229], off
	s_waitcnt vmcnt(6)
	s_waitcnt lgkmcnt(0)
	s_barrier
	s_setprio 1
	s_waitcnt lgkmcnt(0)
	v_mfma_f32_16x16x32_bf16 v[60:63], v[146:149], v[188:191], v[60:63]
	v_mfma_f32_16x16x32_bf16 v[56:59], v[160:163], v[188:191], v[56:59]
	v_mfma_f32_16x16x32_bf16 v[52:55], v[168:171], v[188:191], v[52:55]
	v_mfma_f32_16x16x32_bf16 v[48:51], v[180:183], v[188:191], v[48:51]
	v_mfma_f32_16x16x32_bf16 v[44:47], v[146:149], v[196:199], v[44:47]
	v_mfma_f32_16x16x32_bf16 v[40:43], v[160:163], v[196:199], v[40:43]
	v_mfma_f32_16x16x32_bf16 v[36:39], v[168:171], v[196:199], v[36:39]
	v_mfma_f32_16x16x32_bf16 v[32:35], v[180:183], v[196:199], v[32:35]
	v_mfma_f32_16x16x32_bf16 v[28:31], v[146:149], v[210:213], v[28:31]
	v_mfma_f32_16x16x32_bf16 v[24:27], v[160:163], v[210:213], v[24:27]
	v_mfma_f32_16x16x32_bf16 v[20:23], v[168:171], v[210:213], v[20:23]
	v_mfma_f32_16x16x32_bf16 v[16:19], v[180:183], v[210:213], v[16:19]
	v_mfma_f32_16x16x32_bf16 v[12:15], v[146:149], v[218:221], v[12:15]
	v_mfma_f32_16x16x32_bf16 v[8:11], v[160:163], v[218:221], v[8:11]
	v_lshl_add_u64 v[228:229], s[56:57], 0, v[134:135]
	s_mov_b32 m0, s58
	s_nop 0
	global_load_lds_dwordx4 v[228:229], off
	v_mfma_f32_16x16x32_bf16 v[4:7], v[168:171], v[218:221], v[4:7]
	v_mfma_f32_16x16x32_bf16 v[0:3], v[180:183], v[218:221], v[0:3]
	s_setprio 0
	s_setprio 1
	v_mfma_f32_16x16x32_bf16 v[60:63], v[156:159], v[192:195], v[60:63]
	v_mfma_f32_16x16x32_bf16 v[56:59], v[164:167], v[192:195], v[56:59]
	v_mfma_f32_16x16x32_bf16 v[52:55], v[172:175], v[192:195], v[52:55]
	v_mfma_f32_16x16x32_bf16 v[48:51], v[184:187], v[192:195], v[48:51]
	v_mfma_f32_16x16x32_bf16 v[44:47], v[156:159], v[206:209], v[44:47]
	v_mfma_f32_16x16x32_bf16 v[40:43], v[164:167], v[206:209], v[40:43]
	v_mfma_f32_16x16x32_bf16 v[36:39], v[172:175], v[206:209], v[36:39]
	v_mfma_f32_16x16x32_bf16 v[32:35], v[184:187], v[206:209], v[32:35]
	v_mfma_f32_16x16x32_bf16 v[28:31], v[156:159], v[214:217], v[28:31]
	v_mfma_f32_16x16x32_bf16 v[24:27], v[164:167], v[214:217], v[24:27]
	v_mfma_f32_16x16x32_bf16 v[20:23], v[172:175], v[214:217], v[20:23]
	v_mfma_f32_16x16x32_bf16 v[16:19], v[184:187], v[214:217], v[16:19]
	v_mfma_f32_16x16x32_bf16 v[12:15], v[156:159], v[222:225], v[12:15]
	v_mfma_f32_16x16x32_bf16 v[8:11], v[164:167], v[222:225], v[8:11]
	v_lshl_add_u64 v[230:231], s[56:57], 0, v[130:131]
	s_mov_b32 m0, s59
	s_nop 0
	global_load_lds_dwordx4 v[230:231], off
	v_mfma_f32_16x16x32_bf16 v[4:7], v[172:175], v[222:225], v[4:7]
	v_mfma_f32_16x16x32_bf16 v[0:3], v[184:187], v[222:225], v[0:3]
	s_setprio 0
	s_barrier
; #define PG8_STAGE(bufoff, gbase, voff) do { _Pragma("unroll") for (int _i = 0; _i < 2; ++_i) \
;         __builtin_amdgcn_global_load_lds((const unsigned*)((const char*)(gbase) + (voff)[_i]), (PG8_LAS unsigned*)(lds + (bufoff) + ldsw + _i * 8192), 16, 0, 0); } while (0)
; #define PG8_LDA(dst, b, h) do { _Pragma("unroll") for (int m = 0; m < 4; ++m) _Pragma("unroll") for (int k = 0; k < 2; ++k) dst[m][k] = *(const PG8_LAS bf16x8*)(lds + PG8_SA(b, h) + aoff + m * 2048 + k * 1024); } while (0)
; #define PG8_LDB(dst, b, h) do { _Pragma("unroll") for (int n = 0; n < 2; ++n) _Pragma("unroll") for (int k = 0; k < 2; ++k) dst[n][k] = *(const PG8_LAS bf16x8*)(lds + PG8_SB(b, h) + boff + n * 2048 + k * 1024); } while (0)
; #define PG8_MMA(ai, bj, At, Bt) do { __builtin_amdgcn_s_setprio(1); _Pragma("unroll") for (int m = 0; m < 4; ++m) _Pragma("unroll") for (int n = 0; n < 2; ++n) _Pragma("unroll") for (int k = 0; k < 2; ++k) \
;         acc[ai][bj][m][n] = __builtin_amdgcn_mfma_f32_16x16x32_bf16(Bt[n][k], At[m][k], acc[ai][bj][m][n], 0, 0, 0); __builtin_amdgcn_s_setprio(0); } while (0)
; #define PG8_WAIT_V(n) asm volatile("s_waitcnt vmcnt(" #n ")" ::: "memory")
; #define PG8_WAIT_L(n) asm volatile("s_waitcnt lgkmcnt(" #n ")" ::: "memory")
; #define PG8_BAR __builtin_amdgcn_s_barrier()
; #define PG8_SCHED __builtin_amdgcn_sched_barrier(0)
; template <class Epi, class Sched, bool ALIGN_EPI = false, bool SP2 = false>
; __device__ __forceinline__ void gemm_phase(PG8_LAS unsigned char* lds, const Gemm g, const Sched& S, const Epi& E) {
;     ...
;             PG8_LDB(B0, 1, 0); PG8_LDB(B1, 1, 1); PG8_SCHED; PG8_LDA(At, 1, 0); PG8_STAGE(PG8_SA(0, 1), a2 + hstep, voffA);
;             PG8_WAIT_V(8); PG8_WAIT_L(0); PG8_BAR; PG8_MMA(0, 0, At, B0); PG8_MMA(0, 1, At, B1); PG8_BAR; PG8_SCHED;
	s_add_i32 s82, 0, 0x18000
	s_add_i32 s83, 0, 0x1c000
	v_add_u32_e32 v164, s82, v150
	v_add_u32_e32 v179, s83, v150
	ds_read_b128 v[146:149], v164
	ds_read_b128 v[156:159], v164 offset:1024
	ds_read_b128 v[160:163], v164 offset:2048
	ds_read_b128 v[164:167], v164 offset:3072
	ds_read_b128 v[168:171], v179
	ds_read_b128 v[172:175], v179 offset:1024
	ds_read_b128 v[180:183], v179 offset:2048
	ds_read_b128 v[184:187], v179 offset:3072
	s_add_u32 s56, s56, 0x40000
	s_addc_u32 s57, s57, 0
	s_mov_b32 m0, s60
	v_lshl_add_u64 v[232:233], s[56:57], 0, v[134:135]
	ds_read_b128 v[188:191], v154 offset:32768
	ds_read_b128 v[192:195], v154 offset:33792
	ds_read_b128 v[196:199], v154 offset:34816
	ds_read_b128 v[206:209], v154 offset:35840
	ds_read_b128 v[210:213], v154 offset:36864
	ds_read_b128 v[214:217], v154 offset:37888
	ds_read_b128 v[218:221], v154 offset:38912
	ds_read_b128 v[222:225], v154 offset:39936
	global_load_lds_dwordx4 v[232:233], off
	v_lshl_add_u64 v[232:233], s[56:57], 0, v[130:131]
	s_mov_b32 m0, s61
	s_nop 0
	global_load_lds_dwordx4 v[232:233], off
	s_waitcnt vmcnt(8)
	s_waitcnt lgkmcnt(0)
	s_barrier
	s_setprio 1
	s_waitcnt lgkmcnt(0)
	v_mfma_f32_16x16x32_bf16 v[124:127], v[146:149], v[188:191], v[124:127]
	v_mfma_f32_16x16x32_bf16 v[120:123], v[160:163], v[188:191], v[120:123]
	v_mfma_f32_16x16x32_bf16 v[116:119], v[168:171], v[188:191], v[116:119]
	v_mfma_f32_16x16x32_bf16 v[112:115], v[180:183], v[188:191], v[112:115]
	v_mfma_f32_16x16x32_bf16 v[108:111], v[146:149], v[196:199], v[108:111]
	v_mfma_f32_16x16x32_bf16 v[104:107], v[160:163], v[196:199], v[104:107]
	v_mfma_f32_16x16x32_bf16 v[100:103], v[168:171], v[196:199], v[100:103]
	v_mfma_f32_16x16x32_bf16 v[96:99], v[180:183], v[196:199], v[96:99]
	v_mfma_f32_16x16x32_bf16 v[92:95], v[146:149], v[210:213], v[92:95]
	v_mfma_f32_16x16x32_bf16 v[88:91], v[160:163], v[210:213], v[88:91]
	v_mfma_f32_16x16x32_bf16 v[84:87], v[168:171], v[210:213], v[84:87]
	v_mfma_f32_16x16x32_bf16 v[80:83], v[180:183], v[210:213], v[80:83]
	v_mfma_f32_16x16x32_bf16 v[76:79], v[146:149], v[218:221], v[76:79]
	v_mfma_f32_16x16x32_bf16 v[72:75], v[160:163], v[218:221], v[72:75]
	v_mfma_f32_16x16x32_bf16 v[68:71], v[168:171], v[218:221], v[68:71]
	v_mfma_f32_16x16x32_bf16 v[64:67], v[180:183], v[218:221], v[64:67]
	s_setprio 0
	s_setprio 1
	v_mfma_f32_16x16x32_bf16 v[124:127], v[156:159], v[192:195], v[124:127]
	v_mfma_f32_16x16x32_bf16 v[120:123], v[164:167], v[192:195], v[120:123]
	v_mfma_f32_16x16x32_bf16 v[116:119], v[172:175], v[192:195], v[116:119]
	v_mfma_f32_16x16x32_bf16 v[112:115], v[184:187], v[192:195], v[112:115]
	v_mfma_f32_16x16x32_bf16 v[108:111], v[156:159], v[206:209], v[108:111]
	v_mfma_f32_16x16x32_bf16 v[104:107], v[164:167], v[206:209], v[104:107]
	v_mfma_f32_16x16x32_bf16 v[100:103], v[172:175], v[206:209], v[100:103]
	v_mfma_f32_16x16x32_bf16 v[96:99], v[184:187], v[206:209], v[96:99]
	v_mfma_f32_16x16x32_bf16 v[92:95], v[156:159], v[214:217], v[92:95]
	v_mfma_f32_16x16x32_bf16 v[88:91], v[164:167], v[214:217], v[88:91]
	v_mfma_f32_16x16x32_bf16 v[84:87], v[172:175], v[214:217], v[84:87]
	v_mfma_f32_16x16x32_bf16 v[80:83], v[184:187], v[214:217], v[80:83]
	v_mfma_f32_16x16x32_bf16 v[76:79], v[156:159], v[222:225], v[76:79]
	v_mfma_f32_16x16x32_bf16 v[72:75], v[164:167], v[222:225], v[72:75]
	v_mfma_f32_16x16x32_bf16 v[68:71], v[172:175], v[222:225], v[68:71]
	v_mfma_f32_16x16x32_bf16 v[64:67], v[184:187], v[222:225], v[64:67]
	s_setprio 0
	s_barrier
; #define PG8_STAGE(bufoff, gbase, voff) do { _Pragma("unroll") for (int _i = 0; _i < 2; ++_i) \
;         __builtin_amdgcn_global_load_lds((const unsigned*)((const char*)(gbase) + (voff)[_i]), (PG8_LAS unsigned*)(lds + (bufoff) + ldsw + _i * 8192), 16, 0, 0); } while (0)
; #define PG8_LDA(dst, b, h) do { _Pragma("unroll") for (int m = 0; m < 4; ++m) _Pragma("unroll") for (int k = 0; k < 2; ++k) dst[m][k] = *(const PG8_LAS bf16x8*)(lds + PG8_SA(b, h) + aoff + m * 2048 + k * 1024); } while (0)
; #define PG8_MMA(ai, bj, At, Bt) do { __builtin_amdgcn_s_setprio(1); _Pragma("unroll") for (int m = 0; m < 4; ++m) _Pragma("unroll") for (int n = 0; n < 2; ++n) _Pragma("unroll") for (int k = 0; k < 2; ++k) \
;         acc[ai][bj][m][n] = __builtin_amdgcn_mfma_f32_16x16x32_bf16(Bt[n][k], At[m][k], acc[ai][bj][m][n], 0, 0, 0); __builtin_amdgcn_s_setprio(0); } while (0)
; #define PG8_WAIT_V(n) asm volatile("s_waitcnt vmcnt(" #n ")" ::: "memory")
; #define PG8_WAIT_L(n) asm volatile("s_waitcnt lgkmcnt(" #n ")" ::: "memory")
; #define PG8_BAR __builtin_amdgcn_s_barrier()
; #define PG8_SCHED __builtin_amdgcn_sched_barrier(0)
; template <class Epi, class Sched, bool ALIGN_EPI = false, bool SP2 = false>
; __device__ __forceinline__ void gemm_phase(PG8_LAS unsigned char* lds, const Gemm g, const Sched& S, const Epi& E) {
;     ...
;         for (int t = 0; t < nt; t += 2) {
;             const bool last = (t == nt - 2);
;     ...
;             PG8_LDA(At, 1, 1); PG8_STAGE(PG8_SB(1, 0), b3, voffB); PG8_STAGE(PG8_SB(1, 1), b3 + hstep, voffB); PG8_STAGE(PG8_SA(1, 0), a3, voffA);
;             PG8_WAIT_V(8); PG8_WAIT_L(0); PG8_BAR; PG8_MMA(1, 0, At, B0); PG8_MMA(1, 1, At, B1); PG8_BAR; PG8_SCHED;
	s_add_i32 s56, s82, s34
	v_lshl_add_u64 v[200:201], v[200:201], 0, s[26:27]
	s_mov_b32 m0, s56
	ds_read_b128 v[188:191], v154 offset:49152
	ds_read_b128 v[192:195], v154 offset:50176
	ds_read_b128 v[196:199], v154 offset:51200
	ds_read_b128 v[206:209], v154 offset:52224
	ds_read_b128 v[210:213], v154 offset:53248
	ds_read_b128 v[214:217], v154 offset:54272
	ds_read_b128 v[218:221], v154 offset:55296
	ds_read_b128 v[222:225], v154 offset:56320
	global_load_lds_dwordx4 v[200:201], off
	s_add_i32 m0, s56, 0x2000
	s_add_u32 s54, s54, 0x40080
	v_lshl_add_u64 v[200:201], v[226:227], 0, s[26:27]
	s_addc_u32 s55, s55, 0
	s_add_i32 s56, s83, s34
	global_load_lds_dwordx4 v[200:201], off
	v_lshl_add_u64 v[200:201], s[54:55], 0, v[132:133]
	s_mov_b32 m0, s56
	s_nop 0
	global_load_lds_dwordx4 v[200:201], off
	v_lshl_add_u64 v[200:201], s[54:55], 0, v[128:129]
	s_add_i32 m0, s56, 0x2000
	s_nop 0
	global_load_lds_dwordx4 v[200:201], off
	s_waitcnt vmcnt(6)
	s_waitcnt lgkmcnt(0)
	s_barrier
	s_setprio 1
	s_waitcnt lgkmcnt(0)
	v_mfma_f32_16x16x32_bf16 v[60:63], v[146:149], v[188:191], v[60:63]
	v_mfma_f32_16x16x32_bf16 v[56:59], v[160:163], v[188:191], v[56:59]
	v_mfma_f32_16x16x32_bf16 v[52:55], v[168:171], v[188:191], v[52:55]
	v_mfma_f32_16x16x32_bf16 v[48:51], v[180:183], v[188:191], v[48:51]
	v_mfma_f32_16x16x32_bf16 v[44:47], v[146:149], v[196:199], v[44:47]
	v_mfma_f32_16x16x32_bf16 v[40:43], v[160:163], v[196:199], v[40:43]
	v_mfma_f32_16x16x32_bf16 v[36:39], v[168:171], v[196:199], v[36:39]
	v_mfma_f32_16x16x32_bf16 v[32:35], v[180:183], v[196:199], v[32:35]
	v_mfma_f32_16x16x32_bf16 v[28:31], v[146:149], v[210:213], v[28:31]
	v_mfma_f32_16x16x32_bf16 v[24:27], v[160:163], v[210:213], v[24:27]
	v_mfma_f32_16x16x32_bf16 v[20:23], v[168:171], v[210:213], v[20:23]
	v_mfma_f32_16x16x32_bf16 v[16:19], v[180:183], v[210:213], v[16:19]
	v_mfma_f32_16x16x32_bf16 v[12:15], v[146:149], v[218:221], v[12:15]
	v_mfma_f32_16x16x32_bf16 v[8:11], v[160:163], v[218:221], v[8:11]
	v_lshl_add_u64 v[200:201], v[228:229], 0, s[26:27]
	s_mov_b32 m0, s63
	s_nop 0
	global_load_lds_dwordx4 v[200:201], off
	v_mfma_f32_16x16x32_bf16 v[4:7], v[168:171], v[218:221], v[4:7]
	v_mfma_f32_16x16x32_bf16 v[0:3], v[180:183], v[218:221], v[0:3]
	s_setprio 0
	s_setprio 1
	v_mfma_f32_16x16x32_bf16 v[60:63], v[156:159], v[192:195], v[60:63]
	v_mfma_f32_16x16x32_bf16 v[56:59], v[164:167], v[192:195], v[56:59]
	v_mfma_f32_16x16x32_bf16 v[52:55], v[172:175], v[192:195], v[52:55]
	v_mfma_f32_16x16x32_bf16 v[48:51], v[184:187], v[192:195], v[48:51]
	v_mfma_f32_16x16x32_bf16 v[44:47], v[156:159], v[206:209], v[44:47]
	v_mfma_f32_16x16x32_bf16 v[40:43], v[164:167], v[206:209], v[40:43]
	v_mfma_f32_16x16x32_bf16 v[36:39], v[172:175], v[206:209], v[36:39]
	v_mfma_f32_16x16x32_bf16 v[32:35], v[184:187], v[206:209], v[32:35]
	v_mfma_f32_16x16x32_bf16 v[28:31], v[156:159], v[214:217], v[28:31]
	v_mfma_f32_16x16x32_bf16 v[24:27], v[164:167], v[214:217], v[24:27]
	v_mfma_f32_16x16x32_bf16 v[20:23], v[172:175], v[214:217], v[20:23]
	v_mfma_f32_16x16x32_bf16 v[16:19], v[184:187], v[214:217], v[16:19]
	v_mfma_f32_16x16x32_bf16 v[12:15], v[156:159], v[222:225], v[12:15]
	v_mfma_f32_16x16x32_bf16 v[8:11], v[164:167], v[222:225], v[8:11]
	v_lshl_add_u64 v[200:201], v[230:231], 0, s[26:27]
	s_mov_b32 m0, s64
	s_nop 0
	global_load_lds_dwordx4 v[200:201], off
	v_mfma_f32_16x16x32_bf16 v[4:7], v[172:175], v[222:225], v[4:7]
	v_mfma_f32_16x16x32_bf16 v[0:3], v[184:187], v[222:225], v[0:3]
	s_setprio 0
	s_barrier
	s_add_i32 s81, s81, 2
	s_add_u32 s52, s52, 0x100
	s_addc_u32 s53, s53, 0
	s_add_u32 s79, s79, 0x100
	s_addc_u32 s80, s80, 0
	s_cmp_gt_u32 s81, 13
	s_cbranch_scc0 .LBB0_1681
	s_and_b64 vcc, exec, s[28:29]
	s_cbranch_vccz .LBB0_1684
	s_barrier

; #define PG8_STAGE(bufoff, gbase, voff) do { _Pragma("unroll") for (int _i = 0; _i < 2; ++_i) \
;         __builtin_amdgcn_global_load_lds((const unsigned*)((const char*)(gbase) + (voff)[_i]), (PG8_LAS unsigned*)(lds + (bufoff) + ldsw + _i * 8192), 16, 0, 0); } while (0)
; #define PG8_LDA(dst, b, h) do { _Pragma("unroll") for (int m = 0; m < 4; ++m) _Pragma("unroll") for (int k = 0; k < 2; ++k) dst[m][k] = *(const PG8_LAS bf16x8*)(lds + PG8_SA(b, h) + aoff + m * 2048 + k * 1024); } while (0)
; #define PG8_LDB(dst, b, h) do { _Pragma("unroll") for (int n = 0; n < 2; ++n) _Pragma("unroll") for (int k = 0; k < 2; ++k) dst[n][k] = *(const PG8_LAS bf16x8*)(lds + PG8_SB(b, h) + boff + n * 2048 + k * 1024); } while (0)
; #define PG8_WAIT_V(n) asm volatile("s_waitcnt vmcnt(" #n ")" ::: "memory")
; #define PG8_WAIT_L(n) asm volatile("s_waitcnt lgkmcnt(" #n ")" ::: "memory")
; #define PG8_BAR __builtin_amdgcn_s_barrier()
; #define PG8_SCHED __builtin_amdgcn_sched_barrier(0)
; template <class Epi, class Sched, bool ALIGN_EPI = false, bool SP2 = false>
; __device__ __forceinline__ void gemm_phase(PG8_LAS unsigned char* lds, const Gemm g, const Sched& S, const Epi& E) {
;     ...
;         const bool has_next = S.next(ui + 1, nxt);
;         const char* nA = has_next ? (const char*)g.A + (size_t)nxt.pm * tstep : cA; const char* nB = has_next ? (const char*)g.Bt + (size_t)nxt.pn * tstep : cB;
;         for (int t = 0; t < nt; t += 2) {
;             const bool last = (t == nt - 2);
;             const char* a1 = cA + (size_t)(t + 1) * kstep;
;             const char* a2 = last ? nA : cA + (size_t)(t + 2) * kstep; const char* b2 = last ? nB : cB + (size_t)(t + 2) * kstep;
;             const char* a3 = a2 + kstep; const char* b3 = b2 + kstep;
;             if (last && has_next) S.a_ready(nxt);
;             if constexpr (SP2) {
;             PG8_LDB(B0, 0, 0); PG8_LDB(B1, 0, 1); PG8_SCHED; PG8_LDA(At, 0, 0); PG8_STAGE(PG8_SA(1, 1), a1 + hstep, voffA);
;             PG8_WAIT_V(8); PG8_WAIT_L(0); PG8_BAR; PG8_MMA(0, 0, At, B0); PG8_MMA(0, 1, At, B1); PG8_BAR; PG8_SCHED;
;             PG8_LDA(At, 0, 1); PG8_STAGE(PG8_SB(0, 0), b2, voffB); PG8_STAGE(PG8_SB(0, 1), b2 + hstep, voffB); PG8_STAGE(PG8_SA(0, 0), a2, voffA);
;             PG8_WAIT_V(8); PG8_WAIT_L(0); PG8_BAR; PG8_MMA(1, 0, At, B0); PG8_MMA(1, 1, At, B1); PG8_BAR; PG8_SCHED;
.LBB0_1815:
	s_ashr_i32 s29, s28, 31
	s_lshl_b64 s[36:37], s[28:29], 18
	s_add_u32 s36, s92, s36
	s_addc_u32 s37, s93, s37
	s_and_b64 s[38:39], s[6:7], exec
	s_cselect_b32 s29, s37, s45
	s_cselect_b32 s41, s36, s44
	s_ashr_i32 s27, s26, 31
	s_lshl_b64 s[38:39], s[26:27], 18
	s_add_u32 s38, s3, s38
	s_addc_u32 s39, s14, s39
	s_and_b64 s[48:49], s[6:7], exec
	s_cselect_b32 s27, s39, s47
	s_cselect_b32 s58, s38, s46
	s_add_u32 s44, s44, 0x20080
	s_addc_u32 s45, s45, 0
	s_add_u32 s59, s46, 0x100
	s_addc_u32 s60, s47, 0
	s_mov_b32 s61, -2
	s_waitcnt lgkmcnt(0)
	ds_read_b128 v[144:147], v151
	ds_read_b128 v[156:159], v151 offset:1024
	ds_read_b128 v[160:163], v151 offset:2048
	ds_read_b128 v[164:167], v151 offset:3072
	ds_read_b128 v[168:171], v152
	ds_read_b128 v[172:175], v152 offset:1024
	ds_read_b128 v[176:179], v152 offset:2048
	ds_read_b128 v[180:183], v152 offset:3072
	s_add_u32 s46, s44, 0xfffe0080
	s_addc_u32 s47, s45, -1
	s_cmp_eq_u32 s61, 4
	s_cselect_b32 s49, s29, s47
	s_cselect_b32 s48, s41, s46
	s_cselect_b32 s47, s27, s60
	s_cselect_b32 s46, s58, s59
	v_lshl_add_u64 v[218:219], s[44:45], 0, v[136:137]
	s_add_i32 m0, s33, 0xc000
	ds_read_b128 v[184:187], v153
	ds_read_b128 v[188:191], v153 offset:1024
	ds_read_b128 v[192:195], v153 offset:2048
	ds_read_b128 v[196:199], v153 offset:3072
	ds_read_b128 v[200:203], v153 offset:4096
	ds_read_b128 v[206:209], v153 offset:5120
	ds_read_b128 v[210:213], v153 offset:6144
	ds_read_b128 v[214:217], v153 offset:7168
	global_load_lds_dwordx4 v[218:219], off
	v_lshl_add_u64 v[218:219], s[44:45], 0, v[138:139]
	s_add_i32 m0, s33, 0xe000
	s_nop 0
	global_load_lds_dwordx4 v[218:219], off
	s_waitcnt vmcnt(8)
	s_waitcnt lgkmcnt(0)
	s_barrier
	s_setprio 1
	s_waitcnt lgkmcnt(0)
	v_mfma_f32_16x16x32_bf16 v[124:127], v[144:147], v[184:187], 0
	v_mfma_f32_16x16x32_bf16 v[120:123], v[160:163], v[184:187], 0
	v_mfma_f32_16x16x32_bf16 v[116:119], v[168:171], v[184:187], 0
	v_mfma_f32_16x16x32_bf16 v[112:115], v[176:179], v[184:187], 0
	v_mfma_f32_16x16x32_bf16 v[108:111], v[144:147], v[192:195], 0
	v_mfma_f32_16x16x32_bf16 v[104:107], v[160:163], v[192:195], 0
	v_mfma_f32_16x16x32_bf16 v[100:103], v[168:171], v[192:195], 0
	v_mfma_f32_16x16x32_bf16 v[96:99], v[176:179], v[192:195], 0
	v_mfma_f32_16x16x32_bf16 v[92:95], v[144:147], v[200:203], 0
	v_mfma_f32_16x16x32_bf16 v[88:91], v[160:163], v[200:203], 0
	v_mfma_f32_16x16x32_bf16 v[84:87], v[168:171], v[200:203], 0
	v_mfma_f32_16x16x32_bf16 v[80:83], v[176:179], v[200:203], 0
	v_mfma_f32_16x16x32_bf16 v[76:79], v[144:147], v[210:213], 0
	v_mfma_f32_16x16x32_bf16 v[72:75], v[160:163], v[210:213], 0
	v_mfma_f32_16x16x32_bf16 v[68:71], v[168:171], v[210:213], 0
	v_mfma_f32_16x16x32_bf16 v[64:67], v[176:179], v[210:213], 0
	s_setprio 0
	s_setprio 1
	v_mfma_f32_16x16x32_bf16 v[124:127], v[156:159], v[188:191], v[124:127]
	v_mfma_f32_16x16x32_bf16 v[120:123], v[164:167], v[188:191], v[120:123]
	v_mfma_f32_16x16x32_bf16 v[116:119], v[172:175], v[188:191], v[116:119]
	v_mfma_f32_16x16x32_bf16 v[112:115], v[180:183], v[188:191], v[112:115]
	v_mfma_f32_16x16x32_bf16 v[108:111], v[156:159], v[196:199], v[108:111]
	v_mfma_f32_16x16x32_bf16 v[104:107], v[164:167], v[196:199], v[104:107]
	v_mfma_f32_16x16x32_bf16 v[100:103], v[172:175], v[196:199], v[100:103]
	v_mfma_f32_16x16x32_bf16 v[96:99], v[180:183], v[196:199], v[96:99]
	v_mfma_f32_16x16x32_bf16 v[92:95], v[156:159], v[206:209], v[92:95]
	v_mfma_f32_16x16x32_bf16 v[88:91], v[164:167], v[206:209], v[88:91]
	v_mfma_f32_16x16x32_bf16 v[84:87], v[172:175], v[206:209], v[84:87]
	v_mfma_f32_16x16x32_bf16 v[80:83], v[180:183], v[206:209], v[80:83]
	v_mfma_f32_16x16x32_bf16 v[76:79], v[156:159], v[214:217], v[76:79]
	v_mfma_f32_16x16x32_bf16 v[72:75], v[164:167], v[214:217], v[72:75]
	v_mfma_f32_16x16x32_bf16 v[68:71], v[172:175], v[214:217], v[68:71]
	v_mfma_f32_16x16x32_bf16 v[64:67], v[180:183], v[214:217], v[64:67]
	s_setprio 0
	s_barrier
	s_add_i32 s62, s54, s15
	v_lshl_add_u64 v[218:219], s[46:47], 0, v[130:131]
	s_mov_b32 m0, s62
	ds_read_b128 v[184:187], v153 offset:16384
	ds_read_b128 v[188:191], v153 offset:17408
	ds_read_b128 v[192:195], v153 offset:18432
	ds_read_b128 v[196:199], v153 offset:19456
	ds_read_b128 v[200:203], v153 offset:20480
	ds_read_b128 v[206:209], v153 offset:21504
	ds_read_b128 v[210:213], v153 offset:22528
	ds_read_b128 v[214:217], v153 offset:23552
	global_load_lds_dwordx4 v[218:219], off
	s_add_i32 m0, s62, 0x2000
	s_add_u32 s62, s46, 0x20000
	v_lshl_add_u64 v[220:221], s[46:47], 0, v[134:135]
	s_addc_u32 s63, s47, 0
	s_add_i32 s64, s55, s15
	global_load_lds_dwordx4 v[220:221], off
	v_lshl_add_u64 v[222:223], s[62:63], 0, v[130:131]
	s_mov_b32 m0, s64
	global_load_lds_dwordx4 v[222:223], off
	v_lshl_add_u64 v[222:223], s[62:63], 0, v[134:135]
	s_add_i32 m0, s64, 0x2000
	s_nop 0
	global_load_lds_dwordx4 v[222:223], off
	s_waitcnt vmcnt(6)
	s_waitcnt lgkmcnt(0)
	s_barrier
; #define PG8_STAGE(bufoff, gbase, voff) do { _Pragma("unroll") for (int _i = 0; _i < 2; ++_i) \
;         __builtin_amdgcn_global_load_lds((const unsigned*)((const char*)(gbase) + (voff)[_i]), (PG8_LAS unsigned*)(lds + (bufoff) + ldsw + _i * 8192), 16, 0, 0); } while (0)
; #define PG8_LDA(dst, b, h) do { _Pragma("unroll") for (int m = 0; m < 4; ++m) _Pragma("unroll") for (int k = 0; k < 2; ++k) dst[m][k] = *(const PG8_LAS bf16x8*)(lds + PG8_SA(b, h) + aoff + m * 2048 + k * 1024); } while (0)
; #define PG8_LDB(dst, b, h) do { _Pragma("unroll") for (int n = 0; n < 2; ++n) _Pragma("unroll") for (int k = 0; k < 2; ++k) dst[n][k] = *(const PG8_LAS bf16x8*)(lds + PG8_SB(b, h) + boff + n * 2048 + k * 1024); } while (0)
; #define PG8_MMA(ai, bj, At, Bt) do { __builtin_amdgcn_s_setprio(1); _Pragma("unroll") for (int m = 0; m < 4; ++m) _Pragma("unroll") for (int n = 0; n < 2; ++n) _Pragma("unroll") for (int k = 0; k < 2; ++k) \
;         acc[ai][bj][m][n] = __builtin_amdgcn_mfma_f32_16x16x32_bf16(Bt[n][k], At[m][k], acc[ai][bj][m][n], 0, 0, 0); __builtin_amdgcn_s_setprio(0); } while (0)
; #define PG8_WAIT_V(n) asm volatile("s_waitcnt vmcnt(" #n ")" ::: "memory")
; #define PG8_WAIT_L(n) asm volatile("s_waitcnt lgkmcnt(" #n ")" ::: "memory")
; #define PG8_BAR __builtin_amdgcn_s_barrier()
; #define PG8_SCHED __builtin_amdgcn_sched_barrier(0)
; template <class Epi, class Sched, bool ALIGN_EPI = false, bool SP2 = false>
; __device__ __forceinline__ void gemm_phase(PG8_LAS unsigned char* lds, const Gemm g, const Sched& S, const Epi& E) {
;     ...
;             PG8_WAIT_V(8); PG8_WAIT_L(0); PG8_BAR; PG8_MMA(1, 0, At, B0); PG8_MMA(1, 1, At, B1); PG8_BAR; PG8_SCHED;
;             PG8_LDB(B0, 1, 0); PG8_LDB(B1, 1, 1); PG8_SCHED; PG8_LDA(At, 1, 0); PG8_STAGE(PG8_SA(0, 1), a2 + hstep, voffA);
;             PG8_WAIT_V(8); PG8_WAIT_L(0); PG8_BAR; PG8_MMA(0, 0, At, B0); PG8_MMA(0, 1, At, B1); PG8_BAR; PG8_SCHED;
	s_setprio 1
	s_waitcnt lgkmcnt(0)
	v_mfma_f32_16x16x32_bf16 v[60:63], v[144:147], v[184:187], 0
	v_mfma_f32_16x16x32_bf16 v[56:59], v[160:163], v[184:187], 0
	v_mfma_f32_16x16x32_bf16 v[52:55], v[168:171], v[184:187], 0
	v_mfma_f32_16x16x32_bf16 v[48:51], v[176:179], v[184:187], 0
	v_mfma_f32_16x16x32_bf16 v[44:47], v[144:147], v[192:195], 0
	v_mfma_f32_16x16x32_bf16 v[40:43], v[160:163], v[192:195], 0
	v_mfma_f32_16x16x32_bf16 v[36:39], v[168:171], v[192:195], 0
	v_mfma_f32_16x16x32_bf16 v[32:35], v[176:179], v[192:195], 0
	v_mfma_f32_16x16x32_bf16 v[28:31], v[144:147], v[200:203], 0
	v_mfma_f32_16x16x32_bf16 v[24:27], v[160:163], v[200:203], 0
	v_mfma_f32_16x16x32_bf16 v[20:23], v[168:171], v[200:203], 0
	v_mfma_f32_16x16x32_bf16 v[16:19], v[176:179], v[200:203], 0
	v_mfma_f32_16x16x32_bf16 v[12:15], v[144:147], v[210:213], 0
	v_mfma_f32_16x16x32_bf16 v[8:11], v[160:163], v[210:213], 0
	v_lshl_add_u64 v[222:223], s[48:49], 0, v[128:129]
	s_mov_b32 m0, s33
	s_nop 0
	global_load_lds_dwordx4 v[222:223], off
	v_mfma_f32_16x16x32_bf16 v[4:7], v[168:171], v[210:213], 0
	v_mfma_f32_16x16x32_bf16 v[0:3], v[176:179], v[210:213], 0
	s_setprio 0
	s_setprio 1
	v_mfma_f32_16x16x32_bf16 v[60:63], v[156:159], v[188:191], v[60:63]
	v_mfma_f32_16x16x32_bf16 v[56:59], v[164:167], v[188:191], v[56:59]
	v_mfma_f32_16x16x32_bf16 v[52:55], v[172:175], v[188:191], v[52:55]
	v_mfma_f32_16x16x32_bf16 v[48:51], v[180:183], v[188:191], v[48:51]
	v_mfma_f32_16x16x32_bf16 v[44:47], v[156:159], v[196:199], v[44:47]
	v_mfma_f32_16x16x32_bf16 v[40:43], v[164:167], v[196:199], v[40:43]
	v_mfma_f32_16x16x32_bf16 v[36:39], v[172:175], v[196:199], v[36:39]
	v_mfma_f32_16x16x32_bf16 v[32:35], v[180:183], v[196:199], v[32:35]
	v_mfma_f32_16x16x32_bf16 v[28:31], v[156:159], v[206:209], v[28:31]
	v_mfma_f32_16x16x32_bf16 v[24:27], v[164:167], v[206:209], v[24:27]
	v_mfma_f32_16x16x32_bf16 v[20:23], v[172:175], v[206:209], v[20:23]
	v_mfma_f32_16x16x32_bf16 v[16:19], v[180:183], v[206:209], v[16:19]
	v_mfma_f32_16x16x32_bf16 v[12:15], v[156:159], v[214:217], v[12:15]
	v_mfma_f32_16x16x32_bf16 v[8:11], v[164:167], v[214:217], v[8:11]
	v_lshl_add_u64 v[224:225], s[48:49], 0, v[132:133]
	s_mov_b32 m0, s34
	s_nop 0
	global_load_lds_dwordx4 v[224:225], off
	v_mfma_f32_16x16x32_bf16 v[4:7], v[172:175], v[214:217], v[4:7]
	v_mfma_f32_16x16x32_bf16 v[0:3], v[180:183], v[214:217], v[0:3]
	s_setprio 0
	s_barrier
	s_add_i32 s62, 0, 0x18000
	v_add_u32_e32 v155, s62, v149
	s_add_i32 s63, 0, 0x1c000
	ds_read_b128 v[144:147], v155
	ds_read_b128 v[156:159], v155 offset:1024
	ds_read_b128 v[160:163], v155 offset:2048
	ds_read_b128 v[164:167], v155 offset:3072
	v_add_u32_e32 v155, s63, v149
	ds_read_b128 v[168:171], v155
	ds_read_b128 v[172:175], v155 offset:1024
	ds_read_b128 v[176:179], v155 offset:2048
	ds_read_b128 v[180:183], v155 offset:3072
	s_add_u32 s48, s48, 0x20000
	s_addc_u32 s49, s49, 0
	s_mov_b32 m0, s43
	v_lshl_add_u64 v[226:227], s[48:49], 0, v[128:129]
	ds_read_b128 v[184:187], v153 offset:32768
	ds_read_b128 v[188:191], v153 offset:33792
	ds_read_b128 v[192:195], v153 offset:34816
	ds_read_b128 v[196:199], v153 offset:35840
	ds_read_b128 v[200:203], v153 offset:36864
	ds_read_b128 v[206:209], v153 offset:37888
	ds_read_b128 v[210:213], v153 offset:38912
	ds_read_b128 v[214:217], v153 offset:39936
	global_load_lds_dwordx4 v[226:227], off
	v_lshl_add_u64 v[226:227], s[48:49], 0, v[132:133]
	s_mov_b32 m0, s50
	s_nop 0
	global_load_lds_dwordx4 v[226:227], off
	s_waitcnt vmcnt(8)
	s_waitcnt lgkmcnt(0)
	s_barrier
	s_setprio 1
	s_waitcnt lgkmcnt(0)
	v_mfma_f32_16x16x32_bf16 v[124:127], v[144:147], v[184:187], v[124:127]
	v_mfma_f32_16x16x32_bf16 v[120:123], v[160:163], v[184:187], v[120:123]
	v_mfma_f32_16x16x32_bf16 v[116:119], v[168:171], v[184:187], v[116:119]
	v_mfma_f32_16x16x32_bf16 v[112:115], v[176:179], v[184:187], v[112:115]
	v_mfma_f32_16x16x32_bf16 v[108:111], v[144:147], v[192:195], v[108:111]
	v_mfma_f32_16x16x32_bf16 v[104:107], v[160:163], v[192:195], v[104:107]
	v_mfma_f32_16x16x32_bf16 v[100:103], v[168:171], v[192:195], v[100:103]
	v_mfma_f32_16x16x32_bf16 v[96:99], v[176:179], v[192:195], v[96:99]
	v_mfma_f32_16x16x32_bf16 v[92:95], v[144:147], v[200:203], v[92:95]
	v_mfma_f32_16x16x32_bf16 v[88:91], v[160:163], v[200:203], v[88:91]
	v_mfma_f32_16x16x32_bf16 v[84:87], v[168:171], v[200:203], v[84:87]
	v_mfma_f32_16x16x32_bf16 v[80:83], v[176:179], v[200:203], v[80:83]
	v_mfma_f32_16x16x32_bf16 v[76:79], v[144:147], v[210:213], v[76:79]
	v_mfma_f32_16x16x32_bf16 v[72:75], v[160:163], v[210:213], v[72:75]
	v_mfma_f32_16x16x32_bf16 v[68:71], v[168:171], v[210:213], v[68:71]
	v_mfma_f32_16x16x32_bf16 v[64:67], v[176:179], v[210:213], v[64:67]
	s_setprio 0
	s_setprio 1
	v_mfma_f32_16x16x32_bf16 v[124:127], v[156:159], v[188:191], v[124:127]
	v_mfma_f32_16x16x32_bf16 v[120:123], v[164:167], v[188:191], v[120:123]
	v_mfma_f32_16x16x32_bf16 v[116:119], v[172:175], v[188:191], v[116:119]
	v_mfma_f32_16x16x32_bf16 v[112:115], v[180:183], v[188:191], v[112:115]
	v_mfma_f32_16x16x32_bf16 v[108:111], v[156:159], v[196:199], v[108:111]
	v_mfma_f32_16x16x32_bf16 v[104:107], v[164:167], v[196:199], v[104:107]
	v_mfma_f32_16x16x32_bf16 v[100:103], v[172:175], v[196:199], v[100:103]
	v_mfma_f32_16x16x32_bf16 v[96:99], v[180:183], v[196:199], v[96:99]
	v_mfma_f32_16x16x32_bf16 v[92:95], v[156:159], v[206:209], v[92:95]
	v_mfma_f32_16x16x32_bf16 v[88:91], v[164:167], v[206:209], v[88:91]
	v_mfma_f32_16x16x32_bf16 v[84:87], v[172:175], v[206:209], v[84:87]
	v_mfma_f32_16x16x32_bf16 v[80:83], v[180:183], v[206:209], v[80:83]
	v_mfma_f32_16x16x32_bf16 v[76:79], v[156:159], v[214:217], v[76:79]
	v_mfma_f32_16x16x32_bf16 v[72:75], v[164:167], v[214:217], v[72:75]
	v_mfma_f32_16x16x32_bf16 v[68:71], v[172:175], v[214:217], v[68:71]
	v_mfma_f32_16x16x32_bf16 v[64:67], v[180:183], v[214:217], v[64:67]
	s_setprio 0
	s_barrier
; #define PG8_STAGE(bufoff, gbase, voff) do { _Pragma("unroll") for (int _i = 0; _i < 2; ++_i) \
;         __builtin_amdgcn_global_load_lds((const unsigned*)((const char*)(gbase) + (voff)[_i]), (PG8_LAS unsigned*)(lds + (bufoff) + ldsw + _i * 8192), 16, 0, 0); } while (0)
; #define PG8_LDA(dst, b, h) do { _Pragma("unroll") for (int m = 0; m < 4; ++m) _Pragma("unroll") for (int k = 0; k < 2; ++k) dst[m][k] = *(const PG8_LAS bf16x8*)(lds + PG8_SA(b, h) + aoff + m * 2048 + k * 1024); } while (0)
; #define PG8_LDB(dst, b, h) do { _Pragma("unroll") for (int n = 0; n < 2; ++n) _Pragma("unroll") for (int k = 0; k < 2; ++k) dst[n][k] = *(const PG8_LAS bf16x8*)(lds + PG8_SB(b, h) + boff + n * 2048 + k * 1024); } while (0)
; #define PG8_MMA(ai, bj, At, Bt) do { __builtin_amdgcn_s_setprio(1); _Pragma("unroll") for (int m = 0; m < 4; ++m) _Pragma("unroll") for (int n = 0; n < 2; ++n) _Pragma("unroll") for (int k = 0; k < 2; ++k) \
;         acc[ai][bj][m][n] = __builtin_amdgcn_mfma_f32_16x16x32_bf16(Bt[n][k], At[m][k], acc[ai][bj][m][n], 0, 0, 0); __builtin_amdgcn_s_setprio(0); } while (0)
; #define PG8_WAIT_V(n) asm volatile("s_waitcnt vmcnt(" #n ")" ::: "memory")
; #define PG8_WAIT_L(n) asm volatile("s_waitcnt lgkmcnt(" #n ")" ::: "memory")
; #define PG8_BAR __builtin_amdgcn_s_barrier()
; #define PG8_SCHED __builtin_amdgcn_sched_barrier(0)
; template <class Epi, class Sched, bool ALIGN_EPI = false, bool SP2 = false>
; __device__ __forceinline__ void gemm_phase(PG8_LAS unsigned char* lds, const Gemm g, const Sched& S, const Epi& E) {
;     ...
;             PG8_LDB(B0, 0, 0); PG8_LDB(B1, 0, 1); PG8_SCHED; PG8_LDA(At, 0, 0); PG8_STAGE(PG8_SA(1, 1), a1 + hstep, voffA);
;     ...
;             PG8_LDA(At, 1, 1); PG8_STAGE(PG8_SB(1, 0), b3, voffB); PG8_STAGE(PG8_SB(1, 1), b3 + hstep, voffB); PG8_STAGE(PG8_SA(1, 0), a3, voffA);
;             PG8_WAIT_V(8); PG8_WAIT_L(0); PG8_BAR; PG8_MMA(1, 0, At, B0); PG8_MMA(1, 1, At, B1); PG8_BAR; PG8_SCHED;
	s_add_i32 s48, s62, s15
	v_lshl_add_u64 v[218:219], v[218:219], 0, s[12:13]
	s_mov_b32 m0, s48
	ds_read_b128 v[184:187], v153 offset:49152
	ds_read_b128 v[188:191], v153 offset:50176
	ds_read_b128 v[192:195], v153 offset:51200
	ds_read_b128 v[196:199], v153 offset:52224
	ds_read_b128 v[200:203], v153 offset:53248
	ds_read_b128 v[206:209], v153 offset:54272
	ds_read_b128 v[210:213], v153 offset:55296
	ds_read_b128 v[214:217], v153 offset:56320
	global_load_lds_dwordx4 v[218:219], off
	s_add_i32 m0, s48, 0x2000
	s_add_u32 s46, s46, 0x20080
	v_lshl_add_u64 v[218:219], v[220:221], 0, s[12:13]
	s_addc_u32 s47, s47, 0
	s_add_i32 s48, s63, s15
	global_load_lds_dwordx4 v[218:219], off
	v_lshl_add_u64 v[218:219], s[46:47], 0, v[130:131]
	s_mov_b32 m0, s48
	s_nop 0
	global_load_lds_dwordx4 v[218:219], off
	v_lshl_add_u64 v[218:219], s[46:47], 0, v[134:135]
	s_add_i32 m0, s48, 0x2000
	s_nop 0
	global_load_lds_dwordx4 v[218:219], off
	s_waitcnt vmcnt(6)
	s_waitcnt lgkmcnt(0)
	s_barrier
	s_setprio 1
	s_waitcnt lgkmcnt(0)
	v_mfma_f32_16x16x32_bf16 v[60:63], v[144:147], v[184:187], v[60:63]
	v_mfma_f32_16x16x32_bf16 v[56:59], v[160:163], v[184:187], v[56:59]
	v_mfma_f32_16x16x32_bf16 v[52:55], v[168:171], v[184:187], v[52:55]
	v_mfma_f32_16x16x32_bf16 v[48:51], v[176:179], v[184:187], v[48:51]
	v_mfma_f32_16x16x32_bf16 v[44:47], v[144:147], v[192:195], v[44:47]
	v_mfma_f32_16x16x32_bf16 v[40:43], v[160:163], v[192:195], v[40:43]
	v_mfma_f32_16x16x32_bf16 v[36:39], v[168:171], v[192:195], v[36:39]
	v_mfma_f32_16x16x32_bf16 v[32:35], v[176:179], v[192:195], v[32:35]
	v_mfma_f32_16x16x32_bf16 v[28:31], v[144:147], v[200:203], v[28:31]
	v_mfma_f32_16x16x32_bf16 v[24:27], v[160:163], v[200:203], v[24:27]
	v_mfma_f32_16x16x32_bf16 v[20:23], v[168:171], v[200:203], v[20:23]
	v_mfma_f32_16x16x32_bf16 v[16:19], v[176:179], v[200:203], v[16:19]
	v_mfma_f32_16x16x32_bf16 v[12:15], v[144:147], v[210:213], v[12:15]
	v_mfma_f32_16x16x32_bf16 v[8:11], v[160:163], v[210:213], v[8:11]
	v_lshl_add_u64 v[218:219], v[222:223], 0, s[12:13]
	s_mov_b32 m0, s52
	s_nop 0
	global_load_lds_dwordx4 v[218:219], off
	v_mfma_f32_16x16x32_bf16 v[4:7], v[168:171], v[210:213], v[4:7]
	v_mfma_f32_16x16x32_bf16 v[0:3], v[176:179], v[210:213], v[0:3]
	s_setprio 0
	s_setprio 1
	v_mfma_f32_16x16x32_bf16 v[60:63], v[156:159], v[188:191], v[60:63]
	v_mfma_f32_16x16x32_bf16 v[56:59], v[164:167], v[188:191], v[56:59]
	v_mfma_f32_16x16x32_bf16 v[52:55], v[172:175], v[188:191], v[52:55]
	v_mfma_f32_16x16x32_bf16 v[48:51], v[180:183], v[188:191], v[48:51]
	v_mfma_f32_16x16x32_bf16 v[44:47], v[156:159], v[196:199], v[44:47]
	v_mfma_f32_16x16x32_bf16 v[40:43], v[164:167], v[196:199], v[40:43]
	v_mfma_f32_16x16x32_bf16 v[36:39], v[172:175], v[196:199], v[36:39]
	v_mfma_f32_16x16x32_bf16 v[32:35], v[180:183], v[196:199], v[32:35]
	v_mfma_f32_16x16x32_bf16 v[28:31], v[156:159], v[206:209], v[28:31]
	v_mfma_f32_16x16x32_bf16 v[24:27], v[164:167], v[206:209], v[24:27]
	v_mfma_f32_16x16x32_bf16 v[20:23], v[172:175], v[206:209], v[20:23]
	v_mfma_f32_16x16x32_bf16 v[16:19], v[180:183], v[206:209], v[16:19]
	v_mfma_f32_16x16x32_bf16 v[12:15], v[156:159], v[214:217], v[12:15]
	v_mfma_f32_16x16x32_bf16 v[8:11], v[164:167], v[214:217], v[8:11]
	v_lshl_add_u64 v[218:219], v[224:225], 0, s[12:13]
	s_mov_b32 m0, s53
	s_nop 0
	global_load_lds_dwordx4 v[218:219], off
	v_mfma_f32_16x16x32_bf16 v[4:7], v[172:175], v[214:217], v[4:7]
	v_mfma_f32_16x16x32_bf16 v[0:3], v[180:183], v[214:217], v[0:3]
	s_setprio 0
	s_barrier
	s_add_i32 s61, s61, 2
	s_add_u32 s44, s44, 0x100
	s_addc_u32 s45, s45, 0
	s_add_u32 s59, s59, 0x100
	s_addc_u32 s60, s60, 0
.LBB0_1816:
	ds_read_b128 v[144:147], v151
	ds_read_b128 v[156:159], v151 offset:1024
	ds_read_b128 v[160:163], v151 offset:2048
	ds_read_b128 v[164:167], v151 offset:3072
	ds_read_b128 v[168:171], v152
	ds_read_b128 v[172:175], v152 offset:1024
	ds_read_b128 v[176:179], v152 offset:2048
	ds_read_b128 v[180:183], v152 offset:3072
	s_add_u32 s46, s44, 0xfffe0080
	s_addc_u32 s47, s45, -1
	s_cmp_eq_u32 s61, 4
	s_cselect_b32 s49, s29, s47
	s_cselect_b32 s48, s41, s46
	s_cselect_b32 s47, s27, s60
	s_cselect_b32 s46, s58, s59
	v_lshl_add_u64 v[218:219], s[44:45], 0, v[136:137]
	s_add_i32 m0, s33, 0xc000
	ds_read_b128 v[184:187], v153
	ds_read_b128 v[188:191], v153 offset:1024
	ds_read_b128 v[192:195], v153 offset:2048
	ds_read_b128 v[196:199], v153 offset:3072
	ds_read_b128 v[200:203], v153 offset:4096
	ds_read_b128 v[206:209], v153 offset:5120
	ds_read_b128 v[210:213], v153 offset:6144
	ds_read_b128 v[214:217], v153 offset:7168
	global_load_lds_dwordx4 v[218:219], off
	v_lshl_add_u64 v[218:219], s[44:45], 0, v[138:139]
	s_add_i32 m0, s33, 0xe000
	s_nop 0
	global_load_lds_dwordx4 v[218:219], off
	s_waitcnt vmcnt(8)
	s_waitcnt lgkmcnt(0)
	s_barrier
; #define PG8_STAGE(bufoff, gbase, voff) do { _Pragma("unroll") for (int _i = 0; _i < 2; ++_i) \
;         __builtin_amdgcn_global_load_lds((const unsigned*)((const char*)(gbase) + (voff)[_i]), (PG8_LAS unsigned*)(lds + (bufoff) + ldsw + _i * 8192), 16, 0, 0); } while (0)
; #define PG8_LDA(dst, b, h) do { _Pragma("unroll") for (int m = 0; m < 4; ++m) _Pragma("unroll") for (int k = 0; k < 2; ++k) dst[m][k] = *(const PG8_LAS bf16x8*)(lds + PG8_SA(b, h) + aoff + m * 2048 + k * 1024); } while (0)
; #define PG8_LDB(dst, b, h) do { _Pragma("unroll") for (int n = 0; n < 2; ++n) _Pragma("unroll") for (int k = 0; k < 2; ++k) dst[n][k] = *(const PG8_LAS bf16x8*)(lds + PG8_SB(b, h) + boff + n * 2048 + k * 1024); } while (0)
; #define PG8_MMA(ai, bj, At, Bt) do { __builtin_amdgcn_s_setprio(1); _Pragma("unroll") for (int m = 0; m < 4; ++m) _Pragma("unroll") for (int n = 0; n < 2; ++n) _Pragma("unroll") for (int k = 0; k < 2; ++k) \
;         acc[ai][bj][m][n] = __builtin_amdgcn_mfma_f32_16x16x32_bf16(Bt[n][k], At[m][k], acc[ai][bj][m][n], 0, 0, 0); __builtin_amdgcn_s_setprio(0); } while (0)
; #define PG8_WAIT_V(n) asm volatile("s_waitcnt vmcnt(" #n ")" ::: "memory")
; #define PG8_WAIT_L(n) asm volatile("s_waitcnt lgkmcnt(" #n ")" ::: "memory")
; #define PG8_BAR __builtin_amdgcn_s_barrier()
; #define PG8_SCHED __builtin_amdgcn_sched_barrier(0)
; template <class Epi, class Sched, bool ALIGN_EPI = false, bool SP2 = false>
; __device__ __forceinline__ void gemm_phase(PG8_LAS unsigned char* lds, const Gemm g, const Sched& S, const Epi& E) {
;     ...
;             PG8_LDB(B0, 0, 0); PG8_LDB(B1, 0, 1); PG8_SCHED; PG8_LDA(At, 0, 0); PG8_STAGE(PG8_SA(1, 1), a1 + hstep, voffA);
;             PG8_WAIT_V(8); PG8_WAIT_L(0); PG8_BAR; PG8_MMA(0, 0, At, B0); PG8_MMA(0, 1, At, B1); PG8_BAR; PG8_SCHED;
;             PG8_LDA(At, 0, 1); PG8_STAGE(PG8_SB(0, 0), b2, voffB); PG8_STAGE(PG8_SB(0, 1), b2 + hstep, voffB); PG8_STAGE(PG8_SA(0, 0), a2, voffA);
;             PG8_WAIT_V(8); PG8_WAIT_L(0); PG8_BAR; PG8_MMA(1, 0, At, B0); PG8_MMA(1, 1, At, B1); PG8_BAR; PG8_SCHED;
	s_setprio 1
	s_waitcnt lgkmcnt(0)
	v_mfma_f32_16x16x32_bf16 v[124:127], v[144:147], v[184:187], v[124:127]
	v_mfma_f32_16x16x32_bf16 v[120:123], v[160:163], v[184:187], v[120:123]
	v_mfma_f32_16x16x32_bf16 v[116:119], v[168:171], v[184:187], v[116:119]
	v_mfma_f32_16x16x32_bf16 v[112:115], v[176:179], v[184:187], v[112:115]
	v_mfma_f32_16x16x32_bf16 v[108:111], v[144:147], v[192:195], v[108:111]
	v_mfma_f32_16x16x32_bf16 v[104:107], v[160:163], v[192:195], v[104:107]
	v_mfma_f32_16x16x32_bf16 v[100:103], v[168:171], v[192:195], v[100:103]
	v_mfma_f32_16x16x32_bf16 v[96:99], v[176:179], v[192:195], v[96:99]
	v_mfma_f32_16x16x32_bf16 v[92:95], v[144:147], v[200:203], v[92:95]
	v_mfma_f32_16x16x32_bf16 v[88:91], v[160:163], v[200:203], v[88:91]
	v_mfma_f32_16x16x32_bf16 v[84:87], v[168:171], v[200:203], v[84:87]
	v_mfma_f32_16x16x32_bf16 v[80:83], v[176:179], v[200:203], v[80:83]
	v_mfma_f32_16x16x32_bf16 v[76:79], v[144:147], v[210:213], v[76:79]
	v_mfma_f32_16x16x32_bf16 v[72:75], v[160:163], v[210:213], v[72:75]
	v_mfma_f32_16x16x32_bf16 v[68:71], v[168:171], v[210:213], v[68:71]
	v_mfma_f32_16x16x32_bf16 v[64:67], v[176:179], v[210:213], v[64:67]
	s_setprio 0
	s_setprio 1
	v_mfma_f32_16x16x32_bf16 v[124:127], v[156:159], v[188:191], v[124:127]
	v_mfma_f32_16x16x32_bf16 v[120:123], v[164:167], v[188:191], v[120:123]
	v_mfma_f32_16x16x32_bf16 v[116:119], v[172:175], v[188:191], v[116:119]
	v_mfma_f32_16x16x32_bf16 v[112:115], v[180:183], v[188:191], v[112:115]
	v_mfma_f32_16x16x32_bf16 v[108:111], v[156:159], v[196:199], v[108:111]
	v_mfma_f32_16x16x32_bf16 v[104:107], v[164:167], v[196:199], v[104:107]
	v_mfma_f32_16x16x32_bf16 v[100:103], v[172:175], v[196:199], v[100:103]
	v_mfma_f32_16x16x32_bf16 v[96:99], v[180:183], v[196:199], v[96:99]
	v_mfma_f32_16x16x32_bf16 v[92:95], v[156:159], v[206:209], v[92:95]
	v_mfma_f32_16x16x32_bf16 v[88:91], v[164:167], v[206:209], v[88:91]
	v_mfma_f32_16x16x32_bf16 v[84:87], v[172:175], v[206:209], v[84:87]
	v_mfma_f32_16x16x32_bf16 v[80:83], v[180:183], v[206:209], v[80:83]
	v_mfma_f32_16x16x32_bf16 v[76:79], v[156:159], v[214:217], v[76:79]
	v_mfma_f32_16x16x32_bf16 v[72:75], v[164:167], v[214:217], v[72:75]
	v_mfma_f32_16x16x32_bf16 v[68:71], v[172:175], v[214:217], v[68:71]
	v_mfma_f32_16x16x32_bf16 v[64:67], v[180:183], v[214:217], v[64:67]
	s_setprio 0
	s_barrier
	s_add_i32 s62, s54, s15
	v_lshl_add_u64 v[218:219], s[46:47], 0, v[130:131]
	s_mov_b32 m0, s62
	ds_read_b128 v[184:187], v153 offset:16384
	ds_read_b128 v[188:191], v153 offset:17408
	ds_read_b128 v[192:195], v153 offset:18432
	ds_read_b128 v[196:199], v153 offset:19456
	ds_read_b128 v[200:203], v153 offset:20480
	ds_read_b128 v[206:209], v153 offset:21504
	ds_read_b128 v[210:213], v153 offset:22528
	ds_read_b128 v[214:217], v153 offset:23552
	global_load_lds_dwordx4 v[218:219], off
	s_add_i32 m0, s62, 0x2000
	s_add_u32 s62, s46, 0x20000
	v_lshl_add_u64 v[220:221], s[46:47], 0, v[134:135]
	s_addc_u32 s63, s47, 0
	s_add_i32 s64, s55, s15
	global_load_lds_dwordx4 v[220:221], off
	v_lshl_add_u64 v[222:223], s[62:63], 0, v[130:131]
	s_mov_b32 m0, s64
	global_load_lds_dwordx4 v[222:223], off
	v_lshl_add_u64 v[222:223], s[62:63], 0, v[134:135]
	s_add_i32 m0, s64, 0x2000
	s_nop 0
	global_load_lds_dwordx4 v[222:223], off
	s_waitcnt vmcnt(6)
	s_waitcnt lgkmcnt(0)
	s_barrier
	s_setprio 1
	s_waitcnt lgkmcnt(0)
	v_mfma_f32_16x16x32_bf16 v[60:63], v[144:147], v[184:187], v[60:63]
	v_mfma_f32_16x16x32_bf16 v[56:59], v[160:163], v[184:187], v[56:59]
	v_mfma_f32_16x16x32_bf16 v[52:55], v[168:171], v[184:187], v[52:55]
	v_mfma_f32_16x16x32_bf16 v[48:51], v[176:179], v[184:187], v[48:51]
	v_mfma_f32_16x16x32_bf16 v[44:47], v[144:147], v[192:195], v[44:47]
	v_mfma_f32_16x16x32_bf16 v[40:43], v[160:163], v[192:195], v[40:43]
	v_mfma_f32_16x16x32_bf16 v[36:39], v[168:171], v[192:195], v[36:39]
	v_mfma_f32_16x16x32_bf16 v[32:35], v[176:179], v[192:195], v[32:35]
	v_mfma_f32_16x16x32_bf16 v[28:31], v[144:147], v[200:203], v[28:31]
	v_mfma_f32_16x16x32_bf16 v[24:27], v[160:163], v[200:203], v[24:27]
	v_mfma_f32_16x16x32_bf16 v[20:23], v[168:171], v[200:203], v[20:23]
	v_mfma_f32_16x16x32_bf16 v[16:19], v[176:179], v[200:203], v[16:19]
	v_mfma_f32_16x16x32_bf16 v[12:15], v[144:147], v[210:213], v[12:15]
	v_mfma_f32_16x16x32_bf16 v[8:11], v[160:163], v[210:213], v[8:11]
	v_lshl_add_u64 v[222:223], s[48:49], 0, v[128:129]
	s_mov_b32 m0, s33
	s_nop 0
	global_load_lds_dwordx4 v[222:223], off
	v_mfma_f32_16x16x32_bf16 v[4:7], v[168:171], v[210:213], v[4:7]
	v_mfma_f32_16x16x32_bf16 v[0:3], v[176:179], v[210:213], v[0:3]
	s_setprio 0
	s_setprio 1
	v_mfma_f32_16x16x32_bf16 v[60:63], v[156:159], v[188:191], v[60:63]
	v_mfma_f32_16x16x32_bf16 v[56:59], v[164:167], v[188:191], v[56:59]
	v_mfma_f32_16x16x32_bf16 v[52:55], v[172:175], v[188:191], v[52:55]
	v_mfma_f32_16x16x32_bf16 v[48:51], v[180:183], v[188:191], v[48:51]
	v_mfma_f32_16x16x32_bf16 v[44:47], v[156:159], v[196:199], v[44:47]
	v_mfma_f32_16x16x32_bf16 v[40:43], v[164:167], v[196:199], v[40:43]
	v_mfma_f32_16x16x32_bf16 v[36:39], v[172:175], v[196:199], v[36:39]
	v_mfma_f32_16x16x32_bf16 v[32:35], v[180:183], v[196:199], v[32:35]
	v_mfma_f32_16x16x32_bf16 v[28:31], v[156:159], v[206:209], v[28:31]
	v_mfma_f32_16x16x32_bf16 v[24:27], v[164:167], v[206:209], v[24:27]
	v_mfma_f32_16x16x32_bf16 v[20:23], v[172:175], v[206:209], v[20:23]
	v_mfma_f32_16x16x32_bf16 v[16:19], v[180:183], v[206:209], v[16:19]
	v_mfma_f32_16x16x32_bf16 v[12:15], v[156:159], v[214:217], v[12:15]
	v_mfma_f32_16x16x32_bf16 v[8:11], v[164:167], v[214:217], v[8:11]
	v_lshl_add_u64 v[224:225], s[48:49], 0, v[132:133]
	s_mov_b32 m0, s34
	s_nop 0
	global_load_lds_dwordx4 v[224:225], off
	v_mfma_f32_16x16x32_bf16 v[4:7], v[172:175], v[214:217], v[4:7]
	v_mfma_f32_16x16x32_bf16 v[0:3], v[180:183], v[214:217], v[0:3]
	s_setprio 0
	s_barrier
; #define PG8_STAGE(bufoff, gbase, voff) do { _Pragma("unroll") for (int _i = 0; _i < 2; ++_i) \
;         __builtin_amdgcn_global_load_lds((const unsigned*)((const char*)(gbase) + (voff)[_i]), (PG8_LAS unsigned*)(lds + (bufoff) + ldsw + _i * 8192), 16, 0, 0); } while (0)
; #define PG8_LDA(dst, b, h) do { _Pragma("unroll") for (int m = 0; m < 4; ++m) _Pragma("unroll") for (int k = 0; k < 2; ++k) dst[m][k] = *(const PG8_LAS bf16x8*)(lds + PG8_SA(b, h) + aoff + m * 2048 + k * 1024); } while (0)
; #define PG8_LDB(dst, b, h) do { _Pragma("unroll") for (int n = 0; n < 2; ++n) _Pragma("unroll") for (int k = 0; k < 2; ++k) dst[n][k] = *(const PG8_LAS bf16x8*)(lds + PG8_SB(b, h) + boff + n * 2048 + k * 1024); } while (0)
; #define PG8_MMA(ai, bj, At, Bt) do { __builtin_amdgcn_s_setprio(1); _Pragma("unroll") for (int m = 0; m < 4; ++m) _Pragma("unroll") for (int n = 0; n < 2; ++n) _Pragma("unroll") for (int k = 0; k < 2; ++k) \
;         acc[ai][bj][m][n] = __builtin_amdgcn_mfma_f32_16x16x32_bf16(Bt[n][k], At[m][k], acc[ai][bj][m][n], 0, 0, 0); __builtin_amdgcn_s_setprio(0); } while (0)
; #define PG8_WAIT_V(n) asm volatile("s_waitcnt vmcnt(" #n ")" ::: "memory")
; #define PG8_WAIT_L(n) asm volatile("s_waitcnt lgkmcnt(" #n ")" ::: "memory")
; #define PG8_BAR __builtin_amdgcn_s_barrier()
; #define PG8_SCHED __builtin_amdgcn_sched_barrier(0)
; template <class Epi, class Sched, bool ALIGN_EPI = false, bool SP2 = false>
; __device__ __forceinline__ void gemm_phase(PG8_LAS unsigned char* lds, const Gemm g, const Sched& S, const Epi& E) {
;     ...
;             PG8_LDB(B0, 1, 0); PG8_LDB(B1, 1, 1); PG8_SCHED; PG8_LDA(At, 1, 0); PG8_STAGE(PG8_SA(0, 1), a2 + hstep, voffA);
;             PG8_WAIT_V(8); PG8_WAIT_L(0); PG8_BAR; PG8_MMA(0, 0, At, B0); PG8_MMA(0, 1, At, B1); PG8_BAR; PG8_SCHED;
	s_add_i32 s62, 0, 0x18000
	v_add_u32_e32 v155, s62, v149
	s_add_i32 s63, 0, 0x1c000
	ds_read_b128 v[144:147], v155
	ds_read_b128 v[156:159], v155 offset:1024
	ds_read_b128 v[160:163], v155 offset:2048
	ds_read_b128 v[164:167], v155 offset:3072
	v_add_u32_e32 v155, s63, v149
	ds_read_b128 v[168:171], v155
	ds_read_b128 v[172:175], v155 offset:1024
	ds_read_b128 v[176:179], v155 offset:2048
	ds_read_b128 v[180:183], v155 offset:3072
	s_add_u32 s48, s48, 0x20000
	s_addc_u32 s49, s49, 0
	s_mov_b32 m0, s43
	v_lshl_add_u64 v[226:227], s[48:49], 0, v[128:129]
	ds_read_b128 v[184:187], v153 offset:32768
	ds_read_b128 v[188:191], v153 offset:33792
	ds_read_b128 v[192:195], v153 offset:34816
	ds_read_b128 v[196:199], v153 offset:35840
	ds_read_b128 v[200:203], v153 offset:36864
	ds_read_b128 v[206:209], v153 offset:37888
	ds_read_b128 v[210:213], v153 offset:38912
	ds_read_b128 v[214:217], v153 offset:39936
	global_load_lds_dwordx4 v[226:227], off
	v_lshl_add_u64 v[226:227], s[48:49], 0, v[132:133]
	s_mov_b32 m0, s50
	s_nop 0
	global_load_lds_dwordx4 v[226:227], off
	s_waitcnt vmcnt(8)
	s_waitcnt lgkmcnt(0)
	s_barrier
	s_setprio 1
	s_waitcnt lgkmcnt(0)
	v_mfma_f32_16x16x32_bf16 v[124:127], v[144:147], v[184:187], v[124:127]
	v_mfma_f32_16x16x32_bf16 v[120:123], v[160:163], v[184:187], v[120:123]
	v_mfma_f32_16x16x32_bf16 v[116:119], v[168:171], v[184:187], v[116:119]
	v_mfma_f32_16x16x32_bf16 v[112:115], v[176:179], v[184:187], v[112:115]
	v_mfma_f32_16x16x32_bf16 v[108:111], v[144:147], v[192:195], v[108:111]
	v_mfma_f32_16x16x32_bf16 v[104:107], v[160:163], v[192:195], v[104:107]
	v_mfma_f32_16x16x32_bf16 v[100:103], v[168:171], v[192:195], v[100:103]
	v_mfma_f32_16x16x32_bf16 v[96:99], v[176:179], v[192:195], v[96:99]
	v_mfma_f32_16x16x32_bf16 v[92:95], v[144:147], v[200:203], v[92:95]
	v_mfma_f32_16x16x32_bf16 v[88:91], v[160:163], v[200:203], v[88:91]
	v_mfma_f32_16x16x32_bf16 v[84:87], v[168:171], v[200:203], v[84:87]
	v_mfma_f32_16x16x32_bf16 v[80:83], v[176:179], v[200:203], v[80:83]
	v_mfma_f32_16x16x32_bf16 v[76:79], v[144:147], v[210:213], v[76:79]
	v_mfma_f32_16x16x32_bf16 v[72:75], v[160:163], v[210:213], v[72:75]
	v_mfma_f32_16x16x32_bf16 v[68:71], v[168:171], v[210:213], v[68:71]
	v_mfma_f32_16x16x32_bf16 v[64:67], v[176:179], v[210:213], v[64:67]
	s_setprio 0
	s_setprio 1
	v_mfma_f32_16x16x32_bf16 v[124:127], v[156:159], v[188:191], v[124:127]
	v_mfma_f32_16x16x32_bf16 v[120:123], v[164:167], v[188:191], v[120:123]
	v_mfma_f32_16x16x32_bf16 v[116:119], v[172:175], v[188:191], v[116:119]
	v_mfma_f32_16x16x32_bf16 v[112:115], v[180:183], v[188:191], v[112:115]
	v_mfma_f32_16x16x32_bf16 v[108:111], v[156:159], v[196:199], v[108:111]
	v_mfma_f32_16x16x32_bf16 v[104:107], v[164:167], v[196:199], v[104:107]
	v_mfma_f32_16x16x32_bf16 v[100:103], v[172:175], v[196:199], v[100:103]
	v_mfma_f32_16x16x32_bf16 v[96:99], v[180:183], v[196:199], v[96:99]
	v_mfma_f32_16x16x32_bf16 v[92:95], v[156:159], v[206:209], v[92:95]
	v_mfma_f32_16x16x32_bf16 v[88:91], v[164:167], v[206:209], v[88:91]
	v_mfma_f32_16x16x32_bf16 v[84:87], v[172:175], v[206:209], v[84:87]
	v_mfma_f32_16x16x32_bf16 v[80:83], v[180:183], v[206:209], v[80:83]
	v_mfma_f32_16x16x32_bf16 v[76:79], v[156:159], v[214:217], v[76:79]
	v_mfma_f32_16x16x32_bf16 v[72:75], v[164:167], v[214:217], v[72:75]
	v_mfma_f32_16x16x32_bf16 v[68:71], v[172:175], v[214:217], v[68:71]
	v_mfma_f32_16x16x32_bf16 v[64:67], v[180:183], v[214:217], v[64:67]
	s_setprio 0
	s_barrier
; #define PG8_STAGE(bufoff, gbase, voff) do { _Pragma("unroll") for (int _i = 0; _i < 2; ++_i) \
;         __builtin_amdgcn_global_load_lds((const unsigned*)((const char*)(gbase) + (voff)[_i]), (PG8_LAS unsigned*)(lds + (bufoff) + ldsw + _i * 8192), 16, 0, 0); } while (0)
; #define PG8_LDA(dst, b, h) do { _Pragma("unroll") for (int m = 0; m < 4; ++m) _Pragma("unroll") for (int k = 0; k < 2; ++k) dst[m][k] = *(const PG8_LAS bf16x8*)(lds + PG8_SA(b, h) + aoff + m * 2048 + k * 1024); } while (0)
; #define PG8_MMA(ai, bj, At, Bt) do { __builtin_amdgcn_s_setprio(1); _Pragma("unroll") for (int m = 0; m < 4; ++m) _Pragma("unroll") for (int n = 0; n < 2; ++n) _Pragma("unroll") for (int k = 0; k < 2; ++k) \
;         acc[ai][bj][m][n] = __builtin_amdgcn_mfma_f32_16x16x32_bf16(Bt[n][k], At[m][k], acc[ai][bj][m][n], 0, 0, 0); __builtin_amdgcn_s_setprio(0); } while (0)
; #define PG8_WAIT_V(n) asm volatile("s_waitcnt vmcnt(" #n ")" ::: "memory")
; #define PG8_WAIT_L(n) asm volatile("s_waitcnt lgkmcnt(" #n ")" ::: "memory")
; #define PG8_BAR __builtin_amdgcn_s_barrier()
; #define PG8_SCHED __builtin_amdgcn_sched_barrier(0)
; template <class Epi, class Sched, bool ALIGN_EPI = false, bool SP2 = false>
; __device__ __forceinline__ void gemm_phase(PG8_LAS unsigned char* lds, const Gemm g, const Sched& S, const Epi& E) {
;     ...
;         for (int t = 0; t < nt; t += 2) {
;     ...
;             PG8_LDA(At, 1, 1); PG8_STAGE(PG8_SB(1, 0), b3, voffB); PG8_STAGE(PG8_SB(1, 1), b3 + hstep, voffB); PG8_STAGE(PG8_SA(1, 0), a3, voffA);
;             PG8_WAIT_V(8); PG8_WAIT_L(0); PG8_BAR; PG8_MMA(1, 0, At, B0); PG8_MMA(1, 1, At, B1); PG8_BAR; PG8_SCHED;
	s_add_i32 s48, s62, s15
	v_lshl_add_u64 v[218:219], v[218:219], 0, s[12:13]
	s_mov_b32 m0, s48
	ds_read_b128 v[184:187], v153 offset:49152
	ds_read_b128 v[188:191], v153 offset:50176
	ds_read_b128 v[192:195], v153 offset:51200
	ds_read_b128 v[196:199], v153 offset:52224
	ds_read_b128 v[200:203], v153 offset:53248
	ds_read_b128 v[206:209], v153 offset:54272
	ds_read_b128 v[210:213], v153 offset:55296
	ds_read_b128 v[214:217], v153 offset:56320
	global_load_lds_dwordx4 v[218:219], off
	s_add_i32 m0, s48, 0x2000
	s_add_u32 s46, s46, 0x20080
	v_lshl_add_u64 v[218:219], v[220:221], 0, s[12:13]
	s_addc_u32 s47, s47, 0
	s_add_i32 s48, s63, s15
	global_load_lds_dwordx4 v[218:219], off
	v_lshl_add_u64 v[218:219], s[46:47], 0, v[130:131]
	s_mov_b32 m0, s48
	s_nop 0
	global_load_lds_dwordx4 v[218:219], off
	v_lshl_add_u64 v[218:219], s[46:47], 0, v[134:135]
	s_add_i32 m0, s48, 0x2000
	s_nop 0
	global_load_lds_dwordx4 v[218:219], off
	s_waitcnt vmcnt(6)
	s_waitcnt lgkmcnt(0)
	s_barrier
	s_setprio 1
	s_waitcnt lgkmcnt(0)
	v_mfma_f32_16x16x32_bf16 v[60:63], v[144:147], v[184:187], v[60:63]
	v_mfma_f32_16x16x32_bf16 v[56:59], v[160:163], v[184:187], v[56:59]
	v_mfma_f32_16x16x32_bf16 v[52:55], v[168:171], v[184:187], v[52:55]
	v_mfma_f32_16x16x32_bf16 v[48:51], v[176:179], v[184:187], v[48:51]
	v_mfma_f32_16x16x32_bf16 v[44:47], v[144:147], v[192:195], v[44:47]
	v_mfma_f32_16x16x32_bf16 v[40:43], v[160:163], v[192:195], v[40:43]
	v_mfma_f32_16x16x32_bf16 v[36:39], v[168:171], v[192:195], v[36:39]
	v_mfma_f32_16x16x32_bf16 v[32:35], v[176:179], v[192:195], v[32:35]
	v_mfma_f32_16x16x32_bf16 v[28:31], v[144:147], v[200:203], v[28:31]
	v_mfma_f32_16x16x32_bf16 v[24:27], v[160:163], v[200:203], v[24:27]
	v_mfma_f32_16x16x32_bf16 v[20:23], v[168:171], v[200:203], v[20:23]
	v_mfma_f32_16x16x32_bf16 v[16:19], v[176:179], v[200:203], v[16:19]
	v_mfma_f32_16x16x32_bf16 v[12:15], v[144:147], v[210:213], v[12:15]
	v_mfma_f32_16x16x32_bf16 v[8:11], v[160:163], v[210:213], v[8:11]
	v_lshl_add_u64 v[218:219], v[222:223], 0, s[12:13]
	s_mov_b32 m0, s52
	s_nop 0
	global_load_lds_dwordx4 v[218:219], off
	v_mfma_f32_16x16x32_bf16 v[4:7], v[168:171], v[210:213], v[4:7]
	v_mfma_f32_16x16x32_bf16 v[0:3], v[176:179], v[210:213], v[0:3]
	s_setprio 0
	s_setprio 1
	v_mfma_f32_16x16x32_bf16 v[60:63], v[156:159], v[188:191], v[60:63]
	v_mfma_f32_16x16x32_bf16 v[56:59], v[164:167], v[188:191], v[56:59]
	v_mfma_f32_16x16x32_bf16 v[52:55], v[172:175], v[188:191], v[52:55]
	v_mfma_f32_16x16x32_bf16 v[48:51], v[180:183], v[188:191], v[48:51]
	v_mfma_f32_16x16x32_bf16 v[44:47], v[156:159], v[196:199], v[44:47]
	v_mfma_f32_16x16x32_bf16 v[40:43], v[164:167], v[196:199], v[40:43]
	v_mfma_f32_16x16x32_bf16 v[36:39], v[172:175], v[196:199], v[36:39]
	v_mfma_f32_16x16x32_bf16 v[32:35], v[180:183], v[196:199], v[32:35]
	v_mfma_f32_16x16x32_bf16 v[28:31], v[156:159], v[206:209], v[28:31]
	v_mfma_f32_16x16x32_bf16 v[24:27], v[164:167], v[206:209], v[24:27]
	v_mfma_f32_16x16x32_bf16 v[20:23], v[172:175], v[206:209], v[20:23]
	v_mfma_f32_16x16x32_bf16 v[16:19], v[180:183], v[206:209], v[16:19]
	v_mfma_f32_16x16x32_bf16 v[12:15], v[156:159], v[214:217], v[12:15]
	v_mfma_f32_16x16x32_bf16 v[8:11], v[164:167], v[214:217], v[8:11]
	v_lshl_add_u64 v[218:219], v[224:225], 0, s[12:13]
	s_mov_b32 m0, s53
	s_nop 0
	global_load_lds_dwordx4 v[218:219], off
	v_mfma_f32_16x16x32_bf16 v[4:7], v[172:175], v[214:217], v[4:7]
	v_mfma_f32_16x16x32_bf16 v[0:3], v[180:183], v[214:217], v[0:3]
	s_setprio 0
	s_barrier
	s_add_i32 s61, s61, 2
	s_add_u32 s44, s44, 0x100
	s_addc_u32 s45, s45, 0
	s_add_u32 s59, s59, 0x100
	s_addc_u32 s60, s60, 0
	s_cmp_gt_u32 s61, 5
	s_cbranch_scc0 .LBB0_1816
	s_and_b64 vcc, exec, s[24:25]
	s_cbranch_vccz .LBB0_1819
	s_barrier

; #define PG8_STAGE(bufoff, gbase, voff) do { _Pragma("unroll") for (int _i = 0; _i < 2; ++_i) \
;         __builtin_amdgcn_global_load_lds((const unsigned*)((const char*)(gbase) + (voff)[_i]), (PG8_LAS unsigned*)(lds + (bufoff) + ldsw + _i * 8192), 16, 0, 0); } while (0)
; #define PG8_LDA(dst, b, h) do { _Pragma("unroll") for (int m = 0; m < 4; ++m) _Pragma("unroll") for (int k = 0; k < 2; ++k) dst[m][k] = *(const PG8_LAS bf16x8*)(lds + PG8_SA(b, h) + aoff + m * 2048 + k * 1024); } while (0)
; #define PG8_LDB(dst, b, h) do { _Pragma("unroll") for (int n = 0; n < 2; ++n) _Pragma("unroll") for (int k = 0; k < 2; ++k) dst[n][k] = *(const PG8_LAS bf16x8*)(lds + PG8_SB(b, h) + boff + n * 2048 + k * 1024); } while (0)
; #define PG8_WAIT_V(n) asm volatile("s_waitcnt vmcnt(" #n ")" ::: "memory")
; #define PG8_WAIT_L(n) asm volatile("s_waitcnt lgkmcnt(" #n ")" ::: "memory")
; #define PG8_BAR __builtin_amdgcn_s_barrier()
; #define PG8_SCHED __builtin_amdgcn_sched_barrier(0)
; template <class Epi, class Sched, bool ALIGN_EPI = false, bool SP2 = false>
; __device__ __forceinline__ void gemm_phase(PG8_LAS unsigned char* lds, const Gemm g, const Sched& S, const Epi& E) {
;     ...
;         const bool has_next = S.next(ui + 1, nxt);
;         const char* nA = has_next ? (const char*)g.A + (size_t)nxt.pm * tstep : cA; const char* nB = has_next ? (const char*)g.Bt + (size_t)nxt.pn * tstep : cB;
;         for (int t = 0; t < nt; t += 2) {
;             const bool last = (t == nt - 2);
;             const char* a1 = cA + (size_t)(t + 1) * kstep;
;             const char* a2 = last ? nA : cA + (size_t)(t + 2) * kstep; const char* b2 = last ? nB : cB + (size_t)(t + 2) * kstep;
;             const char* a3 = a2 + kstep; const char* b3 = b2 + kstep;
;             if (last && has_next) S.a_ready(nxt);
;             if constexpr (SP2) {
;             PG8_LDB(B0, 0, 0); PG8_LDB(B1, 0, 1); PG8_SCHED; PG8_LDA(At, 0, 0); PG8_STAGE(PG8_SA(1, 1), a1 + hstep, voffA);
;             PG8_WAIT_V(8); PG8_WAIT_L(0); PG8_BAR; PG8_MMA(0, 0, At, B0); PG8_MMA(0, 1, At, B1); PG8_BAR; PG8_SCHED;
;             PG8_LDA(At, 0, 1); PG8_STAGE(PG8_SB(0, 0), b2, voffB); PG8_STAGE(PG8_SB(0, 1), b2 + hstep, voffB); PG8_STAGE(PG8_SA(0, 0), a2, voffA);
;             PG8_WAIT_V(8); PG8_WAIT_L(0); PG8_BAR; PG8_MMA(1, 0, At, B0); PG8_MMA(1, 1, At, B1); PG8_BAR; PG8_SCHED;
.LBB0_1899:
	s_ashr_i32 s25, s24, 31
	s_lshl_b64 s[26:27], s[24:25], 19
	s_add_u32 s26, s22, s26
	s_addc_u32 s27, s23, s27
	s_and_b64 s[28:29], s[4:5], exec
	s_cselect_b32 s25, s27, s39
	s_cselect_b32 s53, s26, s38
	s_ashr_i32 s13, s12, 31
	s_lshl_b64 s[28:29], s[12:13], 19
	s_add_u32 s28, s3, s28
	s_addc_u32 s29, s14, s29
	s_and_b64 s[42:43], s[4:5], exec
	s_cselect_b32 s13, s29, s41
	s_cselect_b32 s54, s28, s40
	s_add_u32 s38, s38, 0x40080
	s_addc_u32 s39, s39, 0
	s_add_u32 s55, s40, 0x100
	s_addc_u32 s56, s41, 0
	s_mov_b32 s57, -2
	ds_read_b128 v[144:147], v155
	ds_read_b128 v[148:151], v155 offset:1024
	ds_read_b128 v[160:163], v155 offset:2048
	ds_read_b128 v[164:167], v155 offset:3072
	ds_read_b128 v[168:171], v156
	ds_read_b128 v[172:175], v156 offset:1024
	ds_read_b128 v[176:179], v156 offset:2048
	ds_read_b128 v[180:183], v156 offset:3072
	s_add_u32 s40, s38, 0xfffc0080
	s_addc_u32 s41, s39, -1
	s_cmp_eq_u32 s57, 12
	s_cselect_b32 s43, s25, s41
	s_cselect_b32 s42, s53, s40
	s_cselect_b32 s41, s13, s56
	s_cselect_b32 s40, s54, s55
	v_lshl_add_u64 v[218:219], s[38:39], 0, v[136:137]
	s_add_i32 m0, s34, 0xc000
	ds_read_b128 v[184:187], v157
	ds_read_b128 v[188:191], v157 offset:1024
	ds_read_b128 v[192:195], v157 offset:2048
	ds_read_b128 v[196:199], v157 offset:3072
	ds_read_b128 v[200:203], v157 offset:4096
	ds_read_b128 v[206:209], v157 offset:5120
	ds_read_b128 v[210:213], v157 offset:6144
	ds_read_b128 v[214:217], v157 offset:7168
	global_load_lds_dwordx4 v[218:219], off
	v_lshl_add_u64 v[218:219], s[38:39], 0, v[138:139]
	s_add_i32 m0, s34, 0xe000
	s_nop 0
	global_load_lds_dwordx4 v[218:219], off
	s_waitcnt vmcnt(8)
	s_waitcnt lgkmcnt(0)
	s_barrier
	s_setprio 1
	s_waitcnt lgkmcnt(0)
	v_mfma_f32_16x16x32_bf16 v[124:127], v[144:147], v[184:187], 0
	v_mfma_f32_16x16x32_bf16 v[120:123], v[160:163], v[184:187], 0
	v_mfma_f32_16x16x32_bf16 v[116:119], v[168:171], v[184:187], 0
	v_mfma_f32_16x16x32_bf16 v[112:115], v[176:179], v[184:187], 0
	v_mfma_f32_16x16x32_bf16 v[108:111], v[144:147], v[192:195], 0
	v_mfma_f32_16x16x32_bf16 v[104:107], v[160:163], v[192:195], 0
	v_mfma_f32_16x16x32_bf16 v[100:103], v[168:171], v[192:195], 0
	v_mfma_f32_16x16x32_bf16 v[96:99], v[176:179], v[192:195], 0
	v_mfma_f32_16x16x32_bf16 v[92:95], v[144:147], v[200:203], 0
	v_mfma_f32_16x16x32_bf16 v[88:91], v[160:163], v[200:203], 0
	v_mfma_f32_16x16x32_bf16 v[84:87], v[168:171], v[200:203], 0
	v_mfma_f32_16x16x32_bf16 v[80:83], v[176:179], v[200:203], 0
	v_mfma_f32_16x16x32_bf16 v[76:79], v[144:147], v[210:213], 0
	v_mfma_f32_16x16x32_bf16 v[72:75], v[160:163], v[210:213], 0
	v_mfma_f32_16x16x32_bf16 v[68:71], v[168:171], v[210:213], 0
	v_mfma_f32_16x16x32_bf16 v[64:67], v[176:179], v[210:213], 0
	s_setprio 0
	s_setprio 1
	v_mfma_f32_16x16x32_bf16 v[124:127], v[148:151], v[188:191], v[124:127]
	v_mfma_f32_16x16x32_bf16 v[120:123], v[164:167], v[188:191], v[120:123]
	v_mfma_f32_16x16x32_bf16 v[116:119], v[172:175], v[188:191], v[116:119]
	v_mfma_f32_16x16x32_bf16 v[112:115], v[180:183], v[188:191], v[112:115]
	v_mfma_f32_16x16x32_bf16 v[108:111], v[148:151], v[196:199], v[108:111]
	v_mfma_f32_16x16x32_bf16 v[104:107], v[164:167], v[196:199], v[104:107]
	v_mfma_f32_16x16x32_bf16 v[100:103], v[172:175], v[196:199], v[100:103]
	v_mfma_f32_16x16x32_bf16 v[96:99], v[180:183], v[196:199], v[96:99]
	v_mfma_f32_16x16x32_bf16 v[92:95], v[148:151], v[206:209], v[92:95]
	v_mfma_f32_16x16x32_bf16 v[88:91], v[164:167], v[206:209], v[88:91]
	v_mfma_f32_16x16x32_bf16 v[84:87], v[172:175], v[206:209], v[84:87]
	v_mfma_f32_16x16x32_bf16 v[80:83], v[180:183], v[206:209], v[80:83]
	v_mfma_f32_16x16x32_bf16 v[76:79], v[148:151], v[214:217], v[76:79]
	v_mfma_f32_16x16x32_bf16 v[72:75], v[164:167], v[214:217], v[72:75]
	v_mfma_f32_16x16x32_bf16 v[68:71], v[172:175], v[214:217], v[68:71]
	v_mfma_f32_16x16x32_bf16 v[64:67], v[180:183], v[214:217], v[64:67]
	s_setprio 0
	s_barrier
	s_add_i32 s58, s49, s15
	v_lshl_add_u64 v[218:219], s[40:41], 0, v[132:133]
	s_mov_b32 m0, s58
	ds_read_b128 v[184:187], v157 offset:16384
	ds_read_b128 v[188:191], v157 offset:17408
	ds_read_b128 v[192:195], v157 offset:18432
	ds_read_b128 v[196:199], v157 offset:19456
	ds_read_b128 v[200:203], v157 offset:20480
	ds_read_b128 v[206:209], v157 offset:21504
	ds_read_b128 v[210:213], v157 offset:22528
	ds_read_b128 v[214:217], v157 offset:23552
	global_load_lds_dwordx4 v[218:219], off
	s_add_i32 m0, s58, 0x2000
	s_add_u32 s58, s40, 0x40000
	v_lshl_add_u64 v[220:221], s[40:41], 0, v[128:129]
	s_addc_u32 s59, s41, 0
	s_add_i32 s60, s50, s15
	global_load_lds_dwordx4 v[220:221], off
	v_lshl_add_u64 v[222:223], s[58:59], 0, v[132:133]
	s_mov_b32 m0, s60
	global_load_lds_dwordx4 v[222:223], off
	v_lshl_add_u64 v[222:223], s[58:59], 0, v[128:129]
	s_add_i32 m0, s60, 0x2000
	s_nop 0
	global_load_lds_dwordx4 v[222:223], off
	s_waitcnt vmcnt(6)
	s_waitcnt lgkmcnt(0)
	s_barrier
; #define PG8_STAGE(bufoff, gbase, voff) do { _Pragma("unroll") for (int _i = 0; _i < 2; ++_i) \
;         __builtin_amdgcn_global_load_lds((const unsigned*)((const char*)(gbase) + (voff)[_i]), (PG8_LAS unsigned*)(lds + (bufoff) + ldsw + _i * 8192), 16, 0, 0); } while (0)
; #define PG8_LDA(dst, b, h) do { _Pragma("unroll") for (int m = 0; m < 4; ++m) _Pragma("unroll") for (int k = 0; k < 2; ++k) dst[m][k] = *(const PG8_LAS bf16x8*)(lds + PG8_SA(b, h) + aoff + m * 2048 + k * 1024); } while (0)
; #define PG8_LDB(dst, b, h) do { _Pragma("unroll") for (int n = 0; n < 2; ++n) _Pragma("unroll") for (int k = 0; k < 2; ++k) dst[n][k] = *(const PG8_LAS bf16x8*)(lds + PG8_SB(b, h) + boff + n * 2048 + k * 1024); } while (0)
; #define PG8_MMA(ai, bj, At, Bt) do { __builtin_amdgcn_s_setprio(1); _Pragma("unroll") for (int m = 0; m < 4; ++m) _Pragma("unroll") for (int n = 0; n < 2; ++n) _Pragma("unroll") for (int k = 0; k < 2; ++k) \
;         acc[ai][bj][m][n] = __builtin_amdgcn_mfma_f32_16x16x32_bf16(Bt[n][k], At[m][k], acc[ai][bj][m][n], 0, 0, 0); __builtin_amdgcn_s_setprio(0); } while (0)
; #define PG8_WAIT_V(n) asm volatile("s_waitcnt vmcnt(" #n ")" ::: "memory")
; #define PG8_WAIT_L(n) asm volatile("s_waitcnt lgkmcnt(" #n ")" ::: "memory")
; #define PG8_BAR __builtin_amdgcn_s_barrier()
; #define PG8_SCHED __builtin_amdgcn_sched_barrier(0)
; template <class Epi, class Sched, bool ALIGN_EPI = false, bool SP2 = false>
; __device__ __forceinline__ void gemm_phase(PG8_LAS unsigned char* lds, const Gemm g, const Sched& S, const Epi& E) {
;     ...
;             PG8_WAIT_V(8); PG8_WAIT_L(0); PG8_BAR; PG8_MMA(1, 0, At, B0); PG8_MMA(1, 1, At, B1); PG8_BAR; PG8_SCHED;
;             PG8_LDB(B0, 1, 0); PG8_LDB(B1, 1, 1); PG8_SCHED; PG8_LDA(At, 1, 0); PG8_STAGE(PG8_SA(0, 1), a2 + hstep, voffA);
;             PG8_WAIT_V(8); PG8_WAIT_L(0); PG8_BAR; PG8_MMA(0, 0, At, B0); PG8_MMA(0, 1, At, B1); PG8_BAR; PG8_SCHED;
	s_setprio 1
	s_waitcnt lgkmcnt(0)
	v_mfma_f32_16x16x32_bf16 v[60:63], v[144:147], v[184:187], 0
	v_mfma_f32_16x16x32_bf16 v[56:59], v[160:163], v[184:187], 0
	v_mfma_f32_16x16x32_bf16 v[52:55], v[168:171], v[184:187], 0
	v_mfma_f32_16x16x32_bf16 v[48:51], v[176:179], v[184:187], 0
	v_mfma_f32_16x16x32_bf16 v[44:47], v[144:147], v[192:195], 0
	v_mfma_f32_16x16x32_bf16 v[40:43], v[160:163], v[192:195], 0
	v_mfma_f32_16x16x32_bf16 v[36:39], v[168:171], v[192:195], 0
	v_mfma_f32_16x16x32_bf16 v[32:35], v[176:179], v[192:195], 0
	v_mfma_f32_16x16x32_bf16 v[28:31], v[144:147], v[200:203], 0
	v_mfma_f32_16x16x32_bf16 v[24:27], v[160:163], v[200:203], 0
	v_mfma_f32_16x16x32_bf16 v[20:23], v[168:171], v[200:203], 0
	v_mfma_f32_16x16x32_bf16 v[16:19], v[176:179], v[200:203], 0
	v_mfma_f32_16x16x32_bf16 v[12:15], v[144:147], v[210:213], 0
	v_mfma_f32_16x16x32_bf16 v[8:11], v[160:163], v[210:213], 0
	v_lshl_add_u64 v[222:223], s[42:43], 0, v[134:135]
	s_mov_b32 m0, s34
	s_nop 0
	global_load_lds_dwordx4 v[222:223], off
	v_mfma_f32_16x16x32_bf16 v[4:7], v[168:171], v[210:213], 0
	v_mfma_f32_16x16x32_bf16 v[0:3], v[176:179], v[210:213], 0
	s_setprio 0
	s_setprio 1
	v_mfma_f32_16x16x32_bf16 v[60:63], v[148:151], v[188:191], v[60:63]
	v_mfma_f32_16x16x32_bf16 v[56:59], v[164:167], v[188:191], v[56:59]
	v_mfma_f32_16x16x32_bf16 v[52:55], v[172:175], v[188:191], v[52:55]
	v_mfma_f32_16x16x32_bf16 v[48:51], v[180:183], v[188:191], v[48:51]
	v_mfma_f32_16x16x32_bf16 v[44:47], v[148:151], v[196:199], v[44:47]
	v_mfma_f32_16x16x32_bf16 v[40:43], v[164:167], v[196:199], v[40:43]
	v_mfma_f32_16x16x32_bf16 v[36:39], v[172:175], v[196:199], v[36:39]
	v_mfma_f32_16x16x32_bf16 v[32:35], v[180:183], v[196:199], v[32:35]
	v_mfma_f32_16x16x32_bf16 v[28:31], v[148:151], v[206:209], v[28:31]
	v_mfma_f32_16x16x32_bf16 v[24:27], v[164:167], v[206:209], v[24:27]
	v_mfma_f32_16x16x32_bf16 v[20:23], v[172:175], v[206:209], v[20:23]
	v_mfma_f32_16x16x32_bf16 v[16:19], v[180:183], v[206:209], v[16:19]
	v_mfma_f32_16x16x32_bf16 v[12:15], v[148:151], v[214:217], v[12:15]
	v_mfma_f32_16x16x32_bf16 v[8:11], v[164:167], v[214:217], v[8:11]
	v_lshl_add_u64 v[224:225], s[42:43], 0, v[130:131]
	s_mov_b32 m0, s37
	s_nop 0
	global_load_lds_dwordx4 v[224:225], off
	v_mfma_f32_16x16x32_bf16 v[4:7], v[172:175], v[214:217], v[4:7]
	v_mfma_f32_16x16x32_bf16 v[0:3], v[180:183], v[214:217], v[0:3]
	s_setprio 0
	s_barrier
	s_add_i32 s58, 0, 0x18000
	v_add_u32_e32 v159, s58, v153
	s_add_i32 s59, 0, 0x1c000
	ds_read_b128 v[144:147], v159
	ds_read_b128 v[148:151], v159 offset:1024
	ds_read_b128 v[160:163], v159 offset:2048
	ds_read_b128 v[164:167], v159 offset:3072
	v_add_u32_e32 v159, s59, v153
	ds_read_b128 v[168:171], v159
	ds_read_b128 v[172:175], v159 offset:1024
	ds_read_b128 v[176:179], v159 offset:2048
	ds_read_b128 v[180:183], v159 offset:3072
	s_add_u32 s42, s42, 0x40000
	s_addc_u32 s43, s43, 0
	s_mov_b32 m0, s44
	v_lshl_add_u64 v[226:227], s[42:43], 0, v[134:135]
	ds_read_b128 v[184:187], v157 offset:32768
	ds_read_b128 v[188:191], v157 offset:33792
	ds_read_b128 v[192:195], v157 offset:34816
	ds_read_b128 v[196:199], v157 offset:35840
	ds_read_b128 v[200:203], v157 offset:36864
	ds_read_b128 v[206:209], v157 offset:37888
	ds_read_b128 v[210:213], v157 offset:38912
	ds_read_b128 v[214:217], v157 offset:39936
	global_load_lds_dwordx4 v[226:227], off
	v_lshl_add_u64 v[226:227], s[42:43], 0, v[130:131]
	s_mov_b32 m0, s45
	s_nop 0
	global_load_lds_dwordx4 v[226:227], off
	s_waitcnt vmcnt(8)
	s_waitcnt lgkmcnt(0)
	s_barrier
	s_setprio 1
	s_waitcnt lgkmcnt(0)
	v_mfma_f32_16x16x32_bf16 v[124:127], v[144:147], v[184:187], v[124:127]
	v_mfma_f32_16x16x32_bf16 v[120:123], v[160:163], v[184:187], v[120:123]
	v_mfma_f32_16x16x32_bf16 v[116:119], v[168:171], v[184:187], v[116:119]
	v_mfma_f32_16x16x32_bf16 v[112:115], v[176:179], v[184:187], v[112:115]
	v_mfma_f32_16x16x32_bf16 v[108:111], v[144:147], v[192:195], v[108:111]
	v_mfma_f32_16x16x32_bf16 v[104:107], v[160:163], v[192:195], v[104:107]
	v_mfma_f32_16x16x32_bf16 v[100:103], v[168:171], v[192:195], v[100:103]
	v_mfma_f32_16x16x32_bf16 v[96:99], v[176:179], v[192:195], v[96:99]
	v_mfma_f32_16x16x32_bf16 v[92:95], v[144:147], v[200:203], v[92:95]
	v_mfma_f32_16x16x32_bf16 v[88:91], v[160:163], v[200:203], v[88:91]
	v_mfma_f32_16x16x32_bf16 v[84:87], v[168:171], v[200:203], v[84:87]
	v_mfma_f32_16x16x32_bf16 v[80:83], v[176:179], v[200:203], v[80:83]
	v_mfma_f32_16x16x32_bf16 v[76:79], v[144:147], v[210:213], v[76:79]
	v_mfma_f32_16x16x32_bf16 v[72:75], v[160:163], v[210:213], v[72:75]
	v_mfma_f32_16x16x32_bf16 v[68:71], v[168:171], v[210:213], v[68:71]
	v_mfma_f32_16x16x32_bf16 v[64:67], v[176:179], v[210:213], v[64:67]
	s_setprio 0
	s_setprio 1
	v_mfma_f32_16x16x32_bf16 v[124:127], v[148:151], v[188:191], v[124:127]
	v_mfma_f32_16x16x32_bf16 v[120:123], v[164:167], v[188:191], v[120:123]
	v_mfma_f32_16x16x32_bf16 v[116:119], v[172:175], v[188:191], v[116:119]
	v_mfma_f32_16x16x32_bf16 v[112:115], v[180:183], v[188:191], v[112:115]
	v_mfma_f32_16x16x32_bf16 v[108:111], v[148:151], v[196:199], v[108:111]
	v_mfma_f32_16x16x32_bf16 v[104:107], v[164:167], v[196:199], v[104:107]
	v_mfma_f32_16x16x32_bf16 v[100:103], v[172:175], v[196:199], v[100:103]
	v_mfma_f32_16x16x32_bf16 v[96:99], v[180:183], v[196:199], v[96:99]
	v_mfma_f32_16x16x32_bf16 v[92:95], v[148:151], v[206:209], v[92:95]
	v_mfma_f32_16x16x32_bf16 v[88:91], v[164:167], v[206:209], v[88:91]
	v_mfma_f32_16x16x32_bf16 v[84:87], v[172:175], v[206:209], v[84:87]
	v_mfma_f32_16x16x32_bf16 v[80:83], v[180:183], v[206:209], v[80:83]
	v_mfma_f32_16x16x32_bf16 v[76:79], v[148:151], v[214:217], v[76:79]
	v_mfma_f32_16x16x32_bf16 v[72:75], v[164:167], v[214:217], v[72:75]
	v_mfma_f32_16x16x32_bf16 v[68:71], v[172:175], v[214:217], v[68:71]
	v_mfma_f32_16x16x32_bf16 v[64:67], v[180:183], v[214:217], v[64:67]
	s_setprio 0
	s_barrier
; #define PG8_STAGE(bufoff, gbase, voff) do { _Pragma("unroll") for (int _i = 0; _i < 2; ++_i) \
;         __builtin_amdgcn_global_load_lds((const unsigned*)((const char*)(gbase) + (voff)[_i]), (PG8_LAS unsigned*)(lds + (bufoff) + ldsw + _i * 8192), 16, 0, 0); } while (0)
; #define PG8_LDA(dst, b, h) do { _Pragma("unroll") for (int m = 0; m < 4; ++m) _Pragma("unroll") for (int k = 0; k < 2; ++k) dst[m][k] = *(const PG8_LAS bf16x8*)(lds + PG8_SA(b, h) + aoff + m * 2048 + k * 1024); } while (0)
; #define PG8_LDB(dst, b, h) do { _Pragma("unroll") for (int n = 0; n < 2; ++n) _Pragma("unroll") for (int k = 0; k < 2; ++k) dst[n][k] = *(const PG8_LAS bf16x8*)(lds + PG8_SB(b, h) + boff + n * 2048 + k * 1024); } while (0)
; #define PG8_MMA(ai, bj, At, Bt) do { __builtin_amdgcn_s_setprio(1); _Pragma("unroll") for (int m = 0; m < 4; ++m) _Pragma("unroll") for (int n = 0; n < 2; ++n) _Pragma("unroll") for (int k = 0; k < 2; ++k) \
;         acc[ai][bj][m][n] = __builtin_amdgcn_mfma_f32_16x16x32_bf16(Bt[n][k], At[m][k], acc[ai][bj][m][n], 0, 0, 0); __builtin_amdgcn_s_setprio(0); } while (0)
; #define PG8_WAIT_V(n) asm volatile("s_waitcnt vmcnt(" #n ")" ::: "memory")
; #define PG8_WAIT_L(n) asm volatile("s_waitcnt lgkmcnt(" #n ")" ::: "memory")
; #define PG8_BAR __builtin_amdgcn_s_barrier()
; #define PG8_SCHED __builtin_amdgcn_sched_barrier(0)
; template <class Epi, class Sched, bool ALIGN_EPI = false, bool SP2 = false>
; __device__ __forceinline__ void gemm_phase(PG8_LAS unsigned char* lds, const Gemm g, const Sched& S, const Epi& E) {
;     ...
;             PG8_LDB(B0, 0, 0); PG8_LDB(B1, 0, 1); PG8_SCHED; PG8_LDA(At, 0, 0); PG8_STAGE(PG8_SA(1, 1), a1 + hstep, voffA);
;     ...
;             PG8_LDA(At, 1, 1); PG8_STAGE(PG8_SB(1, 0), b3, voffB); PG8_STAGE(PG8_SB(1, 1), b3 + hstep, voffB); PG8_STAGE(PG8_SA(1, 0), a3, voffA);
;             PG8_WAIT_V(8); PG8_WAIT_L(0); PG8_BAR; PG8_MMA(1, 0, At, B0); PG8_MMA(1, 1, At, B1); PG8_BAR; PG8_SCHED;
	s_add_i32 s42, s58, s15
	v_lshl_add_u64 v[218:219], v[218:219], 0, s[8:9]
	s_mov_b32 m0, s42
	ds_read_b128 v[184:187], v157 offset:49152
	ds_read_b128 v[188:191], v157 offset:50176
	ds_read_b128 v[192:195], v157 offset:51200
	ds_read_b128 v[196:199], v157 offset:52224
	ds_read_b128 v[200:203], v157 offset:53248
	ds_read_b128 v[206:209], v157 offset:54272
	ds_read_b128 v[210:213], v157 offset:55296
	ds_read_b128 v[214:217], v157 offset:56320
	global_load_lds_dwordx4 v[218:219], off
	s_add_i32 m0, s42, 0x2000
	s_add_u32 s40, s40, 0x40080
	v_lshl_add_u64 v[218:219], v[220:221], 0, s[8:9]
	s_addc_u32 s41, s41, 0
	s_add_i32 s42, s59, s15
	global_load_lds_dwordx4 v[218:219], off
	v_lshl_add_u64 v[218:219], s[40:41], 0, v[132:133]
	s_mov_b32 m0, s42
	s_nop 0
	global_load_lds_dwordx4 v[218:219], off
	v_lshl_add_u64 v[218:219], s[40:41], 0, v[128:129]
	s_add_i32 m0, s42, 0x2000
	s_nop 0
	global_load_lds_dwordx4 v[218:219], off
	s_waitcnt vmcnt(6)
	s_waitcnt lgkmcnt(0)
	s_barrier
	s_setprio 1
	s_waitcnt lgkmcnt(0)
	v_mfma_f32_16x16x32_bf16 v[60:63], v[144:147], v[184:187], v[60:63]
	v_mfma_f32_16x16x32_bf16 v[56:59], v[160:163], v[184:187], v[56:59]
	v_mfma_f32_16x16x32_bf16 v[52:55], v[168:171], v[184:187], v[52:55]
	v_mfma_f32_16x16x32_bf16 v[48:51], v[176:179], v[184:187], v[48:51]
	v_mfma_f32_16x16x32_bf16 v[44:47], v[144:147], v[192:195], v[44:47]
	v_mfma_f32_16x16x32_bf16 v[40:43], v[160:163], v[192:195], v[40:43]
	v_mfma_f32_16x16x32_bf16 v[36:39], v[168:171], v[192:195], v[36:39]
	v_mfma_f32_16x16x32_bf16 v[32:35], v[176:179], v[192:195], v[32:35]
	v_mfma_f32_16x16x32_bf16 v[28:31], v[144:147], v[200:203], v[28:31]
	v_mfma_f32_16x16x32_bf16 v[24:27], v[160:163], v[200:203], v[24:27]
	v_mfma_f32_16x16x32_bf16 v[20:23], v[168:171], v[200:203], v[20:23]
	v_mfma_f32_16x16x32_bf16 v[16:19], v[176:179], v[200:203], v[16:19]
	v_mfma_f32_16x16x32_bf16 v[12:15], v[144:147], v[210:213], v[12:15]
	v_mfma_f32_16x16x32_bf16 v[8:11], v[160:163], v[210:213], v[8:11]
	v_lshl_add_u64 v[218:219], v[222:223], 0, s[8:9]
	s_mov_b32 m0, s47
	s_nop 0
	global_load_lds_dwordx4 v[218:219], off
	v_mfma_f32_16x16x32_bf16 v[4:7], v[168:171], v[210:213], v[4:7]
	v_mfma_f32_16x16x32_bf16 v[0:3], v[176:179], v[210:213], v[0:3]
	s_setprio 0
	s_setprio 1
	v_mfma_f32_16x16x32_bf16 v[60:63], v[148:151], v[188:191], v[60:63]
	v_mfma_f32_16x16x32_bf16 v[56:59], v[164:167], v[188:191], v[56:59]
	v_mfma_f32_16x16x32_bf16 v[52:55], v[172:175], v[188:191], v[52:55]
	v_mfma_f32_16x16x32_bf16 v[48:51], v[180:183], v[188:191], v[48:51]
	v_mfma_f32_16x16x32_bf16 v[44:47], v[148:151], v[196:199], v[44:47]
	v_mfma_f32_16x16x32_bf16 v[40:43], v[164:167], v[196:199], v[40:43]
	v_mfma_f32_16x16x32_bf16 v[36:39], v[172:175], v[196:199], v[36:39]
	v_mfma_f32_16x16x32_bf16 v[32:35], v[180:183], v[196:199], v[32:35]
	v_mfma_f32_16x16x32_bf16 v[28:31], v[148:151], v[206:209], v[28:31]
	v_mfma_f32_16x16x32_bf16 v[24:27], v[164:167], v[206:209], v[24:27]
	v_mfma_f32_16x16x32_bf16 v[20:23], v[172:175], v[206:209], v[20:23]
	v_mfma_f32_16x16x32_bf16 v[16:19], v[180:183], v[206:209], v[16:19]
	v_mfma_f32_16x16x32_bf16 v[12:15], v[148:151], v[214:217], v[12:15]
	v_mfma_f32_16x16x32_bf16 v[8:11], v[164:167], v[214:217], v[8:11]
	v_lshl_add_u64 v[218:219], v[224:225], 0, s[8:9]
	s_mov_b32 m0, s48
	s_nop 0
	global_load_lds_dwordx4 v[218:219], off
	v_mfma_f32_16x16x32_bf16 v[4:7], v[172:175], v[214:217], v[4:7]
	v_mfma_f32_16x16x32_bf16 v[0:3], v[180:183], v[214:217], v[0:3]
	s_setprio 0
	s_barrier
	s_add_i32 s57, s57, 2
	s_add_u32 s38, s38, 0x100
	s_addc_u32 s39, s39, 0
	s_add_u32 s55, s55, 0x100
	s_addc_u32 s56, s56, 0
.LBB0_1900:
	ds_read_b128 v[144:147], v155
	ds_read_b128 v[148:151], v155 offset:1024
	ds_read_b128 v[160:163], v155 offset:2048
	ds_read_b128 v[164:167], v155 offset:3072
	ds_read_b128 v[168:171], v156
	ds_read_b128 v[172:175], v156 offset:1024
	ds_read_b128 v[176:179], v156 offset:2048
	ds_read_b128 v[180:183], v156 offset:3072
	s_add_u32 s40, s38, 0xfffc0080
	s_addc_u32 s41, s39, -1
	s_cmp_eq_u32 s57, 12
	s_cselect_b32 s43, s25, s41
	s_cselect_b32 s42, s53, s40
	s_cselect_b32 s41, s13, s56
	s_cselect_b32 s40, s54, s55
	v_lshl_add_u64 v[218:219], s[38:39], 0, v[136:137]
	s_add_i32 m0, s34, 0xc000
	ds_read_b128 v[184:187], v157
	ds_read_b128 v[188:191], v157 offset:1024
	ds_read_b128 v[192:195], v157 offset:2048
	ds_read_b128 v[196:199], v157 offset:3072
	ds_read_b128 v[200:203], v157 offset:4096
	ds_read_b128 v[206:209], v157 offset:5120
	ds_read_b128 v[210:213], v157 offset:6144
	ds_read_b128 v[214:217], v157 offset:7168
	global_load_lds_dwordx4 v[218:219], off
	v_lshl_add_u64 v[218:219], s[38:39], 0, v[138:139]
	s_add_i32 m0, s34, 0xe000
	s_nop 0
	global_load_lds_dwordx4 v[218:219], off
	s_waitcnt vmcnt(8)
	s_waitcnt lgkmcnt(0)
	s_barrier
; #define PG8_STAGE(bufoff, gbase, voff) do { _Pragma("unroll") for (int _i = 0; _i < 2; ++_i) \
;         __builtin_amdgcn_global_load_lds((const unsigned*)((const char*)(gbase) + (voff)[_i]), (PG8_LAS unsigned*)(lds + (bufoff) + ldsw + _i * 8192), 16, 0, 0); } while (0)
; #define PG8_LDA(dst, b, h) do { _Pragma("unroll") for (int m = 0; m < 4; ++m) _Pragma("unroll") for (int k = 0; k < 2; ++k) dst[m][k] = *(const PG8_LAS bf16x8*)(lds + PG8_SA(b, h) + aoff + m * 2048 + k * 1024); } while (0)
; #define PG8_LDB(dst, b, h) do { _Pragma("unroll") for (int n = 0; n < 2; ++n) _Pragma("unroll") for (int k = 0; k < 2; ++k) dst[n][k] = *(const PG8_LAS bf16x8*)(lds + PG8_SB(b, h) + boff + n * 2048 + k * 1024); } while (0)
; #define PG8_MMA(ai, bj, At, Bt) do { __builtin_amdgcn_s_setprio(1); _Pragma("unroll") for (int m = 0; m < 4; ++m) _Pragma("unroll") for (int n = 0; n < 2; ++n) _Pragma("unroll") for (int k = 0; k < 2; ++k) \
;         acc[ai][bj][m][n] = __builtin_amdgcn_mfma_f32_16x16x32_bf16(Bt[n][k], At[m][k], acc[ai][bj][m][n], 0, 0, 0); __builtin_amdgcn_s_setprio(0); } while (0)
; #define PG8_WAIT_V(n) asm volatile("s_waitcnt vmcnt(" #n ")" ::: "memory")
; #define PG8_WAIT_L(n) asm volatile("s_waitcnt lgkmcnt(" #n ")" ::: "memory")
; #define PG8_BAR __builtin_amdgcn_s_barrier()
; #define PG8_SCHED __builtin_amdgcn_sched_barrier(0)
; template <class Epi, class Sched, bool ALIGN_EPI = false, bool SP2 = false>
; __device__ __forceinline__ void gemm_phase(PG8_LAS unsigned char* lds, const Gemm g, const Sched& S, const Epi& E) {
;     ...
;             PG8_LDB(B0, 0, 0); PG8_LDB(B1, 0, 1); PG8_SCHED; PG8_LDA(At, 0, 0); PG8_STAGE(PG8_SA(1, 1), a1 + hstep, voffA);
;             PG8_WAIT_V(8); PG8_WAIT_L(0); PG8_BAR; PG8_MMA(0, 0, At, B0); PG8_MMA(0, 1, At, B1); PG8_BAR; PG8_SCHED;
;             PG8_LDA(At, 0, 1); PG8_STAGE(PG8_SB(0, 0), b2, voffB); PG8_STAGE(PG8_SB(0, 1), b2 + hstep, voffB); PG8_STAGE(PG8_SA(0, 0), a2, voffA);
;             PG8_WAIT_V(8); PG8_WAIT_L(0); PG8_BAR; PG8_MMA(1, 0, At, B0); PG8_MMA(1, 1, At, B1); PG8_BAR; PG8_SCHED;
	s_setprio 1
	s_waitcnt lgkmcnt(0)
	v_mfma_f32_16x16x32_bf16 v[124:127], v[144:147], v[184:187], v[124:127]
	v_mfma_f32_16x16x32_bf16 v[120:123], v[160:163], v[184:187], v[120:123]
	v_mfma_f32_16x16x32_bf16 v[116:119], v[168:171], v[184:187], v[116:119]
	v_mfma_f32_16x16x32_bf16 v[112:115], v[176:179], v[184:187], v[112:115]
	v_mfma_f32_16x16x32_bf16 v[108:111], v[144:147], v[192:195], v[108:111]
	v_mfma_f32_16x16x32_bf16 v[104:107], v[160:163], v[192:195], v[104:107]
	v_mfma_f32_16x16x32_bf16 v[100:103], v[168:171], v[192:195], v[100:103]
	v_mfma_f32_16x16x32_bf16 v[96:99], v[176:179], v[192:195], v[96:99]
	v_mfma_f32_16x16x32_bf16 v[92:95], v[144:147], v[200:203], v[92:95]
	v_mfma_f32_16x16x32_bf16 v[88:91], v[160:163], v[200:203], v[88:91]
	v_mfma_f32_16x16x32_bf16 v[84:87], v[168:171], v[200:203], v[84:87]
	v_mfma_f32_16x16x32_bf16 v[80:83], v[176:179], v[200:203], v[80:83]
	v_mfma_f32_16x16x32_bf16 v[76:79], v[144:147], v[210:213], v[76:79]
	v_mfma_f32_16x16x32_bf16 v[72:75], v[160:163], v[210:213], v[72:75]
	v_mfma_f32_16x16x32_bf16 v[68:71], v[168:171], v[210:213], v[68:71]
	v_mfma_f32_16x16x32_bf16 v[64:67], v[176:179], v[210:213], v[64:67]
	s_setprio 0
	s_setprio 1
	v_mfma_f32_16x16x32_bf16 v[124:127], v[148:151], v[188:191], v[124:127]
	v_mfma_f32_16x16x32_bf16 v[120:123], v[164:167], v[188:191], v[120:123]
	v_mfma_f32_16x16x32_bf16 v[116:119], v[172:175], v[188:191], v[116:119]
	v_mfma_f32_16x16x32_bf16 v[112:115], v[180:183], v[188:191], v[112:115]
	v_mfma_f32_16x16x32_bf16 v[108:111], v[148:151], v[196:199], v[108:111]
	v_mfma_f32_16x16x32_bf16 v[104:107], v[164:167], v[196:199], v[104:107]
	v_mfma_f32_16x16x32_bf16 v[100:103], v[172:175], v[196:199], v[100:103]
	v_mfma_f32_16x16x32_bf16 v[96:99], v[180:183], v[196:199], v[96:99]
	v_mfma_f32_16x16x32_bf16 v[92:95], v[148:151], v[206:209], v[92:95]
	v_mfma_f32_16x16x32_bf16 v[88:91], v[164:167], v[206:209], v[88:91]
	v_mfma_f32_16x16x32_bf16 v[84:87], v[172:175], v[206:209], v[84:87]
	v_mfma_f32_16x16x32_bf16 v[80:83], v[180:183], v[206:209], v[80:83]
	v_mfma_f32_16x16x32_bf16 v[76:79], v[148:151], v[214:217], v[76:79]
	v_mfma_f32_16x16x32_bf16 v[72:75], v[164:167], v[214:217], v[72:75]
	v_mfma_f32_16x16x32_bf16 v[68:71], v[172:175], v[214:217], v[68:71]
	v_mfma_f32_16x16x32_bf16 v[64:67], v[180:183], v[214:217], v[64:67]
	s_setprio 0
	s_barrier
	s_add_i32 s58, s49, s15
	v_lshl_add_u64 v[218:219], s[40:41], 0, v[132:133]
	s_mov_b32 m0, s58
	ds_read_b128 v[184:187], v157 offset:16384
	ds_read_b128 v[188:191], v157 offset:17408
	ds_read_b128 v[192:195], v157 offset:18432
	ds_read_b128 v[196:199], v157 offset:19456
	ds_read_b128 v[200:203], v157 offset:20480
	ds_read_b128 v[206:209], v157 offset:21504
	ds_read_b128 v[210:213], v157 offset:22528
	ds_read_b128 v[214:217], v157 offset:23552
	global_load_lds_dwordx4 v[218:219], off
	s_add_i32 m0, s58, 0x2000
	s_add_u32 s58, s40, 0x40000
	v_lshl_add_u64 v[220:221], s[40:41], 0, v[128:129]
	s_addc_u32 s59, s41, 0
	s_add_i32 s60, s50, s15
	global_load_lds_dwordx4 v[220:221], off
	v_lshl_add_u64 v[222:223], s[58:59], 0, v[132:133]
	s_mov_b32 m0, s60
	global_load_lds_dwordx4 v[222:223], off
	v_lshl_add_u64 v[222:223], s[58:59], 0, v[128:129]
	s_add_i32 m0, s60, 0x2000
	s_nop 0
	global_load_lds_dwordx4 v[222:223], off
	s_waitcnt vmcnt(6)
	s_waitcnt lgkmcnt(0)
	s_barrier
	s_setprio 1
	s_waitcnt lgkmcnt(0)
	v_mfma_f32_16x16x32_bf16 v[60:63], v[144:147], v[184:187], v[60:63]
	v_mfma_f32_16x16x32_bf16 v[56:59], v[160:163], v[184:187], v[56:59]
	v_mfma_f32_16x16x32_bf16 v[52:55], v[168:171], v[184:187], v[52:55]
	v_mfma_f32_16x16x32_bf16 v[48:51], v[176:179], v[184:187], v[48:51]
	v_mfma_f32_16x16x32_bf16 v[44:47], v[144:147], v[192:195], v[44:47]
	v_mfma_f32_16x16x32_bf16 v[40:43], v[160:163], v[192:195], v[40:43]
	v_mfma_f32_16x16x32_bf16 v[36:39], v[168:171], v[192:195], v[36:39]
	v_mfma_f32_16x16x32_bf16 v[32:35], v[176:179], v[192:195], v[32:35]
	v_mfma_f32_16x16x32_bf16 v[28:31], v[144:147], v[200:203], v[28:31]
	v_mfma_f32_16x16x32_bf16 v[24:27], v[160:163], v[200:203], v[24:27]
	v_mfma_f32_16x16x32_bf16 v[20:23], v[168:171], v[200:203], v[20:23]
	v_mfma_f32_16x16x32_bf16 v[16:19], v[176:179], v[200:203], v[16:19]
	v_mfma_f32_16x16x32_bf16 v[12:15], v[144:147], v[210:213], v[12:15]
	v_mfma_f32_16x16x32_bf16 v[8:11], v[160:163], v[210:213], v[8:11]
	v_lshl_add_u64 v[222:223], s[42:43], 0, v[134:135]
	s_mov_b32 m0, s34
	s_nop 0
	global_load_lds_dwordx4 v[222:223], off
	v_mfma_f32_16x16x32_bf16 v[4:7], v[168:171], v[210:213], v[4:7]
	v_mfma_f32_16x16x32_bf16 v[0:3], v[176:179], v[210:213], v[0:3]
	s_setprio 0
	s_setprio 1
	v_mfma_f32_16x16x32_bf16 v[60:63], v[148:151], v[188:191], v[60:63]
	v_mfma_f32_16x16x32_bf16 v[56:59], v[164:167], v[188:191], v[56:59]
	v_mfma_f32_16x16x32_bf16 v[52:55], v[172:175], v[188:191], v[52:55]
	v_mfma_f32_16x16x32_bf16 v[48:51], v[180:183], v[188:191], v[48:51]
	v_mfma_f32_16x16x32_bf16 v[44:47], v[148:151], v[196:199], v[44:47]
	v_mfma_f32_16x16x32_bf16 v[40:43], v[164:167], v[196:199], v[40:43]
	v_mfma_f32_16x16x32_bf16 v[36:39], v[172:175], v[196:199], v[36:39]
	v_mfma_f32_16x16x32_bf16 v[32:35], v[180:183], v[196:199], v[32:35]
	v_mfma_f32_16x16x32_bf16 v[28:31], v[148:151], v[206:209], v[28:31]
	v_mfma_f32_16x16x32_bf16 v[24:27], v[164:167], v[206:209], v[24:27]
	v_mfma_f32_16x16x32_bf16 v[20:23], v[172:175], v[206:209], v[20:23]
	v_mfma_f32_16x16x32_bf16 v[16:19], v[180:183], v[206:209], v[16:19]
	v_mfma_f32_16x16x32_bf16 v[12:15], v[148:151], v[214:217], v[12:15]
	v_mfma_f32_16x16x32_bf16 v[8:11], v[164:167], v[214:217], v[8:11]
	v_lshl_add_u64 v[224:225], s[42:43], 0, v[130:131]
	s_mov_b32 m0, s37
	s_nop 0
	global_load_lds_dwordx4 v[224:225], off
	v_mfma_f32_16x16x32_bf16 v[4:7], v[172:175], v[214:217], v[4:7]
	v_mfma_f32_16x16x32_bf16 v[0:3], v[180:183], v[214:217], v[0:3]
	s_setprio 0
	s_barrier
; #define PG8_STAGE(bufoff, gbase, voff) do { _Pragma("unroll") for (int _i = 0; _i < 2; ++_i) \
;         __builtin_amdgcn_global_load_lds((const unsigned*)((const char*)(gbase) + (voff)[_i]), (PG8_LAS unsigned*)(lds + (bufoff) + ldsw + _i * 8192), 16, 0, 0); } while (0)
; #define PG8_LDA(dst, b, h) do { _Pragma("unroll") for (int m = 0; m < 4; ++m) _Pragma("unroll") for (int k = 0; k < 2; ++k) dst[m][k] = *(const PG8_LAS bf16x8*)(lds + PG8_SA(b, h) + aoff + m * 2048 + k * 1024); } while (0)
; #define PG8_LDB(dst, b, h) do { _Pragma("unroll") for (int n = 0; n < 2; ++n) _Pragma("unroll") for (int k = 0; k < 2; ++k) dst[n][k] = *(const PG8_LAS bf16x8*)(lds + PG8_SB(b, h) + boff + n * 2048 + k * 1024); } while (0)
; #define PG8_MMA(ai, bj, At, Bt) do { __builtin_amdgcn_s_setprio(1); _Pragma("unroll") for (int m = 0; m < 4; ++m) _Pragma("unroll") for (int n = 0; n < 2; ++n) _Pragma("unroll") for (int k = 0; k < 2; ++k) \
;         acc[ai][bj][m][n] = __builtin_amdgcn_mfma_f32_16x16x32_bf16(Bt[n][k], At[m][k], acc[ai][bj][m][n], 0, 0, 0); __builtin_amdgcn_s_setprio(0); } while (0)
; #define PG8_WAIT_V(n) asm volatile("s_waitcnt vmcnt(" #n ")" ::: "memory")
; #define PG8_WAIT_L(n) asm volatile("s_waitcnt lgkmcnt(" #n ")" ::: "memory")
; #define PG8_BAR __builtin_amdgcn_s_barrier()
; #define PG8_SCHED __builtin_amdgcn_sched_barrier(0)
; template <class Epi, class Sched, bool ALIGN_EPI = false, bool SP2 = false>
; __device__ __forceinline__ void gemm_phase(PG8_LAS unsigned char* lds, const Gemm g, const Sched& S, const Epi& E) {
;     ...
;             PG8_LDB(B0, 1, 0); PG8_LDB(B1, 1, 1); PG8_SCHED; PG8_LDA(At, 1, 0); PG8_STAGE(PG8_SA(0, 1), a2 + hstep, voffA);
;             PG8_WAIT_V(8); PG8_WAIT_L(0); PG8_BAR; PG8_MMA(0, 0, At, B0); PG8_MMA(0, 1, At, B1); PG8_BAR; PG8_SCHED;
	s_add_i32 s58, 0, 0x18000
	v_add_u32_e32 v159, s58, v153
	s_add_i32 s59, 0, 0x1c000
	ds_read_b128 v[144:147], v159
	ds_read_b128 v[148:151], v159 offset:1024
	ds_read_b128 v[160:163], v159 offset:2048
	ds_read_b128 v[164:167], v159 offset:3072
	v_add_u32_e32 v159, s59, v153
	ds_read_b128 v[168:171], v159
	ds_read_b128 v[172:175], v159 offset:1024
	ds_read_b128 v[176:179], v159 offset:2048
	ds_read_b128 v[180:183], v159 offset:3072
	s_add_u32 s42, s42, 0x40000
	s_addc_u32 s43, s43, 0
	s_mov_b32 m0, s44
	v_lshl_add_u64 v[226:227], s[42:43], 0, v[134:135]
	ds_read_b128 v[184:187], v157 offset:32768
	ds_read_b128 v[188:191], v157 offset:33792
	ds_read_b128 v[192:195], v157 offset:34816
	ds_read_b128 v[196:199], v157 offset:35840
	ds_read_b128 v[200:203], v157 offset:36864
	ds_read_b128 v[206:209], v157 offset:37888
	ds_read_b128 v[210:213], v157 offset:38912
	ds_read_b128 v[214:217], v157 offset:39936
	global_load_lds_dwordx4 v[226:227], off
	v_lshl_add_u64 v[226:227], s[42:43], 0, v[130:131]
	s_mov_b32 m0, s45
	s_nop 0
	global_load_lds_dwordx4 v[226:227], off
	s_waitcnt vmcnt(8)
	s_waitcnt lgkmcnt(0)
	s_barrier
	s_setprio 1
	s_waitcnt lgkmcnt(0)
	v_mfma_f32_16x16x32_bf16 v[124:127], v[144:147], v[184:187], v[124:127]
	v_mfma_f32_16x16x32_bf16 v[120:123], v[160:163], v[184:187], v[120:123]
	v_mfma_f32_16x16x32_bf16 v[116:119], v[168:171], v[184:187], v[116:119]
	v_mfma_f32_16x16x32_bf16 v[112:115], v[176:179], v[184:187], v[112:115]
	v_mfma_f32_16x16x32_bf16 v[108:111], v[144:147], v[192:195], v[108:111]
	v_mfma_f32_16x16x32_bf16 v[104:107], v[160:163], v[192:195], v[104:107]
	v_mfma_f32_16x16x32_bf16 v[100:103], v[168:171], v[192:195], v[100:103]
	v_mfma_f32_16x16x32_bf16 v[96:99], v[176:179], v[192:195], v[96:99]
	v_mfma_f32_16x16x32_bf16 v[92:95], v[144:147], v[200:203], v[92:95]
	v_mfma_f32_16x16x32_bf16 v[88:91], v[160:163], v[200:203], v[88:91]
	v_mfma_f32_16x16x32_bf16 v[84:87], v[168:171], v[200:203], v[84:87]
	v_mfma_f32_16x16x32_bf16 v[80:83], v[176:179], v[200:203], v[80:83]
	v_mfma_f32_16x16x32_bf16 v[76:79], v[144:147], v[210:213], v[76:79]
	v_mfma_f32_16x16x32_bf16 v[72:75], v[160:163], v[210:213], v[72:75]
	v_mfma_f32_16x16x32_bf16 v[68:71], v[168:171], v[210:213], v[68:71]
	v_mfma_f32_16x16x32_bf16 v[64:67], v[176:179], v[210:213], v[64:67]
	s_setprio 0
	s_setprio 1
	v_mfma_f32_16x16x32_bf16 v[124:127], v[148:151], v[188:191], v[124:127]
	v_mfma_f32_16x16x32_bf16 v[120:123], v[164:167], v[188:191], v[120:123]
	v_mfma_f32_16x16x32_bf16 v[116:119], v[172:175], v[188:191], v[116:119]
	v_mfma_f32_16x16x32_bf16 v[112:115], v[180:183], v[188:191], v[112:115]
	v_mfma_f32_16x16x32_bf16 v[108:111], v[148:151], v[196:199], v[108:111]
	v_mfma_f32_16x16x32_bf16 v[104:107], v[164:167], v[196:199], v[104:107]
	v_mfma_f32_16x16x32_bf16 v[100:103], v[172:175], v[196:199], v[100:103]
	v_mfma_f32_16x16x32_bf16 v[96:99], v[180:183], v[196:199], v[96:99]
	v_mfma_f32_16x16x32_bf16 v[92:95], v[148:151], v[206:209], v[92:95]
	v_mfma_f32_16x16x32_bf16 v[88:91], v[164:167], v[206:209], v[88:91]
	v_mfma_f32_16x16x32_bf16 v[84:87], v[172:175], v[206:209], v[84:87]
	v_mfma_f32_16x16x32_bf16 v[80:83], v[180:183], v[206:209], v[80:83]
	v_mfma_f32_16x16x32_bf16 v[76:79], v[148:151], v[214:217], v[76:79]
	v_mfma_f32_16x16x32_bf16 v[72:75], v[164:167], v[214:217], v[72:75]
	v_mfma_f32_16x16x32_bf16 v[68:71], v[172:175], v[214:217], v[68:71]
	v_mfma_f32_16x16x32_bf16 v[64:67], v[180:183], v[214:217], v[64:67]
	s_setprio 0
	s_barrier
; #define PG8_STAGE(bufoff, gbase, voff) do { _Pragma("unroll") for (int _i = 0; _i < 2; ++_i) \
;         __builtin_amdgcn_global_load_lds((const unsigned*)((const char*)(gbase) + (voff)[_i]), (PG8_LAS unsigned*)(lds + (bufoff) + ldsw + _i * 8192), 16, 0, 0); } while (0)
; #define PG8_LDA(dst, b, h) do { _Pragma("unroll") for (int m = 0; m < 4; ++m) _Pragma("unroll") for (int k = 0; k < 2; ++k) dst[m][k] = *(const PG8_LAS bf16x8*)(lds + PG8_SA(b, h) + aoff + m * 2048 + k * 1024); } while (0)
; #define PG8_MMA(ai, bj, At, Bt) do { __builtin_amdgcn_s_setprio(1); _Pragma("unroll") for (int m = 0; m < 4; ++m) _Pragma("unroll") for (int n = 0; n < 2; ++n) _Pragma("unroll") for (int k = 0; k < 2; ++k) \
;         acc[ai][bj][m][n] = __builtin_amdgcn_mfma_f32_16x16x32_bf16(Bt[n][k], At[m][k], acc[ai][bj][m][n], 0, 0, 0); __builtin_amdgcn_s_setprio(0); } while (0)
; #define PG8_WAIT_V(n) asm volatile("s_waitcnt vmcnt(" #n ")" ::: "memory")
; #define PG8_WAIT_L(n) asm volatile("s_waitcnt lgkmcnt(" #n ")" ::: "memory")
; #define PG8_BAR __builtin_amdgcn_s_barrier()
; #define PG8_SCHED __builtin_amdgcn_sched_barrier(0)
; __device__ __forceinline__ float row_rs(const float* ssp, int row) { const unsigned long long v = ((const unsigned long long*)ssp)[row];
; template <class Epi, class Sched, bool ALIGN_EPI = false, bool SP2 = false>
; __device__ __forceinline__ void gemm_phase(PG8_LAS unsigned char* lds, const Gemm g, const Sched& S, const Epi& E) {
;     ...
;             PG8_LDA(At, 1, 1); PG8_STAGE(PG8_SB(1, 0), b3, voffB); PG8_STAGE(PG8_SB(1, 1), b3 + hstep, voffB); PG8_STAGE(PG8_SA(1, 0), a3, voffA);
;             PG8_WAIT_V(8); PG8_WAIT_L(0); PG8_BAR; PG8_MMA(1, 0, At, B0); PG8_MMA(1, 1, At, B1); PG8_BAR; PG8_SCHED;
	s_add_i32 s42, s58, s15
	v_lshl_add_u64 v[218:219], v[218:219], 0, s[8:9]
	s_mov_b32 m0, s42
	ds_read_b128 v[184:187], v157 offset:49152
	ds_read_b128 v[188:191], v157 offset:50176
	ds_read_b128 v[192:195], v157 offset:51200
	ds_read_b128 v[196:199], v157 offset:52224
	ds_read_b128 v[200:203], v157 offset:53248
	ds_read_b128 v[206:209], v157 offset:54272
	ds_read_b128 v[210:213], v157 offset:55296
	ds_read_b128 v[214:217], v157 offset:56320
	global_load_lds_dwordx4 v[218:219], off
	s_add_i32 m0, s42, 0x2000
	s_add_u32 s40, s40, 0x40080
	v_lshl_add_u64 v[218:219], v[220:221], 0, s[8:9]
	s_addc_u32 s41, s41, 0
	s_add_i32 s42, s59, s15
	global_load_lds_dwordx4 v[218:219], off
	v_lshl_add_u64 v[218:219], s[40:41], 0, v[132:133]
	s_mov_b32 m0, s42
	s_nop 0
	global_load_lds_dwordx4 v[218:219], off
	v_lshl_add_u64 v[218:219], s[40:41], 0, v[128:129]
	s_add_i32 m0, s42, 0x2000
	s_nop 0
	global_load_lds_dwordx4 v[218:219], off
	s_waitcnt vmcnt(6)
	s_waitcnt lgkmcnt(0)
	s_barrier
	s_setprio 1
	s_waitcnt lgkmcnt(0)
	v_mfma_f32_16x16x32_bf16 v[60:63], v[144:147], v[184:187], v[60:63]
	v_mfma_f32_16x16x32_bf16 v[56:59], v[160:163], v[184:187], v[56:59]
	v_mfma_f32_16x16x32_bf16 v[52:55], v[168:171], v[184:187], v[52:55]
	v_mfma_f32_16x16x32_bf16 v[48:51], v[176:179], v[184:187], v[48:51]
	v_mfma_f32_16x16x32_bf16 v[44:47], v[144:147], v[192:195], v[44:47]
	v_mfma_f32_16x16x32_bf16 v[40:43], v[160:163], v[192:195], v[40:43]
	v_mfma_f32_16x16x32_bf16 v[36:39], v[168:171], v[192:195], v[36:39]
	v_mfma_f32_16x16x32_bf16 v[32:35], v[176:179], v[192:195], v[32:35]
	v_mfma_f32_16x16x32_bf16 v[28:31], v[144:147], v[200:203], v[28:31]
	v_mfma_f32_16x16x32_bf16 v[24:27], v[160:163], v[200:203], v[24:27]
	v_mfma_f32_16x16x32_bf16 v[20:23], v[168:171], v[200:203], v[20:23]
	v_mfma_f32_16x16x32_bf16 v[16:19], v[176:179], v[200:203], v[16:19]
	v_mfma_f32_16x16x32_bf16 v[12:15], v[144:147], v[210:213], v[12:15]
	v_mfma_f32_16x16x32_bf16 v[8:11], v[160:163], v[210:213], v[8:11]
	v_lshl_add_u64 v[218:219], v[222:223], 0, s[8:9]
	s_mov_b32 m0, s47
	s_nop 0
	global_load_lds_dwordx4 v[218:219], off
	v_mfma_f32_16x16x32_bf16 v[4:7], v[168:171], v[210:213], v[4:7]
	v_mfma_f32_16x16x32_bf16 v[0:3], v[176:179], v[210:213], v[0:3]
	s_setprio 0
	s_setprio 1
	v_mfma_f32_16x16x32_bf16 v[60:63], v[148:151], v[188:191], v[60:63]
	v_mfma_f32_16x16x32_bf16 v[56:59], v[164:167], v[188:191], v[56:59]
	v_mfma_f32_16x16x32_bf16 v[52:55], v[172:175], v[188:191], v[52:55]
	v_mfma_f32_16x16x32_bf16 v[48:51], v[180:183], v[188:191], v[48:51]
	v_mfma_f32_16x16x32_bf16 v[44:47], v[148:151], v[196:199], v[44:47]
	v_mfma_f32_16x16x32_bf16 v[40:43], v[164:167], v[196:199], v[40:43]
	v_mfma_f32_16x16x32_bf16 v[36:39], v[172:175], v[196:199], v[36:39]
	v_mfma_f32_16x16x32_bf16 v[32:35], v[180:183], v[196:199], v[32:35]
	v_mfma_f32_16x16x32_bf16 v[28:31], v[148:151], v[206:209], v[28:31]
	v_mfma_f32_16x16x32_bf16 v[24:27], v[164:167], v[206:209], v[24:27]
	v_mfma_f32_16x16x32_bf16 v[20:23], v[172:175], v[206:209], v[20:23]
	v_mfma_f32_16x16x32_bf16 v[16:19], v[180:183], v[206:209], v[16:19]
	v_mfma_f32_16x16x32_bf16 v[12:15], v[148:151], v[214:217], v[12:15]
	v_mfma_f32_16x16x32_bf16 v[8:11], v[164:167], v[214:217], v[8:11]
	v_lshl_add_u64 v[218:219], v[224:225], 0, s[8:9]
	s_mov_b32 m0, s48
	s_nop 0
	global_load_lds_dwordx4 v[218:219], off
	v_mfma_f32_16x16x32_bf16 v[4:7], v[172:175], v[214:217], v[4:7]
	v_mfma_f32_16x16x32_bf16 v[0:3], v[180:183], v[214:217], v[0:3]
	s_setprio 0
	s_barrier
	s_add_i32 s57, s57, 2
	s_add_u32 s38, s38, 0x100
	s_addc_u32 s39, s39, 0
	s_add_u32 s55, s55, 0x100
	s_addc_u32 s56, s56, 0
	s_cmp_gt_u32 s57, 13
	s_cbranch_scc0 .LBB0_1900
	v_lshl_add_u32 v144, s36, 8, v152
	v_ashrrev_i32_e32 v145, 31, v144
	v_lshl_add_u64 v[150:151], v[144:145], 3, s[0:1]
	global_load_dwordx2 v[182:183], v[150:151], off
	global_load_dwordx2 v[184:185], v[150:151], off offset:128
	global_load_dwordx2 v[186:187], v[150:151], off offset:256
	global_load_dwordx2 v[188:189], v[150:151], off offset:384
	global_load_dwordx2 v[190:191], v[150:151], off offset:1024
	global_load_dwordx2 v[192:193], v[150:151], off offset:1152
	global_load_dwordx2 v[194:195], v[150:151], off offset:1280
	global_load_dwordx2 v[196:197], v[150:151], off offset:1408
	s_and_b64 vcc, exec, s[10:11]
	s_cbranch_vccz .LBB0_1903
	s_barrier

; #define PG8_STAGE(bufoff, gbase, voff) do { _Pragma("unroll") for (int _i = 0; _i < 2; ++_i) \
;         __builtin_amdgcn_global_load_lds((const unsigned*)((const char*)(gbase) + (voff)[_i]), (PG8_LAS unsigned*)(lds + (bufoff) + ldsw + _i * 8192), 16, 0, 0); } while (0)
; #define PG8_LDA(dst, b, h) do { _Pragma("unroll") for (int m = 0; m < 4; ++m) _Pragma("unroll") for (int k = 0; k < 2; ++k) dst[m][k] = *(const PG8_LAS bf16x8*)(lds + PG8_SA(b, h) + aoff + m * 2048 + k * 1024); } while (0)
; #define PG8_LDB(dst, b, h) do { _Pragma("unroll") for (int n = 0; n < 2; ++n) _Pragma("unroll") for (int k = 0; k < 2; ++k) dst[n][k] = *(const PG8_LAS bf16x8*)(lds + PG8_SB(b, h) + boff + n * 2048 + k * 1024); } while (0)
; #define PG8_WAIT_V(n) asm volatile("s_waitcnt vmcnt(" #n ")" ::: "memory")
; #define PG8_WAIT_L(n) asm volatile("s_waitcnt lgkmcnt(" #n ")" ::: "memory")
; #define PG8_BAR __builtin_amdgcn_s_barrier()
; #define PG8_SCHED __builtin_amdgcn_sched_barrier(0)
; template <class Epi, class Sched, bool ALIGN_EPI = false, bool SP2 = false>
; __device__ __forceinline__ void gemm_phase(PG8_LAS unsigned char* lds, const Gemm g, const Sched& S, const Epi& E) {
;     ...
;         const bool has_next = S.next(ui + 1, nxt);
;         const char* nA = has_next ? (const char*)g.A + (size_t)nxt.pm * tstep : cA; const char* nB = has_next ? (const char*)g.Bt + (size_t)nxt.pn * tstep : cB;
;         for (int t = 0; t < nt; t += 2) {
;             const bool last = (t == nt - 2);
;             const char* a1 = cA + (size_t)(t + 1) * kstep;
;             const char* a2 = last ? nA : cA + (size_t)(t + 2) * kstep; const char* b2 = last ? nB : cB + (size_t)(t + 2) * kstep;
;             const char* a3 = a2 + kstep; const char* b3 = b2 + kstep;
;             if (last && has_next) S.a_ready(nxt);
;             if constexpr (SP2) {
;             PG8_LDB(B0, 0, 0); PG8_LDB(B1, 0, 1); PG8_SCHED; PG8_LDA(At, 0, 0); PG8_STAGE(PG8_SA(1, 1), a1 + hstep, voffA);
;             PG8_WAIT_V(8); PG8_WAIT_L(0); PG8_BAR; PG8_MMA(0, 0, At, B0); PG8_MMA(0, 1, At, B1); PG8_BAR; PG8_SCHED;
;             PG8_LDA(At, 0, 1); PG8_STAGE(PG8_SB(0, 0), b2, voffB); PG8_STAGE(PG8_SB(0, 1), b2 + hstep, voffB); PG8_STAGE(PG8_SA(0, 0), a2, voffA);
;             PG8_WAIT_V(8); PG8_WAIT_L(0); PG8_BAR; PG8_MMA(1, 0, At, B0); PG8_MMA(1, 1, At, B1); PG8_BAR; PG8_SCHED;
.LBB0_1977:
	s_add_u32 s53, s28, 0x100
	s_addc_u32 s54, s29, 0
	s_mov_b32 s55, -2
	s_waitcnt lgkmcnt(0)
	ds_read_b128 v[144:147], v151
	ds_read_b128 v[156:159], v151 offset:1024
	ds_read_b128 v[160:163], v151 offset:2048
	ds_read_b128 v[164:167], v151 offset:3072
	ds_read_b128 v[168:171], v152
	ds_read_b128 v[172:175], v152 offset:1024
	ds_read_b128 v[176:179], v152 offset:2048
	ds_read_b128 v[180:183], v152 offset:3072
	s_add_u32 s28, s26, 0x100
	s_addc_u32 s29, s27, 0
	s_cmp_eq_u32 s55, 40
	s_cselect_b32 s39, s1, s29
	s_cselect_b32 s38, s0, s28
	s_cselect_b32 s37, s25, s54
	s_cselect_b32 s36, s24, s53
	v_lshl_add_u64 v[218:219], s[26:27], 0, v[136:137]
	s_add_i32 m0, s33, 0xc000
	ds_read_b128 v[184:187], v153
	ds_read_b128 v[188:191], v153 offset:1024
	ds_read_b128 v[192:195], v153 offset:2048
	ds_read_b128 v[196:199], v153 offset:3072
	ds_read_b128 v[200:203], v153 offset:4096
	ds_read_b128 v[206:209], v153 offset:5120
	ds_read_b128 v[210:213], v153 offset:6144
	ds_read_b128 v[214:217], v153 offset:7168
	global_load_lds_dwordx4 v[218:219], off
	v_lshl_add_u64 v[218:219], s[26:27], 0, v[138:139]
	s_add_i32 m0, s33, 0xe000
	s_nop 0
	global_load_lds_dwordx4 v[218:219], off
	s_waitcnt vmcnt(8)
	s_waitcnt lgkmcnt(0)
	s_barrier
	s_setprio 1
	s_waitcnt lgkmcnt(0)
	v_mfma_f32_16x16x32_bf16 v[124:127], v[144:147], v[184:187], 0
	v_mfma_f32_16x16x32_bf16 v[120:123], v[160:163], v[184:187], 0
	v_mfma_f32_16x16x32_bf16 v[116:119], v[168:171], v[184:187], 0
	v_mfma_f32_16x16x32_bf16 v[112:115], v[176:179], v[184:187], 0
	v_mfma_f32_16x16x32_bf16 v[108:111], v[144:147], v[192:195], 0
	v_mfma_f32_16x16x32_bf16 v[104:107], v[160:163], v[192:195], 0
	v_mfma_f32_16x16x32_bf16 v[100:103], v[168:171], v[192:195], 0
	v_mfma_f32_16x16x32_bf16 v[96:99], v[176:179], v[192:195], 0
	v_mfma_f32_16x16x32_bf16 v[92:95], v[144:147], v[200:203], 0
	v_mfma_f32_16x16x32_bf16 v[88:91], v[160:163], v[200:203], 0
	v_mfma_f32_16x16x32_bf16 v[84:87], v[168:171], v[200:203], 0
	v_mfma_f32_16x16x32_bf16 v[80:83], v[176:179], v[200:203], 0
	v_mfma_f32_16x16x32_bf16 v[76:79], v[144:147], v[210:213], 0
	v_mfma_f32_16x16x32_bf16 v[72:75], v[160:163], v[210:213], 0
	v_mfma_f32_16x16x32_bf16 v[68:71], v[168:171], v[210:213], 0
	v_mfma_f32_16x16x32_bf16 v[64:67], v[176:179], v[210:213], 0
	s_setprio 0
	s_setprio 1
	v_mfma_f32_16x16x32_bf16 v[124:127], v[156:159], v[188:191], v[124:127]
	v_mfma_f32_16x16x32_bf16 v[120:123], v[164:167], v[188:191], v[120:123]
	v_mfma_f32_16x16x32_bf16 v[116:119], v[172:175], v[188:191], v[116:119]
	v_mfma_f32_16x16x32_bf16 v[112:115], v[180:183], v[188:191], v[112:115]
	v_mfma_f32_16x16x32_bf16 v[108:111], v[156:159], v[196:199], v[108:111]
	v_mfma_f32_16x16x32_bf16 v[104:107], v[164:167], v[196:199], v[104:107]
	v_mfma_f32_16x16x32_bf16 v[100:103], v[172:175], v[196:199], v[100:103]
	v_mfma_f32_16x16x32_bf16 v[96:99], v[180:183], v[196:199], v[96:99]
	v_mfma_f32_16x16x32_bf16 v[92:95], v[156:159], v[206:209], v[92:95]
	v_mfma_f32_16x16x32_bf16 v[88:91], v[164:167], v[206:209], v[88:91]
	v_mfma_f32_16x16x32_bf16 v[84:87], v[172:175], v[206:209], v[84:87]
	v_mfma_f32_16x16x32_bf16 v[80:83], v[180:183], v[206:209], v[80:83]
	v_mfma_f32_16x16x32_bf16 v[76:79], v[156:159], v[214:217], v[76:79]
	v_mfma_f32_16x16x32_bf16 v[72:75], v[164:167], v[214:217], v[72:75]
	v_mfma_f32_16x16x32_bf16 v[68:71], v[172:175], v[214:217], v[68:71]
	v_mfma_f32_16x16x32_bf16 v[64:67], v[180:183], v[214:217], v[64:67]
	s_setprio 0
	s_barrier
	s_add_i32 s26, s45, s15
	v_lshl_add_u64 v[218:219], s[36:37], 0, v[130:131]
	s_mov_b32 m0, s26
	ds_read_b128 v[184:187], v153 offset:16384
	ds_read_b128 v[188:191], v153 offset:17408
	ds_read_b128 v[192:195], v153 offset:18432
	ds_read_b128 v[196:199], v153 offset:19456
	ds_read_b128 v[200:203], v153 offset:20480
	ds_read_b128 v[206:209], v153 offset:21504
	ds_read_b128 v[210:213], v153 offset:22528
	ds_read_b128 v[214:217], v153 offset:23552
	global_load_lds_dwordx4 v[218:219], off
	s_add_i32 m0, s26, 0x2000
	s_add_u32 s26, s36, 0xb0000
	v_lshl_add_u64 v[220:221], s[36:37], 0, v[134:135]
	s_addc_u32 s27, s37, 0
	s_add_i32 s56, s46, s15
	global_load_lds_dwordx4 v[220:221], off
	v_lshl_add_u64 v[222:223], s[26:27], 0, v[130:131]
	s_mov_b32 m0, s56
	global_load_lds_dwordx4 v[222:223], off
	v_lshl_add_u64 v[222:223], s[26:27], 0, v[134:135]
	s_add_i32 m0, s56, 0x2000
	s_nop 0
	global_load_lds_dwordx4 v[222:223], off
	s_waitcnt vmcnt(6)
	s_waitcnt lgkmcnt(0)
	s_barrier
; #define PG8_STAGE(bufoff, gbase, voff) do { _Pragma("unroll") for (int _i = 0; _i < 2; ++_i) \
;         __builtin_amdgcn_global_load_lds((const unsigned*)((const char*)(gbase) + (voff)[_i]), (PG8_LAS unsigned*)(lds + (bufoff) + ldsw + _i * 8192), 16, 0, 0); } while (0)
; #define PG8_LDA(dst, b, h) do { _Pragma("unroll") for (int m = 0; m < 4; ++m) _Pragma("unroll") for (int k = 0; k < 2; ++k) dst[m][k] = *(const PG8_LAS bf16x8*)(lds + PG8_SA(b, h) + aoff + m * 2048 + k * 1024); } while (0)
; #define PG8_LDB(dst, b, h) do { _Pragma("unroll") for (int n = 0; n < 2; ++n) _Pragma("unroll") for (int k = 0; k < 2; ++k) dst[n][k] = *(const PG8_LAS bf16x8*)(lds + PG8_SB(b, h) + boff + n * 2048 + k * 1024); } while (0)
; #define PG8_MMA(ai, bj, At, Bt) do { __builtin_amdgcn_s_setprio(1); _Pragma("unroll") for (int m = 0; m < 4; ++m) _Pragma("unroll") for (int n = 0; n < 2; ++n) _Pragma("unroll") for (int k = 0; k < 2; ++k) \
;         acc[ai][bj][m][n] = __builtin_amdgcn_mfma_f32_16x16x32_bf16(Bt[n][k], At[m][k], acc[ai][bj][m][n], 0, 0, 0); __builtin_amdgcn_s_setprio(0); } while (0)
; #define PG8_WAIT_V(n) asm volatile("s_waitcnt vmcnt(" #n ")" ::: "memory")
; #define PG8_WAIT_L(n) asm volatile("s_waitcnt lgkmcnt(" #n ")" ::: "memory")
; #define PG8_BAR __builtin_amdgcn_s_barrier()
; #define PG8_SCHED __builtin_amdgcn_sched_barrier(0)
; template <class Epi, class Sched, bool ALIGN_EPI = false, bool SP2 = false>
; __device__ __forceinline__ void gemm_phase(PG8_LAS unsigned char* lds, const Gemm g, const Sched& S, const Epi& E) {
;     ...
;             PG8_WAIT_V(8); PG8_WAIT_L(0); PG8_BAR; PG8_MMA(1, 0, At, B0); PG8_MMA(1, 1, At, B1); PG8_BAR; PG8_SCHED;
;             PG8_LDB(B0, 1, 0); PG8_LDB(B1, 1, 1); PG8_SCHED; PG8_LDA(At, 1, 0); PG8_STAGE(PG8_SA(0, 1), a2 + hstep, voffA);
;             PG8_WAIT_V(8); PG8_WAIT_L(0); PG8_BAR; PG8_MMA(0, 0, At, B0); PG8_MMA(0, 1, At, B1); PG8_BAR; PG8_SCHED;
	s_setprio 1
	s_waitcnt lgkmcnt(0)
	v_mfma_f32_16x16x32_bf16 v[60:63], v[144:147], v[184:187], 0
	v_mfma_f32_16x16x32_bf16 v[56:59], v[160:163], v[184:187], 0
	v_mfma_f32_16x16x32_bf16 v[52:55], v[168:171], v[184:187], 0
	v_mfma_f32_16x16x32_bf16 v[48:51], v[176:179], v[184:187], 0
	v_mfma_f32_16x16x32_bf16 v[44:47], v[144:147], v[192:195], 0
	v_mfma_f32_16x16x32_bf16 v[40:43], v[160:163], v[192:195], 0
	v_mfma_f32_16x16x32_bf16 v[36:39], v[168:171], v[192:195], 0
	v_mfma_f32_16x16x32_bf16 v[32:35], v[176:179], v[192:195], 0
	v_mfma_f32_16x16x32_bf16 v[28:31], v[144:147], v[200:203], 0
	v_mfma_f32_16x16x32_bf16 v[24:27], v[160:163], v[200:203], 0
	v_mfma_f32_16x16x32_bf16 v[20:23], v[168:171], v[200:203], 0
	v_mfma_f32_16x16x32_bf16 v[16:19], v[176:179], v[200:203], 0
	v_mfma_f32_16x16x32_bf16 v[12:15], v[144:147], v[210:213], 0
	v_mfma_f32_16x16x32_bf16 v[8:11], v[160:163], v[210:213], 0
	v_lshl_add_u64 v[222:223], s[38:39], 0, v[128:129]
	s_mov_b32 m0, s33
	s_nop 0
	global_load_lds_dwordx4 v[222:223], off
	v_mfma_f32_16x16x32_bf16 v[4:7], v[168:171], v[210:213], 0
	v_mfma_f32_16x16x32_bf16 v[0:3], v[176:179], v[210:213], 0
	s_setprio 0
	s_setprio 1
	v_mfma_f32_16x16x32_bf16 v[60:63], v[156:159], v[188:191], v[60:63]
	v_mfma_f32_16x16x32_bf16 v[56:59], v[164:167], v[188:191], v[56:59]
	v_mfma_f32_16x16x32_bf16 v[52:55], v[172:175], v[188:191], v[52:55]
	v_mfma_f32_16x16x32_bf16 v[48:51], v[180:183], v[188:191], v[48:51]
	v_mfma_f32_16x16x32_bf16 v[44:47], v[156:159], v[196:199], v[44:47]
	v_mfma_f32_16x16x32_bf16 v[40:43], v[164:167], v[196:199], v[40:43]
	v_mfma_f32_16x16x32_bf16 v[36:39], v[172:175], v[196:199], v[36:39]
	v_mfma_f32_16x16x32_bf16 v[32:35], v[180:183], v[196:199], v[32:35]
	v_mfma_f32_16x16x32_bf16 v[28:31], v[156:159], v[206:209], v[28:31]
	v_mfma_f32_16x16x32_bf16 v[24:27], v[164:167], v[206:209], v[24:27]
	v_mfma_f32_16x16x32_bf16 v[20:23], v[172:175], v[206:209], v[20:23]
	v_mfma_f32_16x16x32_bf16 v[16:19], v[180:183], v[206:209], v[16:19]
	v_mfma_f32_16x16x32_bf16 v[12:15], v[156:159], v[214:217], v[12:15]
	v_mfma_f32_16x16x32_bf16 v[8:11], v[164:167], v[214:217], v[8:11]
	v_lshl_add_u64 v[224:225], s[38:39], 0, v[132:133]
	s_mov_b32 m0, s34
	s_nop 0
	global_load_lds_dwordx4 v[224:225], off
	v_mfma_f32_16x16x32_bf16 v[4:7], v[172:175], v[214:217], v[4:7]
	v_mfma_f32_16x16x32_bf16 v[0:3], v[180:183], v[214:217], v[0:3]
	s_setprio 0
	s_barrier
	s_add_i32 s56, 0, 0x18000
	v_add_u32_e32 v155, s56, v149
	s_add_i32 s57, 0, 0x1c000
	ds_read_b128 v[144:147], v155
	ds_read_b128 v[156:159], v155 offset:1024
	ds_read_b128 v[160:163], v155 offset:2048
	ds_read_b128 v[164:167], v155 offset:3072
	v_add_u32_e32 v155, s57, v149
	ds_read_b128 v[168:171], v155
	ds_read_b128 v[172:175], v155 offset:1024
	ds_read_b128 v[176:179], v155 offset:2048
	ds_read_b128 v[180:183], v155 offset:3072
	s_add_u32 s26, s38, 0xb0000
	s_addc_u32 s27, s39, 0
	s_mov_b32 m0, s40
	v_lshl_add_u64 v[226:227], s[26:27], 0, v[128:129]
	ds_read_b128 v[184:187], v153 offset:32768
	ds_read_b128 v[188:191], v153 offset:33792
	ds_read_b128 v[192:195], v153 offset:34816
	ds_read_b128 v[196:199], v153 offset:35840
	ds_read_b128 v[200:203], v153 offset:36864
	ds_read_b128 v[206:209], v153 offset:37888
	ds_read_b128 v[210:213], v153 offset:38912
	ds_read_b128 v[214:217], v153 offset:39936
	global_load_lds_dwordx4 v[226:227], off
	v_lshl_add_u64 v[226:227], s[26:27], 0, v[132:133]
	s_mov_b32 m0, s41
	s_nop 0
	global_load_lds_dwordx4 v[226:227], off
	s_waitcnt vmcnt(8)
	s_waitcnt lgkmcnt(0)
	s_barrier
	s_setprio 1
	s_waitcnt lgkmcnt(0)
	v_mfma_f32_16x16x32_bf16 v[124:127], v[144:147], v[184:187], v[124:127]
	v_mfma_f32_16x16x32_bf16 v[120:123], v[160:163], v[184:187], v[120:123]
	v_mfma_f32_16x16x32_bf16 v[116:119], v[168:171], v[184:187], v[116:119]
	v_mfma_f32_16x16x32_bf16 v[112:115], v[176:179], v[184:187], v[112:115]
	v_mfma_f32_16x16x32_bf16 v[108:111], v[144:147], v[192:195], v[108:111]
	v_mfma_f32_16x16x32_bf16 v[104:107], v[160:163], v[192:195], v[104:107]
	v_mfma_f32_16x16x32_bf16 v[100:103], v[168:171], v[192:195], v[100:103]
	v_mfma_f32_16x16x32_bf16 v[96:99], v[176:179], v[192:195], v[96:99]
	v_mfma_f32_16x16x32_bf16 v[92:95], v[144:147], v[200:203], v[92:95]
	v_mfma_f32_16x16x32_bf16 v[88:91], v[160:163], v[200:203], v[88:91]
	v_mfma_f32_16x16x32_bf16 v[84:87], v[168:171], v[200:203], v[84:87]
	v_mfma_f32_16x16x32_bf16 v[80:83], v[176:179], v[200:203], v[80:83]
	v_mfma_f32_16x16x32_bf16 v[76:79], v[144:147], v[210:213], v[76:79]
	v_mfma_f32_16x16x32_bf16 v[72:75], v[160:163], v[210:213], v[72:75]
	v_mfma_f32_16x16x32_bf16 v[68:71], v[168:171], v[210:213], v[68:71]
	v_mfma_f32_16x16x32_bf16 v[64:67], v[176:179], v[210:213], v[64:67]
	s_setprio 0
	s_setprio 1
	v_mfma_f32_16x16x32_bf16 v[124:127], v[156:159], v[188:191], v[124:127]
	v_mfma_f32_16x16x32_bf16 v[120:123], v[164:167], v[188:191], v[120:123]
	v_mfma_f32_16x16x32_bf16 v[116:119], v[172:175], v[188:191], v[116:119]
	v_mfma_f32_16x16x32_bf16 v[112:115], v[180:183], v[188:191], v[112:115]
	v_mfma_f32_16x16x32_bf16 v[108:111], v[156:159], v[196:199], v[108:111]
	v_mfma_f32_16x16x32_bf16 v[104:107], v[164:167], v[196:199], v[104:107]
	v_mfma_f32_16x16x32_bf16 v[100:103], v[172:175], v[196:199], v[100:103]
	v_mfma_f32_16x16x32_bf16 v[96:99], v[180:183], v[196:199], v[96:99]
	v_mfma_f32_16x16x32_bf16 v[92:95], v[156:159], v[206:209], v[92:95]
	v_mfma_f32_16x16x32_bf16 v[88:91], v[164:167], v[206:209], v[88:91]
	v_mfma_f32_16x16x32_bf16 v[84:87], v[172:175], v[206:209], v[84:87]
	v_mfma_f32_16x16x32_bf16 v[80:83], v[180:183], v[206:209], v[80:83]
	v_mfma_f32_16x16x32_bf16 v[76:79], v[156:159], v[214:217], v[76:79]
	v_mfma_f32_16x16x32_bf16 v[72:75], v[164:167], v[214:217], v[72:75]
	v_mfma_f32_16x16x32_bf16 v[68:71], v[172:175], v[214:217], v[68:71]
	v_mfma_f32_16x16x32_bf16 v[64:67], v[180:183], v[214:217], v[64:67]
	s_setprio 0
	s_barrier
; #define PG8_STAGE(bufoff, gbase, voff) do { _Pragma("unroll") for (int _i = 0; _i < 2; ++_i) \
;         __builtin_amdgcn_global_load_lds((const unsigned*)((const char*)(gbase) + (voff)[_i]), (PG8_LAS unsigned*)(lds + (bufoff) + ldsw + _i * 8192), 16, 0, 0); } while (0)
; #define PG8_LDA(dst, b, h) do { _Pragma("unroll") for (int m = 0; m < 4; ++m) _Pragma("unroll") for (int k = 0; k < 2; ++k) dst[m][k] = *(const PG8_LAS bf16x8*)(lds + PG8_SA(b, h) + aoff + m * 2048 + k * 1024); } while (0)
; #define PG8_LDB(dst, b, h) do { _Pragma("unroll") for (int n = 0; n < 2; ++n) _Pragma("unroll") for (int k = 0; k < 2; ++k) dst[n][k] = *(const PG8_LAS bf16x8*)(lds + PG8_SB(b, h) + boff + n * 2048 + k * 1024); } while (0)
; #define PG8_MMA(ai, bj, At, Bt) do { __builtin_amdgcn_s_setprio(1); _Pragma("unroll") for (int m = 0; m < 4; ++m) _Pragma("unroll") for (int n = 0; n < 2; ++n) _Pragma("unroll") for (int k = 0; k < 2; ++k) \
;         acc[ai][bj][m][n] = __builtin_amdgcn_mfma_f32_16x16x32_bf16(Bt[n][k], At[m][k], acc[ai][bj][m][n], 0, 0, 0); __builtin_amdgcn_s_setprio(0); } while (0)
; #define PG8_WAIT_V(n) asm volatile("s_waitcnt vmcnt(" #n ")" ::: "memory")
; #define PG8_WAIT_L(n) asm volatile("s_waitcnt lgkmcnt(" #n ")" ::: "memory")
; #define PG8_BAR __builtin_amdgcn_s_barrier()
; #define PG8_SCHED __builtin_amdgcn_sched_barrier(0)
; template <class Epi, class Sched, bool ALIGN_EPI = false, bool SP2 = false>
; __device__ __forceinline__ void gemm_phase(PG8_LAS unsigned char* lds, const Gemm g, const Sched& S, const Epi& E) {
;     ...
;             PG8_LDB(B0, 0, 0); PG8_LDB(B1, 0, 1); PG8_SCHED; PG8_LDA(At, 0, 0); PG8_STAGE(PG8_SA(1, 1), a1 + hstep, voffA);
;     ...
;             PG8_LDA(At, 1, 1); PG8_STAGE(PG8_SB(1, 0), b3, voffB); PG8_STAGE(PG8_SB(1, 1), b3 + hstep, voffB); PG8_STAGE(PG8_SA(1, 0), a3, voffA);
;             PG8_WAIT_V(8); PG8_WAIT_L(0); PG8_BAR; PG8_MMA(1, 0, At, B0); PG8_MMA(1, 1, At, B1); PG8_BAR; PG8_SCHED;
	s_add_i32 s26, s56, s15
	v_lshl_add_u64 v[218:219], v[218:219], 0, s[12:13]
	s_mov_b32 m0, s26
	ds_read_b128 v[184:187], v153 offset:49152
	ds_read_b128 v[188:191], v153 offset:50176
	ds_read_b128 v[192:195], v153 offset:51200
	ds_read_b128 v[196:199], v153 offset:52224
	ds_read_b128 v[200:203], v153 offset:53248
	ds_read_b128 v[206:209], v153 offset:54272
	ds_read_b128 v[210:213], v153 offset:55296
	ds_read_b128 v[214:217], v153 offset:56320
	global_load_lds_dwordx4 v[218:219], off
	s_add_i32 m0, s26, 0x2000
	s_add_u32 s26, s36, 0xb0080
	v_lshl_add_u64 v[218:219], v[220:221], 0, s[12:13]
	s_addc_u32 s27, s37, 0
	s_add_i32 s36, s57, s15
	global_load_lds_dwordx4 v[218:219], off
	v_lshl_add_u64 v[218:219], s[26:27], 0, v[130:131]
	s_mov_b32 m0, s36
	s_nop 0
	global_load_lds_dwordx4 v[218:219], off
	v_lshl_add_u64 v[218:219], s[26:27], 0, v[134:135]
	s_add_i32 m0, s36, 0x2000
	s_nop 0
	global_load_lds_dwordx4 v[218:219], off
	s_waitcnt vmcnt(6)
	s_waitcnt lgkmcnt(0)
	s_barrier
	s_setprio 1
	s_waitcnt lgkmcnt(0)
	v_mfma_f32_16x16x32_bf16 v[60:63], v[144:147], v[184:187], v[60:63]
	v_mfma_f32_16x16x32_bf16 v[56:59], v[160:163], v[184:187], v[56:59]
	v_mfma_f32_16x16x32_bf16 v[52:55], v[168:171], v[184:187], v[52:55]
	v_mfma_f32_16x16x32_bf16 v[48:51], v[176:179], v[184:187], v[48:51]
	v_mfma_f32_16x16x32_bf16 v[44:47], v[144:147], v[192:195], v[44:47]
	v_mfma_f32_16x16x32_bf16 v[40:43], v[160:163], v[192:195], v[40:43]
	v_mfma_f32_16x16x32_bf16 v[36:39], v[168:171], v[192:195], v[36:39]
	v_mfma_f32_16x16x32_bf16 v[32:35], v[176:179], v[192:195], v[32:35]
	v_mfma_f32_16x16x32_bf16 v[28:31], v[144:147], v[200:203], v[28:31]
	v_mfma_f32_16x16x32_bf16 v[24:27], v[160:163], v[200:203], v[24:27]
	v_mfma_f32_16x16x32_bf16 v[20:23], v[168:171], v[200:203], v[20:23]
	v_mfma_f32_16x16x32_bf16 v[16:19], v[176:179], v[200:203], v[16:19]
	v_mfma_f32_16x16x32_bf16 v[12:15], v[144:147], v[210:213], v[12:15]
	v_mfma_f32_16x16x32_bf16 v[8:11], v[160:163], v[210:213], v[8:11]
	v_lshl_add_u64 v[218:219], v[222:223], 0, s[12:13]
	s_mov_b32 m0, s43
	s_nop 0
	global_load_lds_dwordx4 v[218:219], off
	v_mfma_f32_16x16x32_bf16 v[4:7], v[168:171], v[210:213], v[4:7]
	v_mfma_f32_16x16x32_bf16 v[0:3], v[176:179], v[210:213], v[0:3]
	s_setprio 0
	s_setprio 1
	v_mfma_f32_16x16x32_bf16 v[60:63], v[156:159], v[188:191], v[60:63]
	v_mfma_f32_16x16x32_bf16 v[56:59], v[164:167], v[188:191], v[56:59]
	v_mfma_f32_16x16x32_bf16 v[52:55], v[172:175], v[188:191], v[52:55]
	v_mfma_f32_16x16x32_bf16 v[48:51], v[180:183], v[188:191], v[48:51]
	v_mfma_f32_16x16x32_bf16 v[44:47], v[156:159], v[196:199], v[44:47]
	v_mfma_f32_16x16x32_bf16 v[40:43], v[164:167], v[196:199], v[40:43]
	v_mfma_f32_16x16x32_bf16 v[36:39], v[172:175], v[196:199], v[36:39]
	v_mfma_f32_16x16x32_bf16 v[32:35], v[180:183], v[196:199], v[32:35]
	v_mfma_f32_16x16x32_bf16 v[28:31], v[156:159], v[206:209], v[28:31]
	v_mfma_f32_16x16x32_bf16 v[24:27], v[164:167], v[206:209], v[24:27]
	v_mfma_f32_16x16x32_bf16 v[20:23], v[172:175], v[206:209], v[20:23]
	v_mfma_f32_16x16x32_bf16 v[16:19], v[180:183], v[206:209], v[16:19]
	v_mfma_f32_16x16x32_bf16 v[12:15], v[156:159], v[214:217], v[12:15]
	v_mfma_f32_16x16x32_bf16 v[8:11], v[164:167], v[214:217], v[8:11]
	v_lshl_add_u64 v[218:219], v[224:225], 0, s[12:13]
	s_mov_b32 m0, s44
	s_nop 0
	global_load_lds_dwordx4 v[218:219], off
	v_mfma_f32_16x16x32_bf16 v[4:7], v[172:175], v[214:217], v[4:7]
	v_mfma_f32_16x16x32_bf16 v[0:3], v[180:183], v[214:217], v[0:3]
	s_setprio 0
	s_barrier
	s_add_i32 s55, s55, 2
	s_add_u32 s53, s53, 0x100
	s_addc_u32 s54, s54, 0
	s_mov_b64 s[26:27], s[28:29]
.LBB0_1978:
	ds_read_b128 v[144:147], v151
	ds_read_b128 v[156:159], v151 offset:1024
	ds_read_b128 v[160:163], v151 offset:2048
	ds_read_b128 v[164:167], v151 offset:3072
	ds_read_b128 v[168:171], v152
	ds_read_b128 v[172:175], v152 offset:1024
	ds_read_b128 v[176:179], v152 offset:2048
	ds_read_b128 v[180:183], v152 offset:3072
	s_add_u32 s28, s26, 0x100
	s_addc_u32 s29, s27, 0
	s_cmp_eq_u32 s55, 40
	s_cselect_b32 s39, s1, s29
	s_cselect_b32 s38, s0, s28
	s_cselect_b32 s37, s25, s54
	s_cselect_b32 s36, s24, s53
	v_lshl_add_u64 v[218:219], s[26:27], 0, v[136:137]
	s_add_i32 m0, s33, 0xc000
	ds_read_b128 v[184:187], v153
	ds_read_b128 v[188:191], v153 offset:1024
	ds_read_b128 v[192:195], v153 offset:2048
	ds_read_b128 v[196:199], v153 offset:3072
	ds_read_b128 v[200:203], v153 offset:4096
	ds_read_b128 v[206:209], v153 offset:5120
	ds_read_b128 v[210:213], v153 offset:6144
	ds_read_b128 v[214:217], v153 offset:7168
	global_load_lds_dwordx4 v[218:219], off
	v_lshl_add_u64 v[218:219], s[26:27], 0, v[138:139]
	s_add_i32 m0, s33, 0xe000
	s_nop 0
	global_load_lds_dwordx4 v[218:219], off
	s_waitcnt vmcnt(8)
	s_waitcnt lgkmcnt(0)
	s_barrier
; #define PG8_STAGE(bufoff, gbase, voff) do { _Pragma("unroll") for (int _i = 0; _i < 2; ++_i) \
;         __builtin_amdgcn_global_load_lds((const unsigned*)((const char*)(gbase) + (voff)[_i]), (PG8_LAS unsigned*)(lds + (bufoff) + ldsw + _i * 8192), 16, 0, 0); } while (0)
; #define PG8_LDA(dst, b, h) do { _Pragma("unroll") for (int m = 0; m < 4; ++m) _Pragma("unroll") for (int k = 0; k < 2; ++k) dst[m][k] = *(const PG8_LAS bf16x8*)(lds + PG8_SA(b, h) + aoff + m * 2048 + k * 1024); } while (0)
; #define PG8_LDB(dst, b, h) do { _Pragma("unroll") for (int n = 0; n < 2; ++n) _Pragma("unroll") for (int k = 0; k < 2; ++k) dst[n][k] = *(const PG8_LAS bf16x8*)(lds + PG8_SB(b, h) + boff + n * 2048 + k * 1024); } while (0)
; #define PG8_MMA(ai, bj, At, Bt) do { __builtin_amdgcn_s_setprio(1); _Pragma("unroll") for (int m = 0; m < 4; ++m) _Pragma("unroll") for (int n = 0; n < 2; ++n) _Pragma("unroll") for (int k = 0; k < 2; ++k) \
;         acc[ai][bj][m][n] = __builtin_amdgcn_mfma_f32_16x16x32_bf16(Bt[n][k], At[m][k], acc[ai][bj][m][n], 0, 0, 0); __builtin_amdgcn_s_setprio(0); } while (0)
; #define PG8_WAIT_V(n) asm volatile("s_waitcnt vmcnt(" #n ")" ::: "memory")
; #define PG8_WAIT_L(n) asm volatile("s_waitcnt lgkmcnt(" #n ")" ::: "memory")
; #define PG8_BAR __builtin_amdgcn_s_barrier()
; #define PG8_SCHED __builtin_amdgcn_sched_barrier(0)
; template <class Epi, class Sched, bool ALIGN_EPI = false, bool SP2 = false>
; __device__ __forceinline__ void gemm_phase(PG8_LAS unsigned char* lds, const Gemm g, const Sched& S, const Epi& E) {
;     ...
;             PG8_LDB(B0, 0, 0); PG8_LDB(B1, 0, 1); PG8_SCHED; PG8_LDA(At, 0, 0); PG8_STAGE(PG8_SA(1, 1), a1 + hstep, voffA);
;             PG8_WAIT_V(8); PG8_WAIT_L(0); PG8_BAR; PG8_MMA(0, 0, At, B0); PG8_MMA(0, 1, At, B1); PG8_BAR; PG8_SCHED;
;             PG8_LDA(At, 0, 1); PG8_STAGE(PG8_SB(0, 0), b2, voffB); PG8_STAGE(PG8_SB(0, 1), b2 + hstep, voffB); PG8_STAGE(PG8_SA(0, 0), a2, voffA);
;             PG8_WAIT_V(8); PG8_WAIT_L(0); PG8_BAR; PG8_MMA(1, 0, At, B0); PG8_MMA(1, 1, At, B1); PG8_BAR; PG8_SCHED;
	s_setprio 1
	s_waitcnt lgkmcnt(0)
	v_mfma_f32_16x16x32_bf16 v[124:127], v[144:147], v[184:187], v[124:127]
	v_mfma_f32_16x16x32_bf16 v[120:123], v[160:163], v[184:187], v[120:123]
	v_mfma_f32_16x16x32_bf16 v[116:119], v[168:171], v[184:187], v[116:119]
	v_mfma_f32_16x16x32_bf16 v[112:115], v[176:179], v[184:187], v[112:115]
	v_mfma_f32_16x16x32_bf16 v[108:111], v[144:147], v[192:195], v[108:111]
	v_mfma_f32_16x16x32_bf16 v[104:107], v[160:163], v[192:195], v[104:107]
	v_mfma_f32_16x16x32_bf16 v[100:103], v[168:171], v[192:195], v[100:103]
	v_mfma_f32_16x16x32_bf16 v[96:99], v[176:179], v[192:195], v[96:99]
	v_mfma_f32_16x16x32_bf16 v[92:95], v[144:147], v[200:203], v[92:95]
	v_mfma_f32_16x16x32_bf16 v[88:91], v[160:163], v[200:203], v[88:91]
	v_mfma_f32_16x16x32_bf16 v[84:87], v[168:171], v[200:203], v[84:87]
	v_mfma_f32_16x16x32_bf16 v[80:83], v[176:179], v[200:203], v[80:83]
	v_mfma_f32_16x16x32_bf16 v[76:79], v[144:147], v[210:213], v[76:79]
	v_mfma_f32_16x16x32_bf16 v[72:75], v[160:163], v[210:213], v[72:75]
	v_mfma_f32_16x16x32_bf16 v[68:71], v[168:171], v[210:213], v[68:71]
	v_mfma_f32_16x16x32_bf16 v[64:67], v[176:179], v[210:213], v[64:67]
	s_setprio 0
	s_setprio 1
	v_mfma_f32_16x16x32_bf16 v[124:127], v[156:159], v[188:191], v[124:127]
	v_mfma_f32_16x16x32_bf16 v[120:123], v[164:167], v[188:191], v[120:123]
	v_mfma_f32_16x16x32_bf16 v[116:119], v[172:175], v[188:191], v[116:119]
	v_mfma_f32_16x16x32_bf16 v[112:115], v[180:183], v[188:191], v[112:115]
	v_mfma_f32_16x16x32_bf16 v[108:111], v[156:159], v[196:199], v[108:111]
	v_mfma_f32_16x16x32_bf16 v[104:107], v[164:167], v[196:199], v[104:107]
	v_mfma_f32_16x16x32_bf16 v[100:103], v[172:175], v[196:199], v[100:103]
	v_mfma_f32_16x16x32_bf16 v[96:99], v[180:183], v[196:199], v[96:99]
	v_mfma_f32_16x16x32_bf16 v[92:95], v[156:159], v[206:209], v[92:95]
	v_mfma_f32_16x16x32_bf16 v[88:91], v[164:167], v[206:209], v[88:91]
	v_mfma_f32_16x16x32_bf16 v[84:87], v[172:175], v[206:209], v[84:87]
	v_mfma_f32_16x16x32_bf16 v[80:83], v[180:183], v[206:209], v[80:83]
	v_mfma_f32_16x16x32_bf16 v[76:79], v[156:159], v[214:217], v[76:79]
	v_mfma_f32_16x16x32_bf16 v[72:75], v[164:167], v[214:217], v[72:75]
	v_mfma_f32_16x16x32_bf16 v[68:71], v[172:175], v[214:217], v[68:71]
	v_mfma_f32_16x16x32_bf16 v[64:67], v[180:183], v[214:217], v[64:67]
	s_setprio 0
	s_barrier
	s_add_i32 s26, s45, s15
	v_lshl_add_u64 v[218:219], s[36:37], 0, v[130:131]
	s_mov_b32 m0, s26
	ds_read_b128 v[184:187], v153 offset:16384
	ds_read_b128 v[188:191], v153 offset:17408
	ds_read_b128 v[192:195], v153 offset:18432
	ds_read_b128 v[196:199], v153 offset:19456
	ds_read_b128 v[200:203], v153 offset:20480
	ds_read_b128 v[206:209], v153 offset:21504
	ds_read_b128 v[210:213], v153 offset:22528
	ds_read_b128 v[214:217], v153 offset:23552
	global_load_lds_dwordx4 v[218:219], off
	s_add_i32 m0, s26, 0x2000
	s_add_u32 s26, s36, 0xb0000
	v_lshl_add_u64 v[220:221], s[36:37], 0, v[134:135]
	s_addc_u32 s27, s37, 0
	s_add_i32 s56, s46, s15
	global_load_lds_dwordx4 v[220:221], off
	v_lshl_add_u64 v[222:223], s[26:27], 0, v[130:131]
	s_mov_b32 m0, s56
	global_load_lds_dwordx4 v[222:223], off
	v_lshl_add_u64 v[222:223], s[26:27], 0, v[134:135]
	s_add_i32 m0, s56, 0x2000
	s_nop 0
	global_load_lds_dwordx4 v[222:223], off
	s_waitcnt vmcnt(6)
	s_waitcnt lgkmcnt(0)
	s_barrier
	s_setprio 1
	s_waitcnt lgkmcnt(0)
	v_mfma_f32_16x16x32_bf16 v[60:63], v[144:147], v[184:187], v[60:63]
	v_mfma_f32_16x16x32_bf16 v[56:59], v[160:163], v[184:187], v[56:59]
	v_mfma_f32_16x16x32_bf16 v[52:55], v[168:171], v[184:187], v[52:55]
	v_mfma_f32_16x16x32_bf16 v[48:51], v[176:179], v[184:187], v[48:51]
	v_mfma_f32_16x16x32_bf16 v[44:47], v[144:147], v[192:195], v[44:47]
	v_mfma_f32_16x16x32_bf16 v[40:43], v[160:163], v[192:195], v[40:43]
	v_mfma_f32_16x16x32_bf16 v[36:39], v[168:171], v[192:195], v[36:39]
	v_mfma_f32_16x16x32_bf16 v[32:35], v[176:179], v[192:195], v[32:35]
	v_mfma_f32_16x16x32_bf16 v[28:31], v[144:147], v[200:203], v[28:31]
	v_mfma_f32_16x16x32_bf16 v[24:27], v[160:163], v[200:203], v[24:27]
	v_mfma_f32_16x16x32_bf16 v[20:23], v[168:171], v[200:203], v[20:23]
	v_mfma_f32_16x16x32_bf16 v[16:19], v[176:179], v[200:203], v[16:19]
	v_mfma_f32_16x16x32_bf16 v[12:15], v[144:147], v[210:213], v[12:15]
	v_mfma_f32_16x16x32_bf16 v[8:11], v[160:163], v[210:213], v[8:11]
	v_lshl_add_u64 v[222:223], s[38:39], 0, v[128:129]
	s_mov_b32 m0, s33
	s_nop 0
	global_load_lds_dwordx4 v[222:223], off
	v_mfma_f32_16x16x32_bf16 v[4:7], v[168:171], v[210:213], v[4:7]
	v_mfma_f32_16x16x32_bf16 v[0:3], v[176:179], v[210:213], v[0:3]
	s_setprio 0
	s_setprio 1
	v_mfma_f32_16x16x32_bf16 v[60:63], v[156:159], v[188:191], v[60:63]
	v_mfma_f32_16x16x32_bf16 v[56:59], v[164:167], v[188:191], v[56:59]
	v_mfma_f32_16x16x32_bf16 v[52:55], v[172:175], v[188:191], v[52:55]
	v_mfma_f32_16x16x32_bf16 v[48:51], v[180:183], v[188:191], v[48:51]
	v_mfma_f32_16x16x32_bf16 v[44:47], v[156:159], v[196:199], v[44:47]
	v_mfma_f32_16x16x32_bf16 v[40:43], v[164:167], v[196:199], v[40:43]
	v_mfma_f32_16x16x32_bf16 v[36:39], v[172:175], v[196:199], v[36:39]
	v_mfma_f32_16x16x32_bf16 v[32:35], v[180:183], v[196:199], v[32:35]
	v_mfma_f32_16x16x32_bf16 v[28:31], v[156:159], v[206:209], v[28:31]
	v_mfma_f32_16x16x32_bf16 v[24:27], v[164:167], v[206:209], v[24:27]
	v_mfma_f32_16x16x32_bf16 v[20:23], v[172:175], v[206:209], v[20:23]
	v_mfma_f32_16x16x32_bf16 v[16:19], v[180:183], v[206:209], v[16:19]
	v_mfma_f32_16x16x32_bf16 v[12:15], v[156:159], v[214:217], v[12:15]
	v_mfma_f32_16x16x32_bf16 v[8:11], v[164:167], v[214:217], v[8:11]
	v_lshl_add_u64 v[224:225], s[38:39], 0, v[132:133]
	s_mov_b32 m0, s34
	s_nop 0
	global_load_lds_dwordx4 v[224:225], off
	v_mfma_f32_16x16x32_bf16 v[4:7], v[172:175], v[214:217], v[4:7]
	v_mfma_f32_16x16x32_bf16 v[0:3], v[180:183], v[214:217], v[0:3]
	s_setprio 0
	s_barrier
; #define PG8_STAGE(bufoff, gbase, voff) do { _Pragma("unroll") for (int _i = 0; _i < 2; ++_i) \
;         __builtin_amdgcn_global_load_lds((const unsigned*)((const char*)(gbase) + (voff)[_i]), (PG8_LAS unsigned*)(lds + (bufoff) + ldsw + _i * 8192), 16, 0, 0); } while (0)
; #define PG8_LDA(dst, b, h) do { _Pragma("unroll") for (int m = 0; m < 4; ++m) _Pragma("unroll") for (int k = 0; k < 2; ++k) dst[m][k] = *(const PG8_LAS bf16x8*)(lds + PG8_SA(b, h) + aoff + m * 2048 + k * 1024); } while (0)
; #define PG8_LDB(dst, b, h) do { _Pragma("unroll") for (int n = 0; n < 2; ++n) _Pragma("unroll") for (int k = 0; k < 2; ++k) dst[n][k] = *(const PG8_LAS bf16x8*)(lds + PG8_SB(b, h) + boff + n * 2048 + k * 1024); } while (0)
; #define PG8_MMA(ai, bj, At, Bt) do { __builtin_amdgcn_s_setprio(1); _Pragma("unroll") for (int m = 0; m < 4; ++m) _Pragma("unroll") for (int n = 0; n < 2; ++n) _Pragma("unroll") for (int k = 0; k < 2; ++k) \
;         acc[ai][bj][m][n] = __builtin_amdgcn_mfma_f32_16x16x32_bf16(Bt[n][k], At[m][k], acc[ai][bj][m][n], 0, 0, 0); __builtin_amdgcn_s_setprio(0); } while (0)
; #define PG8_WAIT_V(n) asm volatile("s_waitcnt vmcnt(" #n ")" ::: "memory")
; #define PG8_WAIT_L(n) asm volatile("s_waitcnt lgkmcnt(" #n ")" ::: "memory")
; #define PG8_BAR __builtin_amdgcn_s_barrier()
; #define PG8_SCHED __builtin_amdgcn_sched_barrier(0)
; template <class Epi, class Sched, bool ALIGN_EPI = false, bool SP2 = false>
; __device__ __forceinline__ void gemm_phase(PG8_LAS unsigned char* lds, const Gemm g, const Sched& S, const Epi& E) {
;     ...
;             PG8_LDB(B0, 1, 0); PG8_LDB(B1, 1, 1); PG8_SCHED; PG8_LDA(At, 1, 0); PG8_STAGE(PG8_SA(0, 1), a2 + hstep, voffA);
;             PG8_WAIT_V(8); PG8_WAIT_L(0); PG8_BAR; PG8_MMA(0, 0, At, B0); PG8_MMA(0, 1, At, B1); PG8_BAR; PG8_SCHED;
	s_add_i32 s56, 0, 0x18000
	v_add_u32_e32 v155, s56, v149
	s_add_i32 s57, 0, 0x1c000
	ds_read_b128 v[144:147], v155
	ds_read_b128 v[156:159], v155 offset:1024
	ds_read_b128 v[160:163], v155 offset:2048
	ds_read_b128 v[164:167], v155 offset:3072
	v_add_u32_e32 v155, s57, v149
	ds_read_b128 v[168:171], v155
	ds_read_b128 v[172:175], v155 offset:1024
	ds_read_b128 v[176:179], v155 offset:2048
	ds_read_b128 v[180:183], v155 offset:3072
	s_add_u32 s26, s38, 0xb0000
	s_addc_u32 s27, s39, 0
	s_mov_b32 m0, s40
	v_lshl_add_u64 v[226:227], s[26:27], 0, v[128:129]
	ds_read_b128 v[184:187], v153 offset:32768
	ds_read_b128 v[188:191], v153 offset:33792
	ds_read_b128 v[192:195], v153 offset:34816
	ds_read_b128 v[196:199], v153 offset:35840
	ds_read_b128 v[200:203], v153 offset:36864
	ds_read_b128 v[206:209], v153 offset:37888
	ds_read_b128 v[210:213], v153 offset:38912
	ds_read_b128 v[214:217], v153 offset:39936
	global_load_lds_dwordx4 v[226:227], off
	v_lshl_add_u64 v[226:227], s[26:27], 0, v[132:133]
	s_mov_b32 m0, s41
	s_nop 0
	global_load_lds_dwordx4 v[226:227], off
	s_waitcnt vmcnt(8)
	s_waitcnt lgkmcnt(0)
	s_barrier
	s_setprio 1
	s_waitcnt lgkmcnt(0)
	v_mfma_f32_16x16x32_bf16 v[124:127], v[144:147], v[184:187], v[124:127]
	v_mfma_f32_16x16x32_bf16 v[120:123], v[160:163], v[184:187], v[120:123]
	v_mfma_f32_16x16x32_bf16 v[116:119], v[168:171], v[184:187], v[116:119]
	v_mfma_f32_16x16x32_bf16 v[112:115], v[176:179], v[184:187], v[112:115]
	v_mfma_f32_16x16x32_bf16 v[108:111], v[144:147], v[192:195], v[108:111]
	v_mfma_f32_16x16x32_bf16 v[104:107], v[160:163], v[192:195], v[104:107]
	v_mfma_f32_16x16x32_bf16 v[100:103], v[168:171], v[192:195], v[100:103]
	v_mfma_f32_16x16x32_bf16 v[96:99], v[176:179], v[192:195], v[96:99]
	v_mfma_f32_16x16x32_bf16 v[92:95], v[144:147], v[200:203], v[92:95]
	v_mfma_f32_16x16x32_bf16 v[88:91], v[160:163], v[200:203], v[88:91]
	v_mfma_f32_16x16x32_bf16 v[84:87], v[168:171], v[200:203], v[84:87]
	v_mfma_f32_16x16x32_bf16 v[80:83], v[176:179], v[200:203], v[80:83]
	v_mfma_f32_16x16x32_bf16 v[76:79], v[144:147], v[210:213], v[76:79]
	v_mfma_f32_16x16x32_bf16 v[72:75], v[160:163], v[210:213], v[72:75]
	v_mfma_f32_16x16x32_bf16 v[68:71], v[168:171], v[210:213], v[68:71]
	v_mfma_f32_16x16x32_bf16 v[64:67], v[176:179], v[210:213], v[64:67]
	s_setprio 0
	s_setprio 1
	v_mfma_f32_16x16x32_bf16 v[124:127], v[156:159], v[188:191], v[124:127]
	v_mfma_f32_16x16x32_bf16 v[120:123], v[164:167], v[188:191], v[120:123]
	v_mfma_f32_16x16x32_bf16 v[116:119], v[172:175], v[188:191], v[116:119]
	v_mfma_f32_16x16x32_bf16 v[112:115], v[180:183], v[188:191], v[112:115]
	v_mfma_f32_16x16x32_bf16 v[108:111], v[156:159], v[196:199], v[108:111]
	v_mfma_f32_16x16x32_bf16 v[104:107], v[164:167], v[196:199], v[104:107]
	v_mfma_f32_16x16x32_bf16 v[100:103], v[172:175], v[196:199], v[100:103]
	v_mfma_f32_16x16x32_bf16 v[96:99], v[180:183], v[196:199], v[96:99]
	v_mfma_f32_16x16x32_bf16 v[92:95], v[156:159], v[206:209], v[92:95]
	v_mfma_f32_16x16x32_bf16 v[88:91], v[164:167], v[206:209], v[88:91]
	v_mfma_f32_16x16x32_bf16 v[84:87], v[172:175], v[206:209], v[84:87]
	v_mfma_f32_16x16x32_bf16 v[80:83], v[180:183], v[206:209], v[80:83]
	v_mfma_f32_16x16x32_bf16 v[76:79], v[156:159], v[214:217], v[76:79]
	v_mfma_f32_16x16x32_bf16 v[72:75], v[164:167], v[214:217], v[72:75]
	v_mfma_f32_16x16x32_bf16 v[68:71], v[172:175], v[214:217], v[68:71]
	v_mfma_f32_16x16x32_bf16 v[64:67], v[180:183], v[214:217], v[64:67]
	s_setprio 0
	s_barrier
; #define PG8_STAGE(bufoff, gbase, voff) do { _Pragma("unroll") for (int _i = 0; _i < 2; ++_i) \
;         __builtin_amdgcn_global_load_lds((const unsigned*)((const char*)(gbase) + (voff)[_i]), (PG8_LAS unsigned*)(lds + (bufoff) + ldsw + _i * 8192), 16, 0, 0); } while (0)
; #define PG8_LDA(dst, b, h) do { _Pragma("unroll") for (int m = 0; m < 4; ++m) _Pragma("unroll") for (int k = 0; k < 2; ++k) dst[m][k] = *(const PG8_LAS bf16x8*)(lds + PG8_SA(b, h) + aoff + m * 2048 + k * 1024); } while (0)
; #define PG8_MMA(ai, bj, At, Bt) do { __builtin_amdgcn_s_setprio(1); _Pragma("unroll") for (int m = 0; m < 4; ++m) _Pragma("unroll") for (int n = 0; n < 2; ++n) _Pragma("unroll") for (int k = 0; k < 2; ++k) \
;         acc[ai][bj][m][n] = __builtin_amdgcn_mfma_f32_16x16x32_bf16(Bt[n][k], At[m][k], acc[ai][bj][m][n], 0, 0, 0); __builtin_amdgcn_s_setprio(0); } while (0)
; #define PG8_WAIT_V(n) asm volatile("s_waitcnt vmcnt(" #n ")" ::: "memory")
; #define PG8_WAIT_L(n) asm volatile("s_waitcnt lgkmcnt(" #n ")" ::: "memory")
; #define PG8_BAR __builtin_amdgcn_s_barrier()
; #define PG8_SCHED __builtin_amdgcn_sched_barrier(0)
; template <class Epi, class Sched, bool ALIGN_EPI = false, bool SP2 = false>
; __device__ __forceinline__ void gemm_phase(PG8_LAS unsigned char* lds, const Gemm g, const Sched& S, const Epi& E) {
;     ...
;             PG8_LDA(At, 1, 1); PG8_STAGE(PG8_SB(1, 0), b3, voffB); PG8_STAGE(PG8_SB(1, 1), b3 + hstep, voffB); PG8_STAGE(PG8_SA(1, 0), a3, voffA);
;             PG8_WAIT_V(8); PG8_WAIT_L(0); PG8_BAR; PG8_MMA(1, 0, At, B0); PG8_MMA(1, 1, At, B1); PG8_BAR; PG8_SCHED;
	s_add_i32 s26, s56, s15
	v_lshl_add_u64 v[218:219], v[218:219], 0, s[12:13]
	s_mov_b32 m0, s26
	ds_read_b128 v[184:187], v153 offset:49152
	ds_read_b128 v[188:191], v153 offset:50176
	ds_read_b128 v[192:195], v153 offset:51200
	ds_read_b128 v[196:199], v153 offset:52224
	ds_read_b128 v[200:203], v153 offset:53248
	ds_read_b128 v[206:209], v153 offset:54272
	ds_read_b128 v[210:213], v153 offset:55296
	ds_read_b128 v[214:217], v153 offset:56320
	global_load_lds_dwordx4 v[218:219], off
	s_add_i32 m0, s26, 0x2000
	s_add_u32 s26, s36, 0xb0080
	v_lshl_add_u64 v[218:219], v[220:221], 0, s[12:13]
	s_addc_u32 s27, s37, 0
	s_add_i32 s36, s57, s15
	global_load_lds_dwordx4 v[218:219], off
	v_lshl_add_u64 v[218:219], s[26:27], 0, v[130:131]
	s_mov_b32 m0, s36
	s_nop 0
	global_load_lds_dwordx4 v[218:219], off
	v_lshl_add_u64 v[218:219], s[26:27], 0, v[134:135]
	s_add_i32 m0, s36, 0x2000
	s_nop 0
	global_load_lds_dwordx4 v[218:219], off
	s_waitcnt vmcnt(6)
	s_waitcnt lgkmcnt(0)
	s_barrier
	s_setprio 1
	s_waitcnt lgkmcnt(0)
	v_mfma_f32_16x16x32_bf16 v[60:63], v[144:147], v[184:187], v[60:63]
	v_mfma_f32_16x16x32_bf16 v[56:59], v[160:163], v[184:187], v[56:59]
	v_mfma_f32_16x16x32_bf16 v[52:55], v[168:171], v[184:187], v[52:55]
	v_mfma_f32_16x16x32_bf16 v[48:51], v[176:179], v[184:187], v[48:51]
	v_mfma_f32_16x16x32_bf16 v[44:47], v[144:147], v[192:195], v[44:47]
	v_mfma_f32_16x16x32_bf16 v[40:43], v[160:163], v[192:195], v[40:43]
	v_mfma_f32_16x16x32_bf16 v[36:39], v[168:171], v[192:195], v[36:39]
	v_mfma_f32_16x16x32_bf16 v[32:35], v[176:179], v[192:195], v[32:35]
	v_mfma_f32_16x16x32_bf16 v[28:31], v[144:147], v[200:203], v[28:31]
	v_mfma_f32_16x16x32_bf16 v[24:27], v[160:163], v[200:203], v[24:27]
	v_mfma_f32_16x16x32_bf16 v[20:23], v[168:171], v[200:203], v[20:23]
	v_mfma_f32_16x16x32_bf16 v[16:19], v[176:179], v[200:203], v[16:19]
	v_mfma_f32_16x16x32_bf16 v[12:15], v[144:147], v[210:213], v[12:15]
	v_mfma_f32_16x16x32_bf16 v[8:11], v[160:163], v[210:213], v[8:11]
	v_lshl_add_u64 v[218:219], v[222:223], 0, s[12:13]
	s_mov_b32 m0, s43
	s_nop 0
	global_load_lds_dwordx4 v[218:219], off
	v_mfma_f32_16x16x32_bf16 v[4:7], v[168:171], v[210:213], v[4:7]
	v_mfma_f32_16x16x32_bf16 v[0:3], v[176:179], v[210:213], v[0:3]
	s_setprio 0
	s_setprio 1
	v_mfma_f32_16x16x32_bf16 v[60:63], v[156:159], v[188:191], v[60:63]
	v_mfma_f32_16x16x32_bf16 v[56:59], v[164:167], v[188:191], v[56:59]
	v_mfma_f32_16x16x32_bf16 v[52:55], v[172:175], v[188:191], v[52:55]
	v_mfma_f32_16x16x32_bf16 v[48:51], v[180:183], v[188:191], v[48:51]
	v_mfma_f32_16x16x32_bf16 v[44:47], v[156:159], v[196:199], v[44:47]
	v_mfma_f32_16x16x32_bf16 v[40:43], v[164:167], v[196:199], v[40:43]
	v_mfma_f32_16x16x32_bf16 v[36:39], v[172:175], v[196:199], v[36:39]
	v_mfma_f32_16x16x32_bf16 v[32:35], v[180:183], v[196:199], v[32:35]
	v_mfma_f32_16x16x32_bf16 v[28:31], v[156:159], v[206:209], v[28:31]
	v_mfma_f32_16x16x32_bf16 v[24:27], v[164:167], v[206:209], v[24:27]
	v_mfma_f32_16x16x32_bf16 v[20:23], v[172:175], v[206:209], v[20:23]
	v_mfma_f32_16x16x32_bf16 v[16:19], v[180:183], v[206:209], v[16:19]
	v_mfma_f32_16x16x32_bf16 v[12:15], v[156:159], v[214:217], v[12:15]
	v_mfma_f32_16x16x32_bf16 v[8:11], v[164:167], v[214:217], v[8:11]
	v_lshl_add_u64 v[218:219], v[224:225], 0, s[12:13]
	s_mov_b32 m0, s44
	s_nop 0
	global_load_lds_dwordx4 v[218:219], off
	v_mfma_f32_16x16x32_bf16 v[4:7], v[172:175], v[214:217], v[4:7]
	v_mfma_f32_16x16x32_bf16 v[0:3], v[180:183], v[214:217], v[0:3]
	s_setprio 0
	s_barrier
	s_add_i32 s55, s55, 2
	s_add_u32 s53, s53, 0x100
	s_addc_u32 s54, s54, 0
	s_cmp_gt_u32 s55, 41
	s_mov_b64 s[26:27], s[28:29]
	s_cbranch_scc0 .LBB0_1978
	s_and_b64 vcc, exec, s[16:17]
	s_cbranch_vccz .LBB0_1981
	s_barrier
